# butterfly reductions: xor-1/2/4/8 ds_bpermute steps replaced by DPP moves (quad_perm / row_half_mirror / row_mirror) in all non-attention phases, counted lgkm waits adjusted
# speedup vs baseline: 1.0146x; 1.0095x over previous
.LBB0_209:
	s_or_b64 exec, exec, s[6:7]
	v_ashrrev_i32_e32 v1, 12, v2
	v_mad_i32_i24 v1, v1, s35, s35
	v_cndmask_b32_e64 v34, v1, 0, s[4:5]
	v_ashrrev_i32_e32 v35, 31, v34
	v_lshl_add_u64 v[42:43], v[34:35], 2, s[14:15]
	v_lshl_add_u64 v[54:55], v[42:43], 0, s[28:29]
	v_lshl_add_u64 v[46:47], v[24:25], 0, v[12:13]
	v_lshl_add_u64 v[24:25], v[54:55], 0, v[12:13]
	s_waitcnt lgkmcnt(0)
	v_readfirstlane_b32 s4, v4
	v_readfirstlane_b32 s5, v5
	global_load_dwordx4 v[34:37], v[46:47], off
	s_nop 3
	global_load_dwordx4 v[38:41], v12, s[4:5]
	global_load_dwordx4 v[42:45], v[24:25], off
	v_lshlrev_b64 v[24:25], 12, v[22:23]
	v_lshlrev_b64 v[22:23], 11, v[22:23]
	v_lshl_add_u64 v[58:59], v[6:7], 0, v[24:25]
	v_lshl_add_u64 v[62:63], v[8:9], 0, v[22:23]
	v_lshl_add_u64 v[50:51], v[54:55], 0, v[16:17]
	s_waitcnt vmcnt(2)
	global_store_dwordx4 v[58:59], v[34:37], off sc1
	s_waitcnt vmcnt(2)
	v_pk_mul_f32 v[22:23], v[36:37], v[40:41]
	v_pk_mul_f32 v[24:25], v[34:35], v[38:39]
	s_waitcnt vmcnt(1)
	v_pk_add_f32 v[38:39], v[42:43], 1.0 op_sel_hi:[1,0]
	v_pk_add_f32 v[40:41], v[44:45], 1.0 op_sel_hi:[1,0]
	v_pk_mul_f32 v[24:25], v[38:39], v[24:25]
	v_pk_mul_f32 v[22:23], v[40:41], v[22:23]
	v_cvt_pk_bf16_f32 v24, v24, v25
	v_cvt_pk_bf16_f32 v25, v22, v23
	global_store_dwordx2 v[62:63], v[24:25], off sc1
	v_lshl_add_u64 v[42:43], v[54:55], 0, v[14:15]
	global_load_dwordx4 v[22:25], v[46:47], off offset:1024
	global_load_dwordx4 v[38:41], v12, s[4:5] offset:1024
	v_mul_f32_e32 v1, v35, v35
	global_load_dwordx4 v[42:45], v[42:43], off
	v_fmac_f32_e32 v1, v34, v34
	v_fmac_f32_e32 v1, v36, v36
	v_fmac_f32_e32 v1, v37, v37
	s_waitcnt vmcnt(2)
	global_store_dwordx4 v[58:59], v[22:25], off offset:1024 sc1
	s_waitcnt vmcnt(2)
	v_pk_mul_f32 v[40:41], v[24:25], v[40:41]
	v_pk_mul_f32 v[38:39], v[22:23], v[38:39]
	s_waitcnt vmcnt(1)
	v_pk_add_f32 v[42:43], v[42:43], 1.0 op_sel_hi:[1,0]
	v_pk_add_f32 v[44:45], v[44:45], 1.0 op_sel_hi:[1,0]
	v_pk_mul_f32 v[38:39], v[42:43], v[38:39]
	v_pk_mul_f32 v[40:41], v[44:45], v[40:41]
	v_cvt_pk_bf16_f32 v38, v38, v39
	v_cvt_pk_bf16_f32 v39, v40, v41
	global_store_dwordx2 v[62:63], v[38:39], off offset:512 sc1
	global_load_dwordx4 v[38:41], v[46:47], off offset:2048
	s_nop 0
	global_load_dwordx4 v[42:45], v12, s[4:5] offset:2048
	v_mul_f32_e32 v2, v23, v23
	global_load_dwordx4 v[50:53], v[50:51], off
	v_fmac_f32_e32 v2, v22, v22
	v_fmac_f32_e32 v2, v24, v24
	v_fmac_f32_e32 v2, v25, v25
	v_add_f32_e32 v1, v1, v2
	s_waitcnt vmcnt(2)
	global_store_dwordx4 v[58:59], v[38:41], off offset:2048 sc1
	s_waitcnt vmcnt(2)
	v_pk_mul_f32 v[44:45], v[40:41], v[44:45]
	v_pk_mul_f32 v[42:43], v[38:39], v[42:43]
	s_waitcnt vmcnt(1)
	v_pk_add_f32 v[50:51], v[50:51], 1.0 op_sel_hi:[1,0]
	v_pk_add_f32 v[52:53], v[52:53], 1.0 op_sel_hi:[1,0]
	v_pk_mul_f32 v[42:43], v[50:51], v[42:43]
	v_pk_mul_f32 v[44:45], v[52:53], v[44:45]
	v_cvt_pk_bf16_f32 v42, v42, v43
	v_cvt_pk_bf16_f32 v43, v44, v45
	global_store_dwordx2 v[62:63], v[42:43], off offset:1024 sc1
	global_load_dwordx4 v[42:45], v[46:47], off offset:3072
	s_nop 0
	global_load_dwordx4 v[50:53], v12, s[4:5] offset:3072
	v_lshl_add_u64 v[46:47], v[54:55], 0, v[18:19]
	global_load_dwordx4 v[54:57], v[46:47], off
	v_mul_f32_e32 v2, v39, v39
	v_fmac_f32_e32 v2, v38, v38
	v_fmac_f32_e32 v2, v40, v40
	v_fmac_f32_e32 v2, v41, v41
	v_add_f32_e32 v1, v1, v2
	s_waitcnt vmcnt(2)
	v_mul_f32_e32 v2, v43, v43
	v_fmac_f32_e32 v2, v42, v42
	v_fmac_f32_e32 v2, v44, v44
	v_fmac_f32_e32 v2, v45, v45
	v_add_f32_e32 v1, v1, v2
	s_nop 1
	v_mov_b32_dpp v2, v1 quad_perm:[1,0,3,2] row_mask:0xf bank_mask:0xf
	s_waitcnt vmcnt(1)
	v_pk_mul_f32 v[24:25], v[42:43], v[50:51]
	s_waitcnt vmcnt(0)
	v_pk_add_f32 v[34:35], v[54:55], 1.0 op_sel_hi:[1,0]
	v_pk_mul_f32 v[22:23], v[44:45], v[52:53]
	v_pk_mul_f32 v[24:25], v[34:35], v[24:25]
	s_waitcnt lgkmcnt(0)
	v_add_f32_e32 v1, v1, v2
	s_nop 1
	v_mov_b32_dpp v2, v1 quad_perm:[2,3,0,1] row_mask:0xf bank_mask:0xf
	v_pk_add_f32 v[34:35], v[56:57], 1.0 op_sel_hi:[1,0]
	v_cvt_pk_bf16_f32 v24, v24, v25
	v_pk_mul_f32 v[22:23], v[34:35], v[22:23]
	global_store_dwordx4 v[58:59], v[42:45], off offset:3072 sc1
	s_waitcnt lgkmcnt(0)
	v_add_f32_e32 v1, v1, v2
	s_nop 1
	v_mov_b32_dpp v2, v1 row_half_mirror row_mask:0xf bank_mask:0xf
	v_cvt_pk_bf16_f32 v25, v22, v23
	global_store_dwordx2 v[62:63], v[24:25], off offset:1536 sc1
	s_waitcnt lgkmcnt(0)
	v_add_f32_e32 v1, v1, v2
	s_nop 1
	v_mov_b32_dpp v2, v1 row_mirror row_mask:0xf bank_mask:0xf
	s_waitcnt lgkmcnt(0)
	v_add_f32_e32 v1, v1, v2
	ds_bpermute_b32 v2, v30, v1
	s_waitcnt lgkmcnt(0)
	v_add_f32_e32 v1, v1, v2
	ds_bpermute_b32 v2, v31, v1
	s_and_saveexec_b64 s[4:5], vcc
	s_cbranch_execz .LBB0_204
	v_add_u32_e32 v22, v32, v20
	v_ashrrev_i32_e32 v23, 31, v22
	s_waitcnt lgkmcnt(0)
	v_add_f32_e32 v1, v1, v2
	v_lshl_add_u64 v[22:23], v[22:23], 2, s[22:23]
	v_cndmask_b32_e64 v1, 0, v1, s[0:1]
	global_store_dword v[22:23], v1, off sc1
	s_branch .LBB0_204

.LBB0_214:
	v_lshl_add_u64 v[72:73], s[14:15], 0, v[54:55]
	s_waitcnt lgkmcnt(1)
	global_load_dwordx4 v[64:67], v[72:73], off
	s_waitcnt lgkmcnt(0)
	global_load_dwordx4 v[68:71], v[72:73], off offset:16
	s_waitcnt vmcnt(1)
	v_lshlrev_b32_e32 v63, 16, v64
	v_and_b32_e32 v64, 0xffff0000, v64
	v_lshlrev_b32_e32 v72, 16, v65
	v_and_b32_e32 v65, 0xffff0000, v65
	v_mul_f32_e32 v79, v9, v64
	v_mul_f32_e32 v80, v25, v64
	v_mul_f32_e32 v64, v41, v64
	v_lshlrev_b32_e32 v73, 16, v66
	v_and_b32_e32 v66, 0xffff0000, v66
	v_mul_f32_e32 v81, v11, v65
	v_mul_f32_e32 v82, v27, v65
	v_mul_f32_e32 v65, v43, v65
	v_fmac_f32_e32 v79, v8, v63
	v_fmac_f32_e32 v80, v24, v63
	v_fmac_f32_e32 v64, v40, v63
	v_lshlrev_b32_e32 v74, 16, v67
	v_and_b32_e32 v67, 0xffff0000, v67
	v_mul_f32_e32 v83, v1, v66
	v_mul_f32_e32 v84, v17, v66
	v_mul_f32_e32 v66, v33, v66
	v_fmac_f32_e32 v81, v10, v72
	v_fmac_f32_e32 v82, v26, v72
	v_fmac_f32_e32 v65, v42, v72
	v_add_f32_e32 v63, 0, v79
	v_add_f32_e32 v72, 0, v80
	v_add_f32_e32 v64, 0, v64
	s_waitcnt vmcnt(0)
	v_lshlrev_b32_e32 v75, 16, v68
	v_and_b32_e32 v68, 0xffff0000, v68
	v_mul_f32_e32 v85, v3, v67
	v_mul_f32_e32 v86, v19, v67
	v_mul_f32_e32 v67, v35, v67
	v_fmac_f32_e32 v83, v0, v73
	v_fmac_f32_e32 v84, v16, v73
	v_fmac_f32_e32 v66, v32, v73
	v_add_f32_e32 v63, v63, v81
	v_add_f32_e32 v72, v72, v82
	v_add_f32_e32 v64, v64, v65
	v_lshlrev_b32_e32 v76, 16, v69
	v_and_b32_e32 v69, 0xffff0000, v69
	v_mul_f32_e32 v87, v5, v68
	v_mul_f32_e32 v88, v21, v68
	v_mul_f32_e32 v68, v37, v68
	v_fmac_f32_e32 v85, v2, v74
	v_fmac_f32_e32 v86, v18, v74
	v_fmac_f32_e32 v67, v34, v74
	v_add_f32_e32 v63, v63, v83
	v_add_f32_e32 v65, v72, v84
	v_add_f32_e32 v64, v64, v66
	v_lshlrev_b32_e32 v77, 16, v70
	v_and_b32_e32 v70, 0xffff0000, v70
	v_mul_f32_e32 v89, v7, v69
	v_mul_f32_e32 v90, v23, v69
	v_mul_f32_e32 v69, v39, v69
	v_fmac_f32_e32 v87, v4, v75
	v_fmac_f32_e32 v88, v20, v75
	v_fmac_f32_e32 v68, v36, v75
	v_add_f32_e32 v63, v63, v85
	v_add_f32_e32 v65, v65, v86
	v_add_f32_e32 v64, v64, v67
	v_lshlrev_b32_e32 v78, 16, v71
	v_and_b32_e32 v71, 0xffff0000, v71
	v_mul_f32_e32 v91, v13, v70
	v_mul_f32_e32 v92, v29, v70
	v_mul_f32_e32 v70, v45, v70
	v_fmac_f32_e32 v89, v6, v76
	v_fmac_f32_e32 v90, v22, v76
	v_fmac_f32_e32 v69, v38, v76
	v_add_f32_e32 v63, v63, v87
	v_add_f32_e32 v65, v65, v88
	v_add_f32_e32 v64, v64, v68
	v_mul_f32_e32 v93, v15, v71
	v_mul_f32_e32 v94, v31, v71
	v_mul_f32_e32 v71, v47, v71
	v_fmac_f32_e32 v91, v12, v77
	v_fmac_f32_e32 v92, v28, v77
	v_fmac_f32_e32 v70, v44, v77
	v_add_f32_e32 v63, v63, v89
	v_add_f32_e32 v65, v65, v90
	v_add_f32_e32 v64, v64, v69
	v_fmac_f32_e32 v93, v14, v78
	v_fmac_f32_e32 v94, v30, v78
	v_fmac_f32_e32 v71, v46, v78
	v_add_f32_e32 v63, v63, v91
	v_add_f32_e32 v65, v65, v92
	v_add_f32_e32 v64, v64, v70
	v_add_f32_e32 v63, v63, v93
	v_add_f32_e32 v65, v65, v94
	v_add_f32_e32 v64, v64, v71
	s_nop 1
	v_mov_b32_dpp v66, v63 quad_perm:[1,0,3,2] row_mask:0xf bank_mask:0xf
	s_nop 1
	v_mov_b32_dpp v67, v65 quad_perm:[1,0,3,2] row_mask:0xf bank_mask:0xf
	s_nop 1
	v_mov_b32_dpp v68, v64 quad_perm:[1,0,3,2] row_mask:0xf bank_mask:0xf
	s_waitcnt lgkmcnt(0)
	v_add_f32_e32 v63, v63, v66
	s_waitcnt lgkmcnt(0)
	v_add_f32_e32 v65, v65, v67
	s_waitcnt lgkmcnt(0)
	v_add_f32_e32 v64, v64, v68
	s_nop 1
	v_mov_b32_dpp v66, v63 quad_perm:[2,3,0,1] row_mask:0xf bank_mask:0xf
	s_nop 1
	v_mov_b32_dpp v67, v65 quad_perm:[2,3,0,1] row_mask:0xf bank_mask:0xf
	s_nop 1
	v_mov_b32_dpp v68, v64 quad_perm:[2,3,0,1] row_mask:0xf bank_mask:0xf
	s_waitcnt lgkmcnt(0)
	v_add_f32_e32 v63, v63, v66
	s_waitcnt lgkmcnt(0)
	v_add_f32_e32 v65, v65, v67
	s_waitcnt lgkmcnt(0)
	v_add_f32_e32 v64, v64, v68
	s_nop 1
	v_mov_b32_dpp v66, v63 row_half_mirror row_mask:0xf bank_mask:0xf
	s_nop 1
	v_mov_b32_dpp v67, v65 row_half_mirror row_mask:0xf bank_mask:0xf
	s_nop 1
	v_mov_b32_dpp v68, v64 row_half_mirror row_mask:0xf bank_mask:0xf
	s_waitcnt lgkmcnt(0)
	v_add_f32_e32 v63, v63, v66
	s_waitcnt lgkmcnt(0)
	v_add_f32_e32 v65, v65, v67
	s_waitcnt lgkmcnt(0)
	v_add_f32_e32 v64, v64, v68
	s_nop 1
	v_mov_b32_dpp v66, v63 row_mirror row_mask:0xf bank_mask:0xf
	s_nop 1
	v_mov_b32_dpp v67, v65 row_mirror row_mask:0xf bank_mask:0xf
	s_nop 1
	v_mov_b32_dpp v68, v64 row_mirror row_mask:0xf bank_mask:0xf
	s_waitcnt lgkmcnt(0)
	v_add_f32_e32 v63, v63, v66
	s_waitcnt lgkmcnt(0)
	v_add_f32_e32 v65, v65, v67
	s_waitcnt lgkmcnt(0)
	v_add_f32_e32 v66, v64, v68
	ds_bpermute_b32 v64, v59, v63
	ds_bpermute_b32 v67, v59, v65
	ds_bpermute_b32 v68, v59, v66
	s_waitcnt lgkmcnt(2)
	v_add_f32_e32 v63, v63, v64
	s_waitcnt lgkmcnt(1)
	v_add_f32_e32 v64, v65, v67
	s_waitcnt lgkmcnt(0)
	v_add_f32_e32 v66, v66, v68
	ds_bpermute_b32 v65, v61, v63
	ds_bpermute_b32 v67, v61, v64
	ds_bpermute_b32 v68, v61, v66
	s_and_saveexec_b64 s[24:25], s[0:1]
	s_cbranch_execz .LBB0_213
	s_waitcnt lgkmcnt(1)
	v_add_f32_e32 v69, v64, v67
	v_add_f32_e32 v63, v63, v65
	v_lshl_add_u64 v[64:65], s[14:15], 0, v[52:53]
	s_waitcnt lgkmcnt(0)
	v_add_f32_e32 v68, v66, v68
	v_add_co_u32_e32 v66, vcc, 0x5be8000, v64
	s_nop 1
	v_addc_co_u32_e32 v67, vcc, 0, v65, vcc
	global_store_dword v[66:67], v63, off sc1
	v_add_co_u32_e32 v66, vcc, 0x5beb000, v64
	s_nop 1
	v_addc_co_u32_e32 v67, vcc, 0, v65, vcc
	v_add_co_u32_e32 v64, vcc, 0x5bee000, v64
	global_store_dword v[66:67], v69, off sc1
	s_nop 0
	v_addc_co_u32_e32 v65, vcc, 0, v65, vcc
	global_store_dword v[64:65], v68, off sc1
	s_branch .LBB0_213

.LBB0_219:
	s_waitcnt lgkmcnt(0)
	v_lshl_add_u64 v[68:69], s[14:15], 0, v[54:55]
	v_add_co_u32_e32 v64, vcc, 0x5a0000, v68
	s_nop 1
	v_addc_co_u32_e32 v65, vcc, 0, v69, vcc
	global_load_dwordx4 v[64:67], v[64:65], off
	v_lshl_add_u64 v[68:69], v[68:69], 0, s[24:25]
	global_load_dwordx4 v[68:71], v[68:69], off offset:16
	s_waitcnt vmcnt(1)
	v_lshlrev_b32_e32 v63, 16, v64
	v_and_b32_e32 v64, 0xffff0000, v64
	v_lshlrev_b32_e32 v72, 16, v65
	v_and_b32_e32 v65, 0xffff0000, v65
	v_mul_f32_e32 v79, v9, v64
	v_mul_f32_e32 v80, v25, v64
	v_mul_f32_e32 v64, v41, v64
	v_lshlrev_b32_e32 v73, 16, v66
	v_and_b32_e32 v66, 0xffff0000, v66
	v_mul_f32_e32 v81, v11, v65
	v_mul_f32_e32 v82, v27, v65
	v_mul_f32_e32 v65, v43, v65
	v_fmac_f32_e32 v79, v8, v63
	v_fmac_f32_e32 v80, v24, v63
	v_fmac_f32_e32 v64, v40, v63
	v_lshlrev_b32_e32 v74, 16, v67
	v_and_b32_e32 v67, 0xffff0000, v67
	v_mul_f32_e32 v83, v1, v66
	v_mul_f32_e32 v84, v17, v66
	v_mul_f32_e32 v66, v33, v66
	v_fmac_f32_e32 v81, v10, v72
	v_fmac_f32_e32 v82, v26, v72
	v_fmac_f32_e32 v65, v42, v72
	v_add_f32_e32 v63, 0, v79
	v_add_f32_e32 v72, 0, v80
	v_add_f32_e32 v64, 0, v64
	s_waitcnt vmcnt(0)
	v_lshlrev_b32_e32 v75, 16, v68
	v_and_b32_e32 v68, 0xffff0000, v68
	v_mul_f32_e32 v85, v3, v67
	v_mul_f32_e32 v86, v19, v67
	v_mul_f32_e32 v67, v35, v67
	v_fmac_f32_e32 v83, v0, v73
	v_fmac_f32_e32 v84, v16, v73
	v_fmac_f32_e32 v66, v32, v73
	v_add_f32_e32 v63, v63, v81
	v_add_f32_e32 v72, v72, v82
	v_add_f32_e32 v64, v64, v65
	v_lshlrev_b32_e32 v76, 16, v69
	v_and_b32_e32 v69, 0xffff0000, v69
	v_mul_f32_e32 v87, v5, v68
	v_mul_f32_e32 v88, v21, v68
	v_mul_f32_e32 v68, v37, v68
	v_fmac_f32_e32 v85, v2, v74
	v_fmac_f32_e32 v86, v18, v74
	v_fmac_f32_e32 v67, v34, v74
	v_add_f32_e32 v63, v63, v83
	v_add_f32_e32 v65, v72, v84
	v_add_f32_e32 v64, v64, v66
	v_lshlrev_b32_e32 v77, 16, v70
	v_and_b32_e32 v70, 0xffff0000, v70
	v_mul_f32_e32 v89, v7, v69
	v_mul_f32_e32 v90, v23, v69
	v_mul_f32_e32 v69, v39, v69
	v_fmac_f32_e32 v87, v4, v75
	v_fmac_f32_e32 v88, v20, v75
	v_fmac_f32_e32 v68, v36, v75
	v_add_f32_e32 v63, v63, v85
	v_add_f32_e32 v65, v65, v86
	v_add_f32_e32 v64, v64, v67
	v_lshlrev_b32_e32 v78, 16, v71
	v_and_b32_e32 v71, 0xffff0000, v71
	v_mul_f32_e32 v91, v13, v70
	v_mul_f32_e32 v92, v29, v70
	v_mul_f32_e32 v70, v45, v70
	v_fmac_f32_e32 v89, v6, v76
	v_fmac_f32_e32 v90, v22, v76
	v_fmac_f32_e32 v69, v38, v76
	v_add_f32_e32 v63, v63, v87
	v_add_f32_e32 v65, v65, v88
	v_add_f32_e32 v64, v64, v68
	v_mul_f32_e32 v93, v15, v71
	v_mul_f32_e32 v94, v31, v71
	v_fmac_f32_e32 v91, v12, v77
	v_fmac_f32_e32 v92, v28, v77
	v_fmac_f32_e32 v70, v44, v77
	v_add_f32_e32 v63, v63, v89
	v_add_f32_e32 v65, v65, v90
	v_add_f32_e32 v64, v64, v69
	v_mul_f32_e32 v66, v47, v71
	v_fmac_f32_e32 v93, v14, v78
	v_fmac_f32_e32 v94, v30, v78
	v_add_f32_e32 v63, v63, v91
	v_add_f32_e32 v65, v65, v92
	v_add_f32_e32 v64, v64, v70
	v_fmac_f32_e32 v66, v46, v78
	v_add_f32_e32 v63, v63, v93
	v_add_f32_e32 v65, v65, v94
	v_add_f32_e32 v64, v64, v66
	s_nop 1
	v_mov_b32_dpp v67, v63 quad_perm:[1,0,3,2] row_mask:0xf bank_mask:0xf
	s_nop 1
	v_mov_b32_dpp v68, v65 quad_perm:[1,0,3,2] row_mask:0xf bank_mask:0xf
	s_nop 1
	v_mov_b32_dpp v66, v64 quad_perm:[1,0,3,2] row_mask:0xf bank_mask:0xf
	s_waitcnt lgkmcnt(0)
	v_add_f32_e32 v63, v63, v67
	s_waitcnt lgkmcnt(0)
	v_add_f32_e32 v65, v65, v68
	s_waitcnt lgkmcnt(0)
	v_add_f32_e32 v64, v64, v66
	s_nop 1
	v_mov_b32_dpp v67, v63 quad_perm:[2,3,0,1] row_mask:0xf bank_mask:0xf
	s_nop 1
	v_mov_b32_dpp v68, v65 quad_perm:[2,3,0,1] row_mask:0xf bank_mask:0xf
	s_nop 1
	v_mov_b32_dpp v66, v64 quad_perm:[2,3,0,1] row_mask:0xf bank_mask:0xf
	s_waitcnt lgkmcnt(0)
	v_add_f32_e32 v63, v63, v67
	s_waitcnt lgkmcnt(0)
	v_add_f32_e32 v65, v65, v68
	s_waitcnt lgkmcnt(0)
	v_add_f32_e32 v64, v64, v66
	s_nop 1
	v_mov_b32_dpp v67, v63 row_half_mirror row_mask:0xf bank_mask:0xf
	s_nop 1
	v_mov_b32_dpp v68, v65 row_half_mirror row_mask:0xf bank_mask:0xf
	s_nop 1
	v_mov_b32_dpp v66, v64 row_half_mirror row_mask:0xf bank_mask:0xf
	s_waitcnt lgkmcnt(0)
	v_add_f32_e32 v63, v63, v67
	s_waitcnt lgkmcnt(0)
	v_add_f32_e32 v65, v65, v68
	s_waitcnt lgkmcnt(0)
	v_add_f32_e32 v64, v64, v66
	s_nop 1
	v_mov_b32_dpp v67, v63 row_mirror row_mask:0xf bank_mask:0xf
	s_nop 1
	v_mov_b32_dpp v68, v65 row_mirror row_mask:0xf bank_mask:0xf
	s_nop 1
	v_mov_b32_dpp v66, v64 row_mirror row_mask:0xf bank_mask:0xf
	s_waitcnt lgkmcnt(0)
	v_add_f32_e32 v63, v63, v67
	s_waitcnt lgkmcnt(0)
	v_add_f32_e32 v65, v65, v68
	s_waitcnt lgkmcnt(0)
	v_add_f32_e32 v69, v64, v66
	ds_bpermute_b32 v67, v59, v63
	ds_bpermute_b32 v68, v59, v65
	ds_bpermute_b32 v70, v59, v69
	s_waitcnt lgkmcnt(2)
	v_add_f32_e32 v63, v63, v67
	s_waitcnt lgkmcnt(1)
	v_add_f32_e32 v65, v65, v68
	s_waitcnt lgkmcnt(0)
	v_add_f32_e32 v67, v69, v70
	ds_bpermute_b32 v64, v61, v63
	ds_bpermute_b32 v66, v61, v65
	ds_bpermute_b32 v68, v61, v67
	s_and_saveexec_b64 s[26:27], s[0:1]
	s_cbranch_execz .LBB0_218
	s_waitcnt lgkmcnt(1)
	v_add_f32_e32 v69, v65, v66
	v_add_f32_e32 v63, v63, v64
	v_lshl_add_u64 v[64:65], s[14:15], 0, v[52:53]
	v_add_co_u32_e32 v66, vcc, 0x5bf1000, v64
	s_waitcnt lgkmcnt(0)
	v_add_f32_e32 v68, v67, v68
	v_addc_co_u32_e32 v67, vcc, 0, v65, vcc
	global_store_dword v[66:67], v63, off sc1
	v_add_co_u32_e32 v66, vcc, 0x5bf4000, v64
	s_nop 1
	v_addc_co_u32_e32 v67, vcc, 0, v65, vcc
	v_add_co_u32_e32 v64, vcc, 0x5bf7000, v64
	global_store_dword v[66:67], v69, off sc1
	s_nop 0
	v_addc_co_u32_e32 v65, vcc, 0, v65, vcc
	global_store_dword v[64:65], v68, off sc1
	s_branch .LBB0_218

.LBB0_224:
	s_waitcnt lgkmcnt(0)
	v_lshl_add_u64 v[68:69], s[14:15], 0, v[54:55]
	v_add_co_u32_e32 v64, vcc, 0xda0000, v68
	s_nop 1
	v_addc_co_u32_e32 v65, vcc, 0, v69, vcc
	global_load_dwordx4 v[64:67], v[64:65], off
	v_lshl_add_u64 v[68:69], v[68:69], 0, s[24:25]
	global_load_dwordx4 v[68:71], v[68:69], off offset:16
	s_waitcnt vmcnt(1)
	v_lshlrev_b32_e32 v63, 16, v64
	v_and_b32_e32 v64, 0xffff0000, v64
	v_lshlrev_b32_e32 v72, 16, v65
	v_and_b32_e32 v65, 0xffff0000, v65
	v_mul_f32_e32 v79, v9, v64
	v_mul_f32_e32 v80, v25, v64
	v_mul_f32_e32 v64, v41, v64
	v_lshlrev_b32_e32 v73, 16, v66
	v_and_b32_e32 v66, 0xffff0000, v66
	v_mul_f32_e32 v81, v11, v65
	v_mul_f32_e32 v82, v27, v65
	v_mul_f32_e32 v65, v43, v65
	v_fmac_f32_e32 v79, v8, v63
	v_fmac_f32_e32 v80, v24, v63
	v_fmac_f32_e32 v64, v40, v63
	v_lshlrev_b32_e32 v74, 16, v67
	v_and_b32_e32 v67, 0xffff0000, v67
	v_mul_f32_e32 v83, v1, v66
	v_mul_f32_e32 v84, v17, v66
	v_mul_f32_e32 v66, v33, v66
	v_fmac_f32_e32 v81, v10, v72
	v_fmac_f32_e32 v82, v26, v72
	v_fmac_f32_e32 v65, v42, v72
	v_add_f32_e32 v63, 0, v79
	v_add_f32_e32 v72, 0, v80
	v_add_f32_e32 v64, 0, v64
	s_waitcnt vmcnt(0)
	v_lshlrev_b32_e32 v75, 16, v68
	v_and_b32_e32 v68, 0xffff0000, v68
	v_mul_f32_e32 v85, v3, v67
	v_mul_f32_e32 v86, v19, v67
	v_mul_f32_e32 v67, v35, v67
	v_fmac_f32_e32 v83, v0, v73
	v_fmac_f32_e32 v84, v16, v73
	v_fmac_f32_e32 v66, v32, v73
	v_add_f32_e32 v63, v63, v81
	v_add_f32_e32 v72, v72, v82
	v_add_f32_e32 v64, v64, v65
	v_lshlrev_b32_e32 v76, 16, v69
	v_and_b32_e32 v69, 0xffff0000, v69
	v_mul_f32_e32 v87, v5, v68
	v_mul_f32_e32 v88, v21, v68
	v_mul_f32_e32 v68, v37, v68
	v_fmac_f32_e32 v85, v2, v74
	v_fmac_f32_e32 v86, v18, v74
	v_fmac_f32_e32 v67, v34, v74
	v_add_f32_e32 v63, v63, v83
	v_add_f32_e32 v65, v72, v84
	v_add_f32_e32 v64, v64, v66
	v_lshlrev_b32_e32 v77, 16, v70
	v_and_b32_e32 v70, 0xffff0000, v70
	v_mul_f32_e32 v89, v7, v69
	v_mul_f32_e32 v90, v23, v69
	v_mul_f32_e32 v69, v39, v69
	v_fmac_f32_e32 v87, v4, v75
	v_fmac_f32_e32 v88, v20, v75
	v_fmac_f32_e32 v68, v36, v75
	v_add_f32_e32 v63, v63, v85
	v_add_f32_e32 v65, v65, v86
	v_add_f32_e32 v64, v64, v67
	v_lshlrev_b32_e32 v78, 16, v71
	v_and_b32_e32 v71, 0xffff0000, v71
	v_mul_f32_e32 v91, v13, v70
	v_mul_f32_e32 v92, v29, v70
	v_mul_f32_e32 v70, v45, v70
	v_fmac_f32_e32 v89, v6, v76
	v_fmac_f32_e32 v90, v22, v76
	v_fmac_f32_e32 v69, v38, v76
	v_add_f32_e32 v63, v63, v87
	v_add_f32_e32 v65, v65, v88
	v_add_f32_e32 v64, v64, v68
	v_mul_f32_e32 v93, v15, v71
	v_mul_f32_e32 v94, v31, v71
	v_fmac_f32_e32 v91, v12, v77
	v_fmac_f32_e32 v92, v28, v77
	v_fmac_f32_e32 v70, v44, v77
	v_add_f32_e32 v63, v63, v89
	v_add_f32_e32 v65, v65, v90
	v_add_f32_e32 v64, v64, v69
	v_mul_f32_e32 v66, v47, v71
	v_fmac_f32_e32 v93, v14, v78
	v_fmac_f32_e32 v94, v30, v78
	v_add_f32_e32 v63, v63, v91
	v_add_f32_e32 v65, v65, v92
	v_add_f32_e32 v64, v64, v70
	v_fmac_f32_e32 v66, v46, v78
	v_add_f32_e32 v63, v63, v93
	v_add_f32_e32 v65, v65, v94
	v_add_f32_e32 v64, v64, v66
	s_nop 1
	v_mov_b32_dpp v67, v63 quad_perm:[1,0,3,2] row_mask:0xf bank_mask:0xf
	s_nop 1
	v_mov_b32_dpp v68, v65 quad_perm:[1,0,3,2] row_mask:0xf bank_mask:0xf
	s_nop 1
	v_mov_b32_dpp v66, v64 quad_perm:[1,0,3,2] row_mask:0xf bank_mask:0xf
	s_waitcnt lgkmcnt(0)
	v_add_f32_e32 v63, v63, v67
	s_waitcnt lgkmcnt(0)
	v_add_f32_e32 v65, v65, v68
	s_waitcnt lgkmcnt(0)
	v_add_f32_e32 v64, v64, v66
	s_nop 1
	v_mov_b32_dpp v67, v63 quad_perm:[2,3,0,1] row_mask:0xf bank_mask:0xf
	s_nop 1
	v_mov_b32_dpp v68, v65 quad_perm:[2,3,0,1] row_mask:0xf bank_mask:0xf
	s_nop 1
	v_mov_b32_dpp v66, v64 quad_perm:[2,3,0,1] row_mask:0xf bank_mask:0xf
	s_waitcnt lgkmcnt(0)
	v_add_f32_e32 v63, v63, v67
	s_waitcnt lgkmcnt(0)
	v_add_f32_e32 v65, v65, v68
	s_waitcnt lgkmcnt(0)
	v_add_f32_e32 v64, v64, v66
	s_nop 1
	v_mov_b32_dpp v67, v63 row_half_mirror row_mask:0xf bank_mask:0xf
	s_nop 1
	v_mov_b32_dpp v68, v65 row_half_mirror row_mask:0xf bank_mask:0xf
	s_nop 1
	v_mov_b32_dpp v66, v64 row_half_mirror row_mask:0xf bank_mask:0xf
	s_waitcnt lgkmcnt(0)
	v_add_f32_e32 v63, v63, v67
	s_waitcnt lgkmcnt(0)
	v_add_f32_e32 v65, v65, v68
	s_waitcnt lgkmcnt(0)
	v_add_f32_e32 v64, v64, v66
	s_nop 1
	v_mov_b32_dpp v67, v63 row_mirror row_mask:0xf bank_mask:0xf
	s_nop 1
	v_mov_b32_dpp v68, v65 row_mirror row_mask:0xf bank_mask:0xf
	s_nop 1
	v_mov_b32_dpp v66, v64 row_mirror row_mask:0xf bank_mask:0xf
	s_waitcnt lgkmcnt(0)
	v_add_f32_e32 v63, v63, v67
	s_waitcnt lgkmcnt(0)
	v_add_f32_e32 v65, v65, v68
	s_waitcnt lgkmcnt(0)
	v_add_f32_e32 v69, v64, v66
	ds_bpermute_b32 v67, v59, v63
	ds_bpermute_b32 v68, v59, v65
	ds_bpermute_b32 v70, v59, v69
	s_waitcnt lgkmcnt(2)
	v_add_f32_e32 v63, v63, v67
	s_waitcnt lgkmcnt(1)
	v_add_f32_e32 v65, v65, v68
	s_waitcnt lgkmcnt(0)
	v_add_f32_e32 v67, v69, v70
	ds_bpermute_b32 v64, v61, v63
	ds_bpermute_b32 v66, v61, v65
	ds_bpermute_b32 v68, v61, v67
	s_and_saveexec_b64 s[26:27], s[0:1]
	s_cbranch_execz .LBB0_223
	s_waitcnt lgkmcnt(1)
	v_add_f32_e32 v69, v65, v66
	v_add_f32_e32 v63, v63, v64
	v_lshl_add_u64 v[64:65], s[14:15], 0, v[52:53]
	v_add_co_u32_e32 v66, vcc, 0x5bfa000, v64
	s_waitcnt lgkmcnt(0)
	v_add_f32_e32 v68, v67, v68
	v_addc_co_u32_e32 v67, vcc, 0, v65, vcc
	global_store_dword v[66:67], v63, off sc1
	v_add_co_u32_e32 v66, vcc, 0x5bfd000, v64
	s_nop 1
	v_addc_co_u32_e32 v67, vcc, 0, v65, vcc
	v_add_co_u32_e32 v64, vcc, 0x5c00000, v64
	global_store_dword v[66:67], v69, off sc1
	s_nop 0
	v_addc_co_u32_e32 v65, vcc, 0, v65, vcc
	global_store_dword v[64:65], v68, off sc1
	s_branch .LBB0_223

.LBB0_231:
	s_waitcnt lgkmcnt(0)
	v_lshl_add_u64 v[70:71], s[14:15], 0, v[52:53]
	v_add_co_u32_e32 v66, vcc, 0x12a0000, v70
	s_nop 1
	v_addc_co_u32_e32 v67, vcc, 0, v71, vcc
	global_load_dwordx4 v[66:69], v[66:67], off
	v_lshl_add_u64 v[70:71], v[70:71], 0, s[24:25]
	global_load_dwordx4 v[70:73], v[70:71], off offset:16
	s_waitcnt vmcnt(1)
	v_lshlrev_b32_e32 v74, 16, v66
	v_and_b32_e32 v66, 0xffff0000, v66
	v_lshlrev_b32_e32 v75, 16, v67
	v_and_b32_e32 v67, 0xffff0000, v67
	v_mul_f32_e32 v82, v9, v66
	v_mul_f32_e32 v83, v25, v66
	v_mul_f32_e32 v66, v41, v66
	v_lshlrev_b32_e32 v76, 16, v68
	v_and_b32_e32 v68, 0xffff0000, v68
	v_mul_f32_e32 v84, v11, v67
	v_mul_f32_e32 v85, v27, v67
	v_mul_f32_e32 v67, v43, v67
	v_fmac_f32_e32 v82, v8, v74
	v_fmac_f32_e32 v83, v24, v74
	v_fmac_f32_e32 v66, v40, v74
	v_lshlrev_b32_e32 v77, 16, v69
	v_and_b32_e32 v69, 0xffff0000, v69
	v_mul_f32_e32 v86, v1, v68
	v_mul_f32_e32 v87, v17, v68
	v_mul_f32_e32 v68, v33, v68
	v_fmac_f32_e32 v84, v10, v75
	v_fmac_f32_e32 v85, v26, v75
	v_fmac_f32_e32 v67, v42, v75
	v_add_f32_e32 v74, 0, v82
	v_add_f32_e32 v75, 0, v83
	v_add_f32_e32 v66, 0, v66
	s_waitcnt vmcnt(0)
	v_lshlrev_b32_e32 v78, 16, v70
	v_and_b32_e32 v70, 0xffff0000, v70
	v_mul_f32_e32 v88, v3, v69
	v_mul_f32_e32 v89, v19, v69
	v_mul_f32_e32 v69, v35, v69
	v_fmac_f32_e32 v86, v0, v76
	v_fmac_f32_e32 v87, v16, v76
	v_fmac_f32_e32 v68, v32, v76
	v_add_f32_e32 v74, v74, v84
	v_add_f32_e32 v75, v75, v85
	v_add_f32_e32 v66, v66, v67
	v_lshlrev_b32_e32 v79, 16, v71
	v_and_b32_e32 v71, 0xffff0000, v71
	v_mul_f32_e32 v90, v5, v70
	v_mul_f32_e32 v91, v21, v70
	v_mul_f32_e32 v70, v37, v70
	v_fmac_f32_e32 v88, v2, v77
	v_fmac_f32_e32 v89, v18, v77
	v_fmac_f32_e32 v69, v34, v77
	v_add_f32_e32 v67, v74, v86
	v_add_f32_e32 v74, v75, v87
	v_add_f32_e32 v66, v66, v68
	v_lshlrev_b32_e32 v80, 16, v72
	v_and_b32_e32 v72, 0xffff0000, v72
	v_mul_f32_e32 v92, v7, v71
	v_mul_f32_e32 v93, v23, v71
	v_mul_f32_e32 v71, v39, v71
	v_fmac_f32_e32 v90, v4, v78
	v_fmac_f32_e32 v91, v20, v78
	v_fmac_f32_e32 v70, v36, v78
	v_add_f32_e32 v67, v67, v88
	v_add_f32_e32 v68, v74, v89
	v_add_f32_e32 v66, v66, v69
	v_lshlrev_b32_e32 v81, 16, v73
	v_and_b32_e32 v73, 0xffff0000, v73
	v_mul_f32_e32 v94, v13, v72
	v_mul_f32_e32 v95, v29, v72
	v_mul_f32_e32 v72, v45, v72
	v_fmac_f32_e32 v92, v6, v79
	v_fmac_f32_e32 v93, v22, v79
	v_fmac_f32_e32 v71, v38, v79
	v_add_f32_e32 v67, v67, v90
	v_add_f32_e32 v68, v68, v91
	v_add_f32_e32 v66, v66, v70
	v_mul_f32_e32 v96, v15, v73
	v_mul_f32_e32 v97, v31, v73
	v_fmac_f32_e32 v94, v12, v80
	v_fmac_f32_e32 v95, v28, v80
	v_fmac_f32_e32 v72, v44, v80
	v_add_f32_e32 v67, v67, v92
	v_add_f32_e32 v68, v68, v93
	v_add_f32_e32 v66, v66, v71
	v_mul_f32_e32 v69, v47, v73
	v_fmac_f32_e32 v96, v14, v81
	v_fmac_f32_e32 v97, v30, v81
	v_add_f32_e32 v67, v67, v94
	v_add_f32_e32 v68, v68, v95
	v_add_f32_e32 v66, v66, v72
	v_fmac_f32_e32 v69, v46, v81
	v_add_f32_e32 v67, v67, v96
	v_add_f32_e32 v68, v68, v97
	v_add_f32_e32 v66, v66, v69
	s_nop 1
	v_mov_b32_dpp v70, v67 quad_perm:[1,0,3,2] row_mask:0xf bank_mask:0xf
	s_nop 1
	v_mov_b32_dpp v71, v68 quad_perm:[1,0,3,2] row_mask:0xf bank_mask:0xf
	s_nop 1
	v_mov_b32_dpp v69, v66 quad_perm:[1,0,3,2] row_mask:0xf bank_mask:0xf
	s_waitcnt lgkmcnt(0)
	v_add_f32_e32 v67, v67, v70
	s_waitcnt lgkmcnt(0)
	v_add_f32_e32 v68, v68, v71
	s_waitcnt lgkmcnt(0)
	v_add_f32_e32 v66, v66, v69
	s_nop 1
	v_mov_b32_dpp v70, v67 quad_perm:[2,3,0,1] row_mask:0xf bank_mask:0xf
	s_nop 1
	v_mov_b32_dpp v71, v68 quad_perm:[2,3,0,1] row_mask:0xf bank_mask:0xf
	s_nop 1
	v_mov_b32_dpp v69, v66 quad_perm:[2,3,0,1] row_mask:0xf bank_mask:0xf
	s_waitcnt lgkmcnt(0)
	v_add_f32_e32 v67, v67, v70
	s_waitcnt lgkmcnt(0)
	v_add_f32_e32 v68, v68, v71
	s_waitcnt lgkmcnt(0)
	v_add_f32_e32 v66, v66, v69
	s_nop 1
	v_mov_b32_dpp v70, v67 row_half_mirror row_mask:0xf bank_mask:0xf
	s_nop 1
	v_mov_b32_dpp v71, v68 row_half_mirror row_mask:0xf bank_mask:0xf
	s_nop 1
	v_mov_b32_dpp v69, v66 row_half_mirror row_mask:0xf bank_mask:0xf
	s_waitcnt lgkmcnt(0)
	v_add_f32_e32 v67, v67, v70
	s_waitcnt lgkmcnt(0)
	v_add_f32_e32 v68, v68, v71
	s_waitcnt lgkmcnt(0)
	v_add_f32_e32 v66, v66, v69
	s_nop 1
	v_mov_b32_dpp v70, v67 row_mirror row_mask:0xf bank_mask:0xf
	s_nop 1
	v_mov_b32_dpp v71, v68 row_mirror row_mask:0xf bank_mask:0xf
	s_nop 1
	v_mov_b32_dpp v69, v66 row_mirror row_mask:0xf bank_mask:0xf
	s_waitcnt lgkmcnt(0)
	v_add_f32_e32 v67, v67, v70
	s_waitcnt lgkmcnt(0)
	v_add_f32_e32 v68, v68, v71
	s_waitcnt lgkmcnt(0)
	v_add_f32_e32 v72, v66, v69
	ds_bpermute_b32 v70, v64, v67
	ds_bpermute_b32 v71, v64, v68
	ds_bpermute_b32 v73, v64, v72
	s_waitcnt lgkmcnt(2)
	v_add_f32_e32 v66, v67, v70
	s_waitcnt lgkmcnt(1)
	v_add_f32_e32 v68, v68, v71
	s_waitcnt lgkmcnt(0)
	v_add_f32_e32 v70, v72, v73
	ds_bpermute_b32 v67, v65, v66
	ds_bpermute_b32 v69, v65, v68
	ds_bpermute_b32 v71, v65, v70
	s_and_saveexec_b64 s[26:27], s[0:1]
	s_cbranch_execz .LBB0_230
	s_waitcnt lgkmcnt(2)
	v_add_f32_e32 v72, v66, v67
	v_lshl_add_u64 v[66:67], s[14:15], 0, v[54:55]
	s_waitcnt lgkmcnt(0)
	v_add_f32_e32 v70, v70, v71
	v_add_f32_e32 v71, v68, v69
	v_add_co_u32_e32 v68, vcc, 0x5c03000, v66
	s_nop 1
	v_addc_co_u32_e32 v69, vcc, 0, v67, vcc
	global_store_dword v[68:69], v72, off sc1
	v_add_co_u32_e32 v68, vcc, 0x5c06000, v66
	s_nop 1
	v_addc_co_u32_e32 v69, vcc, 0, v67, vcc
	v_add_co_u32_e32 v66, vcc, 0x5c09000, v66
	global_store_dword v[68:69], v71, off sc1
	s_nop 0
	v_addc_co_u32_e32 v67, vcc, 0, v67, vcc
	global_store_dword v[66:67], v70, off sc1
	s_branch .LBB0_230

.LBB0_239:
	s_waitcnt lgkmcnt(2)
	global_load_dwordx4 v[78:81], v[60:61], off offset:-16
	s_waitcnt lgkmcnt(0)
	global_load_dwordx4 v[82:85], v[60:61], off
	s_waitcnt vmcnt(1)
	v_lshlrev_b32_e32 v86, 16, v78
	v_and_b32_e32 v78, 0xffff0000, v78
	v_lshlrev_b32_e32 v87, 16, v79
	v_and_b32_e32 v79, 0xffff0000, v79
	v_mul_f32_e32 v94, v9, v78
	v_mul_f32_e32 v95, v25, v78
	v_mul_f32_e32 v78, v41, v78
	v_lshlrev_b32_e32 v88, 16, v80
	v_and_b32_e32 v80, 0xffff0000, v80
	v_mul_f32_e32 v96, v11, v79
	v_mul_f32_e32 v97, v27, v79
	v_mul_f32_e32 v79, v43, v79
	v_fmac_f32_e32 v94, v8, v86
	v_fmac_f32_e32 v95, v24, v86
	v_fmac_f32_e32 v78, v40, v86
	v_lshlrev_b32_e32 v89, 16, v81
	v_and_b32_e32 v81, 0xffff0000, v81
	v_mul_f32_e32 v98, v1, v80
	v_mul_f32_e32 v99, v17, v80
	v_mul_f32_e32 v80, v33, v80
	v_fmac_f32_e32 v96, v10, v87
	v_fmac_f32_e32 v97, v26, v87
	v_fmac_f32_e32 v79, v42, v87
	v_add_f32_e32 v86, 0, v94
	v_add_f32_e32 v87, 0, v95
	v_add_f32_e32 v78, 0, v78
	s_waitcnt vmcnt(0)
	v_lshlrev_b32_e32 v90, 16, v82
	v_and_b32_e32 v82, 0xffff0000, v82
	v_mul_f32_e32 v100, v3, v81
	v_mul_f32_e32 v101, v19, v81
	v_mul_f32_e32 v81, v35, v81
	v_fmac_f32_e32 v98, v0, v88
	v_fmac_f32_e32 v99, v16, v88
	v_fmac_f32_e32 v80, v32, v88
	v_add_f32_e32 v86, v86, v96
	v_add_f32_e32 v87, v87, v97
	v_add_f32_e32 v78, v78, v79
	v_lshlrev_b32_e32 v91, 16, v83
	v_and_b32_e32 v83, 0xffff0000, v83
	v_mul_f32_e32 v102, v5, v82
	v_mul_f32_e32 v103, v21, v82
	v_mul_f32_e32 v82, v37, v82
	v_fmac_f32_e32 v100, v2, v89
	v_fmac_f32_e32 v101, v18, v89
	v_fmac_f32_e32 v81, v34, v89
	v_add_f32_e32 v79, v86, v98
	v_add_f32_e32 v86, v87, v99
	v_add_f32_e32 v78, v78, v80
	v_lshlrev_b32_e32 v92, 16, v84
	v_and_b32_e32 v84, 0xffff0000, v84
	v_mul_f32_e32 v104, v7, v83
	v_mul_f32_e32 v105, v23, v83
	v_mul_f32_e32 v83, v39, v83
	v_fmac_f32_e32 v102, v4, v90
	v_fmac_f32_e32 v103, v20, v90
	v_fmac_f32_e32 v82, v36, v90
	v_add_f32_e32 v79, v79, v100
	v_add_f32_e32 v80, v86, v101
	v_add_f32_e32 v78, v78, v81
	v_lshlrev_b32_e32 v93, 16, v85
	v_and_b32_e32 v85, 0xffff0000, v85
	v_mul_f32_e32 v106, v13, v84
	v_mul_f32_e32 v107, v29, v84
	v_mul_f32_e32 v84, v45, v84
	v_fmac_f32_e32 v104, v6, v91
	v_fmac_f32_e32 v105, v22, v91
	v_fmac_f32_e32 v83, v38, v91
	v_add_f32_e32 v79, v79, v102
	v_add_f32_e32 v80, v80, v103
	v_add_f32_e32 v78, v78, v82
	v_mul_f32_e32 v108, v15, v85
	v_mul_f32_e32 v109, v31, v85
	v_mul_f32_e32 v85, v47, v85
	v_fmac_f32_e32 v106, v12, v92
	v_fmac_f32_e32 v107, v28, v92
	v_fmac_f32_e32 v84, v44, v92
	v_add_f32_e32 v79, v79, v104
	v_add_f32_e32 v80, v80, v105
	v_add_f32_e32 v78, v78, v83
	v_fmac_f32_e32 v108, v14, v93
	v_fmac_f32_e32 v109, v30, v93
	v_fmac_f32_e32 v85, v46, v93
	v_add_f32_e32 v79, v79, v106
	v_add_f32_e32 v80, v80, v107
	v_add_f32_e32 v78, v78, v84
	v_add_f32_e32 v79, v79, v108
	v_add_f32_e32 v80, v80, v109
	v_add_f32_e32 v78, v78, v85
	s_nop 1
	v_mov_b32_dpp v81, v79 quad_perm:[1,0,3,2] row_mask:0xf bank_mask:0xf
	s_nop 1
	v_mov_b32_dpp v82, v80 quad_perm:[1,0,3,2] row_mask:0xf bank_mask:0xf
	s_nop 1
	v_mov_b32_dpp v83, v78 quad_perm:[1,0,3,2] row_mask:0xf bank_mask:0xf
	s_waitcnt lgkmcnt(0)
	v_add_f32_e32 v79, v79, v81
	s_waitcnt lgkmcnt(0)
	v_add_f32_e32 v80, v80, v82
	s_waitcnt lgkmcnt(0)
	v_add_f32_e32 v78, v78, v83
	s_nop 1
	v_mov_b32_dpp v81, v79 quad_perm:[2,3,0,1] row_mask:0xf bank_mask:0xf
	s_nop 1
	v_mov_b32_dpp v82, v80 quad_perm:[2,3,0,1] row_mask:0xf bank_mask:0xf
	s_nop 1
	v_mov_b32_dpp v83, v78 quad_perm:[2,3,0,1] row_mask:0xf bank_mask:0xf
	s_waitcnt lgkmcnt(0)
	v_add_f32_e32 v79, v79, v81
	s_waitcnt lgkmcnt(0)
	v_add_f32_e32 v80, v80, v82
	s_waitcnt lgkmcnt(0)
	v_add_f32_e32 v78, v78, v83
	s_nop 1
	v_mov_b32_dpp v81, v79 row_half_mirror row_mask:0xf bank_mask:0xf
	s_nop 1
	v_mov_b32_dpp v82, v80 row_half_mirror row_mask:0xf bank_mask:0xf
	s_nop 1
	v_mov_b32_dpp v83, v78 row_half_mirror row_mask:0xf bank_mask:0xf
	s_waitcnt lgkmcnt(0)
	v_add_f32_e32 v79, v79, v81
	s_waitcnt lgkmcnt(0)
	v_add_f32_e32 v80, v80, v82
	s_waitcnt lgkmcnt(0)
	v_add_f32_e32 v78, v78, v83
	s_nop 1
	v_mov_b32_dpp v81, v79 row_mirror row_mask:0xf bank_mask:0xf
	s_nop 1
	v_mov_b32_dpp v82, v80 row_mirror row_mask:0xf bank_mask:0xf
	s_nop 1
	v_mov_b32_dpp v83, v78 row_mirror row_mask:0xf bank_mask:0xf
	s_waitcnt lgkmcnt(0)
	v_add_f32_e32 v79, v79, v81
	s_waitcnt lgkmcnt(0)
	v_add_f32_e32 v80, v80, v82
	s_waitcnt lgkmcnt(0)
	v_add_f32_e32 v81, v78, v83
	ds_bpermute_b32 v78, v75, v79
	ds_bpermute_b32 v82, v75, v80
	ds_bpermute_b32 v83, v75, v81
	s_waitcnt lgkmcnt(2)
	v_add_f32_e32 v78, v79, v78
	s_waitcnt lgkmcnt(1)
	v_add_f32_e32 v79, v80, v82
	s_waitcnt lgkmcnt(0)
	v_add_f32_e32 v81, v81, v83
	ds_bpermute_b32 v80, v76, v78
	ds_bpermute_b32 v82, v76, v79
	ds_bpermute_b32 v83, v76, v81
	s_and_saveexec_b64 s[36:37], s[4:5]
	s_cbranch_execz .LBB0_238
	s_waitcnt lgkmcnt(2)
	v_add_f32_e32 v78, v78, v80
	global_store_dword v[62:63], v78, off sc1
	v_add_co_u32_e32 v78, vcc, 0x5000, v62
	s_waitcnt lgkmcnt(1)
	v_add_f32_e32 v82, v79, v82
	v_addc_co_u32_e32 v79, vcc, 0, v63, vcc
	global_store_dword v[78:79], v82, off offset:2048 sc1
	v_add_co_u32_e32 v78, vcc, 0xb000, v62
	s_waitcnt lgkmcnt(0)
	v_add_f32_e32 v81, v81, v83
	v_addc_co_u32_e32 v79, vcc, 0, v63, vcc
	global_store_dword v[78:79], v81, off sc1
	s_branch .LBB0_238

.LBB0_266:
	v_add_u32_e32 v164, s76, v173
	v_and_b32_e32 v222, 31, v199
	v_bfe_u32 v223, v199, 5, 1
	v_lshlrev_b32_e32 v224, 2, v223
	v_sub_u32_e32 v222, v222, v224
	v_add_u32_e32 v224, s76, v173
	v_add_lshl_u32 v222, v222, v224, 2
	v_lshlrev_b32_e32 v223, 4, v223
	global_load_dword v194, v222, s[18:19]
	v_add_u32_e32 v224, 0x10000, v222
	global_load_dword v195, v224, s[18:19]
	v_add_u32_e32 v224, 0x20000, v222
	global_load_dword v196, v224, s[18:19]
	v_add_u32_e32 v224, 0x30000, v222
	global_load_dword v197, v224, s[18:19]
	v_add_u32_e32 v224, 0x40000, v222
	global_load_dword v202, v224, s[18:19]
	v_add_u32_e32 v224, 0x50000, v222
	global_load_dword v203, v224, s[18:19]
	v_add_u32_e32 v224, 0x60000, v222
	global_load_dword v204, v224, s[18:19]
	v_add_u32_e32 v224, 0x70000, v222
	global_load_dword v205, v224, s[18:19]
	s_waitcnt vmcnt(0)
	v_add_f32_e32 v194, v194, v195
	v_add_f32_e32 v196, v196, v197
	v_add_f32_e32 v202, v202, v203
	v_add_f32_e32 v204, v204, v205
	v_add_f32_e32 v194, v194, v196
	v_add_f32_e32 v202, v202, v204
	v_add_f32_e32 v194, v194, v202
	v_fmamk_f32 v194, v194, 0x3a800000, v209
	v_rsq_f32_e32 v194, v194
	s_nop 1
	ds_bpermute_b32 v225, v223, v194
	ds_bpermute_b32 v230, v223, v194 offset:4
	ds_bpermute_b32 v231, v223, v194 offset:8
	ds_bpermute_b32 v232, v223, v194 offset:12
	ds_bpermute_b32 v233, v223, v194 offset:32
	ds_bpermute_b32 v234, v223, v194 offset:36
	ds_bpermute_b32 v235, v223, v194 offset:40
	ds_bpermute_b32 v236, v223, v194 offset:44
	ds_bpermute_b32 v237, v223, v194 offset:64
	ds_bpermute_b32 v238, v223, v194 offset:68
	ds_bpermute_b32 v239, v223, v194 offset:72
	ds_bpermute_b32 v240, v223, v194 offset:76
	ds_bpermute_b32 v241, v223, v194 offset:96
	ds_bpermute_b32 v242, v223, v194 offset:100
	ds_bpermute_b32 v243, v223, v194 offset:104
	ds_bpermute_b32 v244, v223, v194 offset:108
	s_waitcnt lgkmcnt(0)
	s_lshl_b64 s[80:81], s[80:81], 2
	s_add_u32 s80, s84, s80
	s_addc_u32 s81, s85, s81
	s_cmp_gt_i32 s95, 23
	v_or_b32_e32 v92, 16, v164
	v_ashrrev_i32_e32 v93, 31, v92
	v_lshl_add_u64 v[92:93], v[92:93], 2, s[18:19]
	v_or_b32_e32 v68, 24, v164
	v_add_co_u32_e32 v94, vcc, s91, v92
	v_ashrrev_i32_e32 v69, 31, v68
	s_nop 0
	v_addc_co_u32_e32 v95, vcc, 0, v93, vcc
	v_lshl_add_u64 v[80:81], v[68:69], 2, s[18:19]
	v_add_co_u32_e32 v88, vcc, s90, v80
	s_nop 1
	v_addc_co_u32_e32 v89, vcc, 0, v81, vcc
	v_add_co_u32_e32 v84, vcc, s91, v80
	s_nop 1
	v_addc_co_u32_e32 v85, vcc, 0, v81, vcc
	v_add_co_u32_e32 v80, vcc, s92, v80
	s_nop 1
	v_addc_co_u32_e32 v81, vcc, 0, v81, vcc
	v_or_b32_e32 v76, s78, v156
	v_ashrrev_i32_e32 v77, 31, v76
	v_lshl_add_u64 v[64:65], v[76:77], 2, s[80:81]
	global_load_dword v81, v[64:65], off
	global_load_dword v80, v[64:65], off offset:128
	global_load_dword v82, v[64:65], off offset:256
	global_load_dword v83, v[64:65], off offset:384
	v_mov_b32_e32 v65, v48
	v_mov_b32_e32 v48, v33
	v_mov_b32_e32 v33, v50
	v_mov_b32_e32 v50, v35
	s_mov_b64 s[80:81], -1
	v_mov_b32_e32 v94, v234
	v_mov_b32_e32 v96, v235
	v_mov_b32_e32 v98, v236
	v_mov_b32_e32 v100, v237
	v_mov_b32_e32 v84, v225
	v_mov_b32_e32 v102, v238
	v_mov_b32_e32 v86, v230
	v_mov_b32_e32 v104, v239
	v_mov_b32_e32 v88, v231
	v_mov_b32_e32 v106, v240
	v_mov_b32_e32 v90, v232
	v_mov_b32_e32 v108, v241
	v_mov_b32_e32 v92, v233
	v_mov_b32_e32 v110, v242
	v_mov_b32_e32 v112, v243
	v_mov_b32_e32 v114, v244
	v_mov_b32_e32 v64, v32
	v_mov_b32_e32 v32, v34
	s_waitcnt vmcnt(2)
	v_pk_fma_f32 v[72:73], v[32:33], v[88:89], v[80:81] op_sel_hi:[1,0,1]
	v_mov_b32_e32 v32, v36
	v_mov_b32_e32 v33, v52
	v_pk_fma_f32 v[68:69], v[32:33], v[92:93], v[80:81] op_sel_hi:[1,0,1]
	v_mov_b32_e32 v32, v38
	v_mov_b32_e32 v33, v54
	v_pk_fma_f32 v[78:79], v[64:65], v[84:85], v[80:81] op_sel_hi:[1,0,1]
	v_mov_b32_e32 v52, v37
	v_pk_fma_f32 v[64:65], v[32:33], v[96:97], v[80:81] op_sel_hi:[1,0,1]
	v_mov_b32_e32 v32, v40
	v_mov_b32_e32 v33, v56
	v_pk_fma_f32 v[66:67], v[52:53], v[94:95], v[80:81] op_sel_hi:[1,0,1]
	v_pk_fma_f32 v[52:53], v[32:33], v[100:101], v[80:81] op_sel_hi:[1,0,1]
	v_mov_b32_e32 v32, v42
	v_mov_b32_e32 v33, v58
	v_pk_fma_f32 v[74:75], v[48:49], v[86:87], v[80:81] op_sel_hi:[1,0,1]
	v_pk_fma_f32 v[48:49], v[32:33], v[104:105], v[80:81] op_sel_hi:[1,0,1]
	v_mov_b32_e32 v32, v44
	v_mov_b32_e32 v33, v60
	v_mov_b32_e32 v54, v39
	v_mov_b32_e32 v56, v41
	v_mov_b32_e32 v58, v43
	v_pk_fma_f32 v[38:39], v[32:33], v[108:109], v[80:81] op_sel_hi:[1,0,1]
	v_mov_b32_e32 v60, v45
	v_mov_b32_e32 v32, v46
	v_mov_b32_e32 v33, v62
	v_mov_b32_e32 v62, v47
	v_pk_fma_f32 v[70:71], v[50:51], v[90:91], v[80:81] op_sel_hi:[1,0,1]
	v_pk_fma_f32 v[54:55], v[54:55], v[98:99], v[80:81] op_sel_hi:[1,0,1]
	v_pk_fma_f32 v[50:51], v[56:57], v[102:103], v[80:81] op_sel_hi:[1,0,1]
	v_pk_fma_f32 v[40:41], v[58:59], v[106:107], v[80:81] op_sel_hi:[1,0,1]
	v_pk_fma_f32 v[36:37], v[60:61], v[110:111], v[80:81] op_sel_hi:[1,0,1]
	v_pk_fma_f32 v[34:35], v[32:33], v[112:113], v[80:81] op_sel_hi:[1,0,1]
	v_pk_fma_f32 v[32:33], v[62:63], v[114:115], v[80:81] op_sel_hi:[1,0,1]
	s_waitcnt vmcnt(1)
	v_fma_f32 v57, v16, v84, v82
	v_fma_f32 v47, v17, v86, v82
	v_fma_f32 v46, v18, v88, v82
	v_fma_f32 v45, v19, v90, v82
	v_fma_f32 v44, v20, v92, v82
	v_fma_f32 v43, v21, v94, v82
	v_fma_f32 v42, v22, v96, v82
	v_fma_f32 v23, v23, v98, v82
	v_fma_f32 v22, v24, v100, v82
	v_fma_f32 v21, v25, v102, v82
	v_fma_f32 v20, v26, v104, v82
	v_fma_f32 v19, v27, v106, v82
	v_fma_f32 v18, v28, v108, v82
	v_fma_f32 v17, v29, v110, v82
	v_fma_f32 v16, v30, v112, v82
	v_fmac_f32_e32 v82, v31, v114
	s_waitcnt vmcnt(0)
	v_fma_f32 v56, v0, v84, v83
	v_fma_f32 v31, v1, v86, v83
	v_fma_f32 v30, v2, v88, v83
	v_fma_f32 v29, v3, v90, v83
	v_fma_f32 v28, v4, v92, v83
	v_fma_f32 v27, v5, v94, v83
	v_fma_f32 v26, v6, v96, v83
	v_fma_f32 v25, v7, v98, v83
	v_fma_f32 v24, v8, v100, v83
	v_fma_f32 v9, v9, v102, v83
	v_fma_f32 v8, v10, v104, v83
	v_fma_f32 v7, v11, v106, v83
	v_fma_f32 v6, v12, v108, v83
	v_fma_f32 v5, v13, v110, v83
	v_fma_f32 v4, v14, v112, v83
	v_fmac_f32_e32 v83, v15, v114
	s_cbranch_scc0 .LBB0_496
	v_cndmask_b32_e64 v0, 0, 1, s[4:5]
	s_cmp_gt_u32 s10, 4
	v_cmp_ne_u32_e64 s[4:5], 1, v0
	s_cbranch_scc0 .LBB0_333
	v_mov_b32_e32 v0, s93
	ds_read_b64 v[0:1], v0
	v_and_b32_e32 v11, 64, v214
	v_xor_b32_e32 v10, 1, v214
	v_add_u32_e32 v13, 64, v11
	v_pk_mul_f32 v[2:3], v[78:79], v[78:79]
	s_waitcnt lgkmcnt(0)
	v_readfirstlane_b32 s80, v0
	v_readfirstlane_b32 s81, v1
	s_nop 4
	global_load_dword v1, v210, s[80:81] offset:1280
	global_load_dword v0, v210, s[80:81] offset:1408
	v_cmp_lt_i32_e32 vcc, v10, v13
	v_add_f32_e32 v2, v3, v2
	v_xor_b32_e32 v11, 4, v214
	v_cndmask_b32_e32 v3, v214, v10, vcc
	v_lshlrev_b32_e32 v14, 2, v3
	s_nop 1
	v_mov_b32_dpp v3, v2 quad_perm:[1,0,3,2] row_mask:0xf bank_mask:0xf
	v_xor_b32_e32 v10, 2, v214
	v_cmp_lt_i32_e32 vcc, v10, v13
	v_xor_b32_e32 v12, 8, v214
	v_xor_b32_e32 v15, 16, v214
	v_cndmask_b32_e32 v10, v214, v10, vcc
	v_lshlrev_b32_e32 v10, 2, v10
	s_waitcnt lgkmcnt(0)
	v_add_f32_e32 v2, v2, v3
	s_nop 1
	v_mov_b32_dpp v3, v2 quad_perm:[2,3,0,1] row_mask:0xf bank_mask:0xf
	v_cmp_lt_i32_e32 vcc, v11, v13
	s_mov_b64 s[80:81], -1
	s_waitcnt lgkmcnt(0)
	v_add_f32_e32 v2, v2, v3
	v_cndmask_b32_e32 v11, v214, v11, vcc
	v_lshlrev_b32_e32 v11, 2, v11
	s_nop 1
	v_mov_b32_dpp v3, v2 row_half_mirror row_mask:0xf bank_mask:0xf
	v_cmp_lt_i32_e32 vcc, v12, v13
	s_waitcnt lgkmcnt(0)
	v_add_f32_e32 v2, v2, v3
	v_cndmask_b32_e32 v12, v214, v12, vcc
	v_lshlrev_b32_e32 v12, 2, v12
	s_nop 1
	v_mov_b32_dpp v3, v2 row_mirror row_mask:0xf bank_mask:0xf
	v_cmp_lt_i32_e32 vcc, v15, v13
	s_waitcnt lgkmcnt(0)
	v_add_f32_e32 v2, v2, v3
	v_cndmask_b32_e32 v13, v214, v15, vcc
	v_lshlrev_b32_e32 v13, 2, v13
	ds_bpermute_b32 v3, v13, v2
	s_and_b64 vcc, exec, s[4:5]
	s_waitcnt lgkmcnt(0)
	v_add_f32_e32 v2, v2, v3
	v_fmamk_f32 v2, v2, 0x3c800000, v209
	v_rsq_f32_e32 v2, v2
	s_waitcnt vmcnt(0)
	v_pk_mul_f32 v[2:3], v[0:1], v[2:3] op_sel_hi:[1,0]
	s_nop 0
	v_pk_mul_f32 v[2:3], v[78:79], v[2:3]
	s_cbranch_vccnz .LBB0_270
	v_lshl_or_b32 v58, v164, 6, v156
	v_ashrrev_i32_e32 v59, 31, v58
	v_lshl_add_u64 v[58:59], v[58:59], 2, s[24:25]
	s_mov_b64 s[80:81], 0
	global_store_dword v[58:59], v3, off sc1
	global_store_dword v[58:59], v2, off offset:128 sc1

.LBB0_272:
	v_cvt_pk_bf16_f32 v60, v2, s0
	v_add_u32_e32 v2, s11, v173
	v_mul_lo_u32 v61, v2, s94
	v_or_b32_e32 v2, v61, v174
	v_cvt_pk_bf16_f32 v15, v3, s0
	v_ashrrev_i32_e32 v3, 31, v2
	v_lshl_add_u64 v[2:3], v[2:3], 1, s[22:23]
	global_store_short v[2:3], v15, off sc1
	v_or_b32_e32 v2, v61, v175
	v_ashrrev_i32_e32 v3, 31, v2
	v_lshl_add_u64 v[2:3], v[2:3], 1, s[22:23]
	v_or_b32_e32 v58, 0xc0, v61
	global_store_short v[2:3], v60, off sc1
	v_add_u32_e32 v2, v58, v174
	v_ashrrev_i32_e32 v3, 31, v2
	v_lshl_add_u64 v[2:3], v[2:3], 1, s[22:23]
	global_store_short v[2:3], v15, off sc1
	v_add_u32_e32 v2, v58, v175
	v_ashrrev_i32_e32 v3, 31, v2
	v_lshl_add_u64 v[2:3], v[2:3], 1, s[22:23]
	v_or_b32_e32 v58, 0x180, v61
	global_store_short v[2:3], v60, off sc1
	v_add_u32_e32 v2, v58, v174
	v_ashrrev_i32_e32 v3, 31, v2
	v_lshl_add_u64 v[2:3], v[2:3], 1, s[22:23]
	global_store_short v[2:3], v15, off sc1
	v_add_u32_e32 v2, v58, v175
	v_ashrrev_i32_e32 v3, 31, v2
	v_lshl_add_u64 v[2:3], v[2:3], 1, s[22:23]
	v_add_u32_e32 v58, 0x240, v61
	global_store_short v[2:3], v60, off sc1
	v_or_b32_e32 v2, v58, v174
	v_ashrrev_i32_e32 v3, 31, v2
	v_lshl_add_u64 v[2:3], v[2:3], 1, s[22:23]
	global_store_short v[2:3], v15, off sc1
	v_or_b32_e32 v2, v58, v175
	v_ashrrev_i32_e32 v3, 31, v2
	v_lshl_add_u64 v[2:3], v[2:3], 1, s[22:23]
	v_add_u32_e32 v58, 0x300, v61
	global_store_short v[2:3], v60, off sc1
	v_or_b32_e32 v2, v58, v174
	v_ashrrev_i32_e32 v3, 31, v2
	v_lshl_add_u64 v[2:3], v[2:3], 1, s[22:23]
	global_store_short v[2:3], v15, off sc1
	v_or_b32_e32 v2, v58, v175
	v_pk_mul_f32 v[58:59], v[74:75], v[74:75]
	v_ashrrev_i32_e32 v3, 31, v2
	v_add_f32_e32 v58, v59, v58
	s_nop 1
	v_mov_b32_dpp v59, v58 quad_perm:[1,0,3,2] row_mask:0xf bank_mask:0xf
	v_lshl_add_u64 v[2:3], v[2:3], 1, s[22:23]
	v_add_u32_e32 v62, 0x3c0, v61
	global_store_short v[2:3], v60, off sc1
	v_add_u32_e32 v2, v62, v174
	s_waitcnt lgkmcnt(0)
	v_add_f32_e32 v58, v58, v59
	s_nop 1
	v_mov_b32_dpp v59, v58 quad_perm:[2,3,0,1] row_mask:0xf bank_mask:0xf
	v_ashrrev_i32_e32 v3, 31, v2
	v_lshl_add_u64 v[2:3], v[2:3], 1, s[22:23]
	global_store_short v[2:3], v15, off sc1
	v_add_u32_e32 v2, v62, v175
	s_waitcnt lgkmcnt(0)
	v_add_f32_e32 v58, v58, v59
	s_nop 1
	v_mov_b32_dpp v59, v58 row_half_mirror row_mask:0xf bank_mask:0xf
	v_ashrrev_i32_e32 v3, 31, v2
	v_lshl_add_u64 v[2:3], v[2:3], 1, s[22:23]
	v_add_u32_e32 v62, 0x480, v61
	global_store_short v[2:3], v60, off sc1
	s_waitcnt lgkmcnt(0)
	v_add_f32_e32 v58, v58, v59
	s_nop 1
	v_mov_b32_dpp v59, v58 row_mirror row_mask:0xf bank_mask:0xf
	v_add_u32_e32 v2, v62, v174
	v_ashrrev_i32_e32 v3, 31, v2
	v_lshl_add_u64 v[2:3], v[2:3], 1, s[22:23]
	global_store_short v[2:3], v15, off sc1
	v_add_u32_e32 v2, v62, v175
	s_waitcnt lgkmcnt(0)
	v_add_f32_e32 v58, v58, v59
	v_ashrrev_i32_e32 v3, 31, v2
	ds_bpermute_b32 v59, v13, v58
	v_lshl_add_u64 v[2:3], v[2:3], 1, s[22:23]
	v_add_u32_e32 v61, 0x540, v61
	global_store_short v[2:3], v60, off sc1
	v_or_b32_e32 v2, v61, v174
	v_ashrrev_i32_e32 v3, 31, v2
	v_lshl_add_u64 v[2:3], v[2:3], 1, s[22:23]
	global_store_short v[2:3], v15, off sc1
	s_waitcnt lgkmcnt(0)
	v_add_f32_e32 v3, v58, v59
	v_fmamk_f32 v3, v3, 0x3c800000, v209
	v_rsq_f32_e32 v58, v3
	v_or_b32_e32 v2, v61, v175
	v_ashrrev_i32_e32 v3, 31, v2
	v_lshl_add_u64 v[2:3], v[2:3], 1, s[22:23]
	global_store_short v[2:3], v60, off sc1
	v_pk_mul_f32 v[2:3], v[0:1], v[58:59] op_sel_hi:[1,0]
	s_and_b64 vcc, exec, s[4:5]
	v_pk_mul_f32 v[2:3], v[74:75], v[2:3]
	s_mov_b64 s[80:81], -1
	s_cbranch_vccnz .LBB0_274
	v_add_u32_e32 v15, s76, v176
	v_lshl_or_b32 v58, v15, 6, v156
	v_ashrrev_i32_e32 v59, 31, v58
	v_lshl_add_u64 v[58:59], v[58:59], 2, s[24:25]
	s_mov_b64 s[80:81], 0
	global_store_dword v[58:59], v3, off sc1
	global_store_dword v[58:59], v2, off offset:128 sc1

.LBB0_276:
	v_cvt_pk_bf16_f32 v60, v2, s0
	v_add_u32_e32 v2, s11, v176
	v_mul_lo_u32 v61, v2, s94
	v_or_b32_e32 v2, v61, v174
	v_cvt_pk_bf16_f32 v15, v3, s0
	v_ashrrev_i32_e32 v3, 31, v2
	v_lshl_add_u64 v[2:3], v[2:3], 1, s[22:23]
	global_store_short v[2:3], v15, off sc1
	v_or_b32_e32 v2, v61, v175
	v_ashrrev_i32_e32 v3, 31, v2
	v_lshl_add_u64 v[2:3], v[2:3], 1, s[22:23]
	v_or_b32_e32 v58, 0xc0, v61
	global_store_short v[2:3], v60, off sc1
	v_add_u32_e32 v2, v58, v174
	v_ashrrev_i32_e32 v3, 31, v2
	v_lshl_add_u64 v[2:3], v[2:3], 1, s[22:23]
	global_store_short v[2:3], v15, off sc1
	v_add_u32_e32 v2, v58, v175
	v_ashrrev_i32_e32 v3, 31, v2
	v_lshl_add_u64 v[2:3], v[2:3], 1, s[22:23]
	v_or_b32_e32 v58, 0x180, v61
	global_store_short v[2:3], v60, off sc1
	v_add_u32_e32 v2, v58, v174
	v_ashrrev_i32_e32 v3, 31, v2
	v_lshl_add_u64 v[2:3], v[2:3], 1, s[22:23]
	global_store_short v[2:3], v15, off sc1
	v_add_u32_e32 v2, v58, v175
	v_ashrrev_i32_e32 v3, 31, v2
	v_lshl_add_u64 v[2:3], v[2:3], 1, s[22:23]
	v_add_u32_e32 v58, 0x240, v61
	global_store_short v[2:3], v60, off sc1
	v_or_b32_e32 v2, v58, v174
	v_ashrrev_i32_e32 v3, 31, v2
	v_lshl_add_u64 v[2:3], v[2:3], 1, s[22:23]
	global_store_short v[2:3], v15, off sc1
	v_or_b32_e32 v2, v58, v175
	v_ashrrev_i32_e32 v3, 31, v2
	v_lshl_add_u64 v[2:3], v[2:3], 1, s[22:23]
	v_add_u32_e32 v58, 0x300, v61
	global_store_short v[2:3], v60, off sc1
	v_or_b32_e32 v2, v58, v174
	v_ashrrev_i32_e32 v3, 31, v2
	v_lshl_add_u64 v[2:3], v[2:3], 1, s[22:23]
	global_store_short v[2:3], v15, off sc1
	v_or_b32_e32 v2, v58, v175
	v_pk_mul_f32 v[58:59], v[72:73], v[72:73]
	v_ashrrev_i32_e32 v3, 31, v2
	v_add_f32_e32 v58, v59, v58
	s_nop 1
	v_mov_b32_dpp v59, v58 quad_perm:[1,0,3,2] row_mask:0xf bank_mask:0xf
	v_lshl_add_u64 v[2:3], v[2:3], 1, s[22:23]
	v_add_u32_e32 v62, 0x3c0, v61
	global_store_short v[2:3], v60, off sc1
	v_add_u32_e32 v2, v62, v174
	s_waitcnt lgkmcnt(0)
	v_add_f32_e32 v58, v58, v59
	s_nop 1
	v_mov_b32_dpp v59, v58 quad_perm:[2,3,0,1] row_mask:0xf bank_mask:0xf
	v_ashrrev_i32_e32 v3, 31, v2
	v_lshl_add_u64 v[2:3], v[2:3], 1, s[22:23]
	global_store_short v[2:3], v15, off sc1
	v_add_u32_e32 v2, v62, v175
	s_waitcnt lgkmcnt(0)
	v_add_f32_e32 v58, v58, v59
	s_nop 1
	v_mov_b32_dpp v59, v58 row_half_mirror row_mask:0xf bank_mask:0xf
	v_ashrrev_i32_e32 v3, 31, v2
	v_lshl_add_u64 v[2:3], v[2:3], 1, s[22:23]
	v_add_u32_e32 v62, 0x480, v61
	global_store_short v[2:3], v60, off sc1
	s_waitcnt lgkmcnt(0)
	v_add_f32_e32 v58, v58, v59
	s_nop 1
	v_mov_b32_dpp v59, v58 row_mirror row_mask:0xf bank_mask:0xf
	v_add_u32_e32 v2, v62, v174
	v_ashrrev_i32_e32 v3, 31, v2
	v_lshl_add_u64 v[2:3], v[2:3], 1, s[22:23]
	global_store_short v[2:3], v15, off sc1
	v_add_u32_e32 v2, v62, v175
	s_waitcnt lgkmcnt(0)
	v_add_f32_e32 v58, v58, v59
	v_ashrrev_i32_e32 v3, 31, v2
	ds_bpermute_b32 v59, v13, v58
	v_lshl_add_u64 v[2:3], v[2:3], 1, s[22:23]
	v_add_u32_e32 v61, 0x540, v61
	global_store_short v[2:3], v60, off sc1
	v_or_b32_e32 v2, v61, v174
	v_ashrrev_i32_e32 v3, 31, v2
	v_lshl_add_u64 v[2:3], v[2:3], 1, s[22:23]
	global_store_short v[2:3], v15, off sc1
	s_waitcnt lgkmcnt(0)
	v_add_f32_e32 v3, v58, v59
	v_fmamk_f32 v3, v3, 0x3c800000, v209
	v_rsq_f32_e32 v58, v3
	v_or_b32_e32 v2, v61, v175
	v_ashrrev_i32_e32 v3, 31, v2
	v_lshl_add_u64 v[2:3], v[2:3], 1, s[22:23]
	global_store_short v[2:3], v60, off sc1
	v_pk_mul_f32 v[2:3], v[0:1], v[58:59] op_sel_hi:[1,0]
	s_and_b64 vcc, exec, s[4:5]
	v_pk_mul_f32 v[2:3], v[72:73], v[2:3]
	s_mov_b64 s[80:81], -1
	s_cbranch_vccnz .LBB0_278
	v_add_u32_e32 v15, s76, v177
	v_lshl_or_b32 v58, v15, 6, v156
	v_ashrrev_i32_e32 v59, 31, v58
	v_lshl_add_u64 v[58:59], v[58:59], 2, s[24:25]
	s_mov_b64 s[80:81], 0
	global_store_dword v[58:59], v3, off sc1
	global_store_dword v[58:59], v2, off offset:128 sc1

.LBB0_280:
	v_cvt_pk_bf16_f32 v60, v2, s0
	v_add_u32_e32 v2, s11, v177
	v_mul_lo_u32 v61, v2, s94
	v_or_b32_e32 v2, v61, v174
	v_cvt_pk_bf16_f32 v15, v3, s0
	v_ashrrev_i32_e32 v3, 31, v2
	v_lshl_add_u64 v[2:3], v[2:3], 1, s[22:23]
	global_store_short v[2:3], v15, off sc1
	v_or_b32_e32 v2, v61, v175
	v_ashrrev_i32_e32 v3, 31, v2
	v_lshl_add_u64 v[2:3], v[2:3], 1, s[22:23]
	v_or_b32_e32 v58, 0xc0, v61
	global_store_short v[2:3], v60, off sc1
	v_add_u32_e32 v2, v58, v174
	v_ashrrev_i32_e32 v3, 31, v2
	v_lshl_add_u64 v[2:3], v[2:3], 1, s[22:23]
	global_store_short v[2:3], v15, off sc1
	v_add_u32_e32 v2, v58, v175
	v_ashrrev_i32_e32 v3, 31, v2
	v_lshl_add_u64 v[2:3], v[2:3], 1, s[22:23]
	v_or_b32_e32 v58, 0x180, v61
	global_store_short v[2:3], v60, off sc1
	v_add_u32_e32 v2, v58, v174
	v_ashrrev_i32_e32 v3, 31, v2
	v_lshl_add_u64 v[2:3], v[2:3], 1, s[22:23]
	global_store_short v[2:3], v15, off sc1
	v_add_u32_e32 v2, v58, v175
	v_ashrrev_i32_e32 v3, 31, v2
	v_lshl_add_u64 v[2:3], v[2:3], 1, s[22:23]
	v_add_u32_e32 v58, 0x240, v61
	global_store_short v[2:3], v60, off sc1
	v_or_b32_e32 v2, v58, v174
	v_ashrrev_i32_e32 v3, 31, v2
	v_lshl_add_u64 v[2:3], v[2:3], 1, s[22:23]
	global_store_short v[2:3], v15, off sc1
	v_or_b32_e32 v2, v58, v175
	v_ashrrev_i32_e32 v3, 31, v2
	v_lshl_add_u64 v[2:3], v[2:3], 1, s[22:23]
	v_add_u32_e32 v58, 0x300, v61
	global_store_short v[2:3], v60, off sc1
	v_or_b32_e32 v2, v58, v174
	v_ashrrev_i32_e32 v3, 31, v2
	v_lshl_add_u64 v[2:3], v[2:3], 1, s[22:23]
	global_store_short v[2:3], v15, off sc1
	v_or_b32_e32 v2, v58, v175
	v_pk_mul_f32 v[58:59], v[70:71], v[70:71]
	v_ashrrev_i32_e32 v3, 31, v2
	v_add_f32_e32 v58, v59, v58
	s_nop 1
	v_mov_b32_dpp v59, v58 quad_perm:[1,0,3,2] row_mask:0xf bank_mask:0xf
	v_lshl_add_u64 v[2:3], v[2:3], 1, s[22:23]
	v_add_u32_e32 v62, 0x3c0, v61
	global_store_short v[2:3], v60, off sc1
	v_add_u32_e32 v2, v62, v174
	s_waitcnt lgkmcnt(0)
	v_add_f32_e32 v58, v58, v59
	s_nop 1
	v_mov_b32_dpp v59, v58 quad_perm:[2,3,0,1] row_mask:0xf bank_mask:0xf
	v_ashrrev_i32_e32 v3, 31, v2
	v_lshl_add_u64 v[2:3], v[2:3], 1, s[22:23]
	global_store_short v[2:3], v15, off sc1
	v_add_u32_e32 v2, v62, v175
	s_waitcnt lgkmcnt(0)
	v_add_f32_e32 v58, v58, v59
	s_nop 1
	v_mov_b32_dpp v59, v58 row_half_mirror row_mask:0xf bank_mask:0xf
	v_ashrrev_i32_e32 v3, 31, v2
	v_lshl_add_u64 v[2:3], v[2:3], 1, s[22:23]
	v_add_u32_e32 v62, 0x480, v61
	global_store_short v[2:3], v60, off sc1
	s_waitcnt lgkmcnt(0)
	v_add_f32_e32 v58, v58, v59
	s_nop 1
	v_mov_b32_dpp v59, v58 row_mirror row_mask:0xf bank_mask:0xf
	v_add_u32_e32 v2, v62, v174
	v_ashrrev_i32_e32 v3, 31, v2
	v_lshl_add_u64 v[2:3], v[2:3], 1, s[22:23]
	global_store_short v[2:3], v15, off sc1
	v_add_u32_e32 v2, v62, v175
	s_waitcnt lgkmcnt(0)
	v_add_f32_e32 v58, v58, v59
	v_ashrrev_i32_e32 v3, 31, v2
	ds_bpermute_b32 v59, v13, v58
	v_lshl_add_u64 v[2:3], v[2:3], 1, s[22:23]
	v_add_u32_e32 v61, 0x540, v61
	global_store_short v[2:3], v60, off sc1
	v_or_b32_e32 v2, v61, v174
	v_ashrrev_i32_e32 v3, 31, v2
	v_lshl_add_u64 v[2:3], v[2:3], 1, s[22:23]
	global_store_short v[2:3], v15, off sc1
	s_waitcnt lgkmcnt(0)
	v_add_f32_e32 v3, v58, v59
	v_fmamk_f32 v3, v3, 0x3c800000, v209
	v_rsq_f32_e32 v58, v3
	v_or_b32_e32 v2, v61, v175
	v_ashrrev_i32_e32 v3, 31, v2
	v_lshl_add_u64 v[2:3], v[2:3], 1, s[22:23]
	global_store_short v[2:3], v60, off sc1
	v_pk_mul_f32 v[2:3], v[0:1], v[58:59] op_sel_hi:[1,0]
	s_and_b64 vcc, exec, s[4:5]
	v_pk_mul_f32 v[2:3], v[70:71], v[2:3]
	s_mov_b64 s[80:81], -1
	s_cbranch_vccnz .LBB0_282
	v_add_u32_e32 v15, s76, v178
	v_lshl_or_b32 v58, v15, 6, v156
	v_ashrrev_i32_e32 v59, 31, v58
	v_lshl_add_u64 v[58:59], v[58:59], 2, s[24:25]
	s_mov_b64 s[80:81], 0
	global_store_dword v[58:59], v3, off sc1
	global_store_dword v[58:59], v2, off offset:128 sc1

.LBB0_284:
	v_cvt_pk_bf16_f32 v60, v2, s0
	v_add_u32_e32 v2, s11, v178
	v_mul_lo_u32 v61, v2, s94
	v_or_b32_e32 v2, v61, v174
	v_cvt_pk_bf16_f32 v15, v3, s0
	v_ashrrev_i32_e32 v3, 31, v2
	v_lshl_add_u64 v[2:3], v[2:3], 1, s[22:23]
	global_store_short v[2:3], v15, off sc1
	v_or_b32_e32 v2, v61, v175
	v_ashrrev_i32_e32 v3, 31, v2
	v_lshl_add_u64 v[2:3], v[2:3], 1, s[22:23]
	v_or_b32_e32 v58, 0xc0, v61
	global_store_short v[2:3], v60, off sc1
	v_add_u32_e32 v2, v58, v174
	v_ashrrev_i32_e32 v3, 31, v2
	v_lshl_add_u64 v[2:3], v[2:3], 1, s[22:23]
	global_store_short v[2:3], v15, off sc1
	v_add_u32_e32 v2, v58, v175
	v_ashrrev_i32_e32 v3, 31, v2
	v_lshl_add_u64 v[2:3], v[2:3], 1, s[22:23]
	v_or_b32_e32 v58, 0x180, v61
	global_store_short v[2:3], v60, off sc1
	v_add_u32_e32 v2, v58, v174
	v_ashrrev_i32_e32 v3, 31, v2
	v_lshl_add_u64 v[2:3], v[2:3], 1, s[22:23]
	global_store_short v[2:3], v15, off sc1
	v_add_u32_e32 v2, v58, v175
	v_ashrrev_i32_e32 v3, 31, v2
	v_lshl_add_u64 v[2:3], v[2:3], 1, s[22:23]
	v_add_u32_e32 v58, 0x240, v61
	global_store_short v[2:3], v60, off sc1
	v_or_b32_e32 v2, v58, v174
	v_ashrrev_i32_e32 v3, 31, v2
	v_lshl_add_u64 v[2:3], v[2:3], 1, s[22:23]
	global_store_short v[2:3], v15, off sc1
	v_or_b32_e32 v2, v58, v175
	v_ashrrev_i32_e32 v3, 31, v2
	v_lshl_add_u64 v[2:3], v[2:3], 1, s[22:23]
	v_add_u32_e32 v58, 0x300, v61
	global_store_short v[2:3], v60, off sc1
	v_or_b32_e32 v2, v58, v174
	v_ashrrev_i32_e32 v3, 31, v2
	v_lshl_add_u64 v[2:3], v[2:3], 1, s[22:23]
	global_store_short v[2:3], v15, off sc1
	v_or_b32_e32 v2, v58, v175
	v_pk_mul_f32 v[58:59], v[68:69], v[68:69]
	v_ashrrev_i32_e32 v3, 31, v2
	v_add_f32_e32 v58, v59, v58
	s_nop 1
	v_mov_b32_dpp v59, v58 quad_perm:[1,0,3,2] row_mask:0xf bank_mask:0xf
	v_lshl_add_u64 v[2:3], v[2:3], 1, s[22:23]
	v_add_u32_e32 v62, 0x3c0, v61
	global_store_short v[2:3], v60, off sc1
	v_add_u32_e32 v2, v62, v174
	s_waitcnt lgkmcnt(0)
	v_add_f32_e32 v58, v58, v59
	s_nop 1
	v_mov_b32_dpp v59, v58 quad_perm:[2,3,0,1] row_mask:0xf bank_mask:0xf
	v_ashrrev_i32_e32 v3, 31, v2
	v_lshl_add_u64 v[2:3], v[2:3], 1, s[22:23]
	global_store_short v[2:3], v15, off sc1
	v_add_u32_e32 v2, v62, v175
	s_waitcnt lgkmcnt(0)
	v_add_f32_e32 v58, v58, v59
	s_nop 1
	v_mov_b32_dpp v59, v58 row_half_mirror row_mask:0xf bank_mask:0xf
	v_ashrrev_i32_e32 v3, 31, v2
	v_lshl_add_u64 v[2:3], v[2:3], 1, s[22:23]
	v_add_u32_e32 v62, 0x480, v61
	global_store_short v[2:3], v60, off sc1
	s_waitcnt lgkmcnt(0)
	v_add_f32_e32 v58, v58, v59
	s_nop 1
	v_mov_b32_dpp v59, v58 row_mirror row_mask:0xf bank_mask:0xf
	v_add_u32_e32 v2, v62, v174
	v_ashrrev_i32_e32 v3, 31, v2
	v_lshl_add_u64 v[2:3], v[2:3], 1, s[22:23]
	global_store_short v[2:3], v15, off sc1
	v_add_u32_e32 v2, v62, v175
	s_waitcnt lgkmcnt(0)
	v_add_f32_e32 v58, v58, v59
	v_ashrrev_i32_e32 v3, 31, v2
	ds_bpermute_b32 v59, v13, v58
	v_lshl_add_u64 v[2:3], v[2:3], 1, s[22:23]
	v_add_u32_e32 v61, 0x540, v61
	global_store_short v[2:3], v60, off sc1
	v_or_b32_e32 v2, v61, v174
	v_ashrrev_i32_e32 v3, 31, v2
	v_lshl_add_u64 v[2:3], v[2:3], 1, s[22:23]
	global_store_short v[2:3], v15, off sc1
	s_waitcnt lgkmcnt(0)
	v_add_f32_e32 v3, v58, v59
	v_fmamk_f32 v3, v3, 0x3c800000, v209
	v_rsq_f32_e32 v58, v3
	v_or_b32_e32 v2, v61, v175
	v_ashrrev_i32_e32 v3, 31, v2
	v_lshl_add_u64 v[2:3], v[2:3], 1, s[22:23]
	global_store_short v[2:3], v60, off sc1
	v_pk_mul_f32 v[2:3], v[0:1], v[58:59] op_sel_hi:[1,0]
	s_and_b64 vcc, exec, s[4:5]
	v_pk_mul_f32 v[2:3], v[68:69], v[2:3]
	s_mov_b64 s[80:81], -1
	s_cbranch_vccnz .LBB0_286
	v_add_u32_e32 v15, s76, v179
	v_lshl_or_b32 v58, v15, 6, v156
	v_ashrrev_i32_e32 v59, 31, v58
	v_lshl_add_u64 v[58:59], v[58:59], 2, s[24:25]
	s_mov_b64 s[80:81], 0
	global_store_dword v[58:59], v3, off sc1
	global_store_dword v[58:59], v2, off offset:128 sc1

.LBB0_288:
	v_cvt_pk_bf16_f32 v60, v2, s0
	v_add_u32_e32 v2, s11, v179
	v_mul_lo_u32 v61, v2, s94
	v_or_b32_e32 v2, v61, v174
	v_cvt_pk_bf16_f32 v15, v3, s0
	v_ashrrev_i32_e32 v3, 31, v2
	v_lshl_add_u64 v[2:3], v[2:3], 1, s[22:23]
	global_store_short v[2:3], v15, off sc1
	v_or_b32_e32 v2, v61, v175
	v_ashrrev_i32_e32 v3, 31, v2
	v_lshl_add_u64 v[2:3], v[2:3], 1, s[22:23]
	v_or_b32_e32 v58, 0xc0, v61
	global_store_short v[2:3], v60, off sc1
	v_add_u32_e32 v2, v58, v174
	v_ashrrev_i32_e32 v3, 31, v2
	v_lshl_add_u64 v[2:3], v[2:3], 1, s[22:23]
	global_store_short v[2:3], v15, off sc1
	v_add_u32_e32 v2, v58, v175
	v_ashrrev_i32_e32 v3, 31, v2
	v_lshl_add_u64 v[2:3], v[2:3], 1, s[22:23]
	v_or_b32_e32 v58, 0x180, v61
	global_store_short v[2:3], v60, off sc1
	v_add_u32_e32 v2, v58, v174
	v_ashrrev_i32_e32 v3, 31, v2
	v_lshl_add_u64 v[2:3], v[2:3], 1, s[22:23]
	global_store_short v[2:3], v15, off sc1
	v_add_u32_e32 v2, v58, v175
	v_ashrrev_i32_e32 v3, 31, v2
	v_lshl_add_u64 v[2:3], v[2:3], 1, s[22:23]
	v_add_u32_e32 v58, 0x240, v61
	global_store_short v[2:3], v60, off sc1
	v_or_b32_e32 v2, v58, v174
	v_ashrrev_i32_e32 v3, 31, v2
	v_lshl_add_u64 v[2:3], v[2:3], 1, s[22:23]
	global_store_short v[2:3], v15, off sc1
	v_or_b32_e32 v2, v58, v175
	v_ashrrev_i32_e32 v3, 31, v2
	v_lshl_add_u64 v[2:3], v[2:3], 1, s[22:23]
	v_add_u32_e32 v58, 0x300, v61
	global_store_short v[2:3], v60, off sc1
	v_or_b32_e32 v2, v58, v174
	v_ashrrev_i32_e32 v3, 31, v2
	v_lshl_add_u64 v[2:3], v[2:3], 1, s[22:23]
	global_store_short v[2:3], v15, off sc1
	v_or_b32_e32 v2, v58, v175
	v_pk_mul_f32 v[58:59], v[66:67], v[66:67]
	v_ashrrev_i32_e32 v3, 31, v2
	v_add_f32_e32 v58, v59, v58
	s_nop 1
	v_mov_b32_dpp v59, v58 quad_perm:[1,0,3,2] row_mask:0xf bank_mask:0xf
	v_lshl_add_u64 v[2:3], v[2:3], 1, s[22:23]
	v_add_u32_e32 v62, 0x3c0, v61
	global_store_short v[2:3], v60, off sc1
	v_add_u32_e32 v2, v62, v174
	s_waitcnt lgkmcnt(0)
	v_add_f32_e32 v58, v58, v59
	s_nop 1
	v_mov_b32_dpp v59, v58 quad_perm:[2,3,0,1] row_mask:0xf bank_mask:0xf
	v_ashrrev_i32_e32 v3, 31, v2
	v_lshl_add_u64 v[2:3], v[2:3], 1, s[22:23]
	global_store_short v[2:3], v15, off sc1
	v_add_u32_e32 v2, v62, v175
	s_waitcnt lgkmcnt(0)
	v_add_f32_e32 v58, v58, v59
	s_nop 1
	v_mov_b32_dpp v59, v58 row_half_mirror row_mask:0xf bank_mask:0xf
	v_ashrrev_i32_e32 v3, 31, v2
	v_lshl_add_u64 v[2:3], v[2:3], 1, s[22:23]
	v_add_u32_e32 v62, 0x480, v61
	global_store_short v[2:3], v60, off sc1
	s_waitcnt lgkmcnt(0)
	v_add_f32_e32 v58, v58, v59
	s_nop 1
	v_mov_b32_dpp v59, v58 row_mirror row_mask:0xf bank_mask:0xf
	v_add_u32_e32 v2, v62, v174
	v_ashrrev_i32_e32 v3, 31, v2
	v_lshl_add_u64 v[2:3], v[2:3], 1, s[22:23]
	global_store_short v[2:3], v15, off sc1
	v_add_u32_e32 v2, v62, v175
	s_waitcnt lgkmcnt(0)
	v_add_f32_e32 v58, v58, v59
	v_ashrrev_i32_e32 v3, 31, v2
	ds_bpermute_b32 v59, v13, v58
	v_lshl_add_u64 v[2:3], v[2:3], 1, s[22:23]
	v_add_u32_e32 v61, 0x540, v61
	global_store_short v[2:3], v60, off sc1
	v_or_b32_e32 v2, v61, v174
	v_ashrrev_i32_e32 v3, 31, v2
	v_lshl_add_u64 v[2:3], v[2:3], 1, s[22:23]
	global_store_short v[2:3], v15, off sc1
	s_waitcnt lgkmcnt(0)
	v_add_f32_e32 v3, v58, v59
	v_fmamk_f32 v3, v3, 0x3c800000, v209
	v_rsq_f32_e32 v58, v3
	v_or_b32_e32 v2, v61, v175
	v_ashrrev_i32_e32 v3, 31, v2
	v_lshl_add_u64 v[2:3], v[2:3], 1, s[22:23]
	global_store_short v[2:3], v60, off sc1
	v_pk_mul_f32 v[2:3], v[0:1], v[58:59] op_sel_hi:[1,0]
	s_and_b64 vcc, exec, s[4:5]
	v_pk_mul_f32 v[2:3], v[66:67], v[2:3]
	s_mov_b64 s[80:81], -1
	s_cbranch_vccnz .LBB0_290
	v_add_u32_e32 v15, s76, v180
	v_lshl_or_b32 v58, v15, 6, v156
	v_ashrrev_i32_e32 v59, 31, v58
	v_lshl_add_u64 v[58:59], v[58:59], 2, s[24:25]
	s_mov_b64 s[80:81], 0
	global_store_dword v[58:59], v3, off sc1
	global_store_dword v[58:59], v2, off offset:128 sc1

.LBB0_292:
	v_cvt_pk_bf16_f32 v60, v2, s0
	v_add_u32_e32 v2, s11, v180
	v_mul_lo_u32 v61, v2, s94
	v_or_b32_e32 v2, v61, v174
	v_cvt_pk_bf16_f32 v15, v3, s0
	v_ashrrev_i32_e32 v3, 31, v2
	v_lshl_add_u64 v[2:3], v[2:3], 1, s[22:23]
	global_store_short v[2:3], v15, off sc1
	v_or_b32_e32 v2, v61, v175
	v_ashrrev_i32_e32 v3, 31, v2
	v_lshl_add_u64 v[2:3], v[2:3], 1, s[22:23]
	v_or_b32_e32 v58, 0xc0, v61
	global_store_short v[2:3], v60, off sc1
	v_add_u32_e32 v2, v58, v174
	v_ashrrev_i32_e32 v3, 31, v2
	v_lshl_add_u64 v[2:3], v[2:3], 1, s[22:23]
	global_store_short v[2:3], v15, off sc1
	v_add_u32_e32 v2, v58, v175
	v_ashrrev_i32_e32 v3, 31, v2
	v_lshl_add_u64 v[2:3], v[2:3], 1, s[22:23]
	v_or_b32_e32 v58, 0x180, v61
	global_store_short v[2:3], v60, off sc1
	v_add_u32_e32 v2, v58, v174
	v_ashrrev_i32_e32 v3, 31, v2
	v_lshl_add_u64 v[2:3], v[2:3], 1, s[22:23]
	global_store_short v[2:3], v15, off sc1
	v_add_u32_e32 v2, v58, v175
	v_ashrrev_i32_e32 v3, 31, v2
	v_lshl_add_u64 v[2:3], v[2:3], 1, s[22:23]
	v_add_u32_e32 v58, 0x240, v61
	global_store_short v[2:3], v60, off sc1
	v_or_b32_e32 v2, v58, v174
	v_ashrrev_i32_e32 v3, 31, v2
	v_lshl_add_u64 v[2:3], v[2:3], 1, s[22:23]
	global_store_short v[2:3], v15, off sc1
	v_or_b32_e32 v2, v58, v175
	v_ashrrev_i32_e32 v3, 31, v2
	v_lshl_add_u64 v[2:3], v[2:3], 1, s[22:23]
	v_add_u32_e32 v58, 0x300, v61
	global_store_short v[2:3], v60, off sc1
	v_or_b32_e32 v2, v58, v174
	v_ashrrev_i32_e32 v3, 31, v2
	v_lshl_add_u64 v[2:3], v[2:3], 1, s[22:23]
	global_store_short v[2:3], v15, off sc1
	v_or_b32_e32 v2, v58, v175
	v_pk_mul_f32 v[58:59], v[64:65], v[64:65]
	v_ashrrev_i32_e32 v3, 31, v2
	v_add_f32_e32 v58, v59, v58
	s_nop 1
	v_mov_b32_dpp v59, v58 quad_perm:[1,0,3,2] row_mask:0xf bank_mask:0xf
	v_lshl_add_u64 v[2:3], v[2:3], 1, s[22:23]
	v_add_u32_e32 v62, 0x3c0, v61
	global_store_short v[2:3], v60, off sc1
	v_add_u32_e32 v2, v62, v174
	s_waitcnt lgkmcnt(0)
	v_add_f32_e32 v58, v58, v59
	s_nop 1
	v_mov_b32_dpp v59, v58 quad_perm:[2,3,0,1] row_mask:0xf bank_mask:0xf
	v_ashrrev_i32_e32 v3, 31, v2
	v_lshl_add_u64 v[2:3], v[2:3], 1, s[22:23]
	global_store_short v[2:3], v15, off sc1
	v_add_u32_e32 v2, v62, v175
	s_waitcnt lgkmcnt(0)
	v_add_f32_e32 v58, v58, v59
	s_nop 1
	v_mov_b32_dpp v59, v58 row_half_mirror row_mask:0xf bank_mask:0xf
	v_ashrrev_i32_e32 v3, 31, v2
	v_lshl_add_u64 v[2:3], v[2:3], 1, s[22:23]
	v_add_u32_e32 v62, 0x480, v61
	global_store_short v[2:3], v60, off sc1
	s_waitcnt lgkmcnt(0)
	v_add_f32_e32 v58, v58, v59
	s_nop 1
	v_mov_b32_dpp v59, v58 row_mirror row_mask:0xf bank_mask:0xf
	v_add_u32_e32 v2, v62, v174
	v_ashrrev_i32_e32 v3, 31, v2
	v_lshl_add_u64 v[2:3], v[2:3], 1, s[22:23]
	global_store_short v[2:3], v15, off sc1
	v_add_u32_e32 v2, v62, v175
	s_waitcnt lgkmcnt(0)
	v_add_f32_e32 v58, v58, v59
	v_ashrrev_i32_e32 v3, 31, v2
	ds_bpermute_b32 v59, v13, v58
	v_lshl_add_u64 v[2:3], v[2:3], 1, s[22:23]
	v_add_u32_e32 v61, 0x540, v61
	global_store_short v[2:3], v60, off sc1
	v_or_b32_e32 v2, v61, v174
	v_ashrrev_i32_e32 v3, 31, v2
	v_lshl_add_u64 v[2:3], v[2:3], 1, s[22:23]
	global_store_short v[2:3], v15, off sc1
	s_waitcnt lgkmcnt(0)
	v_add_f32_e32 v3, v58, v59
	v_fmamk_f32 v3, v3, 0x3c800000, v209
	v_rsq_f32_e32 v58, v3
	v_or_b32_e32 v2, v61, v175
	v_ashrrev_i32_e32 v3, 31, v2
	v_lshl_add_u64 v[2:3], v[2:3], 1, s[22:23]
	global_store_short v[2:3], v60, off sc1
	v_pk_mul_f32 v[2:3], v[0:1], v[58:59] op_sel_hi:[1,0]
	s_and_b64 vcc, exec, s[4:5]
	v_pk_mul_f32 v[2:3], v[64:65], v[2:3]
	s_mov_b64 s[80:81], -1
	s_cbranch_vccnz .LBB0_294
	v_add_u32_e32 v15, s76, v181
	v_lshl_or_b32 v58, v15, 6, v156
	v_ashrrev_i32_e32 v59, 31, v58
	v_lshl_add_u64 v[58:59], v[58:59], 2, s[24:25]
	s_mov_b64 s[80:81], 0
	global_store_dword v[58:59], v3, off sc1
	global_store_dword v[58:59], v2, off offset:128 sc1

.LBB0_296:
	v_cvt_pk_bf16_f32 v60, v2, s0
	v_add_u32_e32 v2, s11, v181
	v_mul_lo_u32 v61, v2, s94
	v_or_b32_e32 v2, v61, v174
	v_cvt_pk_bf16_f32 v15, v3, s0
	v_ashrrev_i32_e32 v3, 31, v2
	v_lshl_add_u64 v[2:3], v[2:3], 1, s[22:23]
	global_store_short v[2:3], v15, off sc1
	v_or_b32_e32 v2, v61, v175
	v_ashrrev_i32_e32 v3, 31, v2
	v_lshl_add_u64 v[2:3], v[2:3], 1, s[22:23]
	v_or_b32_e32 v58, 0xc0, v61
	global_store_short v[2:3], v60, off sc1
	v_add_u32_e32 v2, v58, v174
	v_ashrrev_i32_e32 v3, 31, v2
	v_lshl_add_u64 v[2:3], v[2:3], 1, s[22:23]
	global_store_short v[2:3], v15, off sc1
	v_add_u32_e32 v2, v58, v175
	v_ashrrev_i32_e32 v3, 31, v2
	v_lshl_add_u64 v[2:3], v[2:3], 1, s[22:23]
	v_or_b32_e32 v58, 0x180, v61
	global_store_short v[2:3], v60, off sc1
	v_add_u32_e32 v2, v58, v174
	v_ashrrev_i32_e32 v3, 31, v2
	v_lshl_add_u64 v[2:3], v[2:3], 1, s[22:23]
	global_store_short v[2:3], v15, off sc1
	v_add_u32_e32 v2, v58, v175
	v_ashrrev_i32_e32 v3, 31, v2
	v_lshl_add_u64 v[2:3], v[2:3], 1, s[22:23]
	v_add_u32_e32 v58, 0x240, v61
	global_store_short v[2:3], v60, off sc1
	v_or_b32_e32 v2, v58, v174
	v_ashrrev_i32_e32 v3, 31, v2
	v_lshl_add_u64 v[2:3], v[2:3], 1, s[22:23]
	global_store_short v[2:3], v15, off sc1
	v_or_b32_e32 v2, v58, v175
	v_ashrrev_i32_e32 v3, 31, v2
	v_lshl_add_u64 v[2:3], v[2:3], 1, s[22:23]
	v_add_u32_e32 v58, 0x300, v61
	global_store_short v[2:3], v60, off sc1
	v_or_b32_e32 v2, v58, v174
	v_ashrrev_i32_e32 v3, 31, v2
	v_lshl_add_u64 v[2:3], v[2:3], 1, s[22:23]
	global_store_short v[2:3], v15, off sc1
	v_or_b32_e32 v2, v58, v175
	v_pk_mul_f32 v[58:59], v[54:55], v[54:55]
	v_ashrrev_i32_e32 v3, 31, v2
	v_add_f32_e32 v58, v59, v58
	s_nop 1
	v_mov_b32_dpp v59, v58 quad_perm:[1,0,3,2] row_mask:0xf bank_mask:0xf
	v_lshl_add_u64 v[2:3], v[2:3], 1, s[22:23]
	v_add_u32_e32 v62, 0x3c0, v61
	global_store_short v[2:3], v60, off sc1
	v_add_u32_e32 v2, v62, v174
	s_waitcnt lgkmcnt(0)
	v_add_f32_e32 v58, v58, v59
	s_nop 1
	v_mov_b32_dpp v59, v58 quad_perm:[2,3,0,1] row_mask:0xf bank_mask:0xf
	v_ashrrev_i32_e32 v3, 31, v2
	v_lshl_add_u64 v[2:3], v[2:3], 1, s[22:23]
	global_store_short v[2:3], v15, off sc1
	v_add_u32_e32 v2, v62, v175
	s_waitcnt lgkmcnt(0)
	v_add_f32_e32 v58, v58, v59
	s_nop 1
	v_mov_b32_dpp v59, v58 row_half_mirror row_mask:0xf bank_mask:0xf
	v_ashrrev_i32_e32 v3, 31, v2
	v_lshl_add_u64 v[2:3], v[2:3], 1, s[22:23]
	v_add_u32_e32 v62, 0x480, v61
	global_store_short v[2:3], v60, off sc1
	s_waitcnt lgkmcnt(0)
	v_add_f32_e32 v58, v58, v59
	s_nop 1
	v_mov_b32_dpp v59, v58 row_mirror row_mask:0xf bank_mask:0xf
	v_add_u32_e32 v2, v62, v174
	v_ashrrev_i32_e32 v3, 31, v2
	v_lshl_add_u64 v[2:3], v[2:3], 1, s[22:23]
	global_store_short v[2:3], v15, off sc1
	v_add_u32_e32 v2, v62, v175
	s_waitcnt lgkmcnt(0)
	v_add_f32_e32 v58, v58, v59
	v_ashrrev_i32_e32 v3, 31, v2
	ds_bpermute_b32 v59, v13, v58
	v_lshl_add_u64 v[2:3], v[2:3], 1, s[22:23]
	v_add_u32_e32 v61, 0x540, v61
	global_store_short v[2:3], v60, off sc1
	v_or_b32_e32 v2, v61, v174
	v_ashrrev_i32_e32 v3, 31, v2
	v_lshl_add_u64 v[2:3], v[2:3], 1, s[22:23]
	global_store_short v[2:3], v15, off sc1
	s_waitcnt lgkmcnt(0)
	v_add_f32_e32 v3, v58, v59
	v_fmamk_f32 v3, v3, 0x3c800000, v209
	v_rsq_f32_e32 v58, v3
	v_or_b32_e32 v2, v61, v175
	v_ashrrev_i32_e32 v3, 31, v2
	v_lshl_add_u64 v[2:3], v[2:3], 1, s[22:23]
	global_store_short v[2:3], v60, off sc1
	v_pk_mul_f32 v[2:3], v[0:1], v[58:59] op_sel_hi:[1,0]
	s_and_b64 vcc, exec, s[4:5]
	v_pk_mul_f32 v[2:3], v[54:55], v[2:3]
	s_mov_b64 s[80:81], -1
	s_cbranch_vccnz .LBB0_298
	v_add_u32_e32 v15, s76, v182
	v_lshl_or_b32 v58, v15, 6, v156
	v_ashrrev_i32_e32 v59, 31, v58
	v_lshl_add_u64 v[58:59], v[58:59], 2, s[24:25]
	s_mov_b64 s[80:81], 0
	global_store_dword v[58:59], v3, off sc1
	global_store_dword v[58:59], v2, off offset:128 sc1

.LBB0_300:
	v_cvt_pk_bf16_f32 v60, v2, s0
	v_add_u32_e32 v2, s11, v182
	v_mul_lo_u32 v61, v2, s94
	v_or_b32_e32 v2, v61, v174
	v_cvt_pk_bf16_f32 v15, v3, s0
	v_ashrrev_i32_e32 v3, 31, v2
	v_lshl_add_u64 v[2:3], v[2:3], 1, s[22:23]
	global_store_short v[2:3], v15, off sc1
	v_or_b32_e32 v2, v61, v175
	v_ashrrev_i32_e32 v3, 31, v2
	v_lshl_add_u64 v[2:3], v[2:3], 1, s[22:23]
	v_or_b32_e32 v58, 0xc0, v61
	global_store_short v[2:3], v60, off sc1
	v_add_u32_e32 v2, v58, v174
	v_ashrrev_i32_e32 v3, 31, v2
	v_lshl_add_u64 v[2:3], v[2:3], 1, s[22:23]
	global_store_short v[2:3], v15, off sc1
	v_add_u32_e32 v2, v58, v175
	v_ashrrev_i32_e32 v3, 31, v2
	v_lshl_add_u64 v[2:3], v[2:3], 1, s[22:23]
	v_or_b32_e32 v58, 0x180, v61
	global_store_short v[2:3], v60, off sc1
	v_add_u32_e32 v2, v58, v174
	v_ashrrev_i32_e32 v3, 31, v2
	v_lshl_add_u64 v[2:3], v[2:3], 1, s[22:23]
	global_store_short v[2:3], v15, off sc1
	v_add_u32_e32 v2, v58, v175
	v_ashrrev_i32_e32 v3, 31, v2
	v_lshl_add_u64 v[2:3], v[2:3], 1, s[22:23]
	v_add_u32_e32 v58, 0x240, v61
	global_store_short v[2:3], v60, off sc1
	v_or_b32_e32 v2, v58, v174
	v_ashrrev_i32_e32 v3, 31, v2
	v_lshl_add_u64 v[2:3], v[2:3], 1, s[22:23]
	global_store_short v[2:3], v15, off sc1
	v_or_b32_e32 v2, v58, v175
	v_ashrrev_i32_e32 v3, 31, v2
	v_lshl_add_u64 v[2:3], v[2:3], 1, s[22:23]
	v_add_u32_e32 v58, 0x300, v61
	global_store_short v[2:3], v60, off sc1
	v_or_b32_e32 v2, v58, v174
	v_ashrrev_i32_e32 v3, 31, v2
	v_lshl_add_u64 v[2:3], v[2:3], 1, s[22:23]
	global_store_short v[2:3], v15, off sc1
	v_or_b32_e32 v2, v58, v175
	v_pk_mul_f32 v[58:59], v[52:53], v[52:53]
	v_ashrrev_i32_e32 v3, 31, v2
	v_add_f32_e32 v58, v59, v58
	s_nop 1
	v_mov_b32_dpp v59, v58 quad_perm:[1,0,3,2] row_mask:0xf bank_mask:0xf
	v_lshl_add_u64 v[2:3], v[2:3], 1, s[22:23]
	v_add_u32_e32 v62, 0x3c0, v61
	global_store_short v[2:3], v60, off sc1
	v_add_u32_e32 v2, v62, v174
	s_waitcnt lgkmcnt(0)
	v_add_f32_e32 v58, v58, v59
	s_nop 1
	v_mov_b32_dpp v59, v58 quad_perm:[2,3,0,1] row_mask:0xf bank_mask:0xf
	v_ashrrev_i32_e32 v3, 31, v2
	v_lshl_add_u64 v[2:3], v[2:3], 1, s[22:23]
	global_store_short v[2:3], v15, off sc1
	v_add_u32_e32 v2, v62, v175
	s_waitcnt lgkmcnt(0)
	v_add_f32_e32 v58, v58, v59
	s_nop 1
	v_mov_b32_dpp v59, v58 row_half_mirror row_mask:0xf bank_mask:0xf
	v_ashrrev_i32_e32 v3, 31, v2
	v_lshl_add_u64 v[2:3], v[2:3], 1, s[22:23]
	v_add_u32_e32 v62, 0x480, v61
	global_store_short v[2:3], v60, off sc1
	s_waitcnt lgkmcnt(0)
	v_add_f32_e32 v58, v58, v59
	s_nop 1
	v_mov_b32_dpp v59, v58 row_mirror row_mask:0xf bank_mask:0xf
	v_add_u32_e32 v2, v62, v174
	v_ashrrev_i32_e32 v3, 31, v2
	v_lshl_add_u64 v[2:3], v[2:3], 1, s[22:23]
	global_store_short v[2:3], v15, off sc1
	v_add_u32_e32 v2, v62, v175
	s_waitcnt lgkmcnt(0)
	v_add_f32_e32 v58, v58, v59
	v_ashrrev_i32_e32 v3, 31, v2
	ds_bpermute_b32 v59, v13, v58
	v_lshl_add_u64 v[2:3], v[2:3], 1, s[22:23]
	v_add_u32_e32 v61, 0x540, v61
	global_store_short v[2:3], v60, off sc1
	v_or_b32_e32 v2, v61, v174
	v_ashrrev_i32_e32 v3, 31, v2
	v_lshl_add_u64 v[2:3], v[2:3], 1, s[22:23]
	global_store_short v[2:3], v15, off sc1
	s_waitcnt lgkmcnt(0)
	v_add_f32_e32 v3, v58, v59
	v_fmamk_f32 v3, v3, 0x3c800000, v209
	v_rsq_f32_e32 v58, v3
	v_or_b32_e32 v2, v61, v175
	v_ashrrev_i32_e32 v3, 31, v2
	v_lshl_add_u64 v[2:3], v[2:3], 1, s[22:23]
	global_store_short v[2:3], v60, off sc1
	v_pk_mul_f32 v[2:3], v[0:1], v[58:59] op_sel_hi:[1,0]
	s_and_b64 vcc, exec, s[4:5]
	v_pk_mul_f32 v[2:3], v[52:53], v[2:3]
	s_mov_b64 s[80:81], -1
	s_cbranch_vccnz .LBB0_302
	v_add_u32_e32 v15, s76, v183
	v_lshl_or_b32 v58, v15, 6, v156
	v_ashrrev_i32_e32 v59, 31, v58
	v_lshl_add_u64 v[58:59], v[58:59], 2, s[24:25]
	s_mov_b64 s[80:81], 0
	global_store_dword v[58:59], v3, off sc1
	global_store_dword v[58:59], v2, off offset:128 sc1

.LBB0_304:
	v_cvt_pk_bf16_f32 v60, v2, s0
	v_add_u32_e32 v2, s11, v183
	v_mul_lo_u32 v61, v2, s94
	v_or_b32_e32 v2, v61, v174
	v_cvt_pk_bf16_f32 v15, v3, s0
	v_ashrrev_i32_e32 v3, 31, v2
	v_lshl_add_u64 v[2:3], v[2:3], 1, s[22:23]
	global_store_short v[2:3], v15, off sc1
	v_or_b32_e32 v2, v61, v175
	v_ashrrev_i32_e32 v3, 31, v2
	v_lshl_add_u64 v[2:3], v[2:3], 1, s[22:23]
	v_or_b32_e32 v58, 0xc0, v61
	global_store_short v[2:3], v60, off sc1
	v_add_u32_e32 v2, v58, v174
	v_ashrrev_i32_e32 v3, 31, v2
	v_lshl_add_u64 v[2:3], v[2:3], 1, s[22:23]
	global_store_short v[2:3], v15, off sc1
	v_add_u32_e32 v2, v58, v175
	v_ashrrev_i32_e32 v3, 31, v2
	v_lshl_add_u64 v[2:3], v[2:3], 1, s[22:23]
	v_or_b32_e32 v58, 0x180, v61
	global_store_short v[2:3], v60, off sc1
	v_add_u32_e32 v2, v58, v174
	v_ashrrev_i32_e32 v3, 31, v2
	v_lshl_add_u64 v[2:3], v[2:3], 1, s[22:23]
	global_store_short v[2:3], v15, off sc1
	v_add_u32_e32 v2, v58, v175
	v_ashrrev_i32_e32 v3, 31, v2
	v_lshl_add_u64 v[2:3], v[2:3], 1, s[22:23]
	v_add_u32_e32 v58, 0x240, v61
	global_store_short v[2:3], v60, off sc1
	v_or_b32_e32 v2, v58, v174
	v_ashrrev_i32_e32 v3, 31, v2
	v_lshl_add_u64 v[2:3], v[2:3], 1, s[22:23]
	global_store_short v[2:3], v15, off sc1
	v_or_b32_e32 v2, v58, v175
	v_ashrrev_i32_e32 v3, 31, v2
	v_lshl_add_u64 v[2:3], v[2:3], 1, s[22:23]
	v_add_u32_e32 v58, 0x300, v61
	global_store_short v[2:3], v60, off sc1
	v_or_b32_e32 v2, v58, v174
	v_ashrrev_i32_e32 v3, 31, v2
	v_lshl_add_u64 v[2:3], v[2:3], 1, s[22:23]
	global_store_short v[2:3], v15, off sc1
	v_or_b32_e32 v2, v58, v175
	v_pk_mul_f32 v[58:59], v[50:51], v[50:51]
	v_ashrrev_i32_e32 v3, 31, v2
	v_add_f32_e32 v58, v59, v58
	s_nop 1
	v_mov_b32_dpp v59, v58 quad_perm:[1,0,3,2] row_mask:0xf bank_mask:0xf
	v_lshl_add_u64 v[2:3], v[2:3], 1, s[22:23]
	v_add_u32_e32 v62, 0x3c0, v61
	global_store_short v[2:3], v60, off sc1
	v_add_u32_e32 v2, v62, v174
	s_waitcnt lgkmcnt(0)
	v_add_f32_e32 v58, v58, v59
	s_nop 1
	v_mov_b32_dpp v59, v58 quad_perm:[2,3,0,1] row_mask:0xf bank_mask:0xf
	v_ashrrev_i32_e32 v3, 31, v2
	v_lshl_add_u64 v[2:3], v[2:3], 1, s[22:23]
	global_store_short v[2:3], v15, off sc1
	v_add_u32_e32 v2, v62, v175
	s_waitcnt lgkmcnt(0)
	v_add_f32_e32 v58, v58, v59
	s_nop 1
	v_mov_b32_dpp v59, v58 row_half_mirror row_mask:0xf bank_mask:0xf
	v_ashrrev_i32_e32 v3, 31, v2
	v_lshl_add_u64 v[2:3], v[2:3], 1, s[22:23]
	v_add_u32_e32 v62, 0x480, v61
	global_store_short v[2:3], v60, off sc1
	s_waitcnt lgkmcnt(0)
	v_add_f32_e32 v58, v58, v59
	s_nop 1
	v_mov_b32_dpp v59, v58 row_mirror row_mask:0xf bank_mask:0xf
	v_add_u32_e32 v2, v62, v174
	v_ashrrev_i32_e32 v3, 31, v2
	v_lshl_add_u64 v[2:3], v[2:3], 1, s[22:23]
	global_store_short v[2:3], v15, off sc1
	v_add_u32_e32 v2, v62, v175
	s_waitcnt lgkmcnt(0)
	v_add_f32_e32 v58, v58, v59
	v_ashrrev_i32_e32 v3, 31, v2
	ds_bpermute_b32 v59, v13, v58
	v_lshl_add_u64 v[2:3], v[2:3], 1, s[22:23]
	v_add_u32_e32 v61, 0x540, v61
	global_store_short v[2:3], v60, off sc1
	v_or_b32_e32 v2, v61, v174
	v_ashrrev_i32_e32 v3, 31, v2
	v_lshl_add_u64 v[2:3], v[2:3], 1, s[22:23]
	global_store_short v[2:3], v15, off sc1
	s_waitcnt lgkmcnt(0)
	v_add_f32_e32 v3, v58, v59
	v_fmamk_f32 v3, v3, 0x3c800000, v209
	v_rsq_f32_e32 v58, v3
	v_or_b32_e32 v2, v61, v175
	v_ashrrev_i32_e32 v3, 31, v2
	v_lshl_add_u64 v[2:3], v[2:3], 1, s[22:23]
	global_store_short v[2:3], v60, off sc1
	v_pk_mul_f32 v[2:3], v[0:1], v[58:59] op_sel_hi:[1,0]
	s_and_b64 vcc, exec, s[4:5]
	v_pk_mul_f32 v[2:3], v[50:51], v[2:3]
	s_mov_b64 s[80:81], -1
	s_cbranch_vccnz .LBB0_306
	v_add_u32_e32 v15, s76, v184
	v_lshl_or_b32 v58, v15, 6, v156
	v_ashrrev_i32_e32 v59, 31, v58
	v_lshl_add_u64 v[58:59], v[58:59], 2, s[24:25]
	s_mov_b64 s[80:81], 0
	global_store_dword v[58:59], v3, off sc1
	global_store_dword v[58:59], v2, off offset:128 sc1

.LBB0_308:
	v_cvt_pk_bf16_f32 v60, v2, s0
	v_add_u32_e32 v2, s11, v184
	v_mul_lo_u32 v61, v2, s94
	v_or_b32_e32 v2, v61, v174
	v_cvt_pk_bf16_f32 v15, v3, s0
	v_ashrrev_i32_e32 v3, 31, v2
	v_lshl_add_u64 v[2:3], v[2:3], 1, s[22:23]
	global_store_short v[2:3], v15, off sc1
	v_or_b32_e32 v2, v61, v175
	v_ashrrev_i32_e32 v3, 31, v2
	v_lshl_add_u64 v[2:3], v[2:3], 1, s[22:23]
	v_or_b32_e32 v58, 0xc0, v61
	global_store_short v[2:3], v60, off sc1
	v_add_u32_e32 v2, v58, v174
	v_ashrrev_i32_e32 v3, 31, v2
	v_lshl_add_u64 v[2:3], v[2:3], 1, s[22:23]
	global_store_short v[2:3], v15, off sc1
	v_add_u32_e32 v2, v58, v175
	v_ashrrev_i32_e32 v3, 31, v2
	v_lshl_add_u64 v[2:3], v[2:3], 1, s[22:23]
	v_or_b32_e32 v58, 0x180, v61
	global_store_short v[2:3], v60, off sc1
	v_add_u32_e32 v2, v58, v174
	v_ashrrev_i32_e32 v3, 31, v2
	v_lshl_add_u64 v[2:3], v[2:3], 1, s[22:23]
	global_store_short v[2:3], v15, off sc1
	v_add_u32_e32 v2, v58, v175
	v_ashrrev_i32_e32 v3, 31, v2
	v_lshl_add_u64 v[2:3], v[2:3], 1, s[22:23]
	v_add_u32_e32 v58, 0x240, v61
	global_store_short v[2:3], v60, off sc1
	v_or_b32_e32 v2, v58, v174
	v_ashrrev_i32_e32 v3, 31, v2
	v_lshl_add_u64 v[2:3], v[2:3], 1, s[22:23]
	global_store_short v[2:3], v15, off sc1
	v_or_b32_e32 v2, v58, v175
	v_ashrrev_i32_e32 v3, 31, v2
	v_lshl_add_u64 v[2:3], v[2:3], 1, s[22:23]
	v_add_u32_e32 v58, 0x300, v61
	global_store_short v[2:3], v60, off sc1
	v_or_b32_e32 v2, v58, v174
	v_ashrrev_i32_e32 v3, 31, v2
	v_lshl_add_u64 v[2:3], v[2:3], 1, s[22:23]
	global_store_short v[2:3], v15, off sc1
	v_or_b32_e32 v2, v58, v175
	v_pk_mul_f32 v[58:59], v[48:49], v[48:49]
	v_ashrrev_i32_e32 v3, 31, v2
	v_add_f32_e32 v58, v59, v58
	s_nop 1
	v_mov_b32_dpp v59, v58 quad_perm:[1,0,3,2] row_mask:0xf bank_mask:0xf
	v_lshl_add_u64 v[2:3], v[2:3], 1, s[22:23]
	v_add_u32_e32 v62, 0x3c0, v61
	global_store_short v[2:3], v60, off sc1
	v_add_u32_e32 v2, v62, v174
	s_waitcnt lgkmcnt(0)
	v_add_f32_e32 v58, v58, v59
	s_nop 1
	v_mov_b32_dpp v59, v58 quad_perm:[2,3,0,1] row_mask:0xf bank_mask:0xf
	v_ashrrev_i32_e32 v3, 31, v2
	v_lshl_add_u64 v[2:3], v[2:3], 1, s[22:23]
	global_store_short v[2:3], v15, off sc1
	v_add_u32_e32 v2, v62, v175
	s_waitcnt lgkmcnt(0)
	v_add_f32_e32 v58, v58, v59
	s_nop 1
	v_mov_b32_dpp v59, v58 row_half_mirror row_mask:0xf bank_mask:0xf
	v_ashrrev_i32_e32 v3, 31, v2
	v_lshl_add_u64 v[2:3], v[2:3], 1, s[22:23]
	v_add_u32_e32 v62, 0x480, v61
	global_store_short v[2:3], v60, off sc1
	s_waitcnt lgkmcnt(0)
	v_add_f32_e32 v58, v58, v59
	s_nop 1
	v_mov_b32_dpp v59, v58 row_mirror row_mask:0xf bank_mask:0xf
	v_add_u32_e32 v2, v62, v174
	v_ashrrev_i32_e32 v3, 31, v2
	v_lshl_add_u64 v[2:3], v[2:3], 1, s[22:23]
	global_store_short v[2:3], v15, off sc1
	v_add_u32_e32 v2, v62, v175
	s_waitcnt lgkmcnt(0)
	v_add_f32_e32 v58, v58, v59
	v_ashrrev_i32_e32 v3, 31, v2
	ds_bpermute_b32 v59, v13, v58
	v_lshl_add_u64 v[2:3], v[2:3], 1, s[22:23]
	v_add_u32_e32 v61, 0x540, v61
	global_store_short v[2:3], v60, off sc1
	v_or_b32_e32 v2, v61, v174
	v_ashrrev_i32_e32 v3, 31, v2
	v_lshl_add_u64 v[2:3], v[2:3], 1, s[22:23]
	global_store_short v[2:3], v15, off sc1
	s_waitcnt lgkmcnt(0)
	v_add_f32_e32 v3, v58, v59
	v_fmamk_f32 v3, v3, 0x3c800000, v209
	v_rsq_f32_e32 v58, v3
	v_or_b32_e32 v2, v61, v175
	v_ashrrev_i32_e32 v3, 31, v2
	v_lshl_add_u64 v[2:3], v[2:3], 1, s[22:23]
	global_store_short v[2:3], v60, off sc1
	v_pk_mul_f32 v[2:3], v[0:1], v[58:59] op_sel_hi:[1,0]
	s_and_b64 vcc, exec, s[4:5]
	v_pk_mul_f32 v[2:3], v[48:49], v[2:3]
	s_mov_b64 s[80:81], -1
	s_cbranch_vccnz .LBB0_310
	v_add_u32_e32 v15, s76, v185
	v_lshl_or_b32 v58, v15, 6, v156
	v_ashrrev_i32_e32 v59, 31, v58
	v_lshl_add_u64 v[58:59], v[58:59], 2, s[24:25]
	s_mov_b64 s[80:81], 0
	global_store_dword v[58:59], v3, off sc1
	global_store_dword v[58:59], v2, off offset:128 sc1

.LBB0_312:
	v_cvt_pk_bf16_f32 v60, v2, s0
	v_add_u32_e32 v2, s11, v185
	v_mul_lo_u32 v61, v2, s94
	v_or_b32_e32 v2, v61, v174
	v_cvt_pk_bf16_f32 v15, v3, s0
	v_ashrrev_i32_e32 v3, 31, v2
	v_lshl_add_u64 v[2:3], v[2:3], 1, s[22:23]
	global_store_short v[2:3], v15, off sc1
	v_or_b32_e32 v2, v61, v175
	v_ashrrev_i32_e32 v3, 31, v2
	v_lshl_add_u64 v[2:3], v[2:3], 1, s[22:23]
	v_or_b32_e32 v58, 0xc0, v61
	global_store_short v[2:3], v60, off sc1
	v_add_u32_e32 v2, v58, v174
	v_ashrrev_i32_e32 v3, 31, v2
	v_lshl_add_u64 v[2:3], v[2:3], 1, s[22:23]
	global_store_short v[2:3], v15, off sc1
	v_add_u32_e32 v2, v58, v175
	v_ashrrev_i32_e32 v3, 31, v2
	v_lshl_add_u64 v[2:3], v[2:3], 1, s[22:23]
	v_or_b32_e32 v58, 0x180, v61
	global_store_short v[2:3], v60, off sc1
	v_add_u32_e32 v2, v58, v174
	v_ashrrev_i32_e32 v3, 31, v2
	v_lshl_add_u64 v[2:3], v[2:3], 1, s[22:23]
	global_store_short v[2:3], v15, off sc1
	v_add_u32_e32 v2, v58, v175
	v_ashrrev_i32_e32 v3, 31, v2
	v_lshl_add_u64 v[2:3], v[2:3], 1, s[22:23]
	v_add_u32_e32 v58, 0x240, v61
	global_store_short v[2:3], v60, off sc1
	v_or_b32_e32 v2, v58, v174
	v_ashrrev_i32_e32 v3, 31, v2
	v_lshl_add_u64 v[2:3], v[2:3], 1, s[22:23]
	global_store_short v[2:3], v15, off sc1
	v_or_b32_e32 v2, v58, v175
	v_ashrrev_i32_e32 v3, 31, v2
	v_lshl_add_u64 v[2:3], v[2:3], 1, s[22:23]
	v_add_u32_e32 v58, 0x300, v61
	global_store_short v[2:3], v60, off sc1
	v_or_b32_e32 v2, v58, v174
	v_ashrrev_i32_e32 v3, 31, v2
	v_lshl_add_u64 v[2:3], v[2:3], 1, s[22:23]
	global_store_short v[2:3], v15, off sc1
	v_or_b32_e32 v2, v58, v175
	v_pk_mul_f32 v[58:59], v[40:41], v[40:41]
	v_ashrrev_i32_e32 v3, 31, v2
	v_add_f32_e32 v58, v59, v58
	s_nop 1
	v_mov_b32_dpp v59, v58 quad_perm:[1,0,3,2] row_mask:0xf bank_mask:0xf
	v_lshl_add_u64 v[2:3], v[2:3], 1, s[22:23]
	v_add_u32_e32 v62, 0x3c0, v61
	global_store_short v[2:3], v60, off sc1
	v_add_u32_e32 v2, v62, v174
	s_waitcnt lgkmcnt(0)
	v_add_f32_e32 v58, v58, v59
	s_nop 1
	v_mov_b32_dpp v59, v58 quad_perm:[2,3,0,1] row_mask:0xf bank_mask:0xf
	v_ashrrev_i32_e32 v3, 31, v2
	v_lshl_add_u64 v[2:3], v[2:3], 1, s[22:23]
	global_store_short v[2:3], v15, off sc1
	v_add_u32_e32 v2, v62, v175
	s_waitcnt lgkmcnt(0)
	v_add_f32_e32 v58, v58, v59
	s_nop 1
	v_mov_b32_dpp v59, v58 row_half_mirror row_mask:0xf bank_mask:0xf
	v_ashrrev_i32_e32 v3, 31, v2
	v_lshl_add_u64 v[2:3], v[2:3], 1, s[22:23]
	v_add_u32_e32 v62, 0x480, v61
	global_store_short v[2:3], v60, off sc1
	s_waitcnt lgkmcnt(0)
	v_add_f32_e32 v58, v58, v59
	s_nop 1
	v_mov_b32_dpp v59, v58 row_mirror row_mask:0xf bank_mask:0xf
	v_add_u32_e32 v2, v62, v174
	v_ashrrev_i32_e32 v3, 31, v2
	v_lshl_add_u64 v[2:3], v[2:3], 1, s[22:23]
	global_store_short v[2:3], v15, off sc1
	v_add_u32_e32 v2, v62, v175
	s_waitcnt lgkmcnt(0)
	v_add_f32_e32 v58, v58, v59
	v_ashrrev_i32_e32 v3, 31, v2
	ds_bpermute_b32 v59, v13, v58
	v_lshl_add_u64 v[2:3], v[2:3], 1, s[22:23]
	v_add_u32_e32 v61, 0x540, v61
	global_store_short v[2:3], v60, off sc1
	v_or_b32_e32 v2, v61, v174
	v_ashrrev_i32_e32 v3, 31, v2
	v_lshl_add_u64 v[2:3], v[2:3], 1, s[22:23]
	global_store_short v[2:3], v15, off sc1
	s_waitcnt lgkmcnt(0)
	v_add_f32_e32 v3, v58, v59
	v_fmamk_f32 v3, v3, 0x3c800000, v209
	v_rsq_f32_e32 v58, v3
	v_or_b32_e32 v2, v61, v175
	v_ashrrev_i32_e32 v3, 31, v2
	v_lshl_add_u64 v[2:3], v[2:3], 1, s[22:23]
	global_store_short v[2:3], v60, off sc1
	v_pk_mul_f32 v[2:3], v[0:1], v[58:59] op_sel_hi:[1,0]
	s_and_b64 vcc, exec, s[4:5]
	v_pk_mul_f32 v[2:3], v[40:41], v[2:3]
	s_mov_b64 s[80:81], -1
	s_cbranch_vccnz .LBB0_314
	v_add_u32_e32 v15, s76, v186
	v_lshl_or_b32 v58, v15, 6, v156
	v_ashrrev_i32_e32 v59, 31, v58
	v_lshl_add_u64 v[58:59], v[58:59], 2, s[24:25]
	s_mov_b64 s[80:81], 0
	global_store_dword v[58:59], v3, off sc1
	global_store_dword v[58:59], v2, off offset:128 sc1

.LBB0_316:
	v_cvt_pk_bf16_f32 v60, v2, s0
	v_add_u32_e32 v2, s11, v186
	v_mul_lo_u32 v61, v2, s94
	v_or_b32_e32 v2, v61, v174
	v_cvt_pk_bf16_f32 v15, v3, s0
	v_ashrrev_i32_e32 v3, 31, v2
	v_lshl_add_u64 v[2:3], v[2:3], 1, s[22:23]
	global_store_short v[2:3], v15, off sc1
	v_or_b32_e32 v2, v61, v175
	v_ashrrev_i32_e32 v3, 31, v2
	v_lshl_add_u64 v[2:3], v[2:3], 1, s[22:23]
	v_or_b32_e32 v58, 0xc0, v61
	global_store_short v[2:3], v60, off sc1
	v_add_u32_e32 v2, v58, v174
	v_ashrrev_i32_e32 v3, 31, v2
	v_lshl_add_u64 v[2:3], v[2:3], 1, s[22:23]
	global_store_short v[2:3], v15, off sc1
	v_add_u32_e32 v2, v58, v175
	v_ashrrev_i32_e32 v3, 31, v2
	v_lshl_add_u64 v[2:3], v[2:3], 1, s[22:23]
	v_or_b32_e32 v58, 0x180, v61
	global_store_short v[2:3], v60, off sc1
	v_add_u32_e32 v2, v58, v174
	v_ashrrev_i32_e32 v3, 31, v2
	v_lshl_add_u64 v[2:3], v[2:3], 1, s[22:23]
	global_store_short v[2:3], v15, off sc1
	v_add_u32_e32 v2, v58, v175
	v_ashrrev_i32_e32 v3, 31, v2
	v_lshl_add_u64 v[2:3], v[2:3], 1, s[22:23]
	v_add_u32_e32 v58, 0x240, v61
	global_store_short v[2:3], v60, off sc1
	v_or_b32_e32 v2, v58, v174
	v_ashrrev_i32_e32 v3, 31, v2
	v_lshl_add_u64 v[2:3], v[2:3], 1, s[22:23]
	global_store_short v[2:3], v15, off sc1
	v_or_b32_e32 v2, v58, v175
	v_ashrrev_i32_e32 v3, 31, v2
	v_lshl_add_u64 v[2:3], v[2:3], 1, s[22:23]
	v_add_u32_e32 v58, 0x300, v61
	global_store_short v[2:3], v60, off sc1
	v_or_b32_e32 v2, v58, v174
	v_ashrrev_i32_e32 v3, 31, v2
	v_lshl_add_u64 v[2:3], v[2:3], 1, s[22:23]
	global_store_short v[2:3], v15, off sc1
	v_or_b32_e32 v2, v58, v175
	v_pk_mul_f32 v[58:59], v[38:39], v[38:39]
	v_ashrrev_i32_e32 v3, 31, v2
	v_add_f32_e32 v58, v59, v58
	s_nop 1
	v_mov_b32_dpp v59, v58 quad_perm:[1,0,3,2] row_mask:0xf bank_mask:0xf
	v_lshl_add_u64 v[2:3], v[2:3], 1, s[22:23]
	v_add_u32_e32 v62, 0x3c0, v61
	global_store_short v[2:3], v60, off sc1
	v_add_u32_e32 v2, v62, v174
	s_waitcnt lgkmcnt(0)
	v_add_f32_e32 v58, v58, v59
	s_nop 1
	v_mov_b32_dpp v59, v58 quad_perm:[2,3,0,1] row_mask:0xf bank_mask:0xf
	v_ashrrev_i32_e32 v3, 31, v2
	v_lshl_add_u64 v[2:3], v[2:3], 1, s[22:23]
	global_store_short v[2:3], v15, off sc1
	v_add_u32_e32 v2, v62, v175
	s_waitcnt lgkmcnt(0)
	v_add_f32_e32 v58, v58, v59
	s_nop 1
	v_mov_b32_dpp v59, v58 row_half_mirror row_mask:0xf bank_mask:0xf
	v_ashrrev_i32_e32 v3, 31, v2
	v_lshl_add_u64 v[2:3], v[2:3], 1, s[22:23]
	v_add_u32_e32 v62, 0x480, v61
	global_store_short v[2:3], v60, off sc1
	s_waitcnt lgkmcnt(0)
	v_add_f32_e32 v58, v58, v59
	s_nop 1
	v_mov_b32_dpp v59, v58 row_mirror row_mask:0xf bank_mask:0xf
	v_add_u32_e32 v2, v62, v174
	v_ashrrev_i32_e32 v3, 31, v2
	v_lshl_add_u64 v[2:3], v[2:3], 1, s[22:23]
	global_store_short v[2:3], v15, off sc1
	v_add_u32_e32 v2, v62, v175
	s_waitcnt lgkmcnt(0)
	v_add_f32_e32 v58, v58, v59
	v_ashrrev_i32_e32 v3, 31, v2
	ds_bpermute_b32 v59, v13, v58
	v_lshl_add_u64 v[2:3], v[2:3], 1, s[22:23]
	v_add_u32_e32 v61, 0x540, v61
	global_store_short v[2:3], v60, off sc1
	v_or_b32_e32 v2, v61, v174
	v_ashrrev_i32_e32 v3, 31, v2
	v_lshl_add_u64 v[2:3], v[2:3], 1, s[22:23]
	global_store_short v[2:3], v15, off sc1
	s_waitcnt lgkmcnt(0)
	v_add_f32_e32 v3, v58, v59
	v_fmamk_f32 v3, v3, 0x3c800000, v209
	v_rsq_f32_e32 v58, v3
	v_or_b32_e32 v2, v61, v175
	v_ashrrev_i32_e32 v3, 31, v2
	v_lshl_add_u64 v[2:3], v[2:3], 1, s[22:23]
	global_store_short v[2:3], v60, off sc1
	v_pk_mul_f32 v[2:3], v[0:1], v[58:59] op_sel_hi:[1,0]
	s_and_b64 vcc, exec, s[4:5]
	v_pk_mul_f32 v[2:3], v[38:39], v[2:3]
	s_mov_b64 s[80:81], -1
	s_cbranch_vccnz .LBB0_318
	v_add_u32_e32 v15, s76, v187
	v_lshl_or_b32 v58, v15, 6, v156
	v_ashrrev_i32_e32 v59, 31, v58
	v_lshl_add_u64 v[58:59], v[58:59], 2, s[24:25]
	s_mov_b64 s[80:81], 0
	global_store_dword v[58:59], v3, off sc1
	global_store_dword v[58:59], v2, off offset:128 sc1

.LBB0_320:
	v_cvt_pk_bf16_f32 v60, v2, s0
	v_add_u32_e32 v2, s11, v187
	v_mul_lo_u32 v61, v2, s94
	v_or_b32_e32 v2, v61, v174
	v_cvt_pk_bf16_f32 v15, v3, s0
	v_ashrrev_i32_e32 v3, 31, v2
	v_lshl_add_u64 v[2:3], v[2:3], 1, s[22:23]
	global_store_short v[2:3], v15, off sc1
	v_or_b32_e32 v2, v61, v175
	v_ashrrev_i32_e32 v3, 31, v2
	v_lshl_add_u64 v[2:3], v[2:3], 1, s[22:23]
	v_or_b32_e32 v58, 0xc0, v61
	global_store_short v[2:3], v60, off sc1
	v_add_u32_e32 v2, v58, v174
	v_ashrrev_i32_e32 v3, 31, v2
	v_lshl_add_u64 v[2:3], v[2:3], 1, s[22:23]
	global_store_short v[2:3], v15, off sc1
	v_add_u32_e32 v2, v58, v175
	v_ashrrev_i32_e32 v3, 31, v2
	v_lshl_add_u64 v[2:3], v[2:3], 1, s[22:23]
	v_or_b32_e32 v58, 0x180, v61
	global_store_short v[2:3], v60, off sc1
	v_add_u32_e32 v2, v58, v174
	v_ashrrev_i32_e32 v3, 31, v2
	v_lshl_add_u64 v[2:3], v[2:3], 1, s[22:23]
	global_store_short v[2:3], v15, off sc1
	v_add_u32_e32 v2, v58, v175
	v_ashrrev_i32_e32 v3, 31, v2
	v_lshl_add_u64 v[2:3], v[2:3], 1, s[22:23]
	v_add_u32_e32 v58, 0x240, v61
	global_store_short v[2:3], v60, off sc1
	v_or_b32_e32 v2, v58, v174
	v_ashrrev_i32_e32 v3, 31, v2
	v_lshl_add_u64 v[2:3], v[2:3], 1, s[22:23]
	global_store_short v[2:3], v15, off sc1
	v_or_b32_e32 v2, v58, v175
	v_ashrrev_i32_e32 v3, 31, v2
	v_lshl_add_u64 v[2:3], v[2:3], 1, s[22:23]
	v_add_u32_e32 v58, 0x300, v61
	global_store_short v[2:3], v60, off sc1
	v_or_b32_e32 v2, v58, v174
	v_ashrrev_i32_e32 v3, 31, v2
	v_lshl_add_u64 v[2:3], v[2:3], 1, s[22:23]
	global_store_short v[2:3], v15, off sc1
	v_or_b32_e32 v2, v58, v175
	v_pk_mul_f32 v[58:59], v[36:37], v[36:37]
	v_ashrrev_i32_e32 v3, 31, v2
	v_add_f32_e32 v58, v59, v58
	s_nop 1
	v_mov_b32_dpp v59, v58 quad_perm:[1,0,3,2] row_mask:0xf bank_mask:0xf
	v_lshl_add_u64 v[2:3], v[2:3], 1, s[22:23]
	v_add_u32_e32 v62, 0x3c0, v61
	global_store_short v[2:3], v60, off sc1
	v_add_u32_e32 v2, v62, v174
	s_waitcnt lgkmcnt(0)
	v_add_f32_e32 v58, v58, v59
	s_nop 1
	v_mov_b32_dpp v59, v58 quad_perm:[2,3,0,1] row_mask:0xf bank_mask:0xf
	v_ashrrev_i32_e32 v3, 31, v2
	v_lshl_add_u64 v[2:3], v[2:3], 1, s[22:23]
	global_store_short v[2:3], v15, off sc1
	v_add_u32_e32 v2, v62, v175
	s_waitcnt lgkmcnt(0)
	v_add_f32_e32 v58, v58, v59
	s_nop 1
	v_mov_b32_dpp v59, v58 row_half_mirror row_mask:0xf bank_mask:0xf
	v_ashrrev_i32_e32 v3, 31, v2
	v_lshl_add_u64 v[2:3], v[2:3], 1, s[22:23]
	v_add_u32_e32 v62, 0x480, v61
	global_store_short v[2:3], v60, off sc1
	s_waitcnt lgkmcnt(0)
	v_add_f32_e32 v58, v58, v59
	s_nop 1
	v_mov_b32_dpp v59, v58 row_mirror row_mask:0xf bank_mask:0xf
	v_add_u32_e32 v2, v62, v174
	v_ashrrev_i32_e32 v3, 31, v2
	v_lshl_add_u64 v[2:3], v[2:3], 1, s[22:23]
	global_store_short v[2:3], v15, off sc1
	v_add_u32_e32 v2, v62, v175
	s_waitcnt lgkmcnt(0)
	v_add_f32_e32 v58, v58, v59
	v_ashrrev_i32_e32 v3, 31, v2
	ds_bpermute_b32 v59, v13, v58
	v_lshl_add_u64 v[2:3], v[2:3], 1, s[22:23]
	v_add_u32_e32 v61, 0x540, v61
	global_store_short v[2:3], v60, off sc1
	v_or_b32_e32 v2, v61, v174
	v_ashrrev_i32_e32 v3, 31, v2
	v_lshl_add_u64 v[2:3], v[2:3], 1, s[22:23]
	global_store_short v[2:3], v15, off sc1
	s_waitcnt lgkmcnt(0)
	v_add_f32_e32 v3, v58, v59
	v_fmamk_f32 v3, v3, 0x3c800000, v209
	v_rsq_f32_e32 v58, v3
	v_or_b32_e32 v2, v61, v175
	v_ashrrev_i32_e32 v3, 31, v2
	v_lshl_add_u64 v[2:3], v[2:3], 1, s[22:23]
	global_store_short v[2:3], v60, off sc1
	v_pk_mul_f32 v[2:3], v[0:1], v[58:59] op_sel_hi:[1,0]
	s_and_b64 vcc, exec, s[4:5]
	v_pk_mul_f32 v[2:3], v[36:37], v[2:3]
	s_mov_b64 s[80:81], -1
	s_cbranch_vccnz .LBB0_322
	v_add_u32_e32 v15, s76, v188
	v_lshl_or_b32 v58, v15, 6, v156
	v_ashrrev_i32_e32 v59, 31, v58
	v_lshl_add_u64 v[58:59], v[58:59], 2, s[24:25]
	s_mov_b64 s[80:81], 0
	global_store_dword v[58:59], v3, off sc1
	global_store_dword v[58:59], v2, off offset:128 sc1

.LBB0_324:
	v_cvt_pk_bf16_f32 v60, v2, s0
	v_add_u32_e32 v2, s11, v188
	v_mul_lo_u32 v61, v2, s94
	v_or_b32_e32 v2, v61, v174
	v_cvt_pk_bf16_f32 v15, v3, s0
	v_ashrrev_i32_e32 v3, 31, v2
	v_lshl_add_u64 v[2:3], v[2:3], 1, s[22:23]
	global_store_short v[2:3], v15, off sc1
	v_or_b32_e32 v2, v61, v175
	v_ashrrev_i32_e32 v3, 31, v2
	v_lshl_add_u64 v[2:3], v[2:3], 1, s[22:23]
	v_or_b32_e32 v58, 0xc0, v61
	global_store_short v[2:3], v60, off sc1
	v_add_u32_e32 v2, v58, v174
	v_ashrrev_i32_e32 v3, 31, v2
	v_lshl_add_u64 v[2:3], v[2:3], 1, s[22:23]
	global_store_short v[2:3], v15, off sc1
	v_add_u32_e32 v2, v58, v175
	v_ashrrev_i32_e32 v3, 31, v2
	v_lshl_add_u64 v[2:3], v[2:3], 1, s[22:23]
	v_or_b32_e32 v58, 0x180, v61
	global_store_short v[2:3], v60, off sc1
	v_add_u32_e32 v2, v58, v174
	v_ashrrev_i32_e32 v3, 31, v2
	v_lshl_add_u64 v[2:3], v[2:3], 1, s[22:23]
	global_store_short v[2:3], v15, off sc1
	v_add_u32_e32 v2, v58, v175
	v_ashrrev_i32_e32 v3, 31, v2
	v_lshl_add_u64 v[2:3], v[2:3], 1, s[22:23]
	v_add_u32_e32 v58, 0x240, v61
	global_store_short v[2:3], v60, off sc1
	v_or_b32_e32 v2, v58, v174
	v_ashrrev_i32_e32 v3, 31, v2
	v_lshl_add_u64 v[2:3], v[2:3], 1, s[22:23]
	global_store_short v[2:3], v15, off sc1
	v_or_b32_e32 v2, v58, v175
	v_ashrrev_i32_e32 v3, 31, v2
	v_lshl_add_u64 v[2:3], v[2:3], 1, s[22:23]
	v_add_u32_e32 v58, 0x300, v61
	global_store_short v[2:3], v60, off sc1
	v_or_b32_e32 v2, v58, v174
	v_ashrrev_i32_e32 v3, 31, v2
	v_lshl_add_u64 v[2:3], v[2:3], 1, s[22:23]
	global_store_short v[2:3], v15, off sc1
	v_or_b32_e32 v2, v58, v175
	v_pk_mul_f32 v[58:59], v[34:35], v[34:35]
	v_ashrrev_i32_e32 v3, 31, v2
	v_add_f32_e32 v58, v59, v58
	s_nop 1
	v_mov_b32_dpp v59, v58 quad_perm:[1,0,3,2] row_mask:0xf bank_mask:0xf
	v_lshl_add_u64 v[2:3], v[2:3], 1, s[22:23]
	v_add_u32_e32 v62, 0x3c0, v61
	global_store_short v[2:3], v60, off sc1
	v_add_u32_e32 v2, v62, v174
	s_waitcnt lgkmcnt(0)
	v_add_f32_e32 v58, v58, v59
	s_nop 1
	v_mov_b32_dpp v59, v58 quad_perm:[2,3,0,1] row_mask:0xf bank_mask:0xf
	v_ashrrev_i32_e32 v3, 31, v2
	v_lshl_add_u64 v[2:3], v[2:3], 1, s[22:23]
	global_store_short v[2:3], v15, off sc1
	v_add_u32_e32 v2, v62, v175
	s_waitcnt lgkmcnt(0)
	v_add_f32_e32 v58, v58, v59
	s_nop 1
	v_mov_b32_dpp v59, v58 row_half_mirror row_mask:0xf bank_mask:0xf
	v_ashrrev_i32_e32 v3, 31, v2
	v_lshl_add_u64 v[2:3], v[2:3], 1, s[22:23]
	v_add_u32_e32 v62, 0x480, v61
	global_store_short v[2:3], v60, off sc1
	s_waitcnt lgkmcnt(0)
	v_add_f32_e32 v58, v58, v59
	s_nop 1
	v_mov_b32_dpp v59, v58 row_mirror row_mask:0xf bank_mask:0xf
	v_add_u32_e32 v2, v62, v174
	v_ashrrev_i32_e32 v3, 31, v2
	v_lshl_add_u64 v[2:3], v[2:3], 1, s[22:23]
	global_store_short v[2:3], v15, off sc1
	v_add_u32_e32 v2, v62, v175
	s_waitcnt lgkmcnt(0)
	v_add_f32_e32 v58, v58, v59
	v_ashrrev_i32_e32 v3, 31, v2
	ds_bpermute_b32 v59, v13, v58
	v_lshl_add_u64 v[2:3], v[2:3], 1, s[22:23]
	v_add_u32_e32 v61, 0x540, v61
	global_store_short v[2:3], v60, off sc1
	v_or_b32_e32 v2, v61, v174
	v_ashrrev_i32_e32 v3, 31, v2
	v_lshl_add_u64 v[2:3], v[2:3], 1, s[22:23]
	global_store_short v[2:3], v15, off sc1
	s_waitcnt lgkmcnt(0)
	v_add_f32_e32 v3, v58, v59
	v_fmamk_f32 v3, v3, 0x3c800000, v209
	v_rsq_f32_e32 v58, v3
	v_or_b32_e32 v2, v61, v175
	v_ashrrev_i32_e32 v3, 31, v2
	v_lshl_add_u64 v[2:3], v[2:3], 1, s[22:23]
	global_store_short v[2:3], v60, off sc1
	v_pk_mul_f32 v[2:3], v[0:1], v[58:59] op_sel_hi:[1,0]
	s_and_b64 vcc, exec, s[4:5]
	v_pk_mul_f32 v[2:3], v[34:35], v[2:3]
	s_mov_b64 s[80:81], -1
	s_cbranch_vccnz .LBB0_326
	v_add_u32_e32 v15, s76, v189
	v_lshl_or_b32 v58, v15, 6, v156
	v_ashrrev_i32_e32 v59, 31, v58
	v_lshl_add_u64 v[58:59], v[58:59], 2, s[24:25]
	s_mov_b64 s[80:81], 0
	global_store_dword v[58:59], v3, off sc1
	global_store_dword v[58:59], v2, off offset:128 sc1

.LBB0_328:
	v_cvt_pk_bf16_f32 v60, v2, s0
	v_add_u32_e32 v2, s11, v189
	v_mul_lo_u32 v61, v2, s94
	v_or_b32_e32 v2, v61, v174
	v_cvt_pk_bf16_f32 v15, v3, s0
	v_ashrrev_i32_e32 v3, 31, v2
	v_lshl_add_u64 v[2:3], v[2:3], 1, s[22:23]
	global_store_short v[2:3], v15, off sc1
	v_or_b32_e32 v2, v61, v175
	v_ashrrev_i32_e32 v3, 31, v2
	v_lshl_add_u64 v[2:3], v[2:3], 1, s[22:23]
	v_or_b32_e32 v58, 0xc0, v61
	global_store_short v[2:3], v60, off sc1
	v_add_u32_e32 v2, v58, v174
	v_ashrrev_i32_e32 v3, 31, v2
	v_lshl_add_u64 v[2:3], v[2:3], 1, s[22:23]
	global_store_short v[2:3], v15, off sc1
	v_add_u32_e32 v2, v58, v175
	v_ashrrev_i32_e32 v3, 31, v2
	v_lshl_add_u64 v[2:3], v[2:3], 1, s[22:23]
	v_or_b32_e32 v58, 0x180, v61
	global_store_short v[2:3], v60, off sc1
	v_add_u32_e32 v2, v58, v174
	v_ashrrev_i32_e32 v3, 31, v2
	v_lshl_add_u64 v[2:3], v[2:3], 1, s[22:23]
	global_store_short v[2:3], v15, off sc1
	v_add_u32_e32 v2, v58, v175
	v_ashrrev_i32_e32 v3, 31, v2
	v_lshl_add_u64 v[2:3], v[2:3], 1, s[22:23]
	v_add_u32_e32 v58, 0x240, v61
	global_store_short v[2:3], v60, off sc1
	v_or_b32_e32 v2, v58, v174
	v_ashrrev_i32_e32 v3, 31, v2
	v_lshl_add_u64 v[2:3], v[2:3], 1, s[22:23]
	global_store_short v[2:3], v15, off sc1
	v_or_b32_e32 v2, v58, v175
	v_ashrrev_i32_e32 v3, 31, v2
	v_lshl_add_u64 v[2:3], v[2:3], 1, s[22:23]
	v_add_u32_e32 v58, 0x300, v61
	global_store_short v[2:3], v60, off sc1
	v_or_b32_e32 v2, v58, v174
	v_ashrrev_i32_e32 v3, 31, v2
	v_lshl_add_u64 v[2:3], v[2:3], 1, s[22:23]
	global_store_short v[2:3], v15, off sc1
	v_or_b32_e32 v2, v58, v175
	v_pk_mul_f32 v[58:59], v[32:33], v[32:33]
	v_ashrrev_i32_e32 v3, 31, v2
	v_add_f32_e32 v58, v59, v58
	s_nop 1
	v_mov_b32_dpp v14, v58 quad_perm:[1,0,3,2] row_mask:0xf bank_mask:0xf
	v_lshl_add_u64 v[2:3], v[2:3], 1, s[22:23]
	v_add_u32_e32 v62, 0x3c0, v61
	global_store_short v[2:3], v60, off sc1
	v_add_u32_e32 v2, v62, v174
	s_waitcnt lgkmcnt(0)
	v_add_f32_e32 v14, v58, v14
	s_nop 1
	v_mov_b32_dpp v10, v14 quad_perm:[2,3,0,1] row_mask:0xf bank_mask:0xf
	v_ashrrev_i32_e32 v3, 31, v2
	v_lshl_add_u64 v[2:3], v[2:3], 1, s[22:23]
	global_store_short v[2:3], v15, off sc1
	v_add_u32_e32 v2, v62, v175
	s_waitcnt lgkmcnt(0)
	v_add_f32_e32 v10, v14, v10
	s_nop 1
	v_mov_b32_dpp v11, v10 row_half_mirror row_mask:0xf bank_mask:0xf
	v_ashrrev_i32_e32 v3, 31, v2
	v_lshl_add_u64 v[2:3], v[2:3], 1, s[22:23]
	v_add_u32_e32 v58, 0x480, v61
	global_store_short v[2:3], v60, off sc1
	s_waitcnt lgkmcnt(0)
	v_add_f32_e32 v10, v10, v11
	s_nop 1
	v_mov_b32_dpp v11, v10 row_mirror row_mask:0xf bank_mask:0xf
	v_add_u32_e32 v2, v58, v174
	v_ashrrev_i32_e32 v3, 31, v2
	v_lshl_add_u64 v[2:3], v[2:3], 1, s[22:23]
	global_store_short v[2:3], v15, off sc1
	v_add_u32_e32 v2, v58, v175
	s_waitcnt lgkmcnt(0)
	v_add_f32_e32 v10, v10, v11
	v_ashrrev_i32_e32 v3, 31, v2
	ds_bpermute_b32 v11, v13, v10
	v_lshl_add_u64 v[2:3], v[2:3], 1, s[22:23]
	v_add_u32_e32 v12, 0x540, v61
	global_store_short v[2:3], v60, off sc1
	v_or_b32_e32 v2, v12, v174
	v_ashrrev_i32_e32 v3, 31, v2
	v_lshl_add_u64 v[2:3], v[2:3], 1, s[22:23]
	global_store_short v[2:3], v15, off sc1
	s_waitcnt lgkmcnt(0)
	v_add_f32_e32 v3, v10, v11
	v_fmamk_f32 v3, v3, 0x3c800000, v209
	v_rsq_f32_e32 v10, v3
	v_or_b32_e32 v2, v12, v175
	v_ashrrev_i32_e32 v3, 31, v2
	v_lshl_add_u64 v[2:3], v[2:3], 1, s[22:23]
	v_pk_mul_f32 v[0:1], v[0:1], v[10:11] op_sel_hi:[1,0]
	s_and_b64 vcc, exec, s[4:5]
	v_pk_mul_f32 v[0:1], v[32:33], v[0:1]
	s_mov_b64 s[80:81], -1
	global_store_short v[2:3], v60, off sc1
	s_cbranch_vccnz .LBB0_330
	v_add_u32_e32 v2, s76, v190
	v_lshl_or_b32 v2, v2, 6, v156
	v_ashrrev_i32_e32 v3, 31, v2
	v_lshl_add_u64 v[2:3], v[2:3], 2, s[24:25]
	s_mov_b64 s[80:81], 0
	global_store_dword v[2:3], v1, off sc1
	global_store_dword v[2:3], v0, off offset:128 sc1

.LBB0_462:
	v_pk_mul_f32 v[0:1], v[78:79], v[78:79]
	v_and_b32_e32 v2, 64, v214
	v_add_f32_e32 v0, v1, v0
	v_xor_b32_e32 v1, 1, v214
	v_add_u32_e32 v12, 64, v2
	v_cmp_lt_i32_e32 vcc, v1, v12
	v_fmac_f32_e32 v0, v57, v57
	v_fmac_f32_e32 v0, v56, v56
	v_cndmask_b32_e32 v1, v214, v1, vcc
	v_lshlrev_b32_e32 v2, 2, v1
	s_nop 1
	v_mov_b32_dpp v1, v0 quad_perm:[1,0,3,2] row_mask:0xf bank_mask:0xf
	v_xor_b32_e32 v3, 2, v214
	v_cmp_lt_i32_e32 vcc, v3, v12
	v_xor_b32_e32 v10, 4, v214
	v_xor_b32_e32 v11, 8, v214
	v_cndmask_b32_e32 v3, v214, v3, vcc
	v_lshlrev_b32_e32 v3, 2, v3
	s_waitcnt lgkmcnt(0)
	v_add_f32_e32 v0, v0, v1
	s_nop 1
	v_mov_b32_dpp v1, v0 quad_perm:[2,3,0,1] row_mask:0xf bank_mask:0xf
	v_cmp_lt_i32_e32 vcc, v10, v12
	v_xor_b32_e32 v13, 16, v214
	s_mul_i32 s4, s10, 0x4200
	v_cndmask_b32_e32 v10, v214, v10, vcc
	v_lshlrev_b32_e32 v10, 2, v10
	s_waitcnt lgkmcnt(0)
	v_add_f32_e32 v0, v0, v1
	s_nop 1
	v_mov_b32_dpp v1, v0 row_half_mirror row_mask:0xf bank_mask:0xf
	v_cmp_lt_i32_e32 vcc, v11, v12
	s_add_i32 s11, s11, s4
	s_waitcnt lgkmcnt(0)
	v_add_f32_e32 v0, v0, v1
	v_cndmask_b32_e32 v11, v214, v11, vcc
	v_lshlrev_b32_e32 v11, 2, v11
	s_nop 1
	v_mov_b32_dpp v1, v0 row_mirror row_mask:0xf bank_mask:0xf
	v_cmp_lt_i32_e32 vcc, v13, v12
	s_waitcnt lgkmcnt(0)
	v_add_f32_e32 v1, v0, v1
	v_cndmask_b32_e32 v12, v214, v13, vcc
	v_lshlrev_b32_e32 v12, 2, v12
	ds_bpermute_b32 v13, v12, v1
	v_add_u32_e32 v0, s11, v191
	s_and_saveexec_b64 s[4:5], s[0:1]
	s_cbranch_execz .LBB0_464
	s_waitcnt lgkmcnt(0)
	v_add_f32_e32 v13, v1, v13
	v_ashrrev_i32_e32 v1, 31, v0
	v_lshl_add_u64 v[14:15], v[0:1], 2, s[30:31]
	global_store_dword v[14:15], v13, off sc1
.LBB0_464:
	s_or_b64 exec, exec, s[4:5]
	v_pk_mul_f32 v[14:15], v[74:75], v[74:75]
	s_nop 0
	v_add_f32_e32 v1, v15, v14
	v_fmac_f32_e32 v1, v47, v47
	v_fmac_f32_e32 v1, v31, v31
	s_waitcnt lgkmcnt(0)
	s_nop 1
	v_mov_b32_dpp v13, v1 quad_perm:[1,0,3,2] row_mask:0xf bank_mask:0xf
	s_waitcnt lgkmcnt(0)
	v_add_f32_e32 v1, v1, v13
	s_nop 1
	v_mov_b32_dpp v13, v1 quad_perm:[2,3,0,1] row_mask:0xf bank_mask:0xf
	s_waitcnt lgkmcnt(0)
	v_add_f32_e32 v1, v1, v13
	s_nop 1
	v_mov_b32_dpp v13, v1 row_half_mirror row_mask:0xf bank_mask:0xf
	s_waitcnt lgkmcnt(0)
	v_add_f32_e32 v1, v1, v13
	s_nop 1
	v_mov_b32_dpp v13, v1 row_mirror row_mask:0xf bank_mask:0xf
	s_waitcnt lgkmcnt(0)
	v_add_f32_e32 v1, v1, v13
	ds_bpermute_b32 v13, v12, v1
	s_and_saveexec_b64 s[4:5], s[0:1]
	s_cbranch_execz .LBB0_466
	v_add_u32_e32 v14, 1, v0
	v_ashrrev_i32_e32 v15, 31, v14
	s_waitcnt lgkmcnt(0)
	v_add_f32_e32 v1, v1, v13
	v_lshl_add_u64 v[14:15], v[14:15], 2, s[30:31]
	global_store_dword v[14:15], v1, off sc1
.LBB0_466:
	s_or_b64 exec, exec, s[4:5]
	v_pk_mul_f32 v[14:15], v[72:73], v[72:73]
	s_nop 0
	v_add_f32_e32 v1, v15, v14
	v_fmac_f32_e32 v1, v46, v46
	v_fmac_f32_e32 v1, v30, v30
	s_waitcnt lgkmcnt(0)
	s_nop 1
	v_mov_b32_dpp v13, v1 quad_perm:[1,0,3,2] row_mask:0xf bank_mask:0xf
	s_waitcnt lgkmcnt(0)
	v_add_f32_e32 v1, v1, v13
	s_nop 1
	v_mov_b32_dpp v13, v1 quad_perm:[2,3,0,1] row_mask:0xf bank_mask:0xf
	s_waitcnt lgkmcnt(0)
	v_add_f32_e32 v1, v1, v13
	s_nop 1
	v_mov_b32_dpp v13, v1 row_half_mirror row_mask:0xf bank_mask:0xf
	s_waitcnt lgkmcnt(0)
	v_add_f32_e32 v1, v1, v13
	s_nop 1
	v_mov_b32_dpp v13, v1 row_mirror row_mask:0xf bank_mask:0xf
	s_waitcnt lgkmcnt(0)
	v_add_f32_e32 v1, v1, v13
	ds_bpermute_b32 v13, v12, v1
	s_and_saveexec_b64 s[4:5], s[0:1]
	s_cbranch_execz .LBB0_468
	v_add_u32_e32 v14, 2, v0
	v_ashrrev_i32_e32 v15, 31, v14
	s_waitcnt lgkmcnt(0)
	v_add_f32_e32 v1, v1, v13
	v_lshl_add_u64 v[14:15], v[14:15], 2, s[30:31]
	global_store_dword v[14:15], v1, off sc1
.LBB0_468:
	s_or_b64 exec, exec, s[4:5]
	v_pk_mul_f32 v[14:15], v[70:71], v[70:71]
	s_nop 0
	v_add_f32_e32 v1, v15, v14
	v_fmac_f32_e32 v1, v45, v45
	v_fmac_f32_e32 v1, v29, v29
	s_waitcnt lgkmcnt(0)
	s_nop 1
	v_mov_b32_dpp v13, v1 quad_perm:[1,0,3,2] row_mask:0xf bank_mask:0xf
	s_waitcnt lgkmcnt(0)
	v_add_f32_e32 v1, v1, v13
	s_nop 1
	v_mov_b32_dpp v13, v1 quad_perm:[2,3,0,1] row_mask:0xf bank_mask:0xf
	s_waitcnt lgkmcnt(0)
	v_add_f32_e32 v1, v1, v13
	s_nop 1
	v_mov_b32_dpp v13, v1 row_half_mirror row_mask:0xf bank_mask:0xf
	s_waitcnt lgkmcnt(0)
	v_add_f32_e32 v1, v1, v13
	s_nop 1
	v_mov_b32_dpp v13, v1 row_mirror row_mask:0xf bank_mask:0xf
	s_waitcnt lgkmcnt(0)
	v_add_f32_e32 v1, v1, v13
	ds_bpermute_b32 v13, v12, v1
	s_and_saveexec_b64 s[4:5], s[0:1]
	s_cbranch_execz .LBB0_470
	v_add_u32_e32 v14, 3, v0
	v_ashrrev_i32_e32 v15, 31, v14
	s_waitcnt lgkmcnt(0)
	v_add_f32_e32 v1, v1, v13
	v_lshl_add_u64 v[14:15], v[14:15], 2, s[30:31]
	global_store_dword v[14:15], v1, off sc1
.LBB0_470:
	s_or_b64 exec, exec, s[4:5]
	v_pk_mul_f32 v[14:15], v[68:69], v[68:69]
	s_nop 0
	v_add_f32_e32 v1, v15, v14
	v_fmac_f32_e32 v1, v44, v44
	v_fmac_f32_e32 v1, v28, v28
	s_waitcnt lgkmcnt(0)
	s_nop 1
	v_mov_b32_dpp v13, v1 quad_perm:[1,0,3,2] row_mask:0xf bank_mask:0xf
	s_waitcnt lgkmcnt(0)
	v_add_f32_e32 v1, v1, v13
	s_nop 1
	v_mov_b32_dpp v13, v1 quad_perm:[2,3,0,1] row_mask:0xf bank_mask:0xf
	s_waitcnt lgkmcnt(0)
	v_add_f32_e32 v1, v1, v13
	s_nop 1
	v_mov_b32_dpp v13, v1 row_half_mirror row_mask:0xf bank_mask:0xf
	s_waitcnt lgkmcnt(0)
	v_add_f32_e32 v1, v1, v13
	s_nop 1
	v_mov_b32_dpp v13, v1 row_mirror row_mask:0xf bank_mask:0xf
	s_waitcnt lgkmcnt(0)
	v_add_f32_e32 v1, v1, v13
	ds_bpermute_b32 v13, v12, v1
	s_and_saveexec_b64 s[4:5], s[0:1]
	s_cbranch_execz .LBB0_472
	v_add_u32_e32 v14, 8, v0
	v_ashrrev_i32_e32 v15, 31, v14
	s_waitcnt lgkmcnt(0)
	v_add_f32_e32 v1, v1, v13
	v_lshl_add_u64 v[14:15], v[14:15], 2, s[30:31]
	global_store_dword v[14:15], v1, off sc1
.LBB0_472:
	s_or_b64 exec, exec, s[4:5]
	v_pk_mul_f32 v[14:15], v[66:67], v[66:67]
	s_nop 0
	v_add_f32_e32 v1, v15, v14
	v_fmac_f32_e32 v1, v43, v43
	v_fmac_f32_e32 v1, v27, v27
	s_waitcnt lgkmcnt(0)
	s_nop 1
	v_mov_b32_dpp v13, v1 quad_perm:[1,0,3,2] row_mask:0xf bank_mask:0xf
	s_waitcnt lgkmcnt(0)
	v_add_f32_e32 v1, v1, v13
	s_nop 1
	v_mov_b32_dpp v13, v1 quad_perm:[2,3,0,1] row_mask:0xf bank_mask:0xf
	s_waitcnt lgkmcnt(0)
	v_add_f32_e32 v1, v1, v13
	s_nop 1
	v_mov_b32_dpp v13, v1 row_half_mirror row_mask:0xf bank_mask:0xf
	s_waitcnt lgkmcnt(0)
	v_add_f32_e32 v1, v1, v13
	s_nop 1
	v_mov_b32_dpp v13, v1 row_mirror row_mask:0xf bank_mask:0xf
	s_waitcnt lgkmcnt(0)
	v_add_f32_e32 v1, v1, v13
	ds_bpermute_b32 v13, v12, v1
	s_and_saveexec_b64 s[4:5], s[0:1]
	s_cbranch_execz .LBB0_474
	v_add_u32_e32 v14, 9, v0
	v_ashrrev_i32_e32 v15, 31, v14
	s_waitcnt lgkmcnt(0)
	v_add_f32_e32 v1, v1, v13
	v_lshl_add_u64 v[14:15], v[14:15], 2, s[30:31]
	global_store_dword v[14:15], v1, off sc1
.LBB0_474:
	s_or_b64 exec, exec, s[4:5]
	v_pk_mul_f32 v[14:15], v[64:65], v[64:65]
	s_nop 0
	v_add_f32_e32 v1, v15, v14
	v_fmac_f32_e32 v1, v42, v42
	v_fmac_f32_e32 v1, v26, v26
	s_waitcnt lgkmcnt(0)
	s_nop 1
	v_mov_b32_dpp v13, v1 quad_perm:[1,0,3,2] row_mask:0xf bank_mask:0xf
	s_waitcnt lgkmcnt(0)
	v_add_f32_e32 v1, v1, v13
	s_nop 1
	v_mov_b32_dpp v13, v1 quad_perm:[2,3,0,1] row_mask:0xf bank_mask:0xf
	s_waitcnt lgkmcnt(0)
	v_add_f32_e32 v1, v1, v13
	s_nop 1
	v_mov_b32_dpp v13, v1 row_half_mirror row_mask:0xf bank_mask:0xf
	s_waitcnt lgkmcnt(0)
	v_add_f32_e32 v1, v1, v13
	s_nop 1
	v_mov_b32_dpp v13, v1 row_mirror row_mask:0xf bank_mask:0xf
	s_waitcnt lgkmcnt(0)
	v_add_f32_e32 v1, v1, v13
	ds_bpermute_b32 v13, v12, v1
	s_and_saveexec_b64 s[4:5], s[0:1]
	s_cbranch_execz .LBB0_476
	v_add_u32_e32 v14, 10, v0
	v_ashrrev_i32_e32 v15, 31, v14
	s_waitcnt lgkmcnt(0)
	v_add_f32_e32 v1, v1, v13
	v_lshl_add_u64 v[14:15], v[14:15], 2, s[30:31]
	global_store_dword v[14:15], v1, off sc1
.LBB0_476:
	s_or_b64 exec, exec, s[4:5]
	v_pk_mul_f32 v[14:15], v[54:55], v[54:55]
	s_nop 0
	v_add_f32_e32 v1, v15, v14
	v_fmac_f32_e32 v1, v23, v23
	v_fmac_f32_e32 v1, v25, v25
	s_waitcnt lgkmcnt(0)
	s_nop 1
	v_mov_b32_dpp v13, v1 quad_perm:[1,0,3,2] row_mask:0xf bank_mask:0xf
	s_waitcnt lgkmcnt(0)
	v_add_f32_e32 v1, v1, v13
	s_nop 1
	v_mov_b32_dpp v13, v1 quad_perm:[2,3,0,1] row_mask:0xf bank_mask:0xf
	s_waitcnt lgkmcnt(0)
	v_add_f32_e32 v1, v1, v13
	s_nop 1
	v_mov_b32_dpp v13, v1 row_half_mirror row_mask:0xf bank_mask:0xf
	s_waitcnt lgkmcnt(0)
	v_add_f32_e32 v1, v1, v13
	s_nop 1
	v_mov_b32_dpp v13, v1 row_mirror row_mask:0xf bank_mask:0xf
	s_waitcnt lgkmcnt(0)
	v_add_f32_e32 v1, v1, v13
	ds_bpermute_b32 v13, v12, v1
	s_and_saveexec_b64 s[4:5], s[0:1]
	s_cbranch_execz .LBB0_478
	v_add_u32_e32 v14, 11, v0
	v_ashrrev_i32_e32 v15, 31, v14
	s_waitcnt lgkmcnt(0)
	v_add_f32_e32 v1, v1, v13
	v_lshl_add_u64 v[14:15], v[14:15], 2, s[30:31]
	global_store_dword v[14:15], v1, off sc1
.LBB0_478:
	s_or_b64 exec, exec, s[4:5]
	v_pk_mul_f32 v[14:15], v[52:53], v[52:53]
	s_nop 0
	v_add_f32_e32 v1, v15, v14
	v_fmac_f32_e32 v1, v22, v22
	v_fmac_f32_e32 v1, v24, v24
	s_waitcnt lgkmcnt(0)
	s_nop 1
	v_mov_b32_dpp v13, v1 quad_perm:[1,0,3,2] row_mask:0xf bank_mask:0xf
	s_waitcnt lgkmcnt(0)
	v_add_f32_e32 v1, v1, v13
	s_nop 1
	v_mov_b32_dpp v13, v1 quad_perm:[2,3,0,1] row_mask:0xf bank_mask:0xf
	s_waitcnt lgkmcnt(0)
	v_add_f32_e32 v1, v1, v13
	s_nop 1
	v_mov_b32_dpp v13, v1 row_half_mirror row_mask:0xf bank_mask:0xf
	s_waitcnt lgkmcnt(0)
	v_add_f32_e32 v1, v1, v13
	s_nop 1
	v_mov_b32_dpp v13, v1 row_mirror row_mask:0xf bank_mask:0xf
	s_waitcnt lgkmcnt(0)
	v_add_f32_e32 v1, v1, v13
	ds_bpermute_b32 v13, v12, v1
	s_and_saveexec_b64 s[4:5], s[0:1]
	s_cbranch_execz .LBB0_480
	v_add_u32_e32 v14, 16, v0
	v_ashrrev_i32_e32 v15, 31, v14
	s_waitcnt lgkmcnt(0)
	v_add_f32_e32 v1, v1, v13
	v_lshl_add_u64 v[14:15], v[14:15], 2, s[30:31]
	global_store_dword v[14:15], v1, off sc1
.LBB0_480:
	s_or_b64 exec, exec, s[4:5]
	v_pk_mul_f32 v[14:15], v[50:51], v[50:51]
	s_nop 0
	v_add_f32_e32 v1, v15, v14
	v_fmac_f32_e32 v1, v21, v21
	v_fmac_f32_e32 v1, v9, v9
	s_waitcnt lgkmcnt(0)
	s_nop 1
	v_mov_b32_dpp v13, v1 quad_perm:[1,0,3,2] row_mask:0xf bank_mask:0xf
	s_waitcnt lgkmcnt(0)
	v_add_f32_e32 v1, v1, v13
	s_nop 1
	v_mov_b32_dpp v13, v1 quad_perm:[2,3,0,1] row_mask:0xf bank_mask:0xf
	s_waitcnt lgkmcnt(0)
	v_add_f32_e32 v1, v1, v13
	s_nop 1
	v_mov_b32_dpp v13, v1 row_half_mirror row_mask:0xf bank_mask:0xf
	s_waitcnt lgkmcnt(0)
	v_add_f32_e32 v1, v1, v13
	s_nop 1
	v_mov_b32_dpp v13, v1 row_mirror row_mask:0xf bank_mask:0xf
	s_waitcnt lgkmcnt(0)
	v_add_f32_e32 v1, v1, v13
	ds_bpermute_b32 v13, v12, v1
	s_and_saveexec_b64 s[4:5], s[0:1]
	s_cbranch_execz .LBB0_482
	v_add_u32_e32 v14, 17, v0
	v_ashrrev_i32_e32 v15, 31, v14
	s_waitcnt lgkmcnt(0)
	v_add_f32_e32 v1, v1, v13
	v_lshl_add_u64 v[14:15], v[14:15], 2, s[30:31]
	global_store_dword v[14:15], v1, off sc1
.LBB0_482:
	s_or_b64 exec, exec, s[4:5]
	v_pk_mul_f32 v[14:15], v[48:49], v[48:49]
	s_nop 0
	v_add_f32_e32 v1, v15, v14
	v_fmac_f32_e32 v1, v20, v20
	v_fmac_f32_e32 v1, v8, v8
	s_waitcnt lgkmcnt(0)
	s_nop 1
	v_mov_b32_dpp v13, v1 quad_perm:[1,0,3,2] row_mask:0xf bank_mask:0xf
	s_waitcnt lgkmcnt(0)
	v_add_f32_e32 v1, v1, v13
	s_nop 1
	v_mov_b32_dpp v13, v1 quad_perm:[2,3,0,1] row_mask:0xf bank_mask:0xf
	s_waitcnt lgkmcnt(0)
	v_add_f32_e32 v1, v1, v13
	s_nop 1
	v_mov_b32_dpp v13, v1 row_half_mirror row_mask:0xf bank_mask:0xf
	s_waitcnt lgkmcnt(0)
	v_add_f32_e32 v1, v1, v13
	s_nop 1
	v_mov_b32_dpp v13, v1 row_mirror row_mask:0xf bank_mask:0xf
	s_waitcnt lgkmcnt(0)
	v_add_f32_e32 v1, v1, v13
	ds_bpermute_b32 v13, v12, v1
	s_and_saveexec_b64 s[4:5], s[0:1]
	s_cbranch_execz .LBB0_484
	v_add_u32_e32 v14, 18, v0
	v_ashrrev_i32_e32 v15, 31, v14
	s_waitcnt lgkmcnt(0)
	v_add_f32_e32 v1, v1, v13
	v_lshl_add_u64 v[14:15], v[14:15], 2, s[30:31]
	global_store_dword v[14:15], v1, off sc1
.LBB0_484:
	s_or_b64 exec, exec, s[4:5]
	v_pk_mul_f32 v[14:15], v[40:41], v[40:41]
	s_nop 0
	v_add_f32_e32 v1, v15, v14
	v_fmac_f32_e32 v1, v19, v19
	v_fmac_f32_e32 v1, v7, v7
	s_waitcnt lgkmcnt(0)
	s_nop 1
	v_mov_b32_dpp v13, v1 quad_perm:[1,0,3,2] row_mask:0xf bank_mask:0xf
	s_waitcnt lgkmcnt(0)
	v_add_f32_e32 v1, v1, v13
	s_nop 1
	v_mov_b32_dpp v13, v1 quad_perm:[2,3,0,1] row_mask:0xf bank_mask:0xf
	s_waitcnt lgkmcnt(0)
	v_add_f32_e32 v1, v1, v13
	s_nop 1
	v_mov_b32_dpp v13, v1 row_half_mirror row_mask:0xf bank_mask:0xf
	s_waitcnt lgkmcnt(0)
	v_add_f32_e32 v1, v1, v13
	s_nop 1
	v_mov_b32_dpp v13, v1 row_mirror row_mask:0xf bank_mask:0xf
	s_waitcnt lgkmcnt(0)
	v_add_f32_e32 v1, v1, v13
	ds_bpermute_b32 v13, v12, v1
	s_and_saveexec_b64 s[4:5], s[0:1]
	s_cbranch_execz .LBB0_486
	v_add_u32_e32 v14, 19, v0
	v_ashrrev_i32_e32 v15, 31, v14
	s_waitcnt lgkmcnt(0)
	v_add_f32_e32 v1, v1, v13
	v_lshl_add_u64 v[14:15], v[14:15], 2, s[30:31]
	global_store_dword v[14:15], v1, off sc1
.LBB0_486:
	s_or_b64 exec, exec, s[4:5]
	v_pk_mul_f32 v[14:15], v[38:39], v[38:39]
	s_nop 0
	v_add_f32_e32 v1, v15, v14
	v_fmac_f32_e32 v1, v18, v18
	v_fmac_f32_e32 v1, v6, v6
	s_waitcnt lgkmcnt(0)
	s_nop 1
	v_mov_b32_dpp v13, v1 quad_perm:[1,0,3,2] row_mask:0xf bank_mask:0xf
	s_waitcnt lgkmcnt(0)
	v_add_f32_e32 v1, v1, v13
	s_nop 1
	v_mov_b32_dpp v13, v1 quad_perm:[2,3,0,1] row_mask:0xf bank_mask:0xf
	s_waitcnt lgkmcnt(0)
	v_add_f32_e32 v1, v1, v13
	s_nop 1
	v_mov_b32_dpp v13, v1 row_half_mirror row_mask:0xf bank_mask:0xf
	s_waitcnt lgkmcnt(0)
	v_add_f32_e32 v1, v1, v13
	s_nop 1
	v_mov_b32_dpp v13, v1 row_mirror row_mask:0xf bank_mask:0xf
	s_waitcnt lgkmcnt(0)
	v_add_f32_e32 v1, v1, v13
	ds_bpermute_b32 v13, v12, v1
	s_and_saveexec_b64 s[4:5], s[0:1]
	s_cbranch_execz .LBB0_488
	v_add_u32_e32 v14, 24, v0
	v_ashrrev_i32_e32 v15, 31, v14
	s_waitcnt lgkmcnt(0)
	v_add_f32_e32 v1, v1, v13
	v_lshl_add_u64 v[14:15], v[14:15], 2, s[30:31]
	global_store_dword v[14:15], v1, off sc1
.LBB0_488:
	s_or_b64 exec, exec, s[4:5]
	v_pk_mul_f32 v[14:15], v[36:37], v[36:37]
	s_nop 0
	v_add_f32_e32 v1, v15, v14
	v_fmac_f32_e32 v1, v17, v17
	v_fmac_f32_e32 v1, v5, v5
	s_waitcnt lgkmcnt(0)
	s_nop 1
	v_mov_b32_dpp v13, v1 quad_perm:[1,0,3,2] row_mask:0xf bank_mask:0xf
	s_waitcnt lgkmcnt(0)
	v_add_f32_e32 v1, v1, v13
	s_nop 1
	v_mov_b32_dpp v13, v1 quad_perm:[2,3,0,1] row_mask:0xf bank_mask:0xf
	s_waitcnt lgkmcnt(0)
	v_add_f32_e32 v1, v1, v13
	s_nop 1
	v_mov_b32_dpp v13, v1 row_half_mirror row_mask:0xf bank_mask:0xf
	s_waitcnt lgkmcnt(0)
	v_add_f32_e32 v1, v1, v13
	s_nop 1
	v_mov_b32_dpp v13, v1 row_mirror row_mask:0xf bank_mask:0xf
	s_waitcnt lgkmcnt(0)
	v_add_f32_e32 v1, v1, v13
	ds_bpermute_b32 v13, v12, v1
	s_and_saveexec_b64 s[4:5], s[0:1]
	s_cbranch_execz .LBB0_490
	v_add_u32_e32 v14, 25, v0
	v_ashrrev_i32_e32 v15, 31, v14
	s_waitcnt lgkmcnt(0)
	v_add_f32_e32 v1, v1, v13
	v_lshl_add_u64 v[14:15], v[14:15], 2, s[30:31]
	global_store_dword v[14:15], v1, off sc1
.LBB0_490:
	s_or_b64 exec, exec, s[4:5]
	v_pk_mul_f32 v[14:15], v[34:35], v[34:35]
	s_nop 0
	v_add_f32_e32 v1, v15, v14
	v_fmac_f32_e32 v1, v16, v16
	v_fmac_f32_e32 v1, v4, v4
	s_waitcnt lgkmcnt(0)
	s_nop 1
	v_mov_b32_dpp v13, v1 quad_perm:[1,0,3,2] row_mask:0xf bank_mask:0xf
	s_waitcnt lgkmcnt(0)
	v_add_f32_e32 v1, v1, v13
	s_nop 1
	v_mov_b32_dpp v13, v1 quad_perm:[2,3,0,1] row_mask:0xf bank_mask:0xf
	s_waitcnt lgkmcnt(0)
	v_add_f32_e32 v1, v1, v13
	s_nop 1
	v_mov_b32_dpp v13, v1 row_half_mirror row_mask:0xf bank_mask:0xf
	s_waitcnt lgkmcnt(0)
	v_add_f32_e32 v1, v1, v13
	s_nop 1
	v_mov_b32_dpp v13, v1 row_mirror row_mask:0xf bank_mask:0xf
	s_waitcnt lgkmcnt(0)
	v_add_f32_e32 v1, v1, v13
	ds_bpermute_b32 v13, v12, v1
	s_and_saveexec_b64 s[4:5], s[0:1]
	s_cbranch_execz .LBB0_492
	v_add_u32_e32 v14, 26, v0
	v_ashrrev_i32_e32 v15, 31, v14
	s_waitcnt lgkmcnt(0)
	v_add_f32_e32 v1, v1, v13
	v_lshl_add_u64 v[14:15], v[14:15], 2, s[30:31]
	global_store_dword v[14:15], v1, off sc1
.LBB0_492:
	s_or_b64 exec, exec, s[4:5]
	v_pk_mul_f32 v[14:15], v[32:33], v[32:33]
	s_nop 0
	v_add_f32_e32 v1, v15, v14
	v_fmac_f32_e32 v1, v82, v82
	v_fmac_f32_e32 v1, v83, v83
	s_nop 1
	v_mov_b32_dpp v2, v1 quad_perm:[1,0,3,2] row_mask:0xf bank_mask:0xf
	s_waitcnt lgkmcnt(0)
	v_add_f32_e32 v1, v1, v2
	s_nop 1
	v_mov_b32_dpp v2, v1 quad_perm:[2,3,0,1] row_mask:0xf bank_mask:0xf
	s_waitcnt lgkmcnt(0)
	v_add_f32_e32 v1, v1, v2
	s_nop 1
	v_mov_b32_dpp v2, v1 row_half_mirror row_mask:0xf bank_mask:0xf
	s_waitcnt lgkmcnt(0)
	v_add_f32_e32 v1, v1, v2
	s_nop 1
	v_mov_b32_dpp v2, v1 row_mirror row_mask:0xf bank_mask:0xf
	s_waitcnt lgkmcnt(0)
	v_add_f32_e32 v1, v1, v2
	ds_bpermute_b32 v2, v12, v1
	s_and_saveexec_b64 s[4:5], s[0:1]
	s_cbranch_execz .LBB0_494
	v_add_u32_e32 v0, 27, v0
	s_waitcnt lgkmcnt(0)
	v_add_f32_e32 v2, v1, v2
	v_ashrrev_i32_e32 v1, 31, v0
	v_lshl_add_u64 v[0:1], v[0:1], 2, s[30:31]
	global_store_dword v[0:1], v2, off sc1

.LBB0_497:
	v_mov_b32_e32 v0, s97
	ds_read_b64 v[0:1], v0
	s_waitcnt lgkmcnt(1)
	v_pk_mul_f32 v[2:3], v[78:79], v[78:79]
	v_or_b32_e32 v88, 32, v76
	v_or_b32_e32 v85, 64, v76
	v_or_b32_e32 v10, 0x60, v76
	s_waitcnt lgkmcnt(0)
	v_readfirstlane_b32 s4, v0
	v_readfirstlane_b32 s5, v1
	v_add_f32_e32 v2, v3, v2
	v_mov_b32_e32 v0, s4
	v_mov_b32_e32 v1, s5
	v_lshl_add_u64 v[0:1], v[76:77], 2, v[0:1]
	global_load_dword v77, v[0:1], off
	s_movk_i32 s4, 0x180
	v_fmac_f32_e32 v2, v57, v57
	v_fmac_f32_e32 v2, v56, v56
	s_waitcnt vmcnt(0)
	v_mul_f32_e32 v11, v79, v77
	v_cvt_pk_bf16_f32 v14, v11, s0
	v_mul_lo_u32 v11, v164, s4
	v_add_u32_e32 v12, v11, v76
	v_ashrrev_i32_e32 v13, 31, v12
	v_lshl_add_u64 v[12:13], v[12:13], 1, s[34:35]
	global_store_short v[12:13], v14, off sc1
	v_mul_f32_e32 v12, v75, v77
	v_cvt_pk_bf16_f32 v13, v12, s0
	v_add_u32_e32 v12, 0x180, v11
	v_add_u32_e32 v14, v12, v76
	v_ashrrev_i32_e32 v15, 31, v14
	v_lshl_add_u64 v[14:15], v[14:15], 1, s[34:35]
	global_store_short v[14:15], v13, off sc1
	v_mul_f32_e32 v13, v73, v77
	v_cvt_pk_bf16_f32 v58, v13, s0
	v_add_u32_e32 v13, 0x300, v11
	v_add_u32_e32 v14, v13, v76
	v_ashrrev_i32_e32 v15, 31, v14
	v_lshl_add_u64 v[14:15], v[14:15], 1, s[34:35]
	global_store_short v[14:15], v58, off sc1
	v_mul_f32_e32 v14, v71, v77
	v_cvt_pk_bf16_f32 v15, v14, s0
	v_add_u32_e32 v14, 0x480, v11
	v_add_u32_e32 v58, v14, v76
	v_ashrrev_i32_e32 v59, 31, v58
	v_lshl_add_u64 v[58:59], v[58:59], 1, s[34:35]
	global_store_short v[58:59], v15, off sc1
	v_mul_f32_e32 v15, v69, v77
	v_cvt_pk_bf16_f32 v60, v15, s0
	v_add_u32_e32 v15, 0xc00, v11
	v_add_u32_e32 v58, v15, v76
	v_ashrrev_i32_e32 v59, 31, v58
	v_lshl_add_u64 v[58:59], v[58:59], 1, s[34:35]
	global_store_short v[58:59], v60, off sc1
	v_mul_f32_e32 v58, v67, v77
	v_cvt_pk_bf16_f32 v59, v58, s0
	v_add_u32_e32 v58, 0xd80, v11
	v_add_u32_e32 v60, v58, v76
	v_ashrrev_i32_e32 v61, 31, v60
	v_lshl_add_u64 v[60:61], v[60:61], 1, s[34:35]
	global_store_short v[60:61], v59, off sc1
	v_mul_f32_e32 v59, v65, v77
	v_cvt_pk_bf16_f32 v62, v59, s0
	v_add_u32_e32 v59, 0xf00, v11
	v_add_u32_e32 v60, v59, v76
	v_ashrrev_i32_e32 v61, 31, v60
	v_lshl_add_u64 v[60:61], v[60:61], 1, s[34:35]
	global_store_short v[60:61], v62, off sc1
	v_mul_f32_e32 v60, v55, v77
	v_cvt_pk_bf16_f32 v61, v60, s0
	v_add_u32_e32 v60, 0x1080, v11
	v_add_u32_e32 v62, v60, v76
	v_ashrrev_i32_e32 v63, 31, v62
	v_lshl_add_u64 v[62:63], v[62:63], 1, s[34:35]
	global_store_short v[62:63], v61, off sc1
	v_mul_f32_e32 v61, v53, v77
	v_cvt_pk_bf16_f32 v79, v61, s0
	v_add_u32_e32 v61, 0x1800, v11
	v_add_u32_e32 v62, v61, v76
	v_ashrrev_i32_e32 v63, 31, v62
	v_lshl_add_u64 v[62:63], v[62:63], 1, s[34:35]
	global_store_short v[62:63], v79, off sc1
	v_mul_f32_e32 v62, v51, v77
	v_cvt_pk_bf16_f32 v63, v62, s0
	v_add_u32_e32 v62, 0x1980, v11
	v_add_u32_e32 v80, v62, v76
	v_ashrrev_i32_e32 v81, 31, v80
	v_lshl_add_u64 v[80:81], v[80:81], 1, s[34:35]
	global_store_short v[80:81], v63, off sc1
	v_mul_f32_e32 v63, v49, v77
	v_cvt_pk_bf16_f32 v79, v63, s0
	v_add_u32_e32 v63, 0x1b00, v11
	v_add_u32_e32 v80, v63, v76
	v_ashrrev_i32_e32 v81, 31, v80
	v_lshl_add_u64 v[80:81], v[80:81], 1, s[34:35]
	v_add_u32_e32 v84, 0x1c80, v11
	global_store_short v[80:81], v79, off sc1
	v_add_u32_e32 v80, v84, v76
	v_mul_f32_e32 v79, v41, v77
	v_ashrrev_i32_e32 v81, 31, v80
	v_cvt_pk_bf16_f32 v79, v79, s0
	v_lshl_add_u64 v[80:81], v[80:81], 1, s[34:35]
	global_store_short v[80:81], v79, off sc1
	v_add_u32_e32 v81, 0x2400, v11
	v_add_u32_e32 v86, v81, v76
	v_mul_f32_e32 v79, v39, v77
	v_ashrrev_i32_e32 v87, 31, v86
	v_cvt_pk_bf16_f32 v79, v79, s0
	v_lshl_add_u64 v[86:87], v[86:87], 1, s[34:35]
	v_add_u32_e32 v80, 0x2580, v11
	global_store_short v[86:87], v79, off sc1
	v_add_u32_e32 v86, v80, v76
	v_mul_f32_e32 v79, v37, v77
	v_ashrrev_i32_e32 v87, 31, v86
	v_cvt_pk_bf16_f32 v79, v79, s0
	v_lshl_add_u64 v[86:87], v[86:87], 1, s[34:35]
	global_store_short v[86:87], v79, off sc1
	v_mul_f32_e32 v79, v35, v77
	v_cvt_pk_bf16_f32 v89, v79, s0
	v_add_u32_e32 v79, 0x2700, v11
	v_add_u32_e32 v86, v79, v76
	v_ashrrev_i32_e32 v87, 31, v86
	v_lshl_add_u64 v[86:87], v[86:87], 1, s[34:35]
	v_mul_f32_e32 v77, v33, v77
	global_store_short v[86:87], v89, off sc1
	v_cvt_pk_bf16_f32 v89, v77, s0
	v_add_u32_e32 v77, 0x2880, v11
	v_add_u32_e32 v86, v77, v76
	global_load_dword v76, v[0:1], off offset:128
	v_ashrrev_i32_e32 v87, 31, v86
	v_lshl_add_u64 v[86:87], v[86:87], 1, s[34:35]
	global_store_short v[86:87], v89, off sc1
	v_add_u32_e32 v86, v11, v88
	v_ashrrev_i32_e32 v87, 31, v86
	v_lshl_add_u64 v[86:87], v[86:87], 1, s[34:35]
	s_waitcnt vmcnt(1)
	v_mul_f32_e32 v3, v78, v76
	v_cvt_pk_bf16_f32 v3, v3, s0
	global_store_short v[86:87], v3, off sc1
	v_add_u32_e32 v86, v12, v88
	v_mul_f32_e32 v3, v74, v76
	v_ashrrev_i32_e32 v87, 31, v86
	v_cvt_pk_bf16_f32 v3, v3, s0
	v_lshl_add_u64 v[86:87], v[86:87], 1, s[34:35]
	global_store_short v[86:87], v3, off sc1
	v_add_u32_e32 v86, v13, v88
	v_mul_f32_e32 v3, v72, v76
	v_ashrrev_i32_e32 v87, 31, v86
	v_cvt_pk_bf16_f32 v3, v3, s0
	v_lshl_add_u64 v[86:87], v[86:87], 1, s[34:35]
	global_store_short v[86:87], v3, off sc1
	v_add_u32_e32 v86, v14, v88
	v_mul_f32_e32 v3, v70, v76
	v_ashrrev_i32_e32 v87, 31, v86
	v_cvt_pk_bf16_f32 v3, v3, s0
	v_lshl_add_u64 v[86:87], v[86:87], 1, s[34:35]
	global_store_short v[86:87], v3, off sc1
	v_add_u32_e32 v86, v15, v88
	v_mul_f32_e32 v3, v68, v76
	v_ashrrev_i32_e32 v87, 31, v86
	v_cvt_pk_bf16_f32 v3, v3, s0
	v_lshl_add_u64 v[86:87], v[86:87], 1, s[34:35]
	global_store_short v[86:87], v3, off sc1
	v_add_u32_e32 v86, v58, v88
	v_mul_f32_e32 v3, v66, v76
	v_ashrrev_i32_e32 v87, 31, v86
	v_cvt_pk_bf16_f32 v3, v3, s0
	v_lshl_add_u64 v[86:87], v[86:87], 1, s[34:35]
	global_store_short v[86:87], v3, off sc1
	v_add_u32_e32 v86, v59, v88
	v_mul_f32_e32 v3, v64, v76
	v_ashrrev_i32_e32 v87, 31, v86
	v_cvt_pk_bf16_f32 v3, v3, s0
	v_lshl_add_u64 v[86:87], v[86:87], 1, s[34:35]
	global_store_short v[86:87], v3, off sc1
	v_add_u32_e32 v86, v60, v88
	v_mul_f32_e32 v3, v54, v76
	v_ashrrev_i32_e32 v87, 31, v86
	v_cvt_pk_bf16_f32 v3, v3, s0
	v_lshl_add_u64 v[86:87], v[86:87], 1, s[34:35]
	global_store_short v[86:87], v3, off sc1
	v_add_u32_e32 v86, v61, v88
	v_mul_f32_e32 v3, v52, v76
	v_ashrrev_i32_e32 v87, 31, v86
	v_cvt_pk_bf16_f32 v3, v3, s0
	v_lshl_add_u64 v[86:87], v[86:87], 1, s[34:35]
	global_store_short v[86:87], v3, off sc1
	v_add_u32_e32 v86, v62, v88
	v_mul_f32_e32 v3, v50, v76
	v_ashrrev_i32_e32 v87, 31, v86
	v_cvt_pk_bf16_f32 v3, v3, s0
	v_lshl_add_u64 v[86:87], v[86:87], 1, s[34:35]
	global_store_short v[86:87], v3, off sc1
	v_add_u32_e32 v86, v63, v88
	v_mul_f32_e32 v3, v48, v76
	v_ashrrev_i32_e32 v87, 31, v86
	v_cvt_pk_bf16_f32 v3, v3, s0
	v_lshl_add_u64 v[86:87], v[86:87], 1, s[34:35]
	global_store_short v[86:87], v3, off sc1
	v_add_u32_e32 v86, v84, v88
	v_mul_f32_e32 v3, v40, v76
	v_ashrrev_i32_e32 v87, 31, v86
	v_cvt_pk_bf16_f32 v3, v3, s0
	v_lshl_add_u64 v[86:87], v[86:87], 1, s[34:35]
	global_store_short v[86:87], v3, off sc1
	v_add_u32_e32 v86, v81, v88
	v_mul_f32_e32 v3, v38, v76
	v_ashrrev_i32_e32 v87, 31, v86
	v_cvt_pk_bf16_f32 v3, v3, s0
	v_lshl_add_u64 v[86:87], v[86:87], 1, s[34:35]
	global_store_short v[86:87], v3, off sc1
	v_add_u32_e32 v86, v80, v88
	v_mul_f32_e32 v3, v36, v76
	v_ashrrev_i32_e32 v87, 31, v86
	v_cvt_pk_bf16_f32 v3, v3, s0
	v_lshl_add_u64 v[86:87], v[86:87], 1, s[34:35]
	global_store_short v[86:87], v3, off sc1
	v_add_u32_e32 v86, v79, v88
	v_mul_f32_e32 v3, v34, v76
	v_ashrrev_i32_e32 v87, 31, v86
	v_cvt_pk_bf16_f32 v3, v3, s0
	v_lshl_add_u64 v[86:87], v[86:87], 1, s[34:35]
	global_store_short v[86:87], v3, off sc1
	v_add_u32_e32 v86, v77, v88
	v_mul_f32_e32 v3, v32, v76
	v_ashrrev_i32_e32 v87, 31, v86
	v_cvt_pk_bf16_f32 v3, v3, s0
	v_lshl_add_u64 v[86:87], v[86:87], 1, s[34:35]
	global_store_short v[86:87], v3, off sc1
	global_load_dword v3, v[0:1], off offset:256
	v_add_u32_e32 v86, v11, v85
	v_ashrrev_i32_e32 v87, 31, v86
	v_lshl_add_u64 v[86:87], v[86:87], 1, s[34:35]
	s_waitcnt vmcnt(0)
	v_mul_f32_e32 v57, v57, v3
	v_cvt_pk_bf16_f32 v57, v57, s0
	global_store_short v[86:87], v57, off sc1
	v_add_u32_e32 v86, v12, v85
	v_mul_f32_e32 v57, v47, v3
	v_ashrrev_i32_e32 v87, 31, v86
	v_cvt_pk_bf16_f32 v57, v57, s0
	v_lshl_add_u64 v[86:87], v[86:87], 1, s[34:35]
	global_store_short v[86:87], v57, off sc1
	v_add_u32_e32 v86, v13, v85
	v_mul_f32_e32 v57, v46, v3
	v_ashrrev_i32_e32 v87, 31, v86
	v_cvt_pk_bf16_f32 v57, v57, s0
	v_lshl_add_u64 v[86:87], v[86:87], 1, s[34:35]
	global_store_short v[86:87], v57, off sc1
	v_add_u32_e32 v86, v14, v85
	v_mul_f32_e32 v57, v45, v3
	v_ashrrev_i32_e32 v87, 31, v86
	v_cvt_pk_bf16_f32 v57, v57, s0
	v_lshl_add_u64 v[86:87], v[86:87], 1, s[34:35]
	global_store_short v[86:87], v57, off sc1
	v_add_u32_e32 v86, v15, v85
	v_mul_f32_e32 v57, v44, v3
	v_ashrrev_i32_e32 v87, 31, v86
	v_cvt_pk_bf16_f32 v57, v57, s0
	v_lshl_add_u64 v[86:87], v[86:87], 1, s[34:35]
	global_store_short v[86:87], v57, off sc1
	v_add_u32_e32 v86, v58, v85
	v_mul_f32_e32 v57, v43, v3
	v_ashrrev_i32_e32 v87, 31, v86
	v_cvt_pk_bf16_f32 v57, v57, s0
	v_lshl_add_u64 v[86:87], v[86:87], 1, s[34:35]
	global_store_short v[86:87], v57, off sc1
	v_add_u32_e32 v86, v59, v85
	v_mul_f32_e32 v57, v42, v3
	v_ashrrev_i32_e32 v87, 31, v86
	v_cvt_pk_bf16_f32 v57, v57, s0
	v_lshl_add_u64 v[86:87], v[86:87], 1, s[34:35]
	global_store_short v[86:87], v57, off sc1
	v_add_u32_e32 v86, v60, v85
	v_mul_f32_e32 v57, v23, v3
	v_ashrrev_i32_e32 v87, 31, v86
	v_cvt_pk_bf16_f32 v57, v57, s0
	v_lshl_add_u64 v[86:87], v[86:87], 1, s[34:35]
	global_store_short v[86:87], v57, off sc1
	v_add_u32_e32 v86, v61, v85
	v_mul_f32_e32 v57, v22, v3
	v_ashrrev_i32_e32 v87, 31, v86
	v_cvt_pk_bf16_f32 v57, v57, s0
	v_lshl_add_u64 v[86:87], v[86:87], 1, s[34:35]
	global_store_short v[86:87], v57, off sc1
	v_add_u32_e32 v86, v62, v85
	v_mul_f32_e32 v57, v21, v3
	v_ashrrev_i32_e32 v87, 31, v86
	v_cvt_pk_bf16_f32 v57, v57, s0
	v_lshl_add_u64 v[86:87], v[86:87], 1, s[34:35]
	global_store_short v[86:87], v57, off sc1
	v_add_u32_e32 v86, v63, v85
	v_mul_f32_e32 v57, v20, v3
	v_ashrrev_i32_e32 v87, 31, v86
	v_cvt_pk_bf16_f32 v57, v57, s0
	v_lshl_add_u64 v[86:87], v[86:87], 1, s[34:35]
	global_store_short v[86:87], v57, off sc1
	v_add_u32_e32 v86, v84, v85
	v_mul_f32_e32 v57, v19, v3
	v_ashrrev_i32_e32 v87, 31, v86
	v_cvt_pk_bf16_f32 v57, v57, s0
	v_lshl_add_u64 v[86:87], v[86:87], 1, s[34:35]
	global_store_short v[86:87], v57, off sc1
	v_add_u32_e32 v86, v81, v85
	v_mul_f32_e32 v57, v18, v3
	v_ashrrev_i32_e32 v87, 31, v86
	v_cvt_pk_bf16_f32 v57, v57, s0
	v_lshl_add_u64 v[86:87], v[86:87], 1, s[34:35]
	global_store_short v[86:87], v57, off sc1
	v_add_u32_e32 v86, v80, v85
	v_mul_f32_e32 v57, v17, v3
	v_ashrrev_i32_e32 v87, 31, v86
	v_cvt_pk_bf16_f32 v57, v57, s0
	v_lshl_add_u64 v[86:87], v[86:87], 1, s[34:35]
	global_store_short v[86:87], v57, off sc1
	v_add_u32_e32 v86, v79, v85
	v_mul_f32_e32 v57, v16, v3
	v_ashrrev_i32_e32 v87, 31, v86
	v_cvt_pk_bf16_f32 v57, v57, s0
	v_lshl_add_u64 v[86:87], v[86:87], 1, s[34:35]
	global_store_short v[86:87], v57, off sc1
	v_add_u32_e32 v86, v77, v85
	v_mul_f32_e32 v3, v82, v3
	v_ashrrev_i32_e32 v87, 31, v86
	v_cvt_pk_bf16_f32 v3, v3, s0
	v_lshl_add_u64 v[86:87], v[86:87], 1, s[34:35]
	global_store_short v[86:87], v3, off sc1
	global_load_dword v3, v[0:1], off offset:384
	s_waitcnt vmcnt(0)
	v_mul_f32_e32 v0, v56, v3
	v_cvt_pk_bf16_f32 v56, v0, s0
	v_add_u32_e32 v0, v11, v10
	v_ashrrev_i32_e32 v1, 31, v0
	v_lshl_add_u64 v[0:1], v[0:1], 1, s[34:35]
	global_store_short v[0:1], v56, off sc1
	v_mul_f32_e32 v0, v31, v3
	v_cvt_pk_bf16_f32 v11, v0, s0
	v_add_u32_e32 v0, v12, v10
	v_ashrrev_i32_e32 v1, 31, v0
	v_lshl_add_u64 v[0:1], v[0:1], 1, s[34:35]
	global_store_short v[0:1], v11, off sc1
	v_mul_f32_e32 v0, v30, v3
	v_cvt_pk_bf16_f32 v11, v0, s0
	v_add_u32_e32 v0, v13, v10
	v_ashrrev_i32_e32 v1, 31, v0
	v_lshl_add_u64 v[0:1], v[0:1], 1, s[34:35]
	global_store_short v[0:1], v11, off sc1
	v_mul_f32_e32 v0, v29, v3
	v_cvt_pk_bf16_f32 v11, v0, s0
	v_add_u32_e32 v0, v14, v10
	v_ashrrev_i32_e32 v1, 31, v0
	v_lshl_add_u64 v[0:1], v[0:1], 1, s[34:35]
	global_store_short v[0:1], v11, off sc1
	v_mul_f32_e32 v0, v28, v3
	v_cvt_pk_bf16_f32 v11, v0, s0
	v_add_u32_e32 v0, v15, v10
	v_ashrrev_i32_e32 v1, 31, v0
	v_lshl_add_u64 v[0:1], v[0:1], 1, s[34:35]
	global_store_short v[0:1], v11, off sc1
	v_mul_f32_e32 v0, v27, v3
	v_cvt_pk_bf16_f32 v11, v0, s0
	v_add_u32_e32 v0, v58, v10
	v_ashrrev_i32_e32 v1, 31, v0
	v_lshl_add_u64 v[0:1], v[0:1], 1, s[34:35]
	global_store_short v[0:1], v11, off sc1
	v_mul_f32_e32 v0, v26, v3
	v_cvt_pk_bf16_f32 v11, v0, s0
	v_add_u32_e32 v0, v59, v10
	v_ashrrev_i32_e32 v1, 31, v0
	v_lshl_add_u64 v[0:1], v[0:1], 1, s[34:35]
	global_store_short v[0:1], v11, off sc1
	v_mul_f32_e32 v0, v25, v3
	v_cvt_pk_bf16_f32 v11, v0, s0
	v_add_u32_e32 v0, v60, v10
	v_ashrrev_i32_e32 v1, 31, v0
	v_lshl_add_u64 v[0:1], v[0:1], 1, s[34:35]
	global_store_short v[0:1], v11, off sc1
	v_mul_f32_e32 v0, v24, v3
	v_cvt_pk_bf16_f32 v11, v0, s0
	v_add_u32_e32 v0, v61, v10
	v_ashrrev_i32_e32 v1, 31, v0
	v_lshl_add_u64 v[0:1], v[0:1], 1, s[34:35]
	global_store_short v[0:1], v11, off sc1
	v_mul_f32_e32 v0, v9, v3
	v_cvt_pk_bf16_f32 v11, v0, s0
	v_add_u32_e32 v0, v62, v10
	v_ashrrev_i32_e32 v1, 31, v0
	v_lshl_add_u64 v[0:1], v[0:1], 1, s[34:35]
	global_store_short v[0:1], v11, off sc1
	v_mul_f32_e32 v0, v8, v3
	v_cvt_pk_bf16_f32 v11, v0, s0
	v_add_u32_e32 v0, v63, v10
	v_ashrrev_i32_e32 v1, 31, v0
	v_lshl_add_u64 v[0:1], v[0:1], 1, s[34:35]
	global_store_short v[0:1], v11, off sc1
	v_mul_f32_e32 v0, v7, v3
	v_cvt_pk_bf16_f32 v11, v0, s0
	v_add_u32_e32 v0, v84, v10
	v_ashrrev_i32_e32 v1, 31, v0
	v_lshl_add_u64 v[0:1], v[0:1], 1, s[34:35]
	global_store_short v[0:1], v11, off sc1
	v_mul_f32_e32 v0, v6, v3
	v_cvt_pk_bf16_f32 v11, v0, s0
	v_add_u32_e32 v0, v81, v10
	v_ashrrev_i32_e32 v1, 31, v0
	v_lshl_add_u64 v[0:1], v[0:1], 1, s[34:35]
	global_store_short v[0:1], v11, off sc1
	v_mul_f32_e32 v0, v5, v3
	v_cvt_pk_bf16_f32 v11, v0, s0
	v_add_u32_e32 v0, v80, v10
	v_ashrrev_i32_e32 v1, 31, v0
	v_lshl_add_u64 v[0:1], v[0:1], 1, s[34:35]
	global_store_short v[0:1], v11, off sc1
	v_mul_f32_e32 v0, v4, v3
	v_cvt_pk_bf16_f32 v11, v0, s0
	v_add_u32_e32 v0, v79, v10
	v_ashrrev_i32_e32 v1, 31, v0
	v_lshl_add_u64 v[0:1], v[0:1], 1, s[34:35]
	global_store_short v[0:1], v11, off sc1
	v_mul_f32_e32 v0, v83, v3
	v_cvt_pk_bf16_f32 v3, v0, s0
	v_add_u32_e32 v0, v77, v10
	v_ashrrev_i32_e32 v1, 31, v0
	v_lshl_add_u64 v[0:1], v[0:1], 1, s[34:35]
	global_store_short v[0:1], v3, off sc1
	v_and_b32_e32 v1, 64, v214
	v_xor_b32_e32 v0, 1, v214
	v_add_u32_e32 v1, 64, v1
	v_cmp_lt_i32_e32 vcc, v0, v1
	s_nop 1
	v_cndmask_b32_e32 v0, v214, v0, vcc
	v_lshlrev_b32_e32 v3, 2, v0
	v_xor_b32_e32 v0, 2, v214
	v_cmp_lt_i32_e32 vcc, v0, v1
	s_nop 1
	v_cndmask_b32_e32 v0, v214, v0, vcc
	v_lshlrev_b32_e32 v10, 2, v0
	v_xor_b32_e32 v0, 4, v214
	v_cmp_lt_i32_e32 vcc, v0, v1
	s_nop 1
	v_cndmask_b32_e32 v0, v214, v0, vcc
	v_lshlrev_b32_e32 v11, 2, v0
	v_xor_b32_e32 v0, 8, v214
	v_cmp_lt_i32_e32 vcc, v0, v1
	s_nop 1
	v_cndmask_b32_e32 v0, v214, v0, vcc
	v_lshlrev_b32_e32 v12, 2, v0
	v_xor_b32_e32 v0, 16, v214
	v_cmp_lt_i32_e32 vcc, v0, v1
	s_nop 1
	v_mov_b32_dpp v1, v2 quad_perm:[1,0,3,2] row_mask:0xf bank_mask:0xf
	s_waitcnt lgkmcnt(0)
	v_add_f32_e32 v1, v2, v1
	s_nop 1
	v_mov_b32_dpp v2, v1 quad_perm:[2,3,0,1] row_mask:0xf bank_mask:0xf
	v_cndmask_b32_e32 v0, v214, v0, vcc
	v_lshlrev_b32_e32 v13, 2, v0
	v_lshl_add_u32 v0, s10, 14, v164
	s_waitcnt lgkmcnt(0)
	v_add_f32_e32 v1, v1, v2
	s_nop 1
	v_mov_b32_dpp v2, v1 row_half_mirror row_mask:0xf bank_mask:0xf
	s_waitcnt lgkmcnt(0)
	v_add_f32_e32 v1, v1, v2
	s_nop 1
	v_mov_b32_dpp v2, v1 row_mirror row_mask:0xf bank_mask:0xf
	s_waitcnt lgkmcnt(0)
	v_add_f32_e32 v2, v1, v2
	ds_bpermute_b32 v14, v13, v2
	v_ashrrev_i32_e32 v1, 31, v0
	s_and_saveexec_b64 s[4:5], s[0:1]
	s_cbranch_execz .LBB0_499
	s_waitcnt lgkmcnt(0)
	v_add_f32_e32 v2, v2, v14
	v_lshl_add_u64 v[14:15], v[0:1], 2, s[36:37]
	global_store_dword v[14:15], v2, off sc1
.LBB0_499:
	s_or_b64 exec, exec, s[4:5]
	s_waitcnt lgkmcnt(0)
	v_pk_mul_f32 v[14:15], v[74:75], v[74:75]
	s_nop 0
	v_add_f32_e32 v2, v15, v14
	v_fmac_f32_e32 v2, v47, v47
	v_fmac_f32_e32 v2, v31, v31
	s_nop 1
	v_mov_b32_dpp v14, v2 quad_perm:[1,0,3,2] row_mask:0xf bank_mask:0xf
	s_waitcnt lgkmcnt(0)
	v_add_f32_e32 v2, v2, v14
	s_nop 1
	v_mov_b32_dpp v14, v2 quad_perm:[2,3,0,1] row_mask:0xf bank_mask:0xf
	s_waitcnt lgkmcnt(0)
	v_add_f32_e32 v2, v2, v14
	s_nop 1
	v_mov_b32_dpp v14, v2 row_half_mirror row_mask:0xf bank_mask:0xf
	s_waitcnt lgkmcnt(0)
	v_add_f32_e32 v2, v2, v14
	s_nop 1
	v_mov_b32_dpp v14, v2 row_mirror row_mask:0xf bank_mask:0xf
	s_waitcnt lgkmcnt(0)
	v_add_f32_e32 v2, v2, v14
	ds_bpermute_b32 v14, v13, v2
	s_and_saveexec_b64 s[4:5], s[0:1]
	s_cbranch_execz .LBB0_501
	s_waitcnt lgkmcnt(0)
	v_add_f32_e32 v2, v2, v14
	v_lshl_add_u64 v[14:15], v[0:1], 2, s[36:37]
	global_store_dword v[14:15], v2, off offset:4 sc1
.LBB0_501:
	s_or_b64 exec, exec, s[4:5]
	s_waitcnt lgkmcnt(0)
	v_pk_mul_f32 v[14:15], v[72:73], v[72:73]
	s_nop 0
	v_add_f32_e32 v2, v15, v14
	v_fmac_f32_e32 v2, v46, v46
	v_fmac_f32_e32 v2, v30, v30
	s_nop 1
	v_mov_b32_dpp v14, v2 quad_perm:[1,0,3,2] row_mask:0xf bank_mask:0xf
	s_waitcnt lgkmcnt(0)
	v_add_f32_e32 v2, v2, v14
	s_nop 1
	v_mov_b32_dpp v14, v2 quad_perm:[2,3,0,1] row_mask:0xf bank_mask:0xf
	s_waitcnt lgkmcnt(0)
	v_add_f32_e32 v2, v2, v14
	s_nop 1
	v_mov_b32_dpp v14, v2 row_half_mirror row_mask:0xf bank_mask:0xf
	s_waitcnt lgkmcnt(0)
	v_add_f32_e32 v2, v2, v14
	s_nop 1
	v_mov_b32_dpp v14, v2 row_mirror row_mask:0xf bank_mask:0xf
	s_waitcnt lgkmcnt(0)
	v_add_f32_e32 v2, v2, v14
	ds_bpermute_b32 v14, v13, v2
	s_and_saveexec_b64 s[4:5], s[0:1]
	s_cbranch_execz .LBB0_503
	s_waitcnt lgkmcnt(0)
	v_add_f32_e32 v2, v2, v14
	v_lshl_add_u64 v[14:15], v[0:1], 2, s[36:37]
	global_store_dword v[14:15], v2, off offset:8 sc1
.LBB0_503:
	s_or_b64 exec, exec, s[4:5]
	s_waitcnt lgkmcnt(0)
	v_pk_mul_f32 v[14:15], v[70:71], v[70:71]
	s_nop 0
	v_add_f32_e32 v2, v15, v14
	v_fmac_f32_e32 v2, v45, v45
	v_fmac_f32_e32 v2, v29, v29
	s_nop 1
	v_mov_b32_dpp v14, v2 quad_perm:[1,0,3,2] row_mask:0xf bank_mask:0xf
	s_waitcnt lgkmcnt(0)
	v_add_f32_e32 v2, v2, v14
	s_nop 1
	v_mov_b32_dpp v14, v2 quad_perm:[2,3,0,1] row_mask:0xf bank_mask:0xf
	s_waitcnt lgkmcnt(0)
	v_add_f32_e32 v2, v2, v14
	s_nop 1
	v_mov_b32_dpp v14, v2 row_half_mirror row_mask:0xf bank_mask:0xf
	s_waitcnt lgkmcnt(0)
	v_add_f32_e32 v2, v2, v14
	s_nop 1
	v_mov_b32_dpp v14, v2 row_mirror row_mask:0xf bank_mask:0xf
	s_waitcnt lgkmcnt(0)
	v_add_f32_e32 v2, v2, v14
	ds_bpermute_b32 v14, v13, v2
	s_and_saveexec_b64 s[4:5], s[0:1]
	s_cbranch_execz .LBB0_505
	s_waitcnt lgkmcnt(0)
	v_add_f32_e32 v2, v2, v14
	v_lshl_add_u64 v[14:15], v[0:1], 2, s[36:37]
	global_store_dword v[14:15], v2, off offset:12 sc1
.LBB0_505:
	s_or_b64 exec, exec, s[4:5]
	s_waitcnt lgkmcnt(0)
	v_pk_mul_f32 v[14:15], v[68:69], v[68:69]
	s_nop 0
	v_add_f32_e32 v2, v15, v14
	v_fmac_f32_e32 v2, v44, v44
	v_fmac_f32_e32 v2, v28, v28
	s_nop 1
	v_mov_b32_dpp v14, v2 quad_perm:[1,0,3,2] row_mask:0xf bank_mask:0xf
	s_waitcnt lgkmcnt(0)
	v_add_f32_e32 v2, v2, v14
	s_nop 1
	v_mov_b32_dpp v14, v2 quad_perm:[2,3,0,1] row_mask:0xf bank_mask:0xf
	s_waitcnt lgkmcnt(0)
	v_add_f32_e32 v2, v2, v14
	s_nop 1
	v_mov_b32_dpp v14, v2 row_half_mirror row_mask:0xf bank_mask:0xf
	s_waitcnt lgkmcnt(0)
	v_add_f32_e32 v2, v2, v14
	s_nop 1
	v_mov_b32_dpp v14, v2 row_mirror row_mask:0xf bank_mask:0xf
	s_waitcnt lgkmcnt(0)
	v_add_f32_e32 v2, v2, v14
	ds_bpermute_b32 v14, v13, v2
	s_and_saveexec_b64 s[4:5], s[0:1]
	s_cbranch_execz .LBB0_507
	s_waitcnt lgkmcnt(0)
	v_add_f32_e32 v2, v2, v14
	v_lshl_add_u64 v[14:15], v[0:1], 2, s[36:37]
	global_store_dword v[14:15], v2, off offset:32 sc1
.LBB0_507:
	s_or_b64 exec, exec, s[4:5]
	s_waitcnt lgkmcnt(0)
	v_pk_mul_f32 v[14:15], v[66:67], v[66:67]
	s_nop 0
	v_add_f32_e32 v2, v15, v14
	v_fmac_f32_e32 v2, v43, v43
	v_fmac_f32_e32 v2, v27, v27
	s_nop 1
	v_mov_b32_dpp v14, v2 quad_perm:[1,0,3,2] row_mask:0xf bank_mask:0xf
	s_waitcnt lgkmcnt(0)
	v_add_f32_e32 v2, v2, v14
	s_nop 1
	v_mov_b32_dpp v14, v2 quad_perm:[2,3,0,1] row_mask:0xf bank_mask:0xf
	s_waitcnt lgkmcnt(0)
	v_add_f32_e32 v2, v2, v14
	s_nop 1
	v_mov_b32_dpp v14, v2 row_half_mirror row_mask:0xf bank_mask:0xf
	s_waitcnt lgkmcnt(0)
	v_add_f32_e32 v2, v2, v14
	s_nop 1
	v_mov_b32_dpp v14, v2 row_mirror row_mask:0xf bank_mask:0xf
	s_waitcnt lgkmcnt(0)
	v_add_f32_e32 v2, v2, v14
	ds_bpermute_b32 v14, v13, v2
	s_and_saveexec_b64 s[4:5], s[0:1]
	s_cbranch_execz .LBB0_509
	s_waitcnt lgkmcnt(0)
	v_add_f32_e32 v2, v2, v14
	v_lshl_add_u64 v[14:15], v[0:1], 2, s[36:37]
	global_store_dword v[14:15], v2, off offset:36 sc1
.LBB0_509:
	s_or_b64 exec, exec, s[4:5]
	s_waitcnt lgkmcnt(0)
	v_pk_mul_f32 v[14:15], v[64:65], v[64:65]
	s_nop 0
	v_add_f32_e32 v2, v15, v14
	v_fmac_f32_e32 v2, v42, v42
	v_fmac_f32_e32 v2, v26, v26
	s_nop 1
	v_mov_b32_dpp v14, v2 quad_perm:[1,0,3,2] row_mask:0xf bank_mask:0xf
	s_waitcnt lgkmcnt(0)
	v_add_f32_e32 v2, v2, v14
	s_nop 1
	v_mov_b32_dpp v14, v2 quad_perm:[2,3,0,1] row_mask:0xf bank_mask:0xf
	s_waitcnt lgkmcnt(0)
	v_add_f32_e32 v2, v2, v14
	s_nop 1
	v_mov_b32_dpp v14, v2 row_half_mirror row_mask:0xf bank_mask:0xf
	s_waitcnt lgkmcnt(0)
	v_add_f32_e32 v2, v2, v14
	s_nop 1
	v_mov_b32_dpp v14, v2 row_mirror row_mask:0xf bank_mask:0xf
	s_waitcnt lgkmcnt(0)
	v_add_f32_e32 v2, v2, v14
	ds_bpermute_b32 v14, v13, v2
	s_and_saveexec_b64 s[4:5], s[0:1]
	s_cbranch_execz .LBB0_511
	s_waitcnt lgkmcnt(0)
	v_add_f32_e32 v2, v2, v14
	v_lshl_add_u64 v[14:15], v[0:1], 2, s[36:37]
	global_store_dword v[14:15], v2, off offset:40 sc1
.LBB0_511:
	s_or_b64 exec, exec, s[4:5]
	s_waitcnt lgkmcnt(0)
	v_pk_mul_f32 v[14:15], v[54:55], v[54:55]
	s_nop 0
	v_add_f32_e32 v2, v15, v14
	v_fmac_f32_e32 v2, v23, v23
	v_fmac_f32_e32 v2, v25, v25
	s_nop 1
	v_mov_b32_dpp v14, v2 quad_perm:[1,0,3,2] row_mask:0xf bank_mask:0xf
	s_waitcnt lgkmcnt(0)
	v_add_f32_e32 v2, v2, v14
	s_nop 1
	v_mov_b32_dpp v14, v2 quad_perm:[2,3,0,1] row_mask:0xf bank_mask:0xf
	s_waitcnt lgkmcnt(0)
	v_add_f32_e32 v2, v2, v14
	s_nop 1
	v_mov_b32_dpp v14, v2 row_half_mirror row_mask:0xf bank_mask:0xf
	s_waitcnt lgkmcnt(0)
	v_add_f32_e32 v2, v2, v14
	s_nop 1
	v_mov_b32_dpp v14, v2 row_mirror row_mask:0xf bank_mask:0xf
	s_waitcnt lgkmcnt(0)
	v_add_f32_e32 v2, v2, v14
	ds_bpermute_b32 v14, v13, v2
	s_and_saveexec_b64 s[4:5], s[0:1]
	s_cbranch_execz .LBB0_513
	s_waitcnt lgkmcnt(0)
	v_add_f32_e32 v2, v2, v14
	v_lshl_add_u64 v[14:15], v[0:1], 2, s[36:37]
	global_store_dword v[14:15], v2, off offset:44 sc1
.LBB0_513:
	s_or_b64 exec, exec, s[4:5]
	s_waitcnt lgkmcnt(0)
	v_pk_mul_f32 v[14:15], v[52:53], v[52:53]
	s_nop 0
	v_add_f32_e32 v2, v15, v14
	v_fmac_f32_e32 v2, v22, v22
	v_fmac_f32_e32 v2, v24, v24
	s_nop 1
	v_mov_b32_dpp v14, v2 quad_perm:[1,0,3,2] row_mask:0xf bank_mask:0xf
	s_waitcnt lgkmcnt(0)
	v_add_f32_e32 v2, v2, v14
	s_nop 1
	v_mov_b32_dpp v14, v2 quad_perm:[2,3,0,1] row_mask:0xf bank_mask:0xf
	s_waitcnt lgkmcnt(0)
	v_add_f32_e32 v2, v2, v14
	s_nop 1
	v_mov_b32_dpp v14, v2 row_half_mirror row_mask:0xf bank_mask:0xf
	s_waitcnt lgkmcnt(0)
	v_add_f32_e32 v2, v2, v14
	s_nop 1
	v_mov_b32_dpp v14, v2 row_mirror row_mask:0xf bank_mask:0xf
	s_waitcnt lgkmcnt(0)
	v_add_f32_e32 v2, v2, v14
	ds_bpermute_b32 v14, v13, v2
	s_and_saveexec_b64 s[4:5], s[0:1]
	s_cbranch_execz .LBB0_515
	s_waitcnt lgkmcnt(0)
	v_add_f32_e32 v2, v2, v14
	v_lshl_add_u64 v[14:15], v[0:1], 2, s[36:37]
	global_store_dword v[14:15], v2, off offset:64 sc1
.LBB0_515:
	s_or_b64 exec, exec, s[4:5]
	s_waitcnt lgkmcnt(0)
	v_pk_mul_f32 v[14:15], v[50:51], v[50:51]
	s_nop 0
	v_add_f32_e32 v2, v15, v14
	v_fmac_f32_e32 v2, v21, v21
	v_fmac_f32_e32 v2, v9, v9
	s_nop 1
	v_mov_b32_dpp v9, v2 quad_perm:[1,0,3,2] row_mask:0xf bank_mask:0xf
	s_waitcnt lgkmcnt(0)
	v_add_f32_e32 v2, v2, v9
	s_nop 1
	v_mov_b32_dpp v9, v2 quad_perm:[2,3,0,1] row_mask:0xf bank_mask:0xf
	s_waitcnt lgkmcnt(0)
	v_add_f32_e32 v2, v2, v9
	s_nop 1
	v_mov_b32_dpp v9, v2 row_half_mirror row_mask:0xf bank_mask:0xf
	s_waitcnt lgkmcnt(0)
	v_add_f32_e32 v2, v2, v9
	s_nop 1
	v_mov_b32_dpp v9, v2 row_mirror row_mask:0xf bank_mask:0xf
	s_waitcnt lgkmcnt(0)
	v_add_f32_e32 v2, v2, v9
	ds_bpermute_b32 v9, v13, v2
	s_and_saveexec_b64 s[4:5], s[0:1]
	s_cbranch_execz .LBB0_517
	s_waitcnt lgkmcnt(0)
	v_add_f32_e32 v2, v2, v9
	v_lshl_add_u64 v[14:15], v[0:1], 2, s[36:37]
	global_store_dword v[14:15], v2, off offset:68 sc1
.LBB0_517:
	s_or_b64 exec, exec, s[4:5]
	v_pk_mul_f32 v[14:15], v[48:49], v[48:49]
	s_nop 0
	v_add_f32_e32 v2, v15, v14
	v_fmac_f32_e32 v2, v20, v20
	v_fmac_f32_e32 v2, v8, v8
	s_nop 1
	v_mov_b32_dpp v8, v2 quad_perm:[1,0,3,2] row_mask:0xf bank_mask:0xf
	s_waitcnt lgkmcnt(0)
	v_add_f32_e32 v2, v2, v8
	s_nop 1
	v_mov_b32_dpp v8, v2 quad_perm:[2,3,0,1] row_mask:0xf bank_mask:0xf
	s_waitcnt lgkmcnt(0)
	v_add_f32_e32 v2, v2, v8
	s_nop 1
	v_mov_b32_dpp v8, v2 row_half_mirror row_mask:0xf bank_mask:0xf
	s_waitcnt lgkmcnt(0)
	v_add_f32_e32 v2, v2, v8
	s_nop 1
	v_mov_b32_dpp v8, v2 row_mirror row_mask:0xf bank_mask:0xf
	s_waitcnt lgkmcnt(0)
	v_add_f32_e32 v2, v2, v8
	ds_bpermute_b32 v8, v13, v2
	s_and_saveexec_b64 s[4:5], s[0:1]
	s_cbranch_execz .LBB0_519
	s_waitcnt lgkmcnt(0)
	v_add_f32_e32 v2, v2, v8
	v_lshl_add_u64 v[8:9], v[0:1], 2, s[36:37]
	global_store_dword v[8:9], v2, off offset:72 sc1
.LBB0_519:
	s_or_b64 exec, exec, s[4:5]
	s_waitcnt lgkmcnt(0)
	v_pk_mul_f32 v[8:9], v[40:41], v[40:41]
	s_nop 0
	v_add_f32_e32 v2, v9, v8
	v_fmac_f32_e32 v2, v19, v19
	v_fmac_f32_e32 v2, v7, v7
	s_nop 1
	v_mov_b32_dpp v7, v2 quad_perm:[1,0,3,2] row_mask:0xf bank_mask:0xf
	s_waitcnt lgkmcnt(0)
	v_add_f32_e32 v2, v2, v7
	s_nop 1
	v_mov_b32_dpp v7, v2 quad_perm:[2,3,0,1] row_mask:0xf bank_mask:0xf
	s_waitcnt lgkmcnt(0)
	v_add_f32_e32 v2, v2, v7
	s_nop 1
	v_mov_b32_dpp v7, v2 row_half_mirror row_mask:0xf bank_mask:0xf
	s_waitcnt lgkmcnt(0)
	v_add_f32_e32 v2, v2, v7
	s_nop 1
	v_mov_b32_dpp v7, v2 row_mirror row_mask:0xf bank_mask:0xf
	s_waitcnt lgkmcnt(0)
	v_add_f32_e32 v2, v2, v7
	ds_bpermute_b32 v7, v13, v2
	s_and_saveexec_b64 s[4:5], s[0:1]
	s_cbranch_execz .LBB0_521
	s_waitcnt lgkmcnt(0)
	v_add_f32_e32 v2, v2, v7
	v_lshl_add_u64 v[8:9], v[0:1], 2, s[36:37]
	global_store_dword v[8:9], v2, off offset:76 sc1
.LBB0_521:
	s_or_b64 exec, exec, s[4:5]
	v_pk_mul_f32 v[8:9], v[38:39], v[38:39]
	s_nop 0
	v_add_f32_e32 v2, v9, v8
	v_fmac_f32_e32 v2, v18, v18
	v_fmac_f32_e32 v2, v6, v6
	s_nop 1
	v_mov_b32_dpp v6, v2 quad_perm:[1,0,3,2] row_mask:0xf bank_mask:0xf
	s_waitcnt lgkmcnt(0)
	v_add_f32_e32 v2, v2, v6
	s_nop 1
	v_mov_b32_dpp v6, v2 quad_perm:[2,3,0,1] row_mask:0xf bank_mask:0xf
	s_waitcnt lgkmcnt(0)
	v_add_f32_e32 v2, v2, v6
	s_nop 1
	v_mov_b32_dpp v6, v2 row_half_mirror row_mask:0xf bank_mask:0xf
	s_waitcnt lgkmcnt(0)
	v_add_f32_e32 v2, v2, v6
	s_nop 1
	v_mov_b32_dpp v6, v2 row_mirror row_mask:0xf bank_mask:0xf
	s_waitcnt lgkmcnt(0)
	v_add_f32_e32 v2, v2, v6
	ds_bpermute_b32 v6, v13, v2
	s_and_saveexec_b64 s[4:5], s[0:1]
	s_cbranch_execz .LBB0_523
	s_waitcnt lgkmcnt(0)
	v_add_f32_e32 v2, v2, v6
	v_lshl_add_u64 v[6:7], v[0:1], 2, s[36:37]
	global_store_dword v[6:7], v2, off offset:96 sc1
.LBB0_523:
	s_or_b64 exec, exec, s[4:5]
	s_waitcnt lgkmcnt(0)
	v_pk_mul_f32 v[6:7], v[36:37], v[36:37]
	s_nop 0
	v_add_f32_e32 v2, v7, v6
	v_fmac_f32_e32 v2, v17, v17
	v_fmac_f32_e32 v2, v5, v5
	s_nop 1
	v_mov_b32_dpp v5, v2 quad_perm:[1,0,3,2] row_mask:0xf bank_mask:0xf
	s_waitcnt lgkmcnt(0)
	v_add_f32_e32 v2, v2, v5
	s_nop 1
	v_mov_b32_dpp v5, v2 quad_perm:[2,3,0,1] row_mask:0xf bank_mask:0xf
	s_waitcnt lgkmcnt(0)
	v_add_f32_e32 v2, v2, v5
	s_nop 1
	v_mov_b32_dpp v5, v2 row_half_mirror row_mask:0xf bank_mask:0xf
	s_waitcnt lgkmcnt(0)
	v_add_f32_e32 v2, v2, v5
	s_nop 1
	v_mov_b32_dpp v5, v2 row_mirror row_mask:0xf bank_mask:0xf
	s_waitcnt lgkmcnt(0)
	v_add_f32_e32 v2, v2, v5
	ds_bpermute_b32 v5, v13, v2
	s_and_saveexec_b64 s[4:5], s[0:1]
	s_cbranch_execz .LBB0_525
	s_waitcnt lgkmcnt(0)
	v_add_f32_e32 v2, v2, v5
	v_lshl_add_u64 v[6:7], v[0:1], 2, s[36:37]
	global_store_dword v[6:7], v2, off offset:100 sc1
.LBB0_525:
	s_or_b64 exec, exec, s[4:5]
	v_pk_mul_f32 v[6:7], v[34:35], v[34:35]
	s_nop 0
	v_add_f32_e32 v2, v7, v6
	v_fmac_f32_e32 v2, v16, v16
	v_fmac_f32_e32 v2, v4, v4
	s_nop 1
	v_mov_b32_dpp v4, v2 quad_perm:[1,0,3,2] row_mask:0xf bank_mask:0xf
	s_waitcnt lgkmcnt(0)
	v_add_f32_e32 v2, v2, v4
	s_nop 1
	v_mov_b32_dpp v4, v2 quad_perm:[2,3,0,1] row_mask:0xf bank_mask:0xf
	s_waitcnt lgkmcnt(0)
	v_add_f32_e32 v2, v2, v4
	s_nop 1
	v_mov_b32_dpp v4, v2 row_half_mirror row_mask:0xf bank_mask:0xf
	s_waitcnt lgkmcnt(0)
	v_add_f32_e32 v2, v2, v4
	s_nop 1
	v_mov_b32_dpp v4, v2 row_mirror row_mask:0xf bank_mask:0xf
	s_waitcnt lgkmcnt(0)
	v_add_f32_e32 v2, v2, v4
	ds_bpermute_b32 v4, v13, v2
	s_and_saveexec_b64 s[4:5], s[0:1]
	s_cbranch_execz .LBB0_527
	s_waitcnt lgkmcnt(0)
	v_add_f32_e32 v2, v2, v4
	v_lshl_add_u64 v[4:5], v[0:1], 2, s[36:37]
	global_store_dword v[4:5], v2, off offset:104 sc1
.LBB0_527:
	s_or_b64 exec, exec, s[4:5]
	s_waitcnt lgkmcnt(0)
	v_pk_mul_f32 v[4:5], v[32:33], v[32:33]
	s_nop 0
	v_add_f32_e32 v2, v5, v4
	v_fmac_f32_e32 v2, v82, v82
	v_fmac_f32_e32 v2, v83, v83
	s_nop 1
	v_mov_b32_dpp v3, v2 quad_perm:[1,0,3,2] row_mask:0xf bank_mask:0xf
	s_waitcnt lgkmcnt(0)
	v_add_f32_e32 v2, v2, v3
	s_nop 1
	v_mov_b32_dpp v3, v2 quad_perm:[2,3,0,1] row_mask:0xf bank_mask:0xf
	s_waitcnt lgkmcnt(0)
	v_add_f32_e32 v2, v2, v3
	s_nop 1
	v_mov_b32_dpp v3, v2 row_half_mirror row_mask:0xf bank_mask:0xf
	s_waitcnt lgkmcnt(0)
	v_add_f32_e32 v2, v2, v3
	s_nop 1
	v_mov_b32_dpp v3, v2 row_mirror row_mask:0xf bank_mask:0xf
	s_waitcnt lgkmcnt(0)
	v_add_f32_e32 v2, v2, v3
	ds_bpermute_b32 v3, v13, v2
	s_and_saveexec_b64 s[4:5], s[0:1]
	s_cbranch_execz .LBB0_256
	s_waitcnt lgkmcnt(0)
	v_add_f32_e32 v2, v2, v3
	v_lshl_add_u64 v[0:1], v[0:1], 2, s[36:37]
	global_store_dword v[0:1], v2, off offset:108 sc1
	s_branch .LBB0_256

.LBB0_576:
	s_mul_hi_i32 s0, s71, 0x2aaaaaab
	s_lshr_b32 s1, s0, 31
	s_ashr_i32 s0, s0, 4
	s_add_i32 s0, s0, s1
	s_lshl_b32 s1, s0, 3
	s_mulk_i32 s0, 0xffa0
	s_add_i32 s66, s71, s0
	s_ashr_i32 s0, s66, 31
	s_lshr_b32 s0, s0, 29
	s_add_i32 s0, s66, s0
	s_ashr_i32 s72, s0, 3
	s_and_b32 s0, s0, -8
	s_sub_i32 s74, s66, s0
	s_add_i32 s74, s74, s1
	s_lshl_b32 s73, s74, 7
	v_readfirstlane_b32 s85, v100
	s_lshl_b32 s67, s72, 7
	v_mad_i64_i32 v[72:73], s[0:1], s73, v99, v[66:67]
	s_mov_b32 m0, s85
	v_readfirstlane_b32 s78, v101
	v_mad_i64_i32 v[70:71], s[0:1], s67, v99, v[68:69]
	global_load_lds_dwordx4 v[72:73], off
	s_mov_b32 m0, s78
	v_readfirstlane_b32 s79, v102
	global_load_lds_dwordx4 v[70:71], off
	v_lshl_add_u64 v[0:1], v[72:73], 0, s[18:19]
	s_mov_b32 m0, s79
	v_readfirstlane_b32 s80, v103
	global_load_lds_dwordx4 v[0:1], off
	v_lshl_add_u64 v[0:1], v[70:71], 0, s[18:19]
	s_mov_b32 m0, s80
	v_readfirstlane_b32 s81, v104
	global_load_lds_dwordx4 v[0:1], off
	v_lshl_add_u64 v[0:1], v[72:73], 0, s[20:21]
	s_mov_b32 m0, s81
	v_readfirstlane_b32 s82, v105
	global_load_lds_dwordx4 v[0:1], off
	v_lshl_add_u64 v[0:1], v[70:71], 0, s[20:21]
	s_mov_b32 m0, s82
	v_readfirstlane_b32 s83, v106
	global_load_lds_dwordx4 v[0:1], off
	v_lshl_add_u64 v[0:1], v[72:73], 0, s[22:23]
	s_mov_b32 m0, s83
	v_readfirstlane_b32 s84, v107
	global_load_lds_dwordx4 v[0:1], off
	v_lshl_add_u64 v[0:1], v[70:71], 0, s[22:23]
	s_mov_b32 m0, s84
	v_readfirstlane_b32 s77, v108
	global_load_lds_dwordx4 v[0:1], off
	v_lshl_add_u64 v[0:1], v[72:73], 0, s[24:25]
	s_mov_b32 m0, s77
	v_readfirstlane_b32 s0, v109
	s_waitcnt vmcnt(0)
	s_waitcnt vmcnt(0) lgkmcnt(0)
	s_barrier
	v_lshl_add_u64 v[2:3], v[70:71], 0, s[24:25]
	global_load_lds_dwordx4 v[0:1], off
	s_mov_b32 m0, s0
	v_readfirstlane_b32 s1, v110
	global_load_lds_dwordx4 v[2:3], off
	v_lshl_add_u64 v[0:1], v[72:73], 0, s[26:27]
	s_mov_b32 m0, s1
	v_readfirstlane_b32 s67, v111
	global_load_lds_dwordx4 v[0:1], off
	v_lshl_add_u64 v[0:1], v[70:71], 0, s[26:27]
	s_mov_b32 m0, s67
	v_readfirstlane_b32 s68, v112
	global_load_lds_dwordx4 v[0:1], off
	v_lshl_add_u64 v[0:1], v[72:73], 0, s[28:29]
	s_mov_b32 m0, s68
	v_readfirstlane_b32 s69, v113
	global_load_lds_dwordx4 v[0:1], off
	v_lshl_add_u64 v[0:1], v[70:71], 0, s[28:29]
	s_mov_b32 m0, s69
	v_readfirstlane_b32 s75, v114
	global_load_lds_dwordx4 v[0:1], off
	v_lshl_add_u64 v[0:1], v[72:73], 0, s[30:31]
	s_mov_b32 m0, s75
	v_readfirstlane_b32 s76, v115
	global_load_lds_dwordx4 v[0:1], off
	v_lshl_add_u64 v[0:1], v[70:71], 0, s[30:31]
	s_mov_b32 m0, s76
	v_add_u32_e32 v121, v75, v77
	global_load_lds_dwordx4 v[0:1], off
	ds_read_b128 v[0:3], v116
	ds_read_b128 v[4:7], v117 offset:16384
	ds_read_b128 v[8:11], v117 offset:20480
	ds_read_b128 v[12:15], v117 offset:24576
	ds_read_b128 v[122:125], v117 offset:28672
	ds_read_b128 v[126:129], v118
	ds_read_b128 v[130:133], v121 offset:16384
	ds_read_b128 v[134:137], v121 offset:20480
	ds_read_b128 v[138:141], v121 offset:24576
	ds_read_b128 v[142:145], v121 offset:28672
	s_setprio 1
	s_waitcnt lgkmcnt(0)
	v_mfma_f32_32x32x16_bf16 v[48:63], v[0:3], v[4:7], 0
	v_mfma_f32_32x32x16_bf16 v[32:47], v[0:3], v[8:11], 0
	v_mfma_f32_32x32x16_bf16 v[16:31], v[0:3], v[12:15], 0
	v_mfma_f32_32x32x16_bf16 v[0:15], v[0:3], v[122:125], 0
	s_setprio 0
	v_add_u32_e32 v162, v76, v78
	v_add_u32_e32 v163, v75, v78
	ds_read_b128 v[122:125], v162
	ds_read_b128 v[146:149], v163 offset:16384
	ds_read_b128 v[150:153], v163 offset:20480
	ds_read_b128 v[154:157], v163 offset:24576
	ds_read_b128 v[158:161], v163 offset:28672
	s_setprio 1
	v_mfma_f32_32x32x16_bf16 v[48:63], v[126:129], v[130:133], v[48:63]
	v_mfma_f32_32x32x16_bf16 v[32:47], v[126:129], v[134:137], v[32:47]
	v_mfma_f32_32x32x16_bf16 v[16:31], v[126:129], v[138:141], v[16:31]
	v_mfma_f32_32x32x16_bf16 v[0:15], v[126:129], v[142:145], v[0:15]
	s_setprio 0
	v_add_u32_e32 v164, v76, v79
	v_add_u32_e32 v165, v75, v79
	ds_read_b128 v[126:129], v164
	ds_read_b128 v[130:133], v165 offset:16384
	ds_read_b128 v[134:137], v165 offset:20480
	ds_read_b128 v[138:141], v165 offset:24576
	ds_read_b128 v[142:145], v165 offset:28672
	s_setprio 1
	s_waitcnt lgkmcnt(0)
	v_mfma_f32_32x32x16_bf16 v[48:63], v[122:125], v[146:149], v[48:63]
	v_mfma_f32_32x32x16_bf16 v[32:47], v[122:125], v[150:153], v[32:47]
	v_mfma_f32_32x32x16_bf16 v[16:31], v[122:125], v[154:157], v[16:31]
	v_mfma_f32_32x32x16_bf16 v[0:15], v[122:125], v[158:161], v[0:15]
	s_setprio 0
	s_setprio 1
	v_mfma_f32_32x32x16_bf16 v[48:63], v[126:129], v[130:133], v[48:63]
	v_mfma_f32_32x32x16_bf16 v[32:47], v[126:129], v[134:137], v[32:47]
	v_mfma_f32_32x32x16_bf16 v[16:31], v[126:129], v[138:141], v[16:31]
	v_mfma_f32_32x32x16_bf16 v[0:15], v[126:129], v[142:145], v[0:15]
	s_setprio 0
	s_mov_b32 m0, s85
	v_lshl_add_u64 v[122:123], v[72:73], 0, s[34:35]
	s_waitcnt vmcnt(0)
	s_waitcnt vmcnt(0)
	s_barrier
	v_lshl_add_u64 v[124:125], v[70:71], 0, s[34:35]
	global_load_lds_dwordx4 v[122:123], off
	s_mov_b32 m0, s78
	v_lshl_add_u64 v[122:123], v[72:73], 0, s[36:37]
	global_load_lds_dwordx4 v[124:125], off
	s_mov_b32 m0, s79
	s_nop 0
	global_load_lds_dwordx4 v[122:123], off
	v_lshl_add_u64 v[122:123], v[70:71], 0, s[36:37]
	s_mov_b32 m0, s80
	s_nop 0
	global_load_lds_dwordx4 v[122:123], off
	v_lshl_add_u64 v[122:123], v[72:73], 0, s[38:39]
	s_mov_b32 m0, s81
	s_nop 0
	global_load_lds_dwordx4 v[122:123], off
	v_lshl_add_u64 v[122:123], v[70:71], 0, s[38:39]
	s_mov_b32 m0, s82
	s_nop 0
	global_load_lds_dwordx4 v[122:123], off
	v_lshl_add_u64 v[122:123], v[72:73], 0, s[40:41]
	s_mov_b32 m0, s83
	s_nop 0
	global_load_lds_dwordx4 v[122:123], off
	v_lshl_add_u64 v[122:123], v[70:71], 0, s[40:41]
	s_mov_b32 m0, s84
	s_nop 0
	global_load_lds_dwordx4 v[122:123], off
	ds_read_b128 v[122:125], v116 offset:32768
	ds_read_b128 v[126:129], v117 offset:49152
	ds_read_b128 v[130:133], v117 offset:53248
	ds_read_b128 v[134:137], v117 offset:57344
	ds_read_b128 v[138:141], v117 offset:61440
	ds_read_b128 v[142:145], v118 offset:32768
	ds_read_b128 v[146:149], v121 offset:49152
	ds_read_b128 v[150:153], v121 offset:53248
	ds_read_b128 v[154:157], v121 offset:57344
	ds_read_b128 v[158:161], v121 offset:61440
	s_setprio 1
	s_waitcnt lgkmcnt(0)
	v_mfma_f32_32x32x16_bf16 v[48:63], v[122:125], v[126:129], v[48:63]
	v_mfma_f32_32x32x16_bf16 v[32:47], v[122:125], v[130:133], v[32:47]
	v_mfma_f32_32x32x16_bf16 v[16:31], v[122:125], v[134:137], v[16:31]
	v_mfma_f32_32x32x16_bf16 v[0:15], v[122:125], v[138:141], v[0:15]
	s_setprio 0
	ds_read_b128 v[122:125], v162 offset:32768
	ds_read_b128 v[126:129], v163 offset:49152
	ds_read_b128 v[130:133], v163 offset:53248
	ds_read_b128 v[134:137], v163 offset:57344
	ds_read_b128 v[138:141], v163 offset:61440
	s_setprio 1
	v_mfma_f32_32x32x16_bf16 v[48:63], v[142:145], v[146:149], v[48:63]
	v_mfma_f32_32x32x16_bf16 v[32:47], v[142:145], v[150:153], v[32:47]
	v_mfma_f32_32x32x16_bf16 v[16:31], v[142:145], v[154:157], v[16:31]
	v_mfma_f32_32x32x16_bf16 v[0:15], v[142:145], v[158:161], v[0:15]
	s_setprio 0
	ds_read_b128 v[142:145], v164 offset:32768
	ds_read_b128 v[146:149], v165 offset:49152
	ds_read_b128 v[150:153], v165 offset:53248
	ds_read_b128 v[154:157], v165 offset:57344
	ds_read_b128 v[158:161], v165 offset:61440
	s_setprio 1
	s_waitcnt lgkmcnt(0)
	v_mfma_f32_32x32x16_bf16 v[48:63], v[122:125], v[126:129], v[48:63]
	v_mfma_f32_32x32x16_bf16 v[32:47], v[122:125], v[130:133], v[32:47]
	v_mfma_f32_32x32x16_bf16 v[16:31], v[122:125], v[134:137], v[16:31]
	v_mfma_f32_32x32x16_bf16 v[0:15], v[122:125], v[138:141], v[0:15]
	s_setprio 0
	s_setprio 1
	v_mfma_f32_32x32x16_bf16 v[48:63], v[142:145], v[146:149], v[48:63]
	v_mfma_f32_32x32x16_bf16 v[32:47], v[142:145], v[150:153], v[32:47]
	v_mfma_f32_32x32x16_bf16 v[16:31], v[142:145], v[154:157], v[16:31]
	v_mfma_f32_32x32x16_bf16 v[0:15], v[142:145], v[158:161], v[0:15]
	s_setprio 0
	s_mov_b32 m0, s77
	v_lshl_add_u64 v[122:123], v[72:73], 0, s[42:43]
	s_waitcnt vmcnt(0)
	s_waitcnt vmcnt(0)
	s_barrier
	v_lshl_add_u64 v[124:125], v[70:71], 0, s[42:43]
	global_load_lds_dwordx4 v[122:123], off
	s_mov_b32 m0, s0
	v_lshl_add_u64 v[122:123], v[72:73], 0, s[44:45]
	global_load_lds_dwordx4 v[124:125], off
	s_mov_b32 m0, s1
	s_nop 0
	global_load_lds_dwordx4 v[122:123], off
	v_lshl_add_u64 v[122:123], v[70:71], 0, s[44:45]
	s_mov_b32 m0, s67
	s_nop 0
	global_load_lds_dwordx4 v[122:123], off
	v_lshl_add_u64 v[122:123], v[72:73], 0, s[46:47]
	s_mov_b32 m0, s68
	s_nop 0
	global_load_lds_dwordx4 v[122:123], off
	v_lshl_add_u64 v[122:123], v[70:71], 0, s[46:47]
	s_mov_b32 m0, s69
	s_nop 0
	global_load_lds_dwordx4 v[122:123], off
	v_lshl_add_u64 v[122:123], v[72:73], 0, s[48:49]
	s_mov_b32 m0, s75
	s_nop 0
	global_load_lds_dwordx4 v[122:123], off
	v_lshl_add_u64 v[122:123], v[70:71], 0, s[48:49]
	s_mov_b32 m0, s76
	s_nop 0
	global_load_lds_dwordx4 v[122:123], off
	ds_read_b128 v[122:125], v116
	ds_read_b128 v[126:129], v117 offset:16384
	ds_read_b128 v[130:133], v117 offset:20480
	ds_read_b128 v[134:137], v117 offset:24576
	ds_read_b128 v[138:141], v117 offset:28672
	ds_read_b128 v[142:145], v118
	ds_read_b128 v[146:149], v121 offset:16384
	ds_read_b128 v[150:153], v121 offset:20480
	ds_read_b128 v[154:157], v121 offset:24576
	ds_read_b128 v[158:161], v121 offset:28672
	s_setprio 1
	s_waitcnt lgkmcnt(0)
	v_mfma_f32_32x32x16_bf16 v[48:63], v[122:125], v[126:129], v[48:63]
	v_mfma_f32_32x32x16_bf16 v[32:47], v[122:125], v[130:133], v[32:47]
	v_mfma_f32_32x32x16_bf16 v[16:31], v[122:125], v[134:137], v[16:31]
	v_mfma_f32_32x32x16_bf16 v[0:15], v[122:125], v[138:141], v[0:15]
	s_setprio 0
	ds_read_b128 v[122:125], v162
	ds_read_b128 v[126:129], v163 offset:16384
	ds_read_b128 v[130:133], v163 offset:20480
	ds_read_b128 v[134:137], v163 offset:24576
	ds_read_b128 v[138:141], v163 offset:28672
	s_setprio 1
	v_mfma_f32_32x32x16_bf16 v[48:63], v[142:145], v[146:149], v[48:63]
	v_mfma_f32_32x32x16_bf16 v[32:47], v[142:145], v[150:153], v[32:47]
	v_mfma_f32_32x32x16_bf16 v[16:31], v[142:145], v[154:157], v[16:31]
	v_mfma_f32_32x32x16_bf16 v[0:15], v[142:145], v[158:161], v[0:15]
	s_setprio 0
	ds_read_b128 v[142:145], v164
	ds_read_b128 v[146:149], v165 offset:16384
	ds_read_b128 v[150:153], v165 offset:20480
	ds_read_b128 v[154:157], v165 offset:24576
	ds_read_b128 v[158:161], v165 offset:28672
	s_setprio 1
	s_waitcnt lgkmcnt(0)
	v_mfma_f32_32x32x16_bf16 v[48:63], v[122:125], v[126:129], v[48:63]
	v_mfma_f32_32x32x16_bf16 v[32:47], v[122:125], v[130:133], v[32:47]
	v_mfma_f32_32x32x16_bf16 v[16:31], v[122:125], v[134:137], v[16:31]
	v_mfma_f32_32x32x16_bf16 v[0:15], v[122:125], v[138:141], v[0:15]
	s_setprio 0
	s_setprio 1
	v_mfma_f32_32x32x16_bf16 v[48:63], v[142:145], v[146:149], v[48:63]
	v_mfma_f32_32x32x16_bf16 v[32:47], v[142:145], v[150:153], v[32:47]
	v_mfma_f32_32x32x16_bf16 v[16:31], v[142:145], v[154:157], v[16:31]
	v_mfma_f32_32x32x16_bf16 v[0:15], v[142:145], v[158:161], v[0:15]
	s_setprio 0
	s_mov_b32 m0, s85
	v_lshl_add_u64 v[122:123], v[72:73], 0, s[50:51]
	s_waitcnt vmcnt(0)
	s_waitcnt vmcnt(0)
	s_barrier
	v_lshl_add_u64 v[124:125], v[70:71], 0, s[50:51]
	global_load_lds_dwordx4 v[122:123], off
	s_mov_b32 m0, s78
	v_lshl_add_u64 v[122:123], v[72:73], 0, s[52:53]
	global_load_lds_dwordx4 v[124:125], off
	s_mov_b32 m0, s79
	s_nop 0
	global_load_lds_dwordx4 v[122:123], off
	v_lshl_add_u64 v[122:123], v[70:71], 0, s[52:53]
	s_mov_b32 m0, s80
	s_nop 0
	global_load_lds_dwordx4 v[122:123], off
	v_lshl_add_u64 v[122:123], v[72:73], 0, s[54:55]
	s_mov_b32 m0, s81
	s_nop 0
	global_load_lds_dwordx4 v[122:123], off
	v_lshl_add_u64 v[122:123], v[70:71], 0, s[54:55]
	s_mov_b32 m0, s82
	s_nop 0
	global_load_lds_dwordx4 v[122:123], off
	v_lshl_add_u64 v[122:123], v[72:73], 0, s[56:57]
	s_mov_b32 m0, s83
	s_nop 0
	global_load_lds_dwordx4 v[122:123], off
	v_lshl_add_u64 v[122:123], v[70:71], 0, s[56:57]
	s_mov_b32 m0, s84
	s_nop 0
	global_load_lds_dwordx4 v[122:123], off
	ds_read_b128 v[122:125], v116 offset:32768
	ds_read_b128 v[126:129], v117 offset:49152
	ds_read_b128 v[130:133], v117 offset:53248
	ds_read_b128 v[134:137], v117 offset:57344
	ds_read_b128 v[138:141], v117 offset:61440
	ds_read_b128 v[142:145], v118 offset:32768
	ds_read_b128 v[146:149], v121 offset:49152
	ds_read_b128 v[150:153], v121 offset:53248
	ds_read_b128 v[154:157], v121 offset:57344
	ds_read_b128 v[158:161], v121 offset:61440
	s_setprio 1
	s_waitcnt lgkmcnt(0)
	v_mfma_f32_32x32x16_bf16 v[48:63], v[122:125], v[126:129], v[48:63]
	v_mfma_f32_32x32x16_bf16 v[32:47], v[122:125], v[130:133], v[32:47]
	v_mfma_f32_32x32x16_bf16 v[16:31], v[122:125], v[134:137], v[16:31]
	v_mfma_f32_32x32x16_bf16 v[0:15], v[122:125], v[138:141], v[0:15]
	s_setprio 0
	ds_read_b128 v[122:125], v162 offset:32768
	ds_read_b128 v[126:129], v163 offset:49152
	ds_read_b128 v[130:133], v163 offset:53248
	ds_read_b128 v[134:137], v163 offset:57344
	ds_read_b128 v[138:141], v163 offset:61440
	s_setprio 1
	v_mfma_f32_32x32x16_bf16 v[48:63], v[142:145], v[146:149], v[48:63]
	v_mfma_f32_32x32x16_bf16 v[32:47], v[142:145], v[150:153], v[32:47]
	v_mfma_f32_32x32x16_bf16 v[16:31], v[142:145], v[154:157], v[16:31]
	v_mfma_f32_32x32x16_bf16 v[0:15], v[142:145], v[158:161], v[0:15]
	s_setprio 0
	ds_read_b128 v[142:145], v164 offset:32768
	ds_read_b128 v[146:149], v165 offset:49152
	ds_read_b128 v[150:153], v165 offset:53248
	ds_read_b128 v[154:157], v165 offset:57344
	ds_read_b128 v[158:161], v165 offset:61440
	s_setprio 1
	s_waitcnt lgkmcnt(0)
	v_mfma_f32_32x32x16_bf16 v[48:63], v[122:125], v[126:129], v[48:63]
	v_mfma_f32_32x32x16_bf16 v[32:47], v[122:125], v[130:133], v[32:47]
	v_mfma_f32_32x32x16_bf16 v[16:31], v[122:125], v[134:137], v[16:31]
	v_mfma_f32_32x32x16_bf16 v[0:15], v[122:125], v[138:141], v[0:15]
	s_setprio 0
	s_setprio 1
	v_mfma_f32_32x32x16_bf16 v[48:63], v[142:145], v[146:149], v[48:63]
	v_mfma_f32_32x32x16_bf16 v[32:47], v[142:145], v[150:153], v[32:47]
	v_mfma_f32_32x32x16_bf16 v[16:31], v[142:145], v[154:157], v[16:31]
	v_mfma_f32_32x32x16_bf16 v[0:15], v[142:145], v[158:161], v[0:15]
	s_setprio 0
	s_mov_b32 m0, s77
	v_lshl_add_u64 v[122:123], v[72:73], 0, s[58:59]
	s_waitcnt vmcnt(0)
	s_waitcnt vmcnt(0)
	s_barrier
	v_lshl_add_u64 v[124:125], v[70:71], 0, s[58:59]
	global_load_lds_dwordx4 v[122:123], off
	s_mov_b32 m0, s0
	v_lshl_add_u64 v[122:123], v[72:73], 0, s[60:61]
	global_load_lds_dwordx4 v[124:125], off
	s_mov_b32 m0, s1
	s_nop 0
	global_load_lds_dwordx4 v[122:123], off
	v_lshl_add_u64 v[122:123], v[70:71], 0, s[60:61]
	s_mov_b32 m0, s67
	s_nop 0
	global_load_lds_dwordx4 v[122:123], off
	v_lshl_add_u64 v[122:123], v[72:73], 0, s[62:63]
	s_mov_b32 m0, s68
	v_lshl_add_u64 v[72:73], v[72:73], 0, s[64:65]
	global_load_lds_dwordx4 v[122:123], off
	v_lshl_add_u64 v[122:123], v[70:71], 0, s[62:63]
	s_mov_b32 m0, s69
	v_lshl_add_u64 v[70:71], v[70:71], 0, s[64:65]
	global_load_lds_dwordx4 v[122:123], off
	s_mov_b32 m0, s75
	s_nop 0
	global_load_lds_dwordx4 v[72:73], off
	s_mov_b32 m0, s76
	s_nop 0
	global_load_lds_dwordx4 v[70:71], off
	ds_read_b128 v[70:73], v116
	ds_read_b128 v[122:125], v117 offset:16384
	ds_read_b128 v[126:129], v117 offset:20480
	ds_read_b128 v[130:133], v117 offset:24576
	ds_read_b128 v[134:137], v117 offset:28672
	ds_read_b128 v[138:141], v118
	ds_read_b128 v[142:145], v121 offset:16384
	ds_read_b128 v[146:149], v121 offset:20480
	ds_read_b128 v[150:153], v121 offset:24576
	ds_read_b128 v[154:157], v121 offset:28672
	s_setprio 1
	s_waitcnt lgkmcnt(0)
	v_mfma_f32_32x32x16_bf16 v[48:63], v[70:73], v[122:125], v[48:63]
	v_mfma_f32_32x32x16_bf16 v[32:47], v[70:73], v[126:129], v[32:47]
	v_mfma_f32_32x32x16_bf16 v[16:31], v[70:73], v[130:133], v[16:31]
	v_mfma_f32_32x32x16_bf16 v[0:15], v[70:73], v[134:137], v[0:15]
	s_setprio 0
	ds_read_b128 v[70:73], v162
	ds_read_b128 v[122:125], v163 offset:16384
	ds_read_b128 v[126:129], v163 offset:20480
	ds_read_b128 v[130:133], v163 offset:24576
	ds_read_b128 v[134:137], v163 offset:28672
	s_setprio 1
	v_mfma_f32_32x32x16_bf16 v[48:63], v[138:141], v[142:145], v[48:63]
	v_mfma_f32_32x32x16_bf16 v[32:47], v[138:141], v[146:149], v[32:47]
	v_mfma_f32_32x32x16_bf16 v[16:31], v[138:141], v[150:153], v[16:31]
	v_mfma_f32_32x32x16_bf16 v[0:15], v[138:141], v[154:157], v[0:15]
	s_setprio 0
	ds_read_b128 v[138:141], v164
	ds_read_b128 v[142:145], v165 offset:16384
	ds_read_b128 v[146:149], v165 offset:20480
	ds_read_b128 v[150:153], v165 offset:24576
	ds_read_b128 v[154:157], v165 offset:28672
	s_setprio 1
	s_waitcnt lgkmcnt(0)
	v_mfma_f32_32x32x16_bf16 v[48:63], v[70:73], v[122:125], v[48:63]
	v_mfma_f32_32x32x16_bf16 v[32:47], v[70:73], v[126:129], v[32:47]
	v_mfma_f32_32x32x16_bf16 v[16:31], v[70:73], v[130:133], v[16:31]
	v_mfma_f32_32x32x16_bf16 v[0:15], v[70:73], v[134:137], v[0:15]
	s_setprio 0
	s_setprio 1
	v_mfma_f32_32x32x16_bf16 v[48:63], v[138:141], v[142:145], v[48:63]
	v_mfma_f32_32x32x16_bf16 v[32:47], v[138:141], v[146:149], v[32:47]
	v_mfma_f32_32x32x16_bf16 v[16:31], v[138:141], v[150:153], v[16:31]
	v_mfma_f32_32x32x16_bf16 v[0:15], v[138:141], v[154:157], v[0:15]
	s_setprio 0
	s_waitcnt vmcnt(0)
	s_waitcnt vmcnt(0)
	s_barrier
	ds_read_b128 v[70:73], v121 offset:61440
	ds_read_b128 v[122:125], v121 offset:57344
	ds_read_b128 v[126:129], v121 offset:53248
	ds_read_b128 v[130:133], v121 offset:49152
	ds_read_b128 v[134:137], v118 offset:32768
	ds_read_b128 v[138:141], v117 offset:61440
	ds_read_b128 v[142:145], v117 offset:57344
	ds_read_b128 v[146:149], v117 offset:53248
	ds_read_b128 v[150:153], v117 offset:49152
	ds_read_b128 v[154:157], v116 offset:32768
	s_setprio 1
	s_waitcnt lgkmcnt(0)
	v_mfma_f32_32x32x16_bf16 v[48:63], v[154:157], v[150:153], v[48:63]
	v_mfma_f32_32x32x16_bf16 v[32:47], v[154:157], v[146:149], v[32:47]
	v_mfma_f32_32x32x16_bf16 v[16:31], v[154:157], v[142:145], v[16:31]
	v_mfma_f32_32x32x16_bf16 v[0:15], v[154:157], v[138:141], v[0:15]
	s_setprio 0
	ds_read_b128 v[138:141], v162 offset:32768
	ds_read_b128 v[142:145], v163 offset:49152
	ds_read_b128 v[146:149], v163 offset:53248
	ds_read_b128 v[150:153], v163 offset:57344
	ds_read_b128 v[154:157], v163 offset:61440
	s_setprio 1
	v_mfma_f32_32x32x16_bf16 v[48:63], v[134:137], v[130:133], v[48:63]
	v_mfma_f32_32x32x16_bf16 v[32:47], v[134:137], v[126:129], v[32:47]
	v_mfma_f32_32x32x16_bf16 v[16:31], v[134:137], v[122:125], v[16:31]
	v_mfma_f32_32x32x16_bf16 v[0:15], v[134:137], v[70:73], v[0:15]
	s_setprio 0
	ds_read_b128 v[70:73], v164 offset:32768
	ds_read_b128 v[122:125], v165 offset:49152
	ds_read_b128 v[126:129], v165 offset:53248
	ds_read_b128 v[130:133], v165 offset:57344
	ds_read_b128 v[134:137], v165 offset:61440
	s_setprio 1
	s_waitcnt lgkmcnt(8)
	v_mfma_f32_32x32x16_bf16 v[48:63], v[138:141], v[142:145], v[48:63]
	s_waitcnt lgkmcnt(7)
	v_mfma_f32_32x32x16_bf16 v[32:47], v[138:141], v[146:149], v[32:47]
	s_waitcnt lgkmcnt(6)
	v_mfma_f32_32x32x16_bf16 v[16:31], v[138:141], v[150:153], v[16:31]
	s_waitcnt lgkmcnt(5)
	v_mfma_f32_32x32x16_bf16 v[0:15], v[138:141], v[154:157], v[0:15]
	s_setprio 0
	s_setprio 1
	s_waitcnt lgkmcnt(3)
	v_mfma_f32_32x32x16_bf16 v[48:63], v[70:73], v[122:125], v[48:63]
	s_waitcnt lgkmcnt(2)
	v_mfma_f32_32x32x16_bf16 v[32:47], v[70:73], v[126:129], v[32:47]
	s_waitcnt lgkmcnt(1)
	v_mfma_f32_32x32x16_bf16 v[16:31], v[70:73], v[130:133], v[16:31]
	s_waitcnt lgkmcnt(0)
	v_mfma_f32_32x32x16_bf16 v[0:15], v[70:73], v[134:137], v[0:15]
	s_setprio 0
	v_mov_b32_e32 v70, s10
	ds_read_b64 v[70:71], v70
	s_mov_b64 s[0:1], -1
	s_cmp_gt_i32 s66, 63
	v_lshlrev_b32_e32 v121, 2, v64
	v_mbcnt_hi_u32_b32 v122, -1, v120
	s_waitcnt lgkmcnt(0)
	v_readfirstlane_b32 s66, v70
	v_readfirstlane_b32 s67, v71
	s_cbranch_scc0 .LBB0_642
	s_nop 3
	global_load_dword v71, v121, s[66:67] offset:512
	global_load_dword v70, v121, s[66:67] offset:640
	v_and_b32_e32 v124, 64, v122
	v_xor_b32_e32 v123, 1, v122
	v_add_u32_e32 v128, 64, v124
	v_mov_b32_e32 v72, v48
	v_mov_b32_e32 v73, v32
	v_cmp_lt_i32_e32 vcc, v123, v128
	v_pk_mul_f32 v[72:73], v[72:73], v[72:73]
	v_xor_b32_e32 v125, 2, v122
	v_cndmask_b32_e32 v123, v122, v123, vcc
	v_add_f32_e32 v72, v72, v73
	v_lshlrev_b32_e32 v123, 2, v123
	s_nop 1
	v_mov_b32_dpp v73, v72 quad_perm:[1,0,3,2] row_mask:0xf bank_mask:0xf
	v_cmp_lt_i32_e32 vcc, v125, v128
	v_xor_b32_e32 v126, 4, v122
	v_xor_b32_e32 v127, 8, v122
	v_cndmask_b32_e32 v124, v122, v125, vcc
	v_lshlrev_b32_e32 v124, 2, v124
	s_waitcnt lgkmcnt(0)
	v_add_f32_e32 v72, v72, v73
	s_nop 1
	v_mov_b32_dpp v73, v72 quad_perm:[2,3,0,1] row_mask:0xf bank_mask:0xf
	v_cmp_lt_i32_e32 vcc, v126, v128
	v_xor_b32_e32 v129, 16, v122
	s_cmp_gt_i32 s74, 63
	v_cndmask_b32_e32 v125, v122, v126, vcc
	v_lshlrev_b32_e32 v125, 2, v125
	s_waitcnt lgkmcnt(0)
	v_add_f32_e32 v73, v72, v73
	s_nop 1
	v_mov_b32_dpp v126, v73 row_half_mirror row_mask:0xf bank_mask:0xf
	v_cmp_lt_i32_e32 vcc, v127, v128
	s_cselect_b64 s[68:69], -1, 0
	s_and_b64 s[0:1], s[68:69], exec
	v_cndmask_b32_e32 v127, v122, v127, vcc
	v_lshlrev_b32_e32 v127, 2, v127
	s_waitcnt lgkmcnt(0)
	v_add_f32_e32 v130, v73, v126
	s_nop 1
	v_mov_b32_dpp v131, v130 row_mirror row_mask:0xf bank_mask:0xf
	v_cmp_lt_i32_e32 vcc, v129, v128
	s_cselect_b32 s0, s11, 0x80
	s_and_b32 s76, s0, s73
	v_cndmask_b32_e32 v126, v122, v129, vcc
	v_lshlrev_b32_e32 v126, 2, v126
	s_waitcnt lgkmcnt(0)
	v_add_f32_e32 v128, v130, v131
	ds_bpermute_b32 v129, v126, v128
	v_mov_b32_e32 v72, v32
	v_mov_b32_e32 v73, v48
	v_lshlrev_b32_e32 v142, 3, v64
	v_add_u32_e32 v130, s76, v80
	s_waitcnt lgkmcnt(0)
	v_add_f32_e32 v128, v128, v129
	v_fmamk_f32 v128, v128, 0x3c800000, v119
	v_rsq_f32_e32 v128, v128
	s_cmp_lt_i32 s74, 64
	s_waitcnt vmcnt(0)
	v_pk_mul_f32 v[128:129], v[70:71], v[128:129] op_sel_hi:[1,0]
	s_nop 0
	v_pk_mul_f32 v[72:73], v[72:73], v[128:129]
	v_lshl_or_b32 v128, v130, 8, v142
	s_cbranch_scc1 .LBB0_579
	global_load_dwordx2 v[130:131], v128, s[8:9]
	s_waitcnt vmcnt(0)
	v_pk_mul_f32 v[134:135], v[72:73], v[130:131] op_sel_hi:[0,1]
	v_pk_mul_f32 v[132:133], v[72:73], v[130:131] op_sel:[1,1] op_sel_hi:[1,0]
	v_pk_fma_f32 v[72:73], v[72:73], v[130:131], v[134:135] op_sel:[1,1,0] op_sel_hi:[1,0,1] neg_lo:[0,0,1] neg_hi:[0,0,1]
	s_nop 0
	v_add_f32_e32 v72, v132, v134
.LBB0_579:
	v_mov_b32_e32 v130, v49
	v_mov_b32_e32 v131, v33
	v_pk_mul_f32 v[130:131], v[130:131], v[130:131]
	s_mul_i32 s74, s72, 0x180
	v_add_f32_e32 v129, v130, v131
	s_nop 1
	v_mov_b32_dpp v130, v129 quad_perm:[1,0,3,2] row_mask:0xf bank_mask:0xf
	v_add_u32_e32 v131, s73, v80
	v_cndmask_b32_e64 v133, 0, 1, s[68:69]
	s_add_i32 s75, s74, 0xfffff400
	v_cvt_pk_bf16_f32 v135, v73, s0
	s_waitcnt lgkmcnt(0)
	v_add_f32_e32 v129, v129, v130
	s_nop 1
	v_mov_b32_dpp v130, v129 quad_perm:[2,3,0,1] row_mask:0xf bank_mask:0xf
	v_cvt_pk_bf16_f32 v136, v72, s0
	v_cmp_ne_u32_e64 s[0:1], 1, v133
	v_mov_b32_e32 v72, v33
	v_mov_b32_e32 v73, v49
	s_waitcnt lgkmcnt(0)
	v_add_f32_e32 v130, v129, v130
	s_nop 1
	v_mov_b32_dpp v132, v130 row_half_mirror row_mask:0xf bank_mask:0xf
	v_mul_lo_u32 v129, v131, s70
	v_add_u32_e32 v133, s75, v129
	v_add_u32_e32 v137, s76, v83
	s_andn2_b64 vcc, exec, s[68:69]
	s_waitcnt lgkmcnt(0)
	v_add_f32_e32 v131, v130, v132
	s_nop 1
	v_mov_b32_dpp v132, v131 row_mirror row_mask:0xf bank_mask:0xf
	v_add_u32_e32 v130, v133, v81
	s_waitcnt lgkmcnt(0)
	v_add_f32_e32 v134, v131, v132
	ds_bpermute_b32 v138, v126, v134
	v_add_u32_e32 v132, v133, v82
	v_ashrrev_i32_e32 v131, 31, v130
	v_ashrrev_i32_e32 v133, 31, v132
	v_lshl_add_u64 v[130:131], v[130:131], 1, s[6:7]
	s_waitcnt lgkmcnt(0)
	v_add_f32_e32 v134, v134, v138
	v_fmamk_f32 v134, v134, 0x3c800000, v119
	v_rsq_f32_e32 v134, v134
	v_lshl_add_u64 v[132:133], v[132:133], 1, s[6:7]
	global_store_short v[130:131], v135, off sc1
	global_store_short v[132:133], v136, off sc1
	v_pk_mul_f32 v[130:131], v[70:71], v[134:135] op_sel_hi:[1,0]
	s_nop 0
	v_pk_mul_f32 v[72:73], v[72:73], v[130:131]
	v_lshl_or_b32 v130, v137, 8, v142
	s_cbranch_vccnz .LBB0_581
	global_load_dwordx2 v[132:133], v130, s[8:9]
	s_waitcnt vmcnt(0)
	v_pk_mul_f32 v[136:137], v[72:73], v[132:133] op_sel_hi:[0,1]
	v_pk_mul_f32 v[134:135], v[72:73], v[132:133] op_sel:[1,1] op_sel_hi:[1,0]
	v_pk_fma_f32 v[72:73], v[72:73], v[132:133], v[136:137] op_sel:[1,1,0] op_sel_hi:[1,0,1] neg_lo:[0,0,1] neg_hi:[0,0,1]
	s_nop 0
	v_add_f32_e32 v72, v134, v136
.LBB0_581:
	v_mov_b32_e32 v132, v50
	v_mov_b32_e32 v133, v34
	v_pk_mul_f32 v[132:133], v[132:133], v[132:133]
	v_cvt_pk_bf16_f32 v138, v73, s0
	v_add_f32_e32 v131, v132, v133
	s_nop 1
	v_mov_b32_dpp v132, v131 quad_perm:[1,0,3,2] row_mask:0xf bank_mask:0xf
	v_add_u32_e32 v133, s73, v83
	v_mul_lo_u32 v133, v133, s70
	v_add_u32_e32 v135, s75, v133
	v_add_u32_e32 v134, v135, v81
	s_waitcnt lgkmcnt(0)
	v_add_f32_e32 v131, v131, v132
	s_nop 1
	v_mov_b32_dpp v132, v131 quad_perm:[2,3,0,1] row_mask:0xf bank_mask:0xf
	v_add_u32_e32 v136, v135, v82
	v_ashrrev_i32_e32 v135, 31, v134
	v_ashrrev_i32_e32 v137, 31, v136
	v_lshl_add_u64 v[134:135], v[134:135], 1, s[6:7]
	s_waitcnt lgkmcnt(0)
	v_add_f32_e32 v131, v131, v132
	s_nop 1
	v_mov_b32_dpp v132, v131 row_half_mirror row_mask:0xf bank_mask:0xf
	v_cvt_pk_bf16_f32 v139, v72, s0
	v_mov_b32_e32 v72, v34
	v_mov_b32_e32 v73, v50
	v_add_u32_e32 v140, s76, v84
	s_waitcnt lgkmcnt(0)
	v_add_f32_e32 v131, v131, v132
	s_nop 1
	v_mov_b32_dpp v132, v131 row_mirror row_mask:0xf bank_mask:0xf
	v_lshl_add_u64 v[136:137], v[136:137], 1, s[6:7]
	global_store_short v[134:135], v138, off sc1
	global_store_short v[136:137], v139, off sc1
	s_and_b64 vcc, exec, s[0:1]
	s_waitcnt lgkmcnt(0)
	v_add_f32_e32 v131, v131, v132
	ds_bpermute_b32 v132, v126, v131
	s_waitcnt lgkmcnt(0)
	v_add_f32_e32 v131, v131, v132
	v_fmamk_f32 v131, v131, 0x3c800000, v119
	v_rsq_f32_e32 v132, v131
	v_lshl_or_b32 v131, v140, 8, v142
	v_pk_mul_f32 v[134:135], v[70:71], v[132:133] op_sel_hi:[1,0]
	s_nop 0
	v_pk_mul_f32 v[72:73], v[72:73], v[134:135]
	s_cbranch_vccnz .LBB0_583
	global_load_dwordx2 v[134:135], v131, s[8:9]
	s_waitcnt vmcnt(0)
	v_pk_mul_f32 v[138:139], v[72:73], v[134:135] op_sel_hi:[0,1]
	v_pk_mul_f32 v[136:137], v[72:73], v[134:135] op_sel:[1,1] op_sel_hi:[1,0]
	v_pk_fma_f32 v[72:73], v[72:73], v[134:135], v[138:139] op_sel:[1,1,0] op_sel_hi:[1,0,1] neg_lo:[0,0,1] neg_hi:[0,0,1]
	s_nop 0
	v_add_f32_e32 v72, v136, v138
.LBB0_583:
	v_mov_b32_e32 v134, v51
	v_mov_b32_e32 v135, v35
	v_pk_mul_f32 v[134:135], v[134:135], v[134:135]
	v_cvt_pk_bf16_f32 v140, v73, s0
	v_add_f32_e32 v132, v134, v135
	s_nop 1
	v_mov_b32_dpp v134, v132 quad_perm:[1,0,3,2] row_mask:0xf bank_mask:0xf
	v_add_u32_e32 v135, s73, v84
	v_mul_lo_u32 v135, v135, s70
	v_add_u32_e32 v137, s75, v135
	v_add_u32_e32 v136, v137, v81
	s_waitcnt lgkmcnt(0)
	v_add_f32_e32 v132, v132, v134
	s_nop 1
	v_mov_b32_dpp v134, v132 quad_perm:[2,3,0,1] row_mask:0xf bank_mask:0xf
	v_add_u32_e32 v138, v137, v82
	v_ashrrev_i32_e32 v137, 31, v136
	v_ashrrev_i32_e32 v139, 31, v138
	v_lshl_add_u64 v[136:137], v[136:137], 1, s[6:7]
	s_waitcnt lgkmcnt(0)
	v_add_f32_e32 v132, v132, v134
	s_nop 1
	v_mov_b32_dpp v134, v132 row_half_mirror row_mask:0xf bank_mask:0xf
	v_cvt_pk_bf16_f32 v141, v72, s0
	v_mov_b32_e32 v72, v35
	v_mov_b32_e32 v73, v51
	v_add_u32_e32 v143, s76, v85
	s_waitcnt lgkmcnt(0)
	v_add_f32_e32 v132, v132, v134
	s_nop 1
	v_mov_b32_dpp v134, v132 row_mirror row_mask:0xf bank_mask:0xf
	v_lshl_add_u64 v[138:139], v[138:139], 1, s[6:7]
	global_store_short v[136:137], v140, off sc1
	global_store_short v[138:139], v141, off sc1
	s_and_b64 vcc, exec, s[0:1]
	s_waitcnt lgkmcnt(0)
	v_add_f32_e32 v132, v132, v134
	ds_bpermute_b32 v134, v126, v132
	s_waitcnt lgkmcnt(0)
	v_add_f32_e32 v132, v132, v134
	v_fmamk_f32 v132, v132, 0x3c800000, v119
	v_rsq_f32_e32 v132, v132
	s_nop 0
	v_pk_mul_f32 v[136:137], v[70:71], v[132:133] op_sel_hi:[1,0]
	s_nop 0
	v_pk_mul_f32 v[72:73], v[72:73], v[136:137]
	v_lshl_or_b32 v132, v143, 8, v142
	s_cbranch_vccnz .LBB0_585
	global_load_dwordx2 v[136:137], v132, s[8:9]
	s_waitcnt vmcnt(0)
	v_pk_mul_f32 v[140:141], v[72:73], v[136:137] op_sel_hi:[0,1]
	v_pk_mul_f32 v[138:139], v[72:73], v[136:137] op_sel:[1,1] op_sel_hi:[1,0]
	v_pk_fma_f32 v[72:73], v[72:73], v[136:137], v[140:141] op_sel:[1,1,0] op_sel_hi:[1,0,1] neg_lo:[0,0,1] neg_hi:[0,0,1]
	s_nop 0
	v_add_f32_e32 v72, v138, v140
.LBB0_585:
	v_mov_b32_e32 v136, v52
	v_mov_b32_e32 v137, v36
	v_pk_mul_f32 v[136:137], v[136:137], v[136:137]
	v_cvt_pk_bf16_f32 v143, v73, s0
	v_add_f32_e32 v134, v136, v137
	s_nop 1
	v_mov_b32_dpp v136, v134 quad_perm:[1,0,3,2] row_mask:0xf bank_mask:0xf
	v_add_u32_e32 v137, s73, v85
	v_mul_lo_u32 v137, v137, s70
	v_add_u32_e32 v139, s75, v137
	v_add_u32_e32 v138, v139, v81
	s_waitcnt lgkmcnt(0)
	v_add_f32_e32 v134, v134, v136
	s_nop 1
	v_mov_b32_dpp v136, v134 quad_perm:[2,3,0,1] row_mask:0xf bank_mask:0xf
	v_add_u32_e32 v140, v139, v82
	v_ashrrev_i32_e32 v139, 31, v138
	v_ashrrev_i32_e32 v141, 31, v140
	v_lshl_add_u64 v[138:139], v[138:139], 1, s[6:7]
	s_waitcnt lgkmcnt(0)
	v_add_f32_e32 v134, v134, v136
	s_nop 1
	v_mov_b32_dpp v136, v134 row_half_mirror row_mask:0xf bank_mask:0xf
	v_cvt_pk_bf16_f32 v144, v72, s0
	v_mov_b32_e32 v72, v36
	v_mov_b32_e32 v73, v52
	v_add_u32_e32 v145, s76, v86
	s_waitcnt lgkmcnt(0)
	v_add_f32_e32 v134, v134, v136
	s_nop 1
	v_mov_b32_dpp v136, v134 row_mirror row_mask:0xf bank_mask:0xf
	v_lshl_add_u64 v[140:141], v[140:141], 1, s[6:7]
	global_store_short v[138:139], v143, off sc1
	global_store_short v[140:141], v144, off sc1
	s_and_b64 vcc, exec, s[0:1]
	s_waitcnt lgkmcnt(0)
	v_add_f32_e32 v134, v134, v136
	ds_bpermute_b32 v136, v126, v134
	s_waitcnt lgkmcnt(0)
	v_add_f32_e32 v134, v134, v136
	v_fmamk_f32 v134, v134, 0x3c800000, v119
	v_rsq_f32_e32 v134, v134
	s_nop 0
	v_pk_mul_f32 v[138:139], v[70:71], v[134:135] op_sel_hi:[1,0]
	s_nop 0
	v_pk_mul_f32 v[72:73], v[72:73], v[138:139]
	v_lshl_or_b32 v134, v145, 8, v142
	s_cbranch_vccnz .LBB0_587
	global_load_dwordx2 v[138:139], v134, s[8:9]
	s_waitcnt vmcnt(0)
	v_pk_mul_f32 v[144:145], v[72:73], v[138:139] op_sel_hi:[0,1]
	v_pk_mul_f32 v[140:141], v[72:73], v[138:139] op_sel:[1,1] op_sel_hi:[1,0]
	v_pk_fma_f32 v[72:73], v[72:73], v[138:139], v[144:145] op_sel:[1,1,0] op_sel_hi:[1,0,1] neg_lo:[0,0,1] neg_hi:[0,0,1]
	s_nop 0
	v_add_f32_e32 v72, v140, v144
.LBB0_587:
	v_mov_b32_e32 v138, v53
	v_mov_b32_e32 v139, v37
	v_pk_mul_f32 v[138:139], v[138:139], v[138:139]
	v_cvt_pk_bf16_f32 v143, v73, s0
	v_add_f32_e32 v136, v138, v139
	s_nop 1
	v_mov_b32_dpp v138, v136 quad_perm:[1,0,3,2] row_mask:0xf bank_mask:0xf
	v_add_u32_e32 v139, s73, v86
	v_mul_lo_u32 v139, v139, s70
	v_add_u32_e32 v141, s75, v139
	v_add_u32_e32 v140, v141, v81
	s_waitcnt lgkmcnt(0)
	v_add_f32_e32 v136, v136, v138
	s_nop 1
	v_mov_b32_dpp v138, v136 quad_perm:[2,3,0,1] row_mask:0xf bank_mask:0xf
	v_add_u32_e32 v144, v141, v82
	v_ashrrev_i32_e32 v141, 31, v140
	v_ashrrev_i32_e32 v145, 31, v144
	v_lshl_add_u64 v[140:141], v[140:141], 1, s[6:7]
	s_waitcnt lgkmcnt(0)
	v_add_f32_e32 v136, v136, v138
	s_nop 1
	v_mov_b32_dpp v138, v136 row_half_mirror row_mask:0xf bank_mask:0xf
	v_cvt_pk_bf16_f32 v146, v72, s0
	v_mov_b32_e32 v72, v37
	v_mov_b32_e32 v73, v53
	v_add_u32_e32 v147, s76, v87
	s_waitcnt lgkmcnt(0)
	v_add_f32_e32 v136, v136, v138
	s_nop 1
	v_mov_b32_dpp v138, v136 row_mirror row_mask:0xf bank_mask:0xf
	v_lshl_add_u64 v[144:145], v[144:145], 1, s[6:7]
	global_store_short v[140:141], v143, off sc1
	global_store_short v[144:145], v146, off sc1
	s_and_b64 vcc, exec, s[0:1]
	s_waitcnt lgkmcnt(0)
	v_add_f32_e32 v136, v136, v138
	ds_bpermute_b32 v138, v126, v136
	s_waitcnt lgkmcnt(0)
	v_add_f32_e32 v136, v136, v138
	v_fmamk_f32 v136, v136, 0x3c800000, v119
	v_rsq_f32_e32 v136, v136
	s_nop 0
	v_pk_mul_f32 v[140:141], v[70:71], v[136:137] op_sel_hi:[1,0]
	s_nop 0
	v_pk_mul_f32 v[72:73], v[72:73], v[140:141]
	v_lshl_or_b32 v136, v147, 8, v142
	s_cbranch_vccnz .LBB0_589
	global_load_dwordx2 v[140:141], v136, s[8:9]
	s_waitcnt vmcnt(0)
	v_pk_mul_f32 v[146:147], v[72:73], v[140:141] op_sel_hi:[0,1]
	v_pk_mul_f32 v[144:145], v[72:73], v[140:141] op_sel:[1,1] op_sel_hi:[1,0]
	v_pk_fma_f32 v[72:73], v[72:73], v[140:141], v[146:147] op_sel:[1,1,0] op_sel_hi:[1,0,1] neg_lo:[0,0,1] neg_hi:[0,0,1]
	s_nop 0
	v_add_f32_e32 v72, v144, v146
.LBB0_589:
	v_mov_b32_e32 v140, v54
	v_mov_b32_e32 v141, v38
	v_pk_mul_f32 v[140:141], v[140:141], v[140:141]
	v_cvt_pk_bf16_f32 v143, v73, s0
	v_add_f32_e32 v138, v140, v141
	s_nop 1
	v_mov_b32_dpp v140, v138 quad_perm:[1,0,3,2] row_mask:0xf bank_mask:0xf
	v_add_u32_e32 v141, s73, v87
	v_mul_lo_u32 v141, v141, s70
	v_add_u32_e32 v145, s75, v141
	v_add_u32_e32 v144, v145, v81
	s_waitcnt lgkmcnt(0)
	v_add_f32_e32 v138, v138, v140
	s_nop 1
	v_mov_b32_dpp v140, v138 quad_perm:[2,3,0,1] row_mask:0xf bank_mask:0xf
	v_add_u32_e32 v146, v145, v82
	v_ashrrev_i32_e32 v145, 31, v144
	v_ashrrev_i32_e32 v147, 31, v146
	v_lshl_add_u64 v[144:145], v[144:145], 1, s[6:7]
	s_waitcnt lgkmcnt(0)
	v_add_f32_e32 v138, v138, v140
	s_nop 1
	v_mov_b32_dpp v140, v138 row_half_mirror row_mask:0xf bank_mask:0xf
	v_cvt_pk_bf16_f32 v148, v72, s0
	v_mov_b32_e32 v72, v38
	v_mov_b32_e32 v73, v54
	v_add_u32_e32 v149, s76, v88
	s_waitcnt lgkmcnt(0)
	v_add_f32_e32 v138, v138, v140
	s_nop 1
	v_mov_b32_dpp v140, v138 row_mirror row_mask:0xf bank_mask:0xf
	v_lshl_add_u64 v[146:147], v[146:147], 1, s[6:7]
	global_store_short v[144:145], v143, off sc1
	global_store_short v[146:147], v148, off sc1
	s_and_b64 vcc, exec, s[0:1]
	s_waitcnt lgkmcnt(0)
	v_add_f32_e32 v138, v138, v140
	ds_bpermute_b32 v140, v126, v138
	s_waitcnt lgkmcnt(0)
	v_add_f32_e32 v138, v138, v140
	v_fmamk_f32 v138, v138, 0x3c800000, v119
	v_rsq_f32_e32 v138, v138
	s_nop 0
	v_pk_mul_f32 v[144:145], v[70:71], v[138:139] op_sel_hi:[1,0]
	s_nop 0
	v_pk_mul_f32 v[72:73], v[72:73], v[144:145]
	v_lshl_or_b32 v138, v149, 8, v142
	s_cbranch_vccnz .LBB0_591
	global_load_dwordx2 v[144:145], v138, s[8:9]
	s_waitcnt vmcnt(0)
	v_pk_mul_f32 v[148:149], v[72:73], v[144:145] op_sel_hi:[0,1]
	v_pk_mul_f32 v[146:147], v[72:73], v[144:145] op_sel:[1,1] op_sel_hi:[1,0]
	v_pk_fma_f32 v[72:73], v[72:73], v[144:145], v[148:149] op_sel:[1,1,0] op_sel_hi:[1,0,1] neg_lo:[0,0,1] neg_hi:[0,0,1]
	s_nop 0
	v_add_f32_e32 v72, v146, v148
.LBB0_591:
	v_mov_b32_e32 v144, v55
	v_mov_b32_e32 v145, v39
	v_pk_mul_f32 v[144:145], v[144:145], v[144:145]
	v_cvt_pk_bf16_f32 v150, v72, s0
	v_add_f32_e32 v140, v144, v145
	s_nop 1
	v_mov_b32_dpp v143, v140 quad_perm:[1,0,3,2] row_mask:0xf bank_mask:0xf
	v_add_u32_e32 v144, s73, v88
	v_mul_lo_u32 v144, v144, s70
	v_add_u32_e32 v147, s75, v144
	v_add_u32_e32 v146, v147, v81
	s_waitcnt lgkmcnt(0)
	v_add_f32_e32 v140, v140, v143
	s_nop 1
	v_mov_b32_dpp v143, v140 quad_perm:[2,3,0,1] row_mask:0xf bank_mask:0xf
	v_add_u32_e32 v148, v147, v82
	v_ashrrev_i32_e32 v147, 31, v146
	v_cvt_pk_bf16_f32 v145, v73, s0
	v_ashrrev_i32_e32 v149, 31, v148
	s_waitcnt lgkmcnt(0)
	v_add_f32_e32 v140, v140, v143
	s_nop 1
	v_mov_b32_dpp v143, v140 row_half_mirror row_mask:0xf bank_mask:0xf
	v_lshl_add_u64 v[146:147], v[146:147], 1, s[6:7]
	v_mov_b32_e32 v72, v39
	v_mov_b32_e32 v73, v55
	v_add_u32_e32 v151, s76, v89
	s_waitcnt lgkmcnt(0)
	v_add_f32_e32 v140, v140, v143
	s_nop 1
	v_mov_b32_dpp v143, v140 row_mirror row_mask:0xf bank_mask:0xf
	v_lshl_add_u64 v[148:149], v[148:149], 1, s[6:7]
	global_store_short v[146:147], v145, off sc1
	global_store_short v[148:149], v150, off sc1
	s_and_b64 vcc, exec, s[0:1]
	s_waitcnt lgkmcnt(0)
	v_add_f32_e32 v140, v140, v143
	ds_bpermute_b32 v143, v126, v140
	s_waitcnt lgkmcnt(0)
	v_add_f32_e32 v140, v140, v143
	v_fmamk_f32 v140, v140, 0x3c800000, v119
	v_rsq_f32_e32 v140, v140
	s_nop 0
	v_pk_mul_f32 v[146:147], v[70:71], v[140:141] op_sel_hi:[1,0]
	s_nop 0
	v_pk_mul_f32 v[72:73], v[72:73], v[146:147]
	v_lshl_or_b32 v140, v151, 8, v142
	s_cbranch_vccnz .LBB0_593
	global_load_dwordx2 v[146:147], v140, s[8:9]
	s_waitcnt vmcnt(0)
	v_pk_mul_f32 v[150:151], v[72:73], v[146:147] op_sel_hi:[0,1]
	v_pk_mul_f32 v[148:149], v[72:73], v[146:147] op_sel:[1,1] op_sel_hi:[1,0]
	v_pk_fma_f32 v[72:73], v[72:73], v[146:147], v[150:151] op_sel:[1,1,0] op_sel_hi:[1,0,1] neg_lo:[0,0,1] neg_hi:[0,0,1]
	s_nop 0
	v_add_f32_e32 v72, v148, v150
.LBB0_593:
	v_mov_b32_e32 v146, v56
	v_mov_b32_e32 v147, v40
	v_pk_mul_f32 v[146:147], v[146:147], v[146:147]
	v_cvt_pk_bf16_f32 v153, v72, s0
	v_add_f32_e32 v143, v146, v147
	s_nop 1
	v_mov_b32_dpp v145, v143 quad_perm:[1,0,3,2] row_mask:0xf bank_mask:0xf
	v_add_u32_e32 v146, s73, v89
	v_mul_lo_u32 v146, v146, s70
	v_add_u32_e32 v149, s75, v146
	v_add_u32_e32 v148, v149, v81
	s_waitcnt lgkmcnt(0)
	v_add_f32_e32 v143, v143, v145
	s_nop 1
	v_mov_b32_dpp v145, v143 quad_perm:[2,3,0,1] row_mask:0xf bank_mask:0xf
	v_add_u32_e32 v150, v149, v82
	v_ashrrev_i32_e32 v149, 31, v148
	v_cvt_pk_bf16_f32 v147, v73, s0
	v_ashrrev_i32_e32 v151, 31, v150
	s_waitcnt lgkmcnt(0)
	v_add_f32_e32 v143, v143, v145
	s_nop 1
	v_mov_b32_dpp v145, v143 row_half_mirror row_mask:0xf bank_mask:0xf
	v_lshl_add_u64 v[148:149], v[148:149], 1, s[6:7]
	v_mov_b32_e32 v72, v40
	v_mov_b32_e32 v73, v56
	v_add_u32_e32 v154, s76, v90
	s_waitcnt lgkmcnt(0)
	v_add_f32_e32 v143, v143, v145
	s_nop 1
	v_mov_b32_dpp v145, v143 row_mirror row_mask:0xf bank_mask:0xf
	v_lshl_add_u64 v[150:151], v[150:151], 1, s[6:7]
	global_store_short v[148:149], v147, off sc1
	global_store_short v[150:151], v153, off sc1
	s_and_b64 vcc, exec, s[0:1]
	s_waitcnt lgkmcnt(0)
	v_add_f32_e32 v143, v143, v145
	ds_bpermute_b32 v145, v126, v143
	s_waitcnt lgkmcnt(0)
	v_add_f32_e32 v143, v143, v145
	v_fmamk_f32 v143, v143, 0x3c800000, v119
	v_rsq_f32_e32 v152, v143
	v_lshl_or_b32 v143, v154, 8, v142
	v_pk_mul_f32 v[148:149], v[70:71], v[152:153] op_sel_hi:[1,0]
	s_nop 0
	v_pk_mul_f32 v[72:73], v[72:73], v[148:149]
	s_cbranch_vccnz .LBB0_595
	global_load_dwordx2 v[148:149], v143, s[8:9]
	s_waitcnt vmcnt(0)
	v_pk_mul_f32 v[152:153], v[72:73], v[148:149] op_sel_hi:[0,1]
	v_pk_mul_f32 v[150:151], v[72:73], v[148:149] op_sel:[1,1] op_sel_hi:[1,0]
	v_pk_fma_f32 v[72:73], v[72:73], v[148:149], v[152:153] op_sel:[1,1,0] op_sel_hi:[1,0,1] neg_lo:[0,0,1] neg_hi:[0,0,1]
	s_nop 0
	v_add_f32_e32 v72, v150, v152
.LBB0_595:
	v_mov_b32_e32 v148, v57
	v_mov_b32_e32 v149, v41
	v_pk_mul_f32 v[148:149], v[148:149], v[148:149]
	v_cvt_pk_bf16_f32 v155, v72, s0
	v_add_f32_e32 v145, v148, v149
	s_nop 1
	v_mov_b32_dpp v147, v145 quad_perm:[1,0,3,2] row_mask:0xf bank_mask:0xf
	v_add_u32_e32 v148, s73, v90
	v_mul_lo_u32 v148, v148, s70
	v_add_u32_e32 v151, s75, v148
	v_add_u32_e32 v150, v151, v81
	s_waitcnt lgkmcnt(0)
	v_add_f32_e32 v145, v145, v147
	s_nop 1
	v_mov_b32_dpp v147, v145 quad_perm:[2,3,0,1] row_mask:0xf bank_mask:0xf
	v_add_u32_e32 v152, v151, v82
	v_ashrrev_i32_e32 v151, 31, v150
	v_cvt_pk_bf16_f32 v149, v73, s0
	v_ashrrev_i32_e32 v153, 31, v152
	s_waitcnt lgkmcnt(0)
	v_add_f32_e32 v145, v145, v147
	s_nop 1
	v_mov_b32_dpp v147, v145 row_half_mirror row_mask:0xf bank_mask:0xf
	v_lshl_add_u64 v[150:151], v[150:151], 1, s[6:7]
	v_mov_b32_e32 v72, v41
	v_mov_b32_e32 v73, v57
	v_add_u32_e32 v156, s76, v91
	s_waitcnt lgkmcnt(0)
	v_add_f32_e32 v145, v145, v147
	s_nop 1
	v_mov_b32_dpp v147, v145 row_mirror row_mask:0xf bank_mask:0xf
	v_lshl_add_u64 v[152:153], v[152:153], 1, s[6:7]
	global_store_short v[150:151], v149, off sc1
	global_store_short v[152:153], v155, off sc1
	s_and_b64 vcc, exec, s[0:1]
	s_waitcnt lgkmcnt(0)
	v_add_f32_e32 v145, v145, v147
	ds_bpermute_b32 v147, v126, v145
	s_waitcnt lgkmcnt(0)
	v_add_f32_e32 v145, v145, v147
	v_fmamk_f32 v145, v145, 0x3c800000, v119
	v_rsq_f32_e32 v154, v145
	v_lshl_or_b32 v145, v156, 8, v142
	v_pk_mul_f32 v[150:151], v[70:71], v[154:155] op_sel_hi:[1,0]
	s_nop 0
	v_pk_mul_f32 v[72:73], v[72:73], v[150:151]
	s_cbranch_vccnz .LBB0_597
	global_load_dwordx2 v[150:151], v145, s[8:9]
	s_waitcnt vmcnt(0)
	v_pk_mul_f32 v[154:155], v[72:73], v[150:151] op_sel_hi:[0,1]
	v_pk_mul_f32 v[152:153], v[72:73], v[150:151] op_sel:[1,1] op_sel_hi:[1,0]
	v_pk_fma_f32 v[72:73], v[72:73], v[150:151], v[154:155] op_sel:[1,1,0] op_sel_hi:[1,0,1] neg_lo:[0,0,1] neg_hi:[0,0,1]
	s_nop 0
	v_add_f32_e32 v72, v152, v154
.LBB0_597:
	v_mov_b32_e32 v150, v58
	v_mov_b32_e32 v151, v42
	v_pk_mul_f32 v[150:151], v[150:151], v[150:151]
	v_cvt_pk_bf16_f32 v157, v72, s0
	v_add_f32_e32 v147, v150, v151
	s_nop 1
	v_mov_b32_dpp v149, v147 quad_perm:[1,0,3,2] row_mask:0xf bank_mask:0xf
	v_add_u32_e32 v150, s73, v91
	v_mul_lo_u32 v150, v150, s70
	v_add_u32_e32 v153, s75, v150
	v_add_u32_e32 v152, v153, v81
	s_waitcnt lgkmcnt(0)
	v_add_f32_e32 v147, v147, v149
	s_nop 1
	v_mov_b32_dpp v149, v147 quad_perm:[2,3,0,1] row_mask:0xf bank_mask:0xf
	v_add_u32_e32 v154, v153, v82
	v_ashrrev_i32_e32 v153, 31, v152
	v_cvt_pk_bf16_f32 v151, v73, s0
	v_ashrrev_i32_e32 v155, 31, v154
	s_waitcnt lgkmcnt(0)
	v_add_f32_e32 v147, v147, v149
	s_nop 1
	v_mov_b32_dpp v149, v147 row_half_mirror row_mask:0xf bank_mask:0xf
	v_lshl_add_u64 v[152:153], v[152:153], 1, s[6:7]
	v_mov_b32_e32 v72, v42
	v_mov_b32_e32 v73, v58
	v_add_u32_e32 v158, s76, v92
	s_waitcnt lgkmcnt(0)
	v_add_f32_e32 v147, v147, v149
	s_nop 1
	v_mov_b32_dpp v149, v147 row_mirror row_mask:0xf bank_mask:0xf
	v_lshl_add_u64 v[154:155], v[154:155], 1, s[6:7]
	global_store_short v[152:153], v151, off sc1
	global_store_short v[154:155], v157, off sc1
	s_and_b64 vcc, exec, s[0:1]
	s_waitcnt lgkmcnt(0)
	v_add_f32_e32 v147, v147, v149
	ds_bpermute_b32 v149, v126, v147
	s_waitcnt lgkmcnt(0)
	v_add_f32_e32 v147, v147, v149
	v_fmamk_f32 v147, v147, 0x3c800000, v119
	v_rsq_f32_e32 v156, v147
	v_lshl_or_b32 v147, v158, 8, v142
	v_pk_mul_f32 v[152:153], v[70:71], v[156:157] op_sel_hi:[1,0]
	s_nop 0
	v_pk_mul_f32 v[72:73], v[72:73], v[152:153]
	s_cbranch_vccnz .LBB0_599
	global_load_dwordx2 v[152:153], v147, s[8:9]
	s_waitcnt vmcnt(0)
	v_pk_mul_f32 v[156:157], v[72:73], v[152:153] op_sel_hi:[0,1]
	v_pk_mul_f32 v[154:155], v[72:73], v[152:153] op_sel:[1,1] op_sel_hi:[1,0]
	v_pk_fma_f32 v[72:73], v[72:73], v[152:153], v[156:157] op_sel:[1,1,0] op_sel_hi:[1,0,1] neg_lo:[0,0,1] neg_hi:[0,0,1]
	s_nop 0
	v_add_f32_e32 v72, v154, v156
.LBB0_599:
	v_mov_b32_e32 v152, v59
	v_mov_b32_e32 v153, v43
	v_pk_mul_f32 v[152:153], v[152:153], v[152:153]
	v_cvt_pk_bf16_f32 v159, v72, s0
	v_add_f32_e32 v149, v152, v153
	s_nop 1
	v_mov_b32_dpp v151, v149 quad_perm:[1,0,3,2] row_mask:0xf bank_mask:0xf
	v_add_u32_e32 v152, s73, v92
	v_mul_lo_u32 v152, v152, s70
	v_add_u32_e32 v155, s75, v152
	v_add_u32_e32 v154, v155, v81
	s_waitcnt lgkmcnt(0)
	v_add_f32_e32 v149, v149, v151
	s_nop 1
	v_mov_b32_dpp v151, v149 quad_perm:[2,3,0,1] row_mask:0xf bank_mask:0xf
	v_add_u32_e32 v156, v155, v82
	v_ashrrev_i32_e32 v155, 31, v154
	v_cvt_pk_bf16_f32 v153, v73, s0
	v_ashrrev_i32_e32 v157, 31, v156
	s_waitcnt lgkmcnt(0)
	v_add_f32_e32 v149, v149, v151
	s_nop 1
	v_mov_b32_dpp v151, v149 row_half_mirror row_mask:0xf bank_mask:0xf
	v_lshl_add_u64 v[154:155], v[154:155], 1, s[6:7]
	v_mov_b32_e32 v72, v43
	v_mov_b32_e32 v73, v59
	v_add_u32_e32 v160, s76, v93
	s_waitcnt lgkmcnt(0)
	v_add_f32_e32 v149, v149, v151
	s_nop 1
	v_mov_b32_dpp v151, v149 row_mirror row_mask:0xf bank_mask:0xf
	v_lshl_add_u64 v[156:157], v[156:157], 1, s[6:7]
	global_store_short v[154:155], v153, off sc1
	global_store_short v[156:157], v159, off sc1
	s_and_b64 vcc, exec, s[0:1]
	s_waitcnt lgkmcnt(0)
	v_add_f32_e32 v149, v149, v151
	ds_bpermute_b32 v151, v126, v149
	s_waitcnt lgkmcnt(0)
	v_add_f32_e32 v149, v149, v151
	v_fmamk_f32 v149, v149, 0x3c800000, v119
	v_rsq_f32_e32 v158, v149
	v_lshl_or_b32 v149, v160, 8, v142
	v_pk_mul_f32 v[154:155], v[70:71], v[158:159] op_sel_hi:[1,0]
	s_nop 0
	v_pk_mul_f32 v[72:73], v[72:73], v[154:155]
	s_cbranch_vccnz .LBB0_601
	global_load_dwordx2 v[154:155], v149, s[8:9]
	s_waitcnt vmcnt(0)
	v_pk_mul_f32 v[158:159], v[72:73], v[154:155] op_sel_hi:[0,1]
	v_pk_mul_f32 v[156:157], v[72:73], v[154:155] op_sel:[1,1] op_sel_hi:[1,0]
	v_pk_fma_f32 v[72:73], v[72:73], v[154:155], v[158:159] op_sel:[1,1,0] op_sel_hi:[1,0,1] neg_lo:[0,0,1] neg_hi:[0,0,1]
	s_nop 0
	v_add_f32_e32 v72, v156, v158
.LBB0_601:
	v_mov_b32_e32 v154, v60
	v_mov_b32_e32 v155, v44
	v_pk_mul_f32 v[154:155], v[154:155], v[154:155]
	v_cvt_pk_bf16_f32 v161, v72, s0
	v_add_f32_e32 v151, v154, v155
	s_nop 1
	v_mov_b32_dpp v153, v151 quad_perm:[1,0,3,2] row_mask:0xf bank_mask:0xf
	v_add_u32_e32 v154, s73, v93
	v_mul_lo_u32 v154, v154, s70
	v_add_u32_e32 v157, s75, v154
	v_add_u32_e32 v156, v157, v81
	s_waitcnt lgkmcnt(0)
	v_add_f32_e32 v151, v151, v153
	s_nop 1
	v_mov_b32_dpp v153, v151 quad_perm:[2,3,0,1] row_mask:0xf bank_mask:0xf
	v_add_u32_e32 v158, v157, v82
	v_ashrrev_i32_e32 v157, 31, v156
	v_cvt_pk_bf16_f32 v155, v73, s0
	v_ashrrev_i32_e32 v159, 31, v158
	s_waitcnt lgkmcnt(0)
	v_add_f32_e32 v151, v151, v153
	s_nop 1
	v_mov_b32_dpp v153, v151 row_half_mirror row_mask:0xf bank_mask:0xf
	v_lshl_add_u64 v[156:157], v[156:157], 1, s[6:7]
	v_mov_b32_e32 v72, v44
	v_mov_b32_e32 v73, v60
	v_add_u32_e32 v162, s76, v94
	s_waitcnt lgkmcnt(0)
	v_add_f32_e32 v151, v151, v153
	s_nop 1
	v_mov_b32_dpp v153, v151 row_mirror row_mask:0xf bank_mask:0xf
	v_lshl_add_u64 v[158:159], v[158:159], 1, s[6:7]
	global_store_short v[156:157], v155, off sc1
	global_store_short v[158:159], v161, off sc1
	s_and_b64 vcc, exec, s[0:1]
	s_waitcnt lgkmcnt(0)
	v_add_f32_e32 v151, v151, v153
	ds_bpermute_b32 v153, v126, v151
	s_waitcnt lgkmcnt(0)
	v_add_f32_e32 v151, v151, v153
	v_fmamk_f32 v151, v151, 0x3c800000, v119
	v_rsq_f32_e32 v160, v151
	v_lshl_or_b32 v151, v162, 8, v142
	v_pk_mul_f32 v[156:157], v[70:71], v[160:161] op_sel_hi:[1,0]
	s_nop 0
	v_pk_mul_f32 v[72:73], v[72:73], v[156:157]
	s_cbranch_vccnz .LBB0_603
	global_load_dwordx2 v[156:157], v151, s[8:9]
	s_waitcnt vmcnt(0)
	v_pk_mul_f32 v[160:161], v[72:73], v[156:157] op_sel_hi:[0,1]
	v_pk_mul_f32 v[158:159], v[72:73], v[156:157] op_sel:[1,1] op_sel_hi:[1,0]
	v_pk_fma_f32 v[72:73], v[72:73], v[156:157], v[160:161] op_sel:[1,1,0] op_sel_hi:[1,0,1] neg_lo:[0,0,1] neg_hi:[0,0,1]
	s_nop 0
	v_add_f32_e32 v72, v158, v160
.LBB0_603:
	v_mov_b32_e32 v156, v61
	v_mov_b32_e32 v157, v45
	v_pk_mul_f32 v[156:157], v[156:157], v[156:157]
	v_cvt_pk_bf16_f32 v163, v72, s0
	v_add_f32_e32 v153, v156, v157
	s_nop 1
	v_mov_b32_dpp v155, v153 quad_perm:[1,0,3,2] row_mask:0xf bank_mask:0xf
	v_add_u32_e32 v156, s73, v94
	v_mul_lo_u32 v156, v156, s70
	v_add_u32_e32 v159, s75, v156
	v_add_u32_e32 v158, v159, v81
	s_waitcnt lgkmcnt(0)
	v_add_f32_e32 v153, v153, v155
	s_nop 1
	v_mov_b32_dpp v155, v153 quad_perm:[2,3,0,1] row_mask:0xf bank_mask:0xf
	v_add_u32_e32 v160, v159, v82
	v_ashrrev_i32_e32 v159, 31, v158
	v_cvt_pk_bf16_f32 v157, v73, s0
	v_ashrrev_i32_e32 v161, 31, v160
	s_waitcnt lgkmcnt(0)
	v_add_f32_e32 v153, v153, v155
	s_nop 1
	v_mov_b32_dpp v155, v153 row_half_mirror row_mask:0xf bank_mask:0xf
	v_lshl_add_u64 v[158:159], v[158:159], 1, s[6:7]
	v_mov_b32_e32 v72, v45
	v_mov_b32_e32 v73, v61
	v_add_u32_e32 v164, s76, v95
	s_waitcnt lgkmcnt(0)
	v_add_f32_e32 v153, v153, v155
	s_nop 1
	v_mov_b32_dpp v155, v153 row_mirror row_mask:0xf bank_mask:0xf
	v_lshl_add_u64 v[160:161], v[160:161], 1, s[6:7]
	global_store_short v[158:159], v157, off sc1
	global_store_short v[160:161], v163, off sc1
	s_and_b64 vcc, exec, s[0:1]
	s_waitcnt lgkmcnt(0)
	v_add_f32_e32 v153, v153, v155
	ds_bpermute_b32 v155, v126, v153
	s_waitcnt lgkmcnt(0)
	v_add_f32_e32 v153, v153, v155
	v_fmamk_f32 v153, v153, 0x3c800000, v119
	v_rsq_f32_e32 v162, v153
	v_lshl_or_b32 v153, v164, 8, v142
	v_pk_mul_f32 v[158:159], v[70:71], v[162:163] op_sel_hi:[1,0]
	s_nop 0
	v_pk_mul_f32 v[72:73], v[72:73], v[158:159]
	s_cbranch_vccnz .LBB0_605
	global_load_dwordx2 v[158:159], v153, s[8:9]
	s_waitcnt vmcnt(0)
	v_pk_mul_f32 v[162:163], v[72:73], v[158:159] op_sel_hi:[0,1]
	v_pk_mul_f32 v[160:161], v[72:73], v[158:159] op_sel:[1,1] op_sel_hi:[1,0]
	v_pk_fma_f32 v[72:73], v[72:73], v[158:159], v[162:163] op_sel:[1,1,0] op_sel_hi:[1,0,1] neg_lo:[0,0,1] neg_hi:[0,0,1]
	s_nop 0
	v_add_f32_e32 v72, v160, v162
.LBB0_605:
	v_mov_b32_e32 v158, v62
	v_mov_b32_e32 v159, v46
	v_pk_mul_f32 v[158:159], v[158:159], v[158:159]
	v_cvt_pk_bf16_f32 v163, v73, s0
	v_add_f32_e32 v155, v158, v159
	s_nop 1
	v_mov_b32_dpp v157, v155 quad_perm:[1,0,3,2] row_mask:0xf bank_mask:0xf
	v_add_u32_e32 v158, s73, v95
	v_cvt_pk_bf16_f32 v164, v72, s0
	v_mov_b32_e32 v72, v46
	v_mov_b32_e32 v73, v62
	s_waitcnt lgkmcnt(0)
	v_add_f32_e32 v155, v155, v157
	s_nop 1
	v_mov_b32_dpp v157, v155 quad_perm:[2,3,0,1] row_mask:0xf bank_mask:0xf
	v_add_u32_e32 v165, s76, v96
	s_and_b64 vcc, exec, s[0:1]
	s_waitcnt lgkmcnt(0)
	v_add_f32_e32 v155, v155, v157
	s_nop 1
	v_mov_b32_dpp v157, v155 row_half_mirror row_mask:0xf bank_mask:0xf
	s_waitcnt lgkmcnt(0)
	v_add_f32_e32 v155, v155, v157
	s_nop 1
	v_mov_b32_dpp v159, v155 row_mirror row_mask:0xf bank_mask:0xf
	v_mul_lo_u32 v157, v158, s70
	v_add_u32_e32 v160, s75, v157
	v_add_u32_e32 v158, v160, v81
	v_add_u32_e32 v160, v160, v82
	s_waitcnt lgkmcnt(0)
	v_add_f32_e32 v155, v155, v159
	ds_bpermute_b32 v162, v126, v155
	v_ashrrev_i32_e32 v159, 31, v158
	v_ashrrev_i32_e32 v161, 31, v160
	v_lshl_add_u64 v[158:159], v[158:159], 1, s[6:7]
	v_lshl_add_u64 v[160:161], v[160:161], 1, s[6:7]
	s_waitcnt lgkmcnt(0)
	v_add_f32_e32 v155, v155, v162
	v_fmamk_f32 v155, v155, 0x3c800000, v119
	v_rsq_f32_e32 v162, v155
	global_store_short v[158:159], v163, off sc1
	global_store_short v[160:161], v164, off sc1
	v_lshl_or_b32 v155, v165, 8, v142
	v_pk_mul_f32 v[158:159], v[70:71], v[162:163] op_sel_hi:[1,0]
	s_nop 0
	v_pk_mul_f32 v[72:73], v[72:73], v[158:159]
	s_cbranch_vccnz .LBB0_607
	global_load_dwordx2 v[158:159], v155, s[8:9]
	s_waitcnt vmcnt(0)
	v_pk_mul_f32 v[162:163], v[72:73], v[158:159] op_sel_hi:[0,1]
	v_pk_mul_f32 v[160:161], v[72:73], v[158:159] op_sel:[1,1] op_sel_hi:[1,0]
	v_pk_fma_f32 v[72:73], v[72:73], v[158:159], v[162:163] op_sel:[1,1,0] op_sel_hi:[1,0,1] neg_lo:[0,0,1] neg_hi:[0,0,1]
	s_nop 0
	v_add_f32_e32 v72, v160, v162
.LBB0_607:
	v_mov_b32_e32 v158, v63
	v_mov_b32_e32 v159, v47
	v_pk_mul_f32 v[158:159], v[158:159], v[158:159]
	v_add_u32_e32 v160, s73, v96
	v_add_f32_e32 v158, v158, v159
	s_nop 1
	v_mov_b32_dpp v159, v158 quad_perm:[1,0,3,2] row_mask:0xf bank_mask:0xf
	v_cvt_pk_bf16_f32 v165, v73, s0
	v_cvt_pk_bf16_f32 v166, v72, s0
	v_mov_b32_e32 v72, v47
	v_mov_b32_e32 v73, v63
	s_waitcnt lgkmcnt(0)
	v_add_f32_e32 v158, v158, v159
	s_nop 1
	v_mov_b32_dpp v159, v158 quad_perm:[2,3,0,1] row_mask:0xf bank_mask:0xf
	v_add_u32_e32 v167, s76, v97
	s_and_b64 vcc, exec, s[0:1]
	v_lshl_or_b32 v142, v167, 8, v142
	s_waitcnt lgkmcnt(0)
	v_add_f32_e32 v158, v158, v159
	s_nop 1
	v_mov_b32_dpp v159, v158 row_half_mirror row_mask:0xf bank_mask:0xf
	s_waitcnt lgkmcnt(0)
	v_add_f32_e32 v159, v158, v159
	s_nop 1
	v_mov_b32_dpp v161, v159 row_mirror row_mask:0xf bank_mask:0xf
	v_mul_lo_u32 v158, v160, s70
	v_add_u32_e32 v162, s75, v158
	v_add_u32_e32 v160, v162, v81
	v_add_u32_e32 v162, v162, v82
	s_waitcnt lgkmcnt(0)
	v_add_f32_e32 v159, v159, v161
	ds_bpermute_b32 v164, v126, v159
	v_ashrrev_i32_e32 v161, 31, v160
	v_ashrrev_i32_e32 v163, 31, v162
	v_lshl_add_u64 v[160:161], v[160:161], 1, s[6:7]
	v_lshl_add_u64 v[162:163], v[162:163], 1, s[6:7]
	s_waitcnt lgkmcnt(0)
	v_add_f32_e32 v159, v159, v164
	v_fmamk_f32 v159, v159, 0x3c800000, v119
	v_rsq_f32_e32 v164, v159
	global_store_short v[160:161], v165, off sc1
	global_store_short v[162:163], v166, off sc1
	v_pk_mul_f32 v[160:161], v[70:71], v[164:165] op_sel_hi:[1,0]
	s_nop 0
	v_pk_mul_f32 v[72:73], v[72:73], v[160:161]
	s_cbranch_vccnz .LBB0_609
	global_load_dwordx2 v[160:161], v142, s[8:9]
	s_waitcnt vmcnt(0)
	v_pk_mul_f32 v[164:165], v[72:73], v[160:161] op_sel_hi:[0,1]
	v_pk_mul_f32 v[162:163], v[72:73], v[160:161] op_sel:[1,1] op_sel_hi:[1,0]
	v_pk_fma_f32 v[72:73], v[72:73], v[160:161], v[164:165] op_sel:[1,1,0] op_sel_hi:[1,0,1] neg_lo:[0,0,1] neg_hi:[0,0,1]
	s_nop 0
	v_add_f32_e32 v72, v162, v164
.LBB0_609:
	v_mov_b32_e32 v160, v16
	v_mov_b32_e32 v161, v0
	v_pk_mul_f32 v[160:161], v[160:161], v[160:161]
	v_cvt_pk_bf16_f32 v165, v73, s0
	v_add_f32_e32 v159, v160, v161
	s_nop 1
	v_mov_b32_dpp v160, v159 quad_perm:[1,0,3,2] row_mask:0xf bank_mask:0xf
	v_add_u32_e32 v161, s73, v97
	v_cvt_pk_bf16_f32 v166, v72, s0
	v_mov_b32_e32 v72, v0
	v_mov_b32_e32 v73, v16
	s_waitcnt lgkmcnt(0)
	v_add_f32_e32 v159, v159, v160
	s_nop 1
	v_mov_b32_dpp v160, v159 quad_perm:[2,3,0,1] row_mask:0xf bank_mask:0xf
	s_and_b64 vcc, exec, s[0:1]
	s_waitcnt lgkmcnt(0)
	v_add_f32_e32 v159, v159, v160
	s_nop 1
	v_mov_b32_dpp v160, v159 row_half_mirror row_mask:0xf bank_mask:0xf
	s_waitcnt lgkmcnt(0)
	v_add_f32_e32 v162, v159, v160
	s_nop 1
	v_mov_b32_dpp v163, v162 row_mirror row_mask:0xf bank_mask:0xf
	v_mul_lo_u32 v159, v161, s70
	v_add_u32_e32 v161, s75, v159
	v_add_u32_e32 v160, v161, v81
	s_waitcnt lgkmcnt(0)
	v_add_f32_e32 v164, v162, v163
	ds_bpermute_b32 v167, v126, v164
	v_add_u32_e32 v162, v161, v82
	v_ashrrev_i32_e32 v161, 31, v160
	v_ashrrev_i32_e32 v163, 31, v162
	v_lshl_add_u64 v[160:161], v[160:161], 1, s[6:7]
	s_waitcnt lgkmcnt(0)
	v_add_f32_e32 v164, v164, v167
	v_fmamk_f32 v164, v164, 0x3c800000, v119
	v_rsq_f32_e32 v164, v164
	v_lshl_add_u64 v[162:163], v[162:163], 1, s[6:7]
	global_store_short v[160:161], v165, off sc1
	global_store_short v[162:163], v166, off sc1
	v_pk_mul_f32 v[160:161], v[70:71], v[164:165] op_sel_hi:[1,0]
	s_nop 0
	v_pk_mul_f32 v[72:73], v[72:73], v[160:161]
	s_cbranch_vccnz .LBB0_611
	global_load_dwordx2 v[160:161], v128, s[8:9]
	s_waitcnt vmcnt(0)
	v_pk_mul_f32 v[164:165], v[72:73], v[160:161] op_sel_hi:[0,1]
	v_pk_mul_f32 v[162:163], v[72:73], v[160:161] op_sel:[1,1] op_sel_hi:[1,0]
	v_pk_fma_f32 v[72:73], v[72:73], v[160:161], v[164:165] op_sel:[1,1,0] op_sel_hi:[1,0,1] neg_lo:[0,0,1] neg_hi:[0,0,1]
	s_nop 0
	v_add_f32_e32 v72, v162, v164
.LBB0_611:
	v_mov_b32_e32 v160, v17
	v_mov_b32_e32 v161, v1
	v_pk_mul_f32 v[160:161], v[160:161], v[160:161]
	s_addk_i32 s74, 0xf4c0
	v_add_f32_e32 v128, v160, v161
	s_nop 1
	v_mov_b32_dpp v160, v128 quad_perm:[1,0,3,2] row_mask:0xf bank_mask:0xf
	v_add_u32_e32 v129, s74, v129
	v_cvt_pk_bf16_f32 v163, v73, s0
	v_cvt_pk_bf16_f32 v164, v72, s0
	v_mov_b32_e32 v72, v1
	s_waitcnt lgkmcnt(0)
	v_add_f32_e32 v128, v128, v160
	s_nop 1
	v_mov_b32_dpp v160, v128 quad_perm:[2,3,0,1] row_mask:0xf bank_mask:0xf
	v_mov_b32_e32 v73, v17
	s_and_b64 vcc, exec, s[0:1]
	s_waitcnt lgkmcnt(0)
	v_add_f32_e32 v128, v128, v160
	s_nop 1
	v_mov_b32_dpp v160, v128 row_half_mirror row_mask:0xf bank_mask:0xf
	s_waitcnt lgkmcnt(0)
	v_add_f32_e32 v160, v128, v160
	s_nop 1
	v_mov_b32_dpp v161, v160 row_mirror row_mask:0xf bank_mask:0xf
	v_add_u32_e32 v128, v129, v81
	s_waitcnt lgkmcnt(0)
	v_add_f32_e32 v162, v160, v161
	ds_bpermute_b32 v165, v126, v162
	v_add_u32_e32 v160, v129, v82
	v_ashrrev_i32_e32 v129, 31, v128
	v_ashrrev_i32_e32 v161, 31, v160
	v_lshl_add_u64 v[128:129], v[128:129], 1, s[6:7]
	s_waitcnt lgkmcnt(0)
	v_add_f32_e32 v162, v162, v165
	v_fmamk_f32 v162, v162, 0x3c800000, v119
	v_rsq_f32_e32 v162, v162
	v_lshl_add_u64 v[160:161], v[160:161], 1, s[6:7]
	global_store_short v[128:129], v163, off sc1
	global_store_short v[160:161], v164, off sc1
	v_pk_mul_f32 v[128:129], v[70:71], v[162:163] op_sel_hi:[1,0]
	s_nop 0
	v_pk_mul_f32 v[72:73], v[72:73], v[128:129]
	s_cbranch_vccnz .LBB0_613
	global_load_dwordx2 v[128:129], v130, s[8:9]
	s_waitcnt vmcnt(0)
	v_pk_mul_f32 v[162:163], v[72:73], v[128:129] op_sel_hi:[0,1]
	v_pk_mul_f32 v[160:161], v[72:73], v[128:129] op_sel:[1,1] op_sel_hi:[1,0]
	v_pk_fma_f32 v[72:73], v[72:73], v[128:129], v[162:163] op_sel:[1,1,0] op_sel_hi:[1,0,1] neg_lo:[0,0,1] neg_hi:[0,0,1]
	s_nop 0
	v_add_f32_e32 v72, v160, v162
.LBB0_613:
	v_mov_b32_e32 v128, v18
	v_mov_b32_e32 v129, v2
	v_pk_mul_f32 v[128:129], v[128:129], v[128:129]
	v_add_u32_e32 v130, s74, v133
	v_add_f32_e32 v128, v128, v129
	s_nop 1
	v_mov_b32_dpp v129, v128 quad_perm:[1,0,3,2] row_mask:0xf bank_mask:0xf
	v_add_u32_e32 v160, v130, v82
	v_cvt_pk_bf16_f32 v162, v73, s0
	v_ashrrev_i32_e32 v161, 31, v160
	v_cvt_pk_bf16_f32 v163, v72, s0
	s_waitcnt lgkmcnt(0)
	v_add_f32_e32 v128, v128, v129
	s_nop 1
	v_mov_b32_dpp v129, v128 quad_perm:[2,3,0,1] row_mask:0xf bank_mask:0xf
	v_mov_b32_e32 v72, v2
	v_mov_b32_e32 v73, v18
	v_lshl_add_u64 v[160:161], v[160:161], 1, s[6:7]
	s_and_b64 vcc, exec, s[0:1]
	s_waitcnt lgkmcnt(0)
	v_add_f32_e32 v128, v128, v129
	s_nop 1
	v_mov_b32_dpp v129, v128 row_half_mirror row_mask:0xf bank_mask:0xf
	s_waitcnt lgkmcnt(0)
	v_add_f32_e32 v129, v128, v129
	s_nop 1
	v_mov_b32_dpp v133, v129 row_mirror row_mask:0xf bank_mask:0xf
	v_add_u32_e32 v128, v130, v81
	s_waitcnt lgkmcnt(0)
	v_add_f32_e32 v133, v129, v133
	ds_bpermute_b32 v164, v126, v133
	v_ashrrev_i32_e32 v129, 31, v128
	v_lshl_add_u64 v[128:129], v[128:129], 1, s[6:7]
	global_store_short v[128:129], v162, off sc1
	global_store_short v[160:161], v163, off sc1
	s_waitcnt lgkmcnt(0)
	v_add_f32_e32 v130, v133, v164
	v_fmamk_f32 v130, v130, 0x3c800000, v119
	v_rsq_f32_e32 v130, v130
	s_nop 0
	v_pk_mul_f32 v[128:129], v[70:71], v[130:131] op_sel_hi:[1,0]
	s_nop 0
	v_pk_mul_f32 v[72:73], v[72:73], v[128:129]
	s_cbranch_vccnz .LBB0_615
	global_load_dwordx2 v[128:129], v131, s[8:9]
	s_waitcnt vmcnt(0)
	v_pk_mul_f32 v[160:161], v[72:73], v[128:129] op_sel_hi:[0,1]
	v_pk_mul_f32 v[130:131], v[72:73], v[128:129] op_sel:[1,1] op_sel_hi:[1,0]
	v_pk_fma_f32 v[72:73], v[72:73], v[128:129], v[160:161] op_sel:[1,1,0] op_sel_hi:[1,0,1] neg_lo:[0,0,1] neg_hi:[0,0,1]
	s_nop 0
	v_add_f32_e32 v72, v130, v160
.LBB0_615:
	v_mov_b32_e32 v128, v19
	v_mov_b32_e32 v129, v3
	v_pk_mul_f32 v[128:129], v[128:129], v[128:129]
	v_add_u32_e32 v130, s74, v135
	v_add_f32_e32 v128, v128, v129
	s_nop 1
	v_mov_b32_dpp v129, v128 quad_perm:[1,0,3,2] row_mask:0xf bank_mask:0xf
	v_cvt_pk_bf16_f32 v133, v73, s0
	v_cvt_pk_bf16_f32 v135, v72, s0
	v_mov_b32_e32 v72, v3
	v_mov_b32_e32 v73, v19
	s_waitcnt lgkmcnt(0)
	v_add_f32_e32 v128, v128, v129
	s_nop 1
	v_mov_b32_dpp v129, v128 quad_perm:[2,3,0,1] row_mask:0xf bank_mask:0xf
	s_and_b64 vcc, exec, s[0:1]
	s_waitcnt lgkmcnt(0)
	v_add_f32_e32 v128, v128, v129
	s_nop 1
	v_mov_b32_dpp v129, v128 row_half_mirror row_mask:0xf bank_mask:0xf
	s_waitcnt lgkmcnt(0)
	v_add_f32_e32 v129, v128, v129
	s_nop 1
	v_mov_b32_dpp v131, v129 row_mirror row_mask:0xf bank_mask:0xf
	v_add_u32_e32 v128, v130, v81
	v_add_u32_e32 v130, v130, v82
	s_waitcnt lgkmcnt(0)
	v_add_f32_e32 v160, v129, v131
	ds_bpermute_b32 v161, v126, v160
	v_ashrrev_i32_e32 v129, 31, v128
	v_ashrrev_i32_e32 v131, 31, v130
	v_lshl_add_u64 v[128:129], v[128:129], 1, s[6:7]
	v_lshl_add_u64 v[130:131], v[130:131], 1, s[6:7]
	s_waitcnt lgkmcnt(0)
	v_add_f32_e32 v160, v160, v161
	v_fmamk_f32 v160, v160, 0x3c800000, v119
	v_rsq_f32_e32 v160, v160
	global_store_short v[128:129], v133, off sc1
	global_store_short v[130:131], v135, off sc1
	v_pk_mul_f32 v[128:129], v[70:71], v[160:161] op_sel_hi:[1,0]
	s_nop 0
	v_pk_mul_f32 v[72:73], v[72:73], v[128:129]
	s_cbranch_vccnz .LBB0_617
	global_load_dwordx2 v[128:129], v132, s[8:9]
	s_waitcnt vmcnt(0)
	v_pk_mul_f32 v[132:133], v[72:73], v[128:129] op_sel_hi:[0,1]
	v_pk_mul_f32 v[130:131], v[72:73], v[128:129] op_sel:[1,1] op_sel_hi:[1,0]
	v_pk_fma_f32 v[72:73], v[72:73], v[128:129], v[132:133] op_sel:[1,1,0] op_sel_hi:[1,0,1] neg_lo:[0,0,1] neg_hi:[0,0,1]
	s_nop 0
	v_add_f32_e32 v72, v130, v132
.LBB0_617:
	v_mov_b32_e32 v128, v20
	v_mov_b32_e32 v129, v4
	v_pk_mul_f32 v[128:129], v[128:129], v[128:129]
	v_add_u32_e32 v130, s74, v137
	v_add_f32_e32 v128, v128, v129
	s_nop 1
	v_mov_b32_dpp v129, v128 quad_perm:[1,0,3,2] row_mask:0xf bank_mask:0xf
	v_cvt_pk_bf16_f32 v133, v73, s0
	v_cvt_pk_bf16_f32 v135, v72, s0
	v_mov_b32_e32 v72, v4
	v_mov_b32_e32 v73, v20
	s_waitcnt lgkmcnt(0)
	v_add_f32_e32 v128, v128, v129
	s_nop 1
	v_mov_b32_dpp v129, v128 quad_perm:[2,3,0,1] row_mask:0xf bank_mask:0xf
	s_and_b64 vcc, exec, s[0:1]
	s_waitcnt lgkmcnt(0)
	v_add_f32_e32 v128, v128, v129
	s_nop 1
	v_mov_b32_dpp v129, v128 row_half_mirror row_mask:0xf bank_mask:0xf
	s_waitcnt lgkmcnt(0)
	v_add_f32_e32 v129, v128, v129
	s_nop 1
	v_mov_b32_dpp v131, v129 row_mirror row_mask:0xf bank_mask:0xf
	v_add_u32_e32 v128, v130, v81
	v_add_u32_e32 v130, v130, v82
	s_waitcnt lgkmcnt(0)
	v_add_f32_e32 v132, v129, v131
	ds_bpermute_b32 v137, v126, v132
	v_ashrrev_i32_e32 v129, 31, v128
	v_ashrrev_i32_e32 v131, 31, v130
	v_lshl_add_u64 v[128:129], v[128:129], 1, s[6:7]
	v_lshl_add_u64 v[130:131], v[130:131], 1, s[6:7]
	s_waitcnt lgkmcnt(0)
	v_add_f32_e32 v132, v132, v137
	v_fmamk_f32 v132, v132, 0x3c800000, v119
	v_rsq_f32_e32 v132, v132
	global_store_short v[128:129], v133, off sc1
	global_store_short v[130:131], v135, off sc1
	v_pk_mul_f32 v[128:129], v[70:71], v[132:133] op_sel_hi:[1,0]
	s_nop 0
	v_pk_mul_f32 v[72:73], v[72:73], v[128:129]
	s_cbranch_vccnz .LBB0_619
	global_load_dwordx2 v[128:129], v134, s[8:9]
	s_waitcnt vmcnt(0)
	v_pk_mul_f32 v[132:133], v[72:73], v[128:129] op_sel_hi:[0,1]
	v_pk_mul_f32 v[130:131], v[72:73], v[128:129] op_sel:[1,1] op_sel_hi:[1,0]
	v_pk_fma_f32 v[72:73], v[72:73], v[128:129], v[132:133] op_sel:[1,1,0] op_sel_hi:[1,0,1] neg_lo:[0,0,1] neg_hi:[0,0,1]
	s_nop 0
	v_add_f32_e32 v72, v130, v132
.LBB0_619:
	v_mov_b32_e32 v128, v21
	v_mov_b32_e32 v129, v5
	v_pk_mul_f32 v[128:129], v[128:129], v[128:129]
	v_add_u32_e32 v130, s74, v139
	v_add_f32_e32 v128, v128, v129
	s_nop 1
	v_mov_b32_dpp v129, v128 quad_perm:[1,0,3,2] row_mask:0xf bank_mask:0xf
	v_cvt_pk_bf16_f32 v133, v73, s0
	v_cvt_pk_bf16_f32 v134, v72, s0
	v_mov_b32_e32 v72, v5
	v_mov_b32_e32 v73, v21
	s_waitcnt lgkmcnt(0)
	v_add_f32_e32 v128, v128, v129
	s_nop 1
	v_mov_b32_dpp v129, v128 quad_perm:[2,3,0,1] row_mask:0xf bank_mask:0xf
	s_and_b64 vcc, exec, s[0:1]
	s_waitcnt lgkmcnt(0)
	v_add_f32_e32 v128, v128, v129
	s_nop 1
	v_mov_b32_dpp v129, v128 row_half_mirror row_mask:0xf bank_mask:0xf
	s_waitcnt lgkmcnt(0)
	v_add_f32_e32 v129, v128, v129
	s_nop 1
	v_mov_b32_dpp v131, v129 row_mirror row_mask:0xf bank_mask:0xf
	v_add_u32_e32 v128, v130, v81
	v_add_u32_e32 v130, v130, v82
	s_waitcnt lgkmcnt(0)
	v_add_f32_e32 v132, v129, v131
	ds_bpermute_b32 v135, v126, v132
	v_ashrrev_i32_e32 v129, 31, v128
	v_ashrrev_i32_e32 v131, 31, v130
	v_lshl_add_u64 v[128:129], v[128:129], 1, s[6:7]
	v_lshl_add_u64 v[130:131], v[130:131], 1, s[6:7]
	s_waitcnt lgkmcnt(0)
	v_add_f32_e32 v132, v132, v135
	v_fmamk_f32 v132, v132, 0x3c800000, v119
	v_rsq_f32_e32 v132, v132
	global_store_short v[128:129], v133, off sc1
	global_store_short v[130:131], v134, off sc1
	v_pk_mul_f32 v[128:129], v[70:71], v[132:133] op_sel_hi:[1,0]
	s_nop 0
	v_pk_mul_f32 v[72:73], v[72:73], v[128:129]
	s_cbranch_vccnz .LBB0_621
	global_load_dwordx2 v[128:129], v136, s[8:9]
	s_waitcnt vmcnt(0)
	v_pk_mul_f32 v[132:133], v[72:73], v[128:129] op_sel_hi:[0,1]
	v_pk_mul_f32 v[130:131], v[72:73], v[128:129] op_sel:[1,1] op_sel_hi:[1,0]
	v_pk_fma_f32 v[72:73], v[72:73], v[128:129], v[132:133] op_sel:[1,1,0] op_sel_hi:[1,0,1] neg_lo:[0,0,1] neg_hi:[0,0,1]
	s_nop 0
	v_add_f32_e32 v72, v130, v132
.LBB0_621:
	v_mov_b32_e32 v128, v22
	v_mov_b32_e32 v129, v6
	v_pk_mul_f32 v[128:129], v[128:129], v[128:129]
	v_add_u32_e32 v130, s74, v141
	v_add_f32_e32 v128, v128, v129
	s_nop 1
	v_mov_b32_dpp v129, v128 quad_perm:[1,0,3,2] row_mask:0xf bank_mask:0xf
	v_cvt_pk_bf16_f32 v133, v73, s0
	v_cvt_pk_bf16_f32 v134, v72, s0
	v_mov_b32_e32 v72, v6
	v_mov_b32_e32 v73, v22
	s_waitcnt lgkmcnt(0)
	v_add_f32_e32 v128, v128, v129
	s_nop 1
	v_mov_b32_dpp v129, v128 quad_perm:[2,3,0,1] row_mask:0xf bank_mask:0xf
	s_and_b64 vcc, exec, s[0:1]
	s_waitcnt lgkmcnt(0)
	v_add_f32_e32 v128, v128, v129
	s_nop 1
	v_mov_b32_dpp v129, v128 row_half_mirror row_mask:0xf bank_mask:0xf
	s_waitcnt lgkmcnt(0)
	v_add_f32_e32 v129, v128, v129
	s_nop 1
	v_mov_b32_dpp v131, v129 row_mirror row_mask:0xf bank_mask:0xf
	v_add_u32_e32 v128, v130, v81
	v_add_u32_e32 v130, v130, v82
	s_waitcnt lgkmcnt(0)
	v_add_f32_e32 v132, v129, v131
	ds_bpermute_b32 v135, v126, v132
	v_ashrrev_i32_e32 v129, 31, v128
	v_ashrrev_i32_e32 v131, 31, v130
	v_lshl_add_u64 v[128:129], v[128:129], 1, s[6:7]
	v_lshl_add_u64 v[130:131], v[130:131], 1, s[6:7]
	s_waitcnt lgkmcnt(0)
	v_add_f32_e32 v132, v132, v135
	v_fmamk_f32 v132, v132, 0x3c800000, v119
	v_rsq_f32_e32 v132, v132
	global_store_short v[128:129], v133, off sc1
	global_store_short v[130:131], v134, off sc1
	v_pk_mul_f32 v[128:129], v[70:71], v[132:133] op_sel_hi:[1,0]
	s_nop 0
	v_pk_mul_f32 v[72:73], v[72:73], v[128:129]
	s_cbranch_vccnz .LBB0_623
	global_load_dwordx2 v[128:129], v138, s[8:9]
	s_waitcnt vmcnt(0)
	v_pk_mul_f32 v[132:133], v[72:73], v[128:129] op_sel_hi:[0,1]
	v_pk_mul_f32 v[130:131], v[72:73], v[128:129] op_sel:[1,1] op_sel_hi:[1,0]
	v_pk_fma_f32 v[72:73], v[72:73], v[128:129], v[132:133] op_sel:[1,1,0] op_sel_hi:[1,0,1] neg_lo:[0,0,1] neg_hi:[0,0,1]
	s_nop 0
	v_add_f32_e32 v72, v130, v132
.LBB0_623:
	v_mov_b32_e32 v128, v23
	v_mov_b32_e32 v129, v7
	v_pk_mul_f32 v[128:129], v[128:129], v[128:129]
	v_add_u32_e32 v130, s74, v144
	v_add_f32_e32 v128, v128, v129
	s_nop 1
	v_mov_b32_dpp v129, v128 quad_perm:[1,0,3,2] row_mask:0xf bank_mask:0xf
	v_cvt_pk_bf16_f32 v133, v73, s0
	v_cvt_pk_bf16_f32 v134, v72, s0
	v_mov_b32_e32 v72, v7
	v_mov_b32_e32 v73, v23
	s_waitcnt lgkmcnt(0)
	v_add_f32_e32 v128, v128, v129
	s_nop 1
	v_mov_b32_dpp v129, v128 quad_perm:[2,3,0,1] row_mask:0xf bank_mask:0xf
	s_and_b64 vcc, exec, s[0:1]
	s_waitcnt lgkmcnt(0)
	v_add_f32_e32 v128, v128, v129
	s_nop 1
	v_mov_b32_dpp v129, v128 row_half_mirror row_mask:0xf bank_mask:0xf
	s_waitcnt lgkmcnt(0)
	v_add_f32_e32 v129, v128, v129
	s_nop 1
	v_mov_b32_dpp v131, v129 row_mirror row_mask:0xf bank_mask:0xf
	v_add_u32_e32 v128, v130, v81
	v_add_u32_e32 v130, v130, v82
	s_waitcnt lgkmcnt(0)
	v_add_f32_e32 v132, v129, v131
	ds_bpermute_b32 v135, v126, v132
	v_ashrrev_i32_e32 v129, 31, v128
	v_ashrrev_i32_e32 v131, 31, v130
	v_lshl_add_u64 v[128:129], v[128:129], 1, s[6:7]
	v_lshl_add_u64 v[130:131], v[130:131], 1, s[6:7]
	s_waitcnt lgkmcnt(0)
	v_add_f32_e32 v132, v132, v135
	v_fmamk_f32 v132, v132, 0x3c800000, v119
	v_rsq_f32_e32 v132, v132
	global_store_short v[128:129], v133, off sc1
	global_store_short v[130:131], v134, off sc1
	v_pk_mul_f32 v[128:129], v[70:71], v[132:133] op_sel_hi:[1,0]
	s_nop 0
	v_pk_mul_f32 v[72:73], v[72:73], v[128:129]
	s_cbranch_vccnz .LBB0_625
	global_load_dwordx2 v[128:129], v140, s[8:9]
	s_waitcnt vmcnt(0)
	v_pk_mul_f32 v[132:133], v[72:73], v[128:129] op_sel_hi:[0,1]
	v_pk_mul_f32 v[130:131], v[72:73], v[128:129] op_sel:[1,1] op_sel_hi:[1,0]
	v_pk_fma_f32 v[72:73], v[72:73], v[128:129], v[132:133] op_sel:[1,1,0] op_sel_hi:[1,0,1] neg_lo:[0,0,1] neg_hi:[0,0,1]
	s_nop 0
	v_add_f32_e32 v72, v130, v132
.LBB0_625:
	v_mov_b32_e32 v128, v24
	v_mov_b32_e32 v129, v8
	v_pk_mul_f32 v[128:129], v[128:129], v[128:129]
	v_add_u32_e32 v130, s74, v146
	v_add_f32_e32 v128, v128, v129
	s_nop 1
	v_mov_b32_dpp v129, v128 quad_perm:[1,0,3,2] row_mask:0xf bank_mask:0xf
	v_cvt_pk_bf16_f32 v133, v73, s0
	v_cvt_pk_bf16_f32 v134, v72, s0
	v_mov_b32_e32 v72, v8
	v_mov_b32_e32 v73, v24
	s_waitcnt lgkmcnt(0)
	v_add_f32_e32 v128, v128, v129
	s_nop 1
	v_mov_b32_dpp v129, v128 quad_perm:[2,3,0,1] row_mask:0xf bank_mask:0xf
	s_and_b64 vcc, exec, s[0:1]
	s_waitcnt lgkmcnt(0)
	v_add_f32_e32 v128, v128, v129
	s_nop 1
	v_mov_b32_dpp v129, v128 row_half_mirror row_mask:0xf bank_mask:0xf
	s_waitcnt lgkmcnt(0)
	v_add_f32_e32 v129, v128, v129
	s_nop 1
	v_mov_b32_dpp v131, v129 row_mirror row_mask:0xf bank_mask:0xf
	v_add_u32_e32 v128, v130, v81
	v_add_u32_e32 v130, v130, v82
	s_waitcnt lgkmcnt(0)
	v_add_f32_e32 v132, v129, v131
	ds_bpermute_b32 v135, v126, v132
	v_ashrrev_i32_e32 v129, 31, v128
	v_ashrrev_i32_e32 v131, 31, v130
	v_lshl_add_u64 v[128:129], v[128:129], 1, s[6:7]
	v_lshl_add_u64 v[130:131], v[130:131], 1, s[6:7]
	s_waitcnt lgkmcnt(0)
	v_add_f32_e32 v132, v132, v135
	v_fmamk_f32 v132, v132, 0x3c800000, v119
	v_rsq_f32_e32 v132, v132
	global_store_short v[128:129], v133, off sc1
	global_store_short v[130:131], v134, off sc1
	v_pk_mul_f32 v[128:129], v[70:71], v[132:133] op_sel_hi:[1,0]
	s_nop 0
	v_pk_mul_f32 v[72:73], v[72:73], v[128:129]
	s_cbranch_vccnz .LBB0_627
	global_load_dwordx2 v[128:129], v143, s[8:9]
	s_waitcnt vmcnt(0)
	v_pk_mul_f32 v[132:133], v[72:73], v[128:129] op_sel_hi:[0,1]
	v_pk_mul_f32 v[130:131], v[72:73], v[128:129] op_sel:[1,1] op_sel_hi:[1,0]
	v_pk_fma_f32 v[72:73], v[72:73], v[128:129], v[132:133] op_sel:[1,1,0] op_sel_hi:[1,0,1] neg_lo:[0,0,1] neg_hi:[0,0,1]
	s_nop 0
	v_add_f32_e32 v72, v130, v132
.LBB0_627:
	v_mov_b32_e32 v128, v25
	v_mov_b32_e32 v129, v9
	v_pk_mul_f32 v[128:129], v[128:129], v[128:129]
	v_add_u32_e32 v130, s74, v148
	v_add_f32_e32 v128, v128, v129
	s_nop 1
	v_mov_b32_dpp v129, v128 quad_perm:[1,0,3,2] row_mask:0xf bank_mask:0xf
	v_cvt_pk_bf16_f32 v133, v73, s0
	v_cvt_pk_bf16_f32 v134, v72, s0
	v_mov_b32_e32 v72, v9
	v_mov_b32_e32 v73, v25
	s_waitcnt lgkmcnt(0)
	v_add_f32_e32 v128, v128, v129
	s_nop 1
	v_mov_b32_dpp v129, v128 quad_perm:[2,3,0,1] row_mask:0xf bank_mask:0xf
	s_and_b64 vcc, exec, s[0:1]
	s_waitcnt lgkmcnt(0)
	v_add_f32_e32 v128, v128, v129
	s_nop 1
	v_mov_b32_dpp v129, v128 row_half_mirror row_mask:0xf bank_mask:0xf
	s_waitcnt lgkmcnt(0)
	v_add_f32_e32 v129, v128, v129
	s_nop 1
	v_mov_b32_dpp v131, v129 row_mirror row_mask:0xf bank_mask:0xf
	v_add_u32_e32 v128, v130, v81
	v_add_u32_e32 v130, v130, v82
	s_waitcnt lgkmcnt(0)
	v_add_f32_e32 v132, v129, v131
	ds_bpermute_b32 v135, v126, v132
	v_ashrrev_i32_e32 v129, 31, v128
	v_ashrrev_i32_e32 v131, 31, v130
	v_lshl_add_u64 v[128:129], v[128:129], 1, s[6:7]
	v_lshl_add_u64 v[130:131], v[130:131], 1, s[6:7]
	s_waitcnt lgkmcnt(0)
	v_add_f32_e32 v132, v132, v135
	v_fmamk_f32 v132, v132, 0x3c800000, v119
	v_rsq_f32_e32 v132, v132
	global_store_short v[128:129], v133, off sc1
	global_store_short v[130:131], v134, off sc1
	v_pk_mul_f32 v[128:129], v[70:71], v[132:133] op_sel_hi:[1,0]
	s_nop 0
	v_pk_mul_f32 v[72:73], v[72:73], v[128:129]
	s_cbranch_vccnz .LBB0_629
	global_load_dwordx2 v[128:129], v145, s[8:9]
	s_waitcnt vmcnt(0)
	v_pk_mul_f32 v[132:133], v[72:73], v[128:129] op_sel_hi:[0,1]
	v_pk_mul_f32 v[130:131], v[72:73], v[128:129] op_sel:[1,1] op_sel_hi:[1,0]
	v_pk_fma_f32 v[72:73], v[72:73], v[128:129], v[132:133] op_sel:[1,1,0] op_sel_hi:[1,0,1] neg_lo:[0,0,1] neg_hi:[0,0,1]
	s_nop 0
	v_add_f32_e32 v72, v130, v132
.LBB0_629:
	v_mov_b32_e32 v128, v26
	v_mov_b32_e32 v129, v10
	v_pk_mul_f32 v[128:129], v[128:129], v[128:129]
	v_add_u32_e32 v130, s74, v150
	v_add_f32_e32 v128, v128, v129
	s_nop 1
	v_mov_b32_dpp v129, v128 quad_perm:[1,0,3,2] row_mask:0xf bank_mask:0xf
	v_cvt_pk_bf16_f32 v133, v73, s0
	v_cvt_pk_bf16_f32 v134, v72, s0
	v_mov_b32_e32 v72, v10
	v_mov_b32_e32 v73, v26
	s_waitcnt lgkmcnt(0)
	v_add_f32_e32 v128, v128, v129
	s_nop 1
	v_mov_b32_dpp v129, v128 quad_perm:[2,3,0,1] row_mask:0xf bank_mask:0xf
	s_and_b64 vcc, exec, s[0:1]
	s_waitcnt lgkmcnt(0)
	v_add_f32_e32 v128, v128, v129
	s_nop 1
	v_mov_b32_dpp v129, v128 row_half_mirror row_mask:0xf bank_mask:0xf
	s_waitcnt lgkmcnt(0)
	v_add_f32_e32 v129, v128, v129
	s_nop 1
	v_mov_b32_dpp v131, v129 row_mirror row_mask:0xf bank_mask:0xf
	v_add_u32_e32 v128, v130, v81
	v_add_u32_e32 v130, v130, v82
	s_waitcnt lgkmcnt(0)
	v_add_f32_e32 v132, v129, v131
	ds_bpermute_b32 v135, v126, v132
	v_ashrrev_i32_e32 v129, 31, v128
	v_ashrrev_i32_e32 v131, 31, v130
	v_lshl_add_u64 v[128:129], v[128:129], 1, s[6:7]
	v_lshl_add_u64 v[130:131], v[130:131], 1, s[6:7]
	s_waitcnt lgkmcnt(0)
	v_add_f32_e32 v132, v132, v135
	v_fmamk_f32 v132, v132, 0x3c800000, v119
	v_rsq_f32_e32 v132, v132
	global_store_short v[128:129], v133, off sc1
	global_store_short v[130:131], v134, off sc1
	v_pk_mul_f32 v[128:129], v[70:71], v[132:133] op_sel_hi:[1,0]
	s_nop 0
	v_pk_mul_f32 v[72:73], v[72:73], v[128:129]
	s_cbranch_vccnz .LBB0_631
	global_load_dwordx2 v[128:129], v147, s[8:9]
	s_waitcnt vmcnt(0)
	v_pk_mul_f32 v[132:133], v[72:73], v[128:129] op_sel_hi:[0,1]
	v_pk_mul_f32 v[130:131], v[72:73], v[128:129] op_sel:[1,1] op_sel_hi:[1,0]
	v_pk_fma_f32 v[72:73], v[72:73], v[128:129], v[132:133] op_sel:[1,1,0] op_sel_hi:[1,0,1] neg_lo:[0,0,1] neg_hi:[0,0,1]
	s_nop 0
	v_add_f32_e32 v72, v130, v132
.LBB0_631:
	v_mov_b32_e32 v128, v27
	v_mov_b32_e32 v129, v11
	v_pk_mul_f32 v[128:129], v[128:129], v[128:129]
	v_add_u32_e32 v130, s74, v152
	v_add_f32_e32 v128, v128, v129
	s_nop 1
	v_mov_b32_dpp v129, v128 quad_perm:[1,0,3,2] row_mask:0xf bank_mask:0xf
	v_cvt_pk_bf16_f32 v133, v73, s0
	v_cvt_pk_bf16_f32 v134, v72, s0
	v_mov_b32_e32 v72, v11
	v_mov_b32_e32 v73, v27
	s_waitcnt lgkmcnt(0)
	v_add_f32_e32 v128, v128, v129
	s_nop 1
	v_mov_b32_dpp v129, v128 quad_perm:[2,3,0,1] row_mask:0xf bank_mask:0xf
	s_and_b64 vcc, exec, s[0:1]
	s_waitcnt lgkmcnt(0)
	v_add_f32_e32 v128, v128, v129
	s_nop 1
	v_mov_b32_dpp v129, v128 row_half_mirror row_mask:0xf bank_mask:0xf
	s_waitcnt lgkmcnt(0)
	v_add_f32_e32 v129, v128, v129
	s_nop 1
	v_mov_b32_dpp v131, v129 row_mirror row_mask:0xf bank_mask:0xf
	v_add_u32_e32 v128, v130, v81
	v_add_u32_e32 v130, v130, v82
	s_waitcnt lgkmcnt(0)
	v_add_f32_e32 v132, v129, v131
	ds_bpermute_b32 v135, v126, v132
	v_ashrrev_i32_e32 v129, 31, v128
	v_ashrrev_i32_e32 v131, 31, v130
	v_lshl_add_u64 v[128:129], v[128:129], 1, s[6:7]
	v_lshl_add_u64 v[130:131], v[130:131], 1, s[6:7]
	s_waitcnt lgkmcnt(0)
	v_add_f32_e32 v132, v132, v135
	v_fmamk_f32 v132, v132, 0x3c800000, v119
	v_rsq_f32_e32 v132, v132
	global_store_short v[128:129], v133, off sc1
	global_store_short v[130:131], v134, off sc1
	v_pk_mul_f32 v[128:129], v[70:71], v[132:133] op_sel_hi:[1,0]
	s_nop 0
	v_pk_mul_f32 v[72:73], v[72:73], v[128:129]
	s_cbranch_vccnz .LBB0_633
	global_load_dwordx2 v[128:129], v149, s[8:9]
	s_waitcnt vmcnt(0)
	v_pk_mul_f32 v[132:133], v[72:73], v[128:129] op_sel_hi:[0,1]
	v_pk_mul_f32 v[130:131], v[72:73], v[128:129] op_sel:[1,1] op_sel_hi:[1,0]
	v_pk_fma_f32 v[72:73], v[72:73], v[128:129], v[132:133] op_sel:[1,1,0] op_sel_hi:[1,0,1] neg_lo:[0,0,1] neg_hi:[0,0,1]
	s_nop 0
	v_add_f32_e32 v72, v130, v132
.LBB0_633:
	v_mov_b32_e32 v128, v28
	v_mov_b32_e32 v129, v12
	v_pk_mul_f32 v[128:129], v[128:129], v[128:129]
	v_add_u32_e32 v130, s74, v154
	v_add_f32_e32 v128, v128, v129
	s_nop 1
	v_mov_b32_dpp v129, v128 quad_perm:[1,0,3,2] row_mask:0xf bank_mask:0xf
	v_cvt_pk_bf16_f32 v133, v73, s0
	v_cvt_pk_bf16_f32 v134, v72, s0
	v_mov_b32_e32 v72, v12
	v_mov_b32_e32 v73, v28
	s_waitcnt lgkmcnt(0)
	v_add_f32_e32 v128, v128, v129
	s_nop 1
	v_mov_b32_dpp v129, v128 quad_perm:[2,3,0,1] row_mask:0xf bank_mask:0xf
	s_and_b64 vcc, exec, s[0:1]
	s_waitcnt lgkmcnt(0)
	v_add_f32_e32 v128, v128, v129
	s_nop 1
	v_mov_b32_dpp v129, v128 row_half_mirror row_mask:0xf bank_mask:0xf
	s_waitcnt lgkmcnt(0)
	v_add_f32_e32 v129, v128, v129
	s_nop 1
	v_mov_b32_dpp v131, v129 row_mirror row_mask:0xf bank_mask:0xf
	v_add_u32_e32 v128, v130, v81
	v_add_u32_e32 v130, v130, v82
	s_waitcnt lgkmcnt(0)
	v_add_f32_e32 v132, v129, v131
	ds_bpermute_b32 v135, v126, v132
	v_ashrrev_i32_e32 v129, 31, v128
	v_ashrrev_i32_e32 v131, 31, v130
	v_lshl_add_u64 v[128:129], v[128:129], 1, s[6:7]
	v_lshl_add_u64 v[130:131], v[130:131], 1, s[6:7]
	s_waitcnt lgkmcnt(0)
	v_add_f32_e32 v132, v132, v135
	v_fmamk_f32 v132, v132, 0x3c800000, v119
	v_rsq_f32_e32 v132, v132
	global_store_short v[128:129], v133, off sc1
	global_store_short v[130:131], v134, off sc1
	v_pk_mul_f32 v[128:129], v[70:71], v[132:133] op_sel_hi:[1,0]
	s_nop 0
	v_pk_mul_f32 v[72:73], v[72:73], v[128:129]
	s_cbranch_vccnz .LBB0_635
	global_load_dwordx2 v[128:129], v151, s[8:9]
	s_waitcnt vmcnt(0)
	v_pk_mul_f32 v[132:133], v[72:73], v[128:129] op_sel_hi:[0,1]
	v_pk_mul_f32 v[130:131], v[72:73], v[128:129] op_sel:[1,1] op_sel_hi:[1,0]
	v_pk_fma_f32 v[72:73], v[72:73], v[128:129], v[132:133] op_sel:[1,1,0] op_sel_hi:[1,0,1] neg_lo:[0,0,1] neg_hi:[0,0,1]
	s_nop 0
	v_add_f32_e32 v72, v130, v132
.LBB0_635:
	v_mov_b32_e32 v128, v29
	v_mov_b32_e32 v129, v13
	v_pk_mul_f32 v[128:129], v[128:129], v[128:129]
	v_add_u32_e32 v130, s74, v156
	v_add_f32_e32 v128, v128, v129
	s_nop 1
	v_mov_b32_dpp v129, v128 quad_perm:[1,0,3,2] row_mask:0xf bank_mask:0xf
	v_cvt_pk_bf16_f32 v133, v73, s0
	v_cvt_pk_bf16_f32 v134, v72, s0
	v_mov_b32_e32 v72, v13
	v_mov_b32_e32 v73, v29
	s_waitcnt lgkmcnt(0)
	v_add_f32_e32 v128, v128, v129
	s_nop 1
	v_mov_b32_dpp v129, v128 quad_perm:[2,3,0,1] row_mask:0xf bank_mask:0xf
	s_and_b64 vcc, exec, s[0:1]
	s_waitcnt lgkmcnt(0)
	v_add_f32_e32 v128, v128, v129
	s_nop 1
	v_mov_b32_dpp v129, v128 row_half_mirror row_mask:0xf bank_mask:0xf
	s_waitcnt lgkmcnt(0)
	v_add_f32_e32 v129, v128, v129
	s_nop 1
	v_mov_b32_dpp v131, v129 row_mirror row_mask:0xf bank_mask:0xf
	v_add_u32_e32 v128, v130, v81
	v_add_u32_e32 v130, v130, v82
	s_waitcnt lgkmcnt(0)
	v_add_f32_e32 v132, v129, v131
	ds_bpermute_b32 v135, v126, v132
	v_ashrrev_i32_e32 v129, 31, v128
	v_ashrrev_i32_e32 v131, 31, v130
	v_lshl_add_u64 v[128:129], v[128:129], 1, s[6:7]
	v_lshl_add_u64 v[130:131], v[130:131], 1, s[6:7]
	s_waitcnt lgkmcnt(0)
	v_add_f32_e32 v132, v132, v135
	v_fmamk_f32 v132, v132, 0x3c800000, v119
	v_rsq_f32_e32 v132, v132
	global_store_short v[128:129], v133, off sc1
	global_store_short v[130:131], v134, off sc1
	v_pk_mul_f32 v[128:129], v[70:71], v[132:133] op_sel_hi:[1,0]
	s_nop 0
	v_pk_mul_f32 v[72:73], v[72:73], v[128:129]
	s_cbranch_vccnz .LBB0_637
	global_load_dwordx2 v[128:129], v153, s[8:9]
	s_waitcnt vmcnt(0)
	v_pk_mul_f32 v[132:133], v[72:73], v[128:129] op_sel_hi:[0,1]
	v_pk_mul_f32 v[130:131], v[72:73], v[128:129] op_sel:[1,1] op_sel_hi:[1,0]
	v_pk_fma_f32 v[72:73], v[72:73], v[128:129], v[132:133] op_sel:[1,1,0] op_sel_hi:[1,0,1] neg_lo:[0,0,1] neg_hi:[0,0,1]
	s_nop 0
	v_add_f32_e32 v72, v130, v132
.LBB0_637:
	v_mov_b32_e32 v128, v30
	v_mov_b32_e32 v129, v14
	v_pk_mul_f32 v[128:129], v[128:129], v[128:129]
	v_add_u32_e32 v130, s74, v157
	v_add_f32_e32 v128, v128, v129
	s_nop 1
	v_mov_b32_dpp v129, v128 quad_perm:[1,0,3,2] row_mask:0xf bank_mask:0xf
	v_cvt_pk_bf16_f32 v133, v73, s0
	v_cvt_pk_bf16_f32 v134, v72, s0
	v_mov_b32_e32 v72, v14
	v_mov_b32_e32 v73, v30
	s_waitcnt lgkmcnt(0)
	v_add_f32_e32 v128, v128, v129
	s_nop 1
	v_mov_b32_dpp v129, v128 quad_perm:[2,3,0,1] row_mask:0xf bank_mask:0xf
	s_and_b64 vcc, exec, s[0:1]
	s_waitcnt lgkmcnt(0)
	v_add_f32_e32 v128, v128, v129
	s_nop 1
	v_mov_b32_dpp v129, v128 row_half_mirror row_mask:0xf bank_mask:0xf
	s_waitcnt lgkmcnt(0)
	v_add_f32_e32 v129, v128, v129
	s_nop 1
	v_mov_b32_dpp v131, v129 row_mirror row_mask:0xf bank_mask:0xf
	v_add_u32_e32 v128, v130, v81
	v_add_u32_e32 v130, v130, v82
	s_waitcnt lgkmcnt(0)
	v_add_f32_e32 v132, v129, v131
	ds_bpermute_b32 v135, v126, v132
	v_ashrrev_i32_e32 v129, 31, v128
	v_ashrrev_i32_e32 v131, 31, v130
	v_lshl_add_u64 v[128:129], v[128:129], 1, s[6:7]
	v_lshl_add_u64 v[130:131], v[130:131], 1, s[6:7]
	s_waitcnt lgkmcnt(0)
	v_add_f32_e32 v132, v132, v135
	v_fmamk_f32 v132, v132, 0x3c800000, v119
	v_rsq_f32_e32 v132, v132
	global_store_short v[128:129], v133, off sc1
	global_store_short v[130:131], v134, off sc1
	v_pk_mul_f32 v[128:129], v[70:71], v[132:133] op_sel_hi:[1,0]
	s_nop 0
	v_pk_mul_f32 v[72:73], v[72:73], v[128:129]
	s_cbranch_vccnz .LBB0_639
	global_load_dwordx2 v[128:129], v155, s[8:9]
	s_waitcnt vmcnt(0)
	v_pk_mul_f32 v[132:133], v[72:73], v[128:129] op_sel_hi:[0,1]
	v_pk_mul_f32 v[130:131], v[72:73], v[128:129] op_sel:[1,1] op_sel_hi:[1,0]
	v_pk_fma_f32 v[72:73], v[72:73], v[128:129], v[132:133] op_sel:[1,1,0] op_sel_hi:[1,0,1] neg_lo:[0,0,1] neg_hi:[0,0,1]
	s_nop 0
	v_add_f32_e32 v72, v130, v132
.LBB0_639:
	v_mov_b32_e32 v128, v31
	v_mov_b32_e32 v129, v15
	v_pk_mul_f32 v[128:129], v[128:129], v[128:129]
	v_cvt_pk_bf16_f32 v130, v72, s0
	v_add_f32_e32 v128, v128, v129
	s_nop 1
	v_mov_b32_dpp v123, v128 quad_perm:[1,0,3,2] row_mask:0xf bank_mask:0xf
	v_cvt_pk_bf16_f32 v129, v73, s0
	v_mov_b32_e32 v72, v15
	v_mov_b32_e32 v73, v31
	s_and_b64 vcc, exec, s[0:1]
	s_waitcnt lgkmcnt(0)
	v_add_f32_e32 v123, v128, v123
	s_nop 1
	v_mov_b32_dpp v124, v123 quad_perm:[2,3,0,1] row_mask:0xf bank_mask:0xf
	s_waitcnt lgkmcnt(0)
	v_add_f32_e32 v123, v123, v124
	s_nop 1
	v_mov_b32_dpp v124, v123 row_half_mirror row_mask:0xf bank_mask:0xf
	v_add_u32_e32 v125, s74, v158
	s_waitcnt lgkmcnt(0)
	v_add_f32_e32 v123, v123, v124
	s_nop 1
	v_mov_b32_dpp v127, v123 row_mirror row_mask:0xf bank_mask:0xf
	v_add_u32_e32 v124, v125, v81
	s_waitcnt lgkmcnt(0)
	v_add_f32_e32 v123, v123, v127
	ds_bpermute_b32 v128, v126, v123
	v_add_u32_e32 v126, v125, v82
	v_ashrrev_i32_e32 v125, 31, v124
	v_ashrrev_i32_e32 v127, 31, v126
	v_lshl_add_u64 v[124:125], v[124:125], 1, s[6:7]
	s_waitcnt lgkmcnt(0)
	v_add_f32_e32 v123, v123, v128
	v_fmamk_f32 v123, v123, 0x3c800000, v119
	v_rsq_f32_e32 v128, v123
	v_lshl_add_u64 v[126:127], v[126:127], 1, s[6:7]
	global_store_short v[124:125], v129, off sc1
	global_store_short v[126:127], v130, off sc1
	v_pk_mul_f32 v[70:71], v[70:71], v[128:129] op_sel_hi:[1,0]
	s_nop 0
	v_pk_mul_f32 v[70:71], v[72:73], v[70:71]
	s_cbranch_vccnz .LBB0_641
	global_load_dwordx2 v[72:73], v142, s[8:9]
	s_waitcnt vmcnt(0)
	v_pk_mul_f32 v[126:127], v[70:71], v[72:73] op_sel_hi:[0,1]
	v_pk_mul_f32 v[124:125], v[70:71], v[72:73] op_sel:[1,1] op_sel_hi:[1,0]
	v_pk_fma_f32 v[70:71], v[70:71], v[72:73], v[126:127] op_sel:[1,1,0] op_sel_hi:[1,0,1] neg_lo:[0,0,1] neg_hi:[0,0,1]
	s_nop 0
	v_add_f32_e32 v70, v124, v126

.LBB0_642:
	s_and_b64 vcc, exec, s[0:1]
	s_cbranch_vccz .LBB0_575
	v_and_b32_e32 v71, 64, v122
	v_xor_b32_e32 v70, 1, v122
	v_add_u32_e32 v71, 64, v71
	v_mul_f32_e32 v72, v32, v32
	v_cmp_lt_i32_e32 vcc, v70, v71
	v_fmac_f32_e32 v72, v48, v48
	v_fmac_f32_e32 v72, v16, v16
	v_cndmask_b32_e32 v70, v122, v70, vcc
	v_lshlrev_b32_e32 v132, 2, v70
	v_fmac_f32_e32 v72, v0, v0
	s_nop 1
	v_mov_b32_dpp v73, v72 quad_perm:[1,0,3,2] row_mask:0xf bank_mask:0xf
	v_xor_b32_e32 v70, 2, v122
	v_cmp_lt_i32_e32 vcc, v70, v71
	v_mul_f32_e32 v123, v33, v33
	v_fmac_f32_e32 v123, v49, v49
	v_cndmask_b32_e32 v70, v122, v70, vcc
	v_lshlrev_b32_e32 v133, 2, v70
	s_waitcnt lgkmcnt(0)
	v_add_f32_e32 v72, v72, v73
	v_xor_b32_e32 v70, 4, v122
	s_nop 1
	v_mov_b32_dpp v73, v72 quad_perm:[2,3,0,1] row_mask:0xf bank_mask:0xf
	v_cmp_lt_i32_e32 vcc, v70, v71
	v_fmac_f32_e32 v123, v17, v17
	v_fmac_f32_e32 v123, v1, v1
	v_cndmask_b32_e32 v70, v122, v70, vcc
	v_lshlrev_b32_e32 v135, 2, v70
	v_xor_b32_e32 v70, 8, v122
	v_cmp_lt_i32_e32 vcc, v70, v71
	s_waitcnt lgkmcnt(0)
	v_add_f32_e32 v72, v72, v73
	s_nop 1
	v_mov_b32_dpp v73, v72 row_half_mirror row_mask:0xf bank_mask:0xf
	v_cndmask_b32_e32 v70, v122, v70, vcc
	v_lshlrev_b32_e32 v136, 2, v70
	v_xor_b32_e32 v70, 16, v122
	s_nop 1
	v_mov_b32_dpp v124, v123 quad_perm:[1,0,3,2] row_mask:0xf bank_mask:0xf
	v_cmp_lt_i32_e32 vcc, v70, v71
	v_mul_f32_e32 v128, v40, v40
	v_fmac_f32_e32 v128, v56, v56
	v_cndmask_b32_e32 v70, v122, v70, vcc
	v_mul_f32_e32 v122, v34, v34
	v_fmac_f32_e32 v122, v50, v50
	v_fmac_f32_e32 v122, v18, v18
	v_lshlrev_b32_e32 v137, 2, v70
	s_waitcnt lgkmcnt(0)
	v_add_f32_e32 v70, v72, v73
	s_waitcnt lgkmcnt(0)
	v_add_f32_e32 v72, v123, v124
	v_fmac_f32_e32 v122, v2, v2
	s_nop 1
	v_mov_b32_dpp v71, v70 row_mirror row_mask:0xf bank_mask:0xf
	s_nop 1
	v_mov_b32_dpp v73, v72 quad_perm:[2,3,0,1] row_mask:0xf bank_mask:0xf
	s_nop 1
	v_mov_b32_dpp v123, v122 quad_perm:[1,0,3,2] row_mask:0xf bank_mask:0xf
	v_fmac_f32_e32 v128, v24, v24
	v_fmac_f32_e32 v128, v8, v8
	s_waitcnt lgkmcnt(0)
	v_add_f32_e32 v70, v70, v71
	s_waitcnt lgkmcnt(0)
	v_add_f32_e32 v72, v72, v73
	s_waitcnt lgkmcnt(0)
	v_add_f32_e32 v122, v122, v123
	ds_bpermute_b32 v71, v137, v70
	s_nop 1
	v_mov_b32_dpp v73, v72 row_half_mirror row_mask:0xf bank_mask:0xf
	s_nop 1
	v_mov_b32_dpp v123, v122 quad_perm:[2,3,0,1] row_mask:0xf bank_mask:0xf
	s_nop 1
	v_mov_b32_dpp v129, v128 quad_perm:[1,0,3,2] row_mask:0xf bank_mask:0xf
	v_mul_f32_e32 v141, v46, v46
	s_waitcnt lgkmcnt(0)
	v_add_f32_e32 v70, v70, v71
	s_waitcnt lgkmcnt(0)
	v_add_f32_e32 v71, v72, v73
	s_waitcnt lgkmcnt(0)
	v_add_f32_e32 v73, v122, v123
	v_mul_f32_e32 v123, v35, v35
	v_fmac_f32_e32 v123, v51, v51
	v_fmac_f32_e32 v123, v19, v19
	v_fmac_f32_e32 v123, v3, v3
	s_nop 1
	v_mov_b32_dpp v72, v71 row_mirror row_mask:0xf bank_mask:0xf
	s_nop 1
	v_mov_b32_dpp v122, v73 row_half_mirror row_mask:0xf bank_mask:0xf
	s_nop 1
	v_mov_b32_dpp v124, v123 quad_perm:[1,0,3,2] row_mask:0xf bank_mask:0xf
	v_fmamk_f32 v70, v70, 0x3c000000, v119
	s_waitcnt lgkmcnt(0)
	v_add_f32_e32 v128, v128, v129
	s_waitcnt lgkmcnt(0)
	v_add_f32_e32 v72, v71, v72
	s_waitcnt lgkmcnt(0)
	v_add_f32_e32 v73, v73, v122
	s_waitcnt lgkmcnt(0)
	v_add_f32_e32 v123, v123, v124
	ds_bpermute_b32 v125, v137, v72
	s_nop 1
	v_mov_b32_dpp v122, v73 row_mirror row_mask:0xf bank_mask:0xf
	s_nop 1
	v_mov_b32_dpp v124, v123 quad_perm:[2,3,0,1] row_mask:0xf bank_mask:0xf
	v_rsq_f32_e32 v71, v70
	s_nop 1
	v_mov_b32_dpp v129, v128 quad_perm:[2,3,0,1] row_mask:0xf bank_mask:0xf
	s_waitcnt lgkmcnt(0)
	v_add_f32_e32 v70, v72, v125
	s_waitcnt lgkmcnt(0)
	v_add_f32_e32 v72, v73, v122
	s_waitcnt lgkmcnt(0)
	v_add_f32_e32 v122, v123, v124
	ds_bpermute_b32 v73, v137, v72
	s_nop 1
	v_mov_b32_dpp v123, v122 row_half_mirror row_mask:0xf bank_mask:0xf
	v_mul_f32_e32 v125, v37, v37
	v_fmac_f32_e32 v125, v53, v53
	v_fmac_f32_e32 v125, v21, v21
	s_waitcnt lgkmcnt(0)
	v_add_f32_e32 v72, v72, v73
	s_waitcnt lgkmcnt(0)
	v_add_f32_e32 v73, v122, v123
	v_mul_f32_e32 v123, v36, v36
	v_fmac_f32_e32 v123, v52, v52
	v_fmac_f32_e32 v123, v20, v20
	v_fmac_f32_e32 v123, v4, v4
	v_fmac_f32_e32 v125, v5, v5
	s_nop 1
	v_mov_b32_dpp v122, v73 row_mirror row_mask:0xf bank_mask:0xf
	s_nop 1
	v_mov_b32_dpp v124, v123 quad_perm:[1,0,3,2] row_mask:0xf bank_mask:0xf
	s_nop 1
	v_mov_b32_dpp v126, v125 quad_perm:[1,0,3,2] row_mask:0xf bank_mask:0xf
	v_fmamk_f32 v72, v72, 0x3c000000, v119
	v_mul_f32_e32 v143, v47, v47
	s_waitcnt lgkmcnt(0)
	v_add_f32_e32 v122, v73, v122
	s_waitcnt lgkmcnt(0)
	v_add_f32_e32 v123, v123, v124
	s_waitcnt lgkmcnt(0)
	v_add_f32_e32 v125, v125, v126
	ds_bpermute_b32 v127, v137, v122
	s_nop 1
	v_mov_b32_dpp v124, v123 quad_perm:[2,3,0,1] row_mask:0xf bank_mask:0xf
	s_nop 1
	v_mov_b32_dpp v126, v125 quad_perm:[2,3,0,1] row_mask:0xf bank_mask:0xf
	v_rsq_f32_e32 v73, v72
	v_fmac_f32_e32 v141, v62, v62
	s_waitcnt lgkmcnt(0)
	v_add_f32_e32 v72, v122, v127
	s_waitcnt lgkmcnt(0)
	v_add_f32_e32 v122, v123, v124
	s_waitcnt lgkmcnt(0)
	v_add_f32_e32 v124, v125, v126
	s_nop 1
	v_mov_b32_dpp v123, v122 row_half_mirror row_mask:0xf bank_mask:0xf
	s_nop 1
	v_mov_b32_dpp v125, v124 row_half_mirror row_mask:0xf bank_mask:0xf
	v_mul_f32_e32 v126, v38, v38
	v_fmac_f32_e32 v126, v54, v54
	v_fmac_f32_e32 v126, v22, v22
	s_waitcnt lgkmcnt(0)
	v_add_f32_e32 v122, v122, v123
	s_waitcnt lgkmcnt(0)
	v_add_f32_e32 v124, v124, v125
	v_fmac_f32_e32 v126, v6, v6
	s_nop 1
	v_mov_b32_dpp v123, v122 row_mirror row_mask:0xf bank_mask:0xf
	s_nop 1
	v_mov_b32_dpp v125, v124 row_mirror row_mask:0xf bank_mask:0xf
	s_nop 1
	v_mov_b32_dpp v127, v126 quad_perm:[1,0,3,2] row_mask:0xf bank_mask:0xf
	v_fmac_f32_e32 v143, v63, v63
	v_fmac_f32_e32 v141, v30, v30
	s_waitcnt lgkmcnt(0)
	v_add_f32_e32 v122, v122, v123
	s_waitcnt lgkmcnt(0)
	v_add_f32_e32 v124, v124, v125
	s_waitcnt lgkmcnt(0)
	v_add_f32_e32 v126, v126, v127
	ds_bpermute_b32 v123, v137, v122
	ds_bpermute_b32 v125, v137, v124
	s_nop 1
	v_mov_b32_dpp v127, v126 quad_perm:[2,3,0,1] row_mask:0xf bank_mask:0xf
	v_fmac_f32_e32 v141, v14, v14
	s_nop 1
	v_mov_b32_dpp v142, v141 quad_perm:[1,0,3,2] row_mask:0xf bank_mask:0xf
	s_waitcnt lgkmcnt(1)
	v_add_f32_e32 v122, v122, v123
	s_waitcnt lgkmcnt(0)
	v_add_f32_e32 v123, v124, v125
	s_waitcnt lgkmcnt(0)
	v_add_f32_e32 v124, v126, v127
	v_mul_f32_e32 v126, v39, v39
	v_fmac_f32_e32 v126, v55, v55
	v_fmac_f32_e32 v126, v23, v23
	v_fmac_f32_e32 v126, v7, v7
	s_nop 1
	v_mov_b32_dpp v125, v124 row_half_mirror row_mask:0xf bank_mask:0xf
	s_nop 1
	v_mov_b32_dpp v127, v126 quad_perm:[1,0,3,2] row_mask:0xf bank_mask:0xf
	s_mulk_i32 s72, 0xc0
	v_fmamk_f32 v70, v70, 0x3c000000, v119
	v_rsq_f32_e32 v70, v70
	s_waitcnt lgkmcnt(0)
	v_add_f32_e32 v124, v124, v125
	s_waitcnt lgkmcnt(0)
	v_add_f32_e32 v126, v126, v127
	s_nop 1
	v_mov_b32_dpp v125, v124 row_mirror row_mask:0xf bank_mask:0xf
	s_nop 1
	v_mov_b32_dpp v127, v126 quad_perm:[2,3,0,1] row_mask:0xf bank_mask:0xf
	v_mul_f32_e32 v49, v49, v70
	v_fmamk_f32 v72, v72, 0x3c000000, v119
	v_rsq_f32_e32 v72, v72
	s_waitcnt lgkmcnt(0)
	v_add_f32_e32 v124, v124, v125
	s_waitcnt lgkmcnt(0)
	v_add_f32_e32 v126, v126, v127
	ds_bpermute_b32 v125, v137, v124
	s_nop 1
	v_mov_b32_dpp v127, v126 row_half_mirror row_mask:0xf bank_mask:0xf
	v_fmamk_f32 v122, v122, 0x3c000000, v119
	v_rsq_f32_e32 v122, v122
	v_fmamk_f32 v123, v123, 0x3c000000, v119
	s_waitcnt lgkmcnt(0)
	v_add_f32_e32 v124, v124, v125
	s_waitcnt lgkmcnt(0)
	v_add_f32_e32 v125, v126, v127
	v_add_f32_e32 v127, v128, v129
	v_mul_f32_e32 v129, v41, v41
	v_fmac_f32_e32 v129, v57, v57
	v_fmac_f32_e32 v129, v25, v25
	v_fmac_f32_e32 v129, v9, v9
	s_nop 1
	v_mov_b32_dpp v126, v125 row_mirror row_mask:0xf bank_mask:0xf
	s_nop 1
	v_mov_b32_dpp v130, v129 quad_perm:[1,0,3,2] row_mask:0xf bank_mask:0xf
	s_nop 1
	v_mov_b32_dpp v128, v127 row_half_mirror row_mask:0xf bank_mask:0xf
	v_rsq_f32_e32 v123, v123
	v_fmamk_f32 v124, v124, 0x3c000000, v119
	s_waitcnt lgkmcnt(0)
	v_add_f32_e32 v125, v125, v126
	s_waitcnt lgkmcnt(0)
	v_add_f32_e32 v129, v129, v130
	ds_bpermute_b32 v126, v137, v125
	s_waitcnt lgkmcnt(1)
	v_add_f32_e32 v127, v127, v128
	s_nop 1
	v_mov_b32_dpp v130, v129 quad_perm:[2,3,0,1] row_mask:0xf bank_mask:0xf
	s_nop 1
	v_mov_b32_dpp v128, v127 row_mirror row_mask:0xf bank_mask:0xf
	v_rsq_f32_e32 v124, v124
	s_waitcnt lgkmcnt(0)
	v_add_f32_e32 v125, v125, v126
	v_fmamk_f32 v125, v125, 0x3c000000, v119
	s_waitcnt lgkmcnt(0)
	v_add_f32_e32 v126, v129, v130
	s_waitcnt lgkmcnt(0)
	v_add_f32_e32 v127, v127, v128
	s_nop 1
	v_mov_b32_dpp v128, v126 row_half_mirror row_mask:0xf bank_mask:0xf
	v_mul_f32_e32 v129, v42, v42
	v_fmac_f32_e32 v129, v58, v58
	v_fmac_f32_e32 v129, v26, v26
	v_fmac_f32_e32 v129, v10, v10
	s_waitcnt lgkmcnt(0)
	v_add_f32_e32 v128, v126, v128
	s_nop 1
	v_mov_b32_dpp v130, v129 quad_perm:[1,0,3,2] row_mask:0xf bank_mask:0xf
	s_nop 1
	v_mov_b32_dpp v134, v128 row_mirror row_mask:0xf bank_mask:0xf
	v_rsq_f32_e32 v126, v125
	ds_bpermute_b32 v131, v137, v127
	v_mul_f32_e32 v32, v32, v71
	s_waitcnt lgkmcnt(1)
	v_add_f32_e32 v125, v129, v130
	s_waitcnt lgkmcnt(1)
	v_add_f32_e32 v128, v128, v134
	v_mul_f32_e32 v134, v44, v44
	s_nop 1
	v_mov_b32_dpp v129, v125 quad_perm:[2,3,0,1] row_mask:0xf bank_mask:0xf
	v_fmac_f32_e32 v134, v60, v60
	v_fmac_f32_e32 v134, v28, v28
	v_fmac_f32_e32 v134, v12, v12
	ds_bpermute_b32 v130, v137, v128
	s_nop 1
	v_mov_b32_dpp v138, v134 quad_perm:[1,0,3,2] row_mask:0xf bank_mask:0xf
	s_waitcnt lgkmcnt(1)
	v_add_f32_e32 v129, v125, v129
	v_add_f32_e32 v127, v127, v131
	s_nop 1
	v_mov_b32_dpp v131, v129 row_half_mirror row_mask:0xf bank_mask:0xf
	s_waitcnt lgkmcnt(0)
	v_add_f32_e32 v125, v128, v130
	v_mul_f32_e32 v130, v43, v43
	s_waitcnt lgkmcnt(0)
	v_add_f32_e32 v138, v134, v138
	global_load_dword v134, v121, s[66:67]
	v_fmac_f32_e32 v130, v59, v59
	v_fmac_f32_e32 v130, v27, v27
	s_waitcnt lgkmcnt(0)
	v_add_f32_e32 v128, v129, v131
	v_fmac_f32_e32 v130, v11, v11
	s_nop 1
	v_mov_b32_dpp v129, v128 row_mirror row_mask:0xf bank_mask:0xf
	s_nop 1
	v_mov_b32_dpp v131, v130 quad_perm:[1,0,3,2] row_mask:0xf bank_mask:0xf
	s_nop 1
	v_mov_b32_dpp v139, v138 quad_perm:[2,3,0,1] row_mask:0xf bank_mask:0xf
	v_fmamk_f32 v127, v127, 0x3c000000, v119
	v_rsq_f32_e32 v127, v127
	s_waitcnt lgkmcnt(0)
	v_add_f32_e32 v128, v128, v129
	s_waitcnt lgkmcnt(0)
	v_add_f32_e32 v130, v130, v131
	ds_bpermute_b32 v129, v137, v128
	s_nop 1
	v_mov_b32_dpp v131, v130 quad_perm:[2,3,0,1] row_mask:0xf bank_mask:0xf
	v_fmamk_f32 v125, v125, 0x3c000000, v119
	v_rsq_f32_e32 v125, v125
	v_mul_f32_e32 v16, v16, v71
	s_waitcnt lgkmcnt(0)
	v_add_f32_e32 v128, v128, v129
	s_waitcnt lgkmcnt(0)
	v_add_f32_e32 v129, v130, v131
	v_add_f32_e32 v131, v138, v139
	s_nop 1
	v_mov_b32_dpp v130, v129 row_half_mirror row_mask:0xf bank_mask:0xf
	s_nop 1
	v_mov_b32_dpp v138, v131 row_half_mirror row_mask:0xf bank_mask:0xf
	v_mul_f32_e32 v139, v45, v45
	v_fmac_f32_e32 v139, v61, v61
	v_fmac_f32_e32 v139, v29, v29
	s_waitcnt lgkmcnt(0)
	v_add_f32_e32 v129, v129, v130
	s_waitcnt lgkmcnt(0)
	v_add_f32_e32 v131, v131, v138
	s_nop 1
	v_mov_b32_dpp v130, v129 row_mirror row_mask:0xf bank_mask:0xf
	s_nop 1
	v_mov_b32_dpp v138, v131 row_mirror row_mask:0xf bank_mask:0xf
	v_fmac_f32_e32 v139, v13, v13
	s_nop 1
	v_mov_b32_dpp v140, v139 quad_perm:[1,0,3,2] row_mask:0xf bank_mask:0xf
	v_fmamk_f32 v128, v128, 0x3c000000, v119
	s_waitcnt lgkmcnt(0)
	v_add_f32_e32 v129, v129, v130
	s_waitcnt lgkmcnt(0)
	v_add_f32_e32 v131, v131, v138
	ds_bpermute_b32 v130, v137, v129
	ds_bpermute_b32 v138, v137, v131
	s_waitcnt lgkmcnt(2)
	v_add_f32_e32 v139, v139, v140
	s_nop 1
	v_mov_b32_dpp v140, v139 quad_perm:[2,3,0,1] row_mask:0xf bank_mask:0xf
	v_rsq_f32_e32 v128, v128
	s_waitcnt lgkmcnt(1)
	v_add_f32_e32 v129, v129, v130
	s_waitcnt lgkmcnt(0)
	v_add_f32_e32 v138, v131, v138
	v_mov_b32_e32 v130, v31
	v_mov_b32_e32 v131, v15
	v_pk_mul_f32 v[130:131], v[130:131], v[130:131]
	s_waitcnt lgkmcnt(0)
	v_add_f32_e32 v139, v139, v140
	v_add_f32_e32 v130, v143, v130
	v_add_f32_e32 v130, v130, v131
	s_nop 1
	v_mov_b32_dpp v140, v139 row_half_mirror row_mask:0xf bank_mask:0xf
	s_nop 1
	v_mov_b32_dpp v131, v130 quad_perm:[1,0,3,2] row_mask:0xf bank_mask:0xf
	v_fmamk_f32 v129, v129, 0x3c000000, v119
	v_rsq_f32_e32 v129, v129
	v_mul_f32_e32 v0, v0, v71
	s_waitcnt lgkmcnt(0)
	v_add_f32_e32 v132, v139, v140
	v_add_f32_e32 v139, v141, v142
	s_waitcnt lgkmcnt(0)
	v_add_f32_e32 v130, v130, v131
	s_nop 1
	v_mov_b32_dpp v140, v139 quad_perm:[2,3,0,1] row_mask:0xf bank_mask:0xf
	s_nop 1
	v_mov_b32_dpp v131, v130 quad_perm:[2,3,0,1] row_mask:0xf bank_mask:0xf
	v_fmamk_f32 v133, v138, 0x3c000000, v119
	s_nop 1
	v_mov_b32_dpp v141, v132 row_mirror row_mask:0xf bank_mask:0xf
	s_waitcnt lgkmcnt(0)
	v_add_f32_e32 v138, v139, v140
	s_waitcnt lgkmcnt(0)
	v_add_f32_e32 v130, v130, v131
	s_nop 1
	v_mov_b32_dpp v139, v138 row_half_mirror row_mask:0xf bank_mask:0xf
	s_nop 1
	v_mov_b32_dpp v131, v130 row_half_mirror row_mask:0xf bank_mask:0xf
	s_waitcnt lgkmcnt(0)
	v_add_f32_e32 v140, v132, v141
	ds_bpermute_b32 v135, v137, v140
	v_rsq_f32_e32 v132, v133
	s_waitcnt lgkmcnt(1)
	v_add_f32_e32 v138, v138, v139
	s_waitcnt lgkmcnt(1)
	v_add_f32_e32 v130, v130, v131
	s_nop 1
	v_mov_b32_dpp v139, v138 row_mirror row_mask:0xf bank_mask:0xf
	s_nop 1
	v_mov_b32_dpp v131, v130 row_mirror row_mask:0xf bank_mask:0xf
	s_waitcnt lgkmcnt(0)
	v_add_f32_e32 v133, v140, v135
	v_fmamk_f32 v133, v133, 0x3c000000, v119
	v_rsq_f32_e32 v133, v133
	s_waitcnt lgkmcnt(0)
	v_add_f32_e32 v135, v138, v139
	s_waitcnt lgkmcnt(0)
	v_add_f32_e32 v130, v130, v131
	ds_bpermute_b32 v136, v137, v135
	ds_bpermute_b32 v137, v137, v130
	s_waitcnt vmcnt(0)
	v_mul_f32_e32 v49, v49, v134
	s_waitcnt lgkmcnt(1)
	v_add_f32_e32 v131, v135, v136
	s_waitcnt lgkmcnt(0)
	v_add_f32_e32 v130, v130, v137
	v_mul_f32_e32 v137, v48, v71
	global_load_dword v48, v121, s[66:67] offset:128
	global_load_dword v138, v121, s[66:67] offset:256
	s_nop 0
	global_load_dword v121, v121, s[66:67] offset:384
	v_add_u32_e32 v136, s73, v80
	v_or_b32_e32 v135, s72, v64
	v_mul_lo_u32 v140, v136, s70
	v_mul_f32_e32 v137, v137, v134
	v_add_u32_e32 v136, v140, v135
	v_cvt_pk_bf16_f32 v139, v137, s0
	v_ashrrev_i32_e32 v137, 31, v136
	v_lshl_add_u64 v[136:137], v[136:137], 1, s[6:7]
	global_store_short v[136:137], v139, off sc1
	v_or_b32_e32 v139, 0x600, v140
	v_add_u32_e32 v136, v139, v135
	v_ashrrev_i32_e32 v137, 31, v136
	v_cvt_pk_bf16_f32 v49, v49, s0
	v_lshl_add_u64 v[136:137], v[136:137], 1, s[6:7]
	v_add_u32_e32 v141, 0xc00, v140
	global_store_short v[136:137], v49, off sc1
	v_mul_f32_e32 v49, v50, v73
	v_add_u32_e32 v136, v141, v135
	v_mul_f32_e32 v49, v49, v134
	v_ashrrev_i32_e32 v137, 31, v136
	v_cvt_pk_bf16_f32 v49, v49, s0
	v_lshl_add_u64 v[136:137], v[136:137], 1, s[6:7]
	global_store_short v[136:137], v49, off sc1
	v_add_u32_e32 v136, 0x1200, v140
	v_mul_f32_e32 v49, v51, v72
	v_add_u32_e32 v50, v136, v135
	v_mul_f32_e32 v49, v49, v134
	v_ashrrev_i32_e32 v51, 31, v50
	v_cvt_pk_bf16_f32 v49, v49, s0
	v_lshl_add_u64 v[50:51], v[50:51], 1, s[6:7]
	global_store_short v[50:51], v49, off sc1
	v_mul_f32_e32 v49, v52, v122
	v_add_u32_e32 v52, 0x3000, v140
	v_add_u32_e32 v50, v52, v135
	v_mul_f32_e32 v49, v49, v134
	v_ashrrev_i32_e32 v51, 31, v50
	v_cvt_pk_bf16_f32 v49, v49, s0
	v_lshl_add_u64 v[50:51], v[50:51], 1, s[6:7]
	global_store_short v[50:51], v49, off sc1
	v_mul_f32_e32 v49, v53, v123
	v_add_u32_e32 v53, 0x3600, v140
	v_add_u32_e32 v50, v53, v135
	v_mul_f32_e32 v49, v49, v134
	v_ashrrev_i32_e32 v51, 31, v50
	v_cvt_pk_bf16_f32 v49, v49, s0
	v_lshl_add_u64 v[50:51], v[50:51], 1, s[6:7]
	global_store_short v[50:51], v49, off sc1
	v_mul_f32_e32 v49, v54, v124
	v_add_u32_e32 v54, 0x3c00, v140
	v_add_u32_e32 v50, v54, v135
	v_mul_f32_e32 v49, v49, v134
	v_ashrrev_i32_e32 v51, 31, v50
	v_cvt_pk_bf16_f32 v49, v49, s0
	v_lshl_add_u64 v[50:51], v[50:51], 1, s[6:7]
	global_store_short v[50:51], v49, off sc1
	v_mul_f32_e32 v49, v55, v126
	v_add_u32_e32 v55, 0x4200, v140
	v_add_u32_e32 v50, v55, v135
	v_mul_f32_e32 v49, v49, v134
	v_ashrrev_i32_e32 v51, 31, v50
	v_cvt_pk_bf16_f32 v49, v49, s0
	v_lshl_add_u64 v[50:51], v[50:51], 1, s[6:7]
	global_store_short v[50:51], v49, off sc1
	v_mul_f32_e32 v49, v56, v127
	v_add_u32_e32 v56, 0x6000, v140
	v_add_u32_e32 v50, v56, v135
	v_mul_f32_e32 v49, v49, v134
	v_ashrrev_i32_e32 v51, 31, v50
	v_cvt_pk_bf16_f32 v49, v49, s0
	v_lshl_add_u64 v[50:51], v[50:51], 1, s[6:7]
	global_store_short v[50:51], v49, off sc1
	v_mul_f32_e32 v49, v57, v125
	v_add_u32_e32 v57, 0x6600, v140
	v_add_u32_e32 v50, v57, v135
	v_mul_f32_e32 v49, v49, v134
	v_ashrrev_i32_e32 v51, 31, v50
	v_cvt_pk_bf16_f32 v49, v49, s0
	v_lshl_add_u64 v[50:51], v[50:51], 1, s[6:7]
	global_store_short v[50:51], v49, off sc1
	v_mul_f32_e32 v49, v58, v128
	v_add_u32_e32 v58, 0x6c00, v140
	v_add_u32_e32 v50, v58, v135
	v_mul_f32_e32 v49, v49, v134
	v_ashrrev_i32_e32 v51, 31, v50
	v_cvt_pk_bf16_f32 v49, v49, s0
	v_lshl_add_u64 v[50:51], v[50:51], 1, s[6:7]
	global_store_short v[50:51], v49, off sc1
	v_mul_f32_e32 v49, v59, v129
	v_add_u32_e32 v59, 0x7200, v140
	v_add_u32_e32 v50, v59, v135
	v_mul_f32_e32 v49, v49, v134
	v_ashrrev_i32_e32 v51, 31, v50
	v_cvt_pk_bf16_f32 v49, v49, s0
	v_lshl_add_u64 v[50:51], v[50:51], 1, s[6:7]
	global_store_short v[50:51], v49, off sc1
	v_mul_f32_e32 v49, v60, v132
	v_add_u32_e32 v60, 0x9000, v140
	v_add_u32_e32 v50, v60, v135
	v_mul_f32_e32 v49, v49, v134
	v_ashrrev_i32_e32 v51, 31, v50
	v_fmamk_f32 v131, v131, 0x3c000000, v119
	v_cvt_pk_bf16_f32 v49, v49, s0
	v_lshl_add_u64 v[50:51], v[50:51], 1, s[6:7]
	v_rsq_f32_e32 v131, v131
	global_store_short v[50:51], v49, off sc1
	v_mul_f32_e32 v49, v61, v133
	v_add_u32_e32 v61, 0x9600, v140
	v_add_u32_e32 v50, v61, v135
	v_mul_f32_e32 v49, v49, v134
	v_ashrrev_i32_e32 v51, 31, v50
	v_fmamk_f32 v130, v130, 0x3c000000, v119
	v_cvt_pk_bf16_f32 v49, v49, s0
	v_lshl_add_u64 v[50:51], v[50:51], 1, s[6:7]
	v_rsq_f32_e32 v130, v130
	global_store_short v[50:51], v49, off sc1
	v_mul_f32_e32 v49, v62, v131
	v_add_u32_e32 v62, 0x9c00, v140
	v_add_u32_e32 v50, v62, v135
	v_mul_f32_e32 v49, v134, v49
	v_ashrrev_i32_e32 v51, 31, v50
	v_cvt_pk_bf16_f32 v49, v49, s0
	v_lshl_add_u64 v[50:51], v[50:51], 1, s[6:7]
	global_store_short v[50:51], v49, off sc1
	v_mul_f32_e32 v49, v63, v130
	v_add_u32_e32 v63, 0xa200, v140
	v_add_u32_e32 v50, v63, v135
	v_mul_f32_e32 v49, v134, v49
	v_ashrrev_i32_e32 v51, 31, v50
	v_cvt_pk_bf16_f32 v49, v49, s0
	v_lshl_add_u64 v[50:51], v[50:51], 1, s[6:7]
	global_store_short v[50:51], v49, off sc1
	v_or_b32_e32 v49, s72, v65
	v_add_u32_e32 v50, v140, v49
	s_waitcnt vmcnt(18)
	v_mul_f32_e32 v32, v32, v48
	v_ashrrev_i32_e32 v51, 31, v50
	v_cvt_pk_bf16_f32 v32, v32, s0
	v_lshl_add_u64 v[50:51], v[50:51], 1, s[6:7]
	global_store_short v[50:51], v32, off sc1
	v_mul_f32_e32 v32, v33, v70
	v_mul_f32_e32 v32, v32, v48
	v_cvt_pk_bf16_f32 v50, v32, s0
	v_add_u32_e32 v32, v139, v49
	v_ashrrev_i32_e32 v33, 31, v32
	v_lshl_add_u64 v[32:33], v[32:33], 1, s[6:7]
	global_store_short v[32:33], v50, off sc1
	v_mul_f32_e32 v32, v34, v73
	v_mul_f32_e32 v32, v32, v48
	v_cvt_pk_bf16_f32 v34, v32, s0
	v_add_u32_e32 v32, v141, v49
	v_ashrrev_i32_e32 v33, 31, v32
	v_lshl_add_u64 v[32:33], v[32:33], 1, s[6:7]
	global_store_short v[32:33], v34, off sc1
	v_mul_f32_e32 v32, v35, v72
	v_mul_f32_e32 v32, v32, v48
	v_cvt_pk_bf16_f32 v34, v32, s0
	v_add_u32_e32 v32, v136, v49
	v_ashrrev_i32_e32 v33, 31, v32
	v_lshl_add_u64 v[32:33], v[32:33], 1, s[6:7]
	global_store_short v[32:33], v34, off sc1
	v_mul_f32_e32 v32, v36, v122
	v_mul_f32_e32 v32, v32, v48
	v_cvt_pk_bf16_f32 v34, v32, s0
	v_add_u32_e32 v32, v52, v49
	v_ashrrev_i32_e32 v33, 31, v32
	v_lshl_add_u64 v[32:33], v[32:33], 1, s[6:7]
	global_store_short v[32:33], v34, off sc1
	v_mul_f32_e32 v32, v37, v123
	v_mul_f32_e32 v32, v32, v48
	v_cvt_pk_bf16_f32 v34, v32, s0
	v_add_u32_e32 v32, v53, v49
	v_ashrrev_i32_e32 v33, 31, v32
	v_lshl_add_u64 v[32:33], v[32:33], 1, s[6:7]
	global_store_short v[32:33], v34, off sc1
	v_mul_f32_e32 v32, v38, v124
	v_mul_f32_e32 v32, v32, v48
	v_cvt_pk_bf16_f32 v34, v32, s0
	v_add_u32_e32 v32, v54, v49
	v_ashrrev_i32_e32 v33, 31, v32
	v_lshl_add_u64 v[32:33], v[32:33], 1, s[6:7]
	global_store_short v[32:33], v34, off sc1
	v_mul_f32_e32 v32, v39, v126
	v_mul_f32_e32 v32, v32, v48
	v_cvt_pk_bf16_f32 v34, v32, s0
	v_add_u32_e32 v32, v55, v49
	v_ashrrev_i32_e32 v33, 31, v32
	v_lshl_add_u64 v[32:33], v[32:33], 1, s[6:7]
	global_store_short v[32:33], v34, off sc1
	v_mul_f32_e32 v32, v40, v127
	v_mul_f32_e32 v32, v32, v48
	v_cvt_pk_bf16_f32 v34, v32, s0
	v_add_u32_e32 v32, v56, v49
	v_ashrrev_i32_e32 v33, 31, v32
	v_lshl_add_u64 v[32:33], v[32:33], 1, s[6:7]
	global_store_short v[32:33], v34, off sc1
	v_mul_f32_e32 v32, v41, v125
	v_mul_f32_e32 v32, v32, v48
	v_cvt_pk_bf16_f32 v34, v32, s0
	v_add_u32_e32 v32, v57, v49
	v_ashrrev_i32_e32 v33, 31, v32
	v_lshl_add_u64 v[32:33], v[32:33], 1, s[6:7]
	global_store_short v[32:33], v34, off sc1
	v_mul_f32_e32 v32, v42, v128
	v_mul_f32_e32 v32, v32, v48
	v_cvt_pk_bf16_f32 v34, v32, s0
	v_add_u32_e32 v32, v58, v49
	v_ashrrev_i32_e32 v33, 31, v32
	v_lshl_add_u64 v[32:33], v[32:33], 1, s[6:7]
	global_store_short v[32:33], v34, off sc1
	v_mul_f32_e32 v32, v43, v129
	v_mul_f32_e32 v32, v32, v48
	v_cvt_pk_bf16_f32 v34, v32, s0
	v_add_u32_e32 v32, v59, v49
	v_ashrrev_i32_e32 v33, 31, v32
	v_lshl_add_u64 v[32:33], v[32:33], 1, s[6:7]
	global_store_short v[32:33], v34, off sc1
	v_mul_f32_e32 v32, v44, v132
	v_mul_f32_e32 v32, v32, v48
	v_cvt_pk_bf16_f32 v34, v32, s0
	v_add_u32_e32 v32, v60, v49
	v_ashrrev_i32_e32 v33, 31, v32
	v_lshl_add_u64 v[32:33], v[32:33], 1, s[6:7]
	global_store_short v[32:33], v34, off sc1
	v_mul_f32_e32 v32, v45, v133
	v_mul_f32_e32 v32, v32, v48
	v_cvt_pk_bf16_f32 v34, v32, s0
	v_add_u32_e32 v32, v61, v49
	v_ashrrev_i32_e32 v33, 31, v32
	v_lshl_add_u64 v[32:33], v[32:33], 1, s[6:7]
	global_store_short v[32:33], v34, off sc1
	v_mul_f32_e32 v32, v46, v131
	v_mul_f32_e32 v32, v32, v48
	v_cvt_pk_bf16_f32 v34, v32, s0
	v_add_u32_e32 v32, v62, v49
	v_ashrrev_i32_e32 v33, 31, v32
	v_lshl_add_u64 v[32:33], v[32:33], 1, s[6:7]
	global_store_short v[32:33], v34, off sc1
	v_mul_f32_e32 v32, v47, v130
	v_mul_f32_e32 v32, v32, v48
	v_cvt_pk_bf16_f32 v34, v32, s0
	v_add_u32_e32 v32, v63, v49
	v_ashrrev_i32_e32 v33, 31, v32
	v_lshl_add_u64 v[32:33], v[32:33], 1, s[6:7]
	global_store_short v[32:33], v34, off sc1
	v_add_u32_e32 v34, s72, v74
	v_add_u32_e32 v32, v140, v34
	s_waitcnt vmcnt(33)
	v_mul_f32_e32 v16, v16, v138
	v_ashrrev_i32_e32 v33, 31, v32
	v_cvt_pk_bf16_f32 v16, v16, s0
	v_lshl_add_u64 v[32:33], v[32:33], 1, s[6:7]
	global_store_short v[32:33], v16, off sc1
	v_mul_f32_e32 v16, v17, v70
	v_mul_f32_e32 v16, v16, v138
	v_cvt_pk_bf16_f32 v32, v16, s0
	v_add_u32_e32 v16, v139, v34
	v_ashrrev_i32_e32 v17, 31, v16
	v_lshl_add_u64 v[16:17], v[16:17], 1, s[6:7]
	global_store_short v[16:17], v32, off sc1
	v_mul_f32_e32 v16, v18, v73
	v_mul_f32_e32 v16, v16, v138
	v_cvt_pk_bf16_f32 v18, v16, s0
	v_add_u32_e32 v16, v141, v34
	v_ashrrev_i32_e32 v17, 31, v16
	v_lshl_add_u64 v[16:17], v[16:17], 1, s[6:7]
	global_store_short v[16:17], v18, off sc1
	v_mul_f32_e32 v16, v19, v72
	v_mul_f32_e32 v16, v16, v138
	v_cvt_pk_bf16_f32 v18, v16, s0
	v_add_u32_e32 v16, v136, v34
	v_ashrrev_i32_e32 v17, 31, v16
	v_lshl_add_u64 v[16:17], v[16:17], 1, s[6:7]
	global_store_short v[16:17], v18, off sc1
	v_mul_f32_e32 v16, v20, v122
	v_mul_f32_e32 v16, v16, v138
	v_cvt_pk_bf16_f32 v18, v16, s0
	v_add_u32_e32 v16, v52, v34
	v_ashrrev_i32_e32 v17, 31, v16
	v_lshl_add_u64 v[16:17], v[16:17], 1, s[6:7]
	global_store_short v[16:17], v18, off sc1
	v_mul_f32_e32 v16, v21, v123
	v_mul_f32_e32 v16, v16, v138
	v_cvt_pk_bf16_f32 v18, v16, s0
	v_add_u32_e32 v16, v53, v34
	v_ashrrev_i32_e32 v17, 31, v16
	v_lshl_add_u64 v[16:17], v[16:17], 1, s[6:7]
	global_store_short v[16:17], v18, off sc1
	v_mul_f32_e32 v16, v22, v124
	v_mul_f32_e32 v16, v16, v138
	v_cvt_pk_bf16_f32 v18, v16, s0
	v_add_u32_e32 v16, v54, v34
	v_ashrrev_i32_e32 v17, 31, v16
	v_lshl_add_u64 v[16:17], v[16:17], 1, s[6:7]
	global_store_short v[16:17], v18, off sc1
	v_mul_f32_e32 v16, v23, v126
	v_mul_f32_e32 v16, v16, v138
	v_cvt_pk_bf16_f32 v18, v16, s0
	v_add_u32_e32 v16, v55, v34
	v_ashrrev_i32_e32 v17, 31, v16
	v_lshl_add_u64 v[16:17], v[16:17], 1, s[6:7]
	global_store_short v[16:17], v18, off sc1
	v_mul_f32_e32 v16, v24, v127
	v_mul_f32_e32 v16, v16, v138
	v_cvt_pk_bf16_f32 v18, v16, s0
	v_add_u32_e32 v16, v56, v34
	v_ashrrev_i32_e32 v17, 31, v16
	v_lshl_add_u64 v[16:17], v[16:17], 1, s[6:7]
	global_store_short v[16:17], v18, off sc1
	v_mul_f32_e32 v16, v25, v125
	v_mul_f32_e32 v16, v16, v138
	v_cvt_pk_bf16_f32 v18, v16, s0
	v_add_u32_e32 v16, v57, v34
	v_ashrrev_i32_e32 v17, 31, v16
	v_lshl_add_u64 v[16:17], v[16:17], 1, s[6:7]
	global_store_short v[16:17], v18, off sc1
	v_mul_f32_e32 v16, v26, v128
	v_mul_f32_e32 v16, v16, v138
	v_cvt_pk_bf16_f32 v18, v16, s0
	v_add_u32_e32 v16, v58, v34
	v_ashrrev_i32_e32 v17, 31, v16
	v_lshl_add_u64 v[16:17], v[16:17], 1, s[6:7]
	global_store_short v[16:17], v18, off sc1
	v_mul_f32_e32 v16, v27, v129
	v_mul_f32_e32 v16, v16, v138
	v_cvt_pk_bf16_f32 v18, v16, s0
	v_add_u32_e32 v16, v59, v34
	v_ashrrev_i32_e32 v17, 31, v16
	v_lshl_add_u64 v[16:17], v[16:17], 1, s[6:7]
	global_store_short v[16:17], v18, off sc1
	v_mul_f32_e32 v16, v28, v132
	v_mul_f32_e32 v16, v16, v138
	v_cvt_pk_bf16_f32 v18, v16, s0
	v_add_u32_e32 v16, v60, v34
	v_ashrrev_i32_e32 v17, 31, v16
	v_lshl_add_u64 v[16:17], v[16:17], 1, s[6:7]
	global_store_short v[16:17], v18, off sc1
	v_mul_f32_e32 v16, v29, v133
	v_mul_f32_e32 v16, v16, v138
	v_cvt_pk_bf16_f32 v18, v16, s0
	v_add_u32_e32 v16, v61, v34
	v_ashrrev_i32_e32 v17, 31, v16
	v_lshl_add_u64 v[16:17], v[16:17], 1, s[6:7]
	global_store_short v[16:17], v18, off sc1
	v_mul_f32_e32 v16, v30, v131
	v_mul_f32_e32 v16, v16, v138
	v_cvt_pk_bf16_f32 v18, v16, s0
	v_add_u32_e32 v16, v62, v34
	v_ashrrev_i32_e32 v17, 31, v16
	v_lshl_add_u64 v[16:17], v[16:17], 1, s[6:7]
	global_store_short v[16:17], v18, off sc1
	v_mul_f32_e32 v16, v31, v130
	v_mul_f32_e32 v16, v16, v138
	v_cvt_pk_bf16_f32 v18, v16, s0
	v_add_u32_e32 v16, v63, v34
	v_ashrrev_i32_e32 v17, 31, v16
	v_lshl_add_u64 v[16:17], v[16:17], 1, s[6:7]
	global_store_short v[16:17], v18, off sc1
	v_add_u32_e32 v18, s72, v98
	v_add_u32_e32 v16, v140, v18
	s_waitcnt vmcnt(48)
	v_mul_f32_e32 v0, v0, v121
	v_ashrrev_i32_e32 v17, 31, v16
	v_cvt_pk_bf16_f32 v0, v0, s0
	v_lshl_add_u64 v[16:17], v[16:17], 1, s[6:7]
	global_store_short v[16:17], v0, off sc1
	v_mul_f32_e32 v0, v1, v70
	v_mul_f32_e32 v0, v0, v121
	v_cvt_pk_bf16_f32 v16, v0, s0
	v_add_u32_e32 v0, v139, v18
	v_ashrrev_i32_e32 v1, 31, v0
	v_lshl_add_u64 v[0:1], v[0:1], 1, s[6:7]
	global_store_short v[0:1], v16, off sc1
	v_mul_f32_e32 v0, v2, v73
	v_mul_f32_e32 v0, v0, v121
	v_cvt_pk_bf16_f32 v2, v0, s0
	v_add_u32_e32 v0, v141, v18
	v_ashrrev_i32_e32 v1, 31, v0
	v_lshl_add_u64 v[0:1], v[0:1], 1, s[6:7]
	global_store_short v[0:1], v2, off sc1
	v_mul_f32_e32 v0, v3, v72
	v_mul_f32_e32 v0, v0, v121
	v_cvt_pk_bf16_f32 v2, v0, s0
	v_add_u32_e32 v0, v136, v18
	v_ashrrev_i32_e32 v1, 31, v0
	v_lshl_add_u64 v[0:1], v[0:1], 1, s[6:7]
	global_store_short v[0:1], v2, off sc1
	v_mul_f32_e32 v0, v4, v122
	v_mul_f32_e32 v0, v0, v121
	v_cvt_pk_bf16_f32 v2, v0, s0
	v_add_u32_e32 v0, v52, v18
	v_ashrrev_i32_e32 v1, 31, v0
	v_lshl_add_u64 v[0:1], v[0:1], 1, s[6:7]
	global_store_short v[0:1], v2, off sc1
	v_mul_f32_e32 v0, v5, v123
	v_mul_f32_e32 v0, v0, v121
	v_cvt_pk_bf16_f32 v2, v0, s0
	v_add_u32_e32 v0, v53, v18
	v_ashrrev_i32_e32 v1, 31, v0
	v_lshl_add_u64 v[0:1], v[0:1], 1, s[6:7]
	global_store_short v[0:1], v2, off sc1
	v_mul_f32_e32 v0, v6, v124
	v_mul_f32_e32 v0, v0, v121
	v_cvt_pk_bf16_f32 v2, v0, s0
	v_add_u32_e32 v0, v54, v18
	v_ashrrev_i32_e32 v1, 31, v0
	v_lshl_add_u64 v[0:1], v[0:1], 1, s[6:7]
	global_store_short v[0:1], v2, off sc1
	v_mul_f32_e32 v0, v7, v126
	v_mul_f32_e32 v0, v0, v121
	v_cvt_pk_bf16_f32 v2, v0, s0
	v_add_u32_e32 v0, v55, v18
	v_ashrrev_i32_e32 v1, 31, v0
	v_lshl_add_u64 v[0:1], v[0:1], 1, s[6:7]
	global_store_short v[0:1], v2, off sc1
	v_mul_f32_e32 v0, v8, v127
	v_mul_f32_e32 v0, v0, v121
	v_cvt_pk_bf16_f32 v2, v0, s0
	v_add_u32_e32 v0, v56, v18
	v_ashrrev_i32_e32 v1, 31, v0
	v_lshl_add_u64 v[0:1], v[0:1], 1, s[6:7]
	global_store_short v[0:1], v2, off sc1
	v_mul_f32_e32 v0, v9, v125
	v_mul_f32_e32 v0, v0, v121
	v_cvt_pk_bf16_f32 v2, v0, s0
	v_add_u32_e32 v0, v57, v18
	v_ashrrev_i32_e32 v1, 31, v0
	v_lshl_add_u64 v[0:1], v[0:1], 1, s[6:7]
	global_store_short v[0:1], v2, off sc1
	v_mul_f32_e32 v0, v10, v128
	v_mul_f32_e32 v0, v0, v121
	v_cvt_pk_bf16_f32 v2, v0, s0
	v_add_u32_e32 v0, v58, v18
	v_ashrrev_i32_e32 v1, 31, v0
	v_lshl_add_u64 v[0:1], v[0:1], 1, s[6:7]
	global_store_short v[0:1], v2, off sc1
	v_mul_f32_e32 v0, v11, v129
	v_mul_f32_e32 v0, v0, v121
	v_cvt_pk_bf16_f32 v2, v0, s0
	v_add_u32_e32 v0, v59, v18
	v_ashrrev_i32_e32 v1, 31, v0
	v_lshl_add_u64 v[0:1], v[0:1], 1, s[6:7]
	global_store_short v[0:1], v2, off sc1
	v_mul_f32_e32 v0, v12, v132
	v_mul_f32_e32 v0, v0, v121
	v_cvt_pk_bf16_f32 v2, v0, s0
	v_add_u32_e32 v0, v60, v18
	v_ashrrev_i32_e32 v1, 31, v0
	v_lshl_add_u64 v[0:1], v[0:1], 1, s[6:7]
	global_store_short v[0:1], v2, off sc1
	v_mul_f32_e32 v0, v13, v133
	v_mul_f32_e32 v0, v0, v121
	v_cvt_pk_bf16_f32 v2, v0, s0
	v_add_u32_e32 v0, v61, v18
	v_ashrrev_i32_e32 v1, 31, v0
	v_lshl_add_u64 v[0:1], v[0:1], 1, s[6:7]
	global_store_short v[0:1], v2, off sc1
	v_mul_f32_e32 v0, v14, v131
	v_mul_f32_e32 v0, v0, v121
	v_cvt_pk_bf16_f32 v2, v0, s0
	v_add_u32_e32 v0, v62, v18
	v_ashrrev_i32_e32 v1, 31, v0
	v_lshl_add_u64 v[0:1], v[0:1], 1, s[6:7]
	global_store_short v[0:1], v2, off sc1
	v_mul_f32_e32 v0, v15, v130
	v_mul_f32_e32 v70, v0, v121
	v_add_u32_e32 v72, v63, v18
	s_branch .LBB0_575

.LBB0_653:
	s_and_b64 vcc, exec, s[0:1]
	s_cbranch_vccz .LBB0_646
	v_mov_b32_e32 v70, s63
	ds_read_b64 v[70:71], v70
	v_xor_b32_e32 v110, 2, v105
	v_add_u32_e32 v114, s48, v72
	v_xor_b32_e32 v111, 4, v105
	v_mul_f32_e32 v115, v32, v32
	s_waitcnt lgkmcnt(0)
	v_readfirstlane_b32 s0, v70
	v_readfirstlane_b32 s1, v71
	s_nop 4
	global_load_dword v109, v103, s[0:1] offset:768
	global_load_dword v108, v103, s[0:1] offset:896
	global_load_dword v107, v103, s[0:1] offset:1024
	global_load_dword v106, v103, s[0:1] offset:1152
	v_and_b32_e32 v70, 64, v105
	v_xor_b32_e32 v71, 1, v105
	v_add_u32_e32 v116, 64, v70
	v_cmp_lt_i32_e32 vcc, v71, v116
	v_mul_lo_u32 v70, v114, s64
	v_xor_b32_e32 v112, 8, v105
	v_cndmask_b32_e32 v114, v105, v71, vcc
	v_cmp_lt_i32_e32 vcc, v110, v116
	v_fmac_f32_e32 v115, v48, v48
	v_fmac_f32_e32 v115, v16, v16
	v_cndmask_b32_e32 v110, v105, v110, vcc
	v_cmp_lt_i32_e32 vcc, v111, v116
	v_fmac_f32_e32 v115, v0, v0
	v_xor_b32_e32 v113, 16, v105
	v_cndmask_b32_e32 v111, v105, v111, vcc
	v_cmp_lt_i32_e32 vcc, v112, v116
	v_mul_f32_e32 v118, v33, v33
	v_fmac_f32_e32 v118, v49, v49
	v_cndmask_b32_e32 v120, v105, v112, vcc
	v_lshlrev_b32_e32 v112, 2, v114
	s_nop 1
	v_mov_b32_dpp v114, v115 quad_perm:[1,0,3,2] row_mask:0xf bank_mask:0xf
	v_cmp_lt_i32_e32 vcc, v113, v116
	v_fmac_f32_e32 v118, v17, v17
	v_fmac_f32_e32 v118, v1, v1
	v_cndmask_b32_e32 v121, v105, v113, vcc
	v_lshlrev_b32_e32 v113, 2, v110
	s_waitcnt lgkmcnt(0)
	v_add_f32_e32 v110, v115, v114
	s_nop 1
	v_mov_b32_dpp v115, v110 quad_perm:[2,3,0,1] row_mask:0xf bank_mask:0xf
	v_lshlrev_b32_e32 v114, 2, v111
	s_nop 1
	v_mov_b32_dpp v122, v118 quad_perm:[1,0,3,2] row_mask:0xf bank_mask:0xf
	v_lshlrev_b32_e32 v111, 2, v120
	v_mul_f32_e32 v119, v34, v34
	s_waitcnt lgkmcnt(0)
	v_add_f32_e32 v115, v110, v115
	s_nop 1
	v_mov_b32_dpp v123, v115 row_half_mirror row_mask:0xf bank_mask:0xf
	v_lshlrev_b32_e32 v110, 2, v121
	s_waitcnt lgkmcnt(0)
	v_add_f32_e32 v118, v118, v122
	s_nop 1
	v_mov_b32_dpp v122, v118 quad_perm:[2,3,0,1] row_mask:0xf bank_mask:0xf
	v_fmac_f32_e32 v119, v50, v50
	s_waitcnt lgkmcnt(0)
	v_add_f32_e32 v115, v115, v123
	s_nop 1
	v_mov_b32_dpp v121, v115 row_mirror row_mask:0xf bank_mask:0xf
	v_fmac_f32_e32 v119, v18, v18
	s_waitcnt lgkmcnt(0)
	v_add_f32_e32 v118, v118, v122
	s_nop 1
	v_mov_b32_dpp v120, v118 row_half_mirror row_mask:0xf bank_mask:0xf
	v_fmac_f32_e32 v119, v2, v2
	s_waitcnt lgkmcnt(0)
	v_add_f32_e32 v115, v115, v121
	ds_bpermute_b32 v121, v110, v115
	s_nop 1
	v_mov_b32_dpp v122, v119 quad_perm:[1,0,3,2] row_mask:0xf bank_mask:0xf
	s_waitcnt lgkmcnt(1)
	v_add_f32_e32 v118, v118, v120
	s_nop 1
	v_mov_b32_dpp v120, v118 row_mirror row_mask:0xf bank_mask:0xf
	s_mul_i32 s0, s49, 0xc0
	s_waitcnt lgkmcnt(0)
	v_add_f32_e32 v115, v115, v121
	v_fmamk_f32 v115, v115, 0x3c000000, v104
	v_rsq_f32_e32 v115, v115
	s_ashr_i32 s1, s0, 31
	v_lshl_add_u64 v[116:117], s[0:1], 1, v[68:69]
	v_ashrrev_i32_e32 v71, 31, v70
	v_mul_f32_e32 v48, v48, v115
	v_mul_f32_e32 v16, v16, v115
	v_mul_f32_e32 v32, v32, v115
	v_lshl_add_u64 v[70:71], v[70:71], 1, v[116:117]
	s_waitcnt lgkmcnt(0)
	v_add_f32_e32 v116, v118, v120
	v_add_f32_e32 v118, v119, v122
	ds_bpermute_b32 v117, v110, v116
	v_mul_f32_e32 v0, v0, v115
	s_waitcnt lgkmcnt(0)
	v_add_f32_e32 v116, v116, v117
	v_fmamk_f32 v116, v116, 0x3c000000, v104
	v_rsq_f32_e32 v116, v116
	s_waitcnt vmcnt(3)
	v_mul_f32_e32 v48, v109, v48
	s_waitcnt vmcnt(2)
	v_mul_f32_e32 v32, v108, v32
	s_waitcnt vmcnt(1)
	v_mul_f32_e32 v16, v107, v16
	v_cvt_pk_bf16_f32 v48, v48, s0
	v_cvt_pk_bf16_f32 v16, v16, s0
	v_cvt_pk_bf16_f32 v32, v32, s0
	global_store_short v[70:71], v48, off sc1
	global_store_short v[70:71], v32, off offset:64 sc1
	global_store_short v[70:71], v16, off offset:128 sc1
	s_nop 1
	v_mov_b32_dpp v16, v118 quad_perm:[2,3,0,1] row_mask:0xf bank_mask:0xf
	s_waitcnt vmcnt(3)
	v_mul_f32_e32 v0, v106, v0
	v_cvt_pk_bf16_f32 v0, v0, s0
	global_store_short v[70:71], v0, off offset:192 sc1
	v_mul_f32_e32 v0, v49, v116
	s_waitcnt lgkmcnt(0)
	v_add_f32_e32 v16, v118, v16
	s_nop 1
	v_mov_b32_dpp v32, v16 row_half_mirror row_mask:0xf bank_mask:0xf
	v_mul_f32_e32 v0, v109, v0
	v_cvt_pk_bf16_f32 v0, v0, s0
	global_store_short v[70:71], v0, off offset:3072 sc1
	v_mul_f32_e32 v0, v33, v116
	s_waitcnt lgkmcnt(0)
	v_add_f32_e32 v16, v16, v32
	s_nop 1
	v_mov_b32_dpp v32, v16 row_mirror row_mask:0xf bank_mask:0xf
	v_mul_f32_e32 v0, v108, v0
	v_cvt_pk_bf16_f32 v0, v0, s0
	global_store_short v[70:71], v0, off offset:3136 sc1
	v_mul_f32_e32 v0, v17, v116
	s_waitcnt lgkmcnt(0)
	v_add_f32_e32 v16, v16, v32
	ds_bpermute_b32 v17, v110, v16
	v_mul_f32_e32 v0, v107, v0
	v_cvt_pk_bf16_f32 v0, v0, s0
	global_store_short v[70:71], v0, off offset:3200 sc1
	v_mul_f32_e32 v0, v1, v116
	s_waitcnt lgkmcnt(0)
	v_add_f32_e32 v1, v16, v17
	v_fmamk_f32 v1, v1, 0x3c000000, v104
	v_rsq_f32_e32 v16, v1
	v_mul_f32_e32 v1, v35, v35
	v_fmac_f32_e32 v1, v51, v51
	v_fmac_f32_e32 v1, v19, v19
	v_fmac_f32_e32 v1, v3, v3
	s_nop 1
	v_mov_b32_dpp v17, v1 quad_perm:[1,0,3,2] row_mask:0xf bank_mask:0xf
	v_mul_f32_e32 v0, v106, v0
	v_cvt_pk_bf16_f32 v0, v0, s0
	global_store_short v[70:71], v0, off offset:3264 sc1
	v_mul_f32_e32 v0, v50, v16
	s_waitcnt lgkmcnt(0)
	v_add_f32_e32 v17, v1, v17
	s_nop 1
	v_mov_b32_dpp v33, v17 quad_perm:[2,3,0,1] row_mask:0xf bank_mask:0xf
	v_mul_f32_e32 v0, v109, v0
	v_cvt_pk_bf16_f32 v32, v0, s0
	v_add_co_u32_e32 v0, vcc, s54, v70
	s_waitcnt lgkmcnt(0)
	v_add_f32_e32 v17, v17, v33
	s_nop 1
	v_mov_b32_dpp v33, v17 row_half_mirror row_mask:0xf bank_mask:0xf
	v_addc_co_u32_e32 v1, vcc, 0, v71, vcc
	global_store_short v[0:1], v32, off offset:2048 sc1
	v_mul_f32_e32 v32, v34, v16
	s_waitcnt lgkmcnt(0)
	v_add_f32_e32 v17, v17, v33
	s_nop 1
	v_mov_b32_dpp v33, v17 row_mirror row_mask:0xf bank_mask:0xf
	v_mul_f32_e32 v32, v108, v32
	v_cvt_pk_bf16_f32 v32, v32, s0
	global_store_short v[0:1], v32, off offset:2112 sc1
	v_mul_f32_e32 v18, v18, v16
	s_waitcnt lgkmcnt(0)
	v_add_f32_e32 v17, v17, v33
	ds_bpermute_b32 v32, v110, v17
	v_mul_f32_e32 v2, v2, v16
	v_mul_f32_e32 v18, v107, v18
	v_cvt_pk_bf16_f32 v18, v18, s0
	global_store_short v[0:1], v18, off offset:2176 sc1
	s_waitcnt lgkmcnt(0)
	v_add_f32_e32 v16, v17, v32
	v_mul_f32_e32 v17, v36, v36
	v_fmac_f32_e32 v17, v52, v52
	v_fmac_f32_e32 v17, v20, v20
	v_fmac_f32_e32 v17, v4, v4
	s_nop 1
	v_mov_b32_dpp v18, v17 quad_perm:[1,0,3,2] row_mask:0xf bank_mask:0xf
	v_fmamk_f32 v16, v16, 0x3c000000, v104
	v_rsq_f32_e32 v16, v16
	v_mul_f32_e32 v2, v106, v2
	v_cvt_pk_bf16_f32 v2, v2, s0
	s_waitcnt lgkmcnt(0)
	v_add_f32_e32 v17, v17, v18
	s_nop 1
	v_mov_b32_dpp v18, v17 quad_perm:[2,3,0,1] row_mask:0xf bank_mask:0xf
	global_store_short v[0:1], v2, off offset:2240 sc1
	v_mul_f32_e32 v0, v51, v16
	v_mul_f32_e32 v0, v109, v0
	v_cvt_pk_bf16_f32 v2, v0, s0
	s_waitcnt lgkmcnt(0)
	v_add_f32_e32 v17, v17, v18
	s_nop 1
	v_mov_b32_dpp v18, v17 row_half_mirror row_mask:0xf bank_mask:0xf
	v_add_co_u32_e32 v0, vcc, s55, v70
	s_waitcnt lgkmcnt(0)
	v_add_f32_e32 v17, v17, v18
	v_addc_co_u32_e32 v1, vcc, 0, v71, vcc
	s_nop 1
	v_mov_b32_dpp v18, v17 row_mirror row_mask:0xf bank_mask:0xf
	global_store_short v[0:1], v2, off offset:1024 sc1
	v_mul_f32_e32 v2, v35, v16
	v_mul_f32_e32 v2, v108, v2
	v_cvt_pk_bf16_f32 v2, v2, s0
	global_store_short v[0:1], v2, off offset:1088 sc1
	v_mul_f32_e32 v2, v19, v16
	v_mul_f32_e32 v2, v107, v2
	s_waitcnt lgkmcnt(0)
	v_add_f32_e32 v17, v17, v18
	v_cvt_pk_bf16_f32 v2, v2, s0
	ds_bpermute_b32 v18, v110, v17
	global_store_short v[0:1], v2, off offset:1152 sc1
	v_mul_f32_e32 v2, v3, v16
	v_mul_f32_e32 v16, v37, v37
	v_fmac_f32_e32 v16, v53, v53
	v_fmac_f32_e32 v16, v21, v21
	v_fmac_f32_e32 v16, v5, v5
	s_waitcnt lgkmcnt(0)
	v_add_f32_e32 v3, v17, v18
	s_nop 1
	v_mov_b32_dpp v17, v16 quad_perm:[1,0,3,2] row_mask:0xf bank_mask:0xf
	v_fmamk_f32 v3, v3, 0x3c000000, v104
	v_rsq_f32_e32 v3, v3
	v_mul_f32_e32 v2, v106, v2
	v_cvt_pk_bf16_f32 v2, v2, s0
	s_waitcnt lgkmcnt(0)
	v_add_f32_e32 v16, v16, v17
	s_nop 1
	v_mov_b32_dpp v17, v16 quad_perm:[2,3,0,1] row_mask:0xf bank_mask:0xf
	global_store_short v[0:1], v2, off offset:1216 sc1
	v_mul_f32_e32 v0, v52, v3
	v_mul_f32_e32 v0, v109, v0
	v_cvt_pk_bf16_f32 v2, v0, s0
	s_waitcnt lgkmcnt(0)
	v_add_f32_e32 v16, v16, v17
	s_nop 1
	v_mov_b32_dpp v17, v16 row_half_mirror row_mask:0xf bank_mask:0xf
	v_add_co_u32_e32 v0, vcc, s56, v70
	s_waitcnt lgkmcnt(0)
	v_add_f32_e32 v16, v16, v17
	v_addc_co_u32_e32 v1, vcc, 0, v71, vcc
	global_store_short v[0:1], v2, off sc1
	v_mul_f32_e32 v2, v36, v3
	v_mul_f32_e32 v2, v108, v2
	s_nop 1
	v_mov_b32_dpp v17, v16 row_mirror row_mask:0xf bank_mask:0xf
	v_cvt_pk_bf16_f32 v2, v2, s0
	global_store_short v[0:1], v2, off offset:64 sc1
	v_mul_f32_e32 v2, v20, v3
	v_mul_f32_e32 v2, v107, v2
	v_cvt_pk_bf16_f32 v2, v2, s0
	global_store_short v[0:1], v2, off offset:128 sc1
	v_mul_f32_e32 v2, v4, v3
	s_waitcnt lgkmcnt(0)
	v_add_f32_e32 v3, v16, v17
	v_mul_f32_e32 v16, v38, v38
	v_fmac_f32_e32 v16, v54, v54
	v_fmac_f32_e32 v16, v22, v22
	v_fmac_f32_e32 v16, v6, v6
	ds_bpermute_b32 v4, v110, v3
	s_nop 1
	v_mov_b32_dpp v17, v16 quad_perm:[1,0,3,2] row_mask:0xf bank_mask:0xf
	v_mul_f32_e32 v2, v106, v2
	v_cvt_pk_bf16_f32 v2, v2, s0
	global_store_short v[0:1], v2, off offset:192 sc1
	s_waitcnt lgkmcnt(0)
	v_add_f32_e32 v3, v3, v4
	s_waitcnt lgkmcnt(0)
	v_add_f32_e32 v4, v16, v17
	s_nop 1
	v_mov_b32_dpp v16, v4 quad_perm:[2,3,0,1] row_mask:0xf bank_mask:0xf
	v_fmamk_f32 v3, v3, 0x3c000000, v104
	v_rsq_f32_e32 v3, v3
	s_waitcnt lgkmcnt(0)
	v_add_f32_e32 v4, v4, v16
	s_nop 1
	v_mov_b32_dpp v16, v4 row_half_mirror row_mask:0xf bank_mask:0xf
	v_mul_f32_e32 v2, v53, v3
	v_mul_f32_e32 v2, v109, v2
	v_cvt_pk_bf16_f32 v2, v2, s0
	global_store_short v[0:1], v2, off offset:3072 sc1
	s_waitcnt lgkmcnt(0)
	v_add_f32_e32 v4, v4, v16
	s_nop 1
	v_mov_b32_dpp v16, v4 row_mirror row_mask:0xf bank_mask:0xf
	v_mul_f32_e32 v2, v37, v3
	v_mul_f32_e32 v2, v108, v2
	v_cvt_pk_bf16_f32 v2, v2, s0
	global_store_short v[0:1], v2, off offset:3136 sc1
	s_waitcnt lgkmcnt(0)
	v_add_f32_e32 v4, v4, v16
	ds_bpermute_b32 v16, v110, v4
	v_mul_f32_e32 v2, v21, v3
	v_mul_f32_e32 v2, v107, v2
	v_cvt_pk_bf16_f32 v2, v2, s0
	global_store_short v[0:1], v2, off offset:3200 sc1
	v_mul_f32_e32 v2, v5, v3
	s_waitcnt lgkmcnt(0)
	v_add_f32_e32 v3, v4, v16
	v_mul_f32_e32 v4, v39, v39
	v_fmac_f32_e32 v4, v55, v55
	v_fmac_f32_e32 v4, v23, v23
	v_fmac_f32_e32 v4, v7, v7
	s_nop 1
	v_mov_b32_dpp v5, v4 quad_perm:[1,0,3,2] row_mask:0xf bank_mask:0xf
	v_fmamk_f32 v3, v3, 0x3c000000, v104
	v_rsq_f32_e32 v3, v3
	v_mul_f32_e32 v2, v106, v2
	v_cvt_pk_bf16_f32 v2, v2, s0
	s_waitcnt lgkmcnt(0)
	v_add_f32_e32 v4, v4, v5
	s_nop 1
	v_mov_b32_dpp v5, v4 quad_perm:[2,3,0,1] row_mask:0xf bank_mask:0xf
	global_store_short v[0:1], v2, off offset:3264 sc1
	v_mul_f32_e32 v0, v54, v3
	v_mul_f32_e32 v0, v109, v0
	v_cvt_pk_bf16_f32 v2, v0, s0
	s_waitcnt lgkmcnt(0)
	v_add_f32_e32 v4, v4, v5
	s_nop 1
	v_mov_b32_dpp v5, v4 row_half_mirror row_mask:0xf bank_mask:0xf
	v_add_co_u32_e32 v0, vcc, s57, v70
	s_waitcnt lgkmcnt(0)
	v_add_f32_e32 v4, v4, v5
	s_nop 1
	v_mov_b32_dpp v5, v4 row_mirror row_mask:0xf bank_mask:0xf
	v_addc_co_u32_e32 v1, vcc, 0, v71, vcc
	global_store_short v[0:1], v2, off offset:2048 sc1
	v_mul_f32_e32 v2, v38, v3
	s_waitcnt lgkmcnt(0)
	v_add_f32_e32 v4, v4, v5
	v_mul_f32_e32 v2, v108, v2
	ds_bpermute_b32 v5, v110, v4
	v_cvt_pk_bf16_f32 v2, v2, s0
	global_store_short v[0:1], v2, off offset:2112 sc1
	v_mul_f32_e32 v2, v22, v3
	v_mul_f32_e32 v2, v107, v2
	v_cvt_pk_bf16_f32 v2, v2, s0
	global_store_short v[0:1], v2, off offset:2176 sc1
	v_mul_f32_e32 v2, v6, v3
	s_waitcnt lgkmcnt(0)
	v_add_f32_e32 v3, v4, v5
	v_mul_f32_e32 v4, v40, v40
	v_fmac_f32_e32 v4, v56, v56
	v_fmac_f32_e32 v4, v24, v24
	v_fmac_f32_e32 v4, v8, v8
	s_nop 1
	v_mov_b32_dpp v5, v4 quad_perm:[1,0,3,2] row_mask:0xf bank_mask:0xf
	v_fmamk_f32 v3, v3, 0x3c000000, v104
	v_rsq_f32_e32 v3, v3
	v_mul_f32_e32 v2, v106, v2
	v_cvt_pk_bf16_f32 v2, v2, s0
	s_waitcnt lgkmcnt(0)
	v_add_f32_e32 v4, v4, v5
	s_nop 1
	v_mov_b32_dpp v5, v4 quad_perm:[2,3,0,1] row_mask:0xf bank_mask:0xf
	global_store_short v[0:1], v2, off offset:2240 sc1
	v_mul_f32_e32 v0, v55, v3
	v_mul_f32_e32 v0, v109, v0
	v_cvt_pk_bf16_f32 v2, v0, s0
	s_waitcnt lgkmcnt(0)
	v_add_f32_e32 v4, v4, v5
	s_nop 1
	v_mov_b32_dpp v5, v4 row_half_mirror row_mask:0xf bank_mask:0xf
	v_add_co_u32_e32 v0, vcc, s58, v70
	s_waitcnt lgkmcnt(0)
	v_add_f32_e32 v4, v4, v5
	s_nop 1
	v_mov_b32_dpp v5, v4 row_mirror row_mask:0xf bank_mask:0xf
	v_addc_co_u32_e32 v1, vcc, 0, v71, vcc
	global_store_short v[0:1], v2, off offset:1024 sc1
	v_mul_f32_e32 v2, v39, v3
	s_waitcnt lgkmcnt(0)
	v_add_f32_e32 v4, v4, v5
	v_mul_f32_e32 v2, v108, v2
	ds_bpermute_b32 v5, v110, v4
	v_cvt_pk_bf16_f32 v2, v2, s0
	global_store_short v[0:1], v2, off offset:1088 sc1
	v_mul_f32_e32 v2, v23, v3
	v_mul_f32_e32 v2, v107, v2
	v_cvt_pk_bf16_f32 v2, v2, s0
	global_store_short v[0:1], v2, off offset:1152 sc1
	v_mul_f32_e32 v2, v7, v3
	s_waitcnt lgkmcnt(0)
	v_add_f32_e32 v3, v4, v5
	v_mul_f32_e32 v4, v41, v41
	v_fmac_f32_e32 v4, v57, v57
	v_fmac_f32_e32 v4, v25, v25
	v_fmac_f32_e32 v4, v9, v9
	s_nop 1
	v_mov_b32_dpp v5, v4 quad_perm:[1,0,3,2] row_mask:0xf bank_mask:0xf
	v_fmamk_f32 v3, v3, 0x3c000000, v104
	v_rsq_f32_e32 v3, v3
	v_mul_f32_e32 v2, v106, v2
	v_cvt_pk_bf16_f32 v2, v2, s0
	s_waitcnt lgkmcnt(0)
	v_add_f32_e32 v4, v4, v5
	s_nop 1
	v_mov_b32_dpp v5, v4 quad_perm:[2,3,0,1] row_mask:0xf bank_mask:0xf
	global_store_short v[0:1], v2, off offset:1216 sc1
	v_mul_f32_e32 v0, v56, v3
	v_mul_f32_e32 v0, v109, v0
	v_cvt_pk_bf16_f32 v2, v0, s0
	s_waitcnt lgkmcnt(0)
	v_add_f32_e32 v4, v4, v5
	s_nop 1
	v_mov_b32_dpp v5, v4 row_half_mirror row_mask:0xf bank_mask:0xf
	v_add_co_u32_e32 v0, vcc, s59, v70
	s_waitcnt lgkmcnt(0)
	v_add_f32_e32 v4, v4, v5
	v_addc_co_u32_e32 v1, vcc, 0, v71, vcc
	global_store_short v[0:1], v2, off sc1
	v_mul_f32_e32 v2, v40, v3
	v_mul_f32_e32 v2, v108, v2
	s_nop 1
	v_mov_b32_dpp v5, v4 row_mirror row_mask:0xf bank_mask:0xf
	v_cvt_pk_bf16_f32 v2, v2, s0
	global_store_short v[0:1], v2, off offset:64 sc1
	v_mul_f32_e32 v2, v24, v3
	v_mul_f32_e32 v2, v107, v2
	v_cvt_pk_bf16_f32 v2, v2, s0
	global_store_short v[0:1], v2, off offset:128 sc1
	v_mul_f32_e32 v2, v8, v3
	s_waitcnt lgkmcnt(0)
	v_add_f32_e32 v3, v4, v5
	v_mul_f32_e32 v5, v42, v42
	v_fmac_f32_e32 v5, v58, v58
	v_fmac_f32_e32 v5, v26, v26
	v_fmac_f32_e32 v5, v10, v10
	ds_bpermute_b32 v4, v110, v3
	s_nop 1
	v_mov_b32_dpp v6, v5 quad_perm:[1,0,3,2] row_mask:0xf bank_mask:0xf
	v_mul_f32_e32 v2, v106, v2
	v_cvt_pk_bf16_f32 v2, v2, s0
	global_store_short v[0:1], v2, off offset:192 sc1
	s_waitcnt lgkmcnt(0)
	v_add_f32_e32 v3, v3, v4
	s_waitcnt lgkmcnt(0)
	v_add_f32_e32 v4, v5, v6
	s_nop 1
	v_mov_b32_dpp v5, v4 quad_perm:[2,3,0,1] row_mask:0xf bank_mask:0xf
	v_fmamk_f32 v3, v3, 0x3c000000, v104
	v_rsq_f32_e32 v3, v3
	s_waitcnt lgkmcnt(0)
	v_add_f32_e32 v4, v4, v5
	s_nop 1
	v_mov_b32_dpp v5, v4 row_half_mirror row_mask:0xf bank_mask:0xf
	v_mul_f32_e32 v2, v57, v3
	v_mul_f32_e32 v2, v109, v2
	v_cvt_pk_bf16_f32 v2, v2, s0
	global_store_short v[0:1], v2, off offset:3072 sc1
	s_waitcnt lgkmcnt(0)
	v_add_f32_e32 v4, v4, v5
	s_nop 1
	v_mov_b32_dpp v5, v4 row_mirror row_mask:0xf bank_mask:0xf
	v_mul_f32_e32 v2, v41, v3
	v_mul_f32_e32 v2, v108, v2
	v_cvt_pk_bf16_f32 v2, v2, s0
	global_store_short v[0:1], v2, off offset:3136 sc1
	s_waitcnt lgkmcnt(0)
	v_add_f32_e32 v4, v4, v5
	ds_bpermute_b32 v5, v110, v4
	v_mul_f32_e32 v2, v25, v3
	v_mul_f32_e32 v2, v107, v2
	v_cvt_pk_bf16_f32 v2, v2, s0
	global_store_short v[0:1], v2, off offset:3200 sc1
	v_mul_f32_e32 v2, v9, v3
	s_waitcnt lgkmcnt(0)
	v_add_f32_e32 v3, v4, v5
	v_mul_f32_e32 v4, v43, v43
	v_fmac_f32_e32 v4, v59, v59
	v_fmac_f32_e32 v4, v27, v27
	v_fmac_f32_e32 v4, v11, v11
	s_nop 1
	v_mov_b32_dpp v5, v4 quad_perm:[1,0,3,2] row_mask:0xf bank_mask:0xf
	v_fmamk_f32 v3, v3, 0x3c000000, v104
	v_rsq_f32_e32 v3, v3
	v_mul_f32_e32 v2, v106, v2
	v_cvt_pk_bf16_f32 v2, v2, s0
	s_waitcnt lgkmcnt(0)
	v_add_f32_e32 v4, v4, v5
	s_nop 1
	v_mov_b32_dpp v5, v4 quad_perm:[2,3,0,1] row_mask:0xf bank_mask:0xf
	global_store_short v[0:1], v2, off offset:3264 sc1
	v_mul_f32_e32 v0, v58, v3
	v_mul_f32_e32 v0, v109, v0
	v_cvt_pk_bf16_f32 v2, v0, s0
	s_waitcnt lgkmcnt(0)
	v_add_f32_e32 v4, v4, v5
	s_nop 1
	v_mov_b32_dpp v5, v4 row_half_mirror row_mask:0xf bank_mask:0xf
	v_add_co_u32_e32 v0, vcc, s60, v70
	s_waitcnt lgkmcnt(0)
	v_add_f32_e32 v4, v4, v5
	s_nop 1
	v_mov_b32_dpp v5, v4 row_mirror row_mask:0xf bank_mask:0xf
	v_addc_co_u32_e32 v1, vcc, 0, v71, vcc
	global_store_short v[0:1], v2, off offset:2048 sc1
	v_mul_f32_e32 v2, v42, v3
	s_waitcnt lgkmcnt(0)
	v_add_f32_e32 v4, v4, v5
	v_mul_f32_e32 v2, v108, v2
	ds_bpermute_b32 v5, v110, v4
	v_cvt_pk_bf16_f32 v2, v2, s0
	global_store_short v[0:1], v2, off offset:2112 sc1
	v_mul_f32_e32 v2, v26, v3
	v_mul_f32_e32 v2, v107, v2
	v_cvt_pk_bf16_f32 v2, v2, s0
	global_store_short v[0:1], v2, off offset:2176 sc1
	v_mul_f32_e32 v2, v10, v3
	s_waitcnt lgkmcnt(0)
	v_add_f32_e32 v3, v4, v5
	v_mul_f32_e32 v4, v44, v44
	v_fmac_f32_e32 v4, v60, v60
	v_fmac_f32_e32 v4, v28, v28
	v_fmac_f32_e32 v4, v12, v12
	s_nop 1
	v_mov_b32_dpp v5, v4 quad_perm:[1,0,3,2] row_mask:0xf bank_mask:0xf
	v_fmamk_f32 v3, v3, 0x3c000000, v104
	v_rsq_f32_e32 v3, v3
	v_mul_f32_e32 v2, v106, v2
	v_cvt_pk_bf16_f32 v2, v2, s0
	s_waitcnt lgkmcnt(0)
	v_add_f32_e32 v4, v4, v5
	s_nop 1
	v_mov_b32_dpp v5, v4 quad_perm:[2,3,0,1] row_mask:0xf bank_mask:0xf
	global_store_short v[0:1], v2, off offset:2240 sc1
	v_mul_f32_e32 v0, v59, v3
	v_mul_f32_e32 v0, v109, v0
	v_cvt_pk_bf16_f32 v2, v0, s0
	s_waitcnt lgkmcnt(0)
	v_add_f32_e32 v4, v4, v5
	s_nop 1
	v_mov_b32_dpp v5, v4 row_half_mirror row_mask:0xf bank_mask:0xf
	v_add_co_u32_e32 v0, vcc, s61, v70
	s_waitcnt lgkmcnt(0)
	v_add_f32_e32 v4, v4, v5
	v_addc_co_u32_e32 v1, vcc, 0, v71, vcc
	global_store_short v[0:1], v2, off offset:1024 sc1
	v_mul_f32_e32 v2, v43, v3
	v_mul_f32_e32 v2, v108, v2
	s_nop 1
	v_mov_b32_dpp v5, v4 row_mirror row_mask:0xf bank_mask:0xf
	v_cvt_pk_bf16_f32 v2, v2, s0
	global_store_short v[0:1], v2, off offset:1088 sc1
	v_mul_f32_e32 v2, v27, v3
	v_mul_f32_e32 v2, v107, v2
	v_cvt_pk_bf16_f32 v2, v2, s0
	global_store_short v[0:1], v2, off offset:1152 sc1
	v_mul_f32_e32 v2, v11, v3
	s_waitcnt lgkmcnt(0)
	v_add_f32_e32 v3, v4, v5
	v_mul_f32_e32 v5, v45, v45
	v_fmac_f32_e32 v5, v61, v61
	v_fmac_f32_e32 v5, v29, v29
	v_fmac_f32_e32 v5, v13, v13
	ds_bpermute_b32 v4, v110, v3
	s_nop 1
	v_mov_b32_dpp v6, v5 quad_perm:[1,0,3,2] row_mask:0xf bank_mask:0xf
	v_mul_f32_e32 v2, v106, v2
	v_cvt_pk_bf16_f32 v2, v2, s0
	global_store_short v[0:1], v2, off offset:1216 sc1
	s_waitcnt lgkmcnt(0)
	v_add_f32_e32 v3, v3, v4
	s_waitcnt lgkmcnt(0)
	v_add_f32_e32 v4, v5, v6
	s_nop 1
	v_mov_b32_dpp v5, v4 quad_perm:[2,3,0,1] row_mask:0xf bank_mask:0xf
	v_fmamk_f32 v3, v3, 0x3c000000, v104
	v_rsq_f32_e32 v3, v3
	s_waitcnt lgkmcnt(0)
	v_add_f32_e32 v4, v4, v5
	s_nop 1
	v_mov_b32_dpp v5, v4 row_half_mirror row_mask:0xf bank_mask:0xf
	v_mul_f32_e32 v0, v60, v3
	v_mul_f32_e32 v0, v109, v0
	v_cvt_pk_bf16_f32 v2, v0, s0
	v_add_co_u32_e32 v0, vcc, s65, v70
	s_waitcnt lgkmcnt(0)
	v_add_f32_e32 v4, v4, v5
	s_nop 1
	v_mov_b32_dpp v5, v4 row_mirror row_mask:0xf bank_mask:0xf
	v_addc_co_u32_e32 v1, vcc, 0, v71, vcc
	global_store_short v[0:1], v2, off sc1
	v_mul_f32_e32 v2, v44, v3
	s_waitcnt lgkmcnt(0)
	v_add_f32_e32 v4, v4, v5
	v_mul_f32_e32 v2, v108, v2
	ds_bpermute_b32 v5, v110, v4
	v_cvt_pk_bf16_f32 v2, v2, s0
	global_store_short v[0:1], v2, off offset:64 sc1
	v_mul_f32_e32 v2, v28, v3
	v_mul_f32_e32 v2, v107, v2
	v_cvt_pk_bf16_f32 v2, v2, s0
	global_store_short v[0:1], v2, off offset:128 sc1
	v_mul_f32_e32 v2, v12, v3
	s_waitcnt lgkmcnt(0)
	v_add_f32_e32 v3, v4, v5
	v_mul_f32_e32 v4, v46, v46
	v_fmac_f32_e32 v4, v62, v62
	v_fmac_f32_e32 v4, v30, v30
	v_fmac_f32_e32 v4, v14, v14
	s_nop 1
	v_mov_b32_dpp v5, v4 quad_perm:[1,0,3,2] row_mask:0xf bank_mask:0xf
	v_fmamk_f32 v3, v3, 0x3c000000, v104
	v_rsq_f32_e32 v3, v3
	v_mul_f32_e32 v2, v106, v2
	v_cvt_pk_bf16_f32 v2, v2, s0
	s_waitcnt lgkmcnt(0)
	v_add_f32_e32 v4, v4, v5
	s_nop 1
	v_mov_b32_dpp v5, v4 quad_perm:[2,3,0,1] row_mask:0xf bank_mask:0xf
	global_store_short v[0:1], v2, off offset:192 sc1
	v_mul_f32_e32 v2, v61, v3
	v_mul_f32_e32 v2, v109, v2
	v_cvt_pk_bf16_f32 v2, v2, s0
	s_waitcnt lgkmcnt(0)
	v_add_f32_e32 v4, v4, v5
	s_nop 1
	v_mov_b32_dpp v5, v4 row_half_mirror row_mask:0xf bank_mask:0xf
	global_store_short v[0:1], v2, off offset:3072 sc1
	v_mul_f32_e32 v2, v45, v3
	v_mul_f32_e32 v2, v108, v2
	v_cvt_pk_bf16_f32 v2, v2, s0
	s_waitcnt lgkmcnt(0)
	v_add_f32_e32 v4, v4, v5
	s_nop 1
	v_mov_b32_dpp v5, v4 row_mirror row_mask:0xf bank_mask:0xf
	global_store_short v[0:1], v2, off offset:3136 sc1
	v_mul_f32_e32 v2, v29, v3
	v_mul_f32_e32 v2, v107, v2
	v_cvt_pk_bf16_f32 v2, v2, s0
	global_store_short v[0:1], v2, off offset:3200 sc1
	v_mul_f32_e32 v2, v13, v3
	s_waitcnt lgkmcnt(0)
	v_add_f32_e32 v3, v4, v5
	v_mul_f32_e32 v5, v47, v47
	v_fmac_f32_e32 v5, v63, v63
	v_fmac_f32_e32 v5, v31, v31
	v_fmac_f32_e32 v5, v15, v15
	ds_bpermute_b32 v4, v110, v3
	s_nop 1
	v_mov_b32_dpp v6, v5 quad_perm:[1,0,3,2] row_mask:0xf bank_mask:0xf
	v_mul_f32_e32 v2, v106, v2
	v_cvt_pk_bf16_f32 v2, v2, s0
	global_store_short v[0:1], v2, off offset:3264 sc1
	s_waitcnt lgkmcnt(0)
	v_add_f32_e32 v3, v3, v4
	s_waitcnt lgkmcnt(0)
	v_add_f32_e32 v4, v5, v6
	s_nop 1
	v_mov_b32_dpp v5, v4 quad_perm:[2,3,0,1] row_mask:0xf bank_mask:0xf
	v_fmamk_f32 v3, v3, 0x3c000000, v104
	v_rsq_f32_e32 v3, v3
	s_waitcnt lgkmcnt(0)
	v_add_f32_e32 v4, v4, v5
	s_nop 1
	v_mov_b32_dpp v5, v4 row_half_mirror row_mask:0xf bank_mask:0xf
	v_mul_f32_e32 v0, v62, v3
	v_mul_f32_e32 v0, v109, v0
	v_cvt_pk_bf16_f32 v2, v0, s0
	v_add_co_u32_e32 v0, vcc, s66, v70
	s_waitcnt lgkmcnt(0)
	v_add_f32_e32 v4, v4, v5
	s_nop 1
	v_mov_b32_dpp v5, v4 row_mirror row_mask:0xf bank_mask:0xf
	v_addc_co_u32_e32 v1, vcc, 0, v71, vcc
	global_store_short v[0:1], v2, off offset:2048 sc1
	v_mul_f32_e32 v2, v46, v3
	s_waitcnt lgkmcnt(0)
	v_add_f32_e32 v4, v4, v5
	v_mul_f32_e32 v2, v108, v2
	ds_bpermute_b32 v5, v110, v4
	v_cvt_pk_bf16_f32 v2, v2, s0
	global_store_short v[0:1], v2, off offset:2112 sc1
	v_mul_f32_e32 v2, v30, v3
	v_mul_f32_e32 v2, v107, v2
	v_cvt_pk_bf16_f32 v2, v2, s0
	global_store_short v[0:1], v2, off offset:2176 sc1
	v_mul_f32_e32 v2, v14, v3
	s_waitcnt lgkmcnt(0)
	v_add_f32_e32 v3, v4, v5
	v_fmamk_f32 v3, v3, 0x3c000000, v104
	v_rsq_f32_e32 v3, v3
	v_mul_f32_e32 v2, v106, v2
	v_cvt_pk_bf16_f32 v2, v2, s0
	global_store_short v[0:1], v2, off offset:2240 sc1
	v_mul_f32_e32 v0, v63, v3
	v_mul_f32_e32 v0, v109, v0
	v_cvt_pk_bf16_f32 v2, v0, s0
	v_add_co_u32_e32 v0, vcc, s67, v70
	s_nop 1
	v_addc_co_u32_e32 v1, vcc, 0, v71, vcc
	global_store_short v[0:1], v2, off offset:1024 sc1
	v_mul_f32_e32 v2, v47, v3
	v_mul_f32_e32 v2, v108, v2
	v_cvt_pk_bf16_f32 v2, v2, s0
	global_store_short v[0:1], v2, off offset:1088 sc1
	v_mul_f32_e32 v2, v31, v3
	v_mul_f32_e32 v2, v107, v2
	v_cvt_pk_bf16_f32 v2, v2, s0
	global_store_short v[0:1], v2, off offset:1152 sc1
	v_mul_f32_e32 v2, v15, v3
	v_mul_f32_e32 v2, v106, v2
	v_cvt_pk_bf16_f32 v2, v2, s0
	global_store_short v[0:1], v2, off offset:1216 sc1
	s_branch .LBB0_646

.LBB0_707:
	s_add_i32 s58, s64, 0xffffe000
	s_lshr_b32 s58, s58, 12
	s_mulk_i32 s58, 0x1800
	s_addk_i32 s58, 0x1800
	s_cmp_gt_i32 s6, 63
	s_cselect_b32 s6, s58, 0
	s_lshl_b64 s[58:59], s[6:7], 2
	v_mov_b32_e32 v70, s68
	s_add_u32 s6, s14, s58
	ds_read_b64 v[70:71], v70
	s_addc_u32 s63, s15, s59
	s_lshl_b32 s58, s69, 14
	s_add_i32 s58, s58, 0x20000
	s_ashr_i32 s59, s58, 31
	s_lshl_b64 s[58:59], s[58:59], 2
	s_add_u32 s58, s10, s58
	s_waitcnt lgkmcnt(0)
	v_readfirstlane_b32 s70, v70
	s_addc_u32 s59, s11, s59
	v_add_u32_e32 v70, s64, v141
	s_add_u32 s60, s6, 0x5ba2000
	v_lshlrev_b32_e32 v190, 10, v70
	s_addc_u32 s61, s63, 0
	v_or_b32_e32 v102, s66, v140
	v_or_b32_e32 v188, 0x400, v190
	v_or_b32_e32 v187, 0x4400, v190
	v_or_b32_e32 v191, 0x4c00, v190
	v_or_b32_e32 v195, 0x6c00, v190
	v_readfirstlane_b32 s71, v71
	s_add_u32 s62, s6, 0x5ba4000
	v_ashrrev_i32_e32 v103, 31, v102
	v_add_u32_e32 v134, v190, v102
	v_add_u32_e32 v136, v188, v102
	v_or_b32_e32 v186, 0x800, v190
	v_or_b32_e32 v185, 0xc00, v190
	v_or_b32_e32 v183, 0x2000, v190
	v_or_b32_e32 v181, 0x2400, v190
	v_or_b32_e32 v71, 0x2800, v190
	v_or_b32_e32 v182, 0x2c00, v190
	v_or_b32_e32 v184, 0x4000, v190
	v_add_u32_e32 v114, v187, v102
	v_or_b32_e32 v189, 0x4800, v190
	v_add_u32_e32 v120, v191, v102
	v_or_b32_e32 v192, 0x6000, v190
	v_or_b32_e32 v193, 0x6400, v190
	v_or_b32_e32 v194, 0x6800, v190
	v_add_u32_e32 v130, v195, v102
	s_addc_u32 s63, s63, 0
	v_lshlrev_b64 v[72:73], 2, v[102:103]
	v_ashrrev_i32_e32 v137, 31, v136
	v_add_u32_e32 v138, v186, v102
	v_add_u32_e32 v132, v185, v102
	v_add_u32_e32 v124, v183, v102
	v_add_u32_e32 v116, v181, v102
	v_add_u32_e32 v108, v71, v102
	v_add_u32_e32 v110, v182, v102
	v_add_u32_e32 v112, v184, v102
	v_ashrrev_i32_e32 v115, 31, v114
	v_add_u32_e32 v118, v189, v102
	v_ashrrev_i32_e32 v121, 31, v120
	v_add_u32_e32 v122, v192, v102
	v_add_u32_e32 v126, v193, v102
	v_add_u32_e32 v128, v194, v102
	v_ashrrev_i32_e32 v131, 31, v130
	v_ashrrev_i32_e32 v135, 31, v134
	v_lshl_add_u64 v[74:75], s[60:61], 0, v[72:73]
	v_lshl_add_u64 v[104:105], s[70:71], 0, v[72:73]
	v_lshl_add_u64 v[72:73], s[62:63], 0, v[72:73]
	v_lshl_add_u64 v[88:89], v[136:137], 2, s[12:13]
	v_ashrrev_i32_e32 v139, 31, v138
	v_ashrrev_i32_e32 v133, 31, v132
	v_ashrrev_i32_e32 v125, 31, v124
	v_ashrrev_i32_e32 v117, 31, v116
	v_ashrrev_i32_e32 v109, 31, v108
	v_ashrrev_i32_e32 v111, 31, v110
	v_ashrrev_i32_e32 v113, 31, v112
	v_lshl_add_u64 v[86:87], v[114:115], 2, s[12:13]
	v_ashrrev_i32_e32 v119, 31, v118
	v_lshl_add_u64 v[92:93], v[120:121], 2, s[12:13]
	v_ashrrev_i32_e32 v123, 31, v122
	v_ashrrev_i32_e32 v127, 31, v126
	v_ashrrev_i32_e32 v129, 31, v128
	v_lshl_add_u64 v[100:101], v[130:131], 2, s[12:13]
	v_lshl_add_u64 v[106:107], v[134:135], 2, s[12:13]
	global_load_dword v196, v[74:75], off
	global_load_dword v198, v[72:73], off
	global_load_dword v197, v[104:105], off
	v_lshl_add_u64 v[84:85], v[138:139], 2, s[12:13]
	v_lshl_add_u64 v[82:83], v[132:133], 2, s[12:13]
	v_lshl_add_u64 v[78:79], v[124:125], 2, s[12:13]
	v_lshl_add_u64 v[72:73], v[116:117], 2, s[12:13]
	v_lshl_add_u64 v[74:75], v[108:109], 2, s[12:13]
	v_lshl_add_u64 v[76:77], v[110:111], 2, s[12:13]
	v_lshl_add_u64 v[80:81], v[112:113], 2, s[12:13]
	global_load_dword v180, v[88:89], off
	global_load_dword v179, v[84:85], off
	global_load_dword v178, v[82:83], off
	global_load_dword v177, v[78:79], off
	global_load_dword v176, v[72:73], off
	global_load_dword v175, v[74:75], off
	global_load_dword v174, v[76:77], off
	global_load_dword v173, v[80:81], off
	v_lshl_add_u64 v[90:91], v[118:119], 2, s[12:13]
	global_load_dword v172, v[86:87], off
	global_load_dword v170, v[90:91], off
	v_lshl_add_u64 v[94:95], v[122:123], 2, s[12:13]
	v_lshl_add_u64 v[96:97], v[126:127], 2, s[12:13]
	v_lshl_add_u64 v[98:99], v[128:129], 2, s[12:13]
	global_load_dword v171, v[92:93], off
	global_load_dword v169, v[94:95], off
	global_load_dword v168, v[96:97], off
	global_load_dword v167, v[98:99], off
	global_load_dword v103, v[100:101], off
	global_load_dword v202, v[106:107], off
	v_lshl_add_u64 v[108:109], v[108:109], 1, s[8:9]
	s_waitcnt vmcnt(0)
	v_add_f32_e32 v198, 1.0, v198
	v_mul_f32_e32 v197, v197, v198
	v_fmac_f32_e32 v180, v49, v196
	v_fmac_f32_e32 v179, v50, v196
	v_fmac_f32_e32 v178, v51, v196
	v_fmac_f32_e32 v177, v52, v196
	v_fmac_f32_e32 v176, v53, v196
	v_fmac_f32_e32 v175, v54, v196
	v_fmac_f32_e32 v174, v55, v196
	v_fmac_f32_e32 v173, v56, v196
	v_fmac_f32_e32 v172, v57, v196
	v_fmac_f32_e32 v170, v58, v196
	v_fmac_f32_e32 v171, v59, v196
	v_fmac_f32_e32 v169, v60, v196
	v_fmac_f32_e32 v168, v61, v196
	v_fmac_f32_e32 v167, v62, v196
	v_fmac_f32_e32 v103, v63, v196
	v_fmac_f32_e32 v202, v48, v196
	v_or_b32_e32 v48, 32, v102
	v_ashrrev_i32_e32 v49, 31, v48
	v_lshlrev_b64 v[50:51], 2, v[48:49]
	global_store_dword v[88:89], v180, off sc1
	global_store_dword v[84:85], v179, off sc1
	global_store_dword v[82:83], v178, off sc1
	global_store_dword v[78:79], v177, off sc1
	global_store_dword v[72:73], v176, off sc1
	global_store_dword v[74:75], v175, off sc1
	global_store_dword v[76:77], v174, off sc1
	global_store_dword v[80:81], v173, off sc1
	global_store_dword v[86:87], v172, off sc1
	global_store_dword v[90:91], v170, off sc1
	global_store_dword v[92:93], v171, off sc1
	global_store_dword v[94:95], v169, off sc1
	global_store_dword v[96:97], v168, off sc1
	global_store_dword v[98:99], v167, off sc1
	global_store_dword v[100:101], v103, off sc1
	global_store_dword v[106:107], v202, off sc1
	v_mul_f32_e32 v54, v197, v202
	v_lshl_add_u64 v[52:53], s[60:61], 0, v[50:51]
	v_lshl_add_u64 v[50:51], s[62:63], 0, v[50:51]
	global_load_dword v198, v[106:107], off offset:128
	global_load_dword v196, v[52:53], off
	global_load_dword v203, v[50:51], off
	global_load_dword v204, v[104:105], off offset:128
	v_cvt_pk_bf16_f32 v49, v54, s0
	v_lshl_add_u64 v[50:51], v[134:135], 1, s[8:9]
	global_store_short v[50:51], v49, off sc1
	v_mul_f32_e32 v49, v197, v180
	v_cvt_pk_bf16_f32 v49, v49, s0
	v_lshl_add_u64 v[50:51], v[136:137], 1, s[8:9]
	global_store_short v[50:51], v49, off sc1
	v_mul_f32_e32 v49, v197, v179
	v_cvt_pk_bf16_f32 v49, v49, s0
	v_lshl_add_u64 v[50:51], v[138:139], 1, s[8:9]
	global_store_short v[50:51], v49, off sc1
	v_mul_f32_e32 v49, v197, v178
	v_cvt_pk_bf16_f32 v49, v49, s0
	v_lshl_add_u64 v[50:51], v[132:133], 1, s[8:9]
	global_store_short v[50:51], v49, off sc1
	v_mul_f32_e32 v49, v197, v177
	v_cvt_pk_bf16_f32 v49, v49, s0
	v_lshl_add_u64 v[50:51], v[124:125], 1, s[8:9]
	global_store_short v[50:51], v49, off sc1
	v_mul_f32_e32 v49, v197, v176
	v_cvt_pk_bf16_f32 v49, v49, s0
	v_lshl_add_u64 v[50:51], v[116:117], 1, s[8:9]
	global_store_short v[50:51], v49, off sc1
	v_mul_f32_e32 v49, v197, v175
	global_load_dword v62, v[84:85], off offset:128
	global_load_dword v60, v[78:79], off offset:128
	global_load_dword v59, v[72:73], off offset:128
	global_load_dword v58, v[74:75], off offset:128
	global_load_dword v56, v[80:81], off offset:128
	global_load_dword v57, v[76:77], off offset:128
	global_load_dword v55, v[86:87], off offset:128
	global_load_dword v61, v[82:83], off offset:128
	global_load_dword v54, v[90:91], off offset:128
	global_load_dword v53, v[92:93], off offset:128
	global_load_dword v52, v[94:95], off offset:128
	global_load_dword v51, v[96:97], off offset:128
	global_load_dword v50, v[98:99], off offset:128
	v_cvt_pk_bf16_f32 v63, v49, s0
	global_load_dword v49, v[100:101], off offset:128
	s_waitcnt vmcnt(22)
	v_fmac_f32_e32 v198, v32, v196
	global_store_short v[108:109], v63, off sc1
	global_load_dword v63, v[88:89], off offset:128
	v_mul_f32_e32 v108, v197, v174
	v_cvt_pk_bf16_f32 v116, v108, s0
	v_lshl_add_u64 v[108:109], v[110:111], 1, s[8:9]
	global_store_short v[108:109], v116, off sc1
	v_mul_f32_e32 v108, v197, v173
	v_cvt_pk_bf16_f32 v110, v108, s0
	v_lshl_add_u64 v[108:109], v[112:113], 1, s[8:9]
	global_store_short v[108:109], v110, off sc1
	v_mul_f32_e32 v108, v197, v172
	v_cvt_pk_bf16_f32 v110, v108, s0
	v_lshl_add_u64 v[108:109], v[114:115], 1, s[8:9]
	global_store_short v[108:109], v110, off sc1
	v_mul_f32_e32 v108, v197, v170
	v_cvt_pk_bf16_f32 v110, v108, s0
	v_lshl_add_u64 v[108:109], v[118:119], 1, s[8:9]
	global_store_short v[108:109], v110, off sc1
	v_mul_f32_e32 v108, v197, v171
	v_cvt_pk_bf16_f32 v110, v108, s0
	v_lshl_add_u64 v[108:109], v[120:121], 1, s[8:9]
	global_store_short v[108:109], v110, off sc1
	v_mul_f32_e32 v108, v197, v169
	v_cvt_pk_bf16_f32 v110, v108, s0
	v_lshl_add_u64 v[108:109], v[122:123], 1, s[8:9]
	global_store_short v[108:109], v110, off sc1
	v_mul_f32_e32 v108, v197, v168
	v_cvt_pk_bf16_f32 v110, v108, s0
	v_lshl_add_u64 v[108:109], v[126:127], 1, s[8:9]
	global_store_short v[108:109], v110, off sc1
	v_mul_f32_e32 v108, v197, v167
	v_cvt_pk_bf16_f32 v110, v108, s0
	v_lshl_add_u64 v[108:109], v[128:129], 1, s[8:9]
	global_store_short v[108:109], v110, off sc1
	v_mul_f32_e32 v108, v197, v103
	v_cvt_pk_bf16_f32 v110, v108, s0
	v_lshl_add_u64 v[108:109], v[130:131], 1, s[8:9]
	global_store_short v[108:109], v110, off sc1
	s_waitcnt vmcnt(32)
	v_add_f32_e32 v108, 1.0, v203
	s_waitcnt vmcnt(31)
	v_mul_f32_e32 v112, v204, v108
	v_add_u32_e32 v108, v190, v48
	s_waitcnt vmcnt(24)
	v_fmac_f32_e32 v62, v34, v196
	s_waitcnt vmcnt(17)
	v_fmac_f32_e32 v61, v35, v196
	v_fmac_f32_e32 v60, v36, v196
	v_fmac_f32_e32 v59, v37, v196
	v_fmac_f32_e32 v58, v38, v196
	v_fmac_f32_e32 v57, v39, v196
	v_fmac_f32_e32 v56, v40, v196
	v_fmac_f32_e32 v55, v41, v196
	s_waitcnt vmcnt(16)
	v_fmac_f32_e32 v54, v42, v196
	s_waitcnt vmcnt(15)
	v_fmac_f32_e32 v53, v43, v196
	s_waitcnt vmcnt(14)
	v_fmac_f32_e32 v52, v44, v196
	s_waitcnt vmcnt(13)
	v_fmac_f32_e32 v51, v45, v196
	s_waitcnt vmcnt(12)
	v_fmac_f32_e32 v50, v46, v196
	s_waitcnt vmcnt(11)
	v_fmac_f32_e32 v49, v47, v196
	v_ashrrev_i32_e32 v109, 31, v108
	global_store_dword v[106:107], v198, off offset:128 sc1
	v_mul_f32_e32 v32, v112, v198
	global_store_dword v[84:85], v62, off offset:128 sc1
	global_store_dword v[82:83], v61, off offset:128 sc1
	global_store_dword v[78:79], v60, off offset:128 sc1
	global_store_dword v[72:73], v59, off offset:128 sc1
	global_store_dword v[74:75], v58, off offset:128 sc1
	global_store_dword v[76:77], v57, off offset:128 sc1
	global_store_dword v[80:81], v56, off offset:128 sc1
	global_store_dword v[86:87], v55, off offset:128 sc1
	global_store_dword v[90:91], v54, off offset:128 sc1
	global_store_dword v[92:93], v53, off offset:128 sc1
	global_store_dword v[94:95], v52, off offset:128 sc1
	global_store_dword v[96:97], v51, off offset:128 sc1
	global_store_dword v[98:99], v50, off offset:128 sc1
	global_store_dword v[100:101], v49, off offset:128 sc1
	v_cvt_pk_bf16_f32 v32, v32, s0
	v_lshl_add_u64 v[108:109], v[108:109], 1, s[8:9]
	v_add_u32_e32 v110, v188, v48
	global_load_dword v45, v[88:89], off offset:256
	v_ashrrev_i32_e32 v111, 31, v110
	global_store_short v[108:109], v32, off sc1
	v_mul_f32_e32 v40, v112, v59
	v_mul_f32_e32 v115, v112, v56
	v_cvt_pk_bf16_f32 v115, v115, s0
	s_waitcnt vmcnt(26)
	v_fmac_f32_e32 v63, v33, v196
	v_mul_f32_e32 v32, v112, v63
	v_cvt_pk_bf16_f32 v34, v32, s0
	v_lshl_add_u64 v[32:33], v[110:111], 1, s[8:9]
	global_store_short v[32:33], v34, off sc1
	v_add_u32_e32 v32, v186, v48
	v_ashrrev_i32_e32 v33, 31, v32
	v_mul_f32_e32 v34, v112, v62
	v_cvt_pk_bf16_f32 v34, v34, s0
	v_lshl_add_u64 v[32:33], v[32:33], 1, s[8:9]
	global_store_short v[32:33], v34, off sc1
	v_add_u32_e32 v32, v185, v48
	v_ashrrev_i32_e32 v33, 31, v32
	v_mul_f32_e32 v34, v112, v61
	v_cvt_pk_bf16_f32 v34, v34, s0
	v_lshl_add_u64 v[32:33], v[32:33], 1, s[8:9]
	global_store_short v[32:33], v34, off sc1
	v_add_u32_e32 v32, v183, v48
	v_ashrrev_i32_e32 v33, 31, v32
	v_mul_f32_e32 v34, v112, v60
	v_cvt_pk_bf16_f32 v34, v34, s0
	v_lshl_add_u64 v[32:33], v[32:33], 1, s[8:9]
	global_store_short v[32:33], v34, off sc1
	v_or_b32_e32 v32, 64, v102
	v_add_u32_e32 v34, v181, v48
	v_ashrrev_i32_e32 v33, 31, v32
	v_ashrrev_i32_e32 v35, 31, v34
	v_lshlrev_b64 v[36:37], 2, v[32:33]
	global_store_dword v[88:89], v63, off offset:128 sc1
	v_lshl_add_u64 v[38:39], s[60:61], 0, v[36:37]
	v_cvt_pk_bf16_f32 v33, v40, s0
	v_lshl_add_u64 v[34:35], v[34:35], 1, s[8:9]
	v_lshl_add_u64 v[36:37], s[62:63], 0, v[36:37]
	global_load_dword v109, v[38:39], off
	global_load_dword v113, v[36:37], off
	global_load_dword v114, v[104:105], off offset:256
	global_load_dword v116, v[106:107], off offset:256
	global_load_dword v47, v[84:85], off offset:256
	global_load_dword v44, v[78:79], off offset:256
	global_load_dword v39, v[86:87], off offset:256
	global_load_dword v46, v[82:83], off offset:256
	global_load_dword v43, v[72:73], off offset:256
	global_load_dword v42, v[74:75], off offset:256
	global_load_dword v40, v[80:81], off offset:256
	global_load_dword v41, v[76:77], off offset:256
	global_load_dword v38, v[90:91], off offset:256
	global_load_dword v37, v[92:93], off offset:256
	global_load_dword v36, v[94:95], off offset:256
	v_add_u32_e32 v110, v184, v48
	global_store_short v[34:35], v33, off sc1
	v_add_u32_e32 v34, v71, v48
	v_ashrrev_i32_e32 v35, 31, v34
	v_mul_f32_e32 v33, v112, v58
	v_cvt_pk_bf16_f32 v33, v33, s0
	v_lshl_add_u64 v[34:35], v[34:35], 1, s[8:9]
	global_store_short v[34:35], v33, off sc1
	v_add_u32_e32 v34, v182, v48
	v_ashrrev_i32_e32 v35, 31, v34
	v_mul_f32_e32 v33, v112, v57
	v_cvt_pk_bf16_f32 v33, v33, s0
	v_lshl_add_u64 v[34:35], v[34:35], 1, s[8:9]
	global_store_short v[34:35], v33, off sc1
	global_load_dword v35, v[96:97], off offset:256
	v_ashrrev_i32_e32 v111, 31, v110
	global_load_dword v34, v[98:99], off offset:256
	global_load_dword v33, v[100:101], off offset:256
	v_lshl_add_u64 v[110:111], v[110:111], 1, s[8:9]
	global_store_short v[110:111], v115, off sc1
	v_add_u32_e32 v110, v187, v48
	v_ashrrev_i32_e32 v111, 31, v110
	v_mul_f32_e32 v115, v112, v55
	v_cvt_pk_bf16_f32 v115, v115, s0
	v_lshl_add_u64 v[110:111], v[110:111], 1, s[8:9]
	global_store_short v[110:111], v115, off sc1
	v_add_u32_e32 v110, v189, v48
	v_ashrrev_i32_e32 v111, 31, v110
	v_mul_f32_e32 v115, v112, v54
	v_cvt_pk_bf16_f32 v115, v115, s0
	v_lshl_add_u64 v[110:111], v[110:111], 1, s[8:9]
	global_store_short v[110:111], v115, off sc1
	v_add_u32_e32 v110, v191, v48
	v_ashrrev_i32_e32 v111, 31, v110
	v_mul_f32_e32 v115, v112, v53
	v_cvt_pk_bf16_f32 v115, v115, s0
	v_lshl_add_u64 v[110:111], v[110:111], 1, s[8:9]
	global_store_short v[110:111], v115, off sc1
	v_add_u32_e32 v110, v192, v48
	v_ashrrev_i32_e32 v111, 31, v110
	v_mul_f32_e32 v115, v112, v52
	v_cvt_pk_bf16_f32 v115, v115, s0
	v_lshl_add_u64 v[110:111], v[110:111], 1, s[8:9]
	global_store_short v[110:111], v115, off sc1
	v_add_u32_e32 v110, v193, v48
	v_ashrrev_i32_e32 v111, 31, v110
	v_mul_f32_e32 v115, v112, v51
	v_cvt_pk_bf16_f32 v115, v115, s0
	v_lshl_add_u64 v[110:111], v[110:111], 1, s[8:9]
	global_store_short v[110:111], v115, off sc1
	v_add_u32_e32 v110, v194, v48
	v_ashrrev_i32_e32 v111, 31, v110
	v_mul_f32_e32 v115, v112, v50
	v_cvt_pk_bf16_f32 v115, v115, s0
	v_lshl_add_u64 v[110:111], v[110:111], 1, s[8:9]
	global_store_short v[110:111], v115, off sc1
	v_add_u32_e32 v110, v195, v48
	v_ashrrev_i32_e32 v111, 31, v110
	v_mul_f32_e32 v48, v112, v49
	v_cvt_pk_bf16_f32 v48, v48, s0
	v_lshl_add_u64 v[110:111], v[110:111], 1, s[8:9]
	global_store_short v[110:111], v48, off sc1
	v_add_u32_e32 v110, v190, v32
	v_ashrrev_i32_e32 v111, 31, v110
	v_mul_f32_e32 v108, v198, v198
	s_waitcnt vmcnt(28)
	v_fmac_f32_e32 v45, v17, v109
	s_waitcnt vmcnt(27)
	v_add_f32_e32 v48, 1.0, v113
	s_waitcnt vmcnt(26)
	v_mul_f32_e32 v48, v114, v48
	s_waitcnt vmcnt(25)
	v_fmac_f32_e32 v116, v16, v109
	v_mul_f32_e32 v16, v48, v116
	s_waitcnt vmcnt(24)
	v_fmac_f32_e32 v47, v18, v109
	v_cvt_pk_bf16_f32 v18, v16, s0
	v_lshl_add_u64 v[16:17], v[110:111], 1, s[8:9]
	global_store_short v[16:17], v18, off sc1
	v_add_u32_e32 v16, v188, v32
	v_ashrrev_i32_e32 v17, 31, v16
	v_mul_f32_e32 v18, v48, v45
	v_cvt_pk_bf16_f32 v18, v18, s0
	v_lshl_add_u64 v[16:17], v[16:17], 1, s[8:9]
	global_store_short v[16:17], v18, off sc1
	v_add_u32_e32 v16, v186, v32
	v_ashrrev_i32_e32 v17, 31, v16
	v_mul_f32_e32 v18, v48, v47
	v_cvt_pk_bf16_f32 v18, v18, s0
	v_lshl_add_u64 v[16:17], v[16:17], 1, s[8:9]
	s_waitcnt vmcnt(23)
	v_fmac_f32_e32 v46, v19, v109
	global_store_short v[16:17], v18, off sc1
	v_add_u32_e32 v16, v185, v32
	v_ashrrev_i32_e32 v17, 31, v16
	v_mul_f32_e32 v18, v48, v46
	v_cvt_pk_bf16_f32 v18, v18, s0
	v_lshl_add_u64 v[16:17], v[16:17], 1, s[8:9]
	global_store_short v[16:17], v18, off sc1
	v_or_b32_e32 v16, 0x60, v102
	v_ashrrev_i32_e32 v17, 31, v16
	v_fmac_f32_e32 v44, v20, v109
	s_waitcnt vmcnt(24)
	v_fmac_f32_e32 v43, v21, v109
	s_waitcnt vmcnt(23)
	v_fmac_f32_e32 v42, v22, v109
	s_waitcnt vmcnt(21)
	v_fmac_f32_e32 v41, v23, v109
	v_fmac_f32_e32 v40, v24, v109
	v_fmac_f32_e32 v39, v25, v109
	s_waitcnt vmcnt(20)
	v_fmac_f32_e32 v38, v26, v109
	s_waitcnt vmcnt(19)
	v_fmac_f32_e32 v37, v27, v109
	s_waitcnt vmcnt(18)
	v_fmac_f32_e32 v36, v28, v109
	s_waitcnt vmcnt(14)
	v_fmac_f32_e32 v35, v29, v109
	s_waitcnt vmcnt(13)
	v_fmac_f32_e32 v34, v30, v109
	s_waitcnt vmcnt(12)
	v_fmac_f32_e32 v33, v31, v109
	v_lshlrev_b64 v[20:21], 2, v[16:17]
	global_store_dword v[88:89], v45, off offset:256 sc1
	global_store_dword v[84:85], v47, off offset:256 sc1
	global_store_dword v[82:83], v46, off offset:256 sc1
	global_store_dword v[78:79], v44, off offset:256 sc1
	global_store_dword v[72:73], v43, off offset:256 sc1
	global_store_dword v[74:75], v42, off offset:256 sc1
	global_store_dword v[76:77], v41, off offset:256 sc1
	global_store_dword v[80:81], v40, off offset:256 sc1
	global_store_dword v[86:87], v39, off offset:256 sc1
	global_store_dword v[90:91], v38, off offset:256 sc1
	global_store_dword v[92:93], v37, off offset:256 sc1
	global_store_dword v[94:95], v36, off offset:256 sc1
	global_store_dword v[96:97], v35, off offset:256 sc1
	global_store_dword v[98:99], v34, off offset:256 sc1
	global_store_dword v[100:101], v33, off offset:256 sc1
	global_store_dword v[106:107], v116, off offset:256 sc1
	v_lshl_add_u64 v[22:23], s[60:61], 0, v[20:21]
	v_lshl_add_u64 v[20:21], s[62:63], 0, v[20:21]
	global_load_dword v29, v[106:107], off offset:384
	global_load_dword v102, v[22:23], off
	global_load_dword v17, v[20:21], off
	s_nop 0
	global_load_dword v20, v[104:105], off offset:384
	v_add_u32_e32 v18, v183, v32
	v_ashrrev_i32_e32 v19, 31, v18
	v_mul_f32_e32 v21, v48, v44
	v_cvt_pk_bf16_f32 v21, v21, s0
	v_lshl_add_u64 v[18:19], v[18:19], 1, s[8:9]
	global_store_short v[18:19], v21, off sc1
	v_add_u32_e32 v18, v181, v32
	v_ashrrev_i32_e32 v19, 31, v18
	v_mul_f32_e32 v21, v48, v43
	v_cvt_pk_bf16_f32 v21, v21, s0
	v_lshl_add_u64 v[18:19], v[18:19], 1, s[8:9]
	global_store_short v[18:19], v21, off sc1
	v_add_u32_e32 v18, v71, v32
	v_ashrrev_i32_e32 v19, 31, v18
	v_mul_f32_e32 v21, v48, v42
	v_cvt_pk_bf16_f32 v21, v21, s0
	v_lshl_add_u64 v[18:19], v[18:19], 1, s[8:9]
	global_store_short v[18:19], v21, off sc1
	v_add_u32_e32 v18, v182, v32
	v_ashrrev_i32_e32 v19, 31, v18
	v_mul_f32_e32 v21, v48, v41
	v_cvt_pk_bf16_f32 v21, v21, s0
	v_lshl_add_u64 v[18:19], v[18:19], 1, s[8:9]
	global_store_short v[18:19], v21, off sc1
	v_add_u32_e32 v18, v184, v32
	v_ashrrev_i32_e32 v19, 31, v18
	v_mul_f32_e32 v21, v48, v40
	v_cvt_pk_bf16_f32 v21, v21, s0
	v_lshl_add_u64 v[18:19], v[18:19], 1, s[8:9]
	global_store_short v[18:19], v21, off sc1
	v_add_u32_e32 v18, v187, v32
	v_ashrrev_i32_e32 v19, 31, v18
	v_mul_f32_e32 v21, v48, v39
	v_cvt_pk_bf16_f32 v21, v21, s0
	v_lshl_add_u64 v[18:19], v[18:19], 1, s[8:9]
	global_store_short v[18:19], v21, off sc1
	v_add_u32_e32 v18, v189, v32
	v_ashrrev_i32_e32 v19, 31, v18
	v_mul_f32_e32 v21, v48, v38
	v_cvt_pk_bf16_f32 v21, v21, s0
	v_lshl_add_u64 v[18:19], v[18:19], 1, s[8:9]
	global_store_short v[18:19], v21, off sc1
	v_add_u32_e32 v18, v191, v32
	v_ashrrev_i32_e32 v19, 31, v18
	v_mul_f32_e32 v21, v48, v37
	v_cvt_pk_bf16_f32 v21, v21, s0
	v_lshl_add_u64 v[18:19], v[18:19], 1, s[8:9]
	global_store_short v[18:19], v21, off sc1
	v_add_u32_e32 v18, v192, v32
	v_ashrrev_i32_e32 v19, 31, v18
	v_mul_f32_e32 v21, v48, v36
	v_cvt_pk_bf16_f32 v21, v21, s0
	v_lshl_add_u64 v[18:19], v[18:19], 1, s[8:9]
	global_load_dword v28, v[88:89], off offset:384
	global_load_dword v27, v[84:85], off offset:384
	global_load_dword v25, v[78:79], off offset:384
	global_load_dword v24, v[72:73], off offset:384
	global_load_dword v23, v[74:75], off offset:384
	v_mul_f32_e32 v30, v48, v33
	global_store_short v[18:19], v21, off sc1
	v_add_u32_e32 v18, v193, v32
	v_ashrrev_i32_e32 v19, 31, v18
	v_mul_f32_e32 v21, v48, v35
	v_cvt_pk_bf16_f32 v21, v21, s0
	v_lshl_add_u64 v[18:19], v[18:19], 1, s[8:9]
	global_store_short v[18:19], v21, off sc1
	v_add_u32_e32 v18, v194, v32
	v_ashrrev_i32_e32 v19, 31, v18
	v_mul_f32_e32 v21, v48, v34
	v_cvt_pk_bf16_f32 v21, v21, s0
	v_lshl_add_u64 v[18:19], v[18:19], 1, s[8:9]
	global_store_short v[18:19], v21, off sc1
	v_add_u32_e32 v18, v195, v32
	global_load_dword v21, v[80:81], off offset:384
	global_load_dword v22, v[76:77], off offset:384
	v_ashrrev_i32_e32 v19, 31, v18
	v_cvt_pk_bf16_f32 v30, v30, s0
	v_lshl_add_u64 v[18:19], v[18:19], 1, s[8:9]
	s_waitcnt vmcnt(19)
	v_add_f32_e32 v17, 1.0, v17
	s_waitcnt vmcnt(18)
	v_mul_f32_e32 v32, v20, v17
	global_load_dword v20, v[86:87], off offset:384
	global_load_dword v26, v[82:83], off offset:384
	v_fmac_f32_e32 v29, v0, v102
	global_store_short v[18:19], v30, off sc1
	v_add_u32_e32 v18, v190, v16
	v_ashrrev_i32_e32 v19, 31, v18
	v_mul_f32_e32 v0, v32, v29
	v_cvt_pk_bf16_f32 v0, v0, s0
	v_lshl_add_u64 v[18:19], v[18:19], 1, s[8:9]
	global_store_short v[18:19], v0, off sc1
	global_load_dword v19, v[90:91], off offset:384
	v_add_u32_e32 v30, v188, v16
	global_load_dword v18, v[92:93], off offset:384
	v_ashrrev_i32_e32 v31, 31, v30
	v_fmac_f32_e32 v108, v202, v202
	v_fmac_f32_e32 v108, v116, v116
	v_fmac_f32_e32 v108, v29, v29
	global_store_dword v[106:107], v29, off offset:384 sc1
	s_waitcnt vmcnt(16)
	v_fmac_f32_e32 v28, v1, v102
	v_mul_f32_e32 v0, v32, v28
	v_cvt_pk_bf16_f32 v17, v0, s0
	v_lshl_add_u64 v[0:1], v[30:31], 1, s[8:9]
	global_store_short v[0:1], v17, off sc1
	v_add_u32_e32 v0, v186, v16
	s_waitcnt vmcnt(16)
	v_fmac_f32_e32 v27, v2, v102
	global_load_dword v17, v[94:95], off offset:384
	v_ashrrev_i32_e32 v1, 31, v0
	v_mul_f32_e32 v2, v32, v27
	v_cvt_pk_bf16_f32 v2, v2, s0
	v_lshl_add_u64 v[0:1], v[0:1], 1, s[8:9]
	global_store_short v[0:1], v2, off sc1
	v_add_u32_e32 v0, v185, v16
	global_load_dword v2, v[96:97], off offset:384
	v_ashrrev_i32_e32 v1, 31, v0
	v_lshl_add_u64 v[0:1], v[0:1], 1, s[8:9]
	v_add_u32_e32 v30, v183, v16
	s_waitcnt vmcnt(18)
	v_fmac_f32_e32 v25, v4, v102
	v_ashrrev_i32_e32 v31, 31, v30
	v_lshl_add_u64 v[30:31], v[30:31], 1, s[8:9]
	s_waitcnt vmcnt(17)
	v_fmac_f32_e32 v24, v5, v102
	s_waitcnt vmcnt(16)
	v_fmac_f32_e32 v23, v6, v102
	s_waitcnt vmcnt(11)
	v_fmac_f32_e32 v22, v7, v102
	v_fmac_f32_e32 v21, v8, v102
	global_store_dword v[88:89], v28, off offset:384 sc1
	global_store_dword v[84:85], v27, off offset:384 sc1
	s_waitcnt vmcnt(12)
	v_fmac_f32_e32 v20, v9, v102
	s_waitcnt vmcnt(11)
	v_fmac_f32_e32 v26, v3, v102
	v_mul_f32_e32 v3, v32, v26
	v_cvt_pk_bf16_f32 v3, v3, s0
	global_store_short v[0:1], v3, off sc1
	global_load_dword v1, v[98:99], off offset:384
	v_mul_f32_e32 v0, v32, v25
	v_cvt_pk_bf16_f32 v0, v0, s0
	global_store_short v[30:31], v0, off sc1
	global_load_dword v0, v[100:101], off offset:384
	v_add_u32_e32 v30, v181, v16
	v_ashrrev_i32_e32 v31, 31, v30
	v_mul_f32_e32 v3, v32, v24
	v_cvt_pk_bf16_f32 v3, v3, s0
	v_lshl_add_u64 v[4:5], v[30:31], 1, s[8:9]
	global_store_short v[4:5], v3, off sc1
	v_add_u32_e32 v4, v71, v16
	v_ashrrev_i32_e32 v5, 31, v4
	v_mul_f32_e32 v3, v32, v23
	v_cvt_pk_bf16_f32 v3, v3, s0
	v_lshl_add_u64 v[4:5], v[4:5], 1, s[8:9]
	global_store_short v[4:5], v3, off sc1
	v_add_u32_e32 v4, v182, v16
	v_ashrrev_i32_e32 v5, 31, v4
	v_mul_f32_e32 v3, v32, v22
	v_cvt_pk_bf16_f32 v3, v3, s0
	v_lshl_add_u64 v[4:5], v[4:5], 1, s[8:9]
	global_store_short v[4:5], v3, off sc1
	v_add_u32_e32 v4, v184, v16
	v_ashrrev_i32_e32 v5, 31, v4
	v_mul_f32_e32 v3, v32, v21
	v_cvt_pk_bf16_f32 v3, v3, s0
	v_lshl_add_u64 v[4:5], v[4:5], 1, s[8:9]
	global_store_short v[4:5], v3, off sc1
	v_add_u32_e32 v4, v187, v16
	v_ashrrev_i32_e32 v5, 31, v4
	v_mul_f32_e32 v3, v32, v20
	v_cvt_pk_bf16_f32 v3, v3, s0
	v_lshl_add_u64 v[4:5], v[4:5], 1, s[8:9]
	global_store_short v[4:5], v3, off sc1
	v_add_u32_e32 v4, v189, v16
	s_waitcnt vmcnt(17)
	v_fmac_f32_e32 v19, v10, v102
	v_ashrrev_i32_e32 v5, 31, v4
	v_mul_f32_e32 v3, v32, v19
	v_cvt_pk_bf16_f32 v3, v3, s0
	v_lshl_add_u64 v[4:5], v[4:5], 1, s[8:9]
	global_store_short v[4:5], v3, off sc1
	v_add_u32_e32 v4, v191, v16
	s_waitcnt vmcnt(17)
	v_fmac_f32_e32 v18, v11, v102
	v_ashrrev_i32_e32 v5, 31, v4
	v_mul_f32_e32 v3, v32, v18
	v_cvt_pk_bf16_f32 v3, v3, s0
	v_lshl_add_u64 v[4:5], v[4:5], 1, s[8:9]
	global_store_short v[4:5], v3, off sc1
	v_add_u32_e32 v4, v192, v16
	v_ashrrev_i32_e32 v5, 31, v4
	v_lshl_add_u64 v[4:5], v[4:5], 1, s[8:9]
	v_add_u32_e32 v10, v195, v16
	v_ashrrev_i32_e32 v11, 31, v10
	v_lshl_add_u64 v[10:11], v[10:11], 1, s[8:9]
	s_waitcnt vmcnt(15)
	v_fmac_f32_e32 v17, v12, v102
	v_mul_f32_e32 v3, v32, v17
	v_cvt_pk_bf16_f32 v3, v3, s0
	global_store_short v[4:5], v3, off sc1
	v_add_u32_e32 v4, v193, v16
	v_ashrrev_i32_e32 v5, 31, v4
	v_lshl_add_u64 v[4:5], v[4:5], 1, s[8:9]
	s_waitcnt vmcnt(14)
	v_fmac_f32_e32 v2, v13, v102
	v_mul_f32_e32 v3, v32, v2
	v_cvt_pk_bf16_f32 v3, v3, s0
	global_store_short v[4:5], v3, off sc1
	v_add_u32_e32 v4, v194, v16
	v_ashrrev_i32_e32 v5, 31, v4
	v_lshl_add_u64 v[4:5], v[4:5], 1, s[8:9]
	v_xor_b32_e32 v13, 16, v166
	v_ashrrev_i32_e32 v71, 31, v70
	global_store_dword v[82:83], v26, off offset:384 sc1
	global_store_dword v[78:79], v25, off offset:384 sc1
	global_store_dword v[72:73], v24, off offset:384 sc1
	global_store_dword v[74:75], v23, off offset:384 sc1
	global_store_dword v[76:77], v22, off offset:384 sc1
	global_store_dword v[80:81], v21, off offset:384 sc1
	global_store_dword v[86:87], v20, off offset:384 sc1
	global_store_dword v[90:91], v19, off offset:384 sc1
	global_store_dword v[92:93], v18, off offset:384 sc1
	s_waitcnt vmcnt(20)
	v_fmac_f32_e32 v1, v14, v102
	v_mul_f32_e32 v3, v32, v1
	v_cvt_pk_bf16_f32 v3, v3, s0
	global_store_short v[4:5], v3, off sc1
	v_and_b32_e32 v4, 64, v166
	v_xor_b32_e32 v3, 1, v166
	v_add_u32_e32 v7, 64, v4
	v_cmp_lt_i32_e32 vcc, v3, v7
	v_xor_b32_e32 v4, 2, v166
	s_waitcnt vmcnt(19)
	v_fmac_f32_e32 v0, v15, v102
	v_cndmask_b32_e32 v3, v166, v3, vcc
	v_lshlrev_b32_e32 v3, 2, v3
	s_nop 1
	v_mov_b32_dpp v5, v108 quad_perm:[1,0,3,2] row_mask:0xf bank_mask:0xf
	v_cmp_lt_i32_e32 vcc, v4, v7
	v_mul_f32_e32 v12, v32, v0
	v_cvt_pk_bf16_f32 v12, v12, s0
	v_cndmask_b32_e32 v4, v166, v4, vcc
	v_lshlrev_b32_e32 v4, 2, v4
	s_waitcnt lgkmcnt(0)
	v_add_f32_e32 v6, v108, v5
	s_nop 1
	v_mov_b32_dpp v8, v6 quad_perm:[2,3,0,1] row_mask:0xf bank_mask:0xf
	v_xor_b32_e32 v5, 4, v166
	v_cmp_lt_i32_e32 vcc, v5, v7
	global_store_dword v[94:95], v17, off offset:384 sc1
	global_store_dword v[96:97], v2, off offset:384 sc1
	v_cndmask_b32_e32 v5, v166, v5, vcc
	v_lshlrev_b32_e32 v5, 2, v5
	s_waitcnt lgkmcnt(0)
	v_add_f32_e32 v8, v6, v8
	s_nop 1
	v_mov_b32_dpp v9, v8 row_half_mirror row_mask:0xf bank_mask:0xf
	v_xor_b32_e32 v6, 8, v166
	v_cmp_lt_i32_e32 vcc, v6, v7
	global_store_dword v[98:99], v1, off offset:384 sc1
	global_store_dword v[100:101], v0, off offset:384 sc1
	v_cndmask_b32_e32 v6, v166, v6, vcc
	v_lshlrev_b32_e32 v6, 2, v6
	s_waitcnt lgkmcnt(0)
	v_add_f32_e32 v8, v8, v9
	s_nop 1
	v_mov_b32_dpp v9, v8 row_mirror row_mask:0xf bank_mask:0xf
	v_cmp_lt_i32_e32 vcc, v13, v7
	global_store_short v[10:11], v12, off sc1
	s_waitcnt lgkmcnt(0)
	v_add_f32_e32 v8, v8, v9
	v_cndmask_b32_e32 v7, v166, v13, vcc
	v_lshlrev_b32_e32 v7, 2, v7
	ds_bpermute_b32 v9, v7, v8
	s_and_saveexec_b64 s[60:61], s[0:1]
	s_cbranch_execz .LBB0_709
	s_waitcnt lgkmcnt(0)
	v_add_f32_e32 v10, v8, v9
	v_lshl_add_u64 v[8:9], v[70:71], 2, s[58:59]
	global_store_dword v[8:9], v10, off sc1
.LBB0_709:
	s_or_b64 exec, exec, s[60:61]
	v_mul_f32_e32 v8, v63, v63
	v_fmac_f32_e32 v8, v180, v180
	v_fmac_f32_e32 v8, v45, v45
	v_fmac_f32_e32 v8, v28, v28
	s_waitcnt lgkmcnt(0)
	s_nop 1
	v_mov_b32_dpp v9, v8 quad_perm:[1,0,3,2] row_mask:0xf bank_mask:0xf
	s_waitcnt lgkmcnt(0)
	v_add_f32_e32 v8, v8, v9
	s_nop 1
	v_mov_b32_dpp v9, v8 quad_perm:[2,3,0,1] row_mask:0xf bank_mask:0xf
	s_waitcnt lgkmcnt(0)
	v_add_f32_e32 v8, v8, v9
	s_nop 1
	v_mov_b32_dpp v9, v8 row_half_mirror row_mask:0xf bank_mask:0xf
	s_waitcnt lgkmcnt(0)
	v_add_f32_e32 v8, v8, v9
	s_nop 1
	v_mov_b32_dpp v9, v8 row_mirror row_mask:0xf bank_mask:0xf
	s_waitcnt lgkmcnt(0)
	v_add_f32_e32 v8, v8, v9
	ds_bpermute_b32 v9, v7, v8
	s_and_saveexec_b64 s[60:61], s[0:1]
	s_cbranch_execz .LBB0_711
	s_waitcnt lgkmcnt(0)
	v_add_f32_e32 v10, v8, v9
	v_lshl_add_u64 v[8:9], v[70:71], 2, s[58:59]
	global_store_dword v[8:9], v10, off offset:4 sc1
.LBB0_711:
	s_or_b64 exec, exec, s[60:61]
	v_mul_f32_e32 v8, v62, v62
	v_fmac_f32_e32 v8, v179, v179
	v_fmac_f32_e32 v8, v47, v47
	v_fmac_f32_e32 v8, v27, v27
	s_waitcnt lgkmcnt(0)
	s_nop 1
	v_mov_b32_dpp v9, v8 quad_perm:[1,0,3,2] row_mask:0xf bank_mask:0xf
	s_waitcnt lgkmcnt(0)
	v_add_f32_e32 v8, v8, v9
	s_nop 1
	v_mov_b32_dpp v9, v8 quad_perm:[2,3,0,1] row_mask:0xf bank_mask:0xf
	s_waitcnt lgkmcnt(0)
	v_add_f32_e32 v8, v8, v9
	s_nop 1
	v_mov_b32_dpp v9, v8 row_half_mirror row_mask:0xf bank_mask:0xf
	s_waitcnt lgkmcnt(0)
	v_add_f32_e32 v8, v8, v9
	s_nop 1
	v_mov_b32_dpp v9, v8 row_mirror row_mask:0xf bank_mask:0xf
	s_waitcnt lgkmcnt(0)
	v_add_f32_e32 v8, v8, v9
	ds_bpermute_b32 v9, v7, v8
	s_and_saveexec_b64 s[60:61], s[0:1]
	s_cbranch_execz .LBB0_713
	s_waitcnt lgkmcnt(0)
	v_add_f32_e32 v10, v8, v9
	v_lshl_add_u64 v[8:9], v[70:71], 2, s[58:59]
	global_store_dword v[8:9], v10, off offset:8 sc1
.LBB0_713:
	s_or_b64 exec, exec, s[60:61]
	v_mul_f32_e32 v8, v61, v61
	v_fmac_f32_e32 v8, v178, v178
	v_fmac_f32_e32 v8, v46, v46
	v_fmac_f32_e32 v8, v26, v26
	s_waitcnt lgkmcnt(0)
	s_nop 1
	v_mov_b32_dpp v9, v8 quad_perm:[1,0,3,2] row_mask:0xf bank_mask:0xf
	s_waitcnt lgkmcnt(0)
	v_add_f32_e32 v8, v8, v9
	s_nop 1
	v_mov_b32_dpp v9, v8 quad_perm:[2,3,0,1] row_mask:0xf bank_mask:0xf
	s_waitcnt lgkmcnt(0)
	v_add_f32_e32 v8, v8, v9
	s_nop 1
	v_mov_b32_dpp v9, v8 row_half_mirror row_mask:0xf bank_mask:0xf
	s_waitcnt lgkmcnt(0)
	v_add_f32_e32 v8, v8, v9
	s_nop 1
	v_mov_b32_dpp v9, v8 row_mirror row_mask:0xf bank_mask:0xf
	s_waitcnt lgkmcnt(0)
	v_add_f32_e32 v8, v8, v9
	ds_bpermute_b32 v9, v7, v8
	s_and_saveexec_b64 s[60:61], s[0:1]
	s_cbranch_execz .LBB0_715
	s_waitcnt lgkmcnt(0)
	v_add_f32_e32 v10, v8, v9
	v_lshl_add_u64 v[8:9], v[70:71], 2, s[58:59]
	global_store_dword v[8:9], v10, off offset:12 sc1
.LBB0_715:
	s_or_b64 exec, exec, s[60:61]
	v_mul_f32_e32 v8, v60, v60
	v_fmac_f32_e32 v8, v177, v177
	v_fmac_f32_e32 v8, v44, v44
	v_fmac_f32_e32 v8, v25, v25
	s_waitcnt lgkmcnt(0)
	s_nop 1
	v_mov_b32_dpp v9, v8 quad_perm:[1,0,3,2] row_mask:0xf bank_mask:0xf
	s_waitcnt lgkmcnt(0)
	v_add_f32_e32 v8, v8, v9
	s_nop 1
	v_mov_b32_dpp v9, v8 quad_perm:[2,3,0,1] row_mask:0xf bank_mask:0xf
	s_waitcnt lgkmcnt(0)
	v_add_f32_e32 v8, v8, v9
	s_nop 1
	v_mov_b32_dpp v9, v8 row_half_mirror row_mask:0xf bank_mask:0xf
	s_waitcnt lgkmcnt(0)
	v_add_f32_e32 v8, v8, v9
	s_nop 1
	v_mov_b32_dpp v9, v8 row_mirror row_mask:0xf bank_mask:0xf
	s_waitcnt lgkmcnt(0)
	v_add_f32_e32 v8, v8, v9
	ds_bpermute_b32 v9, v7, v8
	s_and_saveexec_b64 s[60:61], s[0:1]
	s_cbranch_execz .LBB0_717
	s_waitcnt lgkmcnt(0)
	v_add_f32_e32 v10, v8, v9
	v_lshl_add_u64 v[8:9], v[70:71], 2, s[58:59]
	global_store_dword v[8:9], v10, off offset:32 sc1
.LBB0_717:
	s_or_b64 exec, exec, s[60:61]
	v_mul_f32_e32 v8, v59, v59
	v_fmac_f32_e32 v8, v176, v176
	v_fmac_f32_e32 v8, v43, v43
	v_fmac_f32_e32 v8, v24, v24
	s_waitcnt lgkmcnt(0)
	s_nop 1
	v_mov_b32_dpp v9, v8 quad_perm:[1,0,3,2] row_mask:0xf bank_mask:0xf
	s_waitcnt lgkmcnt(0)
	v_add_f32_e32 v8, v8, v9
	s_nop 1
	v_mov_b32_dpp v9, v8 quad_perm:[2,3,0,1] row_mask:0xf bank_mask:0xf
	s_waitcnt lgkmcnt(0)
	v_add_f32_e32 v8, v8, v9
	s_nop 1
	v_mov_b32_dpp v9, v8 row_half_mirror row_mask:0xf bank_mask:0xf
	s_waitcnt lgkmcnt(0)
	v_add_f32_e32 v8, v8, v9
	s_nop 1
	v_mov_b32_dpp v9, v8 row_mirror row_mask:0xf bank_mask:0xf
	s_waitcnt lgkmcnt(0)
	v_add_f32_e32 v8, v8, v9
	ds_bpermute_b32 v9, v7, v8
	s_and_saveexec_b64 s[60:61], s[0:1]
	s_cbranch_execz .LBB0_719
	s_waitcnt lgkmcnt(0)
	v_add_f32_e32 v10, v8, v9
	v_lshl_add_u64 v[8:9], v[70:71], 2, s[58:59]
	global_store_dword v[8:9], v10, off offset:36 sc1
.LBB0_719:
	s_or_b64 exec, exec, s[60:61]
	v_mul_f32_e32 v8, v58, v58
	v_fmac_f32_e32 v8, v175, v175
	v_fmac_f32_e32 v8, v42, v42
	v_fmac_f32_e32 v8, v23, v23
	s_waitcnt lgkmcnt(0)
	s_nop 1
	v_mov_b32_dpp v9, v8 quad_perm:[1,0,3,2] row_mask:0xf bank_mask:0xf
	s_waitcnt lgkmcnt(0)
	v_add_f32_e32 v8, v8, v9
	s_nop 1
	v_mov_b32_dpp v9, v8 quad_perm:[2,3,0,1] row_mask:0xf bank_mask:0xf
	s_waitcnt lgkmcnt(0)
	v_add_f32_e32 v8, v8, v9
	s_nop 1
	v_mov_b32_dpp v9, v8 row_half_mirror row_mask:0xf bank_mask:0xf
	s_waitcnt lgkmcnt(0)
	v_add_f32_e32 v8, v8, v9
	s_nop 1
	v_mov_b32_dpp v9, v8 row_mirror row_mask:0xf bank_mask:0xf
	s_waitcnt lgkmcnt(0)
	v_add_f32_e32 v8, v8, v9
	ds_bpermute_b32 v9, v7, v8
	s_and_saveexec_b64 s[60:61], s[0:1]
	s_cbranch_execz .LBB0_721
	s_waitcnt lgkmcnt(0)
	v_add_f32_e32 v10, v8, v9
	v_lshl_add_u64 v[8:9], v[70:71], 2, s[58:59]
	global_store_dword v[8:9], v10, off offset:40 sc1
.LBB0_721:
	s_or_b64 exec, exec, s[60:61]
	v_mul_f32_e32 v8, v57, v57
	v_fmac_f32_e32 v8, v174, v174
	v_fmac_f32_e32 v8, v41, v41
	v_fmac_f32_e32 v8, v22, v22
	s_waitcnt lgkmcnt(0)
	s_nop 1
	v_mov_b32_dpp v9, v8 quad_perm:[1,0,3,2] row_mask:0xf bank_mask:0xf
	s_waitcnt lgkmcnt(0)
	v_add_f32_e32 v8, v8, v9
	s_nop 1
	v_mov_b32_dpp v9, v8 quad_perm:[2,3,0,1] row_mask:0xf bank_mask:0xf
	s_waitcnt lgkmcnt(0)
	v_add_f32_e32 v8, v8, v9
	s_nop 1
	v_mov_b32_dpp v9, v8 row_half_mirror row_mask:0xf bank_mask:0xf
	s_waitcnt lgkmcnt(0)
	v_add_f32_e32 v8, v8, v9
	s_nop 1
	v_mov_b32_dpp v9, v8 row_mirror row_mask:0xf bank_mask:0xf
	s_waitcnt lgkmcnt(0)
	v_add_f32_e32 v8, v8, v9
	ds_bpermute_b32 v9, v7, v8
	s_and_saveexec_b64 s[60:61], s[0:1]
	s_cbranch_execz .LBB0_723
	s_waitcnt lgkmcnt(0)
	v_add_f32_e32 v10, v8, v9
	v_lshl_add_u64 v[8:9], v[70:71], 2, s[58:59]
	global_store_dword v[8:9], v10, off offset:44 sc1
.LBB0_723:
	s_or_b64 exec, exec, s[60:61]
	v_mul_f32_e32 v8, v56, v56
	v_fmac_f32_e32 v8, v173, v173
	v_fmac_f32_e32 v8, v40, v40
	v_fmac_f32_e32 v8, v21, v21
	s_waitcnt lgkmcnt(0)
	s_nop 1
	v_mov_b32_dpp v9, v8 quad_perm:[1,0,3,2] row_mask:0xf bank_mask:0xf
	s_waitcnt lgkmcnt(0)
	v_add_f32_e32 v8, v8, v9
	s_nop 1
	v_mov_b32_dpp v9, v8 quad_perm:[2,3,0,1] row_mask:0xf bank_mask:0xf
	s_waitcnt lgkmcnt(0)
	v_add_f32_e32 v8, v8, v9
	s_nop 1
	v_mov_b32_dpp v9, v8 row_half_mirror row_mask:0xf bank_mask:0xf
	s_waitcnt lgkmcnt(0)
	v_add_f32_e32 v8, v8, v9
	s_nop 1
	v_mov_b32_dpp v9, v8 row_mirror row_mask:0xf bank_mask:0xf
	s_waitcnt lgkmcnt(0)
	v_add_f32_e32 v8, v8, v9
	ds_bpermute_b32 v9, v7, v8
	s_and_saveexec_b64 s[60:61], s[0:1]
	s_cbranch_execz .LBB0_725
	s_waitcnt lgkmcnt(0)
	v_add_f32_e32 v10, v8, v9
	v_lshl_add_u64 v[8:9], v[70:71], 2, s[58:59]
	global_store_dword v[8:9], v10, off offset:64 sc1
.LBB0_725:
	s_or_b64 exec, exec, s[60:61]
	v_mul_f32_e32 v8, v55, v55
	v_fmac_f32_e32 v8, v172, v172
	v_fmac_f32_e32 v8, v39, v39
	v_fmac_f32_e32 v8, v20, v20
	s_waitcnt lgkmcnt(0)
	s_nop 1
	v_mov_b32_dpp v9, v8 quad_perm:[1,0,3,2] row_mask:0xf bank_mask:0xf
	s_waitcnt lgkmcnt(0)
	v_add_f32_e32 v8, v8, v9
	s_nop 1
	v_mov_b32_dpp v9, v8 quad_perm:[2,3,0,1] row_mask:0xf bank_mask:0xf
	s_waitcnt lgkmcnt(0)
	v_add_f32_e32 v8, v8, v9
	s_nop 1
	v_mov_b32_dpp v9, v8 row_half_mirror row_mask:0xf bank_mask:0xf
	s_waitcnt lgkmcnt(0)
	v_add_f32_e32 v8, v8, v9
	s_nop 1
	v_mov_b32_dpp v9, v8 row_mirror row_mask:0xf bank_mask:0xf
	s_waitcnt lgkmcnt(0)
	v_add_f32_e32 v8, v8, v9
	ds_bpermute_b32 v9, v7, v8
	s_and_saveexec_b64 s[60:61], s[0:1]
	s_cbranch_execz .LBB0_727
	s_waitcnt lgkmcnt(0)
	v_add_f32_e32 v10, v8, v9
	v_lshl_add_u64 v[8:9], v[70:71], 2, s[58:59]
	global_store_dword v[8:9], v10, off offset:68 sc1
.LBB0_727:
	s_or_b64 exec, exec, s[60:61]
	v_mul_f32_e32 v8, v54, v54
	v_fmac_f32_e32 v8, v170, v170
	v_fmac_f32_e32 v8, v38, v38
	v_fmac_f32_e32 v8, v19, v19
	s_waitcnt lgkmcnt(0)
	s_nop 1
	v_mov_b32_dpp v9, v8 quad_perm:[1,0,3,2] row_mask:0xf bank_mask:0xf
	s_waitcnt lgkmcnt(0)
	v_add_f32_e32 v8, v8, v9
	s_nop 1
	v_mov_b32_dpp v9, v8 quad_perm:[2,3,0,1] row_mask:0xf bank_mask:0xf
	s_waitcnt lgkmcnt(0)
	v_add_f32_e32 v8, v8, v9
	s_nop 1
	v_mov_b32_dpp v9, v8 row_half_mirror row_mask:0xf bank_mask:0xf
	s_waitcnt lgkmcnt(0)
	v_add_f32_e32 v8, v8, v9
	s_nop 1
	v_mov_b32_dpp v9, v8 row_mirror row_mask:0xf bank_mask:0xf
	s_waitcnt lgkmcnt(0)
	v_add_f32_e32 v8, v8, v9
	ds_bpermute_b32 v9, v7, v8
	s_and_saveexec_b64 s[60:61], s[0:1]
	s_cbranch_execz .LBB0_729
	s_waitcnt lgkmcnt(0)
	v_add_f32_e32 v10, v8, v9
	v_lshl_add_u64 v[8:9], v[70:71], 2, s[58:59]
	global_store_dword v[8:9], v10, off offset:72 sc1
.LBB0_729:
	s_or_b64 exec, exec, s[60:61]
	v_mul_f32_e32 v8, v53, v53
	v_fmac_f32_e32 v8, v171, v171
	v_fmac_f32_e32 v8, v37, v37
	v_fmac_f32_e32 v8, v18, v18
	s_waitcnt lgkmcnt(0)
	s_nop 1
	v_mov_b32_dpp v9, v8 quad_perm:[1,0,3,2] row_mask:0xf bank_mask:0xf
	s_waitcnt lgkmcnt(0)
	v_add_f32_e32 v8, v8, v9
	s_nop 1
	v_mov_b32_dpp v9, v8 quad_perm:[2,3,0,1] row_mask:0xf bank_mask:0xf
	s_waitcnt lgkmcnt(0)
	v_add_f32_e32 v8, v8, v9
	s_nop 1
	v_mov_b32_dpp v9, v8 row_half_mirror row_mask:0xf bank_mask:0xf
	s_waitcnt lgkmcnt(0)
	v_add_f32_e32 v8, v8, v9
	s_nop 1
	v_mov_b32_dpp v9, v8 row_mirror row_mask:0xf bank_mask:0xf
	s_waitcnt lgkmcnt(0)
	v_add_f32_e32 v8, v8, v9
	ds_bpermute_b32 v9, v7, v8
	s_and_saveexec_b64 s[60:61], s[0:1]
	s_cbranch_execz .LBB0_731
	s_waitcnt lgkmcnt(0)
	v_add_f32_e32 v10, v8, v9
	v_lshl_add_u64 v[8:9], v[70:71], 2, s[58:59]
	global_store_dword v[8:9], v10, off offset:76 sc1
.LBB0_731:
	s_or_b64 exec, exec, s[60:61]
	v_mul_f32_e32 v8, v52, v52
	v_fmac_f32_e32 v8, v169, v169
	v_fmac_f32_e32 v8, v36, v36
	v_fmac_f32_e32 v8, v17, v17
	s_waitcnt lgkmcnt(0)
	s_nop 1
	v_mov_b32_dpp v9, v8 quad_perm:[1,0,3,2] row_mask:0xf bank_mask:0xf
	s_waitcnt lgkmcnt(0)
	v_add_f32_e32 v8, v8, v9
	s_nop 1
	v_mov_b32_dpp v9, v8 quad_perm:[2,3,0,1] row_mask:0xf bank_mask:0xf
	s_waitcnt lgkmcnt(0)
	v_add_f32_e32 v8, v8, v9
	s_nop 1
	v_mov_b32_dpp v9, v8 row_half_mirror row_mask:0xf bank_mask:0xf
	s_waitcnt lgkmcnt(0)
	v_add_f32_e32 v8, v8, v9
	s_nop 1
	v_mov_b32_dpp v9, v8 row_mirror row_mask:0xf bank_mask:0xf
	s_waitcnt lgkmcnt(0)
	v_add_f32_e32 v8, v8, v9
	ds_bpermute_b32 v9, v7, v8
	s_and_saveexec_b64 s[60:61], s[0:1]
	s_cbranch_execz .LBB0_733
	s_waitcnt lgkmcnt(0)
	v_add_f32_e32 v10, v8, v9
	v_lshl_add_u64 v[8:9], v[70:71], 2, s[58:59]
	global_store_dword v[8:9], v10, off offset:96 sc1
.LBB0_733:
	s_or_b64 exec, exec, s[60:61]
	v_mul_f32_e32 v8, v51, v51
	v_fmac_f32_e32 v8, v168, v168
	v_fmac_f32_e32 v8, v35, v35
	v_fmac_f32_e32 v8, v2, v2
	s_nop 1
	v_mov_b32_dpp v2, v8 quad_perm:[1,0,3,2] row_mask:0xf bank_mask:0xf
	s_waitcnt lgkmcnt(0)
	v_add_f32_e32 v2, v8, v2
	s_nop 1
	v_mov_b32_dpp v8, v2 quad_perm:[2,3,0,1] row_mask:0xf bank_mask:0xf
	s_waitcnt lgkmcnt(0)
	v_add_f32_e32 v2, v2, v8
	s_nop 1
	v_mov_b32_dpp v8, v2 row_half_mirror row_mask:0xf bank_mask:0xf
	s_waitcnt lgkmcnt(0)
	v_add_f32_e32 v2, v2, v8
	s_nop 1
	v_mov_b32_dpp v8, v2 row_mirror row_mask:0xf bank_mask:0xf
	s_waitcnt lgkmcnt(0)
	v_add_f32_e32 v2, v2, v8
	ds_bpermute_b32 v8, v7, v2
	s_and_saveexec_b64 s[60:61], s[0:1]
	s_cbranch_execz .LBB0_735
	s_waitcnt lgkmcnt(0)
	v_add_f32_e32 v2, v2, v8
	v_lshl_add_u64 v[8:9], v[70:71], 2, s[58:59]
	global_store_dword v[8:9], v2, off offset:100 sc1
.LBB0_735:
	s_or_b64 exec, exec, s[60:61]
	v_mul_f32_e32 v2, v50, v50
	v_fmac_f32_e32 v2, v167, v167
	v_fmac_f32_e32 v2, v34, v34
	v_fmac_f32_e32 v2, v1, v1
	s_nop 1
	v_mov_b32_dpp v1, v2 quad_perm:[1,0,3,2] row_mask:0xf bank_mask:0xf
	s_waitcnt lgkmcnt(0)
	v_add_f32_e32 v1, v2, v1
	s_nop 1
	v_mov_b32_dpp v2, v1 quad_perm:[2,3,0,1] row_mask:0xf bank_mask:0xf
	s_waitcnt lgkmcnt(0)
	v_add_f32_e32 v1, v1, v2
	s_nop 1
	v_mov_b32_dpp v2, v1 row_half_mirror row_mask:0xf bank_mask:0xf
	s_waitcnt lgkmcnt(0)
	v_add_f32_e32 v1, v1, v2
	s_nop 1
	v_mov_b32_dpp v2, v1 row_mirror row_mask:0xf bank_mask:0xf
	s_waitcnt lgkmcnt(0)
	v_add_f32_e32 v1, v1, v2
	ds_bpermute_b32 v2, v7, v1
	s_and_saveexec_b64 s[60:61], s[0:1]
	s_cbranch_execz .LBB0_737
	s_waitcnt lgkmcnt(0)
	v_add_f32_e32 v1, v1, v2
	v_lshl_add_u64 v[8:9], v[70:71], 2, s[58:59]
	global_store_dword v[8:9], v1, off offset:104 sc1
.LBB0_737:
	s_or_b64 exec, exec, s[60:61]
	v_mul_f32_e32 v1, v49, v49
	v_fmac_f32_e32 v1, v103, v103
	v_fmac_f32_e32 v1, v33, v33
	v_fmac_f32_e32 v1, v0, v0
	s_nop 1
	v_mov_b32_dpp v0, v1 quad_perm:[1,0,3,2] row_mask:0xf bank_mask:0xf
	s_waitcnt lgkmcnt(0)
	v_add_f32_e32 v0, v1, v0
	s_nop 1
	v_mov_b32_dpp v1, v0 quad_perm:[2,3,0,1] row_mask:0xf bank_mask:0xf
	s_waitcnt lgkmcnt(0)
	v_add_f32_e32 v0, v0, v1
	s_nop 1
	v_mov_b32_dpp v1, v0 row_half_mirror row_mask:0xf bank_mask:0xf
	s_waitcnt lgkmcnt(0)
	v_add_f32_e32 v0, v0, v1
	s_nop 1
	v_mov_b32_dpp v1, v0 row_mirror row_mask:0xf bank_mask:0xf
	s_waitcnt lgkmcnt(0)
	v_add_f32_e32 v0, v0, v1
	ds_bpermute_b32 v1, v7, v0
	s_and_saveexec_b64 s[60:61], s[0:1]
	s_cbranch_execz .LBB0_702
	s_waitcnt lgkmcnt(0)
	v_add_f32_e32 v2, v0, v1
	v_lshl_add_u64 v[0:1], v[70:71], 2, s[58:59]
	global_store_dword v[0:1], v2, off offset:108 sc1
	s_branch .LBB0_702

.LBB0_779:
	s_add_i32 s58, s67, 0xffffe000
	s_lshr_b32 s58, s58, 12
	s_mulk_i32 s58, 0x1800
	s_addk_i32 s58, 0x1800
	s_cmp_gt_i32 s6, 63
	s_cselect_b32 s6, s58, 0
	s_lshl_b64 s[58:59], s[6:7], 2
	s_add_u32 s58, s14, s58
	s_addc_u32 s59, s15, s59
	s_add_u32 s60, s58, 0x5ba5000
	s_addc_u32 s61, s59, 0
	s_addk_i32 s6, 0x4800
	s_lshl_b64 s[58:59], s[6:7], 2
	v_mov_b32_e32 v70, s66
	s_add_u32 s6, s14, s58
	ds_read_b64 v[70:71], v70
	s_addc_u32 s65, s15, s59
	s_lshl_b32 s58, s64, 14
	s_add_i32 s58, s58, 0x40000
	s_ashr_i32 s59, s58, 31
	s_lshl_b64 s[58:59], s[58:59], 2
	s_add_u32 s58, s10, s58
	s_waitcnt lgkmcnt(0)
	v_readfirstlane_b32 s62, v70
	s_addc_u32 s59, s11, s59
	v_or_b32_e32 v102, s68, v138
	v_add_u32_e32 v70, s67, v139
	v_readfirstlane_b32 s63, v71
	s_add_u32 s62, s62, 0x1000
	v_ashrrev_i32_e32 v103, 31, v102
	v_lshlrev_b32_e32 v191, 10, v70
	s_addc_u32 s63, s63, 0
	v_lshlrev_b64 v[72:73], 2, v[102:103]
	v_or_b32_e32 v187, 0x400, v191
	v_or_b32_e32 v186, 0x4400, v191
	v_or_b32_e32 v189, 0x4c00, v191
	v_or_b32_e32 v194, 0x6c00, v191
	s_add_u32 s64, s6, 0x5ba1000
	v_lshl_add_u64 v[74:75], s[60:61], 0, v[72:73]
	v_add_u32_e32 v130, v191, v102
	v_add_u32_e32 v132, v187, v102
	v_or_b32_e32 v185, 0x800, v191
	v_or_b32_e32 v184, 0xc00, v191
	v_or_b32_e32 v182, 0x2000, v191
	v_or_b32_e32 v180, 0x2400, v191
	v_or_b32_e32 v71, 0x2800, v191
	v_or_b32_e32 v181, 0x2c00, v191
	v_or_b32_e32 v183, 0x4000, v191
	v_add_u32_e32 v112, v186, v102
	v_or_b32_e32 v188, 0x4800, v191
	v_add_u32_e32 v116, v189, v102
	v_or_b32_e32 v190, 0x6000, v191
	v_or_b32_e32 v192, 0x6400, v191
	v_or_b32_e32 v193, 0x6800, v191
	v_add_u32_e32 v128, v194, v102
	s_addc_u32 s65, s65, 0
	global_load_dword v195, v[74:75], off
	v_lshl_add_u64 v[74:75], s[62:63], 0, v[72:73]
	v_ashrrev_i32_e32 v133, 31, v132
	v_add_u32_e32 v134, v185, v102
	v_add_u32_e32 v136, v184, v102
	v_add_u32_e32 v126, v182, v102
	v_add_u32_e32 v118, v180, v102
	v_add_u32_e32 v110, v71, v102
	v_add_u32_e32 v106, v181, v102
	v_add_u32_e32 v108, v183, v102
	v_ashrrev_i32_e32 v113, 31, v112
	v_add_u32_e32 v114, v188, v102
	v_ashrrev_i32_e32 v117, 31, v116
	v_add_u32_e32 v120, v190, v102
	v_add_u32_e32 v122, v192, v102
	v_add_u32_e32 v124, v193, v102
	v_ashrrev_i32_e32 v129, 31, v128
	v_ashrrev_i32_e32 v131, 31, v130
	v_lshl_add_u64 v[72:73], s[64:65], 0, v[72:73]
	global_load_dword v196, v[74:75], off
	global_load_dword v197, v[72:73], off
	v_lshl_add_u64 v[88:89], v[132:133], 2, s[12:13]
	v_ashrrev_i32_e32 v135, 31, v134
	v_ashrrev_i32_e32 v137, 31, v136
	v_ashrrev_i32_e32 v127, 31, v126
	v_ashrrev_i32_e32 v119, 31, v118
	v_ashrrev_i32_e32 v111, 31, v110
	v_ashrrev_i32_e32 v107, 31, v106
	v_ashrrev_i32_e32 v109, 31, v108
	v_lshl_add_u64 v[86:87], v[112:113], 2, s[12:13]
	v_ashrrev_i32_e32 v115, 31, v114
	v_lshl_add_u64 v[92:93], v[116:117], 2, s[12:13]
	v_ashrrev_i32_e32 v121, 31, v120
	v_ashrrev_i32_e32 v123, 31, v122
	v_ashrrev_i32_e32 v125, 31, v124
	v_lshl_add_u64 v[100:101], v[128:129], 2, s[12:13]
	v_lshl_add_u64 v[104:105], v[130:131], 2, s[12:13]
	v_lshl_add_u64 v[84:85], v[134:135], 2, s[12:13]
	v_lshl_add_u64 v[82:83], v[136:137], 2, s[12:13]
	v_lshl_add_u64 v[78:79], v[126:127], 2, s[12:13]
	v_lshl_add_u64 v[72:73], v[118:119], 2, s[12:13]
	v_lshl_add_u64 v[74:75], v[110:111], 2, s[12:13]
	v_lshl_add_u64 v[76:77], v[106:107], 2, s[12:13]
	v_lshl_add_u64 v[80:81], v[108:109], 2, s[12:13]
	global_load_dword v179, v[88:89], off
	global_load_dword v178, v[84:85], off
	global_load_dword v177, v[82:83], off
	global_load_dword v176, v[78:79], off
	global_load_dword v175, v[72:73], off
	global_load_dword v174, v[74:75], off
	global_load_dword v173, v[76:77], off
	global_load_dword v172, v[80:81], off
	v_lshl_add_u64 v[90:91], v[114:115], 2, s[12:13]
	global_load_dword v171, v[86:87], off
	global_load_dword v169, v[90:91], off
	v_lshl_add_u64 v[94:95], v[120:121], 2, s[12:13]
	v_lshl_add_u64 v[96:97], v[122:123], 2, s[12:13]
	v_lshl_add_u64 v[98:99], v[124:125], 2, s[12:13]
	global_load_dword v170, v[92:93], off
	global_load_dword v168, v[94:95], off
	global_load_dword v167, v[96:97], off
	global_load_dword v166, v[98:99], off
	global_load_dword v103, v[100:101], off
	global_load_dword v198, v[104:105], off
	v_lshl_add_u64 v[110:111], v[110:111], 1, s[8:9]
	v_lshl_add_u64 v[106:107], v[106:107], 1, s[8:9]
	s_waitcnt vmcnt(0)
	v_add_f32_e32 v197, 1.0, v197
	v_mul_f32_e32 v196, v196, v197
	v_fmac_f32_e32 v179, v49, v195
	v_fmac_f32_e32 v178, v50, v195
	v_fmac_f32_e32 v177, v51, v195
	v_fmac_f32_e32 v176, v52, v195
	v_fmac_f32_e32 v175, v53, v195
	v_fmac_f32_e32 v174, v54, v195
	v_fmac_f32_e32 v173, v55, v195
	v_fmac_f32_e32 v172, v56, v195
	v_fmac_f32_e32 v171, v57, v195
	v_fmac_f32_e32 v169, v58, v195
	v_fmac_f32_e32 v170, v59, v195
	v_fmac_f32_e32 v168, v60, v195
	v_fmac_f32_e32 v167, v61, v195
	v_fmac_f32_e32 v166, v62, v195
	v_fmac_f32_e32 v103, v63, v195
	v_fmac_f32_e32 v198, v48, v195
	v_mul_f32_e32 v48, v196, v198
	v_cvt_pk_bf16_f32 v58, v48, s0
	v_or_b32_e32 v48, 32, v102
	v_ashrrev_i32_e32 v49, 31, v48
	v_lshlrev_b64 v[52:53], 2, v[48:49]
	global_store_dword v[88:89], v179, off sc1
	global_store_dword v[84:85], v178, off sc1
	global_store_dword v[82:83], v177, off sc1
	global_store_dword v[78:79], v176, off sc1
	global_store_dword v[72:73], v175, off sc1
	global_store_dword v[74:75], v174, off sc1
	global_store_dword v[76:77], v173, off sc1
	global_store_dword v[80:81], v172, off sc1
	global_store_dword v[86:87], v171, off sc1
	global_store_dword v[90:91], v169, off sc1
	global_store_dword v[92:93], v170, off sc1
	global_store_dword v[94:95], v168, off sc1
	global_store_dword v[96:97], v167, off sc1
	global_store_dword v[98:99], v166, off sc1
	global_store_dword v[100:101], v103, off sc1
	global_store_dword v[104:105], v198, off sc1
	v_lshl_add_u64 v[50:51], v[130:131], 1, s[8:9]
	v_lshl_add_u64 v[56:57], s[64:65], 0, v[52:53]
	global_load_dword v197, v[104:105], off offset:128
	v_lshl_add_u64 v[54:55], s[62:63], 0, v[52:53]
	global_load_dword v130, v[56:57], off
	global_load_dword v131, v[54:55], off
	v_mul_f32_e32 v49, v196, v179
	global_store_short v[50:51], v58, off sc1
	v_lshl_add_u64 v[50:51], s[60:61], 0, v[52:53]
	global_load_dword v195, v[50:51], off
	v_lshl_add_u64 v[50:51], v[132:133], 1, s[8:9]
	v_cvt_pk_bf16_f32 v49, v49, s0
	global_store_short v[50:51], v49, off sc1
	v_mul_f32_e32 v49, v196, v178
	v_lshl_add_u64 v[50:51], v[134:135], 1, s[8:9]
	v_cvt_pk_bf16_f32 v49, v49, s0
	global_store_short v[50:51], v49, off sc1
	v_mul_f32_e32 v49, v196, v177
	v_lshl_add_u64 v[50:51], v[136:137], 1, s[8:9]
	v_cvt_pk_bf16_f32 v49, v49, s0
	global_store_short v[50:51], v49, off sc1
	v_mul_f32_e32 v49, v196, v176
	v_lshl_add_u64 v[50:51], v[126:127], 1, s[8:9]
	v_cvt_pk_bf16_f32 v49, v49, s0
	global_store_short v[50:51], v49, off sc1
	v_mul_f32_e32 v49, v196, v175
	v_lshl_add_u64 v[50:51], v[118:119], 1, s[8:9]
	v_cvt_pk_bf16_f32 v49, v49, s0
	global_load_dword v62, v[84:85], off offset:128
	global_load_dword v60, v[78:79], off offset:128
	global_load_dword v59, v[72:73], off offset:128
	global_load_dword v58, v[74:75], off offset:128
	global_load_dword v56, v[80:81], off offset:128
	global_load_dword v57, v[76:77], off offset:128
	global_load_dword v55, v[86:87], off offset:128
	global_load_dword v61, v[82:83], off offset:128
	global_load_dword v54, v[90:91], off offset:128
	global_load_dword v53, v[92:93], off offset:128
	global_load_dword v52, v[94:95], off offset:128
	v_mul_f32_e32 v63, v196, v174
	global_store_short v[50:51], v49, off sc1
	global_load_dword v51, v[96:97], off offset:128
	v_cvt_pk_bf16_f32 v63, v63, s0
	global_load_dword v50, v[98:99], off offset:128
	global_load_dword v49, v[100:101], off offset:128
	s_waitcnt vmcnt(19)
	v_fmac_f32_e32 v197, v32, v195
	global_store_short v[110:111], v63, off sc1
	global_load_dword v63, v[88:89], off offset:128
	v_mul_f32_e32 v110, v196, v173
	v_cvt_pk_bf16_f32 v110, v110, s0
	global_store_short v[106:107], v110, off sc1
	v_lshl_add_u64 v[106:107], v[108:109], 1, s[8:9]
	v_mul_f32_e32 v108, v196, v172
	v_cvt_pk_bf16_f32 v108, v108, s0
	global_store_short v[106:107], v108, off sc1
	v_mul_f32_e32 v108, v196, v171
	v_lshl_add_u64 v[106:107], v[112:113], 1, s[8:9]
	v_cvt_pk_bf16_f32 v108, v108, s0
	global_store_short v[106:107], v108, off sc1
	v_mul_f32_e32 v108, v196, v169
	v_lshl_add_u64 v[106:107], v[114:115], 1, s[8:9]
	v_cvt_pk_bf16_f32 v108, v108, s0
	global_store_short v[106:107], v108, off sc1
	v_mul_f32_e32 v108, v196, v170
	v_lshl_add_u64 v[106:107], v[116:117], 1, s[8:9]
	v_cvt_pk_bf16_f32 v108, v108, s0
	global_store_short v[106:107], v108, off sc1
	v_mul_f32_e32 v108, v196, v168
	v_lshl_add_u64 v[106:107], v[120:121], 1, s[8:9]
	v_cvt_pk_bf16_f32 v108, v108, s0
	global_store_short v[106:107], v108, off sc1
	v_mul_f32_e32 v108, v196, v167
	v_lshl_add_u64 v[106:107], v[122:123], 1, s[8:9]
	v_cvt_pk_bf16_f32 v108, v108, s0
	global_store_short v[106:107], v108, off sc1
	v_mul_f32_e32 v108, v196, v166
	v_lshl_add_u64 v[106:107], v[124:125], 1, s[8:9]
	v_cvt_pk_bf16_f32 v108, v108, s0
	global_store_short v[106:107], v108, off sc1
	v_mul_f32_e32 v108, v196, v103
	v_lshl_add_u64 v[106:107], v[128:129], 1, s[8:9]
	v_cvt_pk_bf16_f32 v108, v108, s0
	global_store_short v[106:107], v108, off sc1
	v_add_f32_e32 v106, 1.0, v130
	v_mul_f32_e32 v107, v131, v106
	v_add_u32_e32 v108, v191, v48
	v_ashrrev_i32_e32 v109, 31, v108
	v_mul_f32_e32 v32, v107, v197
	s_waitcnt vmcnt(25)
	v_fmac_f32_e32 v62, v34, v195
	s_waitcnt vmcnt(18)
	v_fmac_f32_e32 v61, v35, v195
	v_fmac_f32_e32 v60, v36, v195
	v_fmac_f32_e32 v59, v37, v195
	v_fmac_f32_e32 v58, v38, v195
	v_fmac_f32_e32 v57, v39, v195
	v_fmac_f32_e32 v56, v40, v195
	v_fmac_f32_e32 v55, v41, v195
	s_waitcnt vmcnt(17)
	v_fmac_f32_e32 v54, v42, v195
	s_waitcnt vmcnt(16)
	v_fmac_f32_e32 v53, v43, v195
	s_waitcnt vmcnt(15)
	v_fmac_f32_e32 v52, v44, v195
	s_waitcnt vmcnt(13)
	v_fmac_f32_e32 v51, v45, v195
	s_waitcnt vmcnt(12)
	v_fmac_f32_e32 v50, v46, v195
	s_waitcnt vmcnt(11)
	v_fmac_f32_e32 v49, v47, v195
	global_store_dword v[104:105], v197, off offset:128 sc1
	v_lshl_add_u64 v[108:109], v[108:109], 1, s[8:9]
	v_cvt_pk_bf16_f32 v32, v32, s0
	global_store_dword v[84:85], v62, off offset:128 sc1
	global_store_dword v[82:83], v61, off offset:128 sc1
	global_store_dword v[78:79], v60, off offset:128 sc1
	global_store_dword v[72:73], v59, off offset:128 sc1
	global_store_dword v[74:75], v58, off offset:128 sc1
	global_store_dword v[76:77], v57, off offset:128 sc1
	global_store_dword v[80:81], v56, off offset:128 sc1
	global_store_dword v[86:87], v55, off offset:128 sc1
	global_store_dword v[90:91], v54, off offset:128 sc1
	global_store_dword v[92:93], v53, off offset:128 sc1
	global_store_dword v[94:95], v52, off offset:128 sc1
	global_store_dword v[96:97], v51, off offset:128 sc1
	global_store_dword v[98:99], v50, off offset:128 sc1
	global_store_dword v[100:101], v49, off offset:128 sc1
	global_store_short v[108:109], v32, off sc1
	v_add_u32_e32 v108, v187, v48
	global_load_dword v45, v[88:89], off offset:256
	v_ashrrev_i32_e32 v109, 31, v108
	v_mul_f32_e32 v113, v107, v56
	v_cvt_pk_bf16_f32 v113, v113, s0
	v_mul_f32_e32 v106, v197, v197
	v_fmac_f32_e32 v106, v198, v198
	s_waitcnt vmcnt(26)
	v_fmac_f32_e32 v63, v33, v195
	v_mul_f32_e32 v34, v107, v63
	v_lshl_add_u64 v[32:33], v[108:109], 1, s[8:9]
	v_cvt_pk_bf16_f32 v34, v34, s0
	global_store_short v[32:33], v34, off sc1
	v_add_u32_e32 v32, v185, v48
	v_ashrrev_i32_e32 v33, 31, v32
	v_mul_f32_e32 v34, v107, v62
	v_lshl_add_u64 v[32:33], v[32:33], 1, s[8:9]
	v_cvt_pk_bf16_f32 v34, v34, s0
	global_store_short v[32:33], v34, off sc1
	v_add_u32_e32 v32, v184, v48
	v_ashrrev_i32_e32 v33, 31, v32
	v_mul_f32_e32 v34, v107, v61
	v_lshl_add_u64 v[32:33], v[32:33], 1, s[8:9]
	v_cvt_pk_bf16_f32 v34, v34, s0
	global_store_short v[32:33], v34, off sc1
	v_add_u32_e32 v32, v182, v48
	v_ashrrev_i32_e32 v33, 31, v32
	v_mul_f32_e32 v34, v107, v60
	v_lshl_add_u64 v[32:33], v[32:33], 1, s[8:9]
	v_cvt_pk_bf16_f32 v34, v34, s0
	global_store_short v[32:33], v34, off sc1
	v_add_u32_e32 v32, v180, v48
	v_ashrrev_i32_e32 v33, 31, v32
	v_lshl_add_u64 v[34:35], v[32:33], 1, s[8:9]
	v_mul_f32_e32 v32, v107, v59
	v_cvt_pk_bf16_f32 v42, v32, s0
	v_or_b32_e32 v32, 64, v102
	v_ashrrev_i32_e32 v33, 31, v32
	v_lshlrev_b64 v[36:37], 2, v[32:33]
	global_store_dword v[88:89], v63, off offset:128 sc1
	v_lshl_add_u64 v[40:41], s[64:65], 0, v[36:37]
	v_lshl_add_u64 v[38:39], s[62:63], 0, v[36:37]
	global_load_dword v110, v[40:41], off
	global_load_dword v111, v[38:39], off
	v_mul_f32_e32 v33, v107, v58
	global_store_short v[34:35], v42, off sc1
	v_lshl_add_u64 v[34:35], s[60:61], 0, v[36:37]
	global_load_dword v112, v[34:35], off
	v_add_u32_e32 v34, v71, v48
	v_ashrrev_i32_e32 v35, 31, v34
	v_lshl_add_u64 v[34:35], v[34:35], 1, s[8:9]
	v_cvt_pk_bf16_f32 v33, v33, s0
	global_store_short v[34:35], v33, off sc1
	v_add_u32_e32 v34, v181, v48
	v_ashrrev_i32_e32 v35, 31, v34
	v_mul_f32_e32 v33, v107, v57
	v_lshl_add_u64 v[34:35], v[34:35], 1, s[8:9]
	v_cvt_pk_bf16_f32 v33, v33, s0
	global_load_dword v38, v[90:91], off offset:256
	global_load_dword v37, v[92:93], off offset:256
	global_load_dword v36, v[94:95], off offset:256
	global_load_dword v114, v[104:105], off offset:256
	global_load_dword v47, v[84:85], off offset:256
	global_load_dword v39, v[86:87], off offset:256
	global_load_dword v46, v[82:83], off offset:256
	global_load_dword v44, v[78:79], off offset:256
	global_load_dword v43, v[72:73], off offset:256
	global_load_dword v42, v[74:75], off offset:256
	global_load_dword v40, v[80:81], off offset:256
	global_load_dword v41, v[76:77], off offset:256
	v_add_u32_e32 v108, v183, v48
	global_store_short v[34:35], v33, off sc1
	global_load_dword v35, v[96:97], off offset:256
	v_ashrrev_i32_e32 v109, 31, v108
	global_load_dword v34, v[98:99], off offset:256
	global_load_dword v33, v[100:101], off offset:256
	v_lshl_add_u64 v[108:109], v[108:109], 1, s[8:9]
	global_store_short v[108:109], v113, off sc1
	v_add_u32_e32 v108, v186, v48
	v_ashrrev_i32_e32 v109, 31, v108
	v_mul_f32_e32 v113, v107, v55
	v_lshl_add_u64 v[108:109], v[108:109], 1, s[8:9]
	v_cvt_pk_bf16_f32 v113, v113, s0
	global_store_short v[108:109], v113, off sc1
	v_add_u32_e32 v108, v188, v48
	v_ashrrev_i32_e32 v109, 31, v108
	v_mul_f32_e32 v113, v107, v54
	v_lshl_add_u64 v[108:109], v[108:109], 1, s[8:9]
	v_cvt_pk_bf16_f32 v113, v113, s0
	global_store_short v[108:109], v113, off sc1
	v_add_u32_e32 v108, v189, v48
	v_ashrrev_i32_e32 v109, 31, v108
	v_mul_f32_e32 v113, v107, v53
	v_lshl_add_u64 v[108:109], v[108:109], 1, s[8:9]
	v_cvt_pk_bf16_f32 v113, v113, s0
	global_store_short v[108:109], v113, off sc1
	v_add_u32_e32 v108, v190, v48
	v_ashrrev_i32_e32 v109, 31, v108
	v_mul_f32_e32 v113, v107, v52
	v_lshl_add_u64 v[108:109], v[108:109], 1, s[8:9]
	v_cvt_pk_bf16_f32 v113, v113, s0
	global_store_short v[108:109], v113, off sc1
	v_add_u32_e32 v108, v192, v48
	v_ashrrev_i32_e32 v109, 31, v108
	v_mul_f32_e32 v113, v107, v51
	v_lshl_add_u64 v[108:109], v[108:109], 1, s[8:9]
	v_cvt_pk_bf16_f32 v113, v113, s0
	global_store_short v[108:109], v113, off sc1
	v_add_u32_e32 v108, v193, v48
	v_ashrrev_i32_e32 v109, 31, v108
	v_mul_f32_e32 v113, v107, v50
	v_lshl_add_u64 v[108:109], v[108:109], 1, s[8:9]
	v_cvt_pk_bf16_f32 v113, v113, s0
	global_store_short v[108:109], v113, off sc1
	v_add_u32_e32 v108, v194, v48
	v_ashrrev_i32_e32 v109, 31, v108
	v_mul_f32_e32 v48, v107, v49
	v_lshl_add_u64 v[108:109], v[108:109], 1, s[8:9]
	v_cvt_pk_bf16_f32 v48, v48, s0
	global_store_short v[108:109], v48, off sc1
	v_add_u32_e32 v108, v191, v32
	v_ashrrev_i32_e32 v109, 31, v108
	s_waitcnt vmcnt(28)
	v_add_f32_e32 v48, 1.0, v110
	s_waitcnt vmcnt(27)
	v_mul_f32_e32 v48, v111, v48
	s_waitcnt vmcnt(25)
	v_fmac_f32_e32 v45, v17, v112
	global_store_dword v[88:89], v45, off offset:256 sc1
	s_waitcnt vmcnt(24)
	v_fmac_f32_e32 v38, v26, v112
	s_waitcnt vmcnt(23)
	v_fmac_f32_e32 v37, v27, v112
	s_waitcnt vmcnt(22)
	v_fmac_f32_e32 v36, v28, v112
	s_waitcnt vmcnt(21)
	v_fmac_f32_e32 v114, v16, v112
	s_waitcnt vmcnt(20)
	v_fmac_f32_e32 v47, v18, v112
	v_mul_f32_e32 v18, v48, v114
	v_lshl_add_u64 v[16:17], v[108:109], 1, s[8:9]
	v_cvt_pk_bf16_f32 v18, v18, s0
	global_store_short v[16:17], v18, off sc1
	v_add_u32_e32 v16, v187, v32
	v_ashrrev_i32_e32 v17, 31, v16
	v_mul_f32_e32 v18, v48, v45
	v_lshl_add_u64 v[16:17], v[16:17], 1, s[8:9]
	v_cvt_pk_bf16_f32 v18, v18, s0
	global_store_short v[16:17], v18, off sc1
	v_add_u32_e32 v16, v185, v32
	v_ashrrev_i32_e32 v17, 31, v16
	v_mul_f32_e32 v18, v48, v47
	v_lshl_add_u64 v[16:17], v[16:17], 1, s[8:9]
	v_cvt_pk_bf16_f32 v18, v18, s0
	s_waitcnt vmcnt(20)
	v_fmac_f32_e32 v46, v19, v112
	global_store_short v[16:17], v18, off sc1
	v_add_u32_e32 v16, v184, v32
	v_ashrrev_i32_e32 v17, 31, v16
	v_mul_f32_e32 v18, v48, v46
	v_lshl_add_u64 v[16:17], v[16:17], 1, s[8:9]
	v_cvt_pk_bf16_f32 v18, v18, s0
	global_store_short v[16:17], v18, off sc1
	v_add_u32_e32 v16, v182, v32
	v_ashrrev_i32_e32 v17, 31, v16
	v_lshl_add_u64 v[18:19], v[16:17], 1, s[8:9]
	v_or_b32_e32 v16, 0x60, v102
	v_ashrrev_i32_e32 v17, 31, v16
	s_waitcnt vmcnt(21)
	v_fmac_f32_e32 v44, v20, v112
	s_waitcnt vmcnt(20)
	v_fmac_f32_e32 v43, v21, v112
	s_waitcnt vmcnt(19)
	v_fmac_f32_e32 v42, v22, v112
	s_waitcnt vmcnt(17)
	v_fmac_f32_e32 v41, v23, v112
	v_fmac_f32_e32 v40, v24, v112
	v_fmac_f32_e32 v39, v25, v112
	s_waitcnt vmcnt(15)
	v_fmac_f32_e32 v35, v29, v112
	s_waitcnt vmcnt(14)
	v_fmac_f32_e32 v34, v30, v112
	s_waitcnt vmcnt(13)
	v_fmac_f32_e32 v33, v31, v112
	v_lshlrev_b64 v[20:21], 2, v[16:17]
	global_store_dword v[84:85], v47, off offset:256 sc1
	global_store_dword v[82:83], v46, off offset:256 sc1
	global_store_dword v[78:79], v44, off offset:256 sc1
	global_store_dword v[72:73], v43, off offset:256 sc1
	global_store_dword v[74:75], v42, off offset:256 sc1
	global_store_dword v[76:77], v41, off offset:256 sc1
	global_store_dword v[80:81], v40, off offset:256 sc1
	global_store_dword v[86:87], v39, off offset:256 sc1
	global_store_dword v[90:91], v38, off offset:256 sc1
	global_store_dword v[92:93], v37, off offset:256 sc1
	global_store_dword v[94:95], v36, off offset:256 sc1
	global_store_dword v[96:97], v35, off offset:256 sc1
	global_store_dword v[98:99], v34, off offset:256 sc1
	global_store_dword v[100:101], v33, off offset:256 sc1
	global_store_dword v[104:105], v114, off offset:256 sc1
	v_mul_f32_e32 v26, v48, v44
	v_lshl_add_u64 v[22:23], s[62:63], 0, v[20:21]
	v_lshl_add_u64 v[24:25], s[64:65], 0, v[20:21]
	global_load_dword v29, v[104:105], off offset:384
	global_load_dword v17, v[24:25], off
	global_load_dword v30, v[22:23], off
	v_cvt_pk_bf16_f32 v22, v26, s0
	global_store_short v[18:19], v22, off sc1
	v_lshl_add_u64 v[18:19], s[60:61], 0, v[20:21]
	global_load_dword v102, v[18:19], off
	v_add_u32_e32 v18, v180, v32
	v_ashrrev_i32_e32 v19, 31, v18
	v_mul_f32_e32 v20, v48, v43
	v_lshl_add_u64 v[18:19], v[18:19], 1, s[8:9]
	v_cvt_pk_bf16_f32 v20, v20, s0
	global_store_short v[18:19], v20, off sc1
	v_add_u32_e32 v18, v71, v32
	v_ashrrev_i32_e32 v19, 31, v18
	v_mul_f32_e32 v20, v48, v42
	v_lshl_add_u64 v[18:19], v[18:19], 1, s[8:9]
	v_cvt_pk_bf16_f32 v20, v20, s0
	global_store_short v[18:19], v20, off sc1
	v_add_u32_e32 v18, v181, v32
	v_ashrrev_i32_e32 v19, 31, v18
	v_mul_f32_e32 v20, v48, v41
	v_lshl_add_u64 v[18:19], v[18:19], 1, s[8:9]
	v_cvt_pk_bf16_f32 v20, v20, s0
	global_store_short v[18:19], v20, off sc1
	v_add_u32_e32 v18, v183, v32
	v_ashrrev_i32_e32 v19, 31, v18
	v_mul_f32_e32 v20, v48, v40
	v_lshl_add_u64 v[18:19], v[18:19], 1, s[8:9]
	v_cvt_pk_bf16_f32 v20, v20, s0
	global_store_short v[18:19], v20, off sc1
	v_add_u32_e32 v18, v186, v32
	v_ashrrev_i32_e32 v19, 31, v18
	v_mul_f32_e32 v20, v48, v39
	v_lshl_add_u64 v[18:19], v[18:19], 1, s[8:9]
	v_cvt_pk_bf16_f32 v20, v20, s0
	global_store_short v[18:19], v20, off sc1
	v_add_u32_e32 v18, v188, v32
	v_ashrrev_i32_e32 v19, 31, v18
	v_mul_f32_e32 v20, v48, v38
	v_lshl_add_u64 v[18:19], v[18:19], 1, s[8:9]
	v_cvt_pk_bf16_f32 v20, v20, s0
	global_store_short v[18:19], v20, off sc1
	v_add_u32_e32 v18, v189, v32
	v_ashrrev_i32_e32 v19, 31, v18
	v_mul_f32_e32 v20, v48, v37
	v_lshl_add_u64 v[18:19], v[18:19], 1, s[8:9]
	v_cvt_pk_bf16_f32 v20, v20, s0
	global_store_short v[18:19], v20, off sc1
	v_add_u32_e32 v18, v190, v32
	v_ashrrev_i32_e32 v19, 31, v18
	v_mul_f32_e32 v20, v48, v36
	v_lshl_add_u64 v[18:19], v[18:19], 1, s[8:9]
	v_cvt_pk_bf16_f32 v20, v20, s0
	global_store_short v[18:19], v20, off sc1
	v_add_u32_e32 v18, v192, v32
	v_ashrrev_i32_e32 v19, 31, v18
	v_mul_f32_e32 v20, v48, v35
	v_lshl_add_u64 v[18:19], v[18:19], 1, s[8:9]
	v_cvt_pk_bf16_f32 v20, v20, s0
	global_load_dword v28, v[88:89], off offset:384
	global_load_dword v27, v[84:85], off offset:384
	global_load_dword v25, v[78:79], off offset:384
	global_load_dword v24, v[72:73], off offset:384
	global_load_dword v23, v[74:75], off offset:384
	global_load_dword v21, v[80:81], off offset:384
	global_load_dword v22, v[76:77], off offset:384
	v_fmac_f32_e32 v106, v114, v114
	global_store_short v[18:19], v20, off sc1
	v_add_u32_e32 v18, v193, v32
	v_ashrrev_i32_e32 v19, 31, v18
	v_mul_f32_e32 v20, v48, v34
	v_lshl_add_u64 v[18:19], v[18:19], 1, s[8:9]
	v_cvt_pk_bf16_f32 v20, v20, s0
	global_store_short v[18:19], v20, off sc1
	v_add_u32_e32 v18, v194, v32
	v_ashrrev_i32_e32 v19, 31, v18
	v_mul_f32_e32 v20, v48, v33
	v_lshl_add_u64 v[18:19], v[18:19], 1, s[8:9]
	v_cvt_pk_bf16_f32 v20, v20, s0
	global_store_short v[18:19], v20, off sc1
	global_load_dword v20, v[86:87], off offset:384
	s_waitcnt vmcnt(22)
	v_add_f32_e32 v17, 1.0, v17
	global_load_dword v26, v[82:83], off offset:384
	s_waitcnt vmcnt(22)
	v_mul_f32_e32 v32, v30, v17
	v_add_u32_e32 v18, v191, v16
	s_waitcnt vmcnt(20)
	v_fmac_f32_e32 v29, v0, v102
	v_ashrrev_i32_e32 v19, 31, v18
	v_mul_f32_e32 v0, v32, v29
	v_lshl_add_u64 v[18:19], v[18:19], 1, s[8:9]
	v_cvt_pk_bf16_f32 v0, v0, s0
	global_store_short v[18:19], v0, off sc1
	global_load_dword v19, v[90:91], off offset:384
	v_add_u32_e32 v30, v187, v16
	global_load_dword v18, v[92:93], off offset:384
	v_ashrrev_i32_e32 v31, 31, v30
	v_fmac_f32_e32 v106, v29, v29
	global_store_dword v[104:105], v29, off offset:384 sc1
	s_waitcnt vmcnt(15)
	v_fmac_f32_e32 v28, v1, v102
	v_mul_f32_e32 v17, v32, v28
	v_lshl_add_u64 v[0:1], v[30:31], 1, s[8:9]
	v_cvt_pk_bf16_f32 v17, v17, s0
	global_store_short v[0:1], v17, off sc1
	v_add_u32_e32 v0, v185, v16
	s_waitcnt vmcnt(15)
	v_fmac_f32_e32 v27, v2, v102
	global_load_dword v17, v[94:95], off offset:384
	v_ashrrev_i32_e32 v1, 31, v0
	v_mul_f32_e32 v2, v32, v27
	v_lshl_add_u64 v[0:1], v[0:1], 1, s[8:9]
	v_cvt_pk_bf16_f32 v2, v2, s0
	global_store_short v[0:1], v2, off sc1
	v_add_u32_e32 v0, v184, v16
	global_load_dword v2, v[96:97], off offset:384
	v_ashrrev_i32_e32 v1, 31, v0
	v_lshl_add_u64 v[0:1], v[0:1], 1, s[8:9]
	v_add_u32_e32 v30, v182, v16
	s_waitcnt vmcnt(17)
	v_fmac_f32_e32 v25, v4, v102
	v_ashrrev_i32_e32 v31, 31, v30
	v_lshl_add_u64 v[30:31], v[30:31], 1, s[8:9]
	s_waitcnt vmcnt(16)
	v_fmac_f32_e32 v24, v5, v102
	s_waitcnt vmcnt(15)
	v_fmac_f32_e32 v23, v6, v102
	s_waitcnt vmcnt(8)
	v_fmac_f32_e32 v26, v3, v102
	v_mul_f32_e32 v3, v32, v26
	v_cvt_pk_bf16_f32 v3, v3, s0
	global_store_short v[0:1], v3, off sc1
	global_load_dword v1, v[98:99], off offset:384
	v_mul_f32_e32 v0, v32, v25
	v_cvt_pk_bf16_f32 v0, v0, s0
	global_store_short v[30:31], v0, off sc1
	global_load_dword v0, v[100:101], off offset:384
	v_add_u32_e32 v30, v180, v16
	v_ashrrev_i32_e32 v31, 31, v30
	v_mul_f32_e32 v3, v32, v24
	v_lshl_add_u64 v[4:5], v[30:31], 1, s[8:9]
	v_cvt_pk_bf16_f32 v3, v3, s0
	global_store_short v[4:5], v3, off sc1
	v_add_u32_e32 v4, v71, v16
	v_ashrrev_i32_e32 v5, 31, v4
	v_mul_f32_e32 v3, v32, v23
	v_lshl_add_u64 v[4:5], v[4:5], 1, s[8:9]
	v_cvt_pk_bf16_f32 v3, v3, s0
	global_store_short v[4:5], v3, off sc1
	v_add_u32_e32 v4, v181, v16
	v_fmac_f32_e32 v22, v7, v102
	v_ashrrev_i32_e32 v5, 31, v4
	v_mul_f32_e32 v3, v32, v22
	v_lshl_add_u64 v[4:5], v[4:5], 1, s[8:9]
	v_cvt_pk_bf16_f32 v3, v3, s0
	global_store_short v[4:5], v3, off sc1
	v_add_u32_e32 v4, v183, v16
	v_fmac_f32_e32 v21, v8, v102
	v_ashrrev_i32_e32 v5, 31, v4
	v_mul_f32_e32 v3, v32, v21
	v_lshl_add_u64 v[4:5], v[4:5], 1, s[8:9]
	v_cvt_pk_bf16_f32 v3, v3, s0
	global_store_short v[4:5], v3, off sc1
	v_add_u32_e32 v4, v186, v16
	v_fmac_f32_e32 v20, v9, v102
	v_ashrrev_i32_e32 v5, 31, v4
	v_mul_f32_e32 v3, v32, v20
	v_lshl_add_u64 v[4:5], v[4:5], 1, s[8:9]
	v_cvt_pk_bf16_f32 v3, v3, s0
	global_store_short v[4:5], v3, off sc1
	v_add_u32_e32 v4, v188, v16
	s_waitcnt vmcnt(15)
	v_fmac_f32_e32 v19, v10, v102
	v_ashrrev_i32_e32 v5, 31, v4
	v_mul_f32_e32 v3, v32, v19
	v_lshl_add_u64 v[4:5], v[4:5], 1, s[8:9]
	v_cvt_pk_bf16_f32 v3, v3, s0
	global_store_short v[4:5], v3, off sc1
	v_add_u32_e32 v4, v189, v16
	s_waitcnt vmcnt(15)
	v_fmac_f32_e32 v18, v11, v102
	v_ashrrev_i32_e32 v5, 31, v4
	v_mul_f32_e32 v3, v32, v18
	v_lshl_add_u64 v[4:5], v[4:5], 1, s[8:9]
	v_cvt_pk_bf16_f32 v3, v3, s0
	global_store_short v[4:5], v3, off sc1
	v_add_u32_e32 v4, v190, v16
	v_ashrrev_i32_e32 v5, 31, v4
	v_lshl_add_u64 v[4:5], v[4:5], 1, s[8:9]
	v_ashrrev_i32_e32 v71, 31, v70
	global_store_dword v[88:89], v28, off offset:384 sc1
	global_store_dword v[84:85], v27, off offset:384 sc1
	global_store_dword v[82:83], v26, off offset:384 sc1
	global_store_dword v[78:79], v25, off offset:384 sc1
	s_waitcnt vmcnt(17)
	v_fmac_f32_e32 v17, v12, v102
	v_mul_f32_e32 v3, v32, v17
	v_cvt_pk_bf16_f32 v3, v3, s0
	global_store_short v[4:5], v3, off sc1
	v_add_u32_e32 v4, v192, v16
	v_ashrrev_i32_e32 v5, 31, v4
	v_lshl_add_u64 v[4:5], v[4:5], 1, s[8:9]
	s_waitcnt vmcnt(16)
	v_fmac_f32_e32 v2, v13, v102
	v_mul_f32_e32 v3, v32, v2
	v_cvt_pk_bf16_f32 v3, v3, s0
	global_store_short v[4:5], v3, off sc1
	v_add_u32_e32 v4, v193, v16
	v_ashrrev_i32_e32 v5, 31, v4
	v_lshl_add_u64 v[4:5], v[4:5], 1, s[8:9]
	v_xor_b32_e32 v12, 16, v165
	global_store_dword v[72:73], v24, off offset:384 sc1
	global_store_dword v[74:75], v23, off offset:384 sc1
	global_store_dword v[76:77], v22, off offset:384 sc1
	global_store_dword v[80:81], v21, off offset:384 sc1
	global_store_dword v[86:87], v20, off offset:384 sc1
	s_waitcnt vmcnt(20)
	v_fmac_f32_e32 v1, v14, v102
	v_mul_f32_e32 v3, v32, v1
	v_cvt_pk_bf16_f32 v3, v3, s0
	global_store_short v[4:5], v3, off sc1
	v_add_u32_e32 v4, v194, v16
	v_ashrrev_i32_e32 v5, 31, v4
	v_lshl_add_u64 v[10:11], v[4:5], 1, s[8:9]
	v_and_b32_e32 v4, 64, v165
	v_xor_b32_e32 v3, 1, v165
	v_add_u32_e32 v7, 64, v4
	v_cmp_lt_i32_e32 vcc, v3, v7
	v_xor_b32_e32 v4, 2, v165
	s_waitcnt vmcnt(19)
	v_fmac_f32_e32 v0, v15, v102
	v_cndmask_b32_e32 v3, v165, v3, vcc
	v_lshlrev_b32_e32 v3, 2, v3
	s_nop 1
	v_mov_b32_dpp v5, v106 quad_perm:[1,0,3,2] row_mask:0xf bank_mask:0xf
	v_cmp_lt_i32_e32 vcc, v4, v7
	global_store_dword v[90:91], v19, off offset:384 sc1
	global_store_dword v[92:93], v18, off offset:384 sc1
	v_cndmask_b32_e32 v4, v165, v4, vcc
	v_lshlrev_b32_e32 v4, 2, v4
	s_waitcnt lgkmcnt(0)
	v_add_f32_e32 v6, v106, v5
	s_nop 1
	v_mov_b32_dpp v8, v6 quad_perm:[2,3,0,1] row_mask:0xf bank_mask:0xf
	v_xor_b32_e32 v5, 4, v165
	v_cmp_lt_i32_e32 vcc, v5, v7
	global_store_dword v[94:95], v17, off offset:384 sc1
	global_store_dword v[96:97], v2, off offset:384 sc1
	v_cndmask_b32_e32 v5, v165, v5, vcc
	v_lshlrev_b32_e32 v5, 2, v5
	s_waitcnt lgkmcnt(0)
	v_add_f32_e32 v8, v6, v8
	s_nop 1
	v_mov_b32_dpp v9, v8 row_half_mirror row_mask:0xf bank_mask:0xf
	v_xor_b32_e32 v6, 8, v165
	v_cmp_lt_i32_e32 vcc, v6, v7
	global_store_dword v[98:99], v1, off offset:384 sc1
	global_store_dword v[100:101], v0, off offset:384 sc1
	v_cndmask_b32_e32 v6, v165, v6, vcc
	v_lshlrev_b32_e32 v6, 2, v6
	s_waitcnt lgkmcnt(0)
	v_add_f32_e32 v8, v8, v9
	s_nop 1
	v_mov_b32_dpp v9, v8 row_mirror row_mask:0xf bank_mask:0xf
	v_cmp_lt_i32_e32 vcc, v12, v7
	s_waitcnt lgkmcnt(0)
	v_add_f32_e32 v8, v8, v9
	v_cndmask_b32_e32 v7, v165, v12, vcc
	v_lshlrev_b32_e32 v7, 2, v7
	ds_bpermute_b32 v9, v7, v8
	v_mul_f32_e32 v12, v32, v0
	v_cvt_pk_bf16_f32 v12, v12, s0
	global_store_short v[10:11], v12, off sc1
	s_and_saveexec_b64 s[60:61], s[0:1]
	s_cbranch_execz .LBB0_781
	s_waitcnt lgkmcnt(0)
	v_add_f32_e32 v10, v8, v9
	v_lshl_add_u64 v[8:9], v[70:71], 2, s[58:59]
	global_store_dword v[8:9], v10, off sc1
.LBB0_781:
	s_or_b64 exec, exec, s[60:61]
	v_mul_f32_e32 v8, v63, v63
	v_fmac_f32_e32 v8, v179, v179
	v_fmac_f32_e32 v8, v45, v45
	v_fmac_f32_e32 v8, v28, v28
	s_waitcnt lgkmcnt(0)
	s_nop 1
	v_mov_b32_dpp v9, v8 quad_perm:[1,0,3,2] row_mask:0xf bank_mask:0xf
	s_waitcnt lgkmcnt(0)
	v_add_f32_e32 v8, v8, v9
	s_nop 1
	v_mov_b32_dpp v9, v8 quad_perm:[2,3,0,1] row_mask:0xf bank_mask:0xf
	s_waitcnt lgkmcnt(0)
	v_add_f32_e32 v8, v8, v9
	s_nop 1
	v_mov_b32_dpp v9, v8 row_half_mirror row_mask:0xf bank_mask:0xf
	s_waitcnt lgkmcnt(0)
	v_add_f32_e32 v8, v8, v9
	s_nop 1
	v_mov_b32_dpp v9, v8 row_mirror row_mask:0xf bank_mask:0xf
	s_waitcnt lgkmcnt(0)
	v_add_f32_e32 v8, v8, v9
	ds_bpermute_b32 v9, v7, v8
	s_and_saveexec_b64 s[60:61], s[0:1]
	s_cbranch_execz .LBB0_783
	s_waitcnt lgkmcnt(0)
	v_add_f32_e32 v10, v8, v9
	v_lshl_add_u64 v[8:9], v[70:71], 2, s[58:59]
	global_store_dword v[8:9], v10, off offset:4 sc1
.LBB0_783:
	s_or_b64 exec, exec, s[60:61]
	v_mul_f32_e32 v8, v62, v62
	v_fmac_f32_e32 v8, v178, v178
	v_fmac_f32_e32 v8, v47, v47
	v_fmac_f32_e32 v8, v27, v27
	s_waitcnt lgkmcnt(0)
	s_nop 1
	v_mov_b32_dpp v9, v8 quad_perm:[1,0,3,2] row_mask:0xf bank_mask:0xf
	s_waitcnt lgkmcnt(0)
	v_add_f32_e32 v8, v8, v9
	s_nop 1
	v_mov_b32_dpp v9, v8 quad_perm:[2,3,0,1] row_mask:0xf bank_mask:0xf
	s_waitcnt lgkmcnt(0)
	v_add_f32_e32 v8, v8, v9
	s_nop 1
	v_mov_b32_dpp v9, v8 row_half_mirror row_mask:0xf bank_mask:0xf
	s_waitcnt lgkmcnt(0)
	v_add_f32_e32 v8, v8, v9
	s_nop 1
	v_mov_b32_dpp v9, v8 row_mirror row_mask:0xf bank_mask:0xf
	s_waitcnt lgkmcnt(0)
	v_add_f32_e32 v8, v8, v9
	ds_bpermute_b32 v9, v7, v8
	s_and_saveexec_b64 s[60:61], s[0:1]
	s_cbranch_execz .LBB0_785
	s_waitcnt lgkmcnt(0)
	v_add_f32_e32 v10, v8, v9
	v_lshl_add_u64 v[8:9], v[70:71], 2, s[58:59]
	global_store_dword v[8:9], v10, off offset:8 sc1
.LBB0_785:
	s_or_b64 exec, exec, s[60:61]
	v_mul_f32_e32 v8, v61, v61
	v_fmac_f32_e32 v8, v177, v177
	v_fmac_f32_e32 v8, v46, v46
	v_fmac_f32_e32 v8, v26, v26
	s_waitcnt lgkmcnt(0)
	s_nop 1
	v_mov_b32_dpp v9, v8 quad_perm:[1,0,3,2] row_mask:0xf bank_mask:0xf
	s_waitcnt lgkmcnt(0)
	v_add_f32_e32 v8, v8, v9
	s_nop 1
	v_mov_b32_dpp v9, v8 quad_perm:[2,3,0,1] row_mask:0xf bank_mask:0xf
	s_waitcnt lgkmcnt(0)
	v_add_f32_e32 v8, v8, v9
	s_nop 1
	v_mov_b32_dpp v9, v8 row_half_mirror row_mask:0xf bank_mask:0xf
	s_waitcnt lgkmcnt(0)
	v_add_f32_e32 v8, v8, v9
	s_nop 1
	v_mov_b32_dpp v9, v8 row_mirror row_mask:0xf bank_mask:0xf
	s_waitcnt lgkmcnt(0)
	v_add_f32_e32 v8, v8, v9
	ds_bpermute_b32 v9, v7, v8
	s_and_saveexec_b64 s[60:61], s[0:1]
	s_cbranch_execz .LBB0_787
	s_waitcnt lgkmcnt(0)
	v_add_f32_e32 v10, v8, v9
	v_lshl_add_u64 v[8:9], v[70:71], 2, s[58:59]
	global_store_dword v[8:9], v10, off offset:12 sc1
.LBB0_787:
	s_or_b64 exec, exec, s[60:61]
	v_mul_f32_e32 v8, v60, v60
	v_fmac_f32_e32 v8, v176, v176
	v_fmac_f32_e32 v8, v44, v44
	v_fmac_f32_e32 v8, v25, v25
	s_waitcnt lgkmcnt(0)
	s_nop 1
	v_mov_b32_dpp v9, v8 quad_perm:[1,0,3,2] row_mask:0xf bank_mask:0xf
	s_waitcnt lgkmcnt(0)
	v_add_f32_e32 v8, v8, v9
	s_nop 1
	v_mov_b32_dpp v9, v8 quad_perm:[2,3,0,1] row_mask:0xf bank_mask:0xf
	s_waitcnt lgkmcnt(0)
	v_add_f32_e32 v8, v8, v9
	s_nop 1
	v_mov_b32_dpp v9, v8 row_half_mirror row_mask:0xf bank_mask:0xf
	s_waitcnt lgkmcnt(0)
	v_add_f32_e32 v8, v8, v9
	s_nop 1
	v_mov_b32_dpp v9, v8 row_mirror row_mask:0xf bank_mask:0xf
	s_waitcnt lgkmcnt(0)
	v_add_f32_e32 v8, v8, v9
	ds_bpermute_b32 v9, v7, v8
	s_and_saveexec_b64 s[60:61], s[0:1]
	s_cbranch_execz .LBB0_789
	s_waitcnt lgkmcnt(0)
	v_add_f32_e32 v10, v8, v9
	v_lshl_add_u64 v[8:9], v[70:71], 2, s[58:59]
	global_store_dword v[8:9], v10, off offset:32 sc1
.LBB0_789:
	s_or_b64 exec, exec, s[60:61]
	v_mul_f32_e32 v8, v59, v59
	v_fmac_f32_e32 v8, v175, v175
	v_fmac_f32_e32 v8, v43, v43
	v_fmac_f32_e32 v8, v24, v24
	s_waitcnt lgkmcnt(0)
	s_nop 1
	v_mov_b32_dpp v9, v8 quad_perm:[1,0,3,2] row_mask:0xf bank_mask:0xf
	s_waitcnt lgkmcnt(0)
	v_add_f32_e32 v8, v8, v9
	s_nop 1
	v_mov_b32_dpp v9, v8 quad_perm:[2,3,0,1] row_mask:0xf bank_mask:0xf
	s_waitcnt lgkmcnt(0)
	v_add_f32_e32 v8, v8, v9
	s_nop 1
	v_mov_b32_dpp v9, v8 row_half_mirror row_mask:0xf bank_mask:0xf
	s_waitcnt lgkmcnt(0)
	v_add_f32_e32 v8, v8, v9
	s_nop 1
	v_mov_b32_dpp v9, v8 row_mirror row_mask:0xf bank_mask:0xf
	s_waitcnt lgkmcnt(0)
	v_add_f32_e32 v8, v8, v9
	ds_bpermute_b32 v9, v7, v8
	s_and_saveexec_b64 s[60:61], s[0:1]
	s_cbranch_execz .LBB0_791
	s_waitcnt lgkmcnt(0)
	v_add_f32_e32 v10, v8, v9
	v_lshl_add_u64 v[8:9], v[70:71], 2, s[58:59]
	global_store_dword v[8:9], v10, off offset:36 sc1
.LBB0_791:
	s_or_b64 exec, exec, s[60:61]
	v_mul_f32_e32 v8, v58, v58
	v_fmac_f32_e32 v8, v174, v174
	v_fmac_f32_e32 v8, v42, v42
	v_fmac_f32_e32 v8, v23, v23
	s_waitcnt lgkmcnt(0)
	s_nop 1
	v_mov_b32_dpp v9, v8 quad_perm:[1,0,3,2] row_mask:0xf bank_mask:0xf
	s_waitcnt lgkmcnt(0)
	v_add_f32_e32 v8, v8, v9
	s_nop 1
	v_mov_b32_dpp v9, v8 quad_perm:[2,3,0,1] row_mask:0xf bank_mask:0xf
	s_waitcnt lgkmcnt(0)
	v_add_f32_e32 v8, v8, v9
	s_nop 1
	v_mov_b32_dpp v9, v8 row_half_mirror row_mask:0xf bank_mask:0xf
	s_waitcnt lgkmcnt(0)
	v_add_f32_e32 v8, v8, v9
	s_nop 1
	v_mov_b32_dpp v9, v8 row_mirror row_mask:0xf bank_mask:0xf
	s_waitcnt lgkmcnt(0)
	v_add_f32_e32 v8, v8, v9
	ds_bpermute_b32 v9, v7, v8
	s_and_saveexec_b64 s[60:61], s[0:1]
	s_cbranch_execz .LBB0_793
	s_waitcnt lgkmcnt(0)
	v_add_f32_e32 v10, v8, v9
	v_lshl_add_u64 v[8:9], v[70:71], 2, s[58:59]
	global_store_dword v[8:9], v10, off offset:40 sc1
.LBB0_793:
	s_or_b64 exec, exec, s[60:61]
	v_mul_f32_e32 v8, v57, v57
	v_fmac_f32_e32 v8, v173, v173
	v_fmac_f32_e32 v8, v41, v41
	v_fmac_f32_e32 v8, v22, v22
	s_waitcnt lgkmcnt(0)
	s_nop 1
	v_mov_b32_dpp v9, v8 quad_perm:[1,0,3,2] row_mask:0xf bank_mask:0xf
	s_waitcnt lgkmcnt(0)
	v_add_f32_e32 v8, v8, v9
	s_nop 1
	v_mov_b32_dpp v9, v8 quad_perm:[2,3,0,1] row_mask:0xf bank_mask:0xf
	s_waitcnt lgkmcnt(0)
	v_add_f32_e32 v8, v8, v9
	s_nop 1
	v_mov_b32_dpp v9, v8 row_half_mirror row_mask:0xf bank_mask:0xf
	s_waitcnt lgkmcnt(0)
	v_add_f32_e32 v8, v8, v9
	s_nop 1
	v_mov_b32_dpp v9, v8 row_mirror row_mask:0xf bank_mask:0xf
	s_waitcnt lgkmcnt(0)
	v_add_f32_e32 v8, v8, v9
	ds_bpermute_b32 v9, v7, v8
	s_and_saveexec_b64 s[60:61], s[0:1]
	s_cbranch_execz .LBB0_795
	s_waitcnt lgkmcnt(0)
	v_add_f32_e32 v10, v8, v9
	v_lshl_add_u64 v[8:9], v[70:71], 2, s[58:59]
	global_store_dword v[8:9], v10, off offset:44 sc1
.LBB0_795:
	s_or_b64 exec, exec, s[60:61]
	v_mul_f32_e32 v8, v56, v56
	v_fmac_f32_e32 v8, v172, v172
	v_fmac_f32_e32 v8, v40, v40
	v_fmac_f32_e32 v8, v21, v21
	s_waitcnt lgkmcnt(0)
	s_nop 1
	v_mov_b32_dpp v9, v8 quad_perm:[1,0,3,2] row_mask:0xf bank_mask:0xf
	s_waitcnt lgkmcnt(0)
	v_add_f32_e32 v8, v8, v9
	s_nop 1
	v_mov_b32_dpp v9, v8 quad_perm:[2,3,0,1] row_mask:0xf bank_mask:0xf
	s_waitcnt lgkmcnt(0)
	v_add_f32_e32 v8, v8, v9
	s_nop 1
	v_mov_b32_dpp v9, v8 row_half_mirror row_mask:0xf bank_mask:0xf
	s_waitcnt lgkmcnt(0)
	v_add_f32_e32 v8, v8, v9
	s_nop 1
	v_mov_b32_dpp v9, v8 row_mirror row_mask:0xf bank_mask:0xf
	s_waitcnt lgkmcnt(0)
	v_add_f32_e32 v8, v8, v9
	ds_bpermute_b32 v9, v7, v8
	s_and_saveexec_b64 s[60:61], s[0:1]
	s_cbranch_execz .LBB0_797
	s_waitcnt lgkmcnt(0)
	v_add_f32_e32 v10, v8, v9
	v_lshl_add_u64 v[8:9], v[70:71], 2, s[58:59]
	global_store_dword v[8:9], v10, off offset:64 sc1
.LBB0_797:
	s_or_b64 exec, exec, s[60:61]
	v_mul_f32_e32 v8, v55, v55
	v_fmac_f32_e32 v8, v171, v171
	v_fmac_f32_e32 v8, v39, v39
	v_fmac_f32_e32 v8, v20, v20
	s_waitcnt lgkmcnt(0)
	s_nop 1
	v_mov_b32_dpp v9, v8 quad_perm:[1,0,3,2] row_mask:0xf bank_mask:0xf
	s_waitcnt lgkmcnt(0)
	v_add_f32_e32 v8, v8, v9
	s_nop 1
	v_mov_b32_dpp v9, v8 quad_perm:[2,3,0,1] row_mask:0xf bank_mask:0xf
	s_waitcnt lgkmcnt(0)
	v_add_f32_e32 v8, v8, v9
	s_nop 1
	v_mov_b32_dpp v9, v8 row_half_mirror row_mask:0xf bank_mask:0xf
	s_waitcnt lgkmcnt(0)
	v_add_f32_e32 v8, v8, v9
	s_nop 1
	v_mov_b32_dpp v9, v8 row_mirror row_mask:0xf bank_mask:0xf
	s_waitcnt lgkmcnt(0)
	v_add_f32_e32 v8, v8, v9
	ds_bpermute_b32 v9, v7, v8
	s_and_saveexec_b64 s[60:61], s[0:1]
	s_cbranch_execz .LBB0_799
	s_waitcnt lgkmcnt(0)
	v_add_f32_e32 v10, v8, v9
	v_lshl_add_u64 v[8:9], v[70:71], 2, s[58:59]
	global_store_dword v[8:9], v10, off offset:68 sc1
.LBB0_799:
	s_or_b64 exec, exec, s[60:61]
	v_mul_f32_e32 v8, v54, v54
	v_fmac_f32_e32 v8, v169, v169
	v_fmac_f32_e32 v8, v38, v38
	v_fmac_f32_e32 v8, v19, v19
	s_waitcnt lgkmcnt(0)
	s_nop 1
	v_mov_b32_dpp v9, v8 quad_perm:[1,0,3,2] row_mask:0xf bank_mask:0xf
	s_waitcnt lgkmcnt(0)
	v_add_f32_e32 v8, v8, v9
	s_nop 1
	v_mov_b32_dpp v9, v8 quad_perm:[2,3,0,1] row_mask:0xf bank_mask:0xf
	s_waitcnt lgkmcnt(0)
	v_add_f32_e32 v8, v8, v9
	s_nop 1
	v_mov_b32_dpp v9, v8 row_half_mirror row_mask:0xf bank_mask:0xf
	s_waitcnt lgkmcnt(0)
	v_add_f32_e32 v8, v8, v9
	s_nop 1
	v_mov_b32_dpp v9, v8 row_mirror row_mask:0xf bank_mask:0xf
	s_waitcnt lgkmcnt(0)
	v_add_f32_e32 v8, v8, v9
	ds_bpermute_b32 v9, v7, v8
	s_and_saveexec_b64 s[60:61], s[0:1]
	s_cbranch_execz .LBB0_801
	s_waitcnt lgkmcnt(0)
	v_add_f32_e32 v10, v8, v9
	v_lshl_add_u64 v[8:9], v[70:71], 2, s[58:59]
	global_store_dword v[8:9], v10, off offset:72 sc1
.LBB0_801:
	s_or_b64 exec, exec, s[60:61]
	v_mul_f32_e32 v8, v53, v53
	v_fmac_f32_e32 v8, v170, v170
	v_fmac_f32_e32 v8, v37, v37
	v_fmac_f32_e32 v8, v18, v18
	s_waitcnt lgkmcnt(0)
	s_nop 1
	v_mov_b32_dpp v9, v8 quad_perm:[1,0,3,2] row_mask:0xf bank_mask:0xf
	s_waitcnt lgkmcnt(0)
	v_add_f32_e32 v8, v8, v9
	s_nop 1
	v_mov_b32_dpp v9, v8 quad_perm:[2,3,0,1] row_mask:0xf bank_mask:0xf
	s_waitcnt lgkmcnt(0)
	v_add_f32_e32 v8, v8, v9
	s_nop 1
	v_mov_b32_dpp v9, v8 row_half_mirror row_mask:0xf bank_mask:0xf
	s_waitcnt lgkmcnt(0)
	v_add_f32_e32 v8, v8, v9
	s_nop 1
	v_mov_b32_dpp v9, v8 row_mirror row_mask:0xf bank_mask:0xf
	s_waitcnt lgkmcnt(0)
	v_add_f32_e32 v8, v8, v9
	ds_bpermute_b32 v9, v7, v8
	s_and_saveexec_b64 s[60:61], s[0:1]
	s_cbranch_execz .LBB0_803
	s_waitcnt lgkmcnt(0)
	v_add_f32_e32 v10, v8, v9
	v_lshl_add_u64 v[8:9], v[70:71], 2, s[58:59]
	global_store_dword v[8:9], v10, off offset:76 sc1
.LBB0_803:
	s_or_b64 exec, exec, s[60:61]
	v_mul_f32_e32 v8, v52, v52
	v_fmac_f32_e32 v8, v168, v168
	v_fmac_f32_e32 v8, v36, v36
	v_fmac_f32_e32 v8, v17, v17
	s_waitcnt lgkmcnt(0)
	s_nop 1
	v_mov_b32_dpp v9, v8 quad_perm:[1,0,3,2] row_mask:0xf bank_mask:0xf
	s_waitcnt lgkmcnt(0)
	v_add_f32_e32 v8, v8, v9
	s_nop 1
	v_mov_b32_dpp v9, v8 quad_perm:[2,3,0,1] row_mask:0xf bank_mask:0xf
	s_waitcnt lgkmcnt(0)
	v_add_f32_e32 v8, v8, v9
	s_nop 1
	v_mov_b32_dpp v9, v8 row_half_mirror row_mask:0xf bank_mask:0xf
	s_waitcnt lgkmcnt(0)
	v_add_f32_e32 v8, v8, v9
	s_nop 1
	v_mov_b32_dpp v9, v8 row_mirror row_mask:0xf bank_mask:0xf
	s_waitcnt lgkmcnt(0)
	v_add_f32_e32 v8, v8, v9
	ds_bpermute_b32 v9, v7, v8
	s_and_saveexec_b64 s[60:61], s[0:1]
	s_cbranch_execz .LBB0_805
	s_waitcnt lgkmcnt(0)
	v_add_f32_e32 v10, v8, v9
	v_lshl_add_u64 v[8:9], v[70:71], 2, s[58:59]
	global_store_dword v[8:9], v10, off offset:96 sc1
.LBB0_805:
	s_or_b64 exec, exec, s[60:61]
	v_mul_f32_e32 v8, v51, v51
	v_fmac_f32_e32 v8, v167, v167
	v_fmac_f32_e32 v8, v35, v35
	v_fmac_f32_e32 v8, v2, v2
	s_nop 1
	v_mov_b32_dpp v2, v8 quad_perm:[1,0,3,2] row_mask:0xf bank_mask:0xf
	s_waitcnt lgkmcnt(0)
	v_add_f32_e32 v2, v8, v2
	s_nop 1
	v_mov_b32_dpp v8, v2 quad_perm:[2,3,0,1] row_mask:0xf bank_mask:0xf
	s_waitcnt lgkmcnt(0)
	v_add_f32_e32 v2, v2, v8
	s_nop 1
	v_mov_b32_dpp v8, v2 row_half_mirror row_mask:0xf bank_mask:0xf
	s_waitcnt lgkmcnt(0)
	v_add_f32_e32 v2, v2, v8
	s_nop 1
	v_mov_b32_dpp v8, v2 row_mirror row_mask:0xf bank_mask:0xf
	s_waitcnt lgkmcnt(0)
	v_add_f32_e32 v2, v2, v8
	ds_bpermute_b32 v8, v7, v2
	s_and_saveexec_b64 s[60:61], s[0:1]
	s_cbranch_execz .LBB0_807
	s_waitcnt lgkmcnt(0)
	v_add_f32_e32 v2, v2, v8
	v_lshl_add_u64 v[8:9], v[70:71], 2, s[58:59]
	global_store_dword v[8:9], v2, off offset:100 sc1
.LBB0_807:
	s_or_b64 exec, exec, s[60:61]
	v_mul_f32_e32 v2, v50, v50
	v_fmac_f32_e32 v2, v166, v166
	v_fmac_f32_e32 v2, v34, v34
	v_fmac_f32_e32 v2, v1, v1
	s_nop 1
	v_mov_b32_dpp v1, v2 quad_perm:[1,0,3,2] row_mask:0xf bank_mask:0xf
	s_waitcnt lgkmcnt(0)
	v_add_f32_e32 v1, v2, v1
	s_nop 1
	v_mov_b32_dpp v2, v1 quad_perm:[2,3,0,1] row_mask:0xf bank_mask:0xf
	s_waitcnt lgkmcnt(0)
	v_add_f32_e32 v1, v1, v2
	s_nop 1
	v_mov_b32_dpp v2, v1 row_half_mirror row_mask:0xf bank_mask:0xf
	s_waitcnt lgkmcnt(0)
	v_add_f32_e32 v1, v1, v2
	s_nop 1
	v_mov_b32_dpp v2, v1 row_mirror row_mask:0xf bank_mask:0xf
	s_waitcnt lgkmcnt(0)
	v_add_f32_e32 v1, v1, v2
	ds_bpermute_b32 v2, v7, v1
	s_and_saveexec_b64 s[60:61], s[0:1]
	s_cbranch_execz .LBB0_809
	s_waitcnt lgkmcnt(0)
	v_add_f32_e32 v1, v1, v2
	v_lshl_add_u64 v[8:9], v[70:71], 2, s[58:59]
	global_store_dword v[8:9], v1, off offset:104 sc1

.LBB0_846:
	s_and_b64 vcc, exec, s[0:1]
	s_cbranch_vccz .LBB0_827
	v_mov_b32_e32 v10, s84
	ds_read_b64 v[10:11], v10
	s_lshl_b32 s0, s8, 6
	s_ashr_i32 s1, s0, 31
	s_lshl_b64 s[0:1], s[0:1], 2
	v_and_b32_e32 v15, 64, v204
	s_waitcnt lgkmcnt(0)
	v_readfirstlane_b32 s70, v10
	v_readfirstlane_b32 s71, v11
	s_add_u32 s0, s70, s0
	s_addc_u32 s1, s71, s1
	global_load_dword v11, v197, s[0:1]
	global_load_dword v10, v197, s[0:1] offset:128
	v_xor_b32_e32 v14, 1, v204
	v_add_u32_e32 v15, 64, v15
	v_pk_mul_f32 v[12:13], v[86:87], v[86:87]
	v_cmp_lt_i32_e32 vcc, v14, v15
	v_add_f32_e32 v12, v13, v12
	s_cmp_eq_u32 s8, 1
	v_cndmask_b32_e32 v13, v204, v14, vcc
	v_lshlrev_b32_e32 v100, 2, v13
	s_nop 1
	v_mov_b32_dpp v13, v12 quad_perm:[1,0,3,2] row_mask:0xf bank_mask:0xf
	v_xor_b32_e32 v14, 2, v204
	v_cmp_lt_i32_e32 vcc, v14, v15
	s_cselect_b64 s[0:1], -1, 0
	s_xor_b64 s[70:71], s[4:5], -1
	v_cndmask_b32_e32 v14, v204, v14, vcc
	v_lshlrev_b32_e32 v101, 2, v14
	s_waitcnt lgkmcnt(0)
	v_add_f32_e32 v12, v12, v13
	s_nop 1
	v_mov_b32_dpp v13, v12 quad_perm:[2,3,0,1] row_mask:0xf bank_mask:0xf
	v_xor_b32_e32 v14, 4, v204
	v_cmp_lt_i32_e32 vcc, v14, v15
	s_and_b64 s[70:71], s[70:71], s[0:1]
	v_lshl_or_b32 v134, s72, 7, v140
	v_cndmask_b32_e32 v14, v204, v14, vcc
	v_lshlrev_b32_e32 v102, 2, v14
	s_waitcnt lgkmcnt(0)
	v_add_f32_e32 v12, v12, v13
	s_nop 1
	v_mov_b32_dpp v13, v12 row_half_mirror row_mask:0xf bank_mask:0xf
	v_xor_b32_e32 v14, 8, v204
	v_cmp_lt_i32_e32 vcc, v14, v15
	s_waitcnt lgkmcnt(0)
	v_add_f32_e32 v12, v12, v13
	v_cndmask_b32_e32 v14, v204, v14, vcc
	v_lshlrev_b32_e32 v103, 2, v14
	s_nop 1
	v_mov_b32_dpp v13, v12 row_mirror row_mask:0xf bank_mask:0xf
	v_xor_b32_e32 v14, 16, v204
	v_cmp_lt_i32_e32 vcc, v14, v15
	s_waitcnt lgkmcnt(0)
	v_add_f32_e32 v12, v12, v13
	v_cndmask_b32_e32 v14, v204, v14, vcc
	v_lshlrev_b32_e32 v104, 2, v14
	ds_bpermute_b32 v13, v104, v12
	s_and_b64 vcc, exec, s[70:71]
	s_waitcnt lgkmcnt(0)
	v_add_f32_e32 v12, v12, v13
	v_fmamk_f32 v12, v12, 0x3c800000, v196
	v_rsq_f32_e32 v12, v12
	v_add_u32_e32 v144, s69, v160
	v_lshl_or_b32 v144, v144, 5, v140
	v_lshlrev_b32_e32 v144, 3, v144
	global_load_dwordx2 v[144:145], v144, s[24:25]
	v_add_u32_e32 v146, s69, v168
	v_lshl_or_b32 v146, v146, 5, v140
	v_lshlrev_b32_e32 v146, 3, v146
	global_load_dwordx2 v[146:147], v146, s[24:25]
	v_add_u32_e32 v184, s69, v169
	v_lshl_or_b32 v184, v184, 5, v140
	v_lshlrev_b32_e32 v184, 3, v184
	global_load_dwordx2 v[184:185], v184, s[24:25]
	v_add_u32_e32 v186, s69, v170
	v_lshl_or_b32 v186, v186, 5, v140
	v_lshlrev_b32_e32 v186, 3, v186
	global_load_dwordx2 v[186:187], v186, s[24:25]
	v_add_u32_e32 v226, s69, v171
	v_lshl_or_b32 v226, v226, 5, v140
	v_lshlrev_b32_e32 v226, 3, v226
	global_load_dwordx2 v[226:227], v226, s[24:25]
	v_add_u32_e32 v230, s69, v172
	v_lshl_or_b32 v230, v230, 5, v140
	v_lshlrev_b32_e32 v230, 3, v230
	global_load_dwordx2 v[230:231], v230, s[24:25]
	v_add_u32_e32 v232, s69, v173
	v_lshl_or_b32 v232, v232, 5, v140
	v_lshlrev_b32_e32 v232, 3, v232
	global_load_dwordx2 v[232:233], v232, s[24:25]
	v_add_u32_e32 v234, s69, v174
	v_lshl_or_b32 v234, v234, 5, v140
	v_lshlrev_b32_e32 v234, 3, v234
	global_load_dwordx2 v[234:235], v234, s[24:25]
	v_add_u32_e32 v236, s69, v175
	v_lshl_or_b32 v236, v236, 5, v140
	v_lshlrev_b32_e32 v236, 3, v236
	global_load_dwordx2 v[236:237], v236, s[24:25]
	v_add_u32_e32 v238, s69, v176
	v_lshl_or_b32 v238, v238, 5, v140
	v_lshlrev_b32_e32 v238, 3, v238
	global_load_dwordx2 v[238:239], v238, s[24:25]
	v_add_u32_e32 v240, s69, v177
	v_lshl_or_b32 v240, v240, 5, v140
	v_lshlrev_b32_e32 v240, 3, v240
	global_load_dwordx2 v[240:241], v240, s[24:25]
	v_add_u32_e32 v242, s69, v178
	v_lshl_or_b32 v242, v242, 5, v140
	v_lshlrev_b32_e32 v242, 3, v242
	global_load_dwordx2 v[242:243], v242, s[24:25]
	v_add_u32_e32 v244, s69, v179
	v_lshl_or_b32 v244, v244, 5, v140
	v_lshlrev_b32_e32 v244, 3, v244
	global_load_dwordx2 v[244:245], v244, s[24:25]
	v_add_u32_e32 v246, s69, v180
	v_lshl_or_b32 v246, v246, 5, v140
	v_lshlrev_b32_e32 v246, 3, v246
	global_load_dwordx2 v[246:247], v246, s[24:25]
	v_add_u32_e32 v248, s69, v181
	v_lshl_or_b32 v248, v248, 5, v140
	v_lshlrev_b32_e32 v248, 3, v248
	global_load_dwordx2 v[248:249], v248, s[24:25]
	v_add_u32_e32 v250, s69, v182
	v_lshl_or_b32 v250, v250, 5, v140
	v_lshlrev_b32_e32 v250, 3, v250
	global_load_dwordx2 v[250:251], v250, s[24:25]
	s_waitcnt vmcnt(0)
	v_pk_mul_f32 v[12:13], v[10:11], v[12:13] op_sel_hi:[1,0]
	s_nop 0
	v_pk_mul_f32 v[14:15], v[86:87], v[12:13]
	s_cbranch_vccz .LBB0_849
	v_lshl_or_b32 v12, v148, 10, v134
	v_ashrrev_i32_e32 v13, 31, v12
	v_lshl_add_u64 v[12:13], v[12:13], 2, s[26:27]
	global_store_dword v[12:13], v15, off sc1
	global_store_dword v[12:13], v14, off offset:128 sc1

.LBB0_851:
	v_pk_mul_f32 v[24:25], v[82:83], v[82:83]
	v_cvt_pk_bf16_f32 v28, v14, s0
	v_add_f32_e32 v13, v25, v24
	s_nop 1
	v_mov_b32_dpp v24, v13 quad_perm:[1,0,3,2] row_mask:0xf bank_mask:0xf
	s_cmp_lt_u32 s86, 8
	s_cselect_b64 s[4:5], -1, 0
	s_and_b64 s[4:5], s[4:5], exec
	s_cselect_b32 s8, s68, s74
	s_waitcnt lgkmcnt(0)
	v_add_f32_e32 v13, v13, v24
	s_nop 1
	v_mov_b32_dpp v24, v13 quad_perm:[2,3,0,1] row_mask:0xf bank_mask:0xf
	s_cselect_b32 s4, s85, 0xdf9f000
	s_add_u32 s4, s14, s4
	s_addc_u32 s5, s15, 0
	v_cvt_pk_bf16_f32 v25, v15, s0
	s_waitcnt lgkmcnt(0)
	v_add_f32_e32 v13, v13, v24
	s_nop 1
	v_mov_b32_dpp v24, v13 row_half_mirror row_mask:0xf bank_mask:0xf
	v_add_u32_e32 v15, s68, v168
	s_and_b64 vcc, exec, s[70:71]
	s_waitcnt lgkmcnt(0)
	v_add_f32_e32 v13, v13, v24
	s_nop 1
	v_mov_b32_dpp v14, v13 row_mirror row_mask:0xf bank_mask:0xf
	v_add_lshl_u32 v24, s8, v160, 10
	v_or_b32_e32 v26, v24, v134
	v_ashrrev_i32_e32 v27, 31, v26
	v_lshl_add_u64 v[26:27], v[26:27], 1, s[4:5]
	s_waitcnt lgkmcnt(0)
	v_add_f32_e32 v13, v13, v14
	ds_bpermute_b32 v14, v104, v13
	global_store_short v[26:27], v25, off sc1
	global_store_short v[26:27], v28, off offset:64 sc1
	s_waitcnt lgkmcnt(0)
	v_add_f32_e32 v13, v13, v14
	v_fmamk_f32 v13, v13, 0x3c800000, v196
	v_rsq_f32_e32 v14, v13
	s_nop 0
	v_pk_mul_f32 v[26:27], v[10:11], v[14:15] op_sel_hi:[1,0]
	s_nop 0
	v_pk_mul_f32 v[28:29], v[82:83], v[26:27]
	s_cbranch_vccz .LBB0_853
	v_lshl_or_b32 v26, v15, 10, v134
	v_ashrrev_i32_e32 v27, 31, v26
	v_lshl_add_u64 v[26:27], v[26:27], 2, s[26:27]
	global_store_dword v[26:27], v29, off sc1
	global_store_dword v[26:27], v28, off offset:128 sc1

.LBB0_855:
	v_pk_mul_f32 v[30:31], v[78:79], v[78:79]
	v_cvt_pk_bf16_f32 v58, v28, s0
	v_add_f32_e32 v13, v31, v30
	s_nop 1
	v_mov_b32_dpp v14, v13 quad_perm:[1,0,3,2] row_mask:0xf bank_mask:0xf
	v_cvt_pk_bf16_f32 v27, v29, s0
	v_add_u32_e32 v29, s68, v169
	s_and_b64 vcc, exec, s[70:71]
	s_waitcnt lgkmcnt(0)
	v_add_f32_e32 v13, v13, v14
	s_nop 1
	v_mov_b32_dpp v14, v13 quad_perm:[2,3,0,1] row_mask:0xf bank_mask:0xf
	s_waitcnt lgkmcnt(0)
	v_add_f32_e32 v13, v13, v14
	s_nop 1
	v_mov_b32_dpp v14, v13 row_half_mirror row_mask:0xf bank_mask:0xf
	s_waitcnt lgkmcnt(0)
	v_add_f32_e32 v13, v13, v14
	s_nop 1
	v_mov_b32_dpp v25, v13 row_mirror row_mask:0xf bank_mask:0xf
	v_add_lshl_u32 v14, s8, v168, 10
	v_or_b32_e32 v30, v14, v134
	v_ashrrev_i32_e32 v31, 31, v30
	v_lshl_add_u64 v[30:31], v[30:31], 1, s[4:5]
	s_waitcnt lgkmcnt(0)
	v_add_f32_e32 v13, v13, v25
	ds_bpermute_b32 v25, v104, v13
	global_store_short v[30:31], v27, off sc1
	global_store_short v[30:31], v58, off offset:64 sc1
	s_waitcnt lgkmcnt(0)
	v_add_f32_e32 v13, v13, v25
	v_fmamk_f32 v13, v13, 0x3c800000, v196
	v_rsq_f32_e32 v28, v13
	s_nop 0
	v_pk_mul_f32 v[30:31], v[10:11], v[28:29] op_sel_hi:[1,0]
	s_nop 0
	v_pk_mul_f32 v[58:59], v[78:79], v[30:31]
	s_cbranch_vccz .LBB0_857
	v_lshl_or_b32 v30, v29, 10, v134
	v_ashrrev_i32_e32 v31, 31, v30
	v_lshl_add_u64 v[30:31], v[30:31], 2, s[26:27]
	global_store_dword v[30:31], v59, off sc1
	global_store_dword v[30:31], v58, off offset:128 sc1

.LBB0_859:
	v_pk_mul_f32 v[60:61], v[74:75], v[74:75]
	v_add_lshl_u32 v28, s8, v169, 10
	v_add_f32_e32 v13, v61, v60
	s_nop 1
	v_mov_b32_dpp v25, v13 quad_perm:[1,0,3,2] row_mask:0xf bank_mask:0xf
	v_cvt_pk_bf16_f32 v31, v58, s0
	v_or_b32_e32 v60, v28, v134
	v_ashrrev_i32_e32 v61, 31, v60
	v_cvt_pk_bf16_f32 v27, v59, s0
	s_waitcnt lgkmcnt(0)
	v_add_f32_e32 v13, v13, v25
	s_nop 1
	v_mov_b32_dpp v25, v13 quad_perm:[2,3,0,1] row_mask:0xf bank_mask:0xf
	v_add_u32_e32 v59, s68, v170
	v_lshl_add_u64 v[60:61], v[60:61], 1, s[4:5]
	global_store_short v[60:61], v27, off sc1
	global_store_short v[60:61], v31, off offset:64 sc1
	s_and_b64 vcc, exec, s[70:71]
	s_waitcnt lgkmcnt(0)
	v_add_f32_e32 v13, v13, v25
	s_nop 1
	v_mov_b32_dpp v25, v13 row_half_mirror row_mask:0xf bank_mask:0xf
	s_waitcnt lgkmcnt(0)
	v_add_f32_e32 v13, v13, v25
	s_nop 1
	v_mov_b32_dpp v25, v13 row_mirror row_mask:0xf bank_mask:0xf
	s_waitcnt lgkmcnt(0)
	v_add_f32_e32 v13, v13, v25
	ds_bpermute_b32 v25, v104, v13
	s_waitcnt lgkmcnt(0)
	v_add_f32_e32 v13, v13, v25
	v_fmamk_f32 v13, v13, 0x3c800000, v196
	v_rsq_f32_e32 v58, v13
	s_nop 0
	v_pk_mul_f32 v[60:61], v[10:11], v[58:59] op_sel_hi:[1,0]
	s_nop 0
	v_pk_mul_f32 v[62:63], v[74:75], v[60:61]
	s_cbranch_vccz .LBB0_861
	v_lshl_or_b32 v60, v59, 10, v134
	v_ashrrev_i32_e32 v61, 31, v60
	v_lshl_add_u64 v[60:61], v[60:61], 2, s[26:27]
	global_store_dword v[60:61], v63, off sc1
	global_store_dword v[60:61], v62, off offset:128 sc1

.LBB0_863:
	v_pk_mul_f32 v[74:75], v[70:71], v[70:71]
	v_add_lshl_u32 v58, s8, v170, 10
	v_add_f32_e32 v13, v75, v74
	s_nop 1
	v_mov_b32_dpp v25, v13 quad_perm:[1,0,3,2] row_mask:0xf bank_mask:0xf
	v_cvt_pk_bf16_f32 v31, v62, s0
	v_or_b32_e32 v74, v58, v134
	v_ashrrev_i32_e32 v75, 31, v74
	v_cvt_pk_bf16_f32 v27, v63, s0
	s_waitcnt lgkmcnt(0)
	v_add_f32_e32 v13, v13, v25
	s_nop 1
	v_mov_b32_dpp v25, v13 quad_perm:[2,3,0,1] row_mask:0xf bank_mask:0xf
	v_add_u32_e32 v63, s68, v171
	v_lshl_add_u64 v[74:75], v[74:75], 1, s[4:5]
	global_store_short v[74:75], v27, off sc1
	global_store_short v[74:75], v31, off offset:64 sc1
	s_and_b64 vcc, exec, s[70:71]
	s_waitcnt lgkmcnt(0)
	v_add_f32_e32 v13, v13, v25
	s_nop 1
	v_mov_b32_dpp v25, v13 row_half_mirror row_mask:0xf bank_mask:0xf
	s_waitcnt lgkmcnt(0)
	v_add_f32_e32 v13, v13, v25
	s_nop 1
	v_mov_b32_dpp v25, v13 row_mirror row_mask:0xf bank_mask:0xf
	s_waitcnt lgkmcnt(0)
	v_add_f32_e32 v13, v13, v25
	ds_bpermute_b32 v25, v104, v13
	s_waitcnt lgkmcnt(0)
	v_add_f32_e32 v13, v13, v25
	v_fmamk_f32 v13, v13, 0x3c800000, v196
	v_rsq_f32_e32 v62, v13
	s_nop 0
	v_pk_mul_f32 v[74:75], v[10:11], v[62:63] op_sel_hi:[1,0]
	s_nop 0
	v_pk_mul_f32 v[74:75], v[70:71], v[74:75]
	s_cbranch_vccz .LBB0_865
	v_lshl_or_b32 v70, v63, 10, v134
	v_ashrrev_i32_e32 v71, 31, v70
	v_lshl_add_u64 v[70:71], v[70:71], 2, s[26:27]
	global_store_dword v[70:71], v75, off sc1
	global_store_dword v[70:71], v74, off offset:128 sc1

.LBB0_867:
	v_pk_mul_f32 v[78:79], v[72:73], v[72:73]
	v_add_lshl_u32 v62, s8, v171, 10
	v_add_f32_e32 v13, v79, v78
	s_nop 1
	v_mov_b32_dpp v25, v13 quad_perm:[1,0,3,2] row_mask:0xf bank_mask:0xf
	v_cvt_pk_bf16_f32 v31, v74, s0
	v_or_b32_e32 v74, v62, v134
	v_cvt_pk_bf16_f32 v27, v75, s0
	v_ashrrev_i32_e32 v75, 31, v74
	s_waitcnt lgkmcnt(0)
	v_add_f32_e32 v13, v13, v25
	s_nop 1
	v_mov_b32_dpp v25, v13 quad_perm:[2,3,0,1] row_mask:0xf bank_mask:0xf
	v_lshl_add_u64 v[74:75], v[74:75], 1, s[4:5]
	global_store_short v[74:75], v27, off sc1
	global_store_short v[74:75], v31, off offset:64 sc1
	s_and_b64 vcc, exec, s[70:71]
	v_add_u32_e32 v105, s68, v172
	s_waitcnt lgkmcnt(0)
	v_add_f32_e32 v13, v13, v25
	s_nop 1
	v_mov_b32_dpp v25, v13 row_half_mirror row_mask:0xf bank_mask:0xf
	s_waitcnt lgkmcnt(0)
	v_add_f32_e32 v13, v13, v25
	s_nop 1
	v_mov_b32_dpp v25, v13 row_mirror row_mask:0xf bank_mask:0xf
	s_waitcnt lgkmcnt(0)
	v_add_f32_e32 v13, v13, v25
	ds_bpermute_b32 v25, v104, v13
	s_waitcnt lgkmcnt(0)
	v_add_f32_e32 v13, v13, v25
	v_fmamk_f32 v13, v13, 0x3c800000, v196
	v_rsq_f32_e32 v78, v13
	s_nop 0
	v_pk_mul_f32 v[74:75], v[10:11], v[78:79] op_sel_hi:[1,0]
	s_nop 0
	v_pk_mul_f32 v[78:79], v[72:73], v[74:75]
	s_cbranch_vccz .LBB0_869
	v_lshl_or_b32 v72, v105, 10, v134
	v_ashrrev_i32_e32 v73, 31, v72
	v_lshl_add_u64 v[72:73], v[72:73], 2, s[26:27]
	global_store_dword v[72:73], v79, off sc1
	global_store_dword v[72:73], v78, off offset:128 sc1

.LBB0_871:
	v_pk_mul_f32 v[72:73], v[76:77], v[76:77]
	v_cvt_pk_bf16_f32 v31, v78, s0
	v_add_f32_e32 v13, v73, v72
	s_nop 1
	v_mov_b32_dpp v25, v13 quad_perm:[1,0,3,2] row_mask:0xf bank_mask:0xf
	v_add_lshl_u32 v72, s8, v172, 10
	v_or_b32_e32 v78, v72, v134
	v_cvt_pk_bf16_f32 v27, v79, s0
	v_ashrrev_i32_e32 v79, 31, v78
	s_waitcnt lgkmcnt(0)
	v_add_f32_e32 v13, v13, v25
	s_nop 1
	v_mov_b32_dpp v25, v13 quad_perm:[2,3,0,1] row_mask:0xf bank_mask:0xf
	v_lshl_add_u64 v[78:79], v[78:79], 1, s[4:5]
	global_store_short v[78:79], v27, off sc1
	global_store_short v[78:79], v31, off offset:64 sc1
	s_and_b64 vcc, exec, s[70:71]
	v_add_u32_e32 v106, s68, v173
	s_waitcnt lgkmcnt(0)
	v_add_f32_e32 v13, v13, v25
	s_nop 1
	v_mov_b32_dpp v25, v13 row_half_mirror row_mask:0xf bank_mask:0xf
	s_waitcnt lgkmcnt(0)
	v_add_f32_e32 v13, v13, v25
	s_nop 1
	v_mov_b32_dpp v25, v13 row_mirror row_mask:0xf bank_mask:0xf
	s_waitcnt lgkmcnt(0)
	v_add_f32_e32 v13, v13, v25
	ds_bpermute_b32 v25, v104, v13
	s_waitcnt lgkmcnt(0)
	v_add_f32_e32 v13, v13, v25
	v_fmamk_f32 v13, v13, 0x3c800000, v196
	v_rsq_f32_e32 v80, v13
	s_nop 0
	v_pk_mul_f32 v[78:79], v[10:11], v[80:81] op_sel_hi:[1,0]
	s_nop 0
	v_pk_mul_f32 v[80:81], v[76:77], v[78:79]
	s_cbranch_vccz .LBB0_873
	v_lshl_or_b32 v76, v106, 10, v134
	v_ashrrev_i32_e32 v77, 31, v76
	v_lshl_add_u64 v[76:77], v[76:77], 2, s[26:27]
	global_store_dword v[76:77], v81, off sc1
	global_store_dword v[76:77], v80, off offset:128 sc1

.LBB0_875:
	v_pk_mul_f32 v[76:77], v[68:69], v[68:69]
	v_cvt_pk_bf16_f32 v31, v80, s0
	v_add_f32_e32 v13, v77, v76
	s_nop 1
	v_mov_b32_dpp v25, v13 quad_perm:[1,0,3,2] row_mask:0xf bank_mask:0xf
	v_add_lshl_u32 v76, s8, v173, 10
	v_or_b32_e32 v80, v76, v134
	v_cvt_pk_bf16_f32 v27, v81, s0
	v_ashrrev_i32_e32 v81, 31, v80
	s_waitcnt lgkmcnt(0)
	v_add_f32_e32 v13, v13, v25
	s_nop 1
	v_mov_b32_dpp v25, v13 quad_perm:[2,3,0,1] row_mask:0xf bank_mask:0xf
	v_lshl_add_u64 v[80:81], v[80:81], 1, s[4:5]
	global_store_short v[80:81], v27, off sc1
	global_store_short v[80:81], v31, off offset:64 sc1
	s_and_b64 vcc, exec, s[70:71]
	v_add_u32_e32 v107, s68, v174
	s_waitcnt lgkmcnt(0)
	v_add_f32_e32 v13, v13, v25
	s_nop 1
	v_mov_b32_dpp v25, v13 row_half_mirror row_mask:0xf bank_mask:0xf
	s_waitcnt lgkmcnt(0)
	v_add_f32_e32 v13, v13, v25
	s_nop 1
	v_mov_b32_dpp v25, v13 row_mirror row_mask:0xf bank_mask:0xf
	s_waitcnt lgkmcnt(0)
	v_add_f32_e32 v13, v13, v25
	ds_bpermute_b32 v25, v104, v13
	s_waitcnt lgkmcnt(0)
	v_add_f32_e32 v13, v13, v25
	v_fmamk_f32 v13, v13, 0x3c800000, v196
	v_rsq_f32_e32 v82, v13
	s_nop 0
	v_pk_mul_f32 v[80:81], v[10:11], v[82:83] op_sel_hi:[1,0]
	s_nop 0
	v_pk_mul_f32 v[82:83], v[68:69], v[80:81]
	s_cbranch_vccz .LBB0_877
	v_lshl_or_b32 v68, v107, 10, v134
	v_ashrrev_i32_e32 v69, 31, v68
	v_lshl_add_u64 v[68:69], v[68:69], 2, s[26:27]
	global_store_dword v[68:69], v83, off sc1
	global_store_dword v[68:69], v82, off offset:128 sc1

.LBB0_879:
	v_pk_mul_f32 v[68:69], v[66:67], v[66:67]
	v_cvt_pk_bf16_f32 v31, v82, s0
	v_add_f32_e32 v13, v69, v68
	s_nop 1
	v_mov_b32_dpp v25, v13 quad_perm:[1,0,3,2] row_mask:0xf bank_mask:0xf
	v_add_lshl_u32 v68, s8, v174, 10
	v_or_b32_e32 v82, v68, v134
	v_cvt_pk_bf16_f32 v27, v83, s0
	v_ashrrev_i32_e32 v83, 31, v82
	s_waitcnt lgkmcnt(0)
	v_add_f32_e32 v13, v13, v25
	s_nop 1
	v_mov_b32_dpp v25, v13 quad_perm:[2,3,0,1] row_mask:0xf bank_mask:0xf
	v_lshl_add_u64 v[82:83], v[82:83], 1, s[4:5]
	global_store_short v[82:83], v27, off sc1
	global_store_short v[82:83], v31, off offset:64 sc1
	s_and_b64 vcc, exec, s[70:71]
	v_add_u32_e32 v108, s68, v175
	s_waitcnt lgkmcnt(0)
	v_add_f32_e32 v13, v13, v25
	s_nop 1
	v_mov_b32_dpp v25, v13 row_half_mirror row_mask:0xf bank_mask:0xf
	s_waitcnt lgkmcnt(0)
	v_add_f32_e32 v13, v13, v25
	s_nop 1
	v_mov_b32_dpp v25, v13 row_mirror row_mask:0xf bank_mask:0xf
	s_waitcnt lgkmcnt(0)
	v_add_f32_e32 v13, v13, v25
	ds_bpermute_b32 v25, v104, v13
	s_waitcnt lgkmcnt(0)
	v_add_f32_e32 v13, v13, v25
	v_fmamk_f32 v13, v13, 0x3c800000, v196
	v_rsq_f32_e32 v84, v13
	s_nop 0
	v_pk_mul_f32 v[82:83], v[10:11], v[84:85] op_sel_hi:[1,0]
	s_nop 0
	v_pk_mul_f32 v[84:85], v[66:67], v[82:83]
	s_cbranch_vccz .LBB0_881
	v_lshl_or_b32 v66, v108, 10, v134
	v_ashrrev_i32_e32 v67, 31, v66
	v_lshl_add_u64 v[66:67], v[66:67], 2, s[26:27]
	global_store_dword v[66:67], v85, off sc1
	global_store_dword v[66:67], v84, off offset:128 sc1

.LBB0_883:
	v_pk_mul_f32 v[66:67], v[64:65], v[64:65]
	v_cvt_pk_bf16_f32 v31, v84, s0
	v_add_f32_e32 v13, v67, v66
	s_nop 1
	v_mov_b32_dpp v25, v13 quad_perm:[1,0,3,2] row_mask:0xf bank_mask:0xf
	v_add_lshl_u32 v66, s8, v175, 10
	v_or_b32_e32 v84, v66, v134
	v_cvt_pk_bf16_f32 v27, v85, s0
	v_ashrrev_i32_e32 v85, 31, v84
	s_waitcnt lgkmcnt(0)
	v_add_f32_e32 v13, v13, v25
	s_nop 1
	v_mov_b32_dpp v25, v13 quad_perm:[2,3,0,1] row_mask:0xf bank_mask:0xf
	v_lshl_add_u64 v[84:85], v[84:85], 1, s[4:5]
	global_store_short v[84:85], v27, off sc1
	global_store_short v[84:85], v31, off offset:64 sc1
	s_and_b64 vcc, exec, s[70:71]
	v_add_u32_e32 v109, s68, v176
	s_waitcnt lgkmcnt(0)
	v_add_f32_e32 v13, v13, v25
	s_nop 1
	v_mov_b32_dpp v25, v13 row_half_mirror row_mask:0xf bank_mask:0xf
	s_waitcnt lgkmcnt(0)
	v_add_f32_e32 v13, v13, v25
	s_nop 1
	v_mov_b32_dpp v25, v13 row_mirror row_mask:0xf bank_mask:0xf
	s_waitcnt lgkmcnt(0)
	v_add_f32_e32 v13, v13, v25
	ds_bpermute_b32 v25, v104, v13
	s_waitcnt lgkmcnt(0)
	v_add_f32_e32 v13, v13, v25
	v_fmamk_f32 v13, v13, 0x3c800000, v196
	v_rsq_f32_e32 v86, v13
	s_nop 0
	v_pk_mul_f32 v[84:85], v[10:11], v[86:87] op_sel_hi:[1,0]
	s_nop 0
	v_pk_mul_f32 v[86:87], v[64:65], v[84:85]
	s_cbranch_vccz .LBB0_885
	v_lshl_or_b32 v64, v109, 10, v134
	v_ashrrev_i32_e32 v65, 31, v64
	v_lshl_add_u64 v[64:65], v[64:65], 2, s[26:27]
	global_store_dword v[64:65], v87, off sc1
	global_store_dword v[64:65], v86, off offset:128 sc1

.LBB0_887:
	v_pk_mul_f32 v[64:65], v[56:57], v[56:57]
	v_cvt_pk_bf16_f32 v31, v86, s0
	v_add_f32_e32 v13, v65, v64
	s_nop 1
	v_mov_b32_dpp v25, v13 quad_perm:[1,0,3,2] row_mask:0xf bank_mask:0xf
	v_add_lshl_u32 v64, s8, v176, 10
	v_or_b32_e32 v86, v64, v134
	v_cvt_pk_bf16_f32 v27, v87, s0
	v_ashrrev_i32_e32 v87, 31, v86
	s_waitcnt lgkmcnt(0)
	v_add_f32_e32 v13, v13, v25
	s_nop 1
	v_mov_b32_dpp v25, v13 quad_perm:[2,3,0,1] row_mask:0xf bank_mask:0xf
	v_lshl_add_u64 v[86:87], v[86:87], 1, s[4:5]
	global_store_short v[86:87], v27, off sc1
	global_store_short v[86:87], v31, off offset:64 sc1
	s_and_b64 vcc, exec, s[70:71]
	v_add_u32_e32 v110, s68, v177
	s_waitcnt lgkmcnt(0)
	v_add_f32_e32 v13, v13, v25
	s_nop 1
	v_mov_b32_dpp v25, v13 row_half_mirror row_mask:0xf bank_mask:0xf
	s_waitcnt lgkmcnt(0)
	v_add_f32_e32 v13, v13, v25
	s_nop 1
	v_mov_b32_dpp v25, v13 row_mirror row_mask:0xf bank_mask:0xf
	s_waitcnt lgkmcnt(0)
	v_add_f32_e32 v13, v13, v25
	ds_bpermute_b32 v25, v104, v13
	s_waitcnt lgkmcnt(0)
	v_add_f32_e32 v13, v13, v25
	v_fmamk_f32 v13, v13, 0x3c800000, v196
	v_rsq_f32_e32 v88, v13
	s_nop 0
	v_pk_mul_f32 v[86:87], v[10:11], v[88:89] op_sel_hi:[1,0]
	s_nop 0
	v_pk_mul_f32 v[88:89], v[56:57], v[86:87]
	s_cbranch_vccz .LBB0_889
	v_lshl_or_b32 v56, v110, 10, v134
	v_ashrrev_i32_e32 v57, 31, v56
	v_lshl_add_u64 v[56:57], v[56:57], 2, s[26:27]
	global_store_dword v[56:57], v89, off sc1
	global_store_dword v[56:57], v88, off offset:128 sc1

.LBB0_891:
	v_pk_mul_f32 v[56:57], v[54:55], v[54:55]
	v_cvt_pk_bf16_f32 v31, v88, s0
	v_add_f32_e32 v13, v57, v56
	s_nop 1
	v_mov_b32_dpp v25, v13 quad_perm:[1,0,3,2] row_mask:0xf bank_mask:0xf
	v_add_lshl_u32 v56, s8, v177, 10
	v_or_b32_e32 v88, v56, v134
	v_cvt_pk_bf16_f32 v27, v89, s0
	v_ashrrev_i32_e32 v89, 31, v88
	s_waitcnt lgkmcnt(0)
	v_add_f32_e32 v13, v13, v25
	s_nop 1
	v_mov_b32_dpp v25, v13 quad_perm:[2,3,0,1] row_mask:0xf bank_mask:0xf
	v_lshl_add_u64 v[88:89], v[88:89], 1, s[4:5]
	global_store_short v[88:89], v27, off sc1
	global_store_short v[88:89], v31, off offset:64 sc1
	s_and_b64 vcc, exec, s[70:71]
	v_add_u32_e32 v111, s68, v178
	s_waitcnt lgkmcnt(0)
	v_add_f32_e32 v13, v13, v25
	s_nop 1
	v_mov_b32_dpp v25, v13 row_half_mirror row_mask:0xf bank_mask:0xf
	s_waitcnt lgkmcnt(0)
	v_add_f32_e32 v13, v13, v25
	s_nop 1
	v_mov_b32_dpp v25, v13 row_mirror row_mask:0xf bank_mask:0xf
	s_waitcnt lgkmcnt(0)
	v_add_f32_e32 v13, v13, v25
	ds_bpermute_b32 v25, v104, v13
	s_waitcnt lgkmcnt(0)
	v_add_f32_e32 v13, v13, v25
	v_fmamk_f32 v13, v13, 0x3c800000, v196
	v_rsq_f32_e32 v90, v13
	s_nop 0
	v_pk_mul_f32 v[88:89], v[10:11], v[90:91] op_sel_hi:[1,0]
	s_nop 0
	v_pk_mul_f32 v[90:91], v[54:55], v[88:89]
	s_cbranch_vccz .LBB0_893
	v_lshl_or_b32 v54, v111, 10, v134
	v_ashrrev_i32_e32 v55, 31, v54
	v_lshl_add_u64 v[54:55], v[54:55], 2, s[26:27]
	global_store_dword v[54:55], v91, off sc1
	global_store_dword v[54:55], v90, off offset:128 sc1

.LBB0_895:
	v_pk_mul_f32 v[54:55], v[52:53], v[52:53]
	v_cvt_pk_bf16_f32 v31, v90, s0
	v_add_f32_e32 v13, v55, v54
	s_nop 1
	v_mov_b32_dpp v25, v13 quad_perm:[1,0,3,2] row_mask:0xf bank_mask:0xf
	v_add_lshl_u32 v54, s8, v178, 10
	v_or_b32_e32 v90, v54, v134
	v_cvt_pk_bf16_f32 v27, v91, s0
	v_ashrrev_i32_e32 v91, 31, v90
	s_waitcnt lgkmcnt(0)
	v_add_f32_e32 v13, v13, v25
	s_nop 1
	v_mov_b32_dpp v25, v13 quad_perm:[2,3,0,1] row_mask:0xf bank_mask:0xf
	v_lshl_add_u64 v[90:91], v[90:91], 1, s[4:5]
	global_store_short v[90:91], v27, off sc1
	global_store_short v[90:91], v31, off offset:64 sc1
	s_and_b64 vcc, exec, s[70:71]
	v_add_u32_e32 v112, s68, v179
	s_waitcnt lgkmcnt(0)
	v_add_f32_e32 v13, v13, v25
	s_nop 1
	v_mov_b32_dpp v25, v13 row_half_mirror row_mask:0xf bank_mask:0xf
	s_waitcnt lgkmcnt(0)
	v_add_f32_e32 v13, v13, v25
	s_nop 1
	v_mov_b32_dpp v25, v13 row_mirror row_mask:0xf bank_mask:0xf
	s_waitcnt lgkmcnt(0)
	v_add_f32_e32 v13, v13, v25
	ds_bpermute_b32 v25, v104, v13
	s_waitcnt lgkmcnt(0)
	v_add_f32_e32 v13, v13, v25
	v_fmamk_f32 v13, v13, 0x3c800000, v196
	v_rsq_f32_e32 v92, v13
	s_nop 0
	v_pk_mul_f32 v[90:91], v[10:11], v[92:93] op_sel_hi:[1,0]
	s_nop 0
	v_pk_mul_f32 v[92:93], v[52:53], v[90:91]
	s_cbranch_vccz .LBB0_897
	v_lshl_or_b32 v52, v112, 10, v134
	v_ashrrev_i32_e32 v53, 31, v52
	v_lshl_add_u64 v[52:53], v[52:53], 2, s[26:27]
	global_store_dword v[52:53], v93, off sc1
	global_store_dword v[52:53], v92, off offset:128 sc1

.LBB0_899:
	v_pk_mul_f32 v[52:53], v[50:51], v[50:51]
	v_cvt_pk_bf16_f32 v31, v92, s0
	v_add_f32_e32 v13, v53, v52
	s_nop 1
	v_mov_b32_dpp v25, v13 quad_perm:[1,0,3,2] row_mask:0xf bank_mask:0xf
	v_add_lshl_u32 v52, s8, v179, 10
	v_or_b32_e32 v92, v52, v134
	v_cvt_pk_bf16_f32 v27, v93, s0
	v_ashrrev_i32_e32 v93, 31, v92
	s_waitcnt lgkmcnt(0)
	v_add_f32_e32 v13, v13, v25
	s_nop 1
	v_mov_b32_dpp v25, v13 quad_perm:[2,3,0,1] row_mask:0xf bank_mask:0xf
	v_lshl_add_u64 v[92:93], v[92:93], 1, s[4:5]
	global_store_short v[92:93], v27, off sc1
	global_store_short v[92:93], v31, off offset:64 sc1
	s_and_b64 vcc, exec, s[70:71]
	v_add_u32_e32 v113, s68, v180
	s_waitcnt lgkmcnt(0)
	v_add_f32_e32 v13, v13, v25
	s_nop 1
	v_mov_b32_dpp v25, v13 row_half_mirror row_mask:0xf bank_mask:0xf
	s_waitcnt lgkmcnt(0)
	v_add_f32_e32 v13, v13, v25
	s_nop 1
	v_mov_b32_dpp v25, v13 row_mirror row_mask:0xf bank_mask:0xf
	s_waitcnt lgkmcnt(0)
	v_add_f32_e32 v13, v13, v25
	ds_bpermute_b32 v25, v104, v13
	s_waitcnt lgkmcnt(0)
	v_add_f32_e32 v13, v13, v25
	v_fmamk_f32 v13, v13, 0x3c800000, v196
	v_rsq_f32_e32 v94, v13
	s_nop 0
	v_pk_mul_f32 v[92:93], v[10:11], v[94:95] op_sel_hi:[1,0]
	s_nop 0
	v_pk_mul_f32 v[94:95], v[50:51], v[92:93]
	s_cbranch_vccz .LBB0_901
	v_lshl_or_b32 v50, v113, 10, v134
	v_ashrrev_i32_e32 v51, 31, v50
	v_lshl_add_u64 v[50:51], v[50:51], 2, s[26:27]
	global_store_dword v[50:51], v95, off sc1
	global_store_dword v[50:51], v94, off offset:128 sc1

.LBB0_903:
	v_pk_mul_f32 v[50:51], v[48:49], v[48:49]
	v_cvt_pk_bf16_f32 v31, v94, s0
	v_add_f32_e32 v13, v51, v50
	s_nop 1
	v_mov_b32_dpp v25, v13 quad_perm:[1,0,3,2] row_mask:0xf bank_mask:0xf
	v_add_lshl_u32 v50, s8, v180, 10
	v_or_b32_e32 v94, v50, v134
	v_cvt_pk_bf16_f32 v27, v95, s0
	v_ashrrev_i32_e32 v95, 31, v94
	s_waitcnt lgkmcnt(0)
	v_add_f32_e32 v13, v13, v25
	s_nop 1
	v_mov_b32_dpp v25, v13 quad_perm:[2,3,0,1] row_mask:0xf bank_mask:0xf
	v_lshl_add_u64 v[94:95], v[94:95], 1, s[4:5]
	global_store_short v[94:95], v27, off sc1
	global_store_short v[94:95], v31, off offset:64 sc1
	s_and_b64 vcc, exec, s[70:71]
	v_add_u32_e32 v114, s68, v181
	s_waitcnt lgkmcnt(0)
	v_add_f32_e32 v13, v13, v25
	s_nop 1
	v_mov_b32_dpp v25, v13 row_half_mirror row_mask:0xf bank_mask:0xf
	s_waitcnt lgkmcnt(0)
	v_add_f32_e32 v13, v13, v25
	s_nop 1
	v_mov_b32_dpp v25, v13 row_mirror row_mask:0xf bank_mask:0xf
	s_waitcnt lgkmcnt(0)
	v_add_f32_e32 v13, v13, v25
	ds_bpermute_b32 v25, v104, v13
	s_waitcnt lgkmcnt(0)
	v_add_f32_e32 v13, v13, v25
	v_fmamk_f32 v13, v13, 0x3c800000, v196
	v_rsq_f32_e32 v96, v13
	s_nop 0
	v_pk_mul_f32 v[94:95], v[10:11], v[96:97] op_sel_hi:[1,0]
	s_nop 0
	v_pk_mul_f32 v[96:97], v[48:49], v[94:95]
	s_cbranch_vccz .LBB0_905
	v_lshl_or_b32 v48, v114, 10, v134
	v_ashrrev_i32_e32 v49, 31, v48
	v_lshl_add_u64 v[48:49], v[48:49], 2, s[26:27]
	global_store_dword v[48:49], v97, off sc1
	global_store_dword v[48:49], v96, off offset:128 sc1

.LBB0_907:
	v_pk_mul_f32 v[48:49], v[46:47], v[46:47]
	v_cvt_pk_bf16_f32 v31, v96, s0
	v_add_f32_e32 v13, v49, v48
	s_nop 1
	v_mov_b32_dpp v25, v13 quad_perm:[1,0,3,2] row_mask:0xf bank_mask:0xf
	v_add_lshl_u32 v48, s8, v181, 10
	v_or_b32_e32 v98, v48, v134
	v_ashrrev_i32_e32 v99, 31, v98
	v_cvt_pk_bf16_f32 v27, v97, s0
	s_waitcnt lgkmcnt(0)
	v_add_f32_e32 v13, v13, v25
	s_nop 1
	v_mov_b32_dpp v25, v13 quad_perm:[2,3,0,1] row_mask:0xf bank_mask:0xf
	v_add_u32_e32 v97, s68, v182
	v_lshl_add_u64 v[98:99], v[98:99], 1, s[4:5]
	global_store_short v[98:99], v27, off sc1
	global_store_short v[98:99], v31, off offset:64 sc1
	s_and_b64 vcc, exec, s[70:71]
	s_waitcnt lgkmcnt(0)
	v_add_f32_e32 v13, v13, v25
	s_nop 1
	v_mov_b32_dpp v25, v13 row_half_mirror row_mask:0xf bank_mask:0xf
	s_waitcnt lgkmcnt(0)
	v_add_f32_e32 v13, v13, v25
	s_nop 1
	v_mov_b32_dpp v25, v13 row_mirror row_mask:0xf bank_mask:0xf
	s_waitcnt lgkmcnt(0)
	v_add_f32_e32 v13, v13, v25
	ds_bpermute_b32 v25, v104, v13
	s_waitcnt lgkmcnt(0)
	v_add_f32_e32 v13, v13, v25
	v_fmamk_f32 v13, v13, 0x3c800000, v196
	v_rsq_f32_e32 v96, v13
	s_nop 0
	v_pk_mul_f32 v[98:99], v[10:11], v[96:97] op_sel_hi:[1,0]
	s_nop 0
	v_pk_mul_f32 v[98:99], v[46:47], v[98:99]
	s_cbranch_vccz .LBB0_909
	v_lshl_or_b32 v46, v97, 10, v134
	v_ashrrev_i32_e32 v47, 31, v46
	v_lshl_add_u64 v[46:47], v[46:47], 2, s[26:27]
	global_store_dword v[46:47], v99, off sc1
	global_store_dword v[46:47], v98, off offset:128 sc1

.LBB0_911:
	v_pk_mul_f32 v[116:117], v[44:45], v[44:45]
	v_add_lshl_u32 v96, s8, v182, 10
	v_add_f32_e32 v13, v117, v116
	s_nop 1
	v_mov_b32_dpp v25, v13 quad_perm:[1,0,3,2] row_mask:0xf bank_mask:0xf
	v_cvt_pk_bf16_f32 v31, v98, s0
	v_or_b32_e32 v98, v96, v134
	v_cvt_pk_bf16_f32 v27, v99, s0
	v_ashrrev_i32_e32 v99, 31, v98
	s_waitcnt lgkmcnt(0)
	v_add_f32_e32 v13, v13, v25
	s_nop 1
	v_mov_b32_dpp v25, v13 quad_perm:[2,3,0,1] row_mask:0xf bank_mask:0xf
	v_lshl_add_u64 v[98:99], v[98:99], 1, s[4:5]
	global_store_short v[98:99], v27, off sc1
	global_store_short v[98:99], v31, off offset:64 sc1
	v_or_b32_e32 v47, 64, v134
	s_and_b64 vcc, exec, s[70:71]
	s_waitcnt lgkmcnt(0)
	v_add_f32_e32 v13, v13, v25
	s_nop 1
	v_mov_b32_dpp v25, v13 row_half_mirror row_mask:0xf bank_mask:0xf
	s_waitcnt lgkmcnt(0)
	v_add_f32_e32 v13, v13, v25
	s_nop 1
	v_mov_b32_dpp v25, v13 row_mirror row_mask:0xf bank_mask:0xf
	s_waitcnt lgkmcnt(0)
	v_add_f32_e32 v13, v13, v25
	ds_bpermute_b32 v25, v104, v13
	s_waitcnt lgkmcnt(0)
	v_add_f32_e32 v13, v13, v25
	v_fmamk_f32 v13, v13, 0x3c800000, v196
	v_rsq_f32_e32 v116, v13
	s_nop 0
	v_pk_mul_f32 v[98:99], v[10:11], v[116:117] op_sel_hi:[1,0]
	s_nop 0
	v_pk_mul_f32 v[44:45], v[44:45], v[98:99]
	s_cbranch_vccz .LBB0_913
	v_lshl_or_b32 v98, v148, 10, v47
	v_ashrrev_i32_e32 v99, 31, v98
	v_lshl_add_u64 v[98:99], v[98:99], 2, s[26:27]
	global_store_dword v[98:99], v45, off sc1
	global_store_dword v[98:99], v44, off offset:128 sc1

.LBB0_915:
	v_pk_mul_f32 v[12:13], v[42:43], v[42:43]
	v_cvt_pk_bf16_f32 v27, v45, s0
	v_add_f32_e32 v12, v13, v12
	s_nop 1
	v_mov_b32_dpp v13, v12 quad_perm:[1,0,3,2] row_mask:0xf bank_mask:0xf
	v_ashrrev_i32_e32 v25, 31, v24
	v_cvt_pk_bf16_f32 v44, v44, s0
	s_and_b64 vcc, exec, s[70:71]
	s_waitcnt lgkmcnt(0)
	v_add_f32_e32 v12, v12, v13
	s_nop 1
	v_mov_b32_dpp v13, v12 quad_perm:[2,3,0,1] row_mask:0xf bank_mask:0xf
	s_waitcnt lgkmcnt(0)
	v_add_f32_e32 v12, v12, v13
	s_nop 1
	v_mov_b32_dpp v13, v12 row_half_mirror row_mask:0xf bank_mask:0xf
	s_waitcnt lgkmcnt(0)
	v_add_f32_e32 v12, v12, v13
	s_nop 1
	v_mov_b32_dpp v13, v12 row_mirror row_mask:0xf bank_mask:0xf
	s_waitcnt lgkmcnt(0)
	v_add_f32_e32 v31, v12, v13
	ds_bpermute_b32 v45, v104, v31
	v_lshl_add_u64 v[12:13], v[24:25], 0, v[134:135]
	v_lshl_add_u64 v[12:13], v[12:13], 1, s[4:5]
	global_store_short v[12:13], v27, off offset:128 sc1
	global_store_short v[12:13], v44, off offset:192 sc1
	s_waitcnt lgkmcnt(0)
	v_add_f32_e32 v24, v31, v45
	v_fmamk_f32 v24, v24, 0x3c800000, v196
	v_rsq_f32_e32 v24, v24
	s_nop 0
	v_pk_mul_f32 v[12:13], v[10:11], v[24:25] op_sel_hi:[1,0]
	s_nop 0
	v_pk_mul_f32 v[12:13], v[42:43], v[12:13]
	s_cbranch_vccz .LBB0_917
	v_lshl_or_b32 v24, v15, 10, v47
	v_ashrrev_i32_e32 v25, 31, v24
	v_lshl_add_u64 v[24:25], v[24:25], 2, s[26:27]
	global_store_dword v[24:25], v13, off sc1
	global_store_dword v[24:25], v12, off offset:128 sc1

.LBB0_919:
	v_pk_mul_f32 v[24:25], v[40:41], v[40:41]
	v_cvt_pk_bf16_f32 v27, v12, s0
	v_add_f32_e32 v15, v25, v24
	s_nop 1
	v_mov_b32_dpp v24, v15 quad_perm:[1,0,3,2] row_mask:0xf bank_mask:0xf
	v_cvt_pk_bf16_f32 v25, v13, s0
	s_and_b64 vcc, exec, s[70:71]
	s_waitcnt lgkmcnt(0)
	v_add_f32_e32 v15, v15, v24
	s_nop 1
	v_mov_b32_dpp v24, v15 quad_perm:[2,3,0,1] row_mask:0xf bank_mask:0xf
	s_waitcnt lgkmcnt(0)
	v_add_f32_e32 v15, v15, v24
	s_nop 1
	v_mov_b32_dpp v24, v15 row_half_mirror row_mask:0xf bank_mask:0xf
	s_waitcnt lgkmcnt(0)
	v_add_f32_e32 v15, v15, v24
	s_nop 1
	v_mov_b32_dpp v24, v15 row_mirror row_mask:0xf bank_mask:0xf
	s_waitcnt lgkmcnt(0)
	v_add_f32_e32 v24, v15, v24
	ds_bpermute_b32 v26, v104, v24
	v_ashrrev_i32_e32 v15, 31, v14
	v_lshl_add_u64 v[12:13], v[14:15], 0, v[134:135]
	v_lshl_add_u64 v[12:13], v[12:13], 1, s[4:5]
	global_store_short v[12:13], v25, off offset:128 sc1
	global_store_short v[12:13], v27, off offset:192 sc1
	s_waitcnt lgkmcnt(0)
	v_add_f32_e32 v14, v24, v26
	v_fmamk_f32 v14, v14, 0x3c800000, v196
	v_rsq_f32_e32 v14, v14
	s_nop 0
	v_pk_mul_f32 v[12:13], v[10:11], v[14:15] op_sel_hi:[1,0]
	s_nop 0
	v_pk_mul_f32 v[12:13], v[40:41], v[12:13]
	s_cbranch_vccz .LBB0_921
	v_lshl_or_b32 v14, v29, 10, v47
	v_ashrrev_i32_e32 v15, 31, v14
	v_lshl_add_u64 v[14:15], v[14:15], 2, s[26:27]
	global_store_dword v[14:15], v13, off sc1
	global_store_dword v[14:15], v12, off offset:128 sc1

.LBB0_923:
	v_pk_mul_f32 v[14:15], v[38:39], v[38:39]
	v_ashrrev_i32_e32 v29, 31, v28
	v_add_f32_e32 v14, v15, v14
	s_nop 1
	v_mov_b32_dpp v15, v14 quad_perm:[1,0,3,2] row_mask:0xf bank_mask:0xf
	v_cvt_pk_bf16_f32 v24, v13, s0
	v_cvt_pk_bf16_f32 v25, v12, s0
	v_lshl_add_u64 v[12:13], v[28:29], 0, v[134:135]
	v_lshl_add_u64 v[12:13], v[12:13], 1, s[4:5]
	s_waitcnt lgkmcnt(0)
	v_add_f32_e32 v14, v14, v15
	s_nop 1
	v_mov_b32_dpp v15, v14 quad_perm:[2,3,0,1] row_mask:0xf bank_mask:0xf
	global_store_short v[12:13], v24, off offset:128 sc1
	global_store_short v[12:13], v25, off offset:192 sc1
	s_and_b64 vcc, exec, s[70:71]
	s_waitcnt lgkmcnt(0)
	v_add_f32_e32 v14, v14, v15
	s_nop 1
	v_mov_b32_dpp v15, v14 row_half_mirror row_mask:0xf bank_mask:0xf
	s_waitcnt lgkmcnt(0)
	v_add_f32_e32 v14, v14, v15
	s_nop 1
	v_mov_b32_dpp v15, v14 row_mirror row_mask:0xf bank_mask:0xf
	s_waitcnt lgkmcnt(0)
	v_add_f32_e32 v14, v14, v15
	ds_bpermute_b32 v15, v104, v14
	s_waitcnt lgkmcnt(0)
	v_add_f32_e32 v14, v14, v15
	v_fmamk_f32 v14, v14, 0x3c800000, v196
	v_rsq_f32_e32 v14, v14
	s_nop 0
	v_pk_mul_f32 v[12:13], v[10:11], v[14:15] op_sel_hi:[1,0]
	s_nop 0
	v_pk_mul_f32 v[12:13], v[38:39], v[12:13]
	s_cbranch_vccz .LBB0_925
	v_lshl_or_b32 v14, v59, 10, v47
	v_ashrrev_i32_e32 v15, 31, v14
	v_lshl_add_u64 v[14:15], v[14:15], 2, s[26:27]
	global_store_dword v[14:15], v13, off sc1
	global_store_dword v[14:15], v12, off offset:128 sc1

.LBB0_927:
	v_pk_mul_f32 v[14:15], v[36:37], v[36:37]
	v_ashrrev_i32_e32 v59, 31, v58
	v_add_f32_e32 v14, v15, v14
	s_nop 1
	v_mov_b32_dpp v15, v14 quad_perm:[1,0,3,2] row_mask:0xf bank_mask:0xf
	v_cvt_pk_bf16_f32 v24, v13, s0
	v_cvt_pk_bf16_f32 v25, v12, s0
	v_lshl_add_u64 v[12:13], v[58:59], 0, v[134:135]
	v_lshl_add_u64 v[12:13], v[12:13], 1, s[4:5]
	s_waitcnt lgkmcnt(0)
	v_add_f32_e32 v14, v14, v15
	s_nop 1
	v_mov_b32_dpp v15, v14 quad_perm:[2,3,0,1] row_mask:0xf bank_mask:0xf
	global_store_short v[12:13], v24, off offset:128 sc1
	global_store_short v[12:13], v25, off offset:192 sc1
	s_and_b64 vcc, exec, s[70:71]
	s_waitcnt lgkmcnt(0)
	v_add_f32_e32 v14, v14, v15
	s_nop 1
	v_mov_b32_dpp v15, v14 row_half_mirror row_mask:0xf bank_mask:0xf
	s_waitcnt lgkmcnt(0)
	v_add_f32_e32 v14, v14, v15
	s_nop 1
	v_mov_b32_dpp v15, v14 row_mirror row_mask:0xf bank_mask:0xf
	s_waitcnt lgkmcnt(0)
	v_add_f32_e32 v14, v14, v15
	ds_bpermute_b32 v15, v104, v14
	s_waitcnt lgkmcnt(0)
	v_add_f32_e32 v14, v14, v15
	v_fmamk_f32 v14, v14, 0x3c800000, v196
	v_rsq_f32_e32 v14, v14
	s_nop 0
	v_pk_mul_f32 v[12:13], v[10:11], v[14:15] op_sel_hi:[1,0]
	s_nop 0
	v_pk_mul_f32 v[12:13], v[36:37], v[12:13]
	s_cbranch_vccz .LBB0_929
	v_lshl_or_b32 v14, v63, 10, v47
	v_ashrrev_i32_e32 v15, 31, v14
	v_lshl_add_u64 v[14:15], v[14:15], 2, s[26:27]
	global_store_dword v[14:15], v13, off sc1
	global_store_dword v[14:15], v12, off offset:128 sc1

.LBB0_931:
	v_pk_mul_f32 v[14:15], v[34:35], v[34:35]
	v_ashrrev_i32_e32 v63, 31, v62
	v_add_f32_e32 v14, v15, v14
	s_nop 1
	v_mov_b32_dpp v15, v14 quad_perm:[1,0,3,2] row_mask:0xf bank_mask:0xf
	v_cvt_pk_bf16_f32 v24, v13, s0
	v_cvt_pk_bf16_f32 v25, v12, s0
	v_lshl_add_u64 v[12:13], v[62:63], 0, v[134:135]
	v_lshl_add_u64 v[12:13], v[12:13], 1, s[4:5]
	s_waitcnt lgkmcnt(0)
	v_add_f32_e32 v14, v14, v15
	s_nop 1
	v_mov_b32_dpp v15, v14 quad_perm:[2,3,0,1] row_mask:0xf bank_mask:0xf
	global_store_short v[12:13], v24, off offset:128 sc1
	global_store_short v[12:13], v25, off offset:192 sc1
	s_and_b64 vcc, exec, s[70:71]
	s_waitcnt lgkmcnt(0)
	v_add_f32_e32 v14, v14, v15
	s_nop 1
	v_mov_b32_dpp v15, v14 row_half_mirror row_mask:0xf bank_mask:0xf
	s_waitcnt lgkmcnt(0)
	v_add_f32_e32 v14, v14, v15
	s_nop 1
	v_mov_b32_dpp v15, v14 row_mirror row_mask:0xf bank_mask:0xf
	s_waitcnt lgkmcnt(0)
	v_add_f32_e32 v14, v14, v15
	ds_bpermute_b32 v15, v104, v14
	s_waitcnt lgkmcnt(0)
	v_add_f32_e32 v14, v14, v15
	v_fmamk_f32 v14, v14, 0x3c800000, v196
	v_rsq_f32_e32 v14, v14
	s_nop 0
	v_pk_mul_f32 v[12:13], v[10:11], v[14:15] op_sel_hi:[1,0]
	s_nop 0
	v_pk_mul_f32 v[12:13], v[34:35], v[12:13]
	s_cbranch_vccz .LBB0_933
	v_lshl_or_b32 v14, v105, 10, v47
	v_ashrrev_i32_e32 v15, 31, v14
	v_lshl_add_u64 v[14:15], v[14:15], 2, s[26:27]
	global_store_dword v[14:15], v13, off sc1
	global_store_dword v[14:15], v12, off offset:128 sc1

.LBB0_935:
	v_pk_mul_f32 v[14:15], v[32:33], v[32:33]
	v_ashrrev_i32_e32 v73, 31, v72
	v_add_f32_e32 v14, v15, v14
	s_nop 1
	v_mov_b32_dpp v15, v14 quad_perm:[1,0,3,2] row_mask:0xf bank_mask:0xf
	v_cvt_pk_bf16_f32 v24, v13, s0
	v_cvt_pk_bf16_f32 v25, v12, s0
	v_lshl_add_u64 v[12:13], v[72:73], 0, v[134:135]
	v_lshl_add_u64 v[12:13], v[12:13], 1, s[4:5]
	s_waitcnt lgkmcnt(0)
	v_add_f32_e32 v14, v14, v15
	s_nop 1
	v_mov_b32_dpp v15, v14 quad_perm:[2,3,0,1] row_mask:0xf bank_mask:0xf
	global_store_short v[12:13], v24, off offset:128 sc1
	global_store_short v[12:13], v25, off offset:192 sc1
	s_and_b64 vcc, exec, s[70:71]
	s_waitcnt lgkmcnt(0)
	v_add_f32_e32 v14, v14, v15
	s_nop 1
	v_mov_b32_dpp v15, v14 row_half_mirror row_mask:0xf bank_mask:0xf
	s_waitcnt lgkmcnt(0)
	v_add_f32_e32 v14, v14, v15
	s_nop 1
	v_mov_b32_dpp v15, v14 row_mirror row_mask:0xf bank_mask:0xf
	s_waitcnt lgkmcnt(0)
	v_add_f32_e32 v14, v14, v15
	ds_bpermute_b32 v15, v104, v14
	s_waitcnt lgkmcnt(0)
	v_add_f32_e32 v14, v14, v15
	v_fmamk_f32 v14, v14, 0x3c800000, v196
	v_rsq_f32_e32 v14, v14
	s_nop 0
	v_pk_mul_f32 v[12:13], v[10:11], v[14:15] op_sel_hi:[1,0]
	s_nop 0
	v_pk_mul_f32 v[12:13], v[32:33], v[12:13]
	s_cbranch_vccz .LBB0_937
	v_lshl_or_b32 v14, v106, 10, v47
	v_ashrrev_i32_e32 v15, 31, v14
	v_lshl_add_u64 v[14:15], v[14:15], 2, s[26:27]
	global_store_dword v[14:15], v13, off sc1
	global_store_dword v[14:15], v12, off offset:128 sc1

.LBB0_939:
	v_pk_mul_f32 v[14:15], v[22:23], v[22:23]
	v_ashrrev_i32_e32 v77, 31, v76
	v_add_f32_e32 v14, v15, v14
	s_nop 1
	v_mov_b32_dpp v15, v14 quad_perm:[1,0,3,2] row_mask:0xf bank_mask:0xf
	v_cvt_pk_bf16_f32 v24, v13, s0
	v_cvt_pk_bf16_f32 v25, v12, s0
	v_lshl_add_u64 v[12:13], v[76:77], 0, v[134:135]
	v_lshl_add_u64 v[12:13], v[12:13], 1, s[4:5]
	s_waitcnt lgkmcnt(0)
	v_add_f32_e32 v14, v14, v15
	s_nop 1
	v_mov_b32_dpp v15, v14 quad_perm:[2,3,0,1] row_mask:0xf bank_mask:0xf
	global_store_short v[12:13], v24, off offset:128 sc1
	global_store_short v[12:13], v25, off offset:192 sc1
	s_and_b64 vcc, exec, s[70:71]
	s_waitcnt lgkmcnt(0)
	v_add_f32_e32 v14, v14, v15
	s_nop 1
	v_mov_b32_dpp v15, v14 row_half_mirror row_mask:0xf bank_mask:0xf
	s_waitcnt lgkmcnt(0)
	v_add_f32_e32 v14, v14, v15
	s_nop 1
	v_mov_b32_dpp v15, v14 row_mirror row_mask:0xf bank_mask:0xf
	s_waitcnt lgkmcnt(0)
	v_add_f32_e32 v14, v14, v15
	ds_bpermute_b32 v15, v104, v14
	s_waitcnt lgkmcnt(0)
	v_add_f32_e32 v14, v14, v15
	v_fmamk_f32 v14, v14, 0x3c800000, v196
	v_rsq_f32_e32 v14, v14
	s_nop 0
	v_pk_mul_f32 v[12:13], v[10:11], v[14:15] op_sel_hi:[1,0]
	s_nop 0
	v_pk_mul_f32 v[12:13], v[22:23], v[12:13]
	s_cbranch_vccz .LBB0_941
	v_lshl_or_b32 v14, v107, 10, v47
	v_ashrrev_i32_e32 v15, 31, v14
	v_lshl_add_u64 v[14:15], v[14:15], 2, s[26:27]
	global_store_dword v[14:15], v13, off sc1
	global_store_dword v[14:15], v12, off offset:128 sc1

.LBB0_943:
	v_pk_mul_f32 v[14:15], v[20:21], v[20:21]
	v_ashrrev_i32_e32 v69, 31, v68
	v_add_f32_e32 v14, v15, v14
	s_nop 1
	v_mov_b32_dpp v15, v14 quad_perm:[1,0,3,2] row_mask:0xf bank_mask:0xf
	v_cvt_pk_bf16_f32 v22, v13, s0
	v_cvt_pk_bf16_f32 v23, v12, s0
	v_lshl_add_u64 v[12:13], v[68:69], 0, v[134:135]
	v_lshl_add_u64 v[12:13], v[12:13], 1, s[4:5]
	s_waitcnt lgkmcnt(0)
	v_add_f32_e32 v14, v14, v15
	s_nop 1
	v_mov_b32_dpp v15, v14 quad_perm:[2,3,0,1] row_mask:0xf bank_mask:0xf
	global_store_short v[12:13], v22, off offset:128 sc1
	global_store_short v[12:13], v23, off offset:192 sc1
	s_and_b64 vcc, exec, s[70:71]
	s_waitcnt lgkmcnt(0)
	v_add_f32_e32 v14, v14, v15
	s_nop 1
	v_mov_b32_dpp v15, v14 row_half_mirror row_mask:0xf bank_mask:0xf
	s_waitcnt lgkmcnt(0)
	v_add_f32_e32 v14, v14, v15
	s_nop 1
	v_mov_b32_dpp v15, v14 row_mirror row_mask:0xf bank_mask:0xf
	s_waitcnt lgkmcnt(0)
	v_add_f32_e32 v14, v14, v15
	ds_bpermute_b32 v15, v104, v14
	s_waitcnt lgkmcnt(0)
	v_add_f32_e32 v14, v14, v15
	v_fmamk_f32 v14, v14, 0x3c800000, v196
	v_rsq_f32_e32 v14, v14
	s_nop 0
	v_pk_mul_f32 v[12:13], v[10:11], v[14:15] op_sel_hi:[1,0]
	s_nop 0
	v_pk_mul_f32 v[12:13], v[20:21], v[12:13]
	s_cbranch_vccz .LBB0_945
	v_lshl_or_b32 v14, v108, 10, v47
	v_ashrrev_i32_e32 v15, 31, v14
	v_lshl_add_u64 v[14:15], v[14:15], 2, s[26:27]
	global_store_dword v[14:15], v13, off sc1
	global_store_dword v[14:15], v12, off offset:128 sc1

.LBB0_947:
	v_pk_mul_f32 v[14:15], v[18:19], v[18:19]
	v_ashrrev_i32_e32 v67, 31, v66
	v_add_f32_e32 v14, v15, v14
	s_nop 1
	v_mov_b32_dpp v15, v14 quad_perm:[1,0,3,2] row_mask:0xf bank_mask:0xf
	v_cvt_pk_bf16_f32 v20, v13, s0
	v_cvt_pk_bf16_f32 v21, v12, s0
	v_lshl_add_u64 v[12:13], v[66:67], 0, v[134:135]
	v_lshl_add_u64 v[12:13], v[12:13], 1, s[4:5]
	s_waitcnt lgkmcnt(0)
	v_add_f32_e32 v14, v14, v15
	s_nop 1
	v_mov_b32_dpp v15, v14 quad_perm:[2,3,0,1] row_mask:0xf bank_mask:0xf
	global_store_short v[12:13], v20, off offset:128 sc1
	global_store_short v[12:13], v21, off offset:192 sc1
	s_and_b64 vcc, exec, s[70:71]
	s_waitcnt lgkmcnt(0)
	v_add_f32_e32 v14, v14, v15
	s_nop 1
	v_mov_b32_dpp v15, v14 row_half_mirror row_mask:0xf bank_mask:0xf
	s_waitcnt lgkmcnt(0)
	v_add_f32_e32 v14, v14, v15
	s_nop 1
	v_mov_b32_dpp v15, v14 row_mirror row_mask:0xf bank_mask:0xf
	s_waitcnt lgkmcnt(0)
	v_add_f32_e32 v14, v14, v15
	ds_bpermute_b32 v15, v104, v14
	s_waitcnt lgkmcnt(0)
	v_add_f32_e32 v14, v14, v15
	v_fmamk_f32 v14, v14, 0x3c800000, v196
	v_rsq_f32_e32 v14, v14
	s_nop 0
	v_pk_mul_f32 v[12:13], v[10:11], v[14:15] op_sel_hi:[1,0]
	s_nop 0
	v_pk_mul_f32 v[12:13], v[18:19], v[12:13]
	s_cbranch_vccz .LBB0_949
	v_lshl_or_b32 v14, v109, 10, v47
	v_ashrrev_i32_e32 v15, 31, v14
	v_lshl_add_u64 v[14:15], v[14:15], 2, s[26:27]
	global_store_dword v[14:15], v13, off sc1
	global_store_dword v[14:15], v12, off offset:128 sc1

.LBB0_951:
	v_pk_mul_f32 v[14:15], v[16:17], v[16:17]
	v_ashrrev_i32_e32 v65, 31, v64
	v_add_f32_e32 v14, v15, v14
	s_nop 1
	v_mov_b32_dpp v15, v14 quad_perm:[1,0,3,2] row_mask:0xf bank_mask:0xf
	v_cvt_pk_bf16_f32 v18, v13, s0
	v_cvt_pk_bf16_f32 v19, v12, s0
	v_lshl_add_u64 v[12:13], v[64:65], 0, v[134:135]
	v_lshl_add_u64 v[12:13], v[12:13], 1, s[4:5]
	s_waitcnt lgkmcnt(0)
	v_add_f32_e32 v14, v14, v15
	s_nop 1
	v_mov_b32_dpp v15, v14 quad_perm:[2,3,0,1] row_mask:0xf bank_mask:0xf
	global_store_short v[12:13], v18, off offset:128 sc1
	global_store_short v[12:13], v19, off offset:192 sc1
	s_and_b64 vcc, exec, s[70:71]
	s_waitcnt lgkmcnt(0)
	v_add_f32_e32 v14, v14, v15
	s_nop 1
	v_mov_b32_dpp v15, v14 row_half_mirror row_mask:0xf bank_mask:0xf
	s_waitcnt lgkmcnt(0)
	v_add_f32_e32 v14, v14, v15
	s_nop 1
	v_mov_b32_dpp v15, v14 row_mirror row_mask:0xf bank_mask:0xf
	s_waitcnt lgkmcnt(0)
	v_add_f32_e32 v14, v14, v15
	ds_bpermute_b32 v15, v104, v14
	s_waitcnt lgkmcnt(0)
	v_add_f32_e32 v14, v14, v15
	v_fmamk_f32 v14, v14, 0x3c800000, v196
	v_rsq_f32_e32 v14, v14
	s_nop 0
	v_pk_mul_f32 v[12:13], v[10:11], v[14:15] op_sel_hi:[1,0]
	s_nop 0
	v_pk_mul_f32 v[12:13], v[16:17], v[12:13]
	s_cbranch_vccz .LBB0_953
	v_lshl_or_b32 v14, v110, 10, v47
	v_ashrrev_i32_e32 v15, 31, v14
	v_lshl_add_u64 v[14:15], v[14:15], 2, s[26:27]
	global_store_dword v[14:15], v13, off sc1
	global_store_dword v[14:15], v12, off offset:128 sc1

.LBB0_955:
	v_pk_mul_f32 v[14:15], v[8:9], v[8:9]
	v_ashrrev_i32_e32 v57, 31, v56
	v_add_f32_e32 v14, v15, v14
	s_nop 1
	v_mov_b32_dpp v15, v14 quad_perm:[1,0,3,2] row_mask:0xf bank_mask:0xf
	v_cvt_pk_bf16_f32 v16, v13, s0
	v_cvt_pk_bf16_f32 v17, v12, s0
	v_lshl_add_u64 v[12:13], v[56:57], 0, v[134:135]
	v_lshl_add_u64 v[12:13], v[12:13], 1, s[4:5]
	s_waitcnt lgkmcnt(0)
	v_add_f32_e32 v14, v14, v15
	s_nop 1
	v_mov_b32_dpp v15, v14 quad_perm:[2,3,0,1] row_mask:0xf bank_mask:0xf
	global_store_short v[12:13], v16, off offset:128 sc1
	global_store_short v[12:13], v17, off offset:192 sc1
	s_and_b64 vcc, exec, s[70:71]
	s_waitcnt lgkmcnt(0)
	v_add_f32_e32 v14, v14, v15
	s_nop 1
	v_mov_b32_dpp v15, v14 row_half_mirror row_mask:0xf bank_mask:0xf
	s_waitcnt lgkmcnt(0)
	v_add_f32_e32 v14, v14, v15
	s_nop 1
	v_mov_b32_dpp v15, v14 row_mirror row_mask:0xf bank_mask:0xf
	s_waitcnt lgkmcnt(0)
	v_add_f32_e32 v14, v14, v15
	ds_bpermute_b32 v15, v104, v14
	s_waitcnt lgkmcnt(0)
	v_add_f32_e32 v14, v14, v15
	v_fmamk_f32 v14, v14, 0x3c800000, v196
	v_rsq_f32_e32 v14, v14
	s_nop 0
	v_pk_mul_f32 v[12:13], v[10:11], v[14:15] op_sel_hi:[1,0]
	s_nop 0
	v_pk_mul_f32 v[8:9], v[8:9], v[12:13]
	s_cbranch_vccz .LBB0_957
	v_lshl_or_b32 v12, v111, 10, v47
	v_ashrrev_i32_e32 v13, 31, v12
	v_lshl_add_u64 v[12:13], v[12:13], 2, s[26:27]
	global_store_dword v[12:13], v9, off sc1
	global_store_dword v[12:13], v8, off offset:128 sc1

.LBB0_959:
	v_pk_mul_f32 v[12:13], v[6:7], v[6:7]
	v_ashrrev_i32_e32 v55, 31, v54
	v_add_f32_e32 v12, v13, v12
	s_nop 1
	v_mov_b32_dpp v13, v12 quad_perm:[1,0,3,2] row_mask:0xf bank_mask:0xf
	v_cvt_pk_bf16_f32 v14, v9, s0
	v_cvt_pk_bf16_f32 v15, v8, s0
	v_lshl_add_u64 v[8:9], v[54:55], 0, v[134:135]
	v_lshl_add_u64 v[8:9], v[8:9], 1, s[4:5]
	s_waitcnt lgkmcnt(0)
	v_add_f32_e32 v12, v12, v13
	s_nop 1
	v_mov_b32_dpp v13, v12 quad_perm:[2,3,0,1] row_mask:0xf bank_mask:0xf
	global_store_short v[8:9], v14, off offset:128 sc1
	global_store_short v[8:9], v15, off offset:192 sc1
	s_and_b64 vcc, exec, s[70:71]
	s_waitcnt lgkmcnt(0)
	v_add_f32_e32 v12, v12, v13
	s_nop 1
	v_mov_b32_dpp v13, v12 row_half_mirror row_mask:0xf bank_mask:0xf
	s_waitcnt lgkmcnt(0)
	v_add_f32_e32 v12, v12, v13
	s_nop 1
	v_mov_b32_dpp v13, v12 row_mirror row_mask:0xf bank_mask:0xf
	s_waitcnt lgkmcnt(0)
	v_add_f32_e32 v12, v12, v13
	ds_bpermute_b32 v13, v104, v12
	s_waitcnt lgkmcnt(0)
	v_add_f32_e32 v12, v12, v13
	v_fmamk_f32 v12, v12, 0x3c800000, v196
	v_rsq_f32_e32 v12, v12
	s_nop 0
	v_pk_mul_f32 v[8:9], v[10:11], v[12:13] op_sel_hi:[1,0]
	s_nop 0
	v_pk_mul_f32 v[6:7], v[6:7], v[8:9]
	s_cbranch_vccz .LBB0_961
	v_lshl_or_b32 v8, v112, 10, v47
	v_ashrrev_i32_e32 v9, 31, v8
	v_lshl_add_u64 v[8:9], v[8:9], 2, s[26:27]
	global_store_dword v[8:9], v7, off sc1
	global_store_dword v[8:9], v6, off offset:128 sc1

.LBB0_963:
	v_pk_mul_f32 v[8:9], v[4:5], v[4:5]
	v_ashrrev_i32_e32 v53, 31, v52
	v_add_f32_e32 v8, v9, v8
	s_nop 1
	v_mov_b32_dpp v9, v8 quad_perm:[1,0,3,2] row_mask:0xf bank_mask:0xf
	v_cvt_pk_bf16_f32 v12, v7, s0
	v_cvt_pk_bf16_f32 v13, v6, s0
	v_lshl_add_u64 v[6:7], v[52:53], 0, v[134:135]
	v_lshl_add_u64 v[6:7], v[6:7], 1, s[4:5]
	s_waitcnt lgkmcnt(0)
	v_add_f32_e32 v8, v8, v9
	s_nop 1
	v_mov_b32_dpp v9, v8 quad_perm:[2,3,0,1] row_mask:0xf bank_mask:0xf
	global_store_short v[6:7], v12, off offset:128 sc1
	global_store_short v[6:7], v13, off offset:192 sc1
	s_and_b64 vcc, exec, s[70:71]
	s_waitcnt lgkmcnt(0)
	v_add_f32_e32 v8, v8, v9
	s_nop 1
	v_mov_b32_dpp v9, v8 row_half_mirror row_mask:0xf bank_mask:0xf
	s_waitcnt lgkmcnt(0)
	v_add_f32_e32 v8, v8, v9
	s_nop 1
	v_mov_b32_dpp v9, v8 row_mirror row_mask:0xf bank_mask:0xf
	s_waitcnt lgkmcnt(0)
	v_add_f32_e32 v8, v8, v9
	ds_bpermute_b32 v9, v104, v8
	s_waitcnt lgkmcnt(0)
	v_add_f32_e32 v8, v8, v9
	v_fmamk_f32 v8, v8, 0x3c800000, v196
	v_rsq_f32_e32 v8, v8
	s_nop 0
	v_pk_mul_f32 v[6:7], v[10:11], v[8:9] op_sel_hi:[1,0]
	s_nop 0
	v_pk_mul_f32 v[4:5], v[4:5], v[6:7]
	s_cbranch_vccz .LBB0_965
	v_lshl_or_b32 v6, v113, 10, v47
	v_ashrrev_i32_e32 v7, 31, v6
	v_lshl_add_u64 v[6:7], v[6:7], 2, s[26:27]
	global_store_dword v[6:7], v5, off sc1
	global_store_dword v[6:7], v4, off offset:128 sc1

.LBB0_967:
	v_pk_mul_f32 v[6:7], v[2:3], v[2:3]
	v_ashrrev_i32_e32 v51, 31, v50
	v_add_f32_e32 v6, v7, v6
	s_nop 1
	v_mov_b32_dpp v7, v6 quad_perm:[1,0,3,2] row_mask:0xf bank_mask:0xf
	v_cvt_pk_bf16_f32 v8, v5, s0
	v_cvt_pk_bf16_f32 v9, v4, s0
	v_lshl_add_u64 v[4:5], v[50:51], 0, v[134:135]
	v_lshl_add_u64 v[4:5], v[4:5], 1, s[4:5]
	s_waitcnt lgkmcnt(0)
	v_add_f32_e32 v6, v6, v7
	s_nop 1
	v_mov_b32_dpp v7, v6 quad_perm:[2,3,0,1] row_mask:0xf bank_mask:0xf
	global_store_short v[4:5], v8, off offset:128 sc1
	global_store_short v[4:5], v9, off offset:192 sc1
	s_and_b64 vcc, exec, s[70:71]
	s_waitcnt lgkmcnt(0)
	v_add_f32_e32 v6, v6, v7
	s_nop 1
	v_mov_b32_dpp v7, v6 row_half_mirror row_mask:0xf bank_mask:0xf
	s_waitcnt lgkmcnt(0)
	v_add_f32_e32 v6, v6, v7
	s_nop 1
	v_mov_b32_dpp v7, v6 row_mirror row_mask:0xf bank_mask:0xf
	s_waitcnt lgkmcnt(0)
	v_add_f32_e32 v6, v6, v7
	ds_bpermute_b32 v7, v104, v6
	s_waitcnt lgkmcnt(0)
	v_add_f32_e32 v6, v6, v7
	v_fmamk_f32 v6, v6, 0x3c800000, v196
	v_rsq_f32_e32 v6, v6
	s_nop 0
	v_pk_mul_f32 v[4:5], v[10:11], v[6:7] op_sel_hi:[1,0]
	s_nop 0
	v_pk_mul_f32 v[2:3], v[2:3], v[4:5]
	s_cbranch_vccz .LBB0_969
	v_lshl_or_b32 v4, v114, 10, v47
	v_ashrrev_i32_e32 v5, 31, v4
	v_lshl_add_u64 v[4:5], v[4:5], 2, s[26:27]
	global_store_dword v[4:5], v3, off sc1
	global_store_dword v[4:5], v2, off offset:128 sc1

.LBB0_971:
	v_pk_mul_f32 v[4:5], v[0:1], v[0:1]
	v_ashrrev_i32_e32 v49, 31, v48
	v_add_f32_e32 v4, v5, v4
	s_nop 1
	v_mov_b32_dpp v5, v4 quad_perm:[1,0,3,2] row_mask:0xf bank_mask:0xf
	v_cvt_pk_bf16_f32 v6, v3, s0
	v_cvt_pk_bf16_f32 v7, v2, s0
	v_lshl_add_u64 v[2:3], v[48:49], 0, v[134:135]
	v_lshl_add_u64 v[2:3], v[2:3], 1, s[4:5]
	s_waitcnt lgkmcnt(0)
	v_add_f32_e32 v4, v4, v5
	s_nop 1
	v_mov_b32_dpp v5, v4 quad_perm:[2,3,0,1] row_mask:0xf bank_mask:0xf
	global_store_short v[2:3], v6, off offset:128 sc1
	global_store_short v[2:3], v7, off offset:192 sc1
	s_and_b64 vcc, exec, s[70:71]
	s_waitcnt lgkmcnt(0)
	v_add_f32_e32 v4, v4, v5
	s_nop 1
	v_mov_b32_dpp v5, v4 row_half_mirror row_mask:0xf bank_mask:0xf
	s_waitcnt lgkmcnt(0)
	v_add_f32_e32 v4, v4, v5
	s_nop 1
	v_mov_b32_dpp v5, v4 row_mirror row_mask:0xf bank_mask:0xf
	s_waitcnt lgkmcnt(0)
	v_add_f32_e32 v4, v4, v5
	ds_bpermute_b32 v5, v104, v4
	s_waitcnt lgkmcnt(0)
	v_add_f32_e32 v4, v4, v5
	v_fmamk_f32 v4, v4, 0x3c800000, v196
	v_rsq_f32_e32 v4, v4
	s_nop 0
	v_pk_mul_f32 v[2:3], v[10:11], v[4:5] op_sel_hi:[1,0]
	s_nop 0
	v_pk_mul_f32 v[0:1], v[0:1], v[2:3]
	s_cbranch_vccz .LBB0_973
	v_lshl_or_b32 v2, v97, 10, v47
	v_ashrrev_i32_e32 v3, 31, v2
	v_lshl_add_u64 v[2:3], v[2:3], 2, s[26:27]
	global_store_dword v[2:3], v1, off sc1
	global_store_dword v[2:3], v0, off offset:128 sc1

.LBB0_1050:
	s_add_i32 s58, s66, 0xffffe000
	s_lshr_b32 s58, s58, 12
	s_mulk_i32 s58, 0x1800
	v_mov_b32_e32 v70, s70
	s_addk_i32 s58, 0x6000
	ds_read_b64 v[70:71], v70
	s_cmp_gt_i32 s6, 63
	s_cselect_b32 s6, s58, 0x4800
	s_lshl_b64 s[58:59], s[6:7], 2
	s_add_u32 s6, s14, s58
	s_addc_u32 s65, s15, s59
	s_waitcnt lgkmcnt(0)
	v_readfirstlane_b32 s58, v70
	v_readfirstlane_b32 s59, v71
	s_add_u32 s60, s58, 0x1000
	s_addc_u32 s61, s59, 0
	s_lshl_b32 s58, s64, 14
	s_add_i32 s58, s58, 0x60000
	s_ashr_i32 s59, s58, 31
	s_lshl_b64 s[58:59], s[58:59], 2
	s_add_u32 s58, s10, s58
	s_addc_u32 s59, s11, s59
	s_add_u32 s62, s6, 0x5ba2000
	v_or_b32_e32 v102, s68, v138
	v_add_u32_e32 v70, s66, v139
	s_addc_u32 s63, s65, 0
	v_lshlrev_b32_e32 v188, 10, v70
	v_ashrrev_i32_e32 v103, 31, v102
	s_add_u32 s64, s6, 0x5ba4000
	v_lshlrev_b64 v[72:73], 2, v[102:103]
	v_or_b32_e32 v186, 0x400, v188
	v_or_b32_e32 v185, 0x4400, v188
	v_or_b32_e32 v189, 0x4c00, v188
	v_or_b32_e32 v193, 0x6c00, v188
	s_addc_u32 s65, s65, 0
	v_lshl_add_u64 v[74:75], s[62:63], 0, v[72:73]
	v_add_u32_e32 v132, v188, v102
	v_add_u32_e32 v134, v186, v102
	v_or_b32_e32 v184, 0x800, v188
	v_or_b32_e32 v183, 0xc00, v188
	v_or_b32_e32 v181, 0x2000, v188
	v_or_b32_e32 v179, 0x2400, v188
	v_or_b32_e32 v71, 0x2800, v188
	v_or_b32_e32 v180, 0x2c00, v188
	v_or_b32_e32 v182, 0x4000, v188
	v_add_u32_e32 v112, v185, v102
	v_or_b32_e32 v187, 0x4800, v188
	v_add_u32_e32 v118, v189, v102
	v_or_b32_e32 v190, 0x6000, v188
	v_or_b32_e32 v191, 0x6400, v188
	v_or_b32_e32 v192, 0x6800, v188
	v_add_u32_e32 v128, v193, v102
	global_load_dword v194, v[74:75], off
	v_lshl_add_u64 v[74:75], s[60:61], 0, v[72:73]
	v_lshl_add_u64 v[72:73], s[64:65], 0, v[72:73]
	v_ashrrev_i32_e32 v135, 31, v134
	v_add_u32_e32 v136, v184, v102
	v_add_u32_e32 v130, v183, v102
	v_add_u32_e32 v122, v181, v102
	v_add_u32_e32 v114, v179, v102
	v_add_u32_e32 v106, v71, v102
	v_add_u32_e32 v108, v180, v102
	v_add_u32_e32 v110, v182, v102
	v_ashrrev_i32_e32 v113, 31, v112
	v_add_u32_e32 v116, v187, v102
	v_ashrrev_i32_e32 v119, 31, v118
	v_add_u32_e32 v120, v190, v102
	v_add_u32_e32 v124, v191, v102
	v_add_u32_e32 v126, v192, v102
	v_ashrrev_i32_e32 v129, 31, v128
	v_ashrrev_i32_e32 v133, 31, v132
	global_load_dword v196, v[72:73], off
	v_lshl_add_u64 v[88:89], v[134:135], 2, s[12:13]
	v_ashrrev_i32_e32 v137, 31, v136
	v_ashrrev_i32_e32 v131, 31, v130
	v_ashrrev_i32_e32 v123, 31, v122
	v_ashrrev_i32_e32 v115, 31, v114
	v_ashrrev_i32_e32 v107, 31, v106
	v_ashrrev_i32_e32 v109, 31, v108
	v_ashrrev_i32_e32 v111, 31, v110
	v_lshl_add_u64 v[86:87], v[112:113], 2, s[12:13]
	v_ashrrev_i32_e32 v117, 31, v116
	v_lshl_add_u64 v[92:93], v[118:119], 2, s[12:13]
	v_ashrrev_i32_e32 v121, 31, v120
	v_ashrrev_i32_e32 v125, 31, v124
	v_ashrrev_i32_e32 v127, 31, v126
	v_lshl_add_u64 v[100:101], v[128:129], 2, s[12:13]
	v_lshl_add_u64 v[104:105], v[132:133], 2, s[12:13]
	global_load_dword v195, v[74:75], off
	v_lshl_add_u64 v[84:85], v[136:137], 2, s[12:13]
	v_lshl_add_u64 v[82:83], v[130:131], 2, s[12:13]
	v_lshl_add_u64 v[78:79], v[122:123], 2, s[12:13]
	v_lshl_add_u64 v[72:73], v[114:115], 2, s[12:13]
	v_lshl_add_u64 v[74:75], v[106:107], 2, s[12:13]
	v_lshl_add_u64 v[76:77], v[108:109], 2, s[12:13]
	v_lshl_add_u64 v[80:81], v[110:111], 2, s[12:13]
	global_load_dword v178, v[88:89], off
	global_load_dword v177, v[84:85], off
	global_load_dword v176, v[82:83], off
	global_load_dword v175, v[78:79], off
	global_load_dword v174, v[72:73], off
	global_load_dword v173, v[74:75], off
	global_load_dword v172, v[76:77], off
	global_load_dword v171, v[80:81], off
	v_lshl_add_u64 v[90:91], v[116:117], 2, s[12:13]
	global_load_dword v170, v[86:87], off
	global_load_dword v168, v[90:91], off
	v_lshl_add_u64 v[94:95], v[120:121], 2, s[12:13]
	v_lshl_add_u64 v[96:97], v[124:125], 2, s[12:13]
	v_lshl_add_u64 v[98:99], v[126:127], 2, s[12:13]
	global_load_dword v169, v[92:93], off
	global_load_dword v167, v[94:95], off
	global_load_dword v166, v[96:97], off
	global_load_dword v165, v[98:99], off
	global_load_dword v103, v[100:101], off
	global_load_dword v197, v[104:105], off
	v_lshl_add_u64 v[106:107], v[106:107], 1, s[8:9]
	s_waitcnt vmcnt(0)
	v_add_f32_e32 v196, 1.0, v196
	v_mul_f32_e32 v195, v195, v196
	v_fmac_f32_e32 v178, v49, v194
	v_fmac_f32_e32 v177, v50, v194
	v_fmac_f32_e32 v176, v51, v194
	v_fmac_f32_e32 v175, v52, v194
	v_fmac_f32_e32 v174, v53, v194
	v_fmac_f32_e32 v173, v54, v194
	v_fmac_f32_e32 v172, v55, v194
	v_fmac_f32_e32 v171, v56, v194
	v_fmac_f32_e32 v170, v57, v194
	v_fmac_f32_e32 v168, v58, v194
	v_fmac_f32_e32 v169, v59, v194
	v_fmac_f32_e32 v167, v60, v194
	v_fmac_f32_e32 v166, v61, v194
	v_fmac_f32_e32 v165, v62, v194
	v_fmac_f32_e32 v103, v63, v194
	v_fmac_f32_e32 v197, v48, v194
	v_mul_f32_e32 v48, v195, v197
	v_cvt_pk_bf16_f32 v58, v48, s0
	v_or_b32_e32 v48, 32, v102
	v_ashrrev_i32_e32 v49, 31, v48
	v_lshlrev_b64 v[52:53], 2, v[48:49]
	global_store_dword v[88:89], v178, off sc1
	global_store_dword v[84:85], v177, off sc1
	global_store_dword v[82:83], v176, off sc1
	global_store_dword v[78:79], v175, off sc1
	global_store_dword v[72:73], v174, off sc1
	global_store_dword v[74:75], v173, off sc1
	global_store_dword v[76:77], v172, off sc1
	global_store_dword v[80:81], v171, off sc1
	global_store_dword v[86:87], v170, off sc1
	global_store_dword v[90:91], v168, off sc1
	global_store_dword v[92:93], v169, off sc1
	global_store_dword v[94:95], v167, off sc1
	global_store_dword v[96:97], v166, off sc1
	global_store_dword v[98:99], v165, off sc1
	global_store_dword v[100:101], v103, off sc1
	global_store_dword v[104:105], v197, off sc1
	v_lshl_add_u64 v[50:51], v[132:133], 1, s[8:9]
	v_lshl_add_u64 v[56:57], s[64:65], 0, v[52:53]
	global_load_dword v196, v[104:105], off offset:128
	v_lshl_add_u64 v[54:55], s[60:61], 0, v[52:53]
	global_load_dword v132, v[56:57], off
	global_load_dword v133, v[54:55], off
	v_mul_f32_e32 v49, v195, v178
	global_store_short v[50:51], v58, off sc1
	v_lshl_add_u64 v[50:51], s[62:63], 0, v[52:53]
	global_load_dword v194, v[50:51], off
	v_cvt_pk_bf16_f32 v49, v49, s0
	v_lshl_add_u64 v[50:51], v[134:135], 1, s[8:9]
	global_store_short v[50:51], v49, off sc1
	v_mul_f32_e32 v49, v195, v177
	v_cvt_pk_bf16_f32 v49, v49, s0
	v_lshl_add_u64 v[50:51], v[136:137], 1, s[8:9]
	global_store_short v[50:51], v49, off sc1
	v_mul_f32_e32 v49, v195, v176
	v_cvt_pk_bf16_f32 v49, v49, s0
	v_lshl_add_u64 v[50:51], v[130:131], 1, s[8:9]
	global_store_short v[50:51], v49, off sc1
	v_mul_f32_e32 v49, v195, v175
	v_cvt_pk_bf16_f32 v49, v49, s0
	v_lshl_add_u64 v[50:51], v[122:123], 1, s[8:9]
	global_store_short v[50:51], v49, off sc1
	v_mul_f32_e32 v49, v195, v174
	v_cvt_pk_bf16_f32 v49, v49, s0
	v_lshl_add_u64 v[50:51], v[114:115], 1, s[8:9]
	global_store_short v[50:51], v49, off sc1
	v_mul_f32_e32 v49, v195, v173
	global_load_dword v62, v[84:85], off offset:128
	global_load_dword v60, v[78:79], off offset:128
	global_load_dword v59, v[72:73], off offset:128
	global_load_dword v58, v[74:75], off offset:128
	global_load_dword v56, v[80:81], off offset:128
	global_load_dword v57, v[76:77], off offset:128
	global_load_dword v55, v[86:87], off offset:128
	global_load_dword v61, v[82:83], off offset:128
	global_load_dword v54, v[90:91], off offset:128
	global_load_dword v53, v[92:93], off offset:128
	global_load_dword v52, v[94:95], off offset:128
	global_load_dword v51, v[96:97], off offset:128
	global_load_dword v50, v[98:99], off offset:128
	v_cvt_pk_bf16_f32 v63, v49, s0
	global_load_dword v49, v[100:101], off offset:128
	s_waitcnt vmcnt(19)
	v_fmac_f32_e32 v196, v32, v194
	global_store_short v[106:107], v63, off sc1
	global_load_dword v63, v[88:89], off offset:128
	v_mul_f32_e32 v106, v195, v172
	v_cvt_pk_bf16_f32 v114, v106, s0
	v_lshl_add_u64 v[106:107], v[108:109], 1, s[8:9]
	global_store_short v[106:107], v114, off sc1
	v_mul_f32_e32 v106, v195, v171
	v_cvt_pk_bf16_f32 v108, v106, s0
	v_lshl_add_u64 v[106:107], v[110:111], 1, s[8:9]
	global_store_short v[106:107], v108, off sc1
	v_mul_f32_e32 v106, v195, v170
	v_cvt_pk_bf16_f32 v108, v106, s0
	v_lshl_add_u64 v[106:107], v[112:113], 1, s[8:9]
	global_store_short v[106:107], v108, off sc1
	v_mul_f32_e32 v106, v195, v168
	v_cvt_pk_bf16_f32 v108, v106, s0
	v_lshl_add_u64 v[106:107], v[116:117], 1, s[8:9]
	global_store_short v[106:107], v108, off sc1
	v_mul_f32_e32 v106, v195, v169
	v_cvt_pk_bf16_f32 v108, v106, s0
	v_lshl_add_u64 v[106:107], v[118:119], 1, s[8:9]
	global_store_short v[106:107], v108, off sc1
	v_mul_f32_e32 v106, v195, v167
	v_cvt_pk_bf16_f32 v108, v106, s0
	v_lshl_add_u64 v[106:107], v[120:121], 1, s[8:9]
	global_store_short v[106:107], v108, off sc1
	v_mul_f32_e32 v106, v195, v166
	v_cvt_pk_bf16_f32 v108, v106, s0
	v_lshl_add_u64 v[106:107], v[124:125], 1, s[8:9]
	global_store_short v[106:107], v108, off sc1
	v_mul_f32_e32 v106, v195, v165
	v_cvt_pk_bf16_f32 v108, v106, s0
	v_lshl_add_u64 v[106:107], v[126:127], 1, s[8:9]
	global_store_short v[106:107], v108, off sc1
	v_mul_f32_e32 v106, v195, v103
	v_cvt_pk_bf16_f32 v108, v106, s0
	v_lshl_add_u64 v[106:107], v[128:129], 1, s[8:9]
	global_store_short v[106:107], v108, off sc1
	v_add_f32_e32 v106, 1.0, v132
	v_mul_f32_e32 v110, v133, v106
	v_add_u32_e32 v106, v188, v48
	s_waitcnt vmcnt(24)
	v_fmac_f32_e32 v62, v34, v194
	s_waitcnt vmcnt(17)
	v_fmac_f32_e32 v61, v35, v194
	v_fmac_f32_e32 v60, v36, v194
	v_fmac_f32_e32 v59, v37, v194
	v_fmac_f32_e32 v58, v38, v194
	v_fmac_f32_e32 v57, v39, v194
	v_fmac_f32_e32 v56, v40, v194
	v_fmac_f32_e32 v55, v41, v194
	s_waitcnt vmcnt(16)
	v_fmac_f32_e32 v54, v42, v194
	s_waitcnt vmcnt(15)
	v_fmac_f32_e32 v53, v43, v194
	s_waitcnt vmcnt(14)
	v_fmac_f32_e32 v52, v44, v194
	s_waitcnt vmcnt(13)
	v_fmac_f32_e32 v51, v45, v194
	s_waitcnt vmcnt(12)
	v_fmac_f32_e32 v50, v46, v194
	s_waitcnt vmcnt(11)
	v_fmac_f32_e32 v49, v47, v194
	v_ashrrev_i32_e32 v107, 31, v106
	global_store_dword v[104:105], v196, off offset:128 sc1
	v_mul_f32_e32 v32, v110, v196
	global_store_dword v[84:85], v62, off offset:128 sc1
	global_store_dword v[82:83], v61, off offset:128 sc1
	global_store_dword v[78:79], v60, off offset:128 sc1
	global_store_dword v[72:73], v59, off offset:128 sc1
	global_store_dword v[74:75], v58, off offset:128 sc1
	global_store_dword v[76:77], v57, off offset:128 sc1
	global_store_dword v[80:81], v56, off offset:128 sc1
	global_store_dword v[86:87], v55, off offset:128 sc1
	global_store_dword v[90:91], v54, off offset:128 sc1
	global_store_dword v[92:93], v53, off offset:128 sc1
	global_store_dword v[94:95], v52, off offset:128 sc1
	global_store_dword v[96:97], v51, off offset:128 sc1
	global_store_dword v[98:99], v50, off offset:128 sc1
	global_store_dword v[100:101], v49, off offset:128 sc1
	v_cvt_pk_bf16_f32 v32, v32, s0
	v_lshl_add_u64 v[106:107], v[106:107], 1, s[8:9]
	v_add_u32_e32 v108, v186, v48
	global_load_dword v45, v[88:89], off offset:256
	v_ashrrev_i32_e32 v109, 31, v108
	global_store_short v[106:107], v32, off sc1
	v_mul_f32_e32 v113, v110, v56
	v_cvt_pk_bf16_f32 v113, v113, s0
	v_mul_f32_e32 v106, v196, v196
	s_waitcnt vmcnt(26)
	v_fmac_f32_e32 v63, v33, v194
	v_mul_f32_e32 v32, v110, v63
	v_cvt_pk_bf16_f32 v34, v32, s0
	v_lshl_add_u64 v[32:33], v[108:109], 1, s[8:9]
	global_store_short v[32:33], v34, off sc1
	v_add_u32_e32 v32, v184, v48
	v_ashrrev_i32_e32 v33, 31, v32
	v_mul_f32_e32 v34, v110, v62
	v_cvt_pk_bf16_f32 v34, v34, s0
	v_lshl_add_u64 v[32:33], v[32:33], 1, s[8:9]
	global_store_short v[32:33], v34, off sc1
	v_add_u32_e32 v32, v183, v48
	v_ashrrev_i32_e32 v33, 31, v32
	v_mul_f32_e32 v34, v110, v61
	v_cvt_pk_bf16_f32 v34, v34, s0
	v_lshl_add_u64 v[32:33], v[32:33], 1, s[8:9]
	global_store_short v[32:33], v34, off sc1
	v_add_u32_e32 v32, v181, v48
	v_ashrrev_i32_e32 v33, 31, v32
	v_mul_f32_e32 v34, v110, v60
	v_cvt_pk_bf16_f32 v34, v34, s0
	v_lshl_add_u64 v[32:33], v[32:33], 1, s[8:9]
	global_store_short v[32:33], v34, off sc1
	v_add_u32_e32 v32, v179, v48
	v_ashrrev_i32_e32 v33, 31, v32
	v_mul_f32_e32 v34, v110, v59
	v_cvt_pk_bf16_f32 v42, v34, s0
	v_lshl_add_u64 v[34:35], v[32:33], 1, s[8:9]
	v_or_b32_e32 v32, 64, v102
	v_ashrrev_i32_e32 v33, 31, v32
	v_lshlrev_b64 v[36:37], 2, v[32:33]
	global_store_dword v[88:89], v63, off offset:128 sc1
	v_lshl_add_u64 v[40:41], s[64:65], 0, v[36:37]
	v_lshl_add_u64 v[38:39], s[60:61], 0, v[36:37]
	global_load_dword v107, v[40:41], off
	global_load_dword v111, v[38:39], off
	v_mul_f32_e32 v33, v110, v58
	global_store_short v[34:35], v42, off sc1
	v_lshl_add_u64 v[34:35], s[62:63], 0, v[36:37]
	global_load_dword v112, v[34:35], off
	v_add_u32_e32 v34, v71, v48
	v_ashrrev_i32_e32 v35, 31, v34
	v_cvt_pk_bf16_f32 v33, v33, s0
	v_lshl_add_u64 v[34:35], v[34:35], 1, s[8:9]
	global_store_short v[34:35], v33, off sc1
	v_add_u32_e32 v34, v180, v48
	v_ashrrev_i32_e32 v35, 31, v34
	v_mul_f32_e32 v33, v110, v57
	v_cvt_pk_bf16_f32 v33, v33, s0
	v_lshl_add_u64 v[34:35], v[34:35], 1, s[8:9]
	global_load_dword v38, v[90:91], off offset:256
	global_load_dword v37, v[92:93], off offset:256
	global_load_dword v36, v[94:95], off offset:256
	global_load_dword v114, v[104:105], off offset:256
	global_load_dword v47, v[84:85], off offset:256
	global_load_dword v39, v[86:87], off offset:256
	global_load_dword v46, v[82:83], off offset:256
	global_load_dword v44, v[78:79], off offset:256
	global_load_dword v43, v[72:73], off offset:256
	global_load_dword v42, v[74:75], off offset:256
	global_load_dword v40, v[80:81], off offset:256
	global_load_dword v41, v[76:77], off offset:256
	v_add_u32_e32 v108, v182, v48
	global_store_short v[34:35], v33, off sc1
	global_load_dword v35, v[96:97], off offset:256
	v_ashrrev_i32_e32 v109, 31, v108
	global_load_dword v34, v[98:99], off offset:256
	global_load_dword v33, v[100:101], off offset:256
	v_lshl_add_u64 v[108:109], v[108:109], 1, s[8:9]
	global_store_short v[108:109], v113, off sc1
	v_add_u32_e32 v108, v185, v48
	v_ashrrev_i32_e32 v109, 31, v108
	v_mul_f32_e32 v113, v110, v55
	v_cvt_pk_bf16_f32 v113, v113, s0
	v_lshl_add_u64 v[108:109], v[108:109], 1, s[8:9]
	global_store_short v[108:109], v113, off sc1
	v_add_u32_e32 v108, v187, v48
	v_ashrrev_i32_e32 v109, 31, v108
	v_mul_f32_e32 v113, v110, v54
	v_cvt_pk_bf16_f32 v113, v113, s0
	v_lshl_add_u64 v[108:109], v[108:109], 1, s[8:9]
	global_store_short v[108:109], v113, off sc1
	v_add_u32_e32 v108, v189, v48
	v_ashrrev_i32_e32 v109, 31, v108
	v_mul_f32_e32 v113, v110, v53
	v_cvt_pk_bf16_f32 v113, v113, s0
	v_lshl_add_u64 v[108:109], v[108:109], 1, s[8:9]
	global_store_short v[108:109], v113, off sc1
	v_add_u32_e32 v108, v190, v48
	v_ashrrev_i32_e32 v109, 31, v108
	v_mul_f32_e32 v113, v110, v52
	v_cvt_pk_bf16_f32 v113, v113, s0
	v_lshl_add_u64 v[108:109], v[108:109], 1, s[8:9]
	global_store_short v[108:109], v113, off sc1
	v_add_u32_e32 v108, v191, v48
	v_ashrrev_i32_e32 v109, 31, v108
	v_mul_f32_e32 v113, v110, v51
	v_cvt_pk_bf16_f32 v113, v113, s0
	v_lshl_add_u64 v[108:109], v[108:109], 1, s[8:9]
	global_store_short v[108:109], v113, off sc1
	v_add_u32_e32 v108, v192, v48
	v_ashrrev_i32_e32 v109, 31, v108
	v_mul_f32_e32 v113, v110, v50
	v_cvt_pk_bf16_f32 v113, v113, s0
	v_lshl_add_u64 v[108:109], v[108:109], 1, s[8:9]
	global_store_short v[108:109], v113, off sc1
	v_add_u32_e32 v108, v193, v48
	v_ashrrev_i32_e32 v109, 31, v108
	v_mul_f32_e32 v48, v110, v49
	v_cvt_pk_bf16_f32 v48, v48, s0
	v_lshl_add_u64 v[108:109], v[108:109], 1, s[8:9]
	global_store_short v[108:109], v48, off sc1
	v_add_u32_e32 v108, v188, v32
	v_ashrrev_i32_e32 v109, 31, v108
	s_waitcnt vmcnt(28)
	v_add_f32_e32 v48, 1.0, v107
	s_waitcnt vmcnt(27)
	v_mul_f32_e32 v48, v111, v48
	v_fmac_f32_e32 v106, v197, v197
	s_waitcnt vmcnt(25)
	v_fmac_f32_e32 v45, v17, v112
	global_store_dword v[88:89], v45, off offset:256 sc1
	s_waitcnt vmcnt(24)
	v_fmac_f32_e32 v38, v26, v112
	s_waitcnt vmcnt(23)
	v_fmac_f32_e32 v37, v27, v112
	s_waitcnt vmcnt(22)
	v_fmac_f32_e32 v36, v28, v112
	s_waitcnt vmcnt(21)
	v_fmac_f32_e32 v114, v16, v112
	v_mul_f32_e32 v16, v48, v114
	s_waitcnt vmcnt(20)
	v_fmac_f32_e32 v47, v18, v112
	v_cvt_pk_bf16_f32 v18, v16, s0
	v_lshl_add_u64 v[16:17], v[108:109], 1, s[8:9]
	global_store_short v[16:17], v18, off sc1
	v_add_u32_e32 v16, v186, v32
	v_ashrrev_i32_e32 v17, 31, v16
	v_mul_f32_e32 v18, v48, v45
	v_cvt_pk_bf16_f32 v18, v18, s0
	v_lshl_add_u64 v[16:17], v[16:17], 1, s[8:9]
	global_store_short v[16:17], v18, off sc1
	v_add_u32_e32 v16, v184, v32
	v_ashrrev_i32_e32 v17, 31, v16
	v_mul_f32_e32 v18, v48, v47
	v_cvt_pk_bf16_f32 v18, v18, s0
	v_lshl_add_u64 v[16:17], v[16:17], 1, s[8:9]
	s_waitcnt vmcnt(20)
	v_fmac_f32_e32 v46, v19, v112
	global_store_short v[16:17], v18, off sc1
	v_add_u32_e32 v16, v183, v32
	v_ashrrev_i32_e32 v17, 31, v16
	v_mul_f32_e32 v18, v48, v46
	s_waitcnt vmcnt(20)
	v_fmac_f32_e32 v44, v20, v112
	v_cvt_pk_bf16_f32 v18, v18, s0
	v_lshl_add_u64 v[16:17], v[16:17], 1, s[8:9]
	global_store_short v[16:17], v18, off sc1
	v_mul_f32_e32 v16, v48, v44
	v_cvt_pk_bf16_f32 v26, v16, s0
	v_or_b32_e32 v16, 0x60, v102
	v_add_u32_e32 v18, v181, v32
	v_ashrrev_i32_e32 v17, 31, v16
	s_waitcnt vmcnt(20)
	v_fmac_f32_e32 v43, v21, v112
	s_waitcnt vmcnt(19)
	v_fmac_f32_e32 v42, v22, v112
	s_waitcnt vmcnt(17)
	v_fmac_f32_e32 v41, v23, v112
	v_fmac_f32_e32 v40, v24, v112
	v_fmac_f32_e32 v39, v25, v112
	s_waitcnt vmcnt(15)
	v_fmac_f32_e32 v35, v29, v112
	s_waitcnt vmcnt(14)
	v_fmac_f32_e32 v34, v30, v112
	s_waitcnt vmcnt(13)
	v_fmac_f32_e32 v33, v31, v112
	v_ashrrev_i32_e32 v19, 31, v18
	v_lshlrev_b64 v[20:21], 2, v[16:17]
	global_store_dword v[84:85], v47, off offset:256 sc1
	global_store_dword v[82:83], v46, off offset:256 sc1
	global_store_dword v[78:79], v44, off offset:256 sc1
	global_store_dword v[72:73], v43, off offset:256 sc1
	global_store_dword v[74:75], v42, off offset:256 sc1
	global_store_dword v[76:77], v41, off offset:256 sc1
	global_store_dword v[80:81], v40, off offset:256 sc1
	global_store_dword v[86:87], v39, off offset:256 sc1
	global_store_dword v[90:91], v38, off offset:256 sc1
	global_store_dword v[92:93], v37, off offset:256 sc1
	global_store_dword v[94:95], v36, off offset:256 sc1
	global_store_dword v[96:97], v35, off offset:256 sc1
	global_store_dword v[98:99], v34, off offset:256 sc1
	global_store_dword v[100:101], v33, off offset:256 sc1
	global_store_dword v[104:105], v114, off offset:256 sc1
	v_lshl_add_u64 v[24:25], s[64:65], 0, v[20:21]
	v_lshl_add_u64 v[18:19], v[18:19], 1, s[8:9]
	global_load_dword v29, v[104:105], off offset:384
	v_lshl_add_u64 v[22:23], s[60:61], 0, v[20:21]
	global_load_dword v17, v[24:25], off
	global_load_dword v30, v[22:23], off
	global_load_dword v28, v[88:89], off offset:384
	global_load_dword v27, v[84:85], off offset:384
	v_fmac_f32_e32 v106, v114, v114
	global_store_short v[18:19], v26, off sc1
	v_lshl_add_u64 v[18:19], s[62:63], 0, v[20:21]
	global_load_dword v102, v[18:19], off
	v_add_u32_e32 v18, v179, v32
	v_ashrrev_i32_e32 v19, 31, v18
	v_mul_f32_e32 v20, v48, v43
	v_cvt_pk_bf16_f32 v20, v20, s0
	v_lshl_add_u64 v[18:19], v[18:19], 1, s[8:9]
	global_store_short v[18:19], v20, off sc1
	v_add_u32_e32 v18, v71, v32
	v_ashrrev_i32_e32 v19, 31, v18
	v_mul_f32_e32 v20, v48, v42
	v_cvt_pk_bf16_f32 v20, v20, s0
	v_lshl_add_u64 v[18:19], v[18:19], 1, s[8:9]
	global_store_short v[18:19], v20, off sc1
	v_add_u32_e32 v18, v180, v32
	v_ashrrev_i32_e32 v19, 31, v18
	v_mul_f32_e32 v20, v48, v41
	v_cvt_pk_bf16_f32 v20, v20, s0
	v_lshl_add_u64 v[18:19], v[18:19], 1, s[8:9]
	global_store_short v[18:19], v20, off sc1
	v_add_u32_e32 v18, v182, v32
	v_ashrrev_i32_e32 v19, 31, v18
	v_mul_f32_e32 v20, v48, v40
	v_cvt_pk_bf16_f32 v20, v20, s0
	v_lshl_add_u64 v[18:19], v[18:19], 1, s[8:9]
	global_store_short v[18:19], v20, off sc1
	v_add_u32_e32 v18, v185, v32
	v_ashrrev_i32_e32 v19, 31, v18
	v_mul_f32_e32 v20, v48, v39
	v_cvt_pk_bf16_f32 v20, v20, s0
	v_lshl_add_u64 v[18:19], v[18:19], 1, s[8:9]
	global_store_short v[18:19], v20, off sc1
	v_add_u32_e32 v18, v187, v32
	v_ashrrev_i32_e32 v19, 31, v18
	v_mul_f32_e32 v20, v48, v38
	v_cvt_pk_bf16_f32 v20, v20, s0
	v_lshl_add_u64 v[18:19], v[18:19], 1, s[8:9]
	global_store_short v[18:19], v20, off sc1
	v_add_u32_e32 v18, v189, v32
	v_ashrrev_i32_e32 v19, 31, v18
	v_mul_f32_e32 v20, v48, v37
	v_cvt_pk_bf16_f32 v20, v20, s0
	v_lshl_add_u64 v[18:19], v[18:19], 1, s[8:9]
	global_store_short v[18:19], v20, off sc1
	v_add_u32_e32 v18, v190, v32
	v_ashrrev_i32_e32 v19, 31, v18
	v_mul_f32_e32 v20, v48, v36
	v_cvt_pk_bf16_f32 v20, v20, s0
	v_lshl_add_u64 v[18:19], v[18:19], 1, s[8:9]
	global_store_short v[18:19], v20, off sc1
	v_add_u32_e32 v18, v191, v32
	v_ashrrev_i32_e32 v19, 31, v18
	v_mul_f32_e32 v20, v48, v35
	v_cvt_pk_bf16_f32 v20, v20, s0
	v_lshl_add_u64 v[18:19], v[18:19], 1, s[8:9]
	global_store_short v[18:19], v20, off sc1
	v_add_u32_e32 v18, v192, v32
	v_ashrrev_i32_e32 v19, 31, v18
	v_mul_f32_e32 v20, v48, v34
	v_cvt_pk_bf16_f32 v20, v20, s0
	v_lshl_add_u64 v[18:19], v[18:19], 1, s[8:9]
	global_store_short v[18:19], v20, off sc1
	v_add_u32_e32 v18, v193, v32
	v_ashrrev_i32_e32 v19, 31, v18
	v_mul_f32_e32 v20, v48, v33
	v_cvt_pk_bf16_f32 v20, v20, s0
	v_lshl_add_u64 v[18:19], v[18:19], 1, s[8:9]
	global_store_short v[18:19], v20, off sc1
	global_load_dword v20, v[86:87], off offset:384
	v_add_u32_e32 v18, v188, v16
	global_load_dword v26, v[82:83], off offset:384
	global_load_dword v25, v[78:79], off offset:384
	global_load_dword v24, v[72:73], off offset:384
	global_load_dword v23, v[74:75], off offset:384
	global_load_dword v21, v[80:81], off offset:384
	global_load_dword v22, v[76:77], off offset:384
	s_waitcnt vmcnt(23)
	v_add_f32_e32 v17, 1.0, v17
	s_waitcnt vmcnt(22)
	v_mul_f32_e32 v32, v30, v17
	v_ashrrev_i32_e32 v19, 31, v18
	v_lshl_add_u64 v[18:19], v[18:19], 1, s[8:9]
	v_add_u32_e32 v30, v186, v16
	s_waitcnt vmcnt(18)
	v_fmac_f32_e32 v29, v0, v102
	v_mul_f32_e32 v0, v32, v29
	v_cvt_pk_bf16_f32 v0, v0, s0
	global_store_short v[18:19], v0, off sc1
	global_load_dword v19, v[90:91], off offset:384
	v_ashrrev_i32_e32 v31, 31, v30
	global_load_dword v18, v[92:93], off offset:384
	v_fmac_f32_e32 v28, v1, v102
	v_mul_f32_e32 v0, v32, v28
	v_cvt_pk_bf16_f32 v17, v0, s0
	v_lshl_add_u64 v[0:1], v[30:31], 1, s[8:9]
	global_store_short v[0:1], v17, off sc1
	v_add_u32_e32 v0, v184, v16
	v_fmac_f32_e32 v27, v2, v102
	global_load_dword v17, v[94:95], off offset:384
	v_ashrrev_i32_e32 v1, 31, v0
	v_mul_f32_e32 v2, v32, v27
	v_cvt_pk_bf16_f32 v2, v2, s0
	v_lshl_add_u64 v[0:1], v[0:1], 1, s[8:9]
	global_store_short v[0:1], v2, off sc1
	v_add_u32_e32 v0, v183, v16
	global_load_dword v2, v[96:97], off offset:384
	v_ashrrev_i32_e32 v1, 31, v0
	v_lshl_add_u64 v[0:1], v[0:1], 1, s[8:9]
	v_add_u32_e32 v30, v181, v16
	v_ashrrev_i32_e32 v31, 31, v30
	v_lshl_add_u64 v[30:31], v[30:31], 1, s[8:9]
	v_fmac_f32_e32 v106, v29, v29
	global_store_dword v[104:105], v29, off offset:384 sc1
	global_store_dword v[88:89], v28, off offset:384 sc1
	global_store_dword v[84:85], v27, off offset:384 sc1
	s_waitcnt vmcnt(16)
	v_fmac_f32_e32 v20, v9, v102
	global_store_dword v[86:87], v20, off offset:384 sc1
	s_waitcnt vmcnt(16)
	v_fmac_f32_e32 v26, v3, v102
	v_mul_f32_e32 v3, v32, v26
	v_cvt_pk_bf16_f32 v3, v3, s0
	global_store_short v[0:1], v3, off sc1
	global_load_dword v1, v[98:99], off offset:384
	s_waitcnt vmcnt(17)
	v_fmac_f32_e32 v25, v4, v102
	v_mul_f32_e32 v0, v32, v25
	v_cvt_pk_bf16_f32 v0, v0, s0
	global_store_short v[30:31], v0, off sc1
	global_load_dword v0, v[100:101], off offset:384
	v_add_u32_e32 v30, v179, v16
	s_waitcnt vmcnt(18)
	v_fmac_f32_e32 v24, v5, v102
	v_ashrrev_i32_e32 v31, 31, v30
	v_mul_f32_e32 v3, v32, v24
	v_cvt_pk_bf16_f32 v3, v3, s0
	v_lshl_add_u64 v[4:5], v[30:31], 1, s[8:9]
	global_store_short v[4:5], v3, off sc1
	v_add_u32_e32 v4, v71, v16
	s_waitcnt vmcnt(18)
	v_fmac_f32_e32 v23, v6, v102
	v_ashrrev_i32_e32 v5, 31, v4
	v_mul_f32_e32 v3, v32, v23
	v_cvt_pk_bf16_f32 v3, v3, s0
	v_lshl_add_u64 v[4:5], v[4:5], 1, s[8:9]
	global_store_short v[4:5], v3, off sc1
	v_add_u32_e32 v4, v180, v16
	s_waitcnt vmcnt(17)
	v_fmac_f32_e32 v22, v7, v102
	v_ashrrev_i32_e32 v5, 31, v4
	v_mul_f32_e32 v3, v32, v22
	v_cvt_pk_bf16_f32 v3, v3, s0
	v_lshl_add_u64 v[4:5], v[4:5], 1, s[8:9]
	global_store_short v[4:5], v3, off sc1
	v_add_u32_e32 v4, v182, v16
	v_fmac_f32_e32 v21, v8, v102
	v_ashrrev_i32_e32 v5, 31, v4
	v_mul_f32_e32 v3, v32, v21
	v_cvt_pk_bf16_f32 v3, v3, s0
	v_lshl_add_u64 v[4:5], v[4:5], 1, s[8:9]
	global_store_short v[4:5], v3, off sc1
	v_add_u32_e32 v4, v185, v16
	v_ashrrev_i32_e32 v5, 31, v4
	v_mul_f32_e32 v3, v32, v20
	v_cvt_pk_bf16_f32 v3, v3, s0
	v_lshl_add_u64 v[4:5], v[4:5], 1, s[8:9]
	global_store_short v[4:5], v3, off sc1
	v_add_u32_e32 v4, v187, v16
	s_waitcnt vmcnt(18)
	v_fmac_f32_e32 v19, v10, v102
	v_ashrrev_i32_e32 v5, 31, v4
	v_mul_f32_e32 v3, v32, v19
	v_cvt_pk_bf16_f32 v3, v3, s0
	v_lshl_add_u64 v[4:5], v[4:5], 1, s[8:9]
	global_store_short v[4:5], v3, off sc1
	v_add_u32_e32 v4, v189, v16
	s_waitcnt vmcnt(18)
	v_fmac_f32_e32 v18, v11, v102
	v_ashrrev_i32_e32 v5, 31, v4
	v_mul_f32_e32 v3, v32, v18
	v_cvt_pk_bf16_f32 v3, v3, s0
	v_lshl_add_u64 v[4:5], v[4:5], 1, s[8:9]
	global_store_short v[4:5], v3, off sc1
	v_add_u32_e32 v4, v190, v16
	s_waitcnt vmcnt(17)
	v_fmac_f32_e32 v17, v12, v102
	v_ashrrev_i32_e32 v5, 31, v4
	v_mul_f32_e32 v3, v32, v17
	v_cvt_pk_bf16_f32 v3, v3, s0
	v_lshl_add_u64 v[4:5], v[4:5], 1, s[8:9]
	global_store_short v[4:5], v3, off sc1
	v_add_u32_e32 v4, v191, v16
	s_waitcnt vmcnt(16)
	v_fmac_f32_e32 v2, v13, v102
	v_ashrrev_i32_e32 v5, 31, v4
	v_mul_f32_e32 v3, v32, v2
	v_cvt_pk_bf16_f32 v3, v3, s0
	v_lshl_add_u64 v[4:5], v[4:5], 1, s[8:9]
	global_store_short v[4:5], v3, off sc1
	v_add_u32_e32 v4, v192, v16
	v_ashrrev_i32_e32 v5, 31, v4
	v_lshl_add_u64 v[4:5], v[4:5], 1, s[8:9]
	v_xor_b32_e32 v13, 16, v164
	v_add_u32_e32 v10, v193, v16
	v_ashrrev_i32_e32 v11, 31, v10
	v_lshl_add_u64 v[10:11], v[10:11], 1, s[8:9]
	v_ashrrev_i32_e32 v71, 31, v70
	global_store_dword v[82:83], v26, off offset:384 sc1
	global_store_dword v[78:79], v25, off offset:384 sc1
	global_store_dword v[72:73], v24, off offset:384 sc1
	global_store_dword v[74:75], v23, off offset:384 sc1
	s_waitcnt vmcnt(15)
	v_fmac_f32_e32 v1, v14, v102
	v_mul_f32_e32 v3, v32, v1
	v_cvt_pk_bf16_f32 v3, v3, s0
	global_store_short v[4:5], v3, off sc1
	v_and_b32_e32 v4, 64, v164
	v_xor_b32_e32 v3, 1, v164
	v_add_u32_e32 v7, 64, v4
	v_cmp_lt_i32_e32 vcc, v3, v7
	v_xor_b32_e32 v4, 2, v164
	s_waitcnt vmcnt(14)
	v_fmac_f32_e32 v0, v15, v102
	v_cndmask_b32_e32 v3, v164, v3, vcc
	v_lshlrev_b32_e32 v3, 2, v3
	s_nop 1
	v_mov_b32_dpp v5, v106 quad_perm:[1,0,3,2] row_mask:0xf bank_mask:0xf
	v_cmp_lt_i32_e32 vcc, v4, v7
	v_mul_f32_e32 v12, v32, v0
	v_cvt_pk_bf16_f32 v12, v12, s0
	v_cndmask_b32_e32 v4, v164, v4, vcc
	v_lshlrev_b32_e32 v4, 2, v4
	s_waitcnt lgkmcnt(0)
	v_add_f32_e32 v6, v106, v5
	s_nop 1
	v_mov_b32_dpp v8, v6 quad_perm:[2,3,0,1] row_mask:0xf bank_mask:0xf
	v_xor_b32_e32 v5, 4, v164
	v_cmp_lt_i32_e32 vcc, v5, v7
	global_store_dword v[76:77], v22, off offset:384 sc1
	global_store_dword v[80:81], v21, off offset:384 sc1
	v_cndmask_b32_e32 v5, v164, v5, vcc
	v_lshlrev_b32_e32 v5, 2, v5
	s_waitcnt lgkmcnt(0)
	v_add_f32_e32 v8, v6, v8
	s_nop 1
	v_mov_b32_dpp v9, v8 row_half_mirror row_mask:0xf bank_mask:0xf
	v_xor_b32_e32 v6, 8, v164
	v_cmp_lt_i32_e32 vcc, v6, v7
	global_store_dword v[90:91], v19, off offset:384 sc1
	global_store_dword v[92:93], v18, off offset:384 sc1
	v_cndmask_b32_e32 v6, v164, v6, vcc
	v_lshlrev_b32_e32 v6, 2, v6
	s_waitcnt lgkmcnt(0)
	v_add_f32_e32 v8, v8, v9
	s_nop 1
	v_mov_b32_dpp v9, v8 row_mirror row_mask:0xf bank_mask:0xf
	v_cmp_lt_i32_e32 vcc, v13, v7
	global_store_dword v[94:95], v17, off offset:384 sc1
	global_store_dword v[96:97], v2, off offset:384 sc1
	v_cndmask_b32_e32 v7, v164, v13, vcc
	v_lshlrev_b32_e32 v7, 2, v7
	s_waitcnt lgkmcnt(0)
	v_add_f32_e32 v8, v8, v9
	ds_bpermute_b32 v9, v7, v8
	global_store_dword v[98:99], v1, off offset:384 sc1
	global_store_dword v[100:101], v0, off offset:384 sc1
	global_store_short v[10:11], v12, off sc1
	s_and_saveexec_b64 s[60:61], s[0:1]
	s_cbranch_execz .LBB0_1052
	s_waitcnt lgkmcnt(0)
	v_add_f32_e32 v10, v8, v9
	v_lshl_add_u64 v[8:9], v[70:71], 2, s[58:59]
	global_store_dword v[8:9], v10, off sc1
.LBB0_1052:
	s_or_b64 exec, exec, s[60:61]
	v_mul_f32_e32 v8, v63, v63
	v_fmac_f32_e32 v8, v178, v178
	v_fmac_f32_e32 v8, v45, v45
	v_fmac_f32_e32 v8, v28, v28
	s_waitcnt lgkmcnt(0)
	s_nop 1
	v_mov_b32_dpp v9, v8 quad_perm:[1,0,3,2] row_mask:0xf bank_mask:0xf
	s_waitcnt lgkmcnt(0)
	v_add_f32_e32 v8, v8, v9
	s_nop 1
	v_mov_b32_dpp v9, v8 quad_perm:[2,3,0,1] row_mask:0xf bank_mask:0xf
	s_waitcnt lgkmcnt(0)
	v_add_f32_e32 v8, v8, v9
	s_nop 1
	v_mov_b32_dpp v9, v8 row_half_mirror row_mask:0xf bank_mask:0xf
	s_waitcnt lgkmcnt(0)
	v_add_f32_e32 v8, v8, v9
	s_nop 1
	v_mov_b32_dpp v9, v8 row_mirror row_mask:0xf bank_mask:0xf
	s_waitcnt lgkmcnt(0)
	v_add_f32_e32 v8, v8, v9
	ds_bpermute_b32 v9, v7, v8
	s_and_saveexec_b64 s[60:61], s[0:1]
	s_cbranch_execz .LBB0_1054
	s_waitcnt lgkmcnt(0)
	v_add_f32_e32 v10, v8, v9
	v_lshl_add_u64 v[8:9], v[70:71], 2, s[58:59]
	global_store_dword v[8:9], v10, off offset:4 sc1
.LBB0_1054:
	s_or_b64 exec, exec, s[60:61]
	v_mul_f32_e32 v8, v62, v62
	v_fmac_f32_e32 v8, v177, v177
	v_fmac_f32_e32 v8, v47, v47
	v_fmac_f32_e32 v8, v27, v27
	s_waitcnt lgkmcnt(0)
	s_nop 1
	v_mov_b32_dpp v9, v8 quad_perm:[1,0,3,2] row_mask:0xf bank_mask:0xf
	s_waitcnt lgkmcnt(0)
	v_add_f32_e32 v8, v8, v9
	s_nop 1
	v_mov_b32_dpp v9, v8 quad_perm:[2,3,0,1] row_mask:0xf bank_mask:0xf
	s_waitcnt lgkmcnt(0)
	v_add_f32_e32 v8, v8, v9
	s_nop 1
	v_mov_b32_dpp v9, v8 row_half_mirror row_mask:0xf bank_mask:0xf
	s_waitcnt lgkmcnt(0)
	v_add_f32_e32 v8, v8, v9
	s_nop 1
	v_mov_b32_dpp v9, v8 row_mirror row_mask:0xf bank_mask:0xf
	s_waitcnt lgkmcnt(0)
	v_add_f32_e32 v8, v8, v9
	ds_bpermute_b32 v9, v7, v8
	s_and_saveexec_b64 s[60:61], s[0:1]
	s_cbranch_execz .LBB0_1056
	s_waitcnt lgkmcnt(0)
	v_add_f32_e32 v10, v8, v9
	v_lshl_add_u64 v[8:9], v[70:71], 2, s[58:59]
	global_store_dword v[8:9], v10, off offset:8 sc1
.LBB0_1056:
	s_or_b64 exec, exec, s[60:61]
	v_mul_f32_e32 v8, v61, v61
	v_fmac_f32_e32 v8, v176, v176
	v_fmac_f32_e32 v8, v46, v46
	v_fmac_f32_e32 v8, v26, v26
	s_waitcnt lgkmcnt(0)
	s_nop 1
	v_mov_b32_dpp v9, v8 quad_perm:[1,0,3,2] row_mask:0xf bank_mask:0xf
	s_waitcnt lgkmcnt(0)
	v_add_f32_e32 v8, v8, v9
	s_nop 1
	v_mov_b32_dpp v9, v8 quad_perm:[2,3,0,1] row_mask:0xf bank_mask:0xf
	s_waitcnt lgkmcnt(0)
	v_add_f32_e32 v8, v8, v9
	s_nop 1
	v_mov_b32_dpp v9, v8 row_half_mirror row_mask:0xf bank_mask:0xf
	s_waitcnt lgkmcnt(0)
	v_add_f32_e32 v8, v8, v9
	s_nop 1
	v_mov_b32_dpp v9, v8 row_mirror row_mask:0xf bank_mask:0xf
	s_waitcnt lgkmcnt(0)
	v_add_f32_e32 v8, v8, v9
	ds_bpermute_b32 v9, v7, v8
	s_and_saveexec_b64 s[60:61], s[0:1]
	s_cbranch_execz .LBB0_1058
	s_waitcnt lgkmcnt(0)
	v_add_f32_e32 v10, v8, v9
	v_lshl_add_u64 v[8:9], v[70:71], 2, s[58:59]
	global_store_dword v[8:9], v10, off offset:12 sc1
.LBB0_1058:
	s_or_b64 exec, exec, s[60:61]
	v_mul_f32_e32 v8, v60, v60
	v_fmac_f32_e32 v8, v175, v175
	v_fmac_f32_e32 v8, v44, v44
	v_fmac_f32_e32 v8, v25, v25
	s_waitcnt lgkmcnt(0)
	s_nop 1
	v_mov_b32_dpp v9, v8 quad_perm:[1,0,3,2] row_mask:0xf bank_mask:0xf
	s_waitcnt lgkmcnt(0)
	v_add_f32_e32 v8, v8, v9
	s_nop 1
	v_mov_b32_dpp v9, v8 quad_perm:[2,3,0,1] row_mask:0xf bank_mask:0xf
	s_waitcnt lgkmcnt(0)
	v_add_f32_e32 v8, v8, v9
	s_nop 1
	v_mov_b32_dpp v9, v8 row_half_mirror row_mask:0xf bank_mask:0xf
	s_waitcnt lgkmcnt(0)
	v_add_f32_e32 v8, v8, v9
	s_nop 1
	v_mov_b32_dpp v9, v8 row_mirror row_mask:0xf bank_mask:0xf
	s_waitcnt lgkmcnt(0)
	v_add_f32_e32 v8, v8, v9
	ds_bpermute_b32 v9, v7, v8
	s_and_saveexec_b64 s[60:61], s[0:1]
	s_cbranch_execz .LBB0_1060
	s_waitcnt lgkmcnt(0)
	v_add_f32_e32 v10, v8, v9
	v_lshl_add_u64 v[8:9], v[70:71], 2, s[58:59]
	global_store_dword v[8:9], v10, off offset:32 sc1
.LBB0_1060:
	s_or_b64 exec, exec, s[60:61]
	v_mul_f32_e32 v8, v59, v59
	v_fmac_f32_e32 v8, v174, v174
	v_fmac_f32_e32 v8, v43, v43
	v_fmac_f32_e32 v8, v24, v24
	s_waitcnt lgkmcnt(0)
	s_nop 1
	v_mov_b32_dpp v9, v8 quad_perm:[1,0,3,2] row_mask:0xf bank_mask:0xf
	s_waitcnt lgkmcnt(0)
	v_add_f32_e32 v8, v8, v9
	s_nop 1
	v_mov_b32_dpp v9, v8 quad_perm:[2,3,0,1] row_mask:0xf bank_mask:0xf
	s_waitcnt lgkmcnt(0)
	v_add_f32_e32 v8, v8, v9
	s_nop 1
	v_mov_b32_dpp v9, v8 row_half_mirror row_mask:0xf bank_mask:0xf
	s_waitcnt lgkmcnt(0)
	v_add_f32_e32 v8, v8, v9
	s_nop 1
	v_mov_b32_dpp v9, v8 row_mirror row_mask:0xf bank_mask:0xf
	s_waitcnt lgkmcnt(0)
	v_add_f32_e32 v8, v8, v9
	ds_bpermute_b32 v9, v7, v8
	s_and_saveexec_b64 s[60:61], s[0:1]
	s_cbranch_execz .LBB0_1062
	s_waitcnt lgkmcnt(0)
	v_add_f32_e32 v10, v8, v9
	v_lshl_add_u64 v[8:9], v[70:71], 2, s[58:59]
	global_store_dword v[8:9], v10, off offset:36 sc1
.LBB0_1062:
	s_or_b64 exec, exec, s[60:61]
	v_mul_f32_e32 v8, v58, v58
	v_fmac_f32_e32 v8, v173, v173
	v_fmac_f32_e32 v8, v42, v42
	v_fmac_f32_e32 v8, v23, v23
	s_waitcnt lgkmcnt(0)
	s_nop 1
	v_mov_b32_dpp v9, v8 quad_perm:[1,0,3,2] row_mask:0xf bank_mask:0xf
	s_waitcnt lgkmcnt(0)
	v_add_f32_e32 v8, v8, v9
	s_nop 1
	v_mov_b32_dpp v9, v8 quad_perm:[2,3,0,1] row_mask:0xf bank_mask:0xf
	s_waitcnt lgkmcnt(0)
	v_add_f32_e32 v8, v8, v9
	s_nop 1
	v_mov_b32_dpp v9, v8 row_half_mirror row_mask:0xf bank_mask:0xf
	s_waitcnt lgkmcnt(0)
	v_add_f32_e32 v8, v8, v9
	s_nop 1
	v_mov_b32_dpp v9, v8 row_mirror row_mask:0xf bank_mask:0xf
	s_waitcnt lgkmcnt(0)
	v_add_f32_e32 v8, v8, v9
	ds_bpermute_b32 v9, v7, v8
	s_and_saveexec_b64 s[60:61], s[0:1]
	s_cbranch_execz .LBB0_1064
	s_waitcnt lgkmcnt(0)
	v_add_f32_e32 v10, v8, v9
	v_lshl_add_u64 v[8:9], v[70:71], 2, s[58:59]
	global_store_dword v[8:9], v10, off offset:40 sc1
.LBB0_1064:
	s_or_b64 exec, exec, s[60:61]
	v_mul_f32_e32 v8, v57, v57
	v_fmac_f32_e32 v8, v172, v172
	v_fmac_f32_e32 v8, v41, v41
	v_fmac_f32_e32 v8, v22, v22
	s_waitcnt lgkmcnt(0)
	s_nop 1
	v_mov_b32_dpp v9, v8 quad_perm:[1,0,3,2] row_mask:0xf bank_mask:0xf
	s_waitcnt lgkmcnt(0)
	v_add_f32_e32 v8, v8, v9
	s_nop 1
	v_mov_b32_dpp v9, v8 quad_perm:[2,3,0,1] row_mask:0xf bank_mask:0xf
	s_waitcnt lgkmcnt(0)
	v_add_f32_e32 v8, v8, v9
	s_nop 1
	v_mov_b32_dpp v9, v8 row_half_mirror row_mask:0xf bank_mask:0xf
	s_waitcnt lgkmcnt(0)
	v_add_f32_e32 v8, v8, v9
	s_nop 1
	v_mov_b32_dpp v9, v8 row_mirror row_mask:0xf bank_mask:0xf
	s_waitcnt lgkmcnt(0)
	v_add_f32_e32 v8, v8, v9
	ds_bpermute_b32 v9, v7, v8
	s_and_saveexec_b64 s[60:61], s[0:1]
	s_cbranch_execz .LBB0_1066
	s_waitcnt lgkmcnt(0)
	v_add_f32_e32 v10, v8, v9
	v_lshl_add_u64 v[8:9], v[70:71], 2, s[58:59]
	global_store_dword v[8:9], v10, off offset:44 sc1
.LBB0_1066:
	s_or_b64 exec, exec, s[60:61]
	v_mul_f32_e32 v8, v56, v56
	v_fmac_f32_e32 v8, v171, v171
	v_fmac_f32_e32 v8, v40, v40
	v_fmac_f32_e32 v8, v21, v21
	s_waitcnt lgkmcnt(0)
	s_nop 1
	v_mov_b32_dpp v9, v8 quad_perm:[1,0,3,2] row_mask:0xf bank_mask:0xf
	s_waitcnt lgkmcnt(0)
	v_add_f32_e32 v8, v8, v9
	s_nop 1
	v_mov_b32_dpp v9, v8 quad_perm:[2,3,0,1] row_mask:0xf bank_mask:0xf
	s_waitcnt lgkmcnt(0)
	v_add_f32_e32 v8, v8, v9
	s_nop 1
	v_mov_b32_dpp v9, v8 row_half_mirror row_mask:0xf bank_mask:0xf
	s_waitcnt lgkmcnt(0)
	v_add_f32_e32 v8, v8, v9
	s_nop 1
	v_mov_b32_dpp v9, v8 row_mirror row_mask:0xf bank_mask:0xf
	s_waitcnt lgkmcnt(0)
	v_add_f32_e32 v8, v8, v9
	ds_bpermute_b32 v9, v7, v8
	s_and_saveexec_b64 s[60:61], s[0:1]
	s_cbranch_execz .LBB0_1068
	s_waitcnt lgkmcnt(0)
	v_add_f32_e32 v10, v8, v9
	v_lshl_add_u64 v[8:9], v[70:71], 2, s[58:59]
	global_store_dword v[8:9], v10, off offset:64 sc1
.LBB0_1068:
	s_or_b64 exec, exec, s[60:61]
	v_mul_f32_e32 v8, v55, v55
	v_fmac_f32_e32 v8, v170, v170
	v_fmac_f32_e32 v8, v39, v39
	v_fmac_f32_e32 v8, v20, v20
	s_waitcnt lgkmcnt(0)
	s_nop 1
	v_mov_b32_dpp v9, v8 quad_perm:[1,0,3,2] row_mask:0xf bank_mask:0xf
	s_waitcnt lgkmcnt(0)
	v_add_f32_e32 v8, v8, v9
	s_nop 1
	v_mov_b32_dpp v9, v8 quad_perm:[2,3,0,1] row_mask:0xf bank_mask:0xf
	s_waitcnt lgkmcnt(0)
	v_add_f32_e32 v8, v8, v9
	s_nop 1
	v_mov_b32_dpp v9, v8 row_half_mirror row_mask:0xf bank_mask:0xf
	s_waitcnt lgkmcnt(0)
	v_add_f32_e32 v8, v8, v9
	s_nop 1
	v_mov_b32_dpp v9, v8 row_mirror row_mask:0xf bank_mask:0xf
	s_waitcnt lgkmcnt(0)
	v_add_f32_e32 v8, v8, v9
	ds_bpermute_b32 v9, v7, v8
	s_and_saveexec_b64 s[60:61], s[0:1]
	s_cbranch_execz .LBB0_1070
	s_waitcnt lgkmcnt(0)
	v_add_f32_e32 v10, v8, v9
	v_lshl_add_u64 v[8:9], v[70:71], 2, s[58:59]
	global_store_dword v[8:9], v10, off offset:68 sc1
.LBB0_1070:
	s_or_b64 exec, exec, s[60:61]
	v_mul_f32_e32 v8, v54, v54
	v_fmac_f32_e32 v8, v168, v168
	v_fmac_f32_e32 v8, v38, v38
	v_fmac_f32_e32 v8, v19, v19
	s_waitcnt lgkmcnt(0)
	s_nop 1
	v_mov_b32_dpp v9, v8 quad_perm:[1,0,3,2] row_mask:0xf bank_mask:0xf
	s_waitcnt lgkmcnt(0)
	v_add_f32_e32 v8, v8, v9
	s_nop 1
	v_mov_b32_dpp v9, v8 quad_perm:[2,3,0,1] row_mask:0xf bank_mask:0xf
	s_waitcnt lgkmcnt(0)
	v_add_f32_e32 v8, v8, v9
	s_nop 1
	v_mov_b32_dpp v9, v8 row_half_mirror row_mask:0xf bank_mask:0xf
	s_waitcnt lgkmcnt(0)
	v_add_f32_e32 v8, v8, v9
	s_nop 1
	v_mov_b32_dpp v9, v8 row_mirror row_mask:0xf bank_mask:0xf
	s_waitcnt lgkmcnt(0)
	v_add_f32_e32 v8, v8, v9
	ds_bpermute_b32 v9, v7, v8
	s_and_saveexec_b64 s[60:61], s[0:1]
	s_cbranch_execz .LBB0_1072
	s_waitcnt lgkmcnt(0)
	v_add_f32_e32 v10, v8, v9
	v_lshl_add_u64 v[8:9], v[70:71], 2, s[58:59]
	global_store_dword v[8:9], v10, off offset:72 sc1
.LBB0_1072:
	s_or_b64 exec, exec, s[60:61]
	v_mul_f32_e32 v8, v53, v53
	v_fmac_f32_e32 v8, v169, v169
	v_fmac_f32_e32 v8, v37, v37
	v_fmac_f32_e32 v8, v18, v18
	s_waitcnt lgkmcnt(0)
	s_nop 1
	v_mov_b32_dpp v9, v8 quad_perm:[1,0,3,2] row_mask:0xf bank_mask:0xf
	s_waitcnt lgkmcnt(0)
	v_add_f32_e32 v8, v8, v9
	s_nop 1
	v_mov_b32_dpp v9, v8 quad_perm:[2,3,0,1] row_mask:0xf bank_mask:0xf
	s_waitcnt lgkmcnt(0)
	v_add_f32_e32 v8, v8, v9
	s_nop 1
	v_mov_b32_dpp v9, v8 row_half_mirror row_mask:0xf bank_mask:0xf
	s_waitcnt lgkmcnt(0)
	v_add_f32_e32 v8, v8, v9
	s_nop 1
	v_mov_b32_dpp v9, v8 row_mirror row_mask:0xf bank_mask:0xf
	s_waitcnt lgkmcnt(0)
	v_add_f32_e32 v8, v8, v9
	ds_bpermute_b32 v9, v7, v8
	s_and_saveexec_b64 s[60:61], s[0:1]
	s_cbranch_execz .LBB0_1074
	s_waitcnt lgkmcnt(0)
	v_add_f32_e32 v10, v8, v9
	v_lshl_add_u64 v[8:9], v[70:71], 2, s[58:59]
	global_store_dword v[8:9], v10, off offset:76 sc1
.LBB0_1074:
	s_or_b64 exec, exec, s[60:61]
	v_mul_f32_e32 v8, v52, v52
	v_fmac_f32_e32 v8, v167, v167
	v_fmac_f32_e32 v8, v36, v36
	v_fmac_f32_e32 v8, v17, v17
	s_waitcnt lgkmcnt(0)
	s_nop 1
	v_mov_b32_dpp v9, v8 quad_perm:[1,0,3,2] row_mask:0xf bank_mask:0xf
	s_waitcnt lgkmcnt(0)
	v_add_f32_e32 v8, v8, v9
	s_nop 1
	v_mov_b32_dpp v9, v8 quad_perm:[2,3,0,1] row_mask:0xf bank_mask:0xf
	s_waitcnt lgkmcnt(0)
	v_add_f32_e32 v8, v8, v9
	s_nop 1
	v_mov_b32_dpp v9, v8 row_half_mirror row_mask:0xf bank_mask:0xf
	s_waitcnt lgkmcnt(0)
	v_add_f32_e32 v8, v8, v9
	s_nop 1
	v_mov_b32_dpp v9, v8 row_mirror row_mask:0xf bank_mask:0xf
	s_waitcnt lgkmcnt(0)
	v_add_f32_e32 v8, v8, v9
	ds_bpermute_b32 v9, v7, v8
	s_and_saveexec_b64 s[60:61], s[0:1]
	s_cbranch_execz .LBB0_1076
	s_waitcnt lgkmcnt(0)
	v_add_f32_e32 v10, v8, v9
	v_lshl_add_u64 v[8:9], v[70:71], 2, s[58:59]
	global_store_dword v[8:9], v10, off offset:96 sc1
.LBB0_1076:
	s_or_b64 exec, exec, s[60:61]
	v_mul_f32_e32 v8, v51, v51
	v_fmac_f32_e32 v8, v166, v166
	v_fmac_f32_e32 v8, v35, v35
	v_fmac_f32_e32 v8, v2, v2
	s_nop 1
	v_mov_b32_dpp v2, v8 quad_perm:[1,0,3,2] row_mask:0xf bank_mask:0xf
	s_waitcnt lgkmcnt(0)
	v_add_f32_e32 v2, v8, v2
	s_nop 1
	v_mov_b32_dpp v8, v2 quad_perm:[2,3,0,1] row_mask:0xf bank_mask:0xf
	s_waitcnt lgkmcnt(0)
	v_add_f32_e32 v2, v2, v8
	s_nop 1
	v_mov_b32_dpp v8, v2 row_half_mirror row_mask:0xf bank_mask:0xf
	s_waitcnt lgkmcnt(0)
	v_add_f32_e32 v2, v2, v8
	s_nop 1
	v_mov_b32_dpp v8, v2 row_mirror row_mask:0xf bank_mask:0xf
	s_waitcnt lgkmcnt(0)
	v_add_f32_e32 v2, v2, v8
	ds_bpermute_b32 v8, v7, v2
	s_and_saveexec_b64 s[60:61], s[0:1]
	s_cbranch_execz .LBB0_1078
	s_waitcnt lgkmcnt(0)
	v_add_f32_e32 v2, v2, v8
	v_lshl_add_u64 v[8:9], v[70:71], 2, s[58:59]
	global_store_dword v[8:9], v2, off offset:100 sc1
.LBB0_1078:
	s_or_b64 exec, exec, s[60:61]
	v_mul_f32_e32 v2, v50, v50
	v_fmac_f32_e32 v2, v165, v165
	v_fmac_f32_e32 v2, v34, v34
	v_fmac_f32_e32 v2, v1, v1
	s_nop 1
	v_mov_b32_dpp v1, v2 quad_perm:[1,0,3,2] row_mask:0xf bank_mask:0xf
	s_waitcnt lgkmcnt(0)
	v_add_f32_e32 v1, v2, v1
	s_nop 1
	v_mov_b32_dpp v2, v1 quad_perm:[2,3,0,1] row_mask:0xf bank_mask:0xf
	s_waitcnt lgkmcnt(0)
	v_add_f32_e32 v1, v1, v2
	s_nop 1
	v_mov_b32_dpp v2, v1 row_half_mirror row_mask:0xf bank_mask:0xf
	s_waitcnt lgkmcnt(0)
	v_add_f32_e32 v1, v1, v2
	s_nop 1
	v_mov_b32_dpp v2, v1 row_mirror row_mask:0xf bank_mask:0xf
	s_waitcnt lgkmcnt(0)
	v_add_f32_e32 v1, v1, v2
	ds_bpermute_b32 v2, v7, v1
	s_and_saveexec_b64 s[60:61], s[0:1]
	s_cbranch_execz .LBB0_1080
	s_waitcnt lgkmcnt(0)
	v_add_f32_e32 v1, v1, v2
	v_lshl_add_u64 v[8:9], v[70:71], 2, s[58:59]
	global_store_dword v[8:9], v1, off offset:104 sc1

.LBB0_1122:
	s_add_i32 s58, s67, 0xffffe000
	s_lshr_b32 s58, s58, 12
	s_mulk_i32 s58, 0x1800
	s_addk_i32 s58, 0x1800
	s_cmp_gt_i32 s6, 63
	s_cselect_b32 s62, s58, 0
	s_add_i32 s6, s62, 0x4800
	s_lshl_b64 s[58:59], s[6:7], 2
	s_add_u32 s6, s14, s58
	s_addc_u32 s58, s15, s59
	s_add_u32 s60, s6, 0x5ba5000
	s_addc_u32 s61, s58, 0
	s_add_i32 s6, s62, 0x9000
	s_lshl_b64 s[58:59], s[6:7], 2
	v_mov_b32_e32 v70, s66
	s_add_u32 s6, s14, s58
	ds_read_b64 v[70:71], v70
	s_addc_u32 s69, s15, s59
	s_lshl_b32 s58, s64, 14
	s_add_i32 s58, s58, 0x80000
	s_ashr_i32 s59, s58, 31
	s_lshl_b64 s[58:59], s[58:59], 2
	s_add_u32 s58, s10, s58
	s_waitcnt lgkmcnt(0)
	v_readfirstlane_b32 s63, v70
	s_addc_u32 s59, s11, s59
	v_or_b32_e32 v102, s68, v138
	v_add_u32_e32 v70, s67, v139
	v_readfirstlane_b32 s65, v71
	s_add_u32 s62, s63, 0x2000
	v_ashrrev_i32_e32 v103, 31, v102
	v_lshlrev_b32_e32 v191, 10, v70
	s_addc_u32 s63, s65, 0
	v_lshlrev_b64 v[72:73], 2, v[102:103]
	v_or_b32_e32 v187, 0x400, v191
	v_or_b32_e32 v186, 0x4400, v191
	v_or_b32_e32 v189, 0x4c00, v191
	v_or_b32_e32 v194, 0x6c00, v191
	s_add_u32 s64, s6, 0x5ba1000
	v_lshl_add_u64 v[74:75], s[60:61], 0, v[72:73]
	v_add_u32_e32 v130, v191, v102
	v_add_u32_e32 v132, v187, v102
	v_or_b32_e32 v185, 0x800, v191
	v_or_b32_e32 v184, 0xc00, v191
	v_or_b32_e32 v182, 0x2000, v191
	v_or_b32_e32 v180, 0x2400, v191
	v_or_b32_e32 v71, 0x2800, v191
	v_or_b32_e32 v181, 0x2c00, v191
	v_or_b32_e32 v183, 0x4000, v191
	v_add_u32_e32 v112, v186, v102
	v_or_b32_e32 v188, 0x4800, v191
	v_add_u32_e32 v116, v189, v102
	v_or_b32_e32 v190, 0x6000, v191
	v_or_b32_e32 v192, 0x6400, v191
	v_or_b32_e32 v193, 0x6800, v191
	v_add_u32_e32 v128, v194, v102
	s_addc_u32 s65, s69, 0
	global_load_dword v195, v[74:75], off
	v_lshl_add_u64 v[74:75], s[62:63], 0, v[72:73]
	v_ashrrev_i32_e32 v133, 31, v132
	v_add_u32_e32 v134, v185, v102
	v_add_u32_e32 v136, v184, v102
	v_add_u32_e32 v126, v182, v102
	v_add_u32_e32 v118, v180, v102
	v_add_u32_e32 v110, v71, v102
	v_add_u32_e32 v106, v181, v102
	v_add_u32_e32 v108, v183, v102
	v_ashrrev_i32_e32 v113, 31, v112
	v_add_u32_e32 v114, v188, v102
	v_ashrrev_i32_e32 v117, 31, v116
	v_add_u32_e32 v120, v190, v102
	v_add_u32_e32 v122, v192, v102
	v_add_u32_e32 v124, v193, v102
	v_ashrrev_i32_e32 v129, 31, v128
	v_ashrrev_i32_e32 v131, 31, v130
	v_lshl_add_u64 v[72:73], s[64:65], 0, v[72:73]
	global_load_dword v196, v[74:75], off
	global_load_dword v197, v[72:73], off
	v_lshl_add_u64 v[88:89], v[132:133], 2, s[12:13]
	v_ashrrev_i32_e32 v135, 31, v134
	v_ashrrev_i32_e32 v137, 31, v136
	v_ashrrev_i32_e32 v127, 31, v126
	v_ashrrev_i32_e32 v119, 31, v118
	v_ashrrev_i32_e32 v111, 31, v110
	v_ashrrev_i32_e32 v107, 31, v106
	v_ashrrev_i32_e32 v109, 31, v108
	v_lshl_add_u64 v[86:87], v[112:113], 2, s[12:13]
	v_ashrrev_i32_e32 v115, 31, v114
	v_lshl_add_u64 v[92:93], v[116:117], 2, s[12:13]
	v_ashrrev_i32_e32 v121, 31, v120
	v_ashrrev_i32_e32 v123, 31, v122
	v_ashrrev_i32_e32 v125, 31, v124
	v_lshl_add_u64 v[100:101], v[128:129], 2, s[12:13]
	v_lshl_add_u64 v[104:105], v[130:131], 2, s[12:13]
	v_lshl_add_u64 v[84:85], v[134:135], 2, s[12:13]
	v_lshl_add_u64 v[82:83], v[136:137], 2, s[12:13]
	v_lshl_add_u64 v[78:79], v[126:127], 2, s[12:13]
	v_lshl_add_u64 v[72:73], v[118:119], 2, s[12:13]
	v_lshl_add_u64 v[74:75], v[110:111], 2, s[12:13]
	v_lshl_add_u64 v[76:77], v[106:107], 2, s[12:13]
	v_lshl_add_u64 v[80:81], v[108:109], 2, s[12:13]
	global_load_dword v179, v[88:89], off
	global_load_dword v178, v[84:85], off
	global_load_dword v177, v[82:83], off
	global_load_dword v176, v[78:79], off
	global_load_dword v175, v[72:73], off
	global_load_dword v174, v[74:75], off
	global_load_dword v173, v[76:77], off
	global_load_dword v172, v[80:81], off
	v_lshl_add_u64 v[90:91], v[114:115], 2, s[12:13]
	global_load_dword v171, v[86:87], off
	global_load_dword v169, v[90:91], off
	v_lshl_add_u64 v[94:95], v[120:121], 2, s[12:13]
	v_lshl_add_u64 v[96:97], v[122:123], 2, s[12:13]
	v_lshl_add_u64 v[98:99], v[124:125], 2, s[12:13]
	global_load_dword v170, v[92:93], off
	global_load_dword v168, v[94:95], off
	global_load_dword v167, v[96:97], off
	global_load_dword v166, v[98:99], off
	global_load_dword v103, v[100:101], off
	global_load_dword v198, v[104:105], off
	v_lshl_add_u64 v[110:111], v[110:111], 1, s[8:9]
	v_lshl_add_u64 v[106:107], v[106:107], 1, s[8:9]
	s_waitcnt vmcnt(0)
	v_add_f32_e32 v197, 1.0, v197
	v_mul_f32_e32 v196, v196, v197
	v_fmac_f32_e32 v179, v49, v195
	v_fmac_f32_e32 v178, v50, v195
	v_fmac_f32_e32 v177, v51, v195
	v_fmac_f32_e32 v176, v52, v195
	v_fmac_f32_e32 v175, v53, v195
	v_fmac_f32_e32 v174, v54, v195
	v_fmac_f32_e32 v173, v55, v195
	v_fmac_f32_e32 v172, v56, v195
	v_fmac_f32_e32 v171, v57, v195
	v_fmac_f32_e32 v169, v58, v195
	v_fmac_f32_e32 v170, v59, v195
	v_fmac_f32_e32 v168, v60, v195
	v_fmac_f32_e32 v167, v61, v195
	v_fmac_f32_e32 v166, v62, v195
	v_fmac_f32_e32 v103, v63, v195
	v_fmac_f32_e32 v198, v48, v195
	v_mul_f32_e32 v48, v196, v198
	v_cvt_pk_bf16_f32 v58, v48, s0
	v_or_b32_e32 v48, 32, v102
	v_ashrrev_i32_e32 v49, 31, v48
	v_lshlrev_b64 v[52:53], 2, v[48:49]
	global_store_dword v[88:89], v179, off sc1
	global_store_dword v[84:85], v178, off sc1
	global_store_dword v[82:83], v177, off sc1
	global_store_dword v[78:79], v176, off sc1
	global_store_dword v[72:73], v175, off sc1
	global_store_dword v[74:75], v174, off sc1
	global_store_dword v[76:77], v173, off sc1
	global_store_dword v[80:81], v172, off sc1
	global_store_dword v[86:87], v171, off sc1
	global_store_dword v[90:91], v169, off sc1
	global_store_dword v[92:93], v170, off sc1
	global_store_dword v[94:95], v168, off sc1
	global_store_dword v[96:97], v167, off sc1
	global_store_dword v[98:99], v166, off sc1
	global_store_dword v[100:101], v103, off sc1
	global_store_dword v[104:105], v198, off sc1
	v_lshl_add_u64 v[50:51], v[130:131], 1, s[8:9]
	v_lshl_add_u64 v[56:57], s[64:65], 0, v[52:53]
	global_load_dword v197, v[104:105], off offset:128
	v_lshl_add_u64 v[54:55], s[62:63], 0, v[52:53]
	global_load_dword v130, v[56:57], off
	global_load_dword v131, v[54:55], off
	v_mul_f32_e32 v49, v196, v179
	global_store_short v[50:51], v58, off sc1
	v_lshl_add_u64 v[50:51], s[60:61], 0, v[52:53]
	global_load_dword v195, v[50:51], off
	v_lshl_add_u64 v[50:51], v[132:133], 1, s[8:9]
	v_cvt_pk_bf16_f32 v49, v49, s0
	global_store_short v[50:51], v49, off sc1
	v_mul_f32_e32 v49, v196, v178
	v_lshl_add_u64 v[50:51], v[134:135], 1, s[8:9]
	v_cvt_pk_bf16_f32 v49, v49, s0
	global_store_short v[50:51], v49, off sc1
	v_mul_f32_e32 v49, v196, v177
	v_lshl_add_u64 v[50:51], v[136:137], 1, s[8:9]
	v_cvt_pk_bf16_f32 v49, v49, s0
	global_store_short v[50:51], v49, off sc1
	v_mul_f32_e32 v49, v196, v176
	v_lshl_add_u64 v[50:51], v[126:127], 1, s[8:9]
	v_cvt_pk_bf16_f32 v49, v49, s0
	global_store_short v[50:51], v49, off sc1
	v_mul_f32_e32 v49, v196, v175
	v_lshl_add_u64 v[50:51], v[118:119], 1, s[8:9]
	v_cvt_pk_bf16_f32 v49, v49, s0
	global_load_dword v62, v[84:85], off offset:128
	global_load_dword v60, v[78:79], off offset:128
	global_load_dword v59, v[72:73], off offset:128
	global_load_dword v58, v[74:75], off offset:128
	global_load_dword v56, v[80:81], off offset:128
	global_load_dword v57, v[76:77], off offset:128
	global_load_dword v55, v[86:87], off offset:128
	global_load_dword v61, v[82:83], off offset:128
	global_load_dword v54, v[90:91], off offset:128
	global_load_dword v53, v[92:93], off offset:128
	global_load_dword v52, v[94:95], off offset:128
	v_mul_f32_e32 v63, v196, v174
	global_store_short v[50:51], v49, off sc1
	global_load_dword v51, v[96:97], off offset:128
	v_cvt_pk_bf16_f32 v63, v63, s0
	global_load_dword v50, v[98:99], off offset:128
	global_load_dword v49, v[100:101], off offset:128
	s_waitcnt vmcnt(19)
	v_fmac_f32_e32 v197, v32, v195
	global_store_short v[110:111], v63, off sc1
	global_load_dword v63, v[88:89], off offset:128
	v_mul_f32_e32 v110, v196, v173
	v_cvt_pk_bf16_f32 v110, v110, s0
	global_store_short v[106:107], v110, off sc1
	v_lshl_add_u64 v[106:107], v[108:109], 1, s[8:9]
	v_mul_f32_e32 v108, v196, v172
	v_cvt_pk_bf16_f32 v108, v108, s0
	global_store_short v[106:107], v108, off sc1
	v_mul_f32_e32 v108, v196, v171
	v_lshl_add_u64 v[106:107], v[112:113], 1, s[8:9]
	v_cvt_pk_bf16_f32 v108, v108, s0
	global_store_short v[106:107], v108, off sc1
	v_mul_f32_e32 v108, v196, v169
	v_lshl_add_u64 v[106:107], v[114:115], 1, s[8:9]
	v_cvt_pk_bf16_f32 v108, v108, s0
	global_store_short v[106:107], v108, off sc1
	v_mul_f32_e32 v108, v196, v170
	v_lshl_add_u64 v[106:107], v[116:117], 1, s[8:9]
	v_cvt_pk_bf16_f32 v108, v108, s0
	global_store_short v[106:107], v108, off sc1
	v_mul_f32_e32 v108, v196, v168
	v_lshl_add_u64 v[106:107], v[120:121], 1, s[8:9]
	v_cvt_pk_bf16_f32 v108, v108, s0
	global_store_short v[106:107], v108, off sc1
	v_mul_f32_e32 v108, v196, v167
	v_lshl_add_u64 v[106:107], v[122:123], 1, s[8:9]
	v_cvt_pk_bf16_f32 v108, v108, s0
	global_store_short v[106:107], v108, off sc1
	v_mul_f32_e32 v108, v196, v166
	v_lshl_add_u64 v[106:107], v[124:125], 1, s[8:9]
	v_cvt_pk_bf16_f32 v108, v108, s0
	global_store_short v[106:107], v108, off sc1
	v_mul_f32_e32 v108, v196, v103
	v_lshl_add_u64 v[106:107], v[128:129], 1, s[8:9]
	v_cvt_pk_bf16_f32 v108, v108, s0
	global_store_short v[106:107], v108, off sc1
	v_add_f32_e32 v106, 1.0, v130
	v_mul_f32_e32 v107, v131, v106
	v_add_u32_e32 v108, v191, v48
	v_ashrrev_i32_e32 v109, 31, v108
	v_mul_f32_e32 v32, v107, v197
	s_waitcnt vmcnt(25)
	v_fmac_f32_e32 v62, v34, v195
	s_waitcnt vmcnt(18)
	v_fmac_f32_e32 v61, v35, v195
	v_fmac_f32_e32 v60, v36, v195
	v_fmac_f32_e32 v59, v37, v195
	v_fmac_f32_e32 v58, v38, v195
	v_fmac_f32_e32 v57, v39, v195
	v_fmac_f32_e32 v56, v40, v195
	v_fmac_f32_e32 v55, v41, v195
	s_waitcnt vmcnt(17)
	v_fmac_f32_e32 v54, v42, v195
	s_waitcnt vmcnt(16)
	v_fmac_f32_e32 v53, v43, v195
	s_waitcnt vmcnt(15)
	v_fmac_f32_e32 v52, v44, v195
	s_waitcnt vmcnt(13)
	v_fmac_f32_e32 v51, v45, v195
	s_waitcnt vmcnt(12)
	v_fmac_f32_e32 v50, v46, v195
	s_waitcnt vmcnt(11)
	v_fmac_f32_e32 v49, v47, v195
	global_store_dword v[104:105], v197, off offset:128 sc1
	v_lshl_add_u64 v[108:109], v[108:109], 1, s[8:9]
	v_cvt_pk_bf16_f32 v32, v32, s0
	global_store_dword v[84:85], v62, off offset:128 sc1
	global_store_dword v[82:83], v61, off offset:128 sc1
	global_store_dword v[78:79], v60, off offset:128 sc1
	global_store_dword v[72:73], v59, off offset:128 sc1
	global_store_dword v[74:75], v58, off offset:128 sc1
	global_store_dword v[76:77], v57, off offset:128 sc1
	global_store_dword v[80:81], v56, off offset:128 sc1
	global_store_dword v[86:87], v55, off offset:128 sc1
	global_store_dword v[90:91], v54, off offset:128 sc1
	global_store_dword v[92:93], v53, off offset:128 sc1
	global_store_dword v[94:95], v52, off offset:128 sc1
	global_store_dword v[96:97], v51, off offset:128 sc1
	global_store_dword v[98:99], v50, off offset:128 sc1
	global_store_dword v[100:101], v49, off offset:128 sc1
	global_store_short v[108:109], v32, off sc1
	v_add_u32_e32 v108, v187, v48
	global_load_dword v45, v[88:89], off offset:256
	v_ashrrev_i32_e32 v109, 31, v108
	v_mul_f32_e32 v113, v107, v56
	v_cvt_pk_bf16_f32 v113, v113, s0
	v_mul_f32_e32 v106, v197, v197
	v_fmac_f32_e32 v106, v198, v198
	s_waitcnt vmcnt(26)
	v_fmac_f32_e32 v63, v33, v195
	v_mul_f32_e32 v34, v107, v63
	v_lshl_add_u64 v[32:33], v[108:109], 1, s[8:9]
	v_cvt_pk_bf16_f32 v34, v34, s0
	global_store_short v[32:33], v34, off sc1
	v_add_u32_e32 v32, v185, v48
	v_ashrrev_i32_e32 v33, 31, v32
	v_mul_f32_e32 v34, v107, v62
	v_lshl_add_u64 v[32:33], v[32:33], 1, s[8:9]
	v_cvt_pk_bf16_f32 v34, v34, s0
	global_store_short v[32:33], v34, off sc1
	v_add_u32_e32 v32, v184, v48
	v_ashrrev_i32_e32 v33, 31, v32
	v_mul_f32_e32 v34, v107, v61
	v_lshl_add_u64 v[32:33], v[32:33], 1, s[8:9]
	v_cvt_pk_bf16_f32 v34, v34, s0
	global_store_short v[32:33], v34, off sc1
	v_add_u32_e32 v32, v182, v48
	v_ashrrev_i32_e32 v33, 31, v32
	v_mul_f32_e32 v34, v107, v60
	v_lshl_add_u64 v[32:33], v[32:33], 1, s[8:9]
	v_cvt_pk_bf16_f32 v34, v34, s0
	global_store_short v[32:33], v34, off sc1
	v_add_u32_e32 v32, v180, v48
	v_ashrrev_i32_e32 v33, 31, v32
	v_lshl_add_u64 v[34:35], v[32:33], 1, s[8:9]
	v_mul_f32_e32 v32, v107, v59
	v_cvt_pk_bf16_f32 v42, v32, s0
	v_or_b32_e32 v32, 64, v102
	v_ashrrev_i32_e32 v33, 31, v32
	v_lshlrev_b64 v[36:37], 2, v[32:33]
	global_store_dword v[88:89], v63, off offset:128 sc1
	v_lshl_add_u64 v[40:41], s[64:65], 0, v[36:37]
	v_lshl_add_u64 v[38:39], s[62:63], 0, v[36:37]
	global_load_dword v110, v[40:41], off
	global_load_dword v111, v[38:39], off
	v_mul_f32_e32 v33, v107, v58
	global_store_short v[34:35], v42, off sc1
	v_lshl_add_u64 v[34:35], s[60:61], 0, v[36:37]
	global_load_dword v112, v[34:35], off
	v_add_u32_e32 v34, v71, v48
	v_ashrrev_i32_e32 v35, 31, v34
	v_lshl_add_u64 v[34:35], v[34:35], 1, s[8:9]
	v_cvt_pk_bf16_f32 v33, v33, s0
	global_store_short v[34:35], v33, off sc1
	v_add_u32_e32 v34, v181, v48
	v_ashrrev_i32_e32 v35, 31, v34
	v_mul_f32_e32 v33, v107, v57
	v_lshl_add_u64 v[34:35], v[34:35], 1, s[8:9]
	v_cvt_pk_bf16_f32 v33, v33, s0
	global_load_dword v38, v[90:91], off offset:256
	global_load_dword v37, v[92:93], off offset:256
	global_load_dword v36, v[94:95], off offset:256
	global_load_dword v114, v[104:105], off offset:256
	global_load_dword v47, v[84:85], off offset:256
	global_load_dword v39, v[86:87], off offset:256
	global_load_dword v46, v[82:83], off offset:256
	global_load_dword v44, v[78:79], off offset:256
	global_load_dword v43, v[72:73], off offset:256
	global_load_dword v42, v[74:75], off offset:256
	global_load_dword v40, v[80:81], off offset:256
	global_load_dword v41, v[76:77], off offset:256
	v_add_u32_e32 v108, v183, v48
	global_store_short v[34:35], v33, off sc1
	global_load_dword v35, v[96:97], off offset:256
	v_ashrrev_i32_e32 v109, 31, v108
	global_load_dword v34, v[98:99], off offset:256
	global_load_dword v33, v[100:101], off offset:256
	v_lshl_add_u64 v[108:109], v[108:109], 1, s[8:9]
	global_store_short v[108:109], v113, off sc1
	v_add_u32_e32 v108, v186, v48
	v_ashrrev_i32_e32 v109, 31, v108
	v_mul_f32_e32 v113, v107, v55
	v_lshl_add_u64 v[108:109], v[108:109], 1, s[8:9]
	v_cvt_pk_bf16_f32 v113, v113, s0
	global_store_short v[108:109], v113, off sc1
	v_add_u32_e32 v108, v188, v48
	v_ashrrev_i32_e32 v109, 31, v108
	v_mul_f32_e32 v113, v107, v54
	v_lshl_add_u64 v[108:109], v[108:109], 1, s[8:9]
	v_cvt_pk_bf16_f32 v113, v113, s0
	global_store_short v[108:109], v113, off sc1
	v_add_u32_e32 v108, v189, v48
	v_ashrrev_i32_e32 v109, 31, v108
	v_mul_f32_e32 v113, v107, v53
	v_lshl_add_u64 v[108:109], v[108:109], 1, s[8:9]
	v_cvt_pk_bf16_f32 v113, v113, s0
	global_store_short v[108:109], v113, off sc1
	v_add_u32_e32 v108, v190, v48
	v_ashrrev_i32_e32 v109, 31, v108
	v_mul_f32_e32 v113, v107, v52
	v_lshl_add_u64 v[108:109], v[108:109], 1, s[8:9]
	v_cvt_pk_bf16_f32 v113, v113, s0
	global_store_short v[108:109], v113, off sc1
	v_add_u32_e32 v108, v192, v48
	v_ashrrev_i32_e32 v109, 31, v108
	v_mul_f32_e32 v113, v107, v51
	v_lshl_add_u64 v[108:109], v[108:109], 1, s[8:9]
	v_cvt_pk_bf16_f32 v113, v113, s0
	global_store_short v[108:109], v113, off sc1
	v_add_u32_e32 v108, v193, v48
	v_ashrrev_i32_e32 v109, 31, v108
	v_mul_f32_e32 v113, v107, v50
	v_lshl_add_u64 v[108:109], v[108:109], 1, s[8:9]
	v_cvt_pk_bf16_f32 v113, v113, s0
	global_store_short v[108:109], v113, off sc1
	v_add_u32_e32 v108, v194, v48
	v_ashrrev_i32_e32 v109, 31, v108
	v_mul_f32_e32 v48, v107, v49
	v_lshl_add_u64 v[108:109], v[108:109], 1, s[8:9]
	v_cvt_pk_bf16_f32 v48, v48, s0
	global_store_short v[108:109], v48, off sc1
	v_add_u32_e32 v108, v191, v32
	v_ashrrev_i32_e32 v109, 31, v108
	s_waitcnt vmcnt(28)
	v_add_f32_e32 v48, 1.0, v110
	s_waitcnt vmcnt(27)
	v_mul_f32_e32 v48, v111, v48
	s_waitcnt vmcnt(25)
	v_fmac_f32_e32 v45, v17, v112
	global_store_dword v[88:89], v45, off offset:256 sc1
	s_waitcnt vmcnt(24)
	v_fmac_f32_e32 v38, v26, v112
	s_waitcnt vmcnt(23)
	v_fmac_f32_e32 v37, v27, v112
	s_waitcnt vmcnt(22)
	v_fmac_f32_e32 v36, v28, v112
	s_waitcnt vmcnt(21)
	v_fmac_f32_e32 v114, v16, v112
	s_waitcnt vmcnt(20)
	v_fmac_f32_e32 v47, v18, v112
	v_mul_f32_e32 v18, v48, v114
	v_lshl_add_u64 v[16:17], v[108:109], 1, s[8:9]
	v_cvt_pk_bf16_f32 v18, v18, s0
	global_store_short v[16:17], v18, off sc1
	v_add_u32_e32 v16, v187, v32
	v_ashrrev_i32_e32 v17, 31, v16
	v_mul_f32_e32 v18, v48, v45
	v_lshl_add_u64 v[16:17], v[16:17], 1, s[8:9]
	v_cvt_pk_bf16_f32 v18, v18, s0
	global_store_short v[16:17], v18, off sc1
	v_add_u32_e32 v16, v185, v32
	v_ashrrev_i32_e32 v17, 31, v16
	v_mul_f32_e32 v18, v48, v47
	v_lshl_add_u64 v[16:17], v[16:17], 1, s[8:9]
	v_cvt_pk_bf16_f32 v18, v18, s0
	s_waitcnt vmcnt(20)
	v_fmac_f32_e32 v46, v19, v112
	global_store_short v[16:17], v18, off sc1
	v_add_u32_e32 v16, v184, v32
	v_ashrrev_i32_e32 v17, 31, v16
	v_mul_f32_e32 v18, v48, v46
	v_lshl_add_u64 v[16:17], v[16:17], 1, s[8:9]
	v_cvt_pk_bf16_f32 v18, v18, s0
	global_store_short v[16:17], v18, off sc1
	v_add_u32_e32 v16, v182, v32
	v_ashrrev_i32_e32 v17, 31, v16
	v_lshl_add_u64 v[18:19], v[16:17], 1, s[8:9]
	v_or_b32_e32 v16, 0x60, v102
	v_ashrrev_i32_e32 v17, 31, v16
	s_waitcnt vmcnt(21)
	v_fmac_f32_e32 v44, v20, v112
	s_waitcnt vmcnt(20)
	v_fmac_f32_e32 v43, v21, v112
	s_waitcnt vmcnt(19)
	v_fmac_f32_e32 v42, v22, v112
	s_waitcnt vmcnt(17)
	v_fmac_f32_e32 v41, v23, v112
	v_fmac_f32_e32 v40, v24, v112
	v_fmac_f32_e32 v39, v25, v112
	s_waitcnt vmcnt(15)
	v_fmac_f32_e32 v35, v29, v112
	s_waitcnt vmcnt(14)
	v_fmac_f32_e32 v34, v30, v112
	s_waitcnt vmcnt(13)
	v_fmac_f32_e32 v33, v31, v112
	v_lshlrev_b64 v[20:21], 2, v[16:17]
	global_store_dword v[84:85], v47, off offset:256 sc1
	global_store_dword v[82:83], v46, off offset:256 sc1
	global_store_dword v[78:79], v44, off offset:256 sc1
	global_store_dword v[72:73], v43, off offset:256 sc1
	global_store_dword v[74:75], v42, off offset:256 sc1
	global_store_dword v[76:77], v41, off offset:256 sc1
	global_store_dword v[80:81], v40, off offset:256 sc1
	global_store_dword v[86:87], v39, off offset:256 sc1
	global_store_dword v[90:91], v38, off offset:256 sc1
	global_store_dword v[92:93], v37, off offset:256 sc1
	global_store_dword v[94:95], v36, off offset:256 sc1
	global_store_dword v[96:97], v35, off offset:256 sc1
	global_store_dword v[98:99], v34, off offset:256 sc1
	global_store_dword v[100:101], v33, off offset:256 sc1
	global_store_dword v[104:105], v114, off offset:256 sc1
	v_mul_f32_e32 v26, v48, v44
	v_lshl_add_u64 v[22:23], s[62:63], 0, v[20:21]
	v_lshl_add_u64 v[24:25], s[64:65], 0, v[20:21]
	global_load_dword v29, v[104:105], off offset:384
	global_load_dword v17, v[24:25], off
	global_load_dword v30, v[22:23], off
	v_cvt_pk_bf16_f32 v22, v26, s0
	global_store_short v[18:19], v22, off sc1
	v_lshl_add_u64 v[18:19], s[60:61], 0, v[20:21]
	global_load_dword v102, v[18:19], off
	v_add_u32_e32 v18, v180, v32
	v_ashrrev_i32_e32 v19, 31, v18
	v_mul_f32_e32 v20, v48, v43
	v_lshl_add_u64 v[18:19], v[18:19], 1, s[8:9]
	v_cvt_pk_bf16_f32 v20, v20, s0
	global_store_short v[18:19], v20, off sc1
	v_add_u32_e32 v18, v71, v32
	v_ashrrev_i32_e32 v19, 31, v18
	v_mul_f32_e32 v20, v48, v42
	v_lshl_add_u64 v[18:19], v[18:19], 1, s[8:9]
	v_cvt_pk_bf16_f32 v20, v20, s0
	global_store_short v[18:19], v20, off sc1
	v_add_u32_e32 v18, v181, v32
	v_ashrrev_i32_e32 v19, 31, v18
	v_mul_f32_e32 v20, v48, v41
	v_lshl_add_u64 v[18:19], v[18:19], 1, s[8:9]
	v_cvt_pk_bf16_f32 v20, v20, s0
	global_store_short v[18:19], v20, off sc1
	v_add_u32_e32 v18, v183, v32
	v_ashrrev_i32_e32 v19, 31, v18
	v_mul_f32_e32 v20, v48, v40
	v_lshl_add_u64 v[18:19], v[18:19], 1, s[8:9]
	v_cvt_pk_bf16_f32 v20, v20, s0
	global_store_short v[18:19], v20, off sc1
	v_add_u32_e32 v18, v186, v32
	v_ashrrev_i32_e32 v19, 31, v18
	v_mul_f32_e32 v20, v48, v39
	v_lshl_add_u64 v[18:19], v[18:19], 1, s[8:9]
	v_cvt_pk_bf16_f32 v20, v20, s0
	global_store_short v[18:19], v20, off sc1
	v_add_u32_e32 v18, v188, v32
	v_ashrrev_i32_e32 v19, 31, v18
	v_mul_f32_e32 v20, v48, v38
	v_lshl_add_u64 v[18:19], v[18:19], 1, s[8:9]
	v_cvt_pk_bf16_f32 v20, v20, s0
	global_store_short v[18:19], v20, off sc1
	v_add_u32_e32 v18, v189, v32
	v_ashrrev_i32_e32 v19, 31, v18
	v_mul_f32_e32 v20, v48, v37
	v_lshl_add_u64 v[18:19], v[18:19], 1, s[8:9]
	v_cvt_pk_bf16_f32 v20, v20, s0
	global_store_short v[18:19], v20, off sc1
	v_add_u32_e32 v18, v190, v32
	v_ashrrev_i32_e32 v19, 31, v18
	v_mul_f32_e32 v20, v48, v36
	v_lshl_add_u64 v[18:19], v[18:19], 1, s[8:9]
	v_cvt_pk_bf16_f32 v20, v20, s0
	global_store_short v[18:19], v20, off sc1
	v_add_u32_e32 v18, v192, v32
	v_ashrrev_i32_e32 v19, 31, v18
	v_mul_f32_e32 v20, v48, v35
	v_lshl_add_u64 v[18:19], v[18:19], 1, s[8:9]
	v_cvt_pk_bf16_f32 v20, v20, s0
	global_load_dword v28, v[88:89], off offset:384
	global_load_dword v27, v[84:85], off offset:384
	global_load_dword v25, v[78:79], off offset:384
	global_load_dword v24, v[72:73], off offset:384
	global_load_dword v23, v[74:75], off offset:384
	global_load_dword v21, v[80:81], off offset:384
	global_load_dword v22, v[76:77], off offset:384
	v_fmac_f32_e32 v106, v114, v114
	global_store_short v[18:19], v20, off sc1
	v_add_u32_e32 v18, v193, v32
	v_ashrrev_i32_e32 v19, 31, v18
	v_mul_f32_e32 v20, v48, v34
	v_lshl_add_u64 v[18:19], v[18:19], 1, s[8:9]
	v_cvt_pk_bf16_f32 v20, v20, s0
	global_store_short v[18:19], v20, off sc1
	v_add_u32_e32 v18, v194, v32
	v_ashrrev_i32_e32 v19, 31, v18
	v_mul_f32_e32 v20, v48, v33
	v_lshl_add_u64 v[18:19], v[18:19], 1, s[8:9]
	v_cvt_pk_bf16_f32 v20, v20, s0
	global_store_short v[18:19], v20, off sc1
	global_load_dword v20, v[86:87], off offset:384
	s_waitcnt vmcnt(22)
	v_add_f32_e32 v17, 1.0, v17
	global_load_dword v26, v[82:83], off offset:384
	s_waitcnt vmcnt(22)
	v_mul_f32_e32 v32, v30, v17
	v_add_u32_e32 v18, v191, v16
	s_waitcnt vmcnt(20)
	v_fmac_f32_e32 v29, v0, v102
	v_ashrrev_i32_e32 v19, 31, v18
	v_mul_f32_e32 v0, v32, v29
	v_lshl_add_u64 v[18:19], v[18:19], 1, s[8:9]
	v_cvt_pk_bf16_f32 v0, v0, s0
	global_store_short v[18:19], v0, off sc1
	global_load_dword v19, v[90:91], off offset:384
	v_add_u32_e32 v30, v187, v16
	global_load_dword v18, v[92:93], off offset:384
	v_ashrrev_i32_e32 v31, 31, v30
	v_fmac_f32_e32 v106, v29, v29
	global_store_dword v[104:105], v29, off offset:384 sc1
	s_waitcnt vmcnt(15)
	v_fmac_f32_e32 v28, v1, v102
	v_mul_f32_e32 v17, v32, v28
	v_lshl_add_u64 v[0:1], v[30:31], 1, s[8:9]
	v_cvt_pk_bf16_f32 v17, v17, s0
	global_store_short v[0:1], v17, off sc1
	v_add_u32_e32 v0, v185, v16
	s_waitcnt vmcnt(15)
	v_fmac_f32_e32 v27, v2, v102
	global_load_dword v17, v[94:95], off offset:384
	v_ashrrev_i32_e32 v1, 31, v0
	v_mul_f32_e32 v2, v32, v27
	v_lshl_add_u64 v[0:1], v[0:1], 1, s[8:9]
	v_cvt_pk_bf16_f32 v2, v2, s0
	global_store_short v[0:1], v2, off sc1
	v_add_u32_e32 v0, v184, v16
	global_load_dword v2, v[96:97], off offset:384
	v_ashrrev_i32_e32 v1, 31, v0
	v_lshl_add_u64 v[0:1], v[0:1], 1, s[8:9]
	v_add_u32_e32 v30, v182, v16
	s_waitcnt vmcnt(17)
	v_fmac_f32_e32 v25, v4, v102
	v_ashrrev_i32_e32 v31, 31, v30
	v_lshl_add_u64 v[30:31], v[30:31], 1, s[8:9]
	s_waitcnt vmcnt(16)
	v_fmac_f32_e32 v24, v5, v102
	s_waitcnt vmcnt(15)
	v_fmac_f32_e32 v23, v6, v102
	s_waitcnt vmcnt(8)
	v_fmac_f32_e32 v26, v3, v102
	v_mul_f32_e32 v3, v32, v26
	v_cvt_pk_bf16_f32 v3, v3, s0
	global_store_short v[0:1], v3, off sc1
	global_load_dword v1, v[98:99], off offset:384
	v_mul_f32_e32 v0, v32, v25
	v_cvt_pk_bf16_f32 v0, v0, s0
	global_store_short v[30:31], v0, off sc1
	global_load_dword v0, v[100:101], off offset:384
	v_add_u32_e32 v30, v180, v16
	v_ashrrev_i32_e32 v31, 31, v30
	v_mul_f32_e32 v3, v32, v24
	v_lshl_add_u64 v[4:5], v[30:31], 1, s[8:9]
	v_cvt_pk_bf16_f32 v3, v3, s0
	global_store_short v[4:5], v3, off sc1
	v_add_u32_e32 v4, v71, v16
	v_ashrrev_i32_e32 v5, 31, v4
	v_mul_f32_e32 v3, v32, v23
	v_lshl_add_u64 v[4:5], v[4:5], 1, s[8:9]
	v_cvt_pk_bf16_f32 v3, v3, s0
	global_store_short v[4:5], v3, off sc1
	v_add_u32_e32 v4, v181, v16
	v_fmac_f32_e32 v22, v7, v102
	v_ashrrev_i32_e32 v5, 31, v4
	v_mul_f32_e32 v3, v32, v22
	v_lshl_add_u64 v[4:5], v[4:5], 1, s[8:9]
	v_cvt_pk_bf16_f32 v3, v3, s0
	global_store_short v[4:5], v3, off sc1
	v_add_u32_e32 v4, v183, v16
	v_fmac_f32_e32 v21, v8, v102
	v_ashrrev_i32_e32 v5, 31, v4
	v_mul_f32_e32 v3, v32, v21
	v_lshl_add_u64 v[4:5], v[4:5], 1, s[8:9]
	v_cvt_pk_bf16_f32 v3, v3, s0
	global_store_short v[4:5], v3, off sc1
	v_add_u32_e32 v4, v186, v16
	v_fmac_f32_e32 v20, v9, v102
	v_ashrrev_i32_e32 v5, 31, v4
	v_mul_f32_e32 v3, v32, v20
	v_lshl_add_u64 v[4:5], v[4:5], 1, s[8:9]
	v_cvt_pk_bf16_f32 v3, v3, s0
	global_store_short v[4:5], v3, off sc1
	v_add_u32_e32 v4, v188, v16
	s_waitcnt vmcnt(15)
	v_fmac_f32_e32 v19, v10, v102
	v_ashrrev_i32_e32 v5, 31, v4
	v_mul_f32_e32 v3, v32, v19
	v_lshl_add_u64 v[4:5], v[4:5], 1, s[8:9]
	v_cvt_pk_bf16_f32 v3, v3, s0
	global_store_short v[4:5], v3, off sc1
	v_add_u32_e32 v4, v189, v16
	s_waitcnt vmcnt(15)
	v_fmac_f32_e32 v18, v11, v102
	v_ashrrev_i32_e32 v5, 31, v4
	v_mul_f32_e32 v3, v32, v18
	v_lshl_add_u64 v[4:5], v[4:5], 1, s[8:9]
	v_cvt_pk_bf16_f32 v3, v3, s0
	global_store_short v[4:5], v3, off sc1
	v_add_u32_e32 v4, v190, v16
	v_ashrrev_i32_e32 v5, 31, v4
	v_lshl_add_u64 v[4:5], v[4:5], 1, s[8:9]
	v_ashrrev_i32_e32 v71, 31, v70
	global_store_dword v[88:89], v28, off offset:384 sc1
	global_store_dword v[84:85], v27, off offset:384 sc1
	global_store_dword v[82:83], v26, off offset:384 sc1
	global_store_dword v[78:79], v25, off offset:384 sc1
	s_waitcnt vmcnt(17)
	v_fmac_f32_e32 v17, v12, v102
	v_mul_f32_e32 v3, v32, v17
	v_cvt_pk_bf16_f32 v3, v3, s0
	global_store_short v[4:5], v3, off sc1
	v_add_u32_e32 v4, v192, v16
	v_ashrrev_i32_e32 v5, 31, v4
	v_lshl_add_u64 v[4:5], v[4:5], 1, s[8:9]
	s_waitcnt vmcnt(16)
	v_fmac_f32_e32 v2, v13, v102
	v_mul_f32_e32 v3, v32, v2
	v_cvt_pk_bf16_f32 v3, v3, s0
	global_store_short v[4:5], v3, off sc1
	v_add_u32_e32 v4, v193, v16
	v_ashrrev_i32_e32 v5, 31, v4
	v_lshl_add_u64 v[4:5], v[4:5], 1, s[8:9]
	v_xor_b32_e32 v12, 16, v165
	global_store_dword v[72:73], v24, off offset:384 sc1
	global_store_dword v[74:75], v23, off offset:384 sc1
	global_store_dword v[76:77], v22, off offset:384 sc1
	global_store_dword v[80:81], v21, off offset:384 sc1
	global_store_dword v[86:87], v20, off offset:384 sc1
	s_waitcnt vmcnt(20)
	v_fmac_f32_e32 v1, v14, v102
	v_mul_f32_e32 v3, v32, v1
	v_cvt_pk_bf16_f32 v3, v3, s0
	global_store_short v[4:5], v3, off sc1
	v_add_u32_e32 v4, v194, v16
	v_ashrrev_i32_e32 v5, 31, v4
	v_lshl_add_u64 v[10:11], v[4:5], 1, s[8:9]
	v_and_b32_e32 v4, 64, v165
	v_xor_b32_e32 v3, 1, v165
	v_add_u32_e32 v7, 64, v4
	v_cmp_lt_i32_e32 vcc, v3, v7
	v_xor_b32_e32 v4, 2, v165
	s_waitcnt vmcnt(19)
	v_fmac_f32_e32 v0, v15, v102
	v_cndmask_b32_e32 v3, v165, v3, vcc
	v_lshlrev_b32_e32 v3, 2, v3
	s_nop 1
	v_mov_b32_dpp v5, v106 quad_perm:[1,0,3,2] row_mask:0xf bank_mask:0xf
	v_cmp_lt_i32_e32 vcc, v4, v7
	global_store_dword v[90:91], v19, off offset:384 sc1
	global_store_dword v[92:93], v18, off offset:384 sc1
	v_cndmask_b32_e32 v4, v165, v4, vcc
	v_lshlrev_b32_e32 v4, 2, v4
	s_waitcnt lgkmcnt(0)
	v_add_f32_e32 v6, v106, v5
	s_nop 1
	v_mov_b32_dpp v8, v6 quad_perm:[2,3,0,1] row_mask:0xf bank_mask:0xf
	v_xor_b32_e32 v5, 4, v165
	v_cmp_lt_i32_e32 vcc, v5, v7
	global_store_dword v[94:95], v17, off offset:384 sc1
	global_store_dword v[96:97], v2, off offset:384 sc1
	v_cndmask_b32_e32 v5, v165, v5, vcc
	v_lshlrev_b32_e32 v5, 2, v5
	s_waitcnt lgkmcnt(0)
	v_add_f32_e32 v8, v6, v8
	s_nop 1
	v_mov_b32_dpp v9, v8 row_half_mirror row_mask:0xf bank_mask:0xf
	v_xor_b32_e32 v6, 8, v165
	v_cmp_lt_i32_e32 vcc, v6, v7
	global_store_dword v[98:99], v1, off offset:384 sc1
	global_store_dword v[100:101], v0, off offset:384 sc1
	v_cndmask_b32_e32 v6, v165, v6, vcc
	v_lshlrev_b32_e32 v6, 2, v6
	s_waitcnt lgkmcnt(0)
	v_add_f32_e32 v8, v8, v9
	s_nop 1
	v_mov_b32_dpp v9, v8 row_mirror row_mask:0xf bank_mask:0xf
	v_cmp_lt_i32_e32 vcc, v12, v7
	s_waitcnt lgkmcnt(0)
	v_add_f32_e32 v8, v8, v9
	v_cndmask_b32_e32 v7, v165, v12, vcc
	v_lshlrev_b32_e32 v7, 2, v7
	ds_bpermute_b32 v9, v7, v8
	v_mul_f32_e32 v12, v32, v0
	v_cvt_pk_bf16_f32 v12, v12, s0
	global_store_short v[10:11], v12, off sc1
	s_and_saveexec_b64 s[60:61], s[0:1]
	s_cbranch_execz .LBB0_1124
	s_waitcnt lgkmcnt(0)
	v_add_f32_e32 v10, v8, v9
	v_lshl_add_u64 v[8:9], v[70:71], 2, s[58:59]
	global_store_dword v[8:9], v10, off sc1

.LBB0_1189:
	s_and_b64 vcc, exec, s[4:5]
	s_cbranch_vccz .LBB0_1170
	v_mov_b32_e32 v12, s82
	ds_read_b64 v[12:13], v12
	s_add_i32 s73, s84, -8
	s_cmp_lt_i32 s85, 64
	s_cselect_b64 s[68:69], -1, 0
	s_and_b64 s[4:5], s[68:69], exec
	s_waitcnt lgkmcnt(0)
	v_readfirstlane_b32 s8, v12
	s_cselect_b32 s4, 0, 0x200
	v_readfirstlane_b32 s70, v13
	s_add_u32 s4, s8, s4
	s_addc_u32 s5, s70, 0
	v_lshlrev_b32_e32 v14, 2, v108
	global_load_dword v13, v14, s[4:5]
	global_load_dword v12, v14, s[4:5] offset:128
	global_load_dword v15, v14, s[4:5] offset:256
	s_nop 0
	global_load_dword v14, v14, s[4:5] offset:384
	v_and_b32_e32 v31, 64, v170
	v_xor_b32_e32 v30, 1, v170
	v_pk_mul_f32 v[26:27], v[90:91], v[90:91]
	v_add_u32_e32 v31, 64, v31
	v_pk_mul_f32 v[28:29], v[92:93], v[92:93]
	v_add_f32_e32 v26, v27, v26
	v_cmp_lt_i32_e32 vcc, v30, v31
	v_add_f32_e32 v26, v26, v29
	v_add_f32_e32 v26, v26, v28
	v_cndmask_b32_e32 v27, v170, v30, vcc
	v_lshlrev_b32_e32 v42, 2, v27
	s_nop 1
	v_mov_b32_dpp v27, v26 quad_perm:[1,0,3,2] row_mask:0xf bank_mask:0xf
	v_xor_b32_e32 v28, 2, v170
	v_cmp_lt_i32_e32 vcc, v28, v31
	s_or_b64 s[70:71], s[68:69], s[0:1]
	s_lshl_b32 s8, s73, 7
	v_cndmask_b32_e32 v28, v170, v28, vcc
	v_lshlrev_b32_e32 v44, 2, v28
	s_waitcnt lgkmcnt(0)
	v_add_f32_e32 v26, v26, v27
	s_nop 1
	v_mov_b32_dpp v27, v26 quad_perm:[2,3,0,1] row_mask:0xf bank_mask:0xf
	v_xor_b32_e32 v28, 4, v170
	v_cmp_lt_i32_e32 vcc, v28, v31
	s_waitcnt lgkmcnt(0)
	v_add_f32_e32 v26, v26, v27
	v_cndmask_b32_e32 v28, v170, v28, vcc
	v_lshlrev_b32_e32 v45, 2, v28
	s_nop 1
	v_mov_b32_dpp v27, v26 row_half_mirror row_mask:0xf bank_mask:0xf
	v_xor_b32_e32 v28, 8, v170
	v_cmp_lt_i32_e32 vcc, v28, v31
	s_waitcnt lgkmcnt(0)
	v_add_f32_e32 v26, v26, v27
	v_cndmask_b32_e32 v28, v170, v28, vcc
	v_lshlrev_b32_e32 v46, 2, v28
	s_nop 1
	v_mov_b32_dpp v27, v26 row_mirror row_mask:0xf bank_mask:0xf
	v_xor_b32_e32 v28, 16, v170
	v_cmp_lt_i32_e32 vcc, v28, v31
	s_waitcnt lgkmcnt(0)
	v_add_f32_e32 v26, v26, v27
	v_cndmask_b32_e32 v28, v170, v28, vcc
	v_lshlrev_b32_e32 v43, 2, v28
	ds_bpermute_b32 v27, v43, v26
	s_and_b64 vcc, exec, s[70:71]
	s_waitcnt lgkmcnt(0)
	v_add_f32_e32 v26, v26, v27
	v_fmamk_f32 v26, v26, 0x3c000000, v166
	v_rsq_f32_e32 v28, v26
	v_lshl_add_u64 v[26:27], s[8:9], 2, v[116:117]
	s_waitcnt vmcnt(2)
	v_pk_mul_f32 v[30:31], v[12:13], v[28:29] op_sel_hi:[1,0]
	s_nop 0
	v_pk_mul_f32 v[40:41], v[90:91], v[30:31]
	s_waitcnt vmcnt(0)
	v_pk_mul_f32 v[28:29], v[14:15], v[28:29] op_sel_hi:[1,0]
	s_nop 0
	v_pk_mul_f32 v[30:31], v[92:93], v[28:29]
	s_cbranch_vccnz .LBB0_1192
	v_lshlrev_b32_e32 v28, 8, v118
	v_ashrrev_i32_e32 v29, 31, v28
	v_lshl_add_u64 v[28:29], v[28:29], 2, v[26:27]
	global_store_dword v[28:29], v41, off sc1
	global_store_dword v[28:29], v40, off offset:128 sc1
	global_store_dword v[28:29], v31, off offset:256 sc1
	global_store_dword v[28:29], v30, off offset:384 sc1

.LBB0_1194:
	v_pk_mul_f32 v[28:29], v[88:89], v[88:89]
	v_pk_mul_f32 v[54:55], v[86:87], v[86:87]
	v_add_f32_e32 v28, v29, v28
	v_add_f32_e32 v28, v28, v55
	v_add_f32_e32 v28, v28, v54
	s_nop 1
	v_mov_b32_dpp v29, v28 quad_perm:[1,0,3,2] row_mask:0xf bank_mask:0xf
	s_xor_b64 s[70:71], s[70:71], -1
	s_and_b64 s[0:1], s[68:69], exec
	s_cselect_b32 s0, s83, 0xdf9f000
	s_cselect_b32 s8, s66, s72
	s_waitcnt lgkmcnt(0)
	v_add_f32_e32 v28, v28, v29
	s_nop 1
	v_mov_b32_dpp v29, v28 quad_perm:[2,3,0,1] row_mask:0xf bank_mask:0xf
	s_cselect_b32 s72, s84, s73
	s_add_u32 s73, s14, s0
	s_addc_u32 s84, s15, 0
	s_and_b64 s[0:1], s[68:69], exec
	s_waitcnt lgkmcnt(0)
	v_add_f32_e32 v47, v28, v29
	s_nop 1
	v_mov_b32_dpp v54, v47 row_half_mirror row_mask:0xf bank_mask:0xf
	s_cselect_b32 s68, 10, 8
	s_lshl_b32 s0, s72, 7
	s_ashr_i32 s1, s0, 31
	s_lshl_b64 s[0:1], s[0:1], 1
	s_waitcnt lgkmcnt(0)
	v_add_f32_e32 v47, v47, v54
	s_nop 1
	v_mov_b32_dpp v56, v47 row_mirror row_mask:0xf bank_mask:0xf
	s_add_u32 s0, s73, s0
	v_add_u32_e32 v55, s8, v133
	s_addc_u32 s1, s84, s1
	v_lshlrev_b32_e32 v106, 1, v108
	s_waitcnt lgkmcnt(0)
	v_add_f32_e32 v47, v47, v56
	ds_bpermute_b32 v56, v43, v47
	v_lshlrev_b32_e32 v54, s68, v55
	v_lshl_add_u64 v[28:29], s[0:1], 0, v[106:107]
	v_ashrrev_i32_e32 v55, 31, v54
	v_lshl_add_u64 v[54:55], v[54:55], 1, v[28:29]
	v_cvt_pk_bf16_f32 v40, v40, s0
	global_store_short v[54:55], v40, off offset:64 sc1
	s_waitcnt lgkmcnt(0)
	v_add_f32_e32 v40, v47, v56
	v_fmamk_f32 v40, v40, 0x3c000000, v166
	v_rsq_f32_e32 v40, v40
	v_cvt_pk_bf16_f32 v41, v41, s0
	v_cvt_pk_bf16_f32 v31, v31, s0
	v_cvt_pk_bf16_f32 v30, v30, s0
	global_store_short v[54:55], v41, off sc1
	global_store_short v[54:55], v31, off offset:128 sc1
	global_store_short v[54:55], v30, off offset:192 sc1
	v_pk_mul_f32 v[30:31], v[12:13], v[40:41] op_sel_hi:[1,0]
	v_pk_mul_f32 v[40:41], v[14:15], v[40:41] op_sel_hi:[1,0]
	v_cndmask_b32_e64 v47, 0, 1, s[70:71]
	v_pk_mul_f32 v[30:31], v[88:89], v[30:31]
	v_cmp_ne_u32_e64 s[0:1], 1, v47
	s_andn2_b64 vcc, exec, s[70:71]
	v_pk_mul_f32 v[40:41], v[86:87], v[40:41]
	s_cbranch_vccnz .LBB0_1196
	v_add_lshl_u32 v54, s66, v141, 8
	v_ashrrev_i32_e32 v55, 31, v54
	v_lshl_add_u64 v[54:55], v[54:55], 2, v[26:27]
	global_store_dword v[54:55], v31, off sc1
	global_store_dword v[54:55], v30, off offset:128 sc1
	global_store_dword v[54:55], v41, off offset:256 sc1
	global_store_dword v[54:55], v40, off offset:384 sc1

.LBB0_1198:
	v_pk_mul_f32 v[54:55], v[80:81], v[80:81]
	v_pk_mul_f32 v[56:57], v[82:83], v[82:83]
	v_add_f32_e32 v47, v55, v54
	v_add_f32_e32 v47, v47, v57
	v_add_f32_e32 v47, v47, v56
	s_nop 1
	v_mov_b32_dpp v54, v47 quad_perm:[1,0,3,2] row_mask:0xf bank_mask:0xf
	v_cvt_pk_bf16_f32 v56, v31, s0
	v_cvt_pk_bf16_f32 v57, v40, s0
	v_add_u32_e32 v55, s8, v141
	v_cvt_pk_bf16_f32 v41, v41, s0
	s_waitcnt lgkmcnt(0)
	v_add_f32_e32 v47, v47, v54
	s_nop 1
	v_mov_b32_dpp v54, v47 quad_perm:[2,3,0,1] row_mask:0xf bank_mask:0xf
	s_and_b64 vcc, exec, s[0:1]
	s_waitcnt lgkmcnt(0)
	v_add_f32_e32 v47, v47, v54
	s_nop 1
	v_mov_b32_dpp v54, v47 row_half_mirror row_mask:0xf bank_mask:0xf
	s_waitcnt lgkmcnt(0)
	v_add_f32_e32 v31, v47, v54
	s_nop 1
	v_mov_b32_dpp v47, v31 row_mirror row_mask:0xf bank_mask:0xf
	v_cvt_pk_bf16_f32 v54, v30, s0
	v_lshlrev_b32_e32 v30, s68, v55
	s_waitcnt lgkmcnt(0)
	v_add_f32_e32 v40, v31, v47
	ds_bpermute_b32 v47, v43, v40
	v_ashrrev_i32_e32 v31, 31, v30
	v_lshl_add_u64 v[30:31], v[30:31], 1, v[28:29]
	global_store_short v[30:31], v56, off sc1
	global_store_short v[30:31], v54, off offset:64 sc1
	global_store_short v[30:31], v41, off offset:128 sc1
	global_store_short v[30:31], v57, off offset:192 sc1
	s_waitcnt lgkmcnt(0)
	v_add_f32_e32 v40, v40, v47
	v_fmamk_f32 v40, v40, 0x3c000000, v166
	v_rsq_f32_e32 v40, v40
	s_nop 0
	v_pk_mul_f32 v[30:31], v[12:13], v[40:41] op_sel_hi:[1,0]
	v_pk_mul_f32 v[54:55], v[14:15], v[40:41] op_sel_hi:[1,0]
	v_pk_mul_f32 v[40:41], v[80:81], v[30:31]
	v_pk_mul_f32 v[30:31], v[82:83], v[54:55]
	s_cbranch_vccnz .LBB0_1200
	v_add_lshl_u32 v54, s66, v142, 8
	v_ashrrev_i32_e32 v55, 31, v54
	v_lshl_add_u64 v[54:55], v[54:55], 2, v[26:27]
	global_store_dword v[54:55], v41, off sc1
	global_store_dword v[54:55], v40, off offset:128 sc1
	global_store_dword v[54:55], v31, off offset:256 sc1
	global_store_dword v[54:55], v30, off offset:384 sc1

.LBB0_1202:
	v_pk_mul_f32 v[54:55], v[76:77], v[76:77]
	v_pk_mul_f32 v[56:57], v[78:79], v[78:79]
	v_add_f32_e32 v47, v55, v54
	v_add_f32_e32 v47, v47, v57
	v_add_f32_e32 v47, v47, v56
	s_nop 1
	v_mov_b32_dpp v54, v47 quad_perm:[1,0,3,2] row_mask:0xf bank_mask:0xf
	v_cvt_pk_bf16_f32 v56, v40, s0
	v_add_u32_e32 v55, s8, v142
	v_cvt_pk_bf16_f32 v58, v30, s0
	v_lshlrev_b32_e32 v30, s68, v55
	s_waitcnt lgkmcnt(0)
	v_add_f32_e32 v47, v47, v54
	s_nop 1
	v_mov_b32_dpp v54, v47 quad_perm:[2,3,0,1] row_mask:0xf bank_mask:0xf
	v_cvt_pk_bf16_f32 v57, v31, s0
	v_ashrrev_i32_e32 v31, 31, v30
	v_cvt_pk_bf16_f32 v41, v41, s0
	v_lshl_add_u64 v[30:31], v[30:31], 1, v[28:29]
	s_waitcnt lgkmcnt(0)
	v_add_f32_e32 v47, v47, v54
	s_nop 1
	v_mov_b32_dpp v54, v47 row_half_mirror row_mask:0xf bank_mask:0xf
	global_store_short v[30:31], v41, off sc1
	global_store_short v[30:31], v56, off offset:64 sc1
	global_store_short v[30:31], v57, off offset:128 sc1
	global_store_short v[30:31], v58, off offset:192 sc1
	s_and_b64 vcc, exec, s[0:1]
	s_waitcnt lgkmcnt(0)
	v_add_f32_e32 v47, v47, v54
	s_nop 1
	v_mov_b32_dpp v54, v47 row_mirror row_mask:0xf bank_mask:0xf
	s_waitcnt lgkmcnt(0)
	v_add_f32_e32 v40, v47, v54
	ds_bpermute_b32 v47, v43, v40
	s_waitcnt lgkmcnt(0)
	v_add_f32_e32 v40, v40, v47
	v_fmamk_f32 v40, v40, 0x3c000000, v166
	v_rsq_f32_e32 v40, v40
	s_nop 0
	v_pk_mul_f32 v[30:31], v[12:13], v[40:41] op_sel_hi:[1,0]
	v_pk_mul_f32 v[54:55], v[14:15], v[40:41] op_sel_hi:[1,0]
	v_pk_mul_f32 v[40:41], v[76:77], v[30:31]
	v_pk_mul_f32 v[30:31], v[78:79], v[54:55]
	s_cbranch_vccnz .LBB0_1204
	v_add_lshl_u32 v54, s66, v143, 8
	v_ashrrev_i32_e32 v55, 31, v54
	v_lshl_add_u64 v[54:55], v[54:55], 2, v[26:27]
	global_store_dword v[54:55], v41, off sc1
	global_store_dword v[54:55], v40, off offset:128 sc1
	global_store_dword v[54:55], v31, off offset:256 sc1
	global_store_dword v[54:55], v30, off offset:384 sc1

.LBB0_1206:
	v_pk_mul_f32 v[54:55], v[72:73], v[72:73]
	v_pk_mul_f32 v[56:57], v[74:75], v[74:75]
	v_add_f32_e32 v47, v55, v54
	v_add_f32_e32 v47, v47, v57
	v_add_f32_e32 v47, v47, v56
	s_nop 1
	v_mov_b32_dpp v54, v47 quad_perm:[1,0,3,2] row_mask:0xf bank_mask:0xf
	v_cvt_pk_bf16_f32 v56, v40, s0
	v_add_u32_e32 v55, s8, v143
	v_cvt_pk_bf16_f32 v58, v30, s0
	v_lshlrev_b32_e32 v30, s68, v55
	s_waitcnt lgkmcnt(0)
	v_add_f32_e32 v47, v47, v54
	s_nop 1
	v_mov_b32_dpp v54, v47 quad_perm:[2,3,0,1] row_mask:0xf bank_mask:0xf
	v_cvt_pk_bf16_f32 v57, v31, s0
	v_ashrrev_i32_e32 v31, 31, v30
	v_cvt_pk_bf16_f32 v41, v41, s0
	v_lshl_add_u64 v[30:31], v[30:31], 1, v[28:29]
	s_waitcnt lgkmcnt(0)
	v_add_f32_e32 v47, v47, v54
	s_nop 1
	v_mov_b32_dpp v54, v47 row_half_mirror row_mask:0xf bank_mask:0xf
	global_store_short v[30:31], v41, off sc1
	global_store_short v[30:31], v56, off offset:64 sc1
	global_store_short v[30:31], v57, off offset:128 sc1
	global_store_short v[30:31], v58, off offset:192 sc1
	s_and_b64 vcc, exec, s[0:1]
	s_waitcnt lgkmcnt(0)
	v_add_f32_e32 v47, v47, v54
	s_nop 1
	v_mov_b32_dpp v54, v47 row_mirror row_mask:0xf bank_mask:0xf
	s_waitcnt lgkmcnt(0)
	v_add_f32_e32 v40, v47, v54
	ds_bpermute_b32 v47, v43, v40
	s_waitcnt lgkmcnt(0)
	v_add_f32_e32 v40, v40, v47
	v_fmamk_f32 v40, v40, 0x3c000000, v166
	v_rsq_f32_e32 v40, v40
	s_nop 0
	v_pk_mul_f32 v[30:31], v[12:13], v[40:41] op_sel_hi:[1,0]
	v_pk_mul_f32 v[54:55], v[14:15], v[40:41] op_sel_hi:[1,0]
	v_pk_mul_f32 v[40:41], v[72:73], v[30:31]
	v_pk_mul_f32 v[30:31], v[74:75], v[54:55]
	s_cbranch_vccnz .LBB0_1208
	v_add_lshl_u32 v54, s66, v144, 8
	v_ashrrev_i32_e32 v55, 31, v54
	v_lshl_add_u64 v[54:55], v[54:55], 2, v[26:27]
	global_store_dword v[54:55], v41, off sc1
	global_store_dword v[54:55], v40, off offset:128 sc1
	global_store_dword v[54:55], v31, off offset:256 sc1
	global_store_dword v[54:55], v30, off offset:384 sc1

.LBB0_1210:
	v_pk_mul_f32 v[54:55], v[68:69], v[68:69]
	v_pk_mul_f32 v[56:57], v[70:71], v[70:71]
	v_add_f32_e32 v47, v55, v54
	v_add_f32_e32 v47, v47, v57
	v_add_f32_e32 v47, v47, v56
	s_nop 1
	v_mov_b32_dpp v54, v47 quad_perm:[1,0,3,2] row_mask:0xf bank_mask:0xf
	v_cvt_pk_bf16_f32 v56, v40, s0
	v_add_u32_e32 v55, s8, v144
	v_cvt_pk_bf16_f32 v58, v30, s0
	v_lshlrev_b32_e32 v30, s68, v55
	s_waitcnt lgkmcnt(0)
	v_add_f32_e32 v47, v47, v54
	s_nop 1
	v_mov_b32_dpp v54, v47 quad_perm:[2,3,0,1] row_mask:0xf bank_mask:0xf
	v_cvt_pk_bf16_f32 v57, v31, s0
	v_ashrrev_i32_e32 v31, 31, v30
	v_cvt_pk_bf16_f32 v41, v41, s0
	v_lshl_add_u64 v[30:31], v[30:31], 1, v[28:29]
	s_waitcnt lgkmcnt(0)
	v_add_f32_e32 v47, v47, v54
	s_nop 1
	v_mov_b32_dpp v54, v47 row_half_mirror row_mask:0xf bank_mask:0xf
	global_store_short v[30:31], v41, off sc1
	global_store_short v[30:31], v56, off offset:64 sc1
	global_store_short v[30:31], v57, off offset:128 sc1
	global_store_short v[30:31], v58, off offset:192 sc1
	s_and_b64 vcc, exec, s[0:1]
	s_waitcnt lgkmcnt(0)
	v_add_f32_e32 v47, v47, v54
	s_nop 1
	v_mov_b32_dpp v54, v47 row_mirror row_mask:0xf bank_mask:0xf
	s_waitcnt lgkmcnt(0)
	v_add_f32_e32 v40, v47, v54
	ds_bpermute_b32 v47, v43, v40
	s_waitcnt lgkmcnt(0)
	v_add_f32_e32 v40, v40, v47
	v_fmamk_f32 v40, v40, 0x3c000000, v166
	v_rsq_f32_e32 v40, v40
	s_nop 0
	v_pk_mul_f32 v[30:31], v[12:13], v[40:41] op_sel_hi:[1,0]
	v_pk_mul_f32 v[54:55], v[14:15], v[40:41] op_sel_hi:[1,0]
	v_pk_mul_f32 v[40:41], v[68:69], v[30:31]
	v_pk_mul_f32 v[30:31], v[70:71], v[54:55]
	s_cbranch_vccnz .LBB0_1212
	v_add_lshl_u32 v54, s66, v145, 8
	v_ashrrev_i32_e32 v55, 31, v54
	v_lshl_add_u64 v[54:55], v[54:55], 2, v[26:27]
	global_store_dword v[54:55], v41, off sc1
	global_store_dword v[54:55], v40, off offset:128 sc1
	global_store_dword v[54:55], v31, off offset:256 sc1
	global_store_dword v[54:55], v30, off offset:384 sc1

.LBB0_1214:
	v_pk_mul_f32 v[54:55], v[64:65], v[64:65]
	v_pk_mul_f32 v[56:57], v[66:67], v[66:67]
	v_add_f32_e32 v47, v55, v54
	v_add_f32_e32 v47, v47, v57
	v_add_f32_e32 v47, v47, v56
	s_nop 1
	v_mov_b32_dpp v54, v47 quad_perm:[1,0,3,2] row_mask:0xf bank_mask:0xf
	v_cvt_pk_bf16_f32 v56, v40, s0
	v_add_u32_e32 v55, s8, v145
	v_cvt_pk_bf16_f32 v58, v30, s0
	v_lshlrev_b32_e32 v30, s68, v55
	s_waitcnt lgkmcnt(0)
	v_add_f32_e32 v47, v47, v54
	s_nop 1
	v_mov_b32_dpp v54, v47 quad_perm:[2,3,0,1] row_mask:0xf bank_mask:0xf
	v_cvt_pk_bf16_f32 v57, v31, s0
	v_ashrrev_i32_e32 v31, 31, v30
	v_cvt_pk_bf16_f32 v41, v41, s0
	v_lshl_add_u64 v[30:31], v[30:31], 1, v[28:29]
	s_waitcnt lgkmcnt(0)
	v_add_f32_e32 v47, v47, v54
	s_nop 1
	v_mov_b32_dpp v54, v47 row_half_mirror row_mask:0xf bank_mask:0xf
	global_store_short v[30:31], v41, off sc1
	global_store_short v[30:31], v56, off offset:64 sc1
	global_store_short v[30:31], v57, off offset:128 sc1
	global_store_short v[30:31], v58, off offset:192 sc1
	s_and_b64 vcc, exec, s[0:1]
	s_waitcnt lgkmcnt(0)
	v_add_f32_e32 v47, v47, v54
	s_nop 1
	v_mov_b32_dpp v54, v47 row_mirror row_mask:0xf bank_mask:0xf
	s_waitcnt lgkmcnt(0)
	v_add_f32_e32 v40, v47, v54
	ds_bpermute_b32 v47, v43, v40
	s_waitcnt lgkmcnt(0)
	v_add_f32_e32 v40, v40, v47
	v_fmamk_f32 v40, v40, 0x3c000000, v166
	v_rsq_f32_e32 v40, v40
	s_nop 0
	v_pk_mul_f32 v[30:31], v[12:13], v[40:41] op_sel_hi:[1,0]
	v_pk_mul_f32 v[54:55], v[14:15], v[40:41] op_sel_hi:[1,0]
	v_pk_mul_f32 v[40:41], v[64:65], v[30:31]
	v_pk_mul_f32 v[30:31], v[66:67], v[54:55]
	s_cbranch_vccnz .LBB0_1216
	v_add_lshl_u32 v54, s66, v146, 8
	v_ashrrev_i32_e32 v55, 31, v54
	v_lshl_add_u64 v[54:55], v[54:55], 2, v[26:27]
	global_store_dword v[54:55], v41, off sc1
	global_store_dword v[54:55], v40, off offset:128 sc1
	global_store_dword v[54:55], v31, off offset:256 sc1
	global_store_dword v[54:55], v30, off offset:384 sc1

.LBB0_1218:
	v_pk_mul_f32 v[54:55], v[50:51], v[50:51]
	v_pk_mul_f32 v[56:57], v[52:53], v[52:53]
	v_add_f32_e32 v47, v55, v54
	v_add_f32_e32 v47, v47, v57
	v_add_f32_e32 v47, v47, v56
	s_nop 1
	v_mov_b32_dpp v54, v47 quad_perm:[1,0,3,2] row_mask:0xf bank_mask:0xf
	v_cvt_pk_bf16_f32 v56, v40, s0
	v_add_u32_e32 v55, s8, v146
	v_cvt_pk_bf16_f32 v58, v30, s0
	v_lshlrev_b32_e32 v30, s68, v55
	s_waitcnt lgkmcnt(0)
	v_add_f32_e32 v47, v47, v54
	s_nop 1
	v_mov_b32_dpp v54, v47 quad_perm:[2,3,0,1] row_mask:0xf bank_mask:0xf
	v_cvt_pk_bf16_f32 v57, v31, s0
	v_ashrrev_i32_e32 v31, 31, v30
	v_cvt_pk_bf16_f32 v41, v41, s0
	v_lshl_add_u64 v[30:31], v[30:31], 1, v[28:29]
	s_waitcnt lgkmcnt(0)
	v_add_f32_e32 v47, v47, v54
	s_nop 1
	v_mov_b32_dpp v54, v47 row_half_mirror row_mask:0xf bank_mask:0xf
	global_store_short v[30:31], v41, off sc1
	global_store_short v[30:31], v56, off offset:64 sc1
	global_store_short v[30:31], v57, off offset:128 sc1
	global_store_short v[30:31], v58, off offset:192 sc1
	s_and_b64 vcc, exec, s[0:1]
	s_waitcnt lgkmcnt(0)
	v_add_f32_e32 v47, v47, v54
	s_nop 1
	v_mov_b32_dpp v54, v47 row_mirror row_mask:0xf bank_mask:0xf
	s_waitcnt lgkmcnt(0)
	v_add_f32_e32 v40, v47, v54
	ds_bpermute_b32 v47, v43, v40
	s_waitcnt lgkmcnt(0)
	v_add_f32_e32 v40, v40, v47
	v_fmamk_f32 v40, v40, 0x3c000000, v166
	v_rsq_f32_e32 v40, v40
	s_nop 0
	v_pk_mul_f32 v[30:31], v[12:13], v[40:41] op_sel_hi:[1,0]
	v_pk_mul_f32 v[54:55], v[14:15], v[40:41] op_sel_hi:[1,0]
	v_pk_mul_f32 v[40:41], v[50:51], v[30:31]
	v_pk_mul_f32 v[30:31], v[52:53], v[54:55]
	s_cbranch_vccnz .LBB0_1220
	v_add_lshl_u32 v50, s66, v147, 8
	v_ashrrev_i32_e32 v51, 31, v50
	v_lshl_add_u64 v[50:51], v[50:51], 2, v[26:27]
	global_store_dword v[50:51], v41, off sc1
	global_store_dword v[50:51], v40, off offset:128 sc1
	global_store_dword v[50:51], v31, off offset:256 sc1
	global_store_dword v[50:51], v30, off offset:384 sc1

.LBB0_1222:
	v_pk_mul_f32 v[50:51], v[38:39], v[38:39]
	v_pk_mul_f32 v[52:53], v[48:49], v[48:49]
	v_add_f32_e32 v47, v51, v50
	v_add_f32_e32 v47, v47, v53
	v_add_f32_e32 v47, v47, v52
	s_nop 1
	v_mov_b32_dpp v50, v47 quad_perm:[1,0,3,2] row_mask:0xf bank_mask:0xf
	v_cvt_pk_bf16_f32 v52, v40, s0
	v_add_u32_e32 v51, s8, v147
	v_cvt_pk_bf16_f32 v54, v30, s0
	v_lshlrev_b32_e32 v30, s68, v51
	s_waitcnt lgkmcnt(0)
	v_add_f32_e32 v47, v47, v50
	s_nop 1
	v_mov_b32_dpp v50, v47 quad_perm:[2,3,0,1] row_mask:0xf bank_mask:0xf
	v_cvt_pk_bf16_f32 v53, v31, s0
	v_ashrrev_i32_e32 v31, 31, v30
	v_cvt_pk_bf16_f32 v41, v41, s0
	v_lshl_add_u64 v[30:31], v[30:31], 1, v[28:29]
	s_waitcnt lgkmcnt(0)
	v_add_f32_e32 v47, v47, v50
	s_nop 1
	v_mov_b32_dpp v50, v47 row_half_mirror row_mask:0xf bank_mask:0xf
	global_store_short v[30:31], v41, off sc1
	global_store_short v[30:31], v52, off offset:64 sc1
	global_store_short v[30:31], v53, off offset:128 sc1
	global_store_short v[30:31], v54, off offset:192 sc1
	s_and_b64 vcc, exec, s[0:1]
	s_waitcnt lgkmcnt(0)
	v_add_f32_e32 v47, v47, v50
	s_nop 1
	v_mov_b32_dpp v50, v47 row_mirror row_mask:0xf bank_mask:0xf
	s_waitcnt lgkmcnt(0)
	v_add_f32_e32 v40, v47, v50
	ds_bpermute_b32 v47, v43, v40
	s_waitcnt lgkmcnt(0)
	v_add_f32_e32 v40, v40, v47
	v_fmamk_f32 v40, v40, 0x3c000000, v166
	v_rsq_f32_e32 v40, v40
	s_nop 0
	v_pk_mul_f32 v[30:31], v[12:13], v[40:41] op_sel_hi:[1,0]
	v_pk_mul_f32 v[40:41], v[14:15], v[40:41] op_sel_hi:[1,0]
	v_pk_mul_f32 v[38:39], v[38:39], v[30:31]
	v_pk_mul_f32 v[30:31], v[48:49], v[40:41]
	s_cbranch_vccnz .LBB0_1224
	v_add_lshl_u32 v40, s66, v148, 8
	v_ashrrev_i32_e32 v41, 31, v40
	v_lshl_add_u64 v[40:41], v[40:41], 2, v[26:27]
	global_store_dword v[40:41], v39, off sc1
	global_store_dword v[40:41], v38, off offset:128 sc1
	global_store_dword v[40:41], v31, off offset:256 sc1
	global_store_dword v[40:41], v30, off offset:384 sc1

.LBB0_1226:
	v_pk_mul_f32 v[40:41], v[34:35], v[34:35]
	v_pk_mul_f32 v[48:49], v[36:37], v[36:37]
	v_add_f32_e32 v40, v41, v40
	v_add_f32_e32 v40, v40, v49
	v_add_f32_e32 v40, v40, v48
	s_nop 1
	v_mov_b32_dpp v41, v40 quad_perm:[1,0,3,2] row_mask:0xf bank_mask:0xf
	v_cvt_pk_bf16_f32 v48, v38, s0
	v_add_u32_e32 v47, s8, v148
	v_cvt_pk_bf16_f32 v50, v30, s0
	v_lshlrev_b32_e32 v30, s68, v47
	s_waitcnt lgkmcnt(0)
	v_add_f32_e32 v40, v40, v41
	s_nop 1
	v_mov_b32_dpp v41, v40 quad_perm:[2,3,0,1] row_mask:0xf bank_mask:0xf
	v_cvt_pk_bf16_f32 v49, v31, s0
	v_ashrrev_i32_e32 v31, 31, v30
	v_cvt_pk_bf16_f32 v39, v39, s0
	v_lshl_add_u64 v[30:31], v[30:31], 1, v[28:29]
	s_waitcnt lgkmcnt(0)
	v_add_f32_e32 v40, v40, v41
	s_nop 1
	v_mov_b32_dpp v41, v40 row_half_mirror row_mask:0xf bank_mask:0xf
	global_store_short v[30:31], v39, off sc1
	global_store_short v[30:31], v48, off offset:64 sc1
	global_store_short v[30:31], v49, off offset:128 sc1
	global_store_short v[30:31], v50, off offset:192 sc1
	s_and_b64 vcc, exec, s[0:1]
	s_waitcnt lgkmcnt(0)
	v_add_f32_e32 v40, v40, v41
	s_nop 1
	v_mov_b32_dpp v41, v40 row_mirror row_mask:0xf bank_mask:0xf
	s_waitcnt lgkmcnt(0)
	v_add_f32_e32 v38, v40, v41
	ds_bpermute_b32 v40, v43, v38
	s_waitcnt lgkmcnt(0)
	v_add_f32_e32 v38, v38, v40
	v_fmamk_f32 v38, v38, 0x3c000000, v166
	v_rsq_f32_e32 v38, v38
	s_nop 0
	v_pk_mul_f32 v[30:31], v[12:13], v[38:39] op_sel_hi:[1,0]
	v_pk_mul_f32 v[38:39], v[14:15], v[38:39] op_sel_hi:[1,0]
	v_pk_mul_f32 v[34:35], v[34:35], v[30:31]
	v_pk_mul_f32 v[30:31], v[36:37], v[38:39]
	s_cbranch_vccnz .LBB0_1228
	v_add_lshl_u32 v36, s66, v149, 8
	v_ashrrev_i32_e32 v37, 31, v36
	v_lshl_add_u64 v[36:37], v[36:37], 2, v[26:27]
	global_store_dword v[36:37], v35, off sc1
	global_store_dword v[36:37], v34, off offset:128 sc1
	global_store_dword v[36:37], v31, off offset:256 sc1
	global_store_dword v[36:37], v30, off offset:384 sc1

.LBB0_1230:
	v_pk_mul_f32 v[36:37], v[24:25], v[24:25]
	v_pk_mul_f32 v[38:39], v[32:33], v[32:33]
	v_add_f32_e32 v36, v37, v36
	v_add_f32_e32 v36, v36, v39
	v_add_f32_e32 v36, v36, v38
	s_nop 1
	v_mov_b32_dpp v37, v36 quad_perm:[1,0,3,2] row_mask:0xf bank_mask:0xf
	v_cvt_pk_bf16_f32 v39, v34, s0
	v_add_u32_e32 v38, s8, v149
	v_cvt_pk_bf16_f32 v41, v30, s0
	v_lshlrev_b32_e32 v30, s68, v38
	s_waitcnt lgkmcnt(0)
	v_add_f32_e32 v36, v36, v37
	s_nop 1
	v_mov_b32_dpp v37, v36 quad_perm:[2,3,0,1] row_mask:0xf bank_mask:0xf
	v_cvt_pk_bf16_f32 v40, v31, s0
	v_ashrrev_i32_e32 v31, 31, v30
	v_cvt_pk_bf16_f32 v35, v35, s0
	v_lshl_add_u64 v[30:31], v[30:31], 1, v[28:29]
	s_waitcnt lgkmcnt(0)
	v_add_f32_e32 v36, v36, v37
	s_nop 1
	v_mov_b32_dpp v37, v36 row_half_mirror row_mask:0xf bank_mask:0xf
	global_store_short v[30:31], v35, off sc1
	global_store_short v[30:31], v39, off offset:64 sc1
	global_store_short v[30:31], v40, off offset:128 sc1
	global_store_short v[30:31], v41, off offset:192 sc1
	s_and_b64 vcc, exec, s[0:1]
	s_waitcnt lgkmcnt(0)
	v_add_f32_e32 v36, v36, v37
	s_nop 1
	v_mov_b32_dpp v37, v36 row_mirror row_mask:0xf bank_mask:0xf
	s_waitcnt lgkmcnt(0)
	v_add_f32_e32 v34, v36, v37
	ds_bpermute_b32 v36, v43, v34
	s_waitcnt lgkmcnt(0)
	v_add_f32_e32 v34, v34, v36
	v_fmamk_f32 v34, v34, 0x3c000000, v166
	v_rsq_f32_e32 v34, v34
	s_nop 0
	v_pk_mul_f32 v[30:31], v[12:13], v[34:35] op_sel_hi:[1,0]
	v_pk_mul_f32 v[34:35], v[14:15], v[34:35] op_sel_hi:[1,0]
	v_pk_mul_f32 v[30:31], v[24:25], v[30:31]
	v_pk_mul_f32 v[24:25], v[32:33], v[34:35]
	s_cbranch_vccnz .LBB0_1232
	v_add_lshl_u32 v32, s66, v150, 8
	v_ashrrev_i32_e32 v33, 31, v32
	v_lshl_add_u64 v[32:33], v[32:33], 2, v[26:27]
	global_store_dword v[32:33], v31, off sc1
	global_store_dword v[32:33], v30, off offset:128 sc1
	global_store_dword v[32:33], v25, off offset:256 sc1
	global_store_dword v[32:33], v24, off offset:384 sc1

.LBB0_1234:
	v_pk_mul_f32 v[32:33], v[20:21], v[20:21]
	v_pk_mul_f32 v[34:35], v[22:23], v[22:23]
	v_add_f32_e32 v32, v33, v32
	v_add_f32_e32 v32, v32, v35
	v_add_f32_e32 v32, v32, v34
	s_nop 1
	v_mov_b32_dpp v33, v32 quad_perm:[1,0,3,2] row_mask:0xf bank_mask:0xf
	v_cvt_pk_bf16_f32 v35, v30, s0
	v_add_u32_e32 v34, s8, v150
	v_cvt_pk_bf16_f32 v37, v24, s0
	v_lshlrev_b32_e32 v24, s68, v34
	s_waitcnt lgkmcnt(0)
	v_add_f32_e32 v32, v32, v33
	s_nop 1
	v_mov_b32_dpp v33, v32 quad_perm:[2,3,0,1] row_mask:0xf bank_mask:0xf
	v_cvt_pk_bf16_f32 v36, v25, s0
	v_ashrrev_i32_e32 v25, 31, v24
	v_cvt_pk_bf16_f32 v31, v31, s0
	v_lshl_add_u64 v[24:25], v[24:25], 1, v[28:29]
	s_waitcnt lgkmcnt(0)
	v_add_f32_e32 v32, v32, v33
	s_nop 1
	v_mov_b32_dpp v33, v32 row_half_mirror row_mask:0xf bank_mask:0xf
	global_store_short v[24:25], v31, off sc1
	global_store_short v[24:25], v35, off offset:64 sc1
	global_store_short v[24:25], v36, off offset:128 sc1
	global_store_short v[24:25], v37, off offset:192 sc1
	s_and_b64 vcc, exec, s[0:1]
	s_waitcnt lgkmcnt(0)
	v_add_f32_e32 v32, v32, v33
	s_nop 1
	v_mov_b32_dpp v33, v32 row_mirror row_mask:0xf bank_mask:0xf
	s_waitcnt lgkmcnt(0)
	v_add_f32_e32 v30, v32, v33
	ds_bpermute_b32 v32, v43, v30
	s_waitcnt lgkmcnt(0)
	v_add_f32_e32 v30, v30, v32
	v_fmamk_f32 v30, v30, 0x3c000000, v166
	v_rsq_f32_e32 v30, v30
	s_nop 0
	v_pk_mul_f32 v[24:25], v[12:13], v[30:31] op_sel_hi:[1,0]
	v_pk_mul_f32 v[30:31], v[14:15], v[30:31] op_sel_hi:[1,0]
	v_pk_mul_f32 v[24:25], v[20:21], v[24:25]
	v_pk_mul_f32 v[20:21], v[22:23], v[30:31]
	s_cbranch_vccnz .LBB0_1236
	v_add_lshl_u32 v22, s66, v151, 8
	v_ashrrev_i32_e32 v23, 31, v22
	v_lshl_add_u64 v[22:23], v[22:23], 2, v[26:27]
	global_store_dword v[22:23], v25, off sc1
	global_store_dword v[22:23], v24, off offset:128 sc1
	global_store_dword v[22:23], v21, off offset:256 sc1
	global_store_dword v[22:23], v20, off offset:384 sc1

.LBB0_1238:
	v_pk_mul_f32 v[22:23], v[16:17], v[16:17]
	v_pk_mul_f32 v[30:31], v[18:19], v[18:19]
	v_add_f32_e32 v22, v23, v22
	v_add_f32_e32 v22, v22, v31
	v_add_f32_e32 v22, v22, v30
	s_nop 1
	v_mov_b32_dpp v23, v22 quad_perm:[1,0,3,2] row_mask:0xf bank_mask:0xf
	v_add_u32_e32 v30, s8, v151
	v_cvt_pk_bf16_f32 v32, v20, s0
	v_lshlrev_b32_e32 v20, s68, v30
	v_cvt_pk_bf16_f32 v31, v21, s0
	s_waitcnt lgkmcnt(0)
	v_add_f32_e32 v22, v22, v23
	s_nop 1
	v_mov_b32_dpp v23, v22 quad_perm:[2,3,0,1] row_mask:0xf bank_mask:0xf
	v_ashrrev_i32_e32 v21, 31, v20
	v_cvt_pk_bf16_f32 v25, v25, s0
	v_cvt_pk_bf16_f32 v24, v24, s0
	v_lshl_add_u64 v[20:21], v[20:21], 1, v[28:29]
	s_waitcnt lgkmcnt(0)
	v_add_f32_e32 v22, v22, v23
	s_nop 1
	v_mov_b32_dpp v23, v22 row_half_mirror row_mask:0xf bank_mask:0xf
	global_store_short v[20:21], v25, off sc1
	global_store_short v[20:21], v24, off offset:64 sc1
	global_store_short v[20:21], v31, off offset:128 sc1
	global_store_short v[20:21], v32, off offset:192 sc1
	s_and_b64 vcc, exec, s[0:1]
	s_waitcnt lgkmcnt(0)
	v_add_f32_e32 v22, v22, v23
	s_nop 1
	v_mov_b32_dpp v23, v22 row_mirror row_mask:0xf bank_mask:0xf
	s_waitcnt lgkmcnt(0)
	v_add_f32_e32 v22, v22, v23
	ds_bpermute_b32 v23, v43, v22
	s_waitcnt lgkmcnt(0)
	v_add_f32_e32 v22, v22, v23
	v_fmamk_f32 v22, v22, 0x3c000000, v166
	v_rsq_f32_e32 v22, v22
	s_nop 0
	v_pk_mul_f32 v[20:21], v[12:13], v[22:23] op_sel_hi:[1,0]
	v_pk_mul_f32 v[22:23], v[14:15], v[22:23] op_sel_hi:[1,0]
	v_pk_mul_f32 v[20:21], v[16:17], v[20:21]
	v_pk_mul_f32 v[16:17], v[18:19], v[22:23]
	s_cbranch_vccnz .LBB0_1240
	v_add_lshl_u32 v18, s66, v152, 8
	v_ashrrev_i32_e32 v19, 31, v18
	v_lshl_add_u64 v[18:19], v[18:19], 2, v[26:27]
	global_store_dword v[18:19], v21, off sc1
	global_store_dword v[18:19], v20, off offset:128 sc1
	global_store_dword v[18:19], v17, off offset:256 sc1
	global_store_dword v[18:19], v16, off offset:384 sc1

.LBB0_1242:
	v_pk_mul_f32 v[18:19], v[8:9], v[8:9]
	v_pk_mul_f32 v[22:23], v[10:11], v[10:11]
	v_add_f32_e32 v18, v19, v18
	v_add_f32_e32 v18, v18, v23
	v_add_f32_e32 v18, v18, v22
	s_nop 1
	v_mov_b32_dpp v19, v18 quad_perm:[1,0,3,2] row_mask:0xf bank_mask:0xf
	v_add_u32_e32 v22, s8, v152
	v_cvt_pk_bf16_f32 v24, v16, s0
	v_lshlrev_b32_e32 v16, s68, v22
	v_cvt_pk_bf16_f32 v23, v17, s0
	s_waitcnt lgkmcnt(0)
	v_add_f32_e32 v18, v18, v19
	s_nop 1
	v_mov_b32_dpp v19, v18 quad_perm:[2,3,0,1] row_mask:0xf bank_mask:0xf
	v_ashrrev_i32_e32 v17, 31, v16
	v_cvt_pk_bf16_f32 v21, v21, s0
	v_cvt_pk_bf16_f32 v20, v20, s0
	v_lshl_add_u64 v[16:17], v[16:17], 1, v[28:29]
	s_waitcnt lgkmcnt(0)
	v_add_f32_e32 v18, v18, v19
	s_nop 1
	v_mov_b32_dpp v19, v18 row_half_mirror row_mask:0xf bank_mask:0xf
	global_store_short v[16:17], v21, off sc1
	global_store_short v[16:17], v20, off offset:64 sc1
	global_store_short v[16:17], v23, off offset:128 sc1
	global_store_short v[16:17], v24, off offset:192 sc1
	s_and_b64 vcc, exec, s[0:1]
	s_waitcnt lgkmcnt(0)
	v_add_f32_e32 v18, v18, v19
	s_nop 1
	v_mov_b32_dpp v19, v18 row_mirror row_mask:0xf bank_mask:0xf
	s_waitcnt lgkmcnt(0)
	v_add_f32_e32 v18, v18, v19
	ds_bpermute_b32 v19, v43, v18
	s_waitcnt lgkmcnt(0)
	v_add_f32_e32 v18, v18, v19
	v_fmamk_f32 v18, v18, 0x3c000000, v166
	v_rsq_f32_e32 v18, v18
	s_nop 0
	v_pk_mul_f32 v[16:17], v[12:13], v[18:19] op_sel_hi:[1,0]
	v_pk_mul_f32 v[18:19], v[14:15], v[18:19] op_sel_hi:[1,0]
	v_pk_mul_f32 v[16:17], v[8:9], v[16:17]
	v_pk_mul_f32 v[8:9], v[10:11], v[18:19]
	s_cbranch_vccnz .LBB0_1244
	v_add_lshl_u32 v10, s66, v153, 8
	v_ashrrev_i32_e32 v11, 31, v10
	v_lshl_add_u64 v[10:11], v[10:11], 2, v[26:27]
	global_store_dword v[10:11], v17, off sc1
	global_store_dword v[10:11], v16, off offset:128 sc1
	global_store_dword v[10:11], v9, off offset:256 sc1
	global_store_dword v[10:11], v8, off offset:384 sc1

.LBB0_1246:
	v_pk_mul_f32 v[10:11], v[4:5], v[4:5]
	v_pk_mul_f32 v[18:19], v[6:7], v[6:7]
	v_add_f32_e32 v10, v11, v10
	v_add_f32_e32 v10, v10, v19
	v_add_f32_e32 v10, v10, v18
	s_nop 1
	v_mov_b32_dpp v11, v10 quad_perm:[1,0,3,2] row_mask:0xf bank_mask:0xf
	v_add_u32_e32 v18, s8, v153
	v_cvt_pk_bf16_f32 v20, v8, s0
	v_lshlrev_b32_e32 v8, s68, v18
	v_cvt_pk_bf16_f32 v19, v9, s0
	s_waitcnt lgkmcnt(0)
	v_add_f32_e32 v10, v10, v11
	s_nop 1
	v_mov_b32_dpp v11, v10 quad_perm:[2,3,0,1] row_mask:0xf bank_mask:0xf
	v_ashrrev_i32_e32 v9, 31, v8
	v_cvt_pk_bf16_f32 v17, v17, s0
	v_cvt_pk_bf16_f32 v16, v16, s0
	v_lshl_add_u64 v[8:9], v[8:9], 1, v[28:29]
	s_waitcnt lgkmcnt(0)
	v_add_f32_e32 v10, v10, v11
	s_nop 1
	v_mov_b32_dpp v11, v10 row_half_mirror row_mask:0xf bank_mask:0xf
	global_store_short v[8:9], v17, off sc1
	global_store_short v[8:9], v16, off offset:64 sc1
	global_store_short v[8:9], v19, off offset:128 sc1
	global_store_short v[8:9], v20, off offset:192 sc1
	s_and_b64 vcc, exec, s[0:1]
	s_waitcnt lgkmcnt(0)
	v_add_f32_e32 v10, v10, v11
	s_nop 1
	v_mov_b32_dpp v11, v10 row_mirror row_mask:0xf bank_mask:0xf
	s_waitcnt lgkmcnt(0)
	v_add_f32_e32 v10, v10, v11
	ds_bpermute_b32 v11, v43, v10
	s_waitcnt lgkmcnt(0)
	v_add_f32_e32 v10, v10, v11
	v_fmamk_f32 v10, v10, 0x3c000000, v166
	v_rsq_f32_e32 v10, v10
	s_nop 0
	v_pk_mul_f32 v[8:9], v[12:13], v[10:11] op_sel_hi:[1,0]
	v_pk_mul_f32 v[10:11], v[14:15], v[10:11] op_sel_hi:[1,0]
	v_pk_mul_f32 v[8:9], v[4:5], v[8:9]
	v_pk_mul_f32 v[4:5], v[6:7], v[10:11]
	s_cbranch_vccnz .LBB0_1248
	v_add_lshl_u32 v6, s66, v154, 8
	v_ashrrev_i32_e32 v7, 31, v6
	v_lshl_add_u64 v[6:7], v[6:7], 2, v[26:27]
	global_store_dword v[6:7], v9, off sc1
	global_store_dword v[6:7], v8, off offset:128 sc1
	global_store_dword v[6:7], v5, off offset:256 sc1
	global_store_dword v[6:7], v4, off offset:384 sc1

.LBB0_1250:
	v_pk_mul_f32 v[6:7], v[0:1], v[0:1]
	v_pk_mul_f32 v[10:11], v[2:3], v[2:3]
	v_add_f32_e32 v6, v7, v6
	v_add_f32_e32 v6, v11, v6
	v_add_f32_e32 v6, v10, v6
	s_nop 1
	v_mov_b32_dpp v7, v6 quad_perm:[1,0,3,2] row_mask:0xf bank_mask:0xf
	v_add_u32_e32 v10, s8, v154
	v_cvt_pk_bf16_f32 v16, v4, s0
	v_lshlrev_b32_e32 v4, s68, v10
	v_cvt_pk_bf16_f32 v11, v5, s0
	s_waitcnt lgkmcnt(0)
	v_add_f32_e32 v6, v6, v7
	s_nop 1
	v_mov_b32_dpp v7, v6 quad_perm:[2,3,0,1] row_mask:0xf bank_mask:0xf
	v_ashrrev_i32_e32 v5, 31, v4
	v_cvt_pk_bf16_f32 v9, v9, s0
	v_cvt_pk_bf16_f32 v8, v8, s0
	v_lshl_add_u64 v[4:5], v[4:5], 1, v[28:29]
	s_waitcnt lgkmcnt(0)
	v_add_f32_e32 v6, v6, v7
	s_nop 1
	v_mov_b32_dpp v7, v6 row_half_mirror row_mask:0xf bank_mask:0xf
	global_store_short v[4:5], v9, off sc1
	global_store_short v[4:5], v8, off offset:64 sc1
	global_store_short v[4:5], v11, off offset:128 sc1
	global_store_short v[4:5], v16, off offset:192 sc1
	s_and_b64 vcc, exec, s[0:1]
	s_waitcnt lgkmcnt(0)
	v_add_f32_e32 v6, v6, v7
	s_nop 1
	v_mov_b32_dpp v7, v6 row_mirror row_mask:0xf bank_mask:0xf
	s_waitcnt lgkmcnt(0)
	v_add_f32_e32 v6, v6, v7
	ds_bpermute_b32 v7, v43, v6
	s_waitcnt lgkmcnt(0)
	v_add_f32_e32 v6, v6, v7
	v_fmamk_f32 v6, v6, 0x3c000000, v166
	v_rsq_f32_e32 v6, v6
	s_nop 0
	v_pk_mul_f32 v[4:5], v[12:13], v[6:7] op_sel_hi:[1,0]
	v_pk_mul_f32 v[6:7], v[14:15], v[6:7] op_sel_hi:[1,0]
	v_pk_mul_f32 v[4:5], v[0:1], v[4:5]
	v_pk_mul_f32 v[0:1], v[2:3], v[6:7]
	s_cbranch_vccnz .LBB0_1252
	v_add_lshl_u32 v2, s66, v155, 8
	v_ashrrev_i32_e32 v3, 31, v2
	v_lshl_add_u64 v[2:3], v[2:3], 2, v[26:27]
	global_store_dword v[2:3], v5, off sc1
	global_store_dword v[2:3], v4, off offset:128 sc1
	global_store_dword v[2:3], v1, off offset:256 sc1
	global_store_dword v[2:3], v0, off offset:384 sc1

.LBB0_1326:
	s_add_i32 s58, s66, 0xffffe000
	s_lshr_b32 s58, s58, 12
	s_mulk_i32 s58, 0x1800
	v_mov_b32_e32 v70, s70
	s_add_i32 s58, s58, 0xa800
	ds_read_b64 v[70:71], v70
	s_cmp_gt_i32 s6, 63
	s_cselect_b32 s6, s58, 0x9000
	s_lshl_b64 s[58:59], s[6:7], 2
	s_add_u32 s6, s14, s58
	s_addc_u32 s65, s15, s59
	s_waitcnt lgkmcnt(0)
	v_readfirstlane_b32 s58, v70
	v_readfirstlane_b32 s59, v71
	s_add_u32 s60, s58, 0x2000
	s_addc_u32 s61, s59, 0
	s_lshl_b32 s58, s64, 14
	s_add_i32 s58, s58, 0xa0000
	s_ashr_i32 s59, s58, 31
	s_lshl_b64 s[58:59], s[58:59], 2
	s_add_u32 s58, s10, s58
	s_addc_u32 s59, s11, s59
	s_add_u32 s62, s6, 0x5ba2000
	v_or_b32_e32 v102, s68, v138
	v_add_u32_e32 v70, s66, v139
	s_addc_u32 s63, s65, 0
	v_lshlrev_b32_e32 v188, 10, v70
	v_ashrrev_i32_e32 v103, 31, v102
	s_add_u32 s64, s6, 0x5ba4000
	v_lshlrev_b64 v[72:73], 2, v[102:103]
	v_or_b32_e32 v186, 0x400, v188
	v_or_b32_e32 v185, 0x4400, v188
	v_or_b32_e32 v189, 0x4c00, v188
	v_or_b32_e32 v193, 0x6c00, v188
	s_addc_u32 s65, s65, 0
	v_lshl_add_u64 v[74:75], s[62:63], 0, v[72:73]
	v_add_u32_e32 v132, v188, v102
	v_add_u32_e32 v134, v186, v102
	v_or_b32_e32 v184, 0x800, v188
	v_or_b32_e32 v183, 0xc00, v188
	v_or_b32_e32 v181, 0x2000, v188
	v_or_b32_e32 v179, 0x2400, v188
	v_or_b32_e32 v71, 0x2800, v188
	v_or_b32_e32 v180, 0x2c00, v188
	v_or_b32_e32 v182, 0x4000, v188
	v_add_u32_e32 v112, v185, v102
	v_or_b32_e32 v187, 0x4800, v188
	v_add_u32_e32 v118, v189, v102
	v_or_b32_e32 v190, 0x6000, v188
	v_or_b32_e32 v191, 0x6400, v188
	v_or_b32_e32 v192, 0x6800, v188
	v_add_u32_e32 v128, v193, v102
	global_load_dword v194, v[74:75], off
	v_lshl_add_u64 v[74:75], s[60:61], 0, v[72:73]
	v_lshl_add_u64 v[72:73], s[64:65], 0, v[72:73]
	v_ashrrev_i32_e32 v135, 31, v134
	v_add_u32_e32 v136, v184, v102
	v_add_u32_e32 v130, v183, v102
	v_add_u32_e32 v122, v181, v102
	v_add_u32_e32 v114, v179, v102
	v_add_u32_e32 v106, v71, v102
	v_add_u32_e32 v108, v180, v102
	v_add_u32_e32 v110, v182, v102
	v_ashrrev_i32_e32 v113, 31, v112
	v_add_u32_e32 v116, v187, v102
	v_ashrrev_i32_e32 v119, 31, v118
	v_add_u32_e32 v120, v190, v102
	v_add_u32_e32 v124, v191, v102
	v_add_u32_e32 v126, v192, v102
	v_ashrrev_i32_e32 v129, 31, v128
	v_ashrrev_i32_e32 v133, 31, v132
	global_load_dword v196, v[72:73], off
	v_lshl_add_u64 v[88:89], v[134:135], 2, s[12:13]
	v_ashrrev_i32_e32 v137, 31, v136
	v_ashrrev_i32_e32 v131, 31, v130
	v_ashrrev_i32_e32 v123, 31, v122
	v_ashrrev_i32_e32 v115, 31, v114
	v_ashrrev_i32_e32 v107, 31, v106
	v_ashrrev_i32_e32 v109, 31, v108
	v_ashrrev_i32_e32 v111, 31, v110
	v_lshl_add_u64 v[86:87], v[112:113], 2, s[12:13]
	v_ashrrev_i32_e32 v117, 31, v116
	v_lshl_add_u64 v[92:93], v[118:119], 2, s[12:13]
	v_ashrrev_i32_e32 v121, 31, v120
	v_ashrrev_i32_e32 v125, 31, v124
	v_ashrrev_i32_e32 v127, 31, v126
	v_lshl_add_u64 v[100:101], v[128:129], 2, s[12:13]
	v_lshl_add_u64 v[104:105], v[132:133], 2, s[12:13]
	global_load_dword v195, v[74:75], off
	v_lshl_add_u64 v[84:85], v[136:137], 2, s[12:13]
	v_lshl_add_u64 v[82:83], v[130:131], 2, s[12:13]
	v_lshl_add_u64 v[78:79], v[122:123], 2, s[12:13]
	v_lshl_add_u64 v[72:73], v[114:115], 2, s[12:13]
	v_lshl_add_u64 v[74:75], v[106:107], 2, s[12:13]
	v_lshl_add_u64 v[76:77], v[108:109], 2, s[12:13]
	v_lshl_add_u64 v[80:81], v[110:111], 2, s[12:13]
	global_load_dword v178, v[88:89], off
	global_load_dword v177, v[84:85], off
	global_load_dword v176, v[82:83], off
	global_load_dword v175, v[78:79], off
	global_load_dword v174, v[72:73], off
	global_load_dword v173, v[74:75], off
	global_load_dword v172, v[76:77], off
	global_load_dword v171, v[80:81], off
	v_lshl_add_u64 v[90:91], v[116:117], 2, s[12:13]
	global_load_dword v170, v[86:87], off
	global_load_dword v168, v[90:91], off
	v_lshl_add_u64 v[94:95], v[120:121], 2, s[12:13]
	v_lshl_add_u64 v[96:97], v[124:125], 2, s[12:13]
	v_lshl_add_u64 v[98:99], v[126:127], 2, s[12:13]
	global_load_dword v169, v[92:93], off
	global_load_dword v167, v[94:95], off
	global_load_dword v166, v[96:97], off
	global_load_dword v165, v[98:99], off
	global_load_dword v103, v[100:101], off
	global_load_dword v197, v[104:105], off
	v_lshl_add_u64 v[106:107], v[106:107], 1, s[8:9]
	s_waitcnt vmcnt(0)
	v_add_f32_e32 v196, 1.0, v196
	v_mul_f32_e32 v195, v195, v196
	v_fmac_f32_e32 v178, v49, v194
	v_fmac_f32_e32 v177, v50, v194
	v_fmac_f32_e32 v176, v51, v194
	v_fmac_f32_e32 v175, v52, v194
	v_fmac_f32_e32 v174, v53, v194
	v_fmac_f32_e32 v173, v54, v194
	v_fmac_f32_e32 v172, v55, v194
	v_fmac_f32_e32 v171, v56, v194
	v_fmac_f32_e32 v170, v57, v194
	v_fmac_f32_e32 v168, v58, v194
	v_fmac_f32_e32 v169, v59, v194
	v_fmac_f32_e32 v167, v60, v194
	v_fmac_f32_e32 v166, v61, v194
	v_fmac_f32_e32 v165, v62, v194
	v_fmac_f32_e32 v103, v63, v194
	v_fmac_f32_e32 v197, v48, v194
	v_mul_f32_e32 v48, v195, v197
	v_cvt_pk_bf16_f32 v58, v48, s0
	v_or_b32_e32 v48, 32, v102
	v_ashrrev_i32_e32 v49, 31, v48
	v_lshlrev_b64 v[52:53], 2, v[48:49]
	global_store_dword v[88:89], v178, off sc1
	global_store_dword v[84:85], v177, off sc1
	global_store_dword v[82:83], v176, off sc1
	global_store_dword v[78:79], v175, off sc1
	global_store_dword v[72:73], v174, off sc1
	global_store_dword v[74:75], v173, off sc1
	global_store_dword v[76:77], v172, off sc1
	global_store_dword v[80:81], v171, off sc1
	global_store_dword v[86:87], v170, off sc1
	global_store_dword v[90:91], v168, off sc1
	global_store_dword v[92:93], v169, off sc1
	global_store_dword v[94:95], v167, off sc1
	global_store_dword v[96:97], v166, off sc1
	global_store_dword v[98:99], v165, off sc1
	global_store_dword v[100:101], v103, off sc1
	global_store_dword v[104:105], v197, off sc1
	v_lshl_add_u64 v[50:51], v[132:133], 1, s[8:9]
	v_lshl_add_u64 v[56:57], s[64:65], 0, v[52:53]
	global_load_dword v196, v[104:105], off offset:128
	v_lshl_add_u64 v[54:55], s[60:61], 0, v[52:53]
	global_load_dword v132, v[56:57], off
	global_load_dword v133, v[54:55], off
	v_mul_f32_e32 v49, v195, v178
	global_store_short v[50:51], v58, off sc1
	v_lshl_add_u64 v[50:51], s[62:63], 0, v[52:53]
	global_load_dword v194, v[50:51], off
	v_cvt_pk_bf16_f32 v49, v49, s0
	v_lshl_add_u64 v[50:51], v[134:135], 1, s[8:9]
	global_store_short v[50:51], v49, off sc1
	v_mul_f32_e32 v49, v195, v177
	v_cvt_pk_bf16_f32 v49, v49, s0
	v_lshl_add_u64 v[50:51], v[136:137], 1, s[8:9]
	global_store_short v[50:51], v49, off sc1
	v_mul_f32_e32 v49, v195, v176
	v_cvt_pk_bf16_f32 v49, v49, s0
	v_lshl_add_u64 v[50:51], v[130:131], 1, s[8:9]
	global_store_short v[50:51], v49, off sc1
	v_mul_f32_e32 v49, v195, v175
	v_cvt_pk_bf16_f32 v49, v49, s0
	v_lshl_add_u64 v[50:51], v[122:123], 1, s[8:9]
	global_store_short v[50:51], v49, off sc1
	v_mul_f32_e32 v49, v195, v174
	v_cvt_pk_bf16_f32 v49, v49, s0
	v_lshl_add_u64 v[50:51], v[114:115], 1, s[8:9]
	global_store_short v[50:51], v49, off sc1
	v_mul_f32_e32 v49, v195, v173
	global_load_dword v62, v[84:85], off offset:128
	global_load_dword v60, v[78:79], off offset:128
	global_load_dword v59, v[72:73], off offset:128
	global_load_dword v58, v[74:75], off offset:128
	global_load_dword v56, v[80:81], off offset:128
	global_load_dword v57, v[76:77], off offset:128
	global_load_dword v55, v[86:87], off offset:128
	global_load_dword v61, v[82:83], off offset:128
	global_load_dword v54, v[90:91], off offset:128
	global_load_dword v53, v[92:93], off offset:128
	global_load_dword v52, v[94:95], off offset:128
	global_load_dword v51, v[96:97], off offset:128
	global_load_dword v50, v[98:99], off offset:128
	v_cvt_pk_bf16_f32 v63, v49, s0
	global_load_dword v49, v[100:101], off offset:128
	s_waitcnt vmcnt(19)
	v_fmac_f32_e32 v196, v32, v194
	global_store_short v[106:107], v63, off sc1
	global_load_dword v63, v[88:89], off offset:128
	v_mul_f32_e32 v106, v195, v172
	v_cvt_pk_bf16_f32 v114, v106, s0
	v_lshl_add_u64 v[106:107], v[108:109], 1, s[8:9]
	global_store_short v[106:107], v114, off sc1
	v_mul_f32_e32 v106, v195, v171
	v_cvt_pk_bf16_f32 v108, v106, s0
	v_lshl_add_u64 v[106:107], v[110:111], 1, s[8:9]
	global_store_short v[106:107], v108, off sc1
	v_mul_f32_e32 v106, v195, v170
	v_cvt_pk_bf16_f32 v108, v106, s0
	v_lshl_add_u64 v[106:107], v[112:113], 1, s[8:9]
	global_store_short v[106:107], v108, off sc1
	v_mul_f32_e32 v106, v195, v168
	v_cvt_pk_bf16_f32 v108, v106, s0
	v_lshl_add_u64 v[106:107], v[116:117], 1, s[8:9]
	global_store_short v[106:107], v108, off sc1
	v_mul_f32_e32 v106, v195, v169
	v_cvt_pk_bf16_f32 v108, v106, s0
	v_lshl_add_u64 v[106:107], v[118:119], 1, s[8:9]
	global_store_short v[106:107], v108, off sc1
	v_mul_f32_e32 v106, v195, v167
	v_cvt_pk_bf16_f32 v108, v106, s0
	v_lshl_add_u64 v[106:107], v[120:121], 1, s[8:9]
	global_store_short v[106:107], v108, off sc1
	v_mul_f32_e32 v106, v195, v166
	v_cvt_pk_bf16_f32 v108, v106, s0
	v_lshl_add_u64 v[106:107], v[124:125], 1, s[8:9]
	global_store_short v[106:107], v108, off sc1
	v_mul_f32_e32 v106, v195, v165
	v_cvt_pk_bf16_f32 v108, v106, s0
	v_lshl_add_u64 v[106:107], v[126:127], 1, s[8:9]
	global_store_short v[106:107], v108, off sc1
	v_mul_f32_e32 v106, v195, v103
	v_cvt_pk_bf16_f32 v108, v106, s0
	v_lshl_add_u64 v[106:107], v[128:129], 1, s[8:9]
	global_store_short v[106:107], v108, off sc1
	v_add_f32_e32 v106, 1.0, v132
	v_mul_f32_e32 v110, v133, v106
	v_add_u32_e32 v106, v188, v48
	s_waitcnt vmcnt(24)
	v_fmac_f32_e32 v62, v34, v194
	s_waitcnt vmcnt(17)
	v_fmac_f32_e32 v61, v35, v194
	v_fmac_f32_e32 v60, v36, v194
	v_fmac_f32_e32 v59, v37, v194
	v_fmac_f32_e32 v58, v38, v194
	v_fmac_f32_e32 v57, v39, v194
	v_fmac_f32_e32 v56, v40, v194
	v_fmac_f32_e32 v55, v41, v194
	s_waitcnt vmcnt(16)
	v_fmac_f32_e32 v54, v42, v194
	s_waitcnt vmcnt(15)
	v_fmac_f32_e32 v53, v43, v194
	s_waitcnt vmcnt(14)
	v_fmac_f32_e32 v52, v44, v194
	s_waitcnt vmcnt(13)
	v_fmac_f32_e32 v51, v45, v194
	s_waitcnt vmcnt(12)
	v_fmac_f32_e32 v50, v46, v194
	s_waitcnt vmcnt(11)
	v_fmac_f32_e32 v49, v47, v194
	v_ashrrev_i32_e32 v107, 31, v106
	global_store_dword v[104:105], v196, off offset:128 sc1
	v_mul_f32_e32 v32, v110, v196
	global_store_dword v[84:85], v62, off offset:128 sc1
	global_store_dword v[82:83], v61, off offset:128 sc1
	global_store_dword v[78:79], v60, off offset:128 sc1
	global_store_dword v[72:73], v59, off offset:128 sc1
	global_store_dword v[74:75], v58, off offset:128 sc1
	global_store_dword v[76:77], v57, off offset:128 sc1
	global_store_dword v[80:81], v56, off offset:128 sc1
	global_store_dword v[86:87], v55, off offset:128 sc1
	global_store_dword v[90:91], v54, off offset:128 sc1
	global_store_dword v[92:93], v53, off offset:128 sc1
	global_store_dword v[94:95], v52, off offset:128 sc1
	global_store_dword v[96:97], v51, off offset:128 sc1
	global_store_dword v[98:99], v50, off offset:128 sc1
	global_store_dword v[100:101], v49, off offset:128 sc1
	v_cvt_pk_bf16_f32 v32, v32, s0
	v_lshl_add_u64 v[106:107], v[106:107], 1, s[8:9]
	v_add_u32_e32 v108, v186, v48
	global_load_dword v45, v[88:89], off offset:256
	v_ashrrev_i32_e32 v109, 31, v108
	global_store_short v[106:107], v32, off sc1
	v_mul_f32_e32 v113, v110, v56
	v_cvt_pk_bf16_f32 v113, v113, s0
	v_mul_f32_e32 v106, v196, v196
	s_waitcnt vmcnt(26)
	v_fmac_f32_e32 v63, v33, v194
	v_mul_f32_e32 v32, v110, v63
	v_cvt_pk_bf16_f32 v34, v32, s0
	v_lshl_add_u64 v[32:33], v[108:109], 1, s[8:9]
	global_store_short v[32:33], v34, off sc1
	v_add_u32_e32 v32, v184, v48
	v_ashrrev_i32_e32 v33, 31, v32
	v_mul_f32_e32 v34, v110, v62
	v_cvt_pk_bf16_f32 v34, v34, s0
	v_lshl_add_u64 v[32:33], v[32:33], 1, s[8:9]
	global_store_short v[32:33], v34, off sc1
	v_add_u32_e32 v32, v183, v48
	v_ashrrev_i32_e32 v33, 31, v32
	v_mul_f32_e32 v34, v110, v61
	v_cvt_pk_bf16_f32 v34, v34, s0
	v_lshl_add_u64 v[32:33], v[32:33], 1, s[8:9]
	global_store_short v[32:33], v34, off sc1
	v_add_u32_e32 v32, v181, v48
	v_ashrrev_i32_e32 v33, 31, v32
	v_mul_f32_e32 v34, v110, v60
	v_cvt_pk_bf16_f32 v34, v34, s0
	v_lshl_add_u64 v[32:33], v[32:33], 1, s[8:9]
	global_store_short v[32:33], v34, off sc1
	v_add_u32_e32 v32, v179, v48
	v_ashrrev_i32_e32 v33, 31, v32
	v_mul_f32_e32 v34, v110, v59
	v_cvt_pk_bf16_f32 v42, v34, s0
	v_lshl_add_u64 v[34:35], v[32:33], 1, s[8:9]
	v_or_b32_e32 v32, 64, v102
	v_ashrrev_i32_e32 v33, 31, v32
	v_lshlrev_b64 v[36:37], 2, v[32:33]
	global_store_dword v[88:89], v63, off offset:128 sc1
	v_lshl_add_u64 v[40:41], s[64:65], 0, v[36:37]
	v_lshl_add_u64 v[38:39], s[60:61], 0, v[36:37]
	global_load_dword v107, v[40:41], off
	global_load_dword v111, v[38:39], off
	v_mul_f32_e32 v33, v110, v58
	global_store_short v[34:35], v42, off sc1
	v_lshl_add_u64 v[34:35], s[62:63], 0, v[36:37]
	global_load_dword v112, v[34:35], off
	v_add_u32_e32 v34, v71, v48
	v_ashrrev_i32_e32 v35, 31, v34
	v_cvt_pk_bf16_f32 v33, v33, s0
	v_lshl_add_u64 v[34:35], v[34:35], 1, s[8:9]
	global_store_short v[34:35], v33, off sc1
	v_add_u32_e32 v34, v180, v48
	v_ashrrev_i32_e32 v35, 31, v34
	v_mul_f32_e32 v33, v110, v57
	v_cvt_pk_bf16_f32 v33, v33, s0
	v_lshl_add_u64 v[34:35], v[34:35], 1, s[8:9]
	global_load_dword v38, v[90:91], off offset:256
	global_load_dword v37, v[92:93], off offset:256
	global_load_dword v36, v[94:95], off offset:256
	global_load_dword v114, v[104:105], off offset:256
	global_load_dword v47, v[84:85], off offset:256
	global_load_dword v39, v[86:87], off offset:256
	global_load_dword v46, v[82:83], off offset:256
	global_load_dword v44, v[78:79], off offset:256
	global_load_dword v43, v[72:73], off offset:256
	global_load_dword v42, v[74:75], off offset:256
	global_load_dword v40, v[80:81], off offset:256
	global_load_dword v41, v[76:77], off offset:256
	v_add_u32_e32 v108, v182, v48
	global_store_short v[34:35], v33, off sc1
	global_load_dword v35, v[96:97], off offset:256
	v_ashrrev_i32_e32 v109, 31, v108
	global_load_dword v34, v[98:99], off offset:256
	global_load_dword v33, v[100:101], off offset:256
	v_lshl_add_u64 v[108:109], v[108:109], 1, s[8:9]
	global_store_short v[108:109], v113, off sc1
	v_add_u32_e32 v108, v185, v48
	v_ashrrev_i32_e32 v109, 31, v108
	v_mul_f32_e32 v113, v110, v55
	v_cvt_pk_bf16_f32 v113, v113, s0
	v_lshl_add_u64 v[108:109], v[108:109], 1, s[8:9]
	global_store_short v[108:109], v113, off sc1
	v_add_u32_e32 v108, v187, v48
	v_ashrrev_i32_e32 v109, 31, v108
	v_mul_f32_e32 v113, v110, v54
	v_cvt_pk_bf16_f32 v113, v113, s0
	v_lshl_add_u64 v[108:109], v[108:109], 1, s[8:9]
	global_store_short v[108:109], v113, off sc1
	v_add_u32_e32 v108, v189, v48
	v_ashrrev_i32_e32 v109, 31, v108
	v_mul_f32_e32 v113, v110, v53
	v_cvt_pk_bf16_f32 v113, v113, s0
	v_lshl_add_u64 v[108:109], v[108:109], 1, s[8:9]
	global_store_short v[108:109], v113, off sc1
	v_add_u32_e32 v108, v190, v48
	v_ashrrev_i32_e32 v109, 31, v108
	v_mul_f32_e32 v113, v110, v52
	v_cvt_pk_bf16_f32 v113, v113, s0
	v_lshl_add_u64 v[108:109], v[108:109], 1, s[8:9]
	global_store_short v[108:109], v113, off sc1
	v_add_u32_e32 v108, v191, v48
	v_ashrrev_i32_e32 v109, 31, v108
	v_mul_f32_e32 v113, v110, v51
	v_cvt_pk_bf16_f32 v113, v113, s0
	v_lshl_add_u64 v[108:109], v[108:109], 1, s[8:9]
	global_store_short v[108:109], v113, off sc1
	v_add_u32_e32 v108, v192, v48
	v_ashrrev_i32_e32 v109, 31, v108
	v_mul_f32_e32 v113, v110, v50
	v_cvt_pk_bf16_f32 v113, v113, s0
	v_lshl_add_u64 v[108:109], v[108:109], 1, s[8:9]
	global_store_short v[108:109], v113, off sc1
	v_add_u32_e32 v108, v193, v48
	v_ashrrev_i32_e32 v109, 31, v108
	v_mul_f32_e32 v48, v110, v49
	v_cvt_pk_bf16_f32 v48, v48, s0
	v_lshl_add_u64 v[108:109], v[108:109], 1, s[8:9]
	global_store_short v[108:109], v48, off sc1
	v_add_u32_e32 v108, v188, v32
	v_ashrrev_i32_e32 v109, 31, v108
	s_waitcnt vmcnt(28)
	v_add_f32_e32 v48, 1.0, v107
	s_waitcnt vmcnt(27)
	v_mul_f32_e32 v48, v111, v48
	v_fmac_f32_e32 v106, v197, v197
	s_waitcnt vmcnt(25)
	v_fmac_f32_e32 v45, v17, v112
	global_store_dword v[88:89], v45, off offset:256 sc1
	s_waitcnt vmcnt(24)
	v_fmac_f32_e32 v38, v26, v112
	s_waitcnt vmcnt(23)
	v_fmac_f32_e32 v37, v27, v112
	s_waitcnt vmcnt(22)
	v_fmac_f32_e32 v36, v28, v112
	s_waitcnt vmcnt(21)
	v_fmac_f32_e32 v114, v16, v112
	v_mul_f32_e32 v16, v48, v114
	s_waitcnt vmcnt(20)
	v_fmac_f32_e32 v47, v18, v112
	v_cvt_pk_bf16_f32 v18, v16, s0
	v_lshl_add_u64 v[16:17], v[108:109], 1, s[8:9]
	global_store_short v[16:17], v18, off sc1
	v_add_u32_e32 v16, v186, v32
	v_ashrrev_i32_e32 v17, 31, v16
	v_mul_f32_e32 v18, v48, v45
	v_cvt_pk_bf16_f32 v18, v18, s0
	v_lshl_add_u64 v[16:17], v[16:17], 1, s[8:9]
	global_store_short v[16:17], v18, off sc1
	v_add_u32_e32 v16, v184, v32
	v_ashrrev_i32_e32 v17, 31, v16
	v_mul_f32_e32 v18, v48, v47
	v_cvt_pk_bf16_f32 v18, v18, s0
	v_lshl_add_u64 v[16:17], v[16:17], 1, s[8:9]
	s_waitcnt vmcnt(20)
	v_fmac_f32_e32 v46, v19, v112
	global_store_short v[16:17], v18, off sc1
	v_add_u32_e32 v16, v183, v32
	v_ashrrev_i32_e32 v17, 31, v16
	v_mul_f32_e32 v18, v48, v46
	s_waitcnt vmcnt(20)
	v_fmac_f32_e32 v44, v20, v112
	v_cvt_pk_bf16_f32 v18, v18, s0
	v_lshl_add_u64 v[16:17], v[16:17], 1, s[8:9]
	global_store_short v[16:17], v18, off sc1
	v_mul_f32_e32 v16, v48, v44
	v_cvt_pk_bf16_f32 v26, v16, s0
	v_or_b32_e32 v16, 0x60, v102
	v_add_u32_e32 v18, v181, v32
	v_ashrrev_i32_e32 v17, 31, v16
	s_waitcnt vmcnt(20)
	v_fmac_f32_e32 v43, v21, v112
	s_waitcnt vmcnt(19)
	v_fmac_f32_e32 v42, v22, v112
	s_waitcnt vmcnt(17)
	v_fmac_f32_e32 v41, v23, v112
	v_fmac_f32_e32 v40, v24, v112
	v_fmac_f32_e32 v39, v25, v112
	s_waitcnt vmcnt(15)
	v_fmac_f32_e32 v35, v29, v112
	s_waitcnt vmcnt(14)
	v_fmac_f32_e32 v34, v30, v112
	s_waitcnt vmcnt(13)
	v_fmac_f32_e32 v33, v31, v112
	v_ashrrev_i32_e32 v19, 31, v18
	v_lshlrev_b64 v[20:21], 2, v[16:17]
	global_store_dword v[84:85], v47, off offset:256 sc1
	global_store_dword v[82:83], v46, off offset:256 sc1
	global_store_dword v[78:79], v44, off offset:256 sc1
	global_store_dword v[72:73], v43, off offset:256 sc1
	global_store_dword v[74:75], v42, off offset:256 sc1
	global_store_dword v[76:77], v41, off offset:256 sc1
	global_store_dword v[80:81], v40, off offset:256 sc1
	global_store_dword v[86:87], v39, off offset:256 sc1
	global_store_dword v[90:91], v38, off offset:256 sc1
	global_store_dword v[92:93], v37, off offset:256 sc1
	global_store_dword v[94:95], v36, off offset:256 sc1
	global_store_dword v[96:97], v35, off offset:256 sc1
	global_store_dword v[98:99], v34, off offset:256 sc1
	global_store_dword v[100:101], v33, off offset:256 sc1
	global_store_dword v[104:105], v114, off offset:256 sc1
	v_lshl_add_u64 v[24:25], s[64:65], 0, v[20:21]
	v_lshl_add_u64 v[18:19], v[18:19], 1, s[8:9]
	global_load_dword v29, v[104:105], off offset:384
	v_lshl_add_u64 v[22:23], s[60:61], 0, v[20:21]
	global_load_dword v17, v[24:25], off
	global_load_dword v30, v[22:23], off
	global_load_dword v28, v[88:89], off offset:384
	global_load_dword v27, v[84:85], off offset:384
	v_fmac_f32_e32 v106, v114, v114
	global_store_short v[18:19], v26, off sc1
	v_lshl_add_u64 v[18:19], s[62:63], 0, v[20:21]
	global_load_dword v102, v[18:19], off
	v_add_u32_e32 v18, v179, v32
	v_ashrrev_i32_e32 v19, 31, v18
	v_mul_f32_e32 v20, v48, v43
	v_cvt_pk_bf16_f32 v20, v20, s0
	v_lshl_add_u64 v[18:19], v[18:19], 1, s[8:9]
	global_store_short v[18:19], v20, off sc1
	v_add_u32_e32 v18, v71, v32
	v_ashrrev_i32_e32 v19, 31, v18
	v_mul_f32_e32 v20, v48, v42
	v_cvt_pk_bf16_f32 v20, v20, s0
	v_lshl_add_u64 v[18:19], v[18:19], 1, s[8:9]
	global_store_short v[18:19], v20, off sc1
	v_add_u32_e32 v18, v180, v32
	v_ashrrev_i32_e32 v19, 31, v18
	v_mul_f32_e32 v20, v48, v41
	v_cvt_pk_bf16_f32 v20, v20, s0
	v_lshl_add_u64 v[18:19], v[18:19], 1, s[8:9]
	global_store_short v[18:19], v20, off sc1
	v_add_u32_e32 v18, v182, v32
	v_ashrrev_i32_e32 v19, 31, v18
	v_mul_f32_e32 v20, v48, v40
	v_cvt_pk_bf16_f32 v20, v20, s0
	v_lshl_add_u64 v[18:19], v[18:19], 1, s[8:9]
	global_store_short v[18:19], v20, off sc1
	v_add_u32_e32 v18, v185, v32
	v_ashrrev_i32_e32 v19, 31, v18
	v_mul_f32_e32 v20, v48, v39
	v_cvt_pk_bf16_f32 v20, v20, s0
	v_lshl_add_u64 v[18:19], v[18:19], 1, s[8:9]
	global_store_short v[18:19], v20, off sc1
	v_add_u32_e32 v18, v187, v32
	v_ashrrev_i32_e32 v19, 31, v18
	v_mul_f32_e32 v20, v48, v38
	v_cvt_pk_bf16_f32 v20, v20, s0
	v_lshl_add_u64 v[18:19], v[18:19], 1, s[8:9]
	global_store_short v[18:19], v20, off sc1
	v_add_u32_e32 v18, v189, v32
	v_ashrrev_i32_e32 v19, 31, v18
	v_mul_f32_e32 v20, v48, v37
	v_cvt_pk_bf16_f32 v20, v20, s0
	v_lshl_add_u64 v[18:19], v[18:19], 1, s[8:9]
	global_store_short v[18:19], v20, off sc1
	v_add_u32_e32 v18, v190, v32
	v_ashrrev_i32_e32 v19, 31, v18
	v_mul_f32_e32 v20, v48, v36
	v_cvt_pk_bf16_f32 v20, v20, s0
	v_lshl_add_u64 v[18:19], v[18:19], 1, s[8:9]
	global_store_short v[18:19], v20, off sc1
	v_add_u32_e32 v18, v191, v32
	v_ashrrev_i32_e32 v19, 31, v18
	v_mul_f32_e32 v20, v48, v35
	v_cvt_pk_bf16_f32 v20, v20, s0
	v_lshl_add_u64 v[18:19], v[18:19], 1, s[8:9]
	global_store_short v[18:19], v20, off sc1
	v_add_u32_e32 v18, v192, v32
	v_ashrrev_i32_e32 v19, 31, v18
	v_mul_f32_e32 v20, v48, v34
	v_cvt_pk_bf16_f32 v20, v20, s0
	v_lshl_add_u64 v[18:19], v[18:19], 1, s[8:9]
	global_store_short v[18:19], v20, off sc1
	v_add_u32_e32 v18, v193, v32
	v_ashrrev_i32_e32 v19, 31, v18
	v_mul_f32_e32 v20, v48, v33
	v_cvt_pk_bf16_f32 v20, v20, s0
	v_lshl_add_u64 v[18:19], v[18:19], 1, s[8:9]
	global_store_short v[18:19], v20, off sc1
	global_load_dword v20, v[86:87], off offset:384
	v_add_u32_e32 v18, v188, v16
	global_load_dword v26, v[82:83], off offset:384
	global_load_dword v25, v[78:79], off offset:384
	global_load_dword v24, v[72:73], off offset:384
	global_load_dword v23, v[74:75], off offset:384
	global_load_dword v21, v[80:81], off offset:384
	global_load_dword v22, v[76:77], off offset:384
	s_waitcnt vmcnt(23)
	v_add_f32_e32 v17, 1.0, v17
	s_waitcnt vmcnt(22)
	v_mul_f32_e32 v32, v30, v17
	v_ashrrev_i32_e32 v19, 31, v18
	v_lshl_add_u64 v[18:19], v[18:19], 1, s[8:9]
	v_add_u32_e32 v30, v186, v16
	s_waitcnt vmcnt(18)
	v_fmac_f32_e32 v29, v0, v102
	v_mul_f32_e32 v0, v32, v29
	v_cvt_pk_bf16_f32 v0, v0, s0
	global_store_short v[18:19], v0, off sc1
	global_load_dword v19, v[90:91], off offset:384
	v_ashrrev_i32_e32 v31, 31, v30
	global_load_dword v18, v[92:93], off offset:384
	v_fmac_f32_e32 v28, v1, v102
	v_mul_f32_e32 v0, v32, v28
	v_cvt_pk_bf16_f32 v17, v0, s0
	v_lshl_add_u64 v[0:1], v[30:31], 1, s[8:9]
	global_store_short v[0:1], v17, off sc1
	v_add_u32_e32 v0, v184, v16
	v_fmac_f32_e32 v27, v2, v102
	global_load_dword v17, v[94:95], off offset:384
	v_ashrrev_i32_e32 v1, 31, v0
	v_mul_f32_e32 v2, v32, v27
	v_cvt_pk_bf16_f32 v2, v2, s0
	v_lshl_add_u64 v[0:1], v[0:1], 1, s[8:9]
	global_store_short v[0:1], v2, off sc1
	v_add_u32_e32 v0, v183, v16
	global_load_dword v2, v[96:97], off offset:384
	v_ashrrev_i32_e32 v1, 31, v0
	v_lshl_add_u64 v[0:1], v[0:1], 1, s[8:9]
	v_add_u32_e32 v30, v181, v16
	v_ashrrev_i32_e32 v31, 31, v30
	v_lshl_add_u64 v[30:31], v[30:31], 1, s[8:9]
	v_fmac_f32_e32 v106, v29, v29
	global_store_dword v[104:105], v29, off offset:384 sc1
	global_store_dword v[88:89], v28, off offset:384 sc1
	global_store_dword v[84:85], v27, off offset:384 sc1
	s_waitcnt vmcnt(16)
	v_fmac_f32_e32 v20, v9, v102
	global_store_dword v[86:87], v20, off offset:384 sc1
	s_waitcnt vmcnt(16)
	v_fmac_f32_e32 v26, v3, v102
	v_mul_f32_e32 v3, v32, v26
	v_cvt_pk_bf16_f32 v3, v3, s0
	global_store_short v[0:1], v3, off sc1
	global_load_dword v1, v[98:99], off offset:384
	s_waitcnt vmcnt(17)
	v_fmac_f32_e32 v25, v4, v102
	v_mul_f32_e32 v0, v32, v25
	v_cvt_pk_bf16_f32 v0, v0, s0
	global_store_short v[30:31], v0, off sc1
	global_load_dword v0, v[100:101], off offset:384
	v_add_u32_e32 v30, v179, v16
	s_waitcnt vmcnt(18)
	v_fmac_f32_e32 v24, v5, v102
	v_ashrrev_i32_e32 v31, 31, v30
	v_mul_f32_e32 v3, v32, v24
	v_cvt_pk_bf16_f32 v3, v3, s0
	v_lshl_add_u64 v[4:5], v[30:31], 1, s[8:9]
	global_store_short v[4:5], v3, off sc1
	v_add_u32_e32 v4, v71, v16
	s_waitcnt vmcnt(18)
	v_fmac_f32_e32 v23, v6, v102
	v_ashrrev_i32_e32 v5, 31, v4
	v_mul_f32_e32 v3, v32, v23
	v_cvt_pk_bf16_f32 v3, v3, s0
	v_lshl_add_u64 v[4:5], v[4:5], 1, s[8:9]
	global_store_short v[4:5], v3, off sc1
	v_add_u32_e32 v4, v180, v16
	s_waitcnt vmcnt(17)
	v_fmac_f32_e32 v22, v7, v102
	v_ashrrev_i32_e32 v5, 31, v4
	v_mul_f32_e32 v3, v32, v22
	v_cvt_pk_bf16_f32 v3, v3, s0
	v_lshl_add_u64 v[4:5], v[4:5], 1, s[8:9]
	global_store_short v[4:5], v3, off sc1
	v_add_u32_e32 v4, v182, v16
	v_fmac_f32_e32 v21, v8, v102
	v_ashrrev_i32_e32 v5, 31, v4
	v_mul_f32_e32 v3, v32, v21
	v_cvt_pk_bf16_f32 v3, v3, s0
	v_lshl_add_u64 v[4:5], v[4:5], 1, s[8:9]
	global_store_short v[4:5], v3, off sc1
	v_add_u32_e32 v4, v185, v16
	v_ashrrev_i32_e32 v5, 31, v4
	v_mul_f32_e32 v3, v32, v20
	v_cvt_pk_bf16_f32 v3, v3, s0
	v_lshl_add_u64 v[4:5], v[4:5], 1, s[8:9]
	global_store_short v[4:5], v3, off sc1
	v_add_u32_e32 v4, v187, v16
	s_waitcnt vmcnt(18)
	v_fmac_f32_e32 v19, v10, v102
	v_ashrrev_i32_e32 v5, 31, v4
	v_mul_f32_e32 v3, v32, v19
	v_cvt_pk_bf16_f32 v3, v3, s0
	v_lshl_add_u64 v[4:5], v[4:5], 1, s[8:9]
	global_store_short v[4:5], v3, off sc1
	v_add_u32_e32 v4, v189, v16
	s_waitcnt vmcnt(18)
	v_fmac_f32_e32 v18, v11, v102
	v_ashrrev_i32_e32 v5, 31, v4
	v_mul_f32_e32 v3, v32, v18
	v_cvt_pk_bf16_f32 v3, v3, s0
	v_lshl_add_u64 v[4:5], v[4:5], 1, s[8:9]
	global_store_short v[4:5], v3, off sc1
	v_add_u32_e32 v4, v190, v16
	s_waitcnt vmcnt(17)
	v_fmac_f32_e32 v17, v12, v102
	v_ashrrev_i32_e32 v5, 31, v4
	v_mul_f32_e32 v3, v32, v17
	v_cvt_pk_bf16_f32 v3, v3, s0
	v_lshl_add_u64 v[4:5], v[4:5], 1, s[8:9]
	global_store_short v[4:5], v3, off sc1
	v_add_u32_e32 v4, v191, v16
	s_waitcnt vmcnt(16)
	v_fmac_f32_e32 v2, v13, v102
	v_ashrrev_i32_e32 v5, 31, v4
	v_mul_f32_e32 v3, v32, v2
	v_cvt_pk_bf16_f32 v3, v3, s0
	v_lshl_add_u64 v[4:5], v[4:5], 1, s[8:9]
	global_store_short v[4:5], v3, off sc1
	v_add_u32_e32 v4, v192, v16
	v_ashrrev_i32_e32 v5, 31, v4
	v_lshl_add_u64 v[4:5], v[4:5], 1, s[8:9]
	v_xor_b32_e32 v13, 16, v164
	v_add_u32_e32 v10, v193, v16
	v_ashrrev_i32_e32 v11, 31, v10
	v_lshl_add_u64 v[10:11], v[10:11], 1, s[8:9]
	v_ashrrev_i32_e32 v71, 31, v70
	global_store_dword v[82:83], v26, off offset:384 sc1
	global_store_dword v[78:79], v25, off offset:384 sc1
	global_store_dword v[72:73], v24, off offset:384 sc1
	global_store_dword v[74:75], v23, off offset:384 sc1
	s_waitcnt vmcnt(15)
	v_fmac_f32_e32 v1, v14, v102
	v_mul_f32_e32 v3, v32, v1
	v_cvt_pk_bf16_f32 v3, v3, s0
	global_store_short v[4:5], v3, off sc1
	v_and_b32_e32 v4, 64, v164
	v_xor_b32_e32 v3, 1, v164
	v_add_u32_e32 v7, 64, v4
	v_cmp_lt_i32_e32 vcc, v3, v7
	v_xor_b32_e32 v4, 2, v164
	s_waitcnt vmcnt(14)
	v_fmac_f32_e32 v0, v15, v102
	v_cndmask_b32_e32 v3, v164, v3, vcc
	v_lshlrev_b32_e32 v3, 2, v3
	s_nop 1
	v_mov_b32_dpp v5, v106 quad_perm:[1,0,3,2] row_mask:0xf bank_mask:0xf
	v_cmp_lt_i32_e32 vcc, v4, v7
	v_mul_f32_e32 v12, v32, v0
	v_cvt_pk_bf16_f32 v12, v12, s0
	v_cndmask_b32_e32 v4, v164, v4, vcc
	v_lshlrev_b32_e32 v4, 2, v4
	s_waitcnt lgkmcnt(0)
	v_add_f32_e32 v6, v106, v5
	s_nop 1
	v_mov_b32_dpp v8, v6 quad_perm:[2,3,0,1] row_mask:0xf bank_mask:0xf
	v_xor_b32_e32 v5, 4, v164
	v_cmp_lt_i32_e32 vcc, v5, v7
	global_store_dword v[76:77], v22, off offset:384 sc1
	global_store_dword v[80:81], v21, off offset:384 sc1
	v_cndmask_b32_e32 v5, v164, v5, vcc
	v_lshlrev_b32_e32 v5, 2, v5
	s_waitcnt lgkmcnt(0)
	v_add_f32_e32 v8, v6, v8
	s_nop 1
	v_mov_b32_dpp v9, v8 row_half_mirror row_mask:0xf bank_mask:0xf
	v_xor_b32_e32 v6, 8, v164
	v_cmp_lt_i32_e32 vcc, v6, v7
	global_store_dword v[90:91], v19, off offset:384 sc1
	global_store_dword v[92:93], v18, off offset:384 sc1
	v_cndmask_b32_e32 v6, v164, v6, vcc
	v_lshlrev_b32_e32 v6, 2, v6
	s_waitcnt lgkmcnt(0)
	v_add_f32_e32 v8, v8, v9
	s_nop 1
	v_mov_b32_dpp v9, v8 row_mirror row_mask:0xf bank_mask:0xf
	v_cmp_lt_i32_e32 vcc, v13, v7
	global_store_dword v[94:95], v17, off offset:384 sc1
	global_store_dword v[96:97], v2, off offset:384 sc1
	v_cndmask_b32_e32 v7, v164, v13, vcc
	v_lshlrev_b32_e32 v7, 2, v7
	s_waitcnt lgkmcnt(0)
	v_add_f32_e32 v8, v8, v9
	ds_bpermute_b32 v9, v7, v8
	global_store_dword v[98:99], v1, off offset:384 sc1
	global_store_dword v[100:101], v0, off offset:384 sc1
	global_store_short v[10:11], v12, off sc1
	s_and_saveexec_b64 s[60:61], s[0:1]
	s_cbranch_execz .LBB0_1328
	s_waitcnt lgkmcnt(0)
	v_add_f32_e32 v10, v8, v9
	v_lshl_add_u64 v[8:9], v[70:71], 2, s[58:59]
	global_store_dword v[8:9], v10, off sc1

.LBB0_1398:
	s_add_i32 s58, s67, 0xffffe000
	s_lshr_b32 s58, s58, 12
	s_mulk_i32 s58, 0x1800
	s_addk_i32 s58, 0x1800
	s_cmp_gt_i32 s6, 63
	s_cselect_b32 s62, s58, 0
	s_add_i32 s6, s62, 0x9000
	s_lshl_b64 s[58:59], s[6:7], 2
	s_add_u32 s6, s14, s58
	s_addc_u32 s58, s15, s59
	s_add_u32 s60, s6, 0x5ba5000
	s_addc_u32 s61, s58, 0
	s_add_i32 s6, s62, 0xd800
	s_lshl_b64 s[58:59], s[6:7], 2
	v_mov_b32_e32 v70, s66
	s_add_u32 s6, s14, s58
	ds_read_b64 v[70:71], v70
	s_addc_u32 s69, s15, s59
	s_lshl_b32 s58, s64, 14
	s_add_i32 s58, s58, 0xc0000
	s_ashr_i32 s59, s58, 31
	s_lshl_b64 s[58:59], s[58:59], 2
	s_add_u32 s58, s10, s58
	s_waitcnt lgkmcnt(0)
	v_readfirstlane_b32 s63, v70
	s_addc_u32 s59, s11, s59
	v_or_b32_e32 v102, s68, v138
	v_add_u32_e32 v70, s67, v139
	v_readfirstlane_b32 s65, v71
	s_add_u32 s62, s63, 0x3000
	v_ashrrev_i32_e32 v103, 31, v102
	v_lshlrev_b32_e32 v191, 10, v70
	s_addc_u32 s63, s65, 0
	v_lshlrev_b64 v[72:73], 2, v[102:103]
	v_or_b32_e32 v187, 0x400, v191
	v_or_b32_e32 v186, 0x4400, v191
	v_or_b32_e32 v189, 0x4c00, v191
	v_or_b32_e32 v194, 0x6c00, v191
	s_add_u32 s64, s6, 0x5ba1000
	v_lshl_add_u64 v[74:75], s[60:61], 0, v[72:73]
	v_add_u32_e32 v130, v191, v102
	v_add_u32_e32 v132, v187, v102
	v_or_b32_e32 v185, 0x800, v191
	v_or_b32_e32 v184, 0xc00, v191
	v_or_b32_e32 v182, 0x2000, v191
	v_or_b32_e32 v180, 0x2400, v191
	v_or_b32_e32 v71, 0x2800, v191
	v_or_b32_e32 v181, 0x2c00, v191
	v_or_b32_e32 v183, 0x4000, v191
	v_add_u32_e32 v112, v186, v102
	v_or_b32_e32 v188, 0x4800, v191
	v_add_u32_e32 v116, v189, v102
	v_or_b32_e32 v190, 0x6000, v191
	v_or_b32_e32 v192, 0x6400, v191
	v_or_b32_e32 v193, 0x6800, v191
	v_add_u32_e32 v128, v194, v102
	s_addc_u32 s65, s69, 0
	global_load_dword v195, v[74:75], off
	v_lshl_add_u64 v[74:75], s[62:63], 0, v[72:73]
	v_ashrrev_i32_e32 v133, 31, v132
	v_add_u32_e32 v134, v185, v102
	v_add_u32_e32 v136, v184, v102
	v_add_u32_e32 v126, v182, v102
	v_add_u32_e32 v118, v180, v102
	v_add_u32_e32 v110, v71, v102
	v_add_u32_e32 v106, v181, v102
	v_add_u32_e32 v108, v183, v102
	v_ashrrev_i32_e32 v113, 31, v112
	v_add_u32_e32 v114, v188, v102
	v_ashrrev_i32_e32 v117, 31, v116
	v_add_u32_e32 v120, v190, v102
	v_add_u32_e32 v122, v192, v102
	v_add_u32_e32 v124, v193, v102
	v_ashrrev_i32_e32 v129, 31, v128
	v_ashrrev_i32_e32 v131, 31, v130
	v_lshl_add_u64 v[72:73], s[64:65], 0, v[72:73]
	global_load_dword v196, v[74:75], off
	global_load_dword v197, v[72:73], off
	v_lshl_add_u64 v[88:89], v[132:133], 2, s[12:13]
	v_ashrrev_i32_e32 v135, 31, v134
	v_ashrrev_i32_e32 v137, 31, v136
	v_ashrrev_i32_e32 v127, 31, v126
	v_ashrrev_i32_e32 v119, 31, v118
	v_ashrrev_i32_e32 v111, 31, v110
	v_ashrrev_i32_e32 v107, 31, v106
	v_ashrrev_i32_e32 v109, 31, v108
	v_lshl_add_u64 v[86:87], v[112:113], 2, s[12:13]
	v_ashrrev_i32_e32 v115, 31, v114
	v_lshl_add_u64 v[92:93], v[116:117], 2, s[12:13]
	v_ashrrev_i32_e32 v121, 31, v120
	v_ashrrev_i32_e32 v123, 31, v122
	v_ashrrev_i32_e32 v125, 31, v124
	v_lshl_add_u64 v[100:101], v[128:129], 2, s[12:13]
	v_lshl_add_u64 v[104:105], v[130:131], 2, s[12:13]
	v_lshl_add_u64 v[84:85], v[134:135], 2, s[12:13]
	v_lshl_add_u64 v[82:83], v[136:137], 2, s[12:13]
	v_lshl_add_u64 v[78:79], v[126:127], 2, s[12:13]
	v_lshl_add_u64 v[72:73], v[118:119], 2, s[12:13]
	v_lshl_add_u64 v[74:75], v[110:111], 2, s[12:13]
	v_lshl_add_u64 v[76:77], v[106:107], 2, s[12:13]
	v_lshl_add_u64 v[80:81], v[108:109], 2, s[12:13]
	global_load_dword v179, v[88:89], off
	global_load_dword v178, v[84:85], off
	global_load_dword v177, v[82:83], off
	global_load_dword v176, v[78:79], off
	global_load_dword v175, v[72:73], off
	global_load_dword v174, v[74:75], off
	global_load_dword v173, v[76:77], off
	global_load_dword v172, v[80:81], off
	v_lshl_add_u64 v[90:91], v[114:115], 2, s[12:13]
	global_load_dword v171, v[86:87], off
	global_load_dword v169, v[90:91], off
	v_lshl_add_u64 v[94:95], v[120:121], 2, s[12:13]
	v_lshl_add_u64 v[96:97], v[122:123], 2, s[12:13]
	v_lshl_add_u64 v[98:99], v[124:125], 2, s[12:13]
	global_load_dword v170, v[92:93], off
	global_load_dword v168, v[94:95], off
	global_load_dword v167, v[96:97], off
	global_load_dword v166, v[98:99], off
	global_load_dword v103, v[100:101], off
	global_load_dword v198, v[104:105], off
	v_lshl_add_u64 v[110:111], v[110:111], 1, s[8:9]
	v_lshl_add_u64 v[106:107], v[106:107], 1, s[8:9]
	s_waitcnt vmcnt(0)
	v_add_f32_e32 v197, 1.0, v197
	v_mul_f32_e32 v196, v196, v197
	v_fmac_f32_e32 v179, v49, v195
	v_fmac_f32_e32 v178, v50, v195
	v_fmac_f32_e32 v177, v51, v195
	v_fmac_f32_e32 v176, v52, v195
	v_fmac_f32_e32 v175, v53, v195
	v_fmac_f32_e32 v174, v54, v195
	v_fmac_f32_e32 v173, v55, v195
	v_fmac_f32_e32 v172, v56, v195
	v_fmac_f32_e32 v171, v57, v195
	v_fmac_f32_e32 v169, v58, v195
	v_fmac_f32_e32 v170, v59, v195
	v_fmac_f32_e32 v168, v60, v195
	v_fmac_f32_e32 v167, v61, v195
	v_fmac_f32_e32 v166, v62, v195
	v_fmac_f32_e32 v103, v63, v195
	v_fmac_f32_e32 v198, v48, v195
	v_mul_f32_e32 v48, v196, v198
	v_cvt_pk_bf16_f32 v58, v48, s0
	v_or_b32_e32 v48, 32, v102
	v_ashrrev_i32_e32 v49, 31, v48
	v_lshlrev_b64 v[52:53], 2, v[48:49]
	global_store_dword v[88:89], v179, off sc1
	global_store_dword v[84:85], v178, off sc1
	global_store_dword v[82:83], v177, off sc1
	global_store_dword v[78:79], v176, off sc1
	global_store_dword v[72:73], v175, off sc1
	global_store_dword v[74:75], v174, off sc1
	global_store_dword v[76:77], v173, off sc1
	global_store_dword v[80:81], v172, off sc1
	global_store_dword v[86:87], v171, off sc1
	global_store_dword v[90:91], v169, off sc1
	global_store_dword v[92:93], v170, off sc1
	global_store_dword v[94:95], v168, off sc1
	global_store_dword v[96:97], v167, off sc1
	global_store_dword v[98:99], v166, off sc1
	global_store_dword v[100:101], v103, off sc1
	global_store_dword v[104:105], v198, off sc1
	v_lshl_add_u64 v[50:51], v[130:131], 1, s[8:9]
	v_lshl_add_u64 v[56:57], s[64:65], 0, v[52:53]
	global_load_dword v197, v[104:105], off offset:128
	v_lshl_add_u64 v[54:55], s[62:63], 0, v[52:53]
	global_load_dword v130, v[56:57], off
	global_load_dword v131, v[54:55], off
	v_mul_f32_e32 v49, v196, v179
	global_store_short v[50:51], v58, off sc1
	v_lshl_add_u64 v[50:51], s[60:61], 0, v[52:53]
	global_load_dword v195, v[50:51], off
	v_lshl_add_u64 v[50:51], v[132:133], 1, s[8:9]
	v_cvt_pk_bf16_f32 v49, v49, s0
	global_store_short v[50:51], v49, off sc1
	v_mul_f32_e32 v49, v196, v178
	v_lshl_add_u64 v[50:51], v[134:135], 1, s[8:9]
	v_cvt_pk_bf16_f32 v49, v49, s0
	global_store_short v[50:51], v49, off sc1
	v_mul_f32_e32 v49, v196, v177
	v_lshl_add_u64 v[50:51], v[136:137], 1, s[8:9]
	v_cvt_pk_bf16_f32 v49, v49, s0
	global_store_short v[50:51], v49, off sc1
	v_mul_f32_e32 v49, v196, v176
	v_lshl_add_u64 v[50:51], v[126:127], 1, s[8:9]
	v_cvt_pk_bf16_f32 v49, v49, s0
	global_store_short v[50:51], v49, off sc1
	v_mul_f32_e32 v49, v196, v175
	v_lshl_add_u64 v[50:51], v[118:119], 1, s[8:9]
	v_cvt_pk_bf16_f32 v49, v49, s0
	global_load_dword v62, v[84:85], off offset:128
	global_load_dword v60, v[78:79], off offset:128
	global_load_dword v59, v[72:73], off offset:128
	global_load_dword v58, v[74:75], off offset:128
	global_load_dword v56, v[80:81], off offset:128
	global_load_dword v57, v[76:77], off offset:128
	global_load_dword v55, v[86:87], off offset:128
	global_load_dword v61, v[82:83], off offset:128
	global_load_dword v54, v[90:91], off offset:128
	global_load_dword v53, v[92:93], off offset:128
	global_load_dword v52, v[94:95], off offset:128
	v_mul_f32_e32 v63, v196, v174
	global_store_short v[50:51], v49, off sc1
	global_load_dword v51, v[96:97], off offset:128
	v_cvt_pk_bf16_f32 v63, v63, s0
	global_load_dword v50, v[98:99], off offset:128
	global_load_dword v49, v[100:101], off offset:128
	s_waitcnt vmcnt(19)
	v_fmac_f32_e32 v197, v32, v195
	global_store_short v[110:111], v63, off sc1
	global_load_dword v63, v[88:89], off offset:128
	v_mul_f32_e32 v110, v196, v173
	v_cvt_pk_bf16_f32 v110, v110, s0
	global_store_short v[106:107], v110, off sc1
	v_lshl_add_u64 v[106:107], v[108:109], 1, s[8:9]
	v_mul_f32_e32 v108, v196, v172
	v_cvt_pk_bf16_f32 v108, v108, s0
	global_store_short v[106:107], v108, off sc1
	v_mul_f32_e32 v108, v196, v171
	v_lshl_add_u64 v[106:107], v[112:113], 1, s[8:9]
	v_cvt_pk_bf16_f32 v108, v108, s0
	global_store_short v[106:107], v108, off sc1
	v_mul_f32_e32 v108, v196, v169
	v_lshl_add_u64 v[106:107], v[114:115], 1, s[8:9]
	v_cvt_pk_bf16_f32 v108, v108, s0
	global_store_short v[106:107], v108, off sc1
	v_mul_f32_e32 v108, v196, v170
	v_lshl_add_u64 v[106:107], v[116:117], 1, s[8:9]
	v_cvt_pk_bf16_f32 v108, v108, s0
	global_store_short v[106:107], v108, off sc1
	v_mul_f32_e32 v108, v196, v168
	v_lshl_add_u64 v[106:107], v[120:121], 1, s[8:9]
	v_cvt_pk_bf16_f32 v108, v108, s0
	global_store_short v[106:107], v108, off sc1
	v_mul_f32_e32 v108, v196, v167
	v_lshl_add_u64 v[106:107], v[122:123], 1, s[8:9]
	v_cvt_pk_bf16_f32 v108, v108, s0
	global_store_short v[106:107], v108, off sc1
	v_mul_f32_e32 v108, v196, v166
	v_lshl_add_u64 v[106:107], v[124:125], 1, s[8:9]
	v_cvt_pk_bf16_f32 v108, v108, s0
	global_store_short v[106:107], v108, off sc1
	v_mul_f32_e32 v108, v196, v103
	v_lshl_add_u64 v[106:107], v[128:129], 1, s[8:9]
	v_cvt_pk_bf16_f32 v108, v108, s0
	global_store_short v[106:107], v108, off sc1
	v_add_f32_e32 v106, 1.0, v130
	v_mul_f32_e32 v107, v131, v106
	v_add_u32_e32 v108, v191, v48
	v_ashrrev_i32_e32 v109, 31, v108
	v_mul_f32_e32 v32, v107, v197
	s_waitcnt vmcnt(25)
	v_fmac_f32_e32 v62, v34, v195
	s_waitcnt vmcnt(18)
	v_fmac_f32_e32 v61, v35, v195
	v_fmac_f32_e32 v60, v36, v195
	v_fmac_f32_e32 v59, v37, v195
	v_fmac_f32_e32 v58, v38, v195
	v_fmac_f32_e32 v57, v39, v195
	v_fmac_f32_e32 v56, v40, v195
	v_fmac_f32_e32 v55, v41, v195
	s_waitcnt vmcnt(17)
	v_fmac_f32_e32 v54, v42, v195
	s_waitcnt vmcnt(16)
	v_fmac_f32_e32 v53, v43, v195
	s_waitcnt vmcnt(15)
	v_fmac_f32_e32 v52, v44, v195
	s_waitcnt vmcnt(13)
	v_fmac_f32_e32 v51, v45, v195
	s_waitcnt vmcnt(12)
	v_fmac_f32_e32 v50, v46, v195
	s_waitcnt vmcnt(11)
	v_fmac_f32_e32 v49, v47, v195
	global_store_dword v[104:105], v197, off offset:128 sc1
	v_lshl_add_u64 v[108:109], v[108:109], 1, s[8:9]
	v_cvt_pk_bf16_f32 v32, v32, s0
	global_store_dword v[84:85], v62, off offset:128 sc1
	global_store_dword v[82:83], v61, off offset:128 sc1
	global_store_dword v[78:79], v60, off offset:128 sc1
	global_store_dword v[72:73], v59, off offset:128 sc1
	global_store_dword v[74:75], v58, off offset:128 sc1
	global_store_dword v[76:77], v57, off offset:128 sc1
	global_store_dword v[80:81], v56, off offset:128 sc1
	global_store_dword v[86:87], v55, off offset:128 sc1
	global_store_dword v[90:91], v54, off offset:128 sc1
	global_store_dword v[92:93], v53, off offset:128 sc1
	global_store_dword v[94:95], v52, off offset:128 sc1
	global_store_dword v[96:97], v51, off offset:128 sc1
	global_store_dword v[98:99], v50, off offset:128 sc1
	global_store_dword v[100:101], v49, off offset:128 sc1
	global_store_short v[108:109], v32, off sc1
	v_add_u32_e32 v108, v187, v48
	global_load_dword v45, v[88:89], off offset:256
	v_ashrrev_i32_e32 v109, 31, v108
	v_mul_f32_e32 v113, v107, v56
	v_cvt_pk_bf16_f32 v113, v113, s0
	v_mul_f32_e32 v106, v197, v197
	v_fmac_f32_e32 v106, v198, v198
	s_waitcnt vmcnt(26)
	v_fmac_f32_e32 v63, v33, v195
	v_mul_f32_e32 v34, v107, v63
	v_lshl_add_u64 v[32:33], v[108:109], 1, s[8:9]
	v_cvt_pk_bf16_f32 v34, v34, s0
	global_store_short v[32:33], v34, off sc1
	v_add_u32_e32 v32, v185, v48
	v_ashrrev_i32_e32 v33, 31, v32
	v_mul_f32_e32 v34, v107, v62
	v_lshl_add_u64 v[32:33], v[32:33], 1, s[8:9]
	v_cvt_pk_bf16_f32 v34, v34, s0
	global_store_short v[32:33], v34, off sc1
	v_add_u32_e32 v32, v184, v48
	v_ashrrev_i32_e32 v33, 31, v32
	v_mul_f32_e32 v34, v107, v61
	v_lshl_add_u64 v[32:33], v[32:33], 1, s[8:9]
	v_cvt_pk_bf16_f32 v34, v34, s0
	global_store_short v[32:33], v34, off sc1
	v_add_u32_e32 v32, v182, v48
	v_ashrrev_i32_e32 v33, 31, v32
	v_mul_f32_e32 v34, v107, v60
	v_lshl_add_u64 v[32:33], v[32:33], 1, s[8:9]
	v_cvt_pk_bf16_f32 v34, v34, s0
	global_store_short v[32:33], v34, off sc1
	v_add_u32_e32 v32, v180, v48
	v_ashrrev_i32_e32 v33, 31, v32
	v_lshl_add_u64 v[34:35], v[32:33], 1, s[8:9]
	v_mul_f32_e32 v32, v107, v59
	v_cvt_pk_bf16_f32 v42, v32, s0
	v_or_b32_e32 v32, 64, v102
	v_ashrrev_i32_e32 v33, 31, v32
	v_lshlrev_b64 v[36:37], 2, v[32:33]
	global_store_dword v[88:89], v63, off offset:128 sc1
	v_lshl_add_u64 v[40:41], s[64:65], 0, v[36:37]
	v_lshl_add_u64 v[38:39], s[62:63], 0, v[36:37]
	global_load_dword v110, v[40:41], off
	global_load_dword v111, v[38:39], off
	v_mul_f32_e32 v33, v107, v58
	global_store_short v[34:35], v42, off sc1
	v_lshl_add_u64 v[34:35], s[60:61], 0, v[36:37]
	global_load_dword v112, v[34:35], off
	v_add_u32_e32 v34, v71, v48
	v_ashrrev_i32_e32 v35, 31, v34
	v_lshl_add_u64 v[34:35], v[34:35], 1, s[8:9]
	v_cvt_pk_bf16_f32 v33, v33, s0
	global_store_short v[34:35], v33, off sc1
	v_add_u32_e32 v34, v181, v48
	v_ashrrev_i32_e32 v35, 31, v34
	v_mul_f32_e32 v33, v107, v57
	v_lshl_add_u64 v[34:35], v[34:35], 1, s[8:9]
	v_cvt_pk_bf16_f32 v33, v33, s0
	global_load_dword v38, v[90:91], off offset:256
	global_load_dword v37, v[92:93], off offset:256
	global_load_dword v36, v[94:95], off offset:256
	global_load_dword v114, v[104:105], off offset:256
	global_load_dword v47, v[84:85], off offset:256
	global_load_dword v39, v[86:87], off offset:256
	global_load_dword v46, v[82:83], off offset:256
	global_load_dword v44, v[78:79], off offset:256
	global_load_dword v43, v[72:73], off offset:256
	global_load_dword v42, v[74:75], off offset:256
	global_load_dword v40, v[80:81], off offset:256
	global_load_dword v41, v[76:77], off offset:256
	v_add_u32_e32 v108, v183, v48
	global_store_short v[34:35], v33, off sc1
	global_load_dword v35, v[96:97], off offset:256
	v_ashrrev_i32_e32 v109, 31, v108
	global_load_dword v34, v[98:99], off offset:256
	global_load_dword v33, v[100:101], off offset:256
	v_lshl_add_u64 v[108:109], v[108:109], 1, s[8:9]
	global_store_short v[108:109], v113, off sc1
	v_add_u32_e32 v108, v186, v48
	v_ashrrev_i32_e32 v109, 31, v108
	v_mul_f32_e32 v113, v107, v55
	v_lshl_add_u64 v[108:109], v[108:109], 1, s[8:9]
	v_cvt_pk_bf16_f32 v113, v113, s0
	global_store_short v[108:109], v113, off sc1
	v_add_u32_e32 v108, v188, v48
	v_ashrrev_i32_e32 v109, 31, v108
	v_mul_f32_e32 v113, v107, v54
	v_lshl_add_u64 v[108:109], v[108:109], 1, s[8:9]
	v_cvt_pk_bf16_f32 v113, v113, s0
	global_store_short v[108:109], v113, off sc1
	v_add_u32_e32 v108, v189, v48
	v_ashrrev_i32_e32 v109, 31, v108
	v_mul_f32_e32 v113, v107, v53
	v_lshl_add_u64 v[108:109], v[108:109], 1, s[8:9]
	v_cvt_pk_bf16_f32 v113, v113, s0
	global_store_short v[108:109], v113, off sc1
	v_add_u32_e32 v108, v190, v48
	v_ashrrev_i32_e32 v109, 31, v108
	v_mul_f32_e32 v113, v107, v52
	v_lshl_add_u64 v[108:109], v[108:109], 1, s[8:9]
	v_cvt_pk_bf16_f32 v113, v113, s0
	global_store_short v[108:109], v113, off sc1
	v_add_u32_e32 v108, v192, v48
	v_ashrrev_i32_e32 v109, 31, v108
	v_mul_f32_e32 v113, v107, v51
	v_lshl_add_u64 v[108:109], v[108:109], 1, s[8:9]
	v_cvt_pk_bf16_f32 v113, v113, s0
	global_store_short v[108:109], v113, off sc1
	v_add_u32_e32 v108, v193, v48
	v_ashrrev_i32_e32 v109, 31, v108
	v_mul_f32_e32 v113, v107, v50
	v_lshl_add_u64 v[108:109], v[108:109], 1, s[8:9]
	v_cvt_pk_bf16_f32 v113, v113, s0
	global_store_short v[108:109], v113, off sc1
	v_add_u32_e32 v108, v194, v48
	v_ashrrev_i32_e32 v109, 31, v108
	v_mul_f32_e32 v48, v107, v49
	v_lshl_add_u64 v[108:109], v[108:109], 1, s[8:9]
	v_cvt_pk_bf16_f32 v48, v48, s0
	global_store_short v[108:109], v48, off sc1
	v_add_u32_e32 v108, v191, v32
	v_ashrrev_i32_e32 v109, 31, v108
	s_waitcnt vmcnt(28)
	v_add_f32_e32 v48, 1.0, v110
	s_waitcnt vmcnt(27)
	v_mul_f32_e32 v48, v111, v48
	s_waitcnt vmcnt(25)
	v_fmac_f32_e32 v45, v17, v112
	global_store_dword v[88:89], v45, off offset:256 sc1
	s_waitcnt vmcnt(24)
	v_fmac_f32_e32 v38, v26, v112
	s_waitcnt vmcnt(23)
	v_fmac_f32_e32 v37, v27, v112
	s_waitcnt vmcnt(22)
	v_fmac_f32_e32 v36, v28, v112
	s_waitcnt vmcnt(21)
	v_fmac_f32_e32 v114, v16, v112
	s_waitcnt vmcnt(20)
	v_fmac_f32_e32 v47, v18, v112
	v_mul_f32_e32 v18, v48, v114
	v_lshl_add_u64 v[16:17], v[108:109], 1, s[8:9]
	v_cvt_pk_bf16_f32 v18, v18, s0
	global_store_short v[16:17], v18, off sc1
	v_add_u32_e32 v16, v187, v32
	v_ashrrev_i32_e32 v17, 31, v16
	v_mul_f32_e32 v18, v48, v45
	v_lshl_add_u64 v[16:17], v[16:17], 1, s[8:9]
	v_cvt_pk_bf16_f32 v18, v18, s0
	global_store_short v[16:17], v18, off sc1
	v_add_u32_e32 v16, v185, v32
	v_ashrrev_i32_e32 v17, 31, v16
	v_mul_f32_e32 v18, v48, v47
	v_lshl_add_u64 v[16:17], v[16:17], 1, s[8:9]
	v_cvt_pk_bf16_f32 v18, v18, s0
	s_waitcnt vmcnt(20)
	v_fmac_f32_e32 v46, v19, v112
	global_store_short v[16:17], v18, off sc1
	v_add_u32_e32 v16, v184, v32
	v_ashrrev_i32_e32 v17, 31, v16
	v_mul_f32_e32 v18, v48, v46
	v_lshl_add_u64 v[16:17], v[16:17], 1, s[8:9]
	v_cvt_pk_bf16_f32 v18, v18, s0
	global_store_short v[16:17], v18, off sc1
	v_add_u32_e32 v16, v182, v32
	v_ashrrev_i32_e32 v17, 31, v16
	v_lshl_add_u64 v[18:19], v[16:17], 1, s[8:9]
	v_or_b32_e32 v16, 0x60, v102
	v_ashrrev_i32_e32 v17, 31, v16
	s_waitcnt vmcnt(21)
	v_fmac_f32_e32 v44, v20, v112
	s_waitcnt vmcnt(20)
	v_fmac_f32_e32 v43, v21, v112
	s_waitcnt vmcnt(19)
	v_fmac_f32_e32 v42, v22, v112
	s_waitcnt vmcnt(17)
	v_fmac_f32_e32 v41, v23, v112
	v_fmac_f32_e32 v40, v24, v112
	v_fmac_f32_e32 v39, v25, v112
	s_waitcnt vmcnt(15)
	v_fmac_f32_e32 v35, v29, v112
	s_waitcnt vmcnt(14)
	v_fmac_f32_e32 v34, v30, v112
	s_waitcnt vmcnt(13)
	v_fmac_f32_e32 v33, v31, v112
	v_lshlrev_b64 v[20:21], 2, v[16:17]
	global_store_dword v[84:85], v47, off offset:256 sc1
	global_store_dword v[82:83], v46, off offset:256 sc1
	global_store_dword v[78:79], v44, off offset:256 sc1
	global_store_dword v[72:73], v43, off offset:256 sc1
	global_store_dword v[74:75], v42, off offset:256 sc1
	global_store_dword v[76:77], v41, off offset:256 sc1
	global_store_dword v[80:81], v40, off offset:256 sc1
	global_store_dword v[86:87], v39, off offset:256 sc1
	global_store_dword v[90:91], v38, off offset:256 sc1
	global_store_dword v[92:93], v37, off offset:256 sc1
	global_store_dword v[94:95], v36, off offset:256 sc1
	global_store_dword v[96:97], v35, off offset:256 sc1
	global_store_dword v[98:99], v34, off offset:256 sc1
	global_store_dword v[100:101], v33, off offset:256 sc1
	global_store_dword v[104:105], v114, off offset:256 sc1
	v_mul_f32_e32 v26, v48, v44
	v_lshl_add_u64 v[22:23], s[62:63], 0, v[20:21]
	v_lshl_add_u64 v[24:25], s[64:65], 0, v[20:21]
	global_load_dword v29, v[104:105], off offset:384
	global_load_dword v17, v[24:25], off
	global_load_dword v30, v[22:23], off
	v_cvt_pk_bf16_f32 v22, v26, s0
	global_store_short v[18:19], v22, off sc1
	v_lshl_add_u64 v[18:19], s[60:61], 0, v[20:21]
	global_load_dword v102, v[18:19], off
	v_add_u32_e32 v18, v180, v32
	v_ashrrev_i32_e32 v19, 31, v18
	v_mul_f32_e32 v20, v48, v43
	v_lshl_add_u64 v[18:19], v[18:19], 1, s[8:9]
	v_cvt_pk_bf16_f32 v20, v20, s0
	global_store_short v[18:19], v20, off sc1
	v_add_u32_e32 v18, v71, v32
	v_ashrrev_i32_e32 v19, 31, v18
	v_mul_f32_e32 v20, v48, v42
	v_lshl_add_u64 v[18:19], v[18:19], 1, s[8:9]
	v_cvt_pk_bf16_f32 v20, v20, s0
	global_store_short v[18:19], v20, off sc1
	v_add_u32_e32 v18, v181, v32
	v_ashrrev_i32_e32 v19, 31, v18
	v_mul_f32_e32 v20, v48, v41
	v_lshl_add_u64 v[18:19], v[18:19], 1, s[8:9]
	v_cvt_pk_bf16_f32 v20, v20, s0
	global_store_short v[18:19], v20, off sc1
	v_add_u32_e32 v18, v183, v32
	v_ashrrev_i32_e32 v19, 31, v18
	v_mul_f32_e32 v20, v48, v40
	v_lshl_add_u64 v[18:19], v[18:19], 1, s[8:9]
	v_cvt_pk_bf16_f32 v20, v20, s0
	global_store_short v[18:19], v20, off sc1
	v_add_u32_e32 v18, v186, v32
	v_ashrrev_i32_e32 v19, 31, v18
	v_mul_f32_e32 v20, v48, v39
	v_lshl_add_u64 v[18:19], v[18:19], 1, s[8:9]
	v_cvt_pk_bf16_f32 v20, v20, s0
	global_store_short v[18:19], v20, off sc1
	v_add_u32_e32 v18, v188, v32
	v_ashrrev_i32_e32 v19, 31, v18
	v_mul_f32_e32 v20, v48, v38
	v_lshl_add_u64 v[18:19], v[18:19], 1, s[8:9]
	v_cvt_pk_bf16_f32 v20, v20, s0
	global_store_short v[18:19], v20, off sc1
	v_add_u32_e32 v18, v189, v32
	v_ashrrev_i32_e32 v19, 31, v18
	v_mul_f32_e32 v20, v48, v37
	v_lshl_add_u64 v[18:19], v[18:19], 1, s[8:9]
	v_cvt_pk_bf16_f32 v20, v20, s0
	global_store_short v[18:19], v20, off sc1
	v_add_u32_e32 v18, v190, v32
	v_ashrrev_i32_e32 v19, 31, v18
	v_mul_f32_e32 v20, v48, v36
	v_lshl_add_u64 v[18:19], v[18:19], 1, s[8:9]
	v_cvt_pk_bf16_f32 v20, v20, s0
	global_store_short v[18:19], v20, off sc1
	v_add_u32_e32 v18, v192, v32
	v_ashrrev_i32_e32 v19, 31, v18
	v_mul_f32_e32 v20, v48, v35
	v_lshl_add_u64 v[18:19], v[18:19], 1, s[8:9]
	v_cvt_pk_bf16_f32 v20, v20, s0
	global_load_dword v28, v[88:89], off offset:384
	global_load_dword v27, v[84:85], off offset:384
	global_load_dword v25, v[78:79], off offset:384
	global_load_dword v24, v[72:73], off offset:384
	global_load_dword v23, v[74:75], off offset:384
	global_load_dword v21, v[80:81], off offset:384
	global_load_dword v22, v[76:77], off offset:384
	v_fmac_f32_e32 v106, v114, v114
	global_store_short v[18:19], v20, off sc1
	v_add_u32_e32 v18, v193, v32
	v_ashrrev_i32_e32 v19, 31, v18
	v_mul_f32_e32 v20, v48, v34
	v_lshl_add_u64 v[18:19], v[18:19], 1, s[8:9]
	v_cvt_pk_bf16_f32 v20, v20, s0
	global_store_short v[18:19], v20, off sc1
	v_add_u32_e32 v18, v194, v32
	v_ashrrev_i32_e32 v19, 31, v18
	v_mul_f32_e32 v20, v48, v33
	v_lshl_add_u64 v[18:19], v[18:19], 1, s[8:9]
	v_cvt_pk_bf16_f32 v20, v20, s0
	global_store_short v[18:19], v20, off sc1
	global_load_dword v20, v[86:87], off offset:384
	s_waitcnt vmcnt(22)
	v_add_f32_e32 v17, 1.0, v17
	global_load_dword v26, v[82:83], off offset:384
	s_waitcnt vmcnt(22)
	v_mul_f32_e32 v32, v30, v17
	v_add_u32_e32 v18, v191, v16
	s_waitcnt vmcnt(20)
	v_fmac_f32_e32 v29, v0, v102
	v_ashrrev_i32_e32 v19, 31, v18
	v_mul_f32_e32 v0, v32, v29
	v_lshl_add_u64 v[18:19], v[18:19], 1, s[8:9]
	v_cvt_pk_bf16_f32 v0, v0, s0
	global_store_short v[18:19], v0, off sc1
	global_load_dword v19, v[90:91], off offset:384
	v_add_u32_e32 v30, v187, v16
	global_load_dword v18, v[92:93], off offset:384
	v_ashrrev_i32_e32 v31, 31, v30
	v_fmac_f32_e32 v106, v29, v29
	global_store_dword v[104:105], v29, off offset:384 sc1
	s_waitcnt vmcnt(15)
	v_fmac_f32_e32 v28, v1, v102
	v_mul_f32_e32 v17, v32, v28
	v_lshl_add_u64 v[0:1], v[30:31], 1, s[8:9]
	v_cvt_pk_bf16_f32 v17, v17, s0
	global_store_short v[0:1], v17, off sc1
	v_add_u32_e32 v0, v185, v16
	s_waitcnt vmcnt(15)
	v_fmac_f32_e32 v27, v2, v102
	global_load_dword v17, v[94:95], off offset:384
	v_ashrrev_i32_e32 v1, 31, v0
	v_mul_f32_e32 v2, v32, v27
	v_lshl_add_u64 v[0:1], v[0:1], 1, s[8:9]
	v_cvt_pk_bf16_f32 v2, v2, s0
	global_store_short v[0:1], v2, off sc1
	v_add_u32_e32 v0, v184, v16
	global_load_dword v2, v[96:97], off offset:384
	v_ashrrev_i32_e32 v1, 31, v0
	v_lshl_add_u64 v[0:1], v[0:1], 1, s[8:9]
	v_add_u32_e32 v30, v182, v16
	s_waitcnt vmcnt(17)
	v_fmac_f32_e32 v25, v4, v102
	v_ashrrev_i32_e32 v31, 31, v30
	v_lshl_add_u64 v[30:31], v[30:31], 1, s[8:9]
	s_waitcnt vmcnt(16)
	v_fmac_f32_e32 v24, v5, v102
	s_waitcnt vmcnt(15)
	v_fmac_f32_e32 v23, v6, v102
	s_waitcnt vmcnt(8)
	v_fmac_f32_e32 v26, v3, v102
	v_mul_f32_e32 v3, v32, v26
	v_cvt_pk_bf16_f32 v3, v3, s0
	global_store_short v[0:1], v3, off sc1
	global_load_dword v1, v[98:99], off offset:384
	v_mul_f32_e32 v0, v32, v25
	v_cvt_pk_bf16_f32 v0, v0, s0
	global_store_short v[30:31], v0, off sc1
	global_load_dword v0, v[100:101], off offset:384
	v_add_u32_e32 v30, v180, v16
	v_ashrrev_i32_e32 v31, 31, v30
	v_mul_f32_e32 v3, v32, v24
	v_lshl_add_u64 v[4:5], v[30:31], 1, s[8:9]
	v_cvt_pk_bf16_f32 v3, v3, s0
	global_store_short v[4:5], v3, off sc1
	v_add_u32_e32 v4, v71, v16
	v_ashrrev_i32_e32 v5, 31, v4
	v_mul_f32_e32 v3, v32, v23
	v_lshl_add_u64 v[4:5], v[4:5], 1, s[8:9]
	v_cvt_pk_bf16_f32 v3, v3, s0
	global_store_short v[4:5], v3, off sc1
	v_add_u32_e32 v4, v181, v16
	v_fmac_f32_e32 v22, v7, v102
	v_ashrrev_i32_e32 v5, 31, v4
	v_mul_f32_e32 v3, v32, v22
	v_lshl_add_u64 v[4:5], v[4:5], 1, s[8:9]
	v_cvt_pk_bf16_f32 v3, v3, s0
	global_store_short v[4:5], v3, off sc1
	v_add_u32_e32 v4, v183, v16
	v_fmac_f32_e32 v21, v8, v102
	v_ashrrev_i32_e32 v5, 31, v4
	v_mul_f32_e32 v3, v32, v21
	v_lshl_add_u64 v[4:5], v[4:5], 1, s[8:9]
	v_cvt_pk_bf16_f32 v3, v3, s0
	global_store_short v[4:5], v3, off sc1
	v_add_u32_e32 v4, v186, v16
	v_fmac_f32_e32 v20, v9, v102
	v_ashrrev_i32_e32 v5, 31, v4
	v_mul_f32_e32 v3, v32, v20
	v_lshl_add_u64 v[4:5], v[4:5], 1, s[8:9]
	v_cvt_pk_bf16_f32 v3, v3, s0
	global_store_short v[4:5], v3, off sc1
	v_add_u32_e32 v4, v188, v16
	s_waitcnt vmcnt(15)
	v_fmac_f32_e32 v19, v10, v102
	v_ashrrev_i32_e32 v5, 31, v4
	v_mul_f32_e32 v3, v32, v19
	v_lshl_add_u64 v[4:5], v[4:5], 1, s[8:9]
	v_cvt_pk_bf16_f32 v3, v3, s0
	global_store_short v[4:5], v3, off sc1
	v_add_u32_e32 v4, v189, v16
	s_waitcnt vmcnt(15)
	v_fmac_f32_e32 v18, v11, v102
	v_ashrrev_i32_e32 v5, 31, v4
	v_mul_f32_e32 v3, v32, v18
	v_lshl_add_u64 v[4:5], v[4:5], 1, s[8:9]
	v_cvt_pk_bf16_f32 v3, v3, s0
	global_store_short v[4:5], v3, off sc1
	v_add_u32_e32 v4, v190, v16
	v_ashrrev_i32_e32 v5, 31, v4
	v_lshl_add_u64 v[4:5], v[4:5], 1, s[8:9]
	v_ashrrev_i32_e32 v71, 31, v70
	global_store_dword v[88:89], v28, off offset:384 sc1
	global_store_dword v[84:85], v27, off offset:384 sc1
	global_store_dword v[82:83], v26, off offset:384 sc1
	global_store_dword v[78:79], v25, off offset:384 sc1
	s_waitcnt vmcnt(17)
	v_fmac_f32_e32 v17, v12, v102
	v_mul_f32_e32 v3, v32, v17
	v_cvt_pk_bf16_f32 v3, v3, s0
	global_store_short v[4:5], v3, off sc1
	v_add_u32_e32 v4, v192, v16
	v_ashrrev_i32_e32 v5, 31, v4
	v_lshl_add_u64 v[4:5], v[4:5], 1, s[8:9]
	s_waitcnt vmcnt(16)
	v_fmac_f32_e32 v2, v13, v102
	v_mul_f32_e32 v3, v32, v2
	v_cvt_pk_bf16_f32 v3, v3, s0
	global_store_short v[4:5], v3, off sc1
	v_add_u32_e32 v4, v193, v16
	v_ashrrev_i32_e32 v5, 31, v4
	v_lshl_add_u64 v[4:5], v[4:5], 1, s[8:9]
	v_xor_b32_e32 v12, 16, v165
	global_store_dword v[72:73], v24, off offset:384 sc1
	global_store_dword v[74:75], v23, off offset:384 sc1
	global_store_dword v[76:77], v22, off offset:384 sc1
	global_store_dword v[80:81], v21, off offset:384 sc1
	global_store_dword v[86:87], v20, off offset:384 sc1
	s_waitcnt vmcnt(20)
	v_fmac_f32_e32 v1, v14, v102
	v_mul_f32_e32 v3, v32, v1
	v_cvt_pk_bf16_f32 v3, v3, s0
	global_store_short v[4:5], v3, off sc1
	v_add_u32_e32 v4, v194, v16
	v_ashrrev_i32_e32 v5, 31, v4
	v_lshl_add_u64 v[10:11], v[4:5], 1, s[8:9]
	v_and_b32_e32 v4, 64, v165
	v_xor_b32_e32 v3, 1, v165
	v_add_u32_e32 v7, 64, v4
	v_cmp_lt_i32_e32 vcc, v3, v7
	v_xor_b32_e32 v4, 2, v165
	s_waitcnt vmcnt(19)
	v_fmac_f32_e32 v0, v15, v102
	v_cndmask_b32_e32 v3, v165, v3, vcc
	v_lshlrev_b32_e32 v3, 2, v3
	s_nop 1
	v_mov_b32_dpp v5, v106 quad_perm:[1,0,3,2] row_mask:0xf bank_mask:0xf
	v_cmp_lt_i32_e32 vcc, v4, v7
	global_store_dword v[90:91], v19, off offset:384 sc1
	global_store_dword v[92:93], v18, off offset:384 sc1
	v_cndmask_b32_e32 v4, v165, v4, vcc
	v_lshlrev_b32_e32 v4, 2, v4
	s_waitcnt lgkmcnt(0)
	v_add_f32_e32 v6, v106, v5
	s_nop 1
	v_mov_b32_dpp v8, v6 quad_perm:[2,3,0,1] row_mask:0xf bank_mask:0xf
	v_xor_b32_e32 v5, 4, v165
	v_cmp_lt_i32_e32 vcc, v5, v7
	global_store_dword v[94:95], v17, off offset:384 sc1
	global_store_dword v[96:97], v2, off offset:384 sc1
	v_cndmask_b32_e32 v5, v165, v5, vcc
	v_lshlrev_b32_e32 v5, 2, v5
	s_waitcnt lgkmcnt(0)
	v_add_f32_e32 v8, v6, v8
	s_nop 1
	v_mov_b32_dpp v9, v8 row_half_mirror row_mask:0xf bank_mask:0xf
	v_xor_b32_e32 v6, 8, v165
	v_cmp_lt_i32_e32 vcc, v6, v7
	global_store_dword v[98:99], v1, off offset:384 sc1
	global_store_dword v[100:101], v0, off offset:384 sc1
	v_cndmask_b32_e32 v6, v165, v6, vcc
	v_lshlrev_b32_e32 v6, 2, v6
	s_waitcnt lgkmcnt(0)
	v_add_f32_e32 v8, v8, v9
	s_nop 1
	v_mov_b32_dpp v9, v8 row_mirror row_mask:0xf bank_mask:0xf
	v_cmp_lt_i32_e32 vcc, v12, v7
	s_waitcnt lgkmcnt(0)
	v_add_f32_e32 v8, v8, v9
	v_cndmask_b32_e32 v7, v165, v12, vcc
	v_lshlrev_b32_e32 v7, 2, v7
	ds_bpermute_b32 v9, v7, v8
	v_mul_f32_e32 v12, v32, v0
	v_cvt_pk_bf16_f32 v12, v12, s0
	global_store_short v[10:11], v12, off sc1
	s_and_saveexec_b64 s[60:61], s[0:1]
	s_cbranch_execz .LBB0_1400
	s_waitcnt lgkmcnt(0)
	v_add_f32_e32 v10, v8, v9
	v_lshl_add_u64 v[8:9], v[70:71], 2, s[58:59]
	global_store_dword v[8:9], v10, off sc1

.LBB0_1569:
	s_add_i32 s58, s66, 0xffffe000
	s_lshr_b32 s58, s58, 12
	s_mulk_i32 s58, 0x1800
	v_mov_b32_e32 v70, s70
	s_add_i32 s58, s58, 0xf000
	ds_read_b64 v[70:71], v70
	s_cmp_gt_i32 s6, 63
	s_cselect_b32 s6, s58, 0xd800
	s_lshl_b64 s[58:59], s[6:7], 2
	s_add_u32 s6, s14, s58
	s_addc_u32 s65, s15, s59
	s_waitcnt lgkmcnt(0)
	v_readfirstlane_b32 s58, v70
	v_readfirstlane_b32 s59, v71
	s_add_u32 s60, s58, 0x3000
	s_addc_u32 s61, s59, 0
	s_lshl_b32 s58, s64, 14
	s_add_i32 s58, s58, 0xe0000
	s_ashr_i32 s59, s58, 31
	s_lshl_b64 s[58:59], s[58:59], 2
	s_add_u32 s58, s10, s58
	s_addc_u32 s59, s11, s59
	s_add_u32 s62, s6, 0x5ba2000
	v_or_b32_e32 v102, s68, v138
	v_add_u32_e32 v70, s66, v139
	s_addc_u32 s63, s65, 0
	v_lshlrev_b32_e32 v188, 10, v70
	v_ashrrev_i32_e32 v103, 31, v102
	s_add_u32 s64, s6, 0x5ba4000
	v_lshlrev_b64 v[72:73], 2, v[102:103]
	v_or_b32_e32 v186, 0x400, v188
	v_or_b32_e32 v185, 0x4400, v188
	v_or_b32_e32 v189, 0x4c00, v188
	v_or_b32_e32 v193, 0x6c00, v188
	s_addc_u32 s65, s65, 0
	v_lshl_add_u64 v[74:75], s[62:63], 0, v[72:73]
	v_add_u32_e32 v132, v188, v102
	v_add_u32_e32 v134, v186, v102
	v_or_b32_e32 v184, 0x800, v188
	v_or_b32_e32 v183, 0xc00, v188
	v_or_b32_e32 v181, 0x2000, v188
	v_or_b32_e32 v179, 0x2400, v188
	v_or_b32_e32 v71, 0x2800, v188
	v_or_b32_e32 v180, 0x2c00, v188
	v_or_b32_e32 v182, 0x4000, v188
	v_add_u32_e32 v112, v185, v102
	v_or_b32_e32 v187, 0x4800, v188
	v_add_u32_e32 v118, v189, v102
	v_or_b32_e32 v190, 0x6000, v188
	v_or_b32_e32 v191, 0x6400, v188
	v_or_b32_e32 v192, 0x6800, v188
	v_add_u32_e32 v128, v193, v102
	global_load_dword v194, v[74:75], off
	v_lshl_add_u64 v[74:75], s[60:61], 0, v[72:73]
	v_lshl_add_u64 v[72:73], s[64:65], 0, v[72:73]
	v_ashrrev_i32_e32 v135, 31, v134
	v_add_u32_e32 v136, v184, v102
	v_add_u32_e32 v130, v183, v102
	v_add_u32_e32 v122, v181, v102
	v_add_u32_e32 v114, v179, v102
	v_add_u32_e32 v106, v71, v102
	v_add_u32_e32 v108, v180, v102
	v_add_u32_e32 v110, v182, v102
	v_ashrrev_i32_e32 v113, 31, v112
	v_add_u32_e32 v116, v187, v102
	v_ashrrev_i32_e32 v119, 31, v118
	v_add_u32_e32 v120, v190, v102
	v_add_u32_e32 v124, v191, v102
	v_add_u32_e32 v126, v192, v102
	v_ashrrev_i32_e32 v129, 31, v128
	v_ashrrev_i32_e32 v133, 31, v132
	global_load_dword v196, v[72:73], off
	v_lshl_add_u64 v[88:89], v[134:135], 2, s[12:13]
	v_ashrrev_i32_e32 v137, 31, v136
	v_ashrrev_i32_e32 v131, 31, v130
	v_ashrrev_i32_e32 v123, 31, v122
	v_ashrrev_i32_e32 v115, 31, v114
	v_ashrrev_i32_e32 v107, 31, v106
	v_ashrrev_i32_e32 v109, 31, v108
	v_ashrrev_i32_e32 v111, 31, v110
	v_lshl_add_u64 v[86:87], v[112:113], 2, s[12:13]
	v_ashrrev_i32_e32 v117, 31, v116
	v_lshl_add_u64 v[92:93], v[118:119], 2, s[12:13]
	v_ashrrev_i32_e32 v121, 31, v120
	v_ashrrev_i32_e32 v125, 31, v124
	v_ashrrev_i32_e32 v127, 31, v126
	v_lshl_add_u64 v[100:101], v[128:129], 2, s[12:13]
	v_lshl_add_u64 v[104:105], v[132:133], 2, s[12:13]
	global_load_dword v195, v[74:75], off
	v_lshl_add_u64 v[84:85], v[136:137], 2, s[12:13]
	v_lshl_add_u64 v[82:83], v[130:131], 2, s[12:13]
	v_lshl_add_u64 v[78:79], v[122:123], 2, s[12:13]
	v_lshl_add_u64 v[72:73], v[114:115], 2, s[12:13]
	v_lshl_add_u64 v[74:75], v[106:107], 2, s[12:13]
	v_lshl_add_u64 v[76:77], v[108:109], 2, s[12:13]
	v_lshl_add_u64 v[80:81], v[110:111], 2, s[12:13]
	global_load_dword v178, v[88:89], off
	global_load_dword v177, v[84:85], off
	global_load_dword v176, v[82:83], off
	global_load_dword v175, v[78:79], off
	global_load_dword v174, v[72:73], off
	global_load_dword v173, v[74:75], off
	global_load_dword v172, v[76:77], off
	global_load_dword v171, v[80:81], off
	v_lshl_add_u64 v[90:91], v[116:117], 2, s[12:13]
	global_load_dword v170, v[86:87], off
	global_load_dword v168, v[90:91], off
	v_lshl_add_u64 v[94:95], v[120:121], 2, s[12:13]
	v_lshl_add_u64 v[96:97], v[124:125], 2, s[12:13]
	v_lshl_add_u64 v[98:99], v[126:127], 2, s[12:13]
	global_load_dword v169, v[92:93], off
	global_load_dword v167, v[94:95], off
	global_load_dword v166, v[96:97], off
	global_load_dword v165, v[98:99], off
	global_load_dword v103, v[100:101], off
	global_load_dword v197, v[104:105], off
	v_lshl_add_u64 v[106:107], v[106:107], 1, s[8:9]
	s_waitcnt vmcnt(0)
	v_add_f32_e32 v196, 1.0, v196
	v_mul_f32_e32 v195, v195, v196
	v_fmac_f32_e32 v178, v49, v194
	v_fmac_f32_e32 v177, v50, v194
	v_fmac_f32_e32 v176, v51, v194
	v_fmac_f32_e32 v175, v52, v194
	v_fmac_f32_e32 v174, v53, v194
	v_fmac_f32_e32 v173, v54, v194
	v_fmac_f32_e32 v172, v55, v194
	v_fmac_f32_e32 v171, v56, v194
	v_fmac_f32_e32 v170, v57, v194
	v_fmac_f32_e32 v168, v58, v194
	v_fmac_f32_e32 v169, v59, v194
	v_fmac_f32_e32 v167, v60, v194
	v_fmac_f32_e32 v166, v61, v194
	v_fmac_f32_e32 v165, v62, v194
	v_fmac_f32_e32 v103, v63, v194
	v_fmac_f32_e32 v197, v48, v194
	v_mul_f32_e32 v48, v195, v197
	v_cvt_pk_bf16_f32 v58, v48, s0
	v_or_b32_e32 v48, 32, v102
	v_ashrrev_i32_e32 v49, 31, v48
	v_lshlrev_b64 v[52:53], 2, v[48:49]
	global_store_dword v[88:89], v178, off sc1
	global_store_dword v[84:85], v177, off sc1
	global_store_dword v[82:83], v176, off sc1
	global_store_dword v[78:79], v175, off sc1
	global_store_dword v[72:73], v174, off sc1
	global_store_dword v[74:75], v173, off sc1
	global_store_dword v[76:77], v172, off sc1
	global_store_dword v[80:81], v171, off sc1
	global_store_dword v[86:87], v170, off sc1
	global_store_dword v[90:91], v168, off sc1
	global_store_dword v[92:93], v169, off sc1
	global_store_dword v[94:95], v167, off sc1
	global_store_dword v[96:97], v166, off sc1
	global_store_dword v[98:99], v165, off sc1
	global_store_dword v[100:101], v103, off sc1
	global_store_dword v[104:105], v197, off sc1
	v_lshl_add_u64 v[50:51], v[132:133], 1, s[8:9]
	v_lshl_add_u64 v[56:57], s[64:65], 0, v[52:53]
	global_load_dword v196, v[104:105], off offset:128
	v_lshl_add_u64 v[54:55], s[60:61], 0, v[52:53]
	global_load_dword v132, v[56:57], off
	global_load_dword v133, v[54:55], off
	v_mul_f32_e32 v49, v195, v178
	global_store_short v[50:51], v58, off sc1
	v_lshl_add_u64 v[50:51], s[62:63], 0, v[52:53]
	global_load_dword v194, v[50:51], off
	v_cvt_pk_bf16_f32 v49, v49, s0
	v_lshl_add_u64 v[50:51], v[134:135], 1, s[8:9]
	global_store_short v[50:51], v49, off sc1
	v_mul_f32_e32 v49, v195, v177
	v_cvt_pk_bf16_f32 v49, v49, s0
	v_lshl_add_u64 v[50:51], v[136:137], 1, s[8:9]
	global_store_short v[50:51], v49, off sc1
	v_mul_f32_e32 v49, v195, v176
	v_cvt_pk_bf16_f32 v49, v49, s0
	v_lshl_add_u64 v[50:51], v[130:131], 1, s[8:9]
	global_store_short v[50:51], v49, off sc1
	v_mul_f32_e32 v49, v195, v175
	v_cvt_pk_bf16_f32 v49, v49, s0
	v_lshl_add_u64 v[50:51], v[122:123], 1, s[8:9]
	global_store_short v[50:51], v49, off sc1
	v_mul_f32_e32 v49, v195, v174
	v_cvt_pk_bf16_f32 v49, v49, s0
	v_lshl_add_u64 v[50:51], v[114:115], 1, s[8:9]
	global_store_short v[50:51], v49, off sc1
	v_mul_f32_e32 v49, v195, v173
	global_load_dword v62, v[84:85], off offset:128
	global_load_dword v60, v[78:79], off offset:128
	global_load_dword v59, v[72:73], off offset:128
	global_load_dword v58, v[74:75], off offset:128
	global_load_dword v56, v[80:81], off offset:128
	global_load_dword v57, v[76:77], off offset:128
	global_load_dword v55, v[86:87], off offset:128
	global_load_dword v61, v[82:83], off offset:128
	global_load_dword v54, v[90:91], off offset:128
	global_load_dword v53, v[92:93], off offset:128
	global_load_dword v52, v[94:95], off offset:128
	global_load_dword v51, v[96:97], off offset:128
	global_load_dword v50, v[98:99], off offset:128
	v_cvt_pk_bf16_f32 v63, v49, s0
	global_load_dword v49, v[100:101], off offset:128
	s_waitcnt vmcnt(19)
	v_fmac_f32_e32 v196, v32, v194
	global_store_short v[106:107], v63, off sc1
	global_load_dword v63, v[88:89], off offset:128
	v_mul_f32_e32 v106, v195, v172
	v_cvt_pk_bf16_f32 v114, v106, s0
	v_lshl_add_u64 v[106:107], v[108:109], 1, s[8:9]
	global_store_short v[106:107], v114, off sc1
	v_mul_f32_e32 v106, v195, v171
	v_cvt_pk_bf16_f32 v108, v106, s0
	v_lshl_add_u64 v[106:107], v[110:111], 1, s[8:9]
	global_store_short v[106:107], v108, off sc1
	v_mul_f32_e32 v106, v195, v170
	v_cvt_pk_bf16_f32 v108, v106, s0
	v_lshl_add_u64 v[106:107], v[112:113], 1, s[8:9]
	global_store_short v[106:107], v108, off sc1
	v_mul_f32_e32 v106, v195, v168
	v_cvt_pk_bf16_f32 v108, v106, s0
	v_lshl_add_u64 v[106:107], v[116:117], 1, s[8:9]
	global_store_short v[106:107], v108, off sc1
	v_mul_f32_e32 v106, v195, v169
	v_cvt_pk_bf16_f32 v108, v106, s0
	v_lshl_add_u64 v[106:107], v[118:119], 1, s[8:9]
	global_store_short v[106:107], v108, off sc1
	v_mul_f32_e32 v106, v195, v167
	v_cvt_pk_bf16_f32 v108, v106, s0
	v_lshl_add_u64 v[106:107], v[120:121], 1, s[8:9]
	global_store_short v[106:107], v108, off sc1
	v_mul_f32_e32 v106, v195, v166
	v_cvt_pk_bf16_f32 v108, v106, s0
	v_lshl_add_u64 v[106:107], v[124:125], 1, s[8:9]
	global_store_short v[106:107], v108, off sc1
	v_mul_f32_e32 v106, v195, v165
	v_cvt_pk_bf16_f32 v108, v106, s0
	v_lshl_add_u64 v[106:107], v[126:127], 1, s[8:9]
	global_store_short v[106:107], v108, off sc1
	v_mul_f32_e32 v106, v195, v103
	v_cvt_pk_bf16_f32 v108, v106, s0
	v_lshl_add_u64 v[106:107], v[128:129], 1, s[8:9]
	global_store_short v[106:107], v108, off sc1
	v_add_f32_e32 v106, 1.0, v132
	v_mul_f32_e32 v110, v133, v106
	v_add_u32_e32 v106, v188, v48
	s_waitcnt vmcnt(24)
	v_fmac_f32_e32 v62, v34, v194
	s_waitcnt vmcnt(17)
	v_fmac_f32_e32 v61, v35, v194
	v_fmac_f32_e32 v60, v36, v194
	v_fmac_f32_e32 v59, v37, v194
	v_fmac_f32_e32 v58, v38, v194
	v_fmac_f32_e32 v57, v39, v194
	v_fmac_f32_e32 v56, v40, v194
	v_fmac_f32_e32 v55, v41, v194
	s_waitcnt vmcnt(16)
	v_fmac_f32_e32 v54, v42, v194
	s_waitcnt vmcnt(15)
	v_fmac_f32_e32 v53, v43, v194
	s_waitcnt vmcnt(14)
	v_fmac_f32_e32 v52, v44, v194
	s_waitcnt vmcnt(13)
	v_fmac_f32_e32 v51, v45, v194
	s_waitcnt vmcnt(12)
	v_fmac_f32_e32 v50, v46, v194
	s_waitcnt vmcnt(11)
	v_fmac_f32_e32 v49, v47, v194
	v_ashrrev_i32_e32 v107, 31, v106
	global_store_dword v[104:105], v196, off offset:128 sc1
	v_mul_f32_e32 v32, v110, v196
	global_store_dword v[84:85], v62, off offset:128 sc1
	global_store_dword v[82:83], v61, off offset:128 sc1
	global_store_dword v[78:79], v60, off offset:128 sc1
	global_store_dword v[72:73], v59, off offset:128 sc1
	global_store_dword v[74:75], v58, off offset:128 sc1
	global_store_dword v[76:77], v57, off offset:128 sc1
	global_store_dword v[80:81], v56, off offset:128 sc1
	global_store_dword v[86:87], v55, off offset:128 sc1
	global_store_dword v[90:91], v54, off offset:128 sc1
	global_store_dword v[92:93], v53, off offset:128 sc1
	global_store_dword v[94:95], v52, off offset:128 sc1
	global_store_dword v[96:97], v51, off offset:128 sc1
	global_store_dword v[98:99], v50, off offset:128 sc1
	global_store_dword v[100:101], v49, off offset:128 sc1
	v_cvt_pk_bf16_f32 v32, v32, s0
	v_lshl_add_u64 v[106:107], v[106:107], 1, s[8:9]
	v_add_u32_e32 v108, v186, v48
	global_load_dword v45, v[88:89], off offset:256
	v_ashrrev_i32_e32 v109, 31, v108
	global_store_short v[106:107], v32, off sc1
	v_mul_f32_e32 v113, v110, v56
	v_cvt_pk_bf16_f32 v113, v113, s0
	v_mul_f32_e32 v106, v196, v196
	s_waitcnt vmcnt(26)
	v_fmac_f32_e32 v63, v33, v194
	v_mul_f32_e32 v32, v110, v63
	v_cvt_pk_bf16_f32 v34, v32, s0
	v_lshl_add_u64 v[32:33], v[108:109], 1, s[8:9]
	global_store_short v[32:33], v34, off sc1
	v_add_u32_e32 v32, v184, v48
	v_ashrrev_i32_e32 v33, 31, v32
	v_mul_f32_e32 v34, v110, v62
	v_cvt_pk_bf16_f32 v34, v34, s0
	v_lshl_add_u64 v[32:33], v[32:33], 1, s[8:9]
	global_store_short v[32:33], v34, off sc1
	v_add_u32_e32 v32, v183, v48
	v_ashrrev_i32_e32 v33, 31, v32
	v_mul_f32_e32 v34, v110, v61
	v_cvt_pk_bf16_f32 v34, v34, s0
	v_lshl_add_u64 v[32:33], v[32:33], 1, s[8:9]
	global_store_short v[32:33], v34, off sc1
	v_add_u32_e32 v32, v181, v48
	v_ashrrev_i32_e32 v33, 31, v32
	v_mul_f32_e32 v34, v110, v60
	v_cvt_pk_bf16_f32 v34, v34, s0
	v_lshl_add_u64 v[32:33], v[32:33], 1, s[8:9]
	global_store_short v[32:33], v34, off sc1
	v_add_u32_e32 v32, v179, v48
	v_ashrrev_i32_e32 v33, 31, v32
	v_mul_f32_e32 v34, v110, v59
	v_cvt_pk_bf16_f32 v42, v34, s0
	v_lshl_add_u64 v[34:35], v[32:33], 1, s[8:9]
	v_or_b32_e32 v32, 64, v102
	v_ashrrev_i32_e32 v33, 31, v32
	v_lshlrev_b64 v[36:37], 2, v[32:33]
	global_store_dword v[88:89], v63, off offset:128 sc1
	v_lshl_add_u64 v[40:41], s[64:65], 0, v[36:37]
	v_lshl_add_u64 v[38:39], s[60:61], 0, v[36:37]
	global_load_dword v107, v[40:41], off
	global_load_dword v111, v[38:39], off
	v_mul_f32_e32 v33, v110, v58
	global_store_short v[34:35], v42, off sc1
	v_lshl_add_u64 v[34:35], s[62:63], 0, v[36:37]
	global_load_dword v112, v[34:35], off
	v_add_u32_e32 v34, v71, v48
	v_ashrrev_i32_e32 v35, 31, v34
	v_cvt_pk_bf16_f32 v33, v33, s0
	v_lshl_add_u64 v[34:35], v[34:35], 1, s[8:9]
	global_store_short v[34:35], v33, off sc1
	v_add_u32_e32 v34, v180, v48
	v_ashrrev_i32_e32 v35, 31, v34
	v_mul_f32_e32 v33, v110, v57
	v_cvt_pk_bf16_f32 v33, v33, s0
	v_lshl_add_u64 v[34:35], v[34:35], 1, s[8:9]
	global_load_dword v38, v[90:91], off offset:256
	global_load_dword v37, v[92:93], off offset:256
	global_load_dword v36, v[94:95], off offset:256
	global_load_dword v114, v[104:105], off offset:256
	global_load_dword v47, v[84:85], off offset:256
	global_load_dword v39, v[86:87], off offset:256
	global_load_dword v46, v[82:83], off offset:256
	global_load_dword v44, v[78:79], off offset:256
	global_load_dword v43, v[72:73], off offset:256
	global_load_dword v42, v[74:75], off offset:256
	global_load_dword v40, v[80:81], off offset:256
	global_load_dword v41, v[76:77], off offset:256
	v_add_u32_e32 v108, v182, v48
	global_store_short v[34:35], v33, off sc1
	global_load_dword v35, v[96:97], off offset:256
	v_ashrrev_i32_e32 v109, 31, v108
	global_load_dword v34, v[98:99], off offset:256
	global_load_dword v33, v[100:101], off offset:256
	v_lshl_add_u64 v[108:109], v[108:109], 1, s[8:9]
	global_store_short v[108:109], v113, off sc1
	v_add_u32_e32 v108, v185, v48
	v_ashrrev_i32_e32 v109, 31, v108
	v_mul_f32_e32 v113, v110, v55
	v_cvt_pk_bf16_f32 v113, v113, s0
	v_lshl_add_u64 v[108:109], v[108:109], 1, s[8:9]
	global_store_short v[108:109], v113, off sc1
	v_add_u32_e32 v108, v187, v48
	v_ashrrev_i32_e32 v109, 31, v108
	v_mul_f32_e32 v113, v110, v54
	v_cvt_pk_bf16_f32 v113, v113, s0
	v_lshl_add_u64 v[108:109], v[108:109], 1, s[8:9]
	global_store_short v[108:109], v113, off sc1
	v_add_u32_e32 v108, v189, v48
	v_ashrrev_i32_e32 v109, 31, v108
	v_mul_f32_e32 v113, v110, v53
	v_cvt_pk_bf16_f32 v113, v113, s0
	v_lshl_add_u64 v[108:109], v[108:109], 1, s[8:9]
	global_store_short v[108:109], v113, off sc1
	v_add_u32_e32 v108, v190, v48
	v_ashrrev_i32_e32 v109, 31, v108
	v_mul_f32_e32 v113, v110, v52
	v_cvt_pk_bf16_f32 v113, v113, s0
	v_lshl_add_u64 v[108:109], v[108:109], 1, s[8:9]
	global_store_short v[108:109], v113, off sc1
	v_add_u32_e32 v108, v191, v48
	v_ashrrev_i32_e32 v109, 31, v108
	v_mul_f32_e32 v113, v110, v51
	v_cvt_pk_bf16_f32 v113, v113, s0
	v_lshl_add_u64 v[108:109], v[108:109], 1, s[8:9]
	global_store_short v[108:109], v113, off sc1
	v_add_u32_e32 v108, v192, v48
	v_ashrrev_i32_e32 v109, 31, v108
	v_mul_f32_e32 v113, v110, v50
	v_cvt_pk_bf16_f32 v113, v113, s0
	v_lshl_add_u64 v[108:109], v[108:109], 1, s[8:9]
	global_store_short v[108:109], v113, off sc1
	v_add_u32_e32 v108, v193, v48
	v_ashrrev_i32_e32 v109, 31, v108
	v_mul_f32_e32 v48, v110, v49
	v_cvt_pk_bf16_f32 v48, v48, s0
	v_lshl_add_u64 v[108:109], v[108:109], 1, s[8:9]
	global_store_short v[108:109], v48, off sc1
	v_add_u32_e32 v108, v188, v32
	v_ashrrev_i32_e32 v109, 31, v108
	s_waitcnt vmcnt(28)
	v_add_f32_e32 v48, 1.0, v107
	s_waitcnt vmcnt(27)
	v_mul_f32_e32 v48, v111, v48
	v_fmac_f32_e32 v106, v197, v197
	s_waitcnt vmcnt(25)
	v_fmac_f32_e32 v45, v17, v112
	global_store_dword v[88:89], v45, off offset:256 sc1
	s_waitcnt vmcnt(24)
	v_fmac_f32_e32 v38, v26, v112
	s_waitcnt vmcnt(23)
	v_fmac_f32_e32 v37, v27, v112
	s_waitcnt vmcnt(22)
	v_fmac_f32_e32 v36, v28, v112
	s_waitcnt vmcnt(21)
	v_fmac_f32_e32 v114, v16, v112
	v_mul_f32_e32 v16, v48, v114
	s_waitcnt vmcnt(20)
	v_fmac_f32_e32 v47, v18, v112
	v_cvt_pk_bf16_f32 v18, v16, s0
	v_lshl_add_u64 v[16:17], v[108:109], 1, s[8:9]
	global_store_short v[16:17], v18, off sc1
	v_add_u32_e32 v16, v186, v32
	v_ashrrev_i32_e32 v17, 31, v16
	v_mul_f32_e32 v18, v48, v45
	v_cvt_pk_bf16_f32 v18, v18, s0
	v_lshl_add_u64 v[16:17], v[16:17], 1, s[8:9]
	global_store_short v[16:17], v18, off sc1
	v_add_u32_e32 v16, v184, v32
	v_ashrrev_i32_e32 v17, 31, v16
	v_mul_f32_e32 v18, v48, v47
	v_cvt_pk_bf16_f32 v18, v18, s0
	v_lshl_add_u64 v[16:17], v[16:17], 1, s[8:9]
	s_waitcnt vmcnt(20)
	v_fmac_f32_e32 v46, v19, v112
	global_store_short v[16:17], v18, off sc1
	v_add_u32_e32 v16, v183, v32
	v_ashrrev_i32_e32 v17, 31, v16
	v_mul_f32_e32 v18, v48, v46
	s_waitcnt vmcnt(20)
	v_fmac_f32_e32 v44, v20, v112
	v_cvt_pk_bf16_f32 v18, v18, s0
	v_lshl_add_u64 v[16:17], v[16:17], 1, s[8:9]
	global_store_short v[16:17], v18, off sc1
	v_mul_f32_e32 v16, v48, v44
	v_cvt_pk_bf16_f32 v26, v16, s0
	v_or_b32_e32 v16, 0x60, v102
	v_add_u32_e32 v18, v181, v32
	v_ashrrev_i32_e32 v17, 31, v16
	s_waitcnt vmcnt(20)
	v_fmac_f32_e32 v43, v21, v112
	s_waitcnt vmcnt(19)
	v_fmac_f32_e32 v42, v22, v112
	s_waitcnt vmcnt(17)
	v_fmac_f32_e32 v41, v23, v112
	v_fmac_f32_e32 v40, v24, v112
	v_fmac_f32_e32 v39, v25, v112
	s_waitcnt vmcnt(15)
	v_fmac_f32_e32 v35, v29, v112
	s_waitcnt vmcnt(14)
	v_fmac_f32_e32 v34, v30, v112
	s_waitcnt vmcnt(13)
	v_fmac_f32_e32 v33, v31, v112
	v_ashrrev_i32_e32 v19, 31, v18
	v_lshlrev_b64 v[20:21], 2, v[16:17]
	global_store_dword v[84:85], v47, off offset:256 sc1
	global_store_dword v[82:83], v46, off offset:256 sc1
	global_store_dword v[78:79], v44, off offset:256 sc1
	global_store_dword v[72:73], v43, off offset:256 sc1
	global_store_dword v[74:75], v42, off offset:256 sc1
	global_store_dword v[76:77], v41, off offset:256 sc1
	global_store_dword v[80:81], v40, off offset:256 sc1
	global_store_dword v[86:87], v39, off offset:256 sc1
	global_store_dword v[90:91], v38, off offset:256 sc1
	global_store_dword v[92:93], v37, off offset:256 sc1
	global_store_dword v[94:95], v36, off offset:256 sc1
	global_store_dword v[96:97], v35, off offset:256 sc1
	global_store_dword v[98:99], v34, off offset:256 sc1
	global_store_dword v[100:101], v33, off offset:256 sc1
	global_store_dword v[104:105], v114, off offset:256 sc1
	v_lshl_add_u64 v[24:25], s[64:65], 0, v[20:21]
	v_lshl_add_u64 v[18:19], v[18:19], 1, s[8:9]
	global_load_dword v29, v[104:105], off offset:384
	v_lshl_add_u64 v[22:23], s[60:61], 0, v[20:21]
	global_load_dword v17, v[24:25], off
	global_load_dword v30, v[22:23], off
	global_load_dword v28, v[88:89], off offset:384
	global_load_dword v27, v[84:85], off offset:384
	v_fmac_f32_e32 v106, v114, v114
	global_store_short v[18:19], v26, off sc1
	v_lshl_add_u64 v[18:19], s[62:63], 0, v[20:21]
	global_load_dword v102, v[18:19], off
	v_add_u32_e32 v18, v179, v32
	v_ashrrev_i32_e32 v19, 31, v18
	v_mul_f32_e32 v20, v48, v43
	v_cvt_pk_bf16_f32 v20, v20, s0
	v_lshl_add_u64 v[18:19], v[18:19], 1, s[8:9]
	global_store_short v[18:19], v20, off sc1
	v_add_u32_e32 v18, v71, v32
	v_ashrrev_i32_e32 v19, 31, v18
	v_mul_f32_e32 v20, v48, v42
	v_cvt_pk_bf16_f32 v20, v20, s0
	v_lshl_add_u64 v[18:19], v[18:19], 1, s[8:9]
	global_store_short v[18:19], v20, off sc1
	v_add_u32_e32 v18, v180, v32
	v_ashrrev_i32_e32 v19, 31, v18
	v_mul_f32_e32 v20, v48, v41
	v_cvt_pk_bf16_f32 v20, v20, s0
	v_lshl_add_u64 v[18:19], v[18:19], 1, s[8:9]
	global_store_short v[18:19], v20, off sc1
	v_add_u32_e32 v18, v182, v32
	v_ashrrev_i32_e32 v19, 31, v18
	v_mul_f32_e32 v20, v48, v40
	v_cvt_pk_bf16_f32 v20, v20, s0
	v_lshl_add_u64 v[18:19], v[18:19], 1, s[8:9]
	global_store_short v[18:19], v20, off sc1
	v_add_u32_e32 v18, v185, v32
	v_ashrrev_i32_e32 v19, 31, v18
	v_mul_f32_e32 v20, v48, v39
	v_cvt_pk_bf16_f32 v20, v20, s0
	v_lshl_add_u64 v[18:19], v[18:19], 1, s[8:9]
	global_store_short v[18:19], v20, off sc1
	v_add_u32_e32 v18, v187, v32
	v_ashrrev_i32_e32 v19, 31, v18
	v_mul_f32_e32 v20, v48, v38
	v_cvt_pk_bf16_f32 v20, v20, s0
	v_lshl_add_u64 v[18:19], v[18:19], 1, s[8:9]
	global_store_short v[18:19], v20, off sc1
	v_add_u32_e32 v18, v189, v32
	v_ashrrev_i32_e32 v19, 31, v18
	v_mul_f32_e32 v20, v48, v37
	v_cvt_pk_bf16_f32 v20, v20, s0
	v_lshl_add_u64 v[18:19], v[18:19], 1, s[8:9]
	global_store_short v[18:19], v20, off sc1
	v_add_u32_e32 v18, v190, v32
	v_ashrrev_i32_e32 v19, 31, v18
	v_mul_f32_e32 v20, v48, v36
	v_cvt_pk_bf16_f32 v20, v20, s0
	v_lshl_add_u64 v[18:19], v[18:19], 1, s[8:9]
	global_store_short v[18:19], v20, off sc1
	v_add_u32_e32 v18, v191, v32
	v_ashrrev_i32_e32 v19, 31, v18
	v_mul_f32_e32 v20, v48, v35
	v_cvt_pk_bf16_f32 v20, v20, s0
	v_lshl_add_u64 v[18:19], v[18:19], 1, s[8:9]
	global_store_short v[18:19], v20, off sc1
	v_add_u32_e32 v18, v192, v32
	v_ashrrev_i32_e32 v19, 31, v18
	v_mul_f32_e32 v20, v48, v34
	v_cvt_pk_bf16_f32 v20, v20, s0
	v_lshl_add_u64 v[18:19], v[18:19], 1, s[8:9]
	global_store_short v[18:19], v20, off sc1
	v_add_u32_e32 v18, v193, v32
	v_ashrrev_i32_e32 v19, 31, v18
	v_mul_f32_e32 v20, v48, v33
	v_cvt_pk_bf16_f32 v20, v20, s0
	v_lshl_add_u64 v[18:19], v[18:19], 1, s[8:9]
	global_store_short v[18:19], v20, off sc1
	global_load_dword v20, v[86:87], off offset:384
	v_add_u32_e32 v18, v188, v16
	global_load_dword v26, v[82:83], off offset:384
	global_load_dword v25, v[78:79], off offset:384
	global_load_dword v24, v[72:73], off offset:384
	global_load_dword v23, v[74:75], off offset:384
	global_load_dword v21, v[80:81], off offset:384
	global_load_dword v22, v[76:77], off offset:384
	s_waitcnt vmcnt(23)
	v_add_f32_e32 v17, 1.0, v17
	s_waitcnt vmcnt(22)
	v_mul_f32_e32 v32, v30, v17
	v_ashrrev_i32_e32 v19, 31, v18
	v_lshl_add_u64 v[18:19], v[18:19], 1, s[8:9]
	v_add_u32_e32 v30, v186, v16
	s_waitcnt vmcnt(18)
	v_fmac_f32_e32 v29, v0, v102
	v_mul_f32_e32 v0, v32, v29
	v_cvt_pk_bf16_f32 v0, v0, s0
	global_store_short v[18:19], v0, off sc1
	global_load_dword v19, v[90:91], off offset:384
	v_ashrrev_i32_e32 v31, 31, v30
	global_load_dword v18, v[92:93], off offset:384
	v_fmac_f32_e32 v28, v1, v102
	v_mul_f32_e32 v0, v32, v28
	v_cvt_pk_bf16_f32 v17, v0, s0
	v_lshl_add_u64 v[0:1], v[30:31], 1, s[8:9]
	global_store_short v[0:1], v17, off sc1
	v_add_u32_e32 v0, v184, v16
	v_fmac_f32_e32 v27, v2, v102
	global_load_dword v17, v[94:95], off offset:384
	v_ashrrev_i32_e32 v1, 31, v0
	v_mul_f32_e32 v2, v32, v27
	v_cvt_pk_bf16_f32 v2, v2, s0
	v_lshl_add_u64 v[0:1], v[0:1], 1, s[8:9]
	global_store_short v[0:1], v2, off sc1
	v_add_u32_e32 v0, v183, v16
	global_load_dword v2, v[96:97], off offset:384
	v_ashrrev_i32_e32 v1, 31, v0
	v_lshl_add_u64 v[0:1], v[0:1], 1, s[8:9]
	v_add_u32_e32 v30, v181, v16
	v_ashrrev_i32_e32 v31, 31, v30
	v_lshl_add_u64 v[30:31], v[30:31], 1, s[8:9]
	v_fmac_f32_e32 v106, v29, v29
	global_store_dword v[104:105], v29, off offset:384 sc1
	global_store_dword v[88:89], v28, off offset:384 sc1
	global_store_dword v[84:85], v27, off offset:384 sc1
	s_waitcnt vmcnt(16)
	v_fmac_f32_e32 v20, v9, v102
	global_store_dword v[86:87], v20, off offset:384 sc1
	s_waitcnt vmcnt(16)
	v_fmac_f32_e32 v26, v3, v102
	v_mul_f32_e32 v3, v32, v26
	v_cvt_pk_bf16_f32 v3, v3, s0
	global_store_short v[0:1], v3, off sc1
	global_load_dword v1, v[98:99], off offset:384
	s_waitcnt vmcnt(17)
	v_fmac_f32_e32 v25, v4, v102
	v_mul_f32_e32 v0, v32, v25
	v_cvt_pk_bf16_f32 v0, v0, s0
	global_store_short v[30:31], v0, off sc1
	global_load_dword v0, v[100:101], off offset:384
	v_add_u32_e32 v30, v179, v16
	s_waitcnt vmcnt(18)
	v_fmac_f32_e32 v24, v5, v102
	v_ashrrev_i32_e32 v31, 31, v30
	v_mul_f32_e32 v3, v32, v24
	v_cvt_pk_bf16_f32 v3, v3, s0
	v_lshl_add_u64 v[4:5], v[30:31], 1, s[8:9]
	global_store_short v[4:5], v3, off sc1
	v_add_u32_e32 v4, v71, v16
	s_waitcnt vmcnt(18)
	v_fmac_f32_e32 v23, v6, v102
	v_ashrrev_i32_e32 v5, 31, v4
	v_mul_f32_e32 v3, v32, v23
	v_cvt_pk_bf16_f32 v3, v3, s0
	v_lshl_add_u64 v[4:5], v[4:5], 1, s[8:9]
	global_store_short v[4:5], v3, off sc1
	v_add_u32_e32 v4, v180, v16
	s_waitcnt vmcnt(17)
	v_fmac_f32_e32 v22, v7, v102
	v_ashrrev_i32_e32 v5, 31, v4
	v_mul_f32_e32 v3, v32, v22
	v_cvt_pk_bf16_f32 v3, v3, s0
	v_lshl_add_u64 v[4:5], v[4:5], 1, s[8:9]
	global_store_short v[4:5], v3, off sc1
	v_add_u32_e32 v4, v182, v16
	v_fmac_f32_e32 v21, v8, v102
	v_ashrrev_i32_e32 v5, 31, v4
	v_mul_f32_e32 v3, v32, v21
	v_cvt_pk_bf16_f32 v3, v3, s0
	v_lshl_add_u64 v[4:5], v[4:5], 1, s[8:9]
	global_store_short v[4:5], v3, off sc1
	v_add_u32_e32 v4, v185, v16
	v_ashrrev_i32_e32 v5, 31, v4
	v_mul_f32_e32 v3, v32, v20
	v_cvt_pk_bf16_f32 v3, v3, s0
	v_lshl_add_u64 v[4:5], v[4:5], 1, s[8:9]
	global_store_short v[4:5], v3, off sc1
	v_add_u32_e32 v4, v187, v16
	s_waitcnt vmcnt(18)
	v_fmac_f32_e32 v19, v10, v102
	v_ashrrev_i32_e32 v5, 31, v4
	v_mul_f32_e32 v3, v32, v19
	v_cvt_pk_bf16_f32 v3, v3, s0
	v_lshl_add_u64 v[4:5], v[4:5], 1, s[8:9]
	global_store_short v[4:5], v3, off sc1
	v_add_u32_e32 v4, v189, v16
	s_waitcnt vmcnt(18)
	v_fmac_f32_e32 v18, v11, v102
	v_ashrrev_i32_e32 v5, 31, v4
	v_mul_f32_e32 v3, v32, v18
	v_cvt_pk_bf16_f32 v3, v3, s0
	v_lshl_add_u64 v[4:5], v[4:5], 1, s[8:9]
	global_store_short v[4:5], v3, off sc1
	v_add_u32_e32 v4, v190, v16
	s_waitcnt vmcnt(17)
	v_fmac_f32_e32 v17, v12, v102
	v_ashrrev_i32_e32 v5, 31, v4
	v_mul_f32_e32 v3, v32, v17
	v_cvt_pk_bf16_f32 v3, v3, s0
	v_lshl_add_u64 v[4:5], v[4:5], 1, s[8:9]
	global_store_short v[4:5], v3, off sc1
	v_add_u32_e32 v4, v191, v16
	s_waitcnt vmcnt(16)
	v_fmac_f32_e32 v2, v13, v102
	v_ashrrev_i32_e32 v5, 31, v4
	v_mul_f32_e32 v3, v32, v2
	v_cvt_pk_bf16_f32 v3, v3, s0
	v_lshl_add_u64 v[4:5], v[4:5], 1, s[8:9]
	global_store_short v[4:5], v3, off sc1
	v_add_u32_e32 v4, v192, v16
	v_ashrrev_i32_e32 v5, 31, v4
	v_lshl_add_u64 v[4:5], v[4:5], 1, s[8:9]
	v_xor_b32_e32 v13, 16, v164
	v_add_u32_e32 v10, v193, v16
	v_ashrrev_i32_e32 v11, 31, v10
	v_lshl_add_u64 v[10:11], v[10:11], 1, s[8:9]
	v_ashrrev_i32_e32 v71, 31, v70
	global_store_dword v[82:83], v26, off offset:384 sc1
	global_store_dword v[78:79], v25, off offset:384 sc1
	global_store_dword v[72:73], v24, off offset:384 sc1
	global_store_dword v[74:75], v23, off offset:384 sc1
	s_waitcnt vmcnt(15)
	v_fmac_f32_e32 v1, v14, v102
	v_mul_f32_e32 v3, v32, v1
	v_cvt_pk_bf16_f32 v3, v3, s0
	global_store_short v[4:5], v3, off sc1
	v_and_b32_e32 v4, 64, v164
	v_xor_b32_e32 v3, 1, v164
	v_add_u32_e32 v7, 64, v4
	v_cmp_lt_i32_e32 vcc, v3, v7
	v_xor_b32_e32 v4, 2, v164
	s_waitcnt vmcnt(14)
	v_fmac_f32_e32 v0, v15, v102
	v_cndmask_b32_e32 v3, v164, v3, vcc
	v_lshlrev_b32_e32 v3, 2, v3
	s_nop 1
	v_mov_b32_dpp v5, v106 quad_perm:[1,0,3,2] row_mask:0xf bank_mask:0xf
	v_cmp_lt_i32_e32 vcc, v4, v7
	v_mul_f32_e32 v12, v32, v0
	v_cvt_pk_bf16_f32 v12, v12, s0
	v_cndmask_b32_e32 v4, v164, v4, vcc
	v_lshlrev_b32_e32 v4, 2, v4
	s_waitcnt lgkmcnt(0)
	v_add_f32_e32 v6, v106, v5
	s_nop 1
	v_mov_b32_dpp v8, v6 quad_perm:[2,3,0,1] row_mask:0xf bank_mask:0xf
	v_xor_b32_e32 v5, 4, v164
	v_cmp_lt_i32_e32 vcc, v5, v7
	global_store_dword v[76:77], v22, off offset:384 sc1
	global_store_dword v[80:81], v21, off offset:384 sc1
	v_cndmask_b32_e32 v5, v164, v5, vcc
	v_lshlrev_b32_e32 v5, 2, v5
	s_waitcnt lgkmcnt(0)
	v_add_f32_e32 v8, v6, v8
	s_nop 1
	v_mov_b32_dpp v9, v8 row_half_mirror row_mask:0xf bank_mask:0xf
	v_xor_b32_e32 v6, 8, v164
	v_cmp_lt_i32_e32 vcc, v6, v7
	global_store_dword v[90:91], v19, off offset:384 sc1
	global_store_dword v[92:93], v18, off offset:384 sc1
	v_cndmask_b32_e32 v6, v164, v6, vcc
	v_lshlrev_b32_e32 v6, 2, v6
	s_waitcnt lgkmcnt(0)
	v_add_f32_e32 v8, v8, v9
	s_nop 1
	v_mov_b32_dpp v9, v8 row_mirror row_mask:0xf bank_mask:0xf
	v_cmp_lt_i32_e32 vcc, v13, v7
	global_store_dword v[94:95], v17, off offset:384 sc1
	global_store_dword v[96:97], v2, off offset:384 sc1
	v_cndmask_b32_e32 v7, v164, v13, vcc
	v_lshlrev_b32_e32 v7, 2, v7
	s_waitcnt lgkmcnt(0)
	v_add_f32_e32 v8, v8, v9
	ds_bpermute_b32 v9, v7, v8
	global_store_dword v[98:99], v1, off offset:384 sc1
	global_store_dword v[100:101], v0, off offset:384 sc1
	global_store_short v[10:11], v12, off sc1
	s_and_saveexec_b64 s[60:61], s[0:1]
	s_cbranch_execz .LBB0_1571
	s_waitcnt lgkmcnt(0)
	v_add_f32_e32 v10, v8, v9
	v_lshl_add_u64 v[8:9], v[70:71], 2, s[58:59]
	global_store_dword v[8:9], v10, off sc1
